# K-loop rescheduling (ds_writes early) + LDS-DMA for up-projection + s_setprio 1 in K-loops
# baseline (speedup 1.0000x reference)
; DI int BIDX() { int b = blockIdx.x; asm volatile("" : "+s"(b)); return b; }
; DI int tile_groups(int MT, int NT) { return (MT >> 6) * ((NT + 7) >> 3) * 512; }
; DI void load_rstd(float (&rs)[4], const float* ssq, int row0, int lr) {
; #pragma unroll
;   for (int mt = 0; mt < 4; ++mt) {
;     const float4* q = (const float4*)(ssq + (size_t)(row0 + mt * 16 + lr) * 16);
;     const float4 a = q[0], b = q[1], c = q[2], d = q[3];
;     const float s = ((a.x + a.y) + (a.z + a.w)) + ((b.x + b.y) + (b.z + b.w)) + ((c.x + c.y) + (c.z + c.w)) + ((d.x + d.y) + (d.z + d.w));
;     rs[mt] = rsqrtf(s * (1.0f / 1024.0f) + EPS);
;   }
; }
; DI void phase_proj(const Params& P, int l, char* smem) {
;     ...
;   for (int vb = BIDX(); vb < tile_groups(128, 63); vb += gridDim.x) {
;     int tm, tn; if (!tile_of(vb, 128, 63, tm, tn)) continue;
;     const int m0 = tm * 128, n0 = tn * 128;
;     f32x4 acc[4][4]; zero_acc(acc);
;     const int row0 = m0 + wm * 64, col0 = n0 + wn * 64;
;     float rs[4]; load_rstd(rs, ssq, row0, lr);
;     if (n0 >= PW) {
.LBB0_637:
	s_ashr_i32 s1, s28, 9
	s_lshr_b32 s2, s1, 29
	s_add_i32 s2, s1, s2
	s_lshl_b32 s2, s2, 3
	s_and_b32 s4, s2, 0xffffffc0
	s_and_b32 s2, s26, 56
	s_bfe_u32 s5, s28, 0x30003
	s_or_b32 s2, s2, s5
	s_lshl_b32 s1, s1, 3
	s_or_b32 s2, s2, s4
	s_sub_i32 s1, s1, s4
	s_bfe_u32 s4, s28, 0x30006
	s_or_b32 s1, s1, s4
	s_cmpk_lt_i32 s2, 0x80
	s_cselect_b64 s[4:5], -1, 0
	s_cmp_lt_i32 s1, 63
	s_cselect_b64 s[16:17], -1, 0
	s_and_b64 s[4:5], s[4:5], s[16:17]
	s_andn2_b64 vcc, exec, s[4:5]
	s_cbranch_vccnz .LBB0_636
	s_lshl_b32 s18, s2, 7
	v_add_u32_e32 v99, s18, v101
	s_waitcnt vmcnt(0)
	v_or_b32_e32 v70, v99, v97
	v_ashrrev_i32_e32 v71, 31, v70
	v_readlane_b32 s20, v253, 13
	v_lshlrev_b64 v[0:1], 6, v[70:71]
	v_readlane_b32 s21, v253, 14
	v_or_b32_e32 v68, 16, v70
	v_ashrrev_i32_e32 v69, 31, v68
	v_lshl_add_u64 v[12:13], s[20:21], 0, v[0:1]
	global_load_dwordx4 v[0:3], v[12:13], off offset:48
	global_load_dwordx4 v[4:7], v[12:13], off offset:32
	global_load_dwordx4 v[8:11], v[12:13], off offset:16
	s_nop 0
	global_load_dwordx4 v[12:15], v[12:13], off
	s_mov_b32 s2, 0x358637bd
	s_mov_b32 s22, 0x3a800000
	v_or_b32_e32 v66, 32, v70
	v_ashrrev_i32_e32 v67, 31, v66
	v_or_b32_e32 v64, 48, v70
	v_ashrrev_i32_e32 v65, 31, v64
	s_ashr_i32 s19, s18, 31
	s_lshl_b32 s16, s1, 7
	v_or_b32_e32 v94, s16, v85
	s_waitcnt vmcnt(1)
	v_mov_b32_e32 v18, v9
	s_waitcnt vmcnt(0)
	v_mov_b32_e32 v16, v13
	v_mov_b32_e32 v17, v14
	v_mov_b32_e32 v19, v10
	v_mov_b32_e32 v13, v15
	v_mov_b32_e32 v9, v11
	v_pk_add_f32 v[12:13], v[16:17], v[12:13]
	v_pk_add_f32 v[8:9], v[18:19], v[8:9]
	v_pk_add_f32 v[10:11], v[12:13], v[12:13] op_sel:[0,1] op_sel_hi:[1,0]
	v_pk_add_f32 v[8:9], v[8:9], v[8:9] op_sel:[0,1] op_sel_hi:[1,0]
	v_mov_b32_e32 v11, v0
	v_mov_b32_e32 v9, v1
	v_pk_add_f32 v[0:1], v[10:11], v[8:9]
	v_mov_b32_e32 v8, v5
	v_pk_add_f32 v[4:5], v[4:5], v[8:9]
	s_nop 0
	v_mov_b32_e32 v5, v2
	v_mov_b32_e32 v2, v7
	v_pk_add_f32 v[6:7], v[6:7], v[2:3]
	s_nop 0
	v_mov_b32_e32 v7, v3
	v_pk_add_f32 v[2:3], v[4:5], v[6:7]
	s_nop 0
	v_pk_add_f32 v[16:17], v[0:1], v[2:3]
	v_lshlrev_b64 v[0:1], 6, v[68:69]
	v_lshl_add_u64 v[12:13], s[20:21], 0, v[0:1]
	global_load_dwordx4 v[0:3], v[12:13], off offset:48
	global_load_dwordx4 v[4:7], v[12:13], off offset:32
	global_load_dwordx4 v[8:11], v[12:13], off offset:16
	s_nop 0
	global_load_dwordx4 v[12:15], v[12:13], off
	s_waitcnt vmcnt(1)
	v_mov_b32_e32 v20, v9
	s_waitcnt vmcnt(0)
	v_mov_b32_e32 v18, v13
	v_mov_b32_e32 v19, v14
	v_mov_b32_e32 v21, v10
	v_mov_b32_e32 v13, v15
	v_mov_b32_e32 v9, v11
	v_pk_add_f32 v[12:13], v[18:19], v[12:13]
	v_pk_add_f32 v[8:9], v[20:21], v[8:9]
	v_pk_add_f32 v[10:11], v[12:13], v[12:13] op_sel:[0,1] op_sel_hi:[1,0]
	v_pk_add_f32 v[8:9], v[8:9], v[8:9] op_sel:[0,1] op_sel_hi:[1,0]
	v_mov_b32_e32 v11, v0
	v_mov_b32_e32 v9, v1
	v_pk_add_f32 v[0:1], v[10:11], v[8:9]
	v_mov_b32_e32 v8, v5
	v_pk_add_f32 v[4:5], v[4:5], v[8:9]
	s_nop 0
	v_mov_b32_e32 v5, v2
	v_mov_b32_e32 v2, v7
	v_pk_add_f32 v[6:7], v[6:7], v[2:3]
	s_nop 0
	v_mov_b32_e32 v7, v3
	v_pk_add_f32 v[2:3], v[4:5], v[6:7]
	s_nop 0
	v_pk_add_f32 v[0:1], v[0:1], v[2:3]
	v_mov_b32_e32 v3, v16
	v_mov_b32_e32 v2, v0
	v_mov_b32_e32 v16, v1
	v_pk_add_f32 v[0:1], v[2:3], v[16:17]
	v_mov_b64_e32 v[16:17], s[2:3]
	v_pk_fma_f32 v[0:1], v[0:1], s[22:23], v[16:17] op_sel_hi:[1,0,0]
	s_mov_b32 s2, 0x800000
	v_mul_f32_e32 v2, 0x4b800000, v1
	v_cmp_gt_f32_e64 s[4:5], s2, v1
	v_cmp_gt_f32_e32 vcc, s2, v0
	s_nop 0
	v_cndmask_b32_e64 v1, v1, v2, s[4:5]
	v_rsq_f32_e32 v1, v1
	s_nop 0
	v_mul_f32_e32 v2, 0x45800000, v1
	v_cndmask_b32_e64 v98, v1, v2, s[4:5]
	v_mul_f32_e32 v1, 0x4b800000, v0
	v_cndmask_b32_e32 v0, v0, v1, vcc
	v_rsq_f32_e32 v0, v0
	s_nop 0
	v_mul_f32_e32 v1, 0x45800000, v0
	v_cndmask_b32_e32 v96, v0, v1, vcc
	v_lshlrev_b64 v[0:1], 6, v[66:67]
	v_lshl_add_u64 v[12:13], s[20:21], 0, v[0:1]
	global_load_dwordx4 v[0:3], v[12:13], off offset:48
	global_load_dwordx4 v[4:7], v[12:13], off offset:32
	global_load_dwordx4 v[8:11], v[12:13], off offset:16
	s_nop 0
	global_load_dwordx4 v[12:15], v[12:13], off
	s_waitcnt vmcnt(1)
	v_mov_b32_e32 v20, v9
	s_waitcnt vmcnt(0)
	v_mov_b32_e32 v18, v13
	v_mov_b32_e32 v19, v14
	v_mov_b32_e32 v21, v10
	v_mov_b32_e32 v13, v15
	v_mov_b32_e32 v9, v11
	v_pk_add_f32 v[12:13], v[18:19], v[12:13]
	v_pk_add_f32 v[8:9], v[20:21], v[8:9]
	v_pk_add_f32 v[10:11], v[12:13], v[12:13] op_sel:[0,1] op_sel_hi:[1,0]
	v_pk_add_f32 v[8:9], v[8:9], v[8:9] op_sel:[0,1] op_sel_hi:[1,0]
	v_mov_b32_e32 v11, v0
	v_mov_b32_e32 v9, v1
	v_pk_add_f32 v[0:1], v[10:11], v[8:9]
	v_mov_b32_e32 v8, v5
	v_pk_add_f32 v[4:5], v[4:5], v[8:9]
	s_nop 0
	v_mov_b32_e32 v5, v2
	v_mov_b32_e32 v2, v7
	v_pk_add_f32 v[6:7], v[6:7], v[2:3]
	s_nop 0
	v_mov_b32_e32 v7, v3
	v_pk_add_f32 v[2:3], v[4:5], v[6:7]
	s_nop 0
	v_pk_add_f32 v[18:19], v[0:1], v[2:3]
	v_lshlrev_b64 v[0:1], 6, v[64:65]
	v_lshl_add_u64 v[12:13], s[20:21], 0, v[0:1]
	global_load_dwordx4 v[0:3], v[12:13], off offset:48
	global_load_dwordx4 v[4:7], v[12:13], off offset:32
	global_load_dwordx4 v[8:11], v[12:13], off offset:16
	s_nop 0
	global_load_dwordx4 v[12:15], v[12:13], off
	s_waitcnt vmcnt(1)
	v_mov_b32_e32 v22, v9
	s_waitcnt vmcnt(0)
	v_mov_b32_e32 v20, v13
	v_mov_b32_e32 v21, v14
	v_mov_b32_e32 v23, v10
	v_mov_b32_e32 v13, v15
	v_mov_b32_e32 v9, v11
	v_pk_add_f32 v[12:13], v[20:21], v[12:13]
	v_pk_add_f32 v[8:9], v[22:23], v[8:9]
	v_pk_add_f32 v[10:11], v[12:13], v[12:13] op_sel:[0,1] op_sel_hi:[1,0]
	v_pk_add_f32 v[8:9], v[8:9], v[8:9] op_sel:[0,1] op_sel_hi:[1,0]
	v_mov_b32_e32 v11, v0
	v_mov_b32_e32 v9, v1
	v_pk_add_f32 v[0:1], v[10:11], v[8:9]
	v_mov_b32_e32 v8, v5
	v_pk_add_f32 v[4:5], v[4:5], v[8:9]
	s_nop 0
	v_mov_b32_e32 v5, v2
	v_mov_b32_e32 v2, v7
	v_pk_add_f32 v[6:7], v[6:7], v[2:3]
	s_nop 0
	v_mov_b32_e32 v7, v3
	v_pk_add_f32 v[2:3], v[4:5], v[6:7]
	s_nop 0
	v_pk_add_f32 v[0:1], v[0:1], v[2:3]
	v_mov_b32_e32 v3, v18
	v_mov_b32_e32 v2, v0
	v_mov_b32_e32 v18, v1
	v_pk_add_f32 v[0:1], v[2:3], v[18:19]
	s_nop 0
	v_pk_fma_f32 v[0:1], v[0:1], s[22:23], v[16:17] op_sel_hi:[1,0,0]
	s_nop 0
	v_mul_f32_e32 v2, 0x4b800000, v1
	v_cmp_gt_f32_e64 s[4:5], s2, v1
	v_cmp_gt_f32_e32 vcc, s2, v0
	s_nop 0
	v_cndmask_b32_e64 v1, v1, v2, s[4:5]
	v_rsq_f32_e32 v1, v1
	s_nop 0
	v_mul_f32_e32 v2, 0x45800000, v1
	v_cndmask_b32_e64 v102, v1, v2, s[4:5]
	v_mul_f32_e32 v1, 0x4b800000, v0
	v_cndmask_b32_e32 v0, v0, v1, vcc
	v_rsq_f32_e32 v0, v0
	s_lshl_b64 s[4:5], s[18:19], 11
	v_readlane_b32 s18, v253, 11
	v_readlane_b32 s19, v253, 12
	s_add_u32 s18, s18, s4
	v_mul_f32_e32 v1, 0x45800000, v0
	s_addc_u32 s19, s19, s5
	v_cndmask_b32_e32 v100, v0, v1, vcc
	s_cmp_lt_i32 s1, 51
	s_mov_b64 s[4:5], -1
	s_cbranch_scc0 .LBB0_691
; DI int TIDX() { int t = threadIdx.x; asm volatile("" : "+v"(t)); return t; }
; #define GL_LOAD(s_, kt_) if (VAR != 1) { a##s_##0 = GL_A(0, kt_); a##s_##1 = GL_A(1, kt_); a##s_##2 = GL_A(2, kt_); a##s_##3 = GL_A(3, kt_); b##s_##0 = GL_B(0, kt_); b##s_##1 = GL_B(1, kt_); b##s_##2 = GL_B(2, kt_); b##s_##3 = GL_B(3, kt_); }
; #define LDS_STORE(s_, buf_) if (VAR != 2) { LDS_ST1(sA, 0, buf_, a##s_##0) LDS_ST1(sA, 1, buf_, a##s_##1) LDS_ST1(sA, 2, buf_, a##s_##2) LDS_ST1(sA, 3, buf_, a##s_##3) LDS_ST1(sB, 0, buf_, b##s_##0) LDS_ST1(sB, 1, buf_, b##s_##1) LDS_ST1(sB, 2, buf_, b##s_##2) LDS_ST1(sB, 3, buf_, b##s_##3) }
;   const int tid = TIDX(), lane = tid & 63, wid = tid >> 6, wm = wid >> 1, wn = wid & 1, lr = lane & 15, g = lane >> 4;
;   char* sA = smem; char* sB = smem + 2 * LTILE;
;   uint4 a00 = {}, a01 = {}, a02 = {}, a03 = {}, b00 = {}, b01 = {}, b02 = {}, b03 = {}, a10 = {}, a11 = {}, a12 = {}, a13 = {}, b10 = {}, b11 = {}, b12 = {}, b13 = {};
;   constexpr int nk = NK;
;   const int sw0 = (g ^ ((lr >> 1) & 7)) << 4, sw1 = sw0 ^ 64;
;   const int r0 = tid >> 3, kc = tid & 7, kcs = kc ^ ((r0 >> 1) & 7);
;     ...
;   GL_LOAD(0, 0)
;   GL_LOAD(1, 1)
;   LDS_STORE(0, 0)
;   if (VAR != 4) __syncthreads();
; #pragma unroll
;   for (int kt = 0; kt < nk; kt += 2) {
;     if (kt + 2 < nk) { GL_LOAD(0, kt + 2) }
;     MMA_TILE(0)
;     LDS_STORE(1, 1)
	v_mov_b32_e32 v56, v148
	s_ashr_i32 s17, s16, 31
	s_lshl_b64 s[4:5], s[16:17], 11
	v_ashrrev_i32_e32 v16, 3, v56
	v_readlane_b32 s1, v252, 19
	v_ashrrev_i32_e32 v17, 31, v16
	s_add_u32 s4, s1, s4
	v_readlane_b32 s1, v252, 20
	v_lshlrev_b64 v[8:9], 11, v[16:17]
	v_lshlrev_b32_e32 v17, 4, v56
	v_add_u32_e32 v18, 32, v16
	s_addc_u32 s5, s1, s5
	v_lshl_add_u64 v[0:1], s[18:19], 0, v[8:9]
	v_and_b32_e32 v150, 0x70, v17
	v_ashrrev_i32_e32 v19, 31, v18
	v_add_u32_e32 v20, 64, v16
	v_lshl_add_u64 v[0:1], v[0:1], 0, v[150:151]
	v_lshlrev_b64 v[10:11], 11, v[18:19]
	v_ashrrev_i32_e32 v21, 31, v20
	v_add_u32_e32 v54, 0x60, v16
	v_lshl_add_u64 v[8:9], s[4:5], 0, v[8:9]
	global_load_dwordx4 v[22:25], v[0:1], off
	v_lshl_add_u64 v[2:3], s[18:19], 0, v[10:11]
	v_lshlrev_b64 v[12:13], 11, v[20:21]
	v_ashrrev_i32_e32 v55, 31, v54
	v_lshl_add_u64 v[8:9], v[8:9], 0, v[150:151]
	v_lshl_add_u64 v[2:3], v[2:3], 0, v[150:151]
	v_lshl_add_u64 v[4:5], s[18:19], 0, v[12:13]
	v_lshlrev_b64 v[14:15], 11, v[54:55]
	global_load_dwordx4 v[38:41], v[8:9], off
	global_load_dwordx4 v[26:29], v[2:3], off
	v_lshl_add_u64 v[4:5], v[4:5], 0, v[150:151]
	v_lshl_add_u64 v[6:7], s[18:19], 0, v[14:15]
	global_load_dwordx4 v[30:33], v[4:5], off
	v_lshl_add_u64 v[6:7], v[6:7], 0, v[150:151]
	v_lshl_add_u64 v[10:11], s[4:5], 0, v[10:11]
	global_load_dwordx4 v[34:37], v[6:7], off
	v_lshl_add_u64 v[10:11], v[10:11], 0, v[150:151]
	v_lshl_add_u64 v[12:13], s[4:5], 0, v[12:13]
	global_load_dwordx4 v[42:45], v[10:11], off
	v_lshl_add_u64 v[12:13], v[12:13], 0, v[150:151]
	v_lshl_add_u64 v[14:15], s[4:5], 0, v[14:15]
	global_load_dwordx4 v[46:49], v[12:13], off
	v_lshl_add_u64 v[14:15], v[14:15], 0, v[150:151]
	global_load_dwordx4 v[50:53], v[14:15], off
	v_lshlrev_b32_e32 v21, 3, v56
	v_and_b32_e32 v62, 48, v56
	s_movk_i32 s1, 0x70
	v_and_b32_e32 v19, 15, v56
	v_lshrrev_b32_e32 v55, 1, v56
	v_lshlrev_b32_e32 v57, 7, v56
	v_and_b32_e32 v63, 0x70, v21
	v_bitop3_b32 v95, v21, v62, s1 bitop3:0x6c
	v_bitop3_b32 v21, v17, s1, v56 bitop3:0x48
	v_and_or_b32 v103, v55, s29, v19
	v_and_b32_e32 v150, 0x2780, v57
	v_lshl_or_b32 v19, v20, 7, v21
	v_lshl_or_b32 v20, v54, 7, v21
	global_load_dwordx4 v[54:57], v[0:1], off offset:128
	global_load_dwordx4 v[58:61], v[8:9], off offset:128
	global_load_dwordx4 v[72:75], v[2:3], off offset:128
	global_load_dwordx4 v[76:79], v[4:5], off offset:128
	global_load_dwordx4 v[80:83], v[6:7], off offset:128
	global_load_dwordx4 v[104:107], v[10:11], off offset:128
	global_load_dwordx4 v[108:111], v[12:13], off offset:128
	global_load_dwordx4 v[112:115], v[14:15], off offset:128
	v_lshl_or_b32 v17, v16, 7, v21
	v_or_b32_e32 v16, v150, v95
	v_lshlrev_b32_e32 v103, 7, v103
	v_lshl_or_b32 v18, v18, 7, v21
	v_bitop3_b32 v21, v103, v63, v62 bitop3:0xf6
	s_movk_i32 s1, 0x1ff
	v_cmp_lt_i32_e32 vcc, s1, v94
	s_mov_b64 s[22:23], -1
	s_mov_b64 s[20:21], 0
	s_waitcnt vmcnt(15)
	ds_write_b128 v17, v[22:25]
	s_waitcnt vmcnt(14)
	ds_write_b128 v17, v[38:41] offset:32768
	s_waitcnt vmcnt(13)
	ds_write_b128 v18, v[26:29]
	s_waitcnt vmcnt(12)
	ds_write_b128 v19, v[30:33]
	s_waitcnt vmcnt(11)
	ds_write_b128 v20, v[34:37]
	s_waitcnt vmcnt(10)
	ds_write_b128 v18, v[42:45] offset:32768
	s_waitcnt vmcnt(9)
	ds_write_b128 v19, v[46:49] offset:32768
	s_waitcnt vmcnt(8)
	ds_write_b128 v20, v[50:53] offset:32768
	s_waitcnt lgkmcnt(0)
	s_barrier
	s_setprio 1
	ds_read_b128 v[22:25], v16 offset:32768
	ds_read_b128 v[30:33], v21
	s_waitcnt lgkmcnt(0)
	v_mfma_f32_16x16x32_f16 v[38:41], v[22:25], v[30:33], 0
	ds_read_b128 v[26:29], v16 offset:34816
	s_waitcnt lgkmcnt(0)
	v_mfma_f32_16x16x32_f16 v[46:49], v[26:29], v[30:33], 0
	ds_read_b128 v[34:37], v21 offset:2048
	ds_read_b128 v[42:45], v16 offset:36864
	s_waitcnt lgkmcnt(0)
	v_mfma_f32_16x16x32_f16 v[116:119], v[42:45], v[30:33], 0
	ds_read_b128 v[50:53], v16 offset:38912
	s_waitcnt lgkmcnt(0)
	v_mfma_f32_16x16x32_f16 v[120:123], v[50:53], v[30:33], 0
	ds_read_b128 v[30:33], v21 offset:4096
	v_mfma_f32_16x16x32_f16 v[124:127], v[22:25], v[34:37], 0
	ds_read_b128 v[136:139], v21 offset:6144
	s_waitcnt lgkmcnt(0)
	v_mfma_f32_16x16x32_f16 v[162:165], v[22:25], v[136:139], 0
	s_waitcnt vmcnt(7)
	ds_write_b128 v17, v[54:57] offset:16384
	v_mfma_f32_16x16x32_f16 v[128:131], v[26:29], v[34:37], 0
	s_waitcnt vmcnt(5)
	ds_write_b128 v18, v[72:75] offset:16384
	v_mfma_f32_16x16x32_f16 v[132:135], v[42:45], v[34:37], 0
	s_waitcnt vmcnt(4)
	ds_write_b128 v19, v[76:79] offset:16384
	v_mfma_f32_16x16x32_f16 v[34:37], v[50:53], v[34:37], 0
	s_waitcnt vmcnt(3)
	ds_write_b128 v20, v[80:83] offset:16384
	v_mfma_f32_16x16x32_f16 v[140:143], v[22:25], v[30:33], 0
	v_xor_b32_e32 v22, 64, v95
	v_or_b32_e32 v22, v150, v22
	v_mfma_f32_16x16x32_f16 v[144:147], v[26:29], v[30:33], 0
	v_mfma_f32_16x16x32_f16 v[154:157], v[42:45], v[30:33], 0
	v_mfma_f32_16x16x32_f16 v[158:161], v[50:53], v[30:33], 0
	v_bitop3_b32 v32, v103, v95, 64 bitop3:0xf6
	ds_read_b128 v[166:169], v32
	ds_read_b128 v[192:195], v22 offset:36864
	s_waitcnt lgkmcnt(0)
	v_mfma_f32_16x16x32_f16 v[116:119], v[192:195], v[166:169], v[116:119]
	ds_read_b128 v[188:191], v32 offset:2048
	ds_read_b128 v[196:199], v22 offset:38912
	s_waitcnt lgkmcnt(0)
	v_mfma_f32_16x16x32_f16 v[120:123], v[196:199], v[166:169], v[120:123]
	ds_write_b128 v17, v[58:61] offset:49152
	v_mfma_f32_16x16x32_f16 v[132:135], v[192:195], v[188:191], v[132:135]
	s_waitcnt vmcnt(2)
	ds_write_b128 v18, v[104:107] offset:49152
	v_mfma_f32_16x16x32_f16 v[34:37], v[196:199], v[188:191], v[34:37]
	s_waitcnt vmcnt(1)
	ds_write_b128 v19, v[108:111] offset:49152
	s_waitcnt vmcnt(0)
; #define GL_LOAD(s_, kt_) if (VAR != 1) { a##s_##0 = GL_A(0, kt_); a##s_##1 = GL_A(1, kt_); a##s_##2 = GL_A(2, kt_); a##s_##3 = GL_A(3, kt_); b##s_##0 = GL_B(0, kt_); b##s_##1 = GL_B(1, kt_); b##s_##2 = GL_B(2, kt_); b##s_##3 = GL_B(3, kt_); }
; #define LDS_STORE(s_, buf_) if (VAR != 2) { LDS_ST1(sA, 0, buf_, a##s_##0) LDS_ST1(sA, 1, buf_, a##s_##1) LDS_ST1(sA, 2, buf_, a##s_##2) LDS_ST1(sA, 3, buf_, a##s_##3) LDS_ST1(sB, 0, buf_, b##s_##0) LDS_ST1(sB, 1, buf_, b##s_##1) LDS_ST1(sB, 2, buf_, b##s_##2) LDS_ST1(sB, 3, buf_, b##s_##3) }
;     ...
;   GL_LOAD(0, 0)
;   GL_LOAD(1, 1)
;   LDS_STORE(0, 0)
;   if (VAR != 4) __syncthreads();
; #pragma unroll
;   for (int kt = 0; kt < nk; kt += 2) {
;     if (kt + 2 < nk) { GL_LOAD(0, kt + 2) }
;     MMA_TILE(0)
;     LDS_STORE(1, 1)
;     if (VAR != 4) __syncthreads();
;     if (kt + 3 < nk) { GL_LOAD(1, kt + 3) }
;     MMA_TILE(1)
;     if (kt + 2 < nk) { LDS_STORE(0, 0) }
;     if (VAR != 4) __syncthreads();
	ds_write_b128 v20, v[112:115] offset:49152
	v_mfma_f32_16x16x32_f16 v[24:27], v[26:29], v[136:139], 0
	v_mfma_f32_16x16x32_f16 v[28:31], v[42:45], v[136:139], 0
	ds_read_b128 v[42:45], v22 offset:32768
	v_mfma_f32_16x16x32_f16 v[50:53], v[50:53], v[136:139], 0
	ds_read_b128 v[136:139], v22 offset:34816
	s_waitcnt lgkmcnt(1)
	v_mfma_f32_16x16x32_f16 v[38:41], v[42:45], v[166:169], v[38:41]
	v_mfma_f32_16x16x32_f16 v[124:127], v[42:45], v[188:191], v[124:127]
	s_waitcnt lgkmcnt(0)
	v_mfma_f32_16x16x32_f16 v[46:49], v[136:139], v[166:169], v[46:49]
	ds_read_b128 v[166:169], v32 offset:4096
	v_mfma_f32_16x16x32_f16 v[128:131], v[136:139], v[188:191], v[128:131]
	ds_read_b128 v[188:191], v32 offset:6144
	s_waitcnt lgkmcnt(1)
	v_mfma_f32_16x16x32_f16 v[140:143], v[42:45], v[166:169], v[140:143]
	s_waitcnt lgkmcnt(0)
	v_mfma_f32_16x16x32_f16 v[42:45], v[42:45], v[188:191], v[162:165]
	s_nop 2
	global_load_dwordx4 v[162:165], v[0:1], off offset:256
	v_mfma_f32_16x16x32_f16 v[144:147], v[136:139], v[166:169], v[144:147]
	v_mfma_f32_16x16x32_f16 v[24:27], v[136:139], v[188:191], v[24:27]
	v_mfma_f32_16x16x32_f16 v[154:157], v[192:195], v[166:169], v[154:157]
	v_mfma_f32_16x16x32_f16 v[158:161], v[196:199], v[166:169], v[158:161]
	global_load_dwordx4 v[166:169], v[2:3], off offset:256
	global_load_dwordx4 v[200:203], v[4:5], off offset:256
	global_load_dwordx4 v[204:207], v[6:7], off offset:256
	global_load_dwordx4 v[136:139], v[8:9], off offset:256
	global_load_dwordx4 v[208:211], v[10:11], off offset:256
	global_load_dwordx4 v[212:215], v[12:13], off offset:256
	global_load_dwordx4 v[220:223], v[14:15], off offset:256
	s_waitcnt lgkmcnt(0)
	s_barrier
	v_mfma_f32_16x16x32_f16 v[28:31], v[192:195], v[188:191], v[28:31]
	ds_read_b128 v[54:57], v16 offset:49152
	v_mfma_f32_16x16x32_f16 v[50:53], v[196:199], v[188:191], v[50:53]
	ds_read_b128 v[58:61], v16 offset:51200
	ds_read_b128 v[72:75], v21 offset:16384
	s_waitcnt lgkmcnt(0)
	v_mfma_f32_16x16x32_f16 v[38:41], v[54:57], v[72:75], v[38:41]
	ds_read_b128 v[76:79], v21 offset:18432
	s_waitcnt lgkmcnt(0)
	v_mfma_f32_16x16x32_f16 v[112:115], v[54:57], v[76:79], v[124:127]
	ds_read_b128 v[80:83], v16 offset:53248
	v_mfma_f32_16x16x32_f16 v[46:49], v[58:61], v[72:75], v[46:49]
	ds_read_b128 v[104:107], v16 offset:55296
	s_waitcnt lgkmcnt(1)
	v_mfma_f32_16x16x32_f16 v[108:111], v[80:83], v[72:75], v[116:119]
	v_mfma_f32_16x16x32_f16 v[116:119], v[58:61], v[76:79], v[128:131]
	ds_read_b128 v[124:127], v21 offset:22528
	s_waitcnt vmcnt(7)
	ds_write_b128 v17, v[162:165]
	s_waitcnt lgkmcnt(2)
	v_mfma_f32_16x16x32_f16 v[72:75], v[104:107], v[72:75], v[120:123]
	v_mfma_f32_16x16x32_f16 v[120:123], v[80:83], v[76:79], v[132:135]
	s_waitcnt vmcnt(6)
	ds_write_b128 v18, v[166:169]
	s_waitcnt vmcnt(5)
	ds_write_b128 v19, v[200:203]
	v_mfma_f32_16x16x32_f16 v[34:37], v[104:107], v[76:79], v[34:37]
	ds_read_b128 v[76:79], v21 offset:20480
	s_waitcnt lgkmcnt(0)
	v_mfma_f32_16x16x32_f16 v[128:131], v[54:57], v[76:79], v[140:143]
	s_waitcnt vmcnt(4)
	ds_write_b128 v20, v[204:207]
	v_mfma_f32_16x16x32_f16 v[42:45], v[54:57], v[124:127], v[42:45]
	ds_read_b128 v[54:57], v22 offset:49152
	v_mfma_f32_16x16x32_f16 v[132:135], v[58:61], v[76:79], v[144:147]
	s_nop 2
	ds_read_b128 v[144:147], v22 offset:55296
	v_mfma_f32_16x16x32_f16 v[24:27], v[58:61], v[124:127], v[24:27]
	ds_read_b128 v[58:61], v22 offset:51200
	v_mfma_f32_16x16x32_f16 v[140:143], v[80:83], v[76:79], v[154:157]
	s_waitcnt vmcnt(3)
	ds_write_b128 v17, v[136:139] offset:32768
	v_mfma_f32_16x16x32_f16 v[28:31], v[80:83], v[124:127], v[28:31]
	ds_read_b128 v[80:83], v32 offset:16384
	v_mfma_f32_16x16x32_f16 v[76:79], v[104:107], v[76:79], v[158:161]
	s_waitcnt vmcnt(2)
	ds_write_b128 v18, v[208:211] offset:32768
	v_mfma_f32_16x16x32_f16 v[50:53], v[104:107], v[124:127], v[50:53]
	ds_read_b128 v[104:107], v32 offset:18432
	s_waitcnt lgkmcnt(2)
	v_mfma_f32_16x16x32_f16 v[38:41], v[54:57], v[80:83], v[38:41]
	ds_read_b128 v[124:127], v22 offset:53248
	v_mfma_f32_16x16x32_f16 v[46:49], v[58:61], v[80:83], v[46:49]
	s_waitcnt lgkmcnt(0)
	v_mfma_f32_16x16x32_f16 v[108:111], v[124:127], v[80:83], v[108:111]
	v_mfma_f32_16x16x32_f16 v[72:75], v[144:147], v[80:83], v[72:75]
	v_mfma_f32_16x16x32_f16 v[80:83], v[54:57], v[104:107], v[112:115]
	s_waitcnt vmcnt(1)
	ds_write_b128 v19, v[212:215] offset:32768
	s_waitcnt vmcnt(0)
	ds_write_b128 v20, v[220:223] offset:32768
	v_mfma_f32_16x16x32_f16 v[112:115], v[58:61], v[104:107], v[116:119]
	v_mfma_f32_16x16x32_f16 v[116:119], v[124:127], v[104:107], v[120:123]
	s_nop 2
	ds_read_b128 v[120:123], v32 offset:22528
	v_mfma_f32_16x16x32_f16 v[34:37], v[144:147], v[104:107], v[34:37]
	ds_read_b128 v[104:107], v32 offset:20480
	s_waitcnt lgkmcnt(0)
	v_mfma_f32_16x16x32_f16 v[128:131], v[54:57], v[104:107], v[128:131]
	v_mfma_f32_16x16x32_f16 v[42:45], v[54:57], v[120:123], v[42:45]
	global_load_dwordx4 v[54:57], v[0:1], off offset:384
	v_mfma_f32_16x16x32_f16 v[132:135], v[58:61], v[104:107], v[132:135]
	v_mfma_f32_16x16x32_f16 v[24:27], v[58:61], v[120:123], v[24:27]
	v_mfma_f32_16x16x32_f16 v[140:143], v[124:127], v[104:107], v[140:143]
	v_mfma_f32_16x16x32_f16 v[28:31], v[124:127], v[120:123], v[28:31]
	v_mfma_f32_16x16x32_f16 v[76:79], v[144:147], v[104:107], v[76:79]
	global_load_dwordx4 v[104:107], v[2:3], off offset:384
	global_load_dwordx4 v[154:157], v[4:5], off offset:384
	global_load_dwordx4 v[158:161], v[6:7], off offset:384
	global_load_dwordx4 v[58:61], v[8:9], off offset:384
	global_load_dwordx4 v[188:191], v[10:11], off offset:384
	global_load_dwordx4 v[192:195], v[12:13], off offset:384
	global_load_dwordx4 v[196:199], v[14:15], off offset:384
	s_waitcnt lgkmcnt(0)
	s_barrier
; #define GL_LOAD(s_, kt_) if (VAR != 1) { a##s_##0 = GL_A(0, kt_); a##s_##1 = GL_A(1, kt_); a##s_##2 = GL_A(2, kt_); a##s_##3 = GL_A(3, kt_); b##s_##0 = GL_B(0, kt_); b##s_##1 = GL_B(1, kt_); b##s_##2 = GL_B(2, kt_); b##s_##3 = GL_B(3, kt_); }
; #define LDS_STORE(s_, buf_) if (VAR != 2) { LDS_ST1(sA, 0, buf_, a##s_##0) LDS_ST1(sA, 1, buf_, a##s_##1) LDS_ST1(sA, 2, buf_, a##s_##2) LDS_ST1(sA, 3, buf_, a##s_##3) LDS_ST1(sB, 0, buf_, b##s_##0) LDS_ST1(sB, 1, buf_, b##s_##1) LDS_ST1(sB, 2, buf_, b##s_##2) LDS_ST1(sB, 3, buf_, b##s_##3) }
;     ...
;   GL_LOAD(0, 0)
;   GL_LOAD(1, 1)
;   LDS_STORE(0, 0)
;   if (VAR != 4) __syncthreads();
; #pragma unroll
;   for (int kt = 0; kt < nk; kt += 2) {
;     if (kt + 2 < nk) { GL_LOAD(0, kt + 2) }
;     MMA_TILE(0)
;     LDS_STORE(1, 1)
;     if (VAR != 4) __syncthreads();
;     if (kt + 3 < nk) { GL_LOAD(1, kt + 3) }
;     MMA_TILE(1)
;     if (kt + 2 < nk) { LDS_STORE(0, 0) }
;     if (VAR != 4) __syncthreads();
	v_mfma_f32_16x16x32_f16 v[50:53], v[144:147], v[120:123], v[50:53]
	ds_read_b128 v[124:127], v16 offset:32768
	ds_read_b128 v[136:139], v21
	s_waitcnt lgkmcnt(0)
	v_mfma_f32_16x16x32_f16 v[38:41], v[124:127], v[136:139], v[38:41]
	ds_read_b128 v[120:123], v16 offset:34816
	ds_read_b128 v[144:147], v21 offset:2048
	s_waitcnt lgkmcnt(0)
	v_mfma_f32_16x16x32_f16 v[80:83], v[124:127], v[144:147], v[80:83]
	ds_read_b128 v[162:165], v16 offset:36864
	v_mfma_f32_16x16x32_f16 v[46:49], v[120:123], v[136:139], v[46:49]
	ds_read_b128 v[166:169], v16 offset:38912
	v_mfma_f32_16x16x32_f16 v[112:115], v[120:123], v[144:147], v[112:115]
	s_waitcnt vmcnt(7)
	ds_write_b128 v17, v[54:57] offset:16384
	s_waitcnt lgkmcnt(2)
	v_mfma_f32_16x16x32_f16 v[108:111], v[162:165], v[136:139], v[108:111]
	s_waitcnt vmcnt(6)
	ds_write_b128 v18, v[104:107] offset:16384
	v_mfma_f32_16x16x32_f16 v[116:119], v[162:165], v[144:147], v[116:119]
	s_waitcnt vmcnt(5)
	ds_write_b128 v19, v[154:157] offset:16384
	s_waitcnt lgkmcnt(3)
	v_mfma_f32_16x16x32_f16 v[72:75], v[166:169], v[136:139], v[72:75]
	ds_read_b128 v[136:139], v21 offset:4096
	v_mfma_f32_16x16x32_f16 v[34:37], v[166:169], v[144:147], v[34:37]
	ds_read_b128 v[144:147], v21 offset:6144
	s_waitcnt lgkmcnt(1)
	v_mfma_f32_16x16x32_f16 v[128:131], v[124:127], v[136:139], v[128:131]
	s_waitcnt vmcnt(4)
	ds_write_b128 v20, v[158:161] offset:16384
	s_waitcnt lgkmcnt(1)
	v_mfma_f32_16x16x32_f16 v[42:45], v[124:127], v[144:147], v[42:45]
	ds_read_b128 v[124:127], v22 offset:34816
	v_mfma_f32_16x16x32_f16 v[132:135], v[120:123], v[136:139], v[132:135]
	s_waitcnt vmcnt(3)
	ds_write_b128 v17, v[58:61] offset:49152
	v_mfma_f32_16x16x32_f16 v[24:27], v[120:123], v[144:147], v[24:27]
	ds_read_b128 v[120:123], v22 offset:32768
	v_mfma_f32_16x16x32_f16 v[140:143], v[162:165], v[136:139], v[140:143]
	s_waitcnt vmcnt(2)
	ds_write_b128 v18, v[188:191] offset:49152
	v_mfma_f32_16x16x32_f16 v[28:31], v[162:165], v[144:147], v[28:31]
	ds_read_b128 v[162:165], v22 offset:36864
	v_mfma_f32_16x16x32_f16 v[76:79], v[166:169], v[136:139], v[76:79]
	ds_read_b128 v[136:139], v32
	v_mfma_f32_16x16x32_f16 v[50:53], v[166:169], v[144:147], v[50:53]
	ds_read_b128 v[144:147], v32 offset:2048
	s_waitcnt lgkmcnt(1)
	v_mfma_f32_16x16x32_f16 v[38:41], v[120:123], v[136:139], v[38:41]
	ds_read_b128 v[166:169], v22 offset:38912
	s_waitcnt lgkmcnt(1)
	v_mfma_f32_16x16x32_f16 v[80:83], v[120:123], v[144:147], v[80:83]
	s_waitcnt vmcnt(1)
	ds_write_b128 v19, v[192:195] offset:49152
	v_mfma_f32_16x16x32_f16 v[46:49], v[124:127], v[136:139], v[46:49]
	s_waitcnt vmcnt(0)
	ds_write_b128 v20, v[196:199] offset:49152
	v_mfma_f32_16x16x32_f16 v[112:115], v[124:127], v[144:147], v[112:115]
	v_mfma_f32_16x16x32_f16 v[108:111], v[162:165], v[136:139], v[108:111]
	v_mfma_f32_16x16x32_f16 v[116:119], v[162:165], v[144:147], v[116:119]
	s_waitcnt lgkmcnt(2)
	v_mfma_f32_16x16x32_f16 v[72:75], v[166:169], v[136:139], v[72:75]
	ds_read_b128 v[136:139], v32 offset:4096
	v_mfma_f32_16x16x32_f16 v[34:37], v[166:169], v[144:147], v[34:37]
	ds_read_b128 v[144:147], v32 offset:6144
	s_waitcnt lgkmcnt(1)
	v_mfma_f32_16x16x32_f16 v[128:131], v[120:123], v[136:139], v[128:131]
	s_waitcnt lgkmcnt(0)
	v_mfma_f32_16x16x32_f16 v[42:45], v[120:123], v[144:147], v[42:45]
	global_load_dwordx4 v[120:123], v[0:1], off offset:512
	v_mfma_f32_16x16x32_f16 v[132:135], v[124:127], v[136:139], v[132:135]
	v_mfma_f32_16x16x32_f16 v[24:27], v[124:127], v[144:147], v[24:27]
	v_mfma_f32_16x16x32_f16 v[140:143], v[162:165], v[136:139], v[140:143]
	v_mfma_f32_16x16x32_f16 v[28:31], v[162:165], v[144:147], v[28:31]
	v_mfma_f32_16x16x32_f16 v[76:79], v[166:169], v[136:139], v[76:79]
	global_load_dwordx4 v[136:139], v[2:3], off offset:512
	global_load_dwordx4 v[200:203], v[4:5], off offset:512
	global_load_dwordx4 v[204:207], v[6:7], off offset:512
	global_load_dwordx4 v[124:127], v[8:9], off offset:512
	global_load_dwordx4 v[208:211], v[10:11], off offset:512
	global_load_dwordx4 v[212:215], v[12:13], off offset:512
	global_load_dwordx4 v[220:223], v[14:15], off offset:512
	s_waitcnt lgkmcnt(0)
	s_barrier
	v_mfma_f32_16x16x32_f16 v[50:53], v[166:169], v[144:147], v[50:53]
	ds_read_b128 v[54:57], v16 offset:49152
	ds_read_b128 v[104:107], v21 offset:16384
	s_waitcnt lgkmcnt(0)
	v_mfma_f32_16x16x32_f16 v[38:41], v[54:57], v[104:107], v[38:41]
	ds_read_b128 v[58:61], v16 offset:51200
	ds_read_b128 v[144:147], v21 offset:18432
	s_waitcnt lgkmcnt(0)
	v_mfma_f32_16x16x32_f16 v[80:83], v[54:57], v[144:147], v[80:83]
	ds_read_b128 v[154:157], v16 offset:53248
	v_mfma_f32_16x16x32_f16 v[46:49], v[58:61], v[104:107], v[46:49]
	ds_read_b128 v[158:161], v16 offset:55296
	s_waitcnt lgkmcnt(1)
	v_mfma_f32_16x16x32_f16 v[108:111], v[154:157], v[104:107], v[108:111]
	s_waitcnt lgkmcnt(0)
	v_mfma_f32_16x16x32_f16 v[72:75], v[158:161], v[104:107], v[72:75]
	v_mfma_f32_16x16x32_f16 v[104:107], v[58:61], v[144:147], v[112:115]
	s_waitcnt vmcnt(7)
	ds_write_b128 v17, v[120:123]
	s_waitcnt vmcnt(6)
	ds_write_b128 v18, v[136:139]
	v_mfma_f32_16x16x32_f16 v[112:115], v[154:157], v[144:147], v[116:119]
	s_nop 2
	ds_read_b128 v[116:119], v21 offset:20480
	s_waitcnt vmcnt(5)
	ds_write_b128 v19, v[200:203]
	v_mfma_f32_16x16x32_f16 v[34:37], v[158:161], v[144:147], v[34:37]
	ds_read_b128 v[144:147], v21 offset:22528
	s_waitcnt lgkmcnt(2)
	v_mfma_f32_16x16x32_f16 v[128:131], v[54:57], v[116:119], v[128:131]
	s_waitcnt vmcnt(4)
	ds_write_b128 v20, v[204:207]
	s_waitcnt lgkmcnt(1)
	v_mfma_f32_16x16x32_f16 v[42:45], v[54:57], v[144:147], v[42:45]
	ds_read_b128 v[54:57], v22 offset:49152
	v_mfma_f32_16x16x32_f16 v[132:135], v[58:61], v[116:119], v[132:135]
	s_waitcnt vmcnt(3)
; #define GL_LOAD(s_, kt_) if (VAR != 1) { a##s_##0 = GL_A(0, kt_); a##s_##1 = GL_A(1, kt_); a##s_##2 = GL_A(2, kt_); a##s_##3 = GL_A(3, kt_); b##s_##0 = GL_B(0, kt_); b##s_##1 = GL_B(1, kt_); b##s_##2 = GL_B(2, kt_); b##s_##3 = GL_B(3, kt_); }
; #define LDS_STORE(s_, buf_) if (VAR != 2) { LDS_ST1(sA, 0, buf_, a##s_##0) LDS_ST1(sA, 1, buf_, a##s_##1) LDS_ST1(sA, 2, buf_, a##s_##2) LDS_ST1(sA, 3, buf_, a##s_##3) LDS_ST1(sB, 0, buf_, b##s_##0) LDS_ST1(sB, 1, buf_, b##s_##1) LDS_ST1(sB, 2, buf_, b##s_##2) LDS_ST1(sB, 3, buf_, b##s_##3) }
;     ...
;   GL_LOAD(0, 0)
;   GL_LOAD(1, 1)
;   LDS_STORE(0, 0)
;   if (VAR != 4) __syncthreads();
; #pragma unroll
;   for (int kt = 0; kt < nk; kt += 2) {
;     if (kt + 2 < nk) { GL_LOAD(0, kt + 2) }
;     MMA_TILE(0)
;     LDS_STORE(1, 1)
;     if (VAR != 4) __syncthreads();
;     if (kt + 3 < nk) { GL_LOAD(1, kt + 3) }
;     MMA_TILE(1)
;     if (kt + 2 < nk) { LDS_STORE(0, 0) }
;     if (VAR != 4) __syncthreads();
	ds_write_b128 v17, v[124:127] offset:32768
	v_mfma_f32_16x16x32_f16 v[24:27], v[58:61], v[144:147], v[24:27]
	ds_read_b128 v[58:61], v22 offset:51200
	v_mfma_f32_16x16x32_f16 v[140:143], v[154:157], v[116:119], v[140:143]
	s_waitcnt vmcnt(2)
	ds_write_b128 v18, v[208:211] offset:32768
	v_mfma_f32_16x16x32_f16 v[28:31], v[154:157], v[144:147], v[28:31]
	ds_read_b128 v[154:157], v22 offset:53248
	v_mfma_f32_16x16x32_f16 v[76:79], v[158:161], v[116:119], v[76:79]
	ds_read_b128 v[116:119], v32 offset:16384
	v_mfma_f32_16x16x32_f16 v[50:53], v[158:161], v[144:147], v[50:53]
	ds_read_b128 v[144:147], v32 offset:18432
	s_waitcnt lgkmcnt(1)
	v_mfma_f32_16x16x32_f16 v[38:41], v[54:57], v[116:119], v[38:41]
	ds_read_b128 v[158:161], v22 offset:55296
	s_waitcnt lgkmcnt(1)
	v_mfma_f32_16x16x32_f16 v[80:83], v[54:57], v[144:147], v[80:83]
	s_waitcnt vmcnt(1)
	ds_write_b128 v19, v[212:215] offset:32768
	v_mfma_f32_16x16x32_f16 v[46:49], v[58:61], v[116:119], v[46:49]
	s_waitcnt vmcnt(0)
	ds_write_b128 v20, v[220:223] offset:32768
	v_mfma_f32_16x16x32_f16 v[104:107], v[58:61], v[144:147], v[104:107]
	v_mfma_f32_16x16x32_f16 v[108:111], v[154:157], v[116:119], v[108:111]
	v_mfma_f32_16x16x32_f16 v[112:115], v[154:157], v[144:147], v[112:115]
	s_waitcnt lgkmcnt(2)
	v_mfma_f32_16x16x32_f16 v[72:75], v[158:161], v[116:119], v[72:75]
	ds_read_b128 v[116:119], v32 offset:20480
	v_mfma_f32_16x16x32_f16 v[34:37], v[158:161], v[144:147], v[34:37]
	ds_read_b128 v[144:147], v32 offset:22528
	s_waitcnt lgkmcnt(1)
	v_mfma_f32_16x16x32_f16 v[128:131], v[54:57], v[116:119], v[128:131]
	s_waitcnt lgkmcnt(0)
	v_mfma_f32_16x16x32_f16 v[42:45], v[54:57], v[144:147], v[42:45]
	global_load_dwordx4 v[54:57], v[0:1], off offset:640
	v_mfma_f32_16x16x32_f16 v[132:135], v[58:61], v[116:119], v[132:135]
	v_mfma_f32_16x16x32_f16 v[24:27], v[58:61], v[144:147], v[24:27]
	v_mfma_f32_16x16x32_f16 v[140:143], v[154:157], v[116:119], v[140:143]
	v_mfma_f32_16x16x32_f16 v[28:31], v[154:157], v[144:147], v[28:31]
	v_mfma_f32_16x16x32_f16 v[76:79], v[158:161], v[116:119], v[76:79]
	global_load_dwordx4 v[116:119], v[2:3], off offset:640
	global_load_dwordx4 v[162:165], v[4:5], off offset:640
	global_load_dwordx4 v[166:169], v[6:7], off offset:640
	global_load_dwordx4 v[58:61], v[8:9], off offset:640
	global_load_dwordx4 v[188:191], v[10:11], off offset:640
	global_load_dwordx4 v[192:195], v[12:13], off offset:640
	global_load_dwordx4 v[196:199], v[14:15], off offset:640
	s_waitcnt lgkmcnt(0)
	s_barrier
	v_mfma_f32_16x16x32_f16 v[50:53], v[158:161], v[144:147], v[50:53]
	ds_read_b128 v[120:123], v16 offset:32768
	ds_read_b128 v[136:139], v21
	s_waitcnt lgkmcnt(0)
	v_mfma_f32_16x16x32_f16 v[38:41], v[120:123], v[136:139], v[38:41]
	ds_read_b128 v[124:127], v16 offset:34816
	ds_read_b128 v[144:147], v21 offset:2048
	s_waitcnt lgkmcnt(0)
	v_mfma_f32_16x16x32_f16 v[80:83], v[120:123], v[144:147], v[80:83]
	ds_read_b128 v[154:157], v16 offset:36864
	v_mfma_f32_16x16x32_f16 v[46:49], v[124:127], v[136:139], v[46:49]
	ds_read_b128 v[158:161], v16 offset:38912
	v_mfma_f32_16x16x32_f16 v[104:107], v[124:127], v[144:147], v[104:107]
	s_waitcnt vmcnt(7)
	ds_write_b128 v17, v[54:57] offset:16384
	s_waitcnt lgkmcnt(2)
	v_mfma_f32_16x16x32_f16 v[108:111], v[154:157], v[136:139], v[108:111]
	s_waitcnt vmcnt(6)
	ds_write_b128 v18, v[116:119] offset:16384
	v_mfma_f32_16x16x32_f16 v[112:115], v[154:157], v[144:147], v[112:115]
	s_waitcnt vmcnt(5)
	ds_write_b128 v19, v[162:165] offset:16384
	s_waitcnt lgkmcnt(3)
	v_mfma_f32_16x16x32_f16 v[72:75], v[158:161], v[136:139], v[72:75]
	ds_read_b128 v[136:139], v21 offset:4096
	v_mfma_f32_16x16x32_f16 v[34:37], v[158:161], v[144:147], v[34:37]
	ds_read_b128 v[144:147], v21 offset:6144
	s_waitcnt lgkmcnt(1)
	v_mfma_f32_16x16x32_f16 v[128:131], v[120:123], v[136:139], v[128:131]
	s_waitcnt vmcnt(4)
	ds_write_b128 v20, v[166:169] offset:16384
	s_waitcnt lgkmcnt(1)
	v_mfma_f32_16x16x32_f16 v[42:45], v[120:123], v[144:147], v[42:45]
	ds_read_b128 v[120:123], v22 offset:32768
	v_mfma_f32_16x16x32_f16 v[132:135], v[124:127], v[136:139], v[132:135]
	s_waitcnt vmcnt(3)
	ds_write_b128 v17, v[58:61] offset:49152
	v_mfma_f32_16x16x32_f16 v[24:27], v[124:127], v[144:147], v[24:27]
	ds_read_b128 v[124:127], v22 offset:34816
	v_mfma_f32_16x16x32_f16 v[140:143], v[154:157], v[136:139], v[140:143]
	s_waitcnt vmcnt(2)
	ds_write_b128 v18, v[188:191] offset:49152
	v_mfma_f32_16x16x32_f16 v[28:31], v[154:157], v[144:147], v[28:31]
	ds_read_b128 v[154:157], v22 offset:36864
	v_mfma_f32_16x16x32_f16 v[76:79], v[158:161], v[136:139], v[76:79]
	ds_read_b128 v[136:139], v32
	v_mfma_f32_16x16x32_f16 v[50:53], v[158:161], v[144:147], v[50:53]
	ds_read_b128 v[144:147], v32 offset:2048
	s_waitcnt lgkmcnt(1)
	v_mfma_f32_16x16x32_f16 v[38:41], v[120:123], v[136:139], v[38:41]
	ds_read_b128 v[158:161], v22 offset:38912
	s_waitcnt lgkmcnt(1)
	v_mfma_f32_16x16x32_f16 v[80:83], v[120:123], v[144:147], v[80:83]
	s_waitcnt vmcnt(1)
	ds_write_b128 v19, v[192:195] offset:49152
	v_mfma_f32_16x16x32_f16 v[46:49], v[124:127], v[136:139], v[46:49]
	s_waitcnt vmcnt(0)
	ds_write_b128 v20, v[196:199] offset:49152
	v_mfma_f32_16x16x32_f16 v[104:107], v[124:127], v[144:147], v[104:107]
	v_mfma_f32_16x16x32_f16 v[108:111], v[154:157], v[136:139], v[108:111]
	v_mfma_f32_16x16x32_f16 v[112:115], v[154:157], v[144:147], v[112:115]
	s_waitcnt lgkmcnt(2)
	v_mfma_f32_16x16x32_f16 v[72:75], v[158:161], v[136:139], v[72:75]
	ds_read_b128 v[136:139], v32 offset:4096
	v_mfma_f32_16x16x32_f16 v[34:37], v[158:161], v[144:147], v[34:37]
	ds_read_b128 v[144:147], v32 offset:6144
	s_waitcnt lgkmcnt(1)
	v_mfma_f32_16x16x32_f16 v[128:131], v[120:123], v[136:139], v[128:131]
	s_waitcnt lgkmcnt(0)
	v_mfma_f32_16x16x32_f16 v[42:45], v[120:123], v[144:147], v[42:45]
	global_load_dwordx4 v[120:123], v[0:1], off offset:768
	v_mfma_f32_16x16x32_f16 v[132:135], v[124:127], v[136:139], v[132:135]
	v_mfma_f32_16x16x32_f16 v[24:27], v[124:127], v[144:147], v[24:27]
	v_mfma_f32_16x16x32_f16 v[140:143], v[154:157], v[136:139], v[140:143]
	v_mfma_f32_16x16x32_f16 v[28:31], v[154:157], v[144:147], v[28:31]
	v_mfma_f32_16x16x32_f16 v[76:79], v[158:161], v[136:139], v[76:79]
	global_load_dwordx4 v[136:139], v[2:3], off offset:768
	global_load_dwordx4 v[200:203], v[4:5], off offset:768
	global_load_dwordx4 v[204:207], v[6:7], off offset:768
	global_load_dwordx4 v[124:127], v[8:9], off offset:768
	global_load_dwordx4 v[208:211], v[10:11], off offset:768
	global_load_dwordx4 v[212:215], v[12:13], off offset:768
	global_load_dwordx4 v[220:223], v[14:15], off offset:768
	s_waitcnt lgkmcnt(0)
	s_barrier
; #define GL_LOAD(s_, kt_) if (VAR != 1) { a##s_##0 = GL_A(0, kt_); a##s_##1 = GL_A(1, kt_); a##s_##2 = GL_A(2, kt_); a##s_##3 = GL_A(3, kt_); b##s_##0 = GL_B(0, kt_); b##s_##1 = GL_B(1, kt_); b##s_##2 = GL_B(2, kt_); b##s_##3 = GL_B(3, kt_); }
; #define LDS_STORE(s_, buf_) if (VAR != 2) { LDS_ST1(sA, 0, buf_, a##s_##0) LDS_ST1(sA, 1, buf_, a##s_##1) LDS_ST1(sA, 2, buf_, a##s_##2) LDS_ST1(sA, 3, buf_, a##s_##3) LDS_ST1(sB, 0, buf_, b##s_##0) LDS_ST1(sB, 1, buf_, b##s_##1) LDS_ST1(sB, 2, buf_, b##s_##2) LDS_ST1(sB, 3, buf_, b##s_##3) }
;     ...
;   GL_LOAD(0, 0)
;   GL_LOAD(1, 1)
;   LDS_STORE(0, 0)
;   if (VAR != 4) __syncthreads();
; #pragma unroll
;   for (int kt = 0; kt < nk; kt += 2) {
;     if (kt + 2 < nk) { GL_LOAD(0, kt + 2) }
;     MMA_TILE(0)
;     LDS_STORE(1, 1)
;     if (VAR != 4) __syncthreads();
;     if (kt + 3 < nk) { GL_LOAD(1, kt + 3) }
;     MMA_TILE(1)
;     if (kt + 2 < nk) { LDS_STORE(0, 0) }
;     if (VAR != 4) __syncthreads();
	v_mfma_f32_16x16x32_f16 v[50:53], v[158:161], v[144:147], v[50:53]
	ds_read_b128 v[54:57], v16 offset:49152
	ds_read_b128 v[116:119], v21 offset:16384
	s_waitcnt lgkmcnt(0)
	v_mfma_f32_16x16x32_f16 v[38:41], v[54:57], v[116:119], v[38:41]
	ds_read_b128 v[58:61], v16 offset:51200
	ds_read_b128 v[144:147], v21 offset:18432
	s_waitcnt lgkmcnt(0)
	v_mfma_f32_16x16x32_f16 v[80:83], v[54:57], v[144:147], v[80:83]
	ds_read_b128 v[154:157], v16 offset:53248
	v_mfma_f32_16x16x32_f16 v[46:49], v[58:61], v[116:119], v[46:49]
	ds_read_b128 v[158:161], v16 offset:55296
	v_mfma_f32_16x16x32_f16 v[104:107], v[58:61], v[144:147], v[104:107]
	s_waitcnt vmcnt(7)
	ds_write_b128 v17, v[120:123]
	s_waitcnt lgkmcnt(2)
	v_mfma_f32_16x16x32_f16 v[108:111], v[154:157], v[116:119], v[108:111]
	s_waitcnt vmcnt(6)
	ds_write_b128 v18, v[136:139]
	v_mfma_f32_16x16x32_f16 v[112:115], v[154:157], v[144:147], v[112:115]
	s_waitcnt vmcnt(5)
	ds_write_b128 v19, v[200:203]
	s_waitcnt lgkmcnt(3)
	v_mfma_f32_16x16x32_f16 v[72:75], v[158:161], v[116:119], v[72:75]
	ds_read_b128 v[116:119], v21 offset:20480
	v_mfma_f32_16x16x32_f16 v[34:37], v[158:161], v[144:147], v[34:37]
	ds_read_b128 v[144:147], v21 offset:22528
	s_waitcnt lgkmcnt(1)
	v_mfma_f32_16x16x32_f16 v[128:131], v[54:57], v[116:119], v[128:131]
	s_waitcnt vmcnt(4)
	ds_write_b128 v20, v[204:207]
	s_waitcnt lgkmcnt(1)
	v_mfma_f32_16x16x32_f16 v[42:45], v[54:57], v[144:147], v[42:45]
	ds_read_b128 v[54:57], v22 offset:49152
	v_mfma_f32_16x16x32_f16 v[132:135], v[58:61], v[116:119], v[132:135]
	s_waitcnt vmcnt(3)
	ds_write_b128 v17, v[124:127] offset:32768
	v_mfma_f32_16x16x32_f16 v[24:27], v[58:61], v[144:147], v[24:27]
	ds_read_b128 v[58:61], v22 offset:51200
	v_mfma_f32_16x16x32_f16 v[140:143], v[154:157], v[116:119], v[140:143]
	s_waitcnt vmcnt(2)
	ds_write_b128 v18, v[208:211] offset:32768
	v_mfma_f32_16x16x32_f16 v[28:31], v[154:157], v[144:147], v[28:31]
	ds_read_b128 v[154:157], v22 offset:53248
	v_mfma_f32_16x16x32_f16 v[76:79], v[158:161], v[116:119], v[76:79]
	ds_read_b128 v[116:119], v32 offset:16384
	v_mfma_f32_16x16x32_f16 v[50:53], v[158:161], v[144:147], v[50:53]
	ds_read_b128 v[144:147], v32 offset:18432
	s_waitcnt lgkmcnt(1)
	v_mfma_f32_16x16x32_f16 v[38:41], v[54:57], v[116:119], v[38:41]
	ds_read_b128 v[158:161], v22 offset:55296
	s_waitcnt lgkmcnt(1)
	v_mfma_f32_16x16x32_f16 v[80:83], v[54:57], v[144:147], v[80:83]
	s_waitcnt vmcnt(1)
	ds_write_b128 v19, v[212:215] offset:32768
	v_mfma_f32_16x16x32_f16 v[46:49], v[58:61], v[116:119], v[46:49]
	s_waitcnt vmcnt(0)
	ds_write_b128 v20, v[220:223] offset:32768
	v_mfma_f32_16x16x32_f16 v[104:107], v[58:61], v[144:147], v[104:107]
	v_mfma_f32_16x16x32_f16 v[108:111], v[154:157], v[116:119], v[108:111]
	v_mfma_f32_16x16x32_f16 v[112:115], v[154:157], v[144:147], v[112:115]
	s_waitcnt lgkmcnt(2)
	v_mfma_f32_16x16x32_f16 v[72:75], v[158:161], v[116:119], v[72:75]
	ds_read_b128 v[116:119], v32 offset:20480
	v_mfma_f32_16x16x32_f16 v[34:37], v[158:161], v[144:147], v[34:37]
	ds_read_b128 v[144:147], v32 offset:22528
	s_waitcnt lgkmcnt(1)
	v_mfma_f32_16x16x32_f16 v[128:131], v[54:57], v[116:119], v[128:131]
	s_waitcnt lgkmcnt(0)
	v_mfma_f32_16x16x32_f16 v[42:45], v[54:57], v[144:147], v[42:45]
	global_load_dwordx4 v[54:57], v[0:1], off offset:896
	v_mfma_f32_16x16x32_f16 v[132:135], v[58:61], v[116:119], v[132:135]
	v_mfma_f32_16x16x32_f16 v[24:27], v[58:61], v[144:147], v[24:27]
	v_mfma_f32_16x16x32_f16 v[140:143], v[154:157], v[116:119], v[140:143]
	v_mfma_f32_16x16x32_f16 v[28:31], v[154:157], v[144:147], v[28:31]
	v_mfma_f32_16x16x32_f16 v[76:79], v[158:161], v[116:119], v[76:79]
	global_load_dwordx4 v[116:119], v[2:3], off offset:896
	global_load_dwordx4 v[162:165], v[4:5], off offset:896
	global_load_dwordx4 v[166:169], v[6:7], off offset:896
	global_load_dwordx4 v[58:61], v[8:9], off offset:896
	global_load_dwordx4 v[188:191], v[10:11], off offset:896
	global_load_dwordx4 v[192:195], v[12:13], off offset:896
	global_load_dwordx4 v[196:199], v[14:15], off offset:896
	s_waitcnt lgkmcnt(0)
	s_barrier
	v_mfma_f32_16x16x32_f16 v[50:53], v[158:161], v[144:147], v[50:53]
	ds_read_b128 v[120:123], v16 offset:32768
	ds_read_b128 v[136:139], v21
	s_waitcnt lgkmcnt(0)
	v_mfma_f32_16x16x32_f16 v[38:41], v[120:123], v[136:139], v[38:41]
	ds_read_b128 v[124:127], v16 offset:34816
	ds_read_b128 v[144:147], v21 offset:2048
	s_waitcnt lgkmcnt(0)
	v_mfma_f32_16x16x32_f16 v[80:83], v[120:123], v[144:147], v[80:83]
	ds_read_b128 v[154:157], v16 offset:36864
	v_mfma_f32_16x16x32_f16 v[46:49], v[124:127], v[136:139], v[46:49]
	ds_read_b128 v[158:161], v16 offset:38912
	v_mfma_f32_16x16x32_f16 v[104:107], v[124:127], v[144:147], v[104:107]
	s_waitcnt vmcnt(7)
	ds_write_b128 v17, v[54:57] offset:16384
	s_waitcnt lgkmcnt(2)
	v_mfma_f32_16x16x32_f16 v[108:111], v[154:157], v[136:139], v[108:111]
	s_waitcnt vmcnt(6)
	ds_write_b128 v18, v[116:119] offset:16384
	v_mfma_f32_16x16x32_f16 v[112:115], v[154:157], v[144:147], v[112:115]
	s_waitcnt vmcnt(5)
	ds_write_b128 v19, v[162:165] offset:16384
	s_waitcnt lgkmcnt(3)
	v_mfma_f32_16x16x32_f16 v[72:75], v[158:161], v[136:139], v[72:75]
	ds_read_b128 v[136:139], v21 offset:4096
	v_mfma_f32_16x16x32_f16 v[34:37], v[158:161], v[144:147], v[34:37]
	ds_read_b128 v[144:147], v21 offset:6144
	s_waitcnt lgkmcnt(1)
	v_mfma_f32_16x16x32_f16 v[128:131], v[120:123], v[136:139], v[128:131]
	s_waitcnt vmcnt(4)
	ds_write_b128 v20, v[166:169] offset:16384
	s_waitcnt lgkmcnt(1)
	v_mfma_f32_16x16x32_f16 v[42:45], v[120:123], v[144:147], v[42:45]
	ds_read_b128 v[120:123], v22 offset:32768
	v_mfma_f32_16x16x32_f16 v[132:135], v[124:127], v[136:139], v[132:135]
	s_waitcnt vmcnt(3)
; #define GL_LOAD(s_, kt_) if (VAR != 1) { a##s_##0 = GL_A(0, kt_); a##s_##1 = GL_A(1, kt_); a##s_##2 = GL_A(2, kt_); a##s_##3 = GL_A(3, kt_); b##s_##0 = GL_B(0, kt_); b##s_##1 = GL_B(1, kt_); b##s_##2 = GL_B(2, kt_); b##s_##3 = GL_B(3, kt_); }
; #define LDS_STORE(s_, buf_) if (VAR != 2) { LDS_ST1(sA, 0, buf_, a##s_##0) LDS_ST1(sA, 1, buf_, a##s_##1) LDS_ST1(sA, 2, buf_, a##s_##2) LDS_ST1(sA, 3, buf_, a##s_##3) LDS_ST1(sB, 0, buf_, b##s_##0) LDS_ST1(sB, 1, buf_, b##s_##1) LDS_ST1(sB, 2, buf_, b##s_##2) LDS_ST1(sB, 3, buf_, b##s_##3) }
;     ...
;   GL_LOAD(0, 0)
;   GL_LOAD(1, 1)
;   LDS_STORE(0, 0)
;   if (VAR != 4) __syncthreads();
; #pragma unroll
;   for (int kt = 0; kt < nk; kt += 2) {
;     if (kt + 2 < nk) { GL_LOAD(0, kt + 2) }
;     MMA_TILE(0)
;     LDS_STORE(1, 1)
;     if (VAR != 4) __syncthreads();
;     if (kt + 3 < nk) { GL_LOAD(1, kt + 3) }
;     MMA_TILE(1)
;     if (kt + 2 < nk) { LDS_STORE(0, 0) }
;     if (VAR != 4) __syncthreads();
	ds_write_b128 v17, v[58:61] offset:49152
	v_mfma_f32_16x16x32_f16 v[24:27], v[124:127], v[144:147], v[24:27]
	ds_read_b128 v[124:127], v22 offset:34816
	v_mfma_f32_16x16x32_f16 v[140:143], v[154:157], v[136:139], v[140:143]
	s_waitcnt vmcnt(2)
	ds_write_b128 v18, v[188:191] offset:49152
	v_mfma_f32_16x16x32_f16 v[28:31], v[154:157], v[144:147], v[28:31]
	ds_read_b128 v[154:157], v22 offset:36864
	v_mfma_f32_16x16x32_f16 v[76:79], v[158:161], v[136:139], v[76:79]
	ds_read_b128 v[136:139], v32
	v_mfma_f32_16x16x32_f16 v[50:53], v[158:161], v[144:147], v[50:53]
	ds_read_b128 v[144:147], v32 offset:2048
	s_waitcnt lgkmcnt(1)
	v_mfma_f32_16x16x32_f16 v[38:41], v[120:123], v[136:139], v[38:41]
	ds_read_b128 v[158:161], v22 offset:38912
	s_waitcnt lgkmcnt(1)
	v_mfma_f32_16x16x32_f16 v[80:83], v[120:123], v[144:147], v[80:83]
	s_waitcnt vmcnt(1)
	ds_write_b128 v19, v[192:195] offset:49152
	v_mfma_f32_16x16x32_f16 v[46:49], v[124:127], v[136:139], v[46:49]
	s_waitcnt vmcnt(0)
	ds_write_b128 v20, v[196:199] offset:49152
	v_mfma_f32_16x16x32_f16 v[104:107], v[124:127], v[144:147], v[104:107]
	v_mfma_f32_16x16x32_f16 v[108:111], v[154:157], v[136:139], v[108:111]
	v_mfma_f32_16x16x32_f16 v[112:115], v[154:157], v[144:147], v[112:115]
	s_waitcnt lgkmcnt(2)
	v_mfma_f32_16x16x32_f16 v[72:75], v[158:161], v[136:139], v[72:75]
	ds_read_b128 v[136:139], v32 offset:4096
	v_mfma_f32_16x16x32_f16 v[34:37], v[158:161], v[144:147], v[34:37]
	ds_read_b128 v[144:147], v32 offset:6144
	s_waitcnt lgkmcnt(1)
	v_mfma_f32_16x16x32_f16 v[128:131], v[120:123], v[136:139], v[128:131]
	s_waitcnt lgkmcnt(0)
	v_mfma_f32_16x16x32_f16 v[42:45], v[120:123], v[144:147], v[42:45]
	global_load_dwordx4 v[120:123], v[0:1], off offset:1024
	v_mfma_f32_16x16x32_f16 v[132:135], v[124:127], v[136:139], v[132:135]
	v_mfma_f32_16x16x32_f16 v[24:27], v[124:127], v[144:147], v[24:27]
	v_mfma_f32_16x16x32_f16 v[140:143], v[154:157], v[136:139], v[140:143]
	v_mfma_f32_16x16x32_f16 v[28:31], v[154:157], v[144:147], v[28:31]
	v_mfma_f32_16x16x32_f16 v[76:79], v[158:161], v[136:139], v[76:79]
	global_load_dwordx4 v[136:139], v[2:3], off offset:1024
	global_load_dwordx4 v[200:203], v[4:5], off offset:1024
	global_load_dwordx4 v[204:207], v[6:7], off offset:1024
	global_load_dwordx4 v[124:127], v[8:9], off offset:1024
	global_load_dwordx4 v[208:211], v[10:11], off offset:1024
	global_load_dwordx4 v[212:215], v[12:13], off offset:1024
	global_load_dwordx4 v[220:223], v[14:15], off offset:1024
	s_waitcnt lgkmcnt(0)
	s_barrier
	v_mfma_f32_16x16x32_f16 v[50:53], v[158:161], v[144:147], v[50:53]
	ds_read_b128 v[54:57], v16 offset:49152
	ds_read_b128 v[116:119], v21 offset:16384
	s_waitcnt lgkmcnt(0)
	v_mfma_f32_16x16x32_f16 v[38:41], v[54:57], v[116:119], v[38:41]
	ds_read_b128 v[58:61], v16 offset:51200
	ds_read_b128 v[144:147], v21 offset:18432
	s_waitcnt lgkmcnt(0)
	v_mfma_f32_16x16x32_f16 v[80:83], v[54:57], v[144:147], v[80:83]
	ds_read_b128 v[154:157], v16 offset:53248
	v_mfma_f32_16x16x32_f16 v[46:49], v[58:61], v[116:119], v[46:49]
	ds_read_b128 v[158:161], v16 offset:55296
	v_mfma_f32_16x16x32_f16 v[104:107], v[58:61], v[144:147], v[104:107]
	s_waitcnt vmcnt(7)
	ds_write_b128 v17, v[120:123]
	s_waitcnt lgkmcnt(2)
	v_mfma_f32_16x16x32_f16 v[108:111], v[154:157], v[116:119], v[108:111]
	s_waitcnt vmcnt(6)
	ds_write_b128 v18, v[136:139]
	v_mfma_f32_16x16x32_f16 v[112:115], v[154:157], v[144:147], v[112:115]
	s_waitcnt vmcnt(5)
	ds_write_b128 v19, v[200:203]
	s_waitcnt lgkmcnt(3)
	v_mfma_f32_16x16x32_f16 v[72:75], v[158:161], v[116:119], v[72:75]
	ds_read_b128 v[116:119], v21 offset:20480
	v_mfma_f32_16x16x32_f16 v[34:37], v[158:161], v[144:147], v[34:37]
	ds_read_b128 v[144:147], v21 offset:22528
	s_waitcnt lgkmcnt(1)
	v_mfma_f32_16x16x32_f16 v[128:131], v[54:57], v[116:119], v[128:131]
	s_waitcnt vmcnt(4)
	ds_write_b128 v20, v[204:207]
	s_waitcnt lgkmcnt(1)
	v_mfma_f32_16x16x32_f16 v[42:45], v[54:57], v[144:147], v[42:45]
	ds_read_b128 v[54:57], v22 offset:49152
	v_mfma_f32_16x16x32_f16 v[132:135], v[58:61], v[116:119], v[132:135]
	s_waitcnt vmcnt(3)
	ds_write_b128 v17, v[124:127] offset:32768
	v_mfma_f32_16x16x32_f16 v[24:27], v[58:61], v[144:147], v[24:27]
	ds_read_b128 v[58:61], v22 offset:51200
	v_mfma_f32_16x16x32_f16 v[140:143], v[154:157], v[116:119], v[140:143]
	s_waitcnt vmcnt(2)
	ds_write_b128 v18, v[208:211] offset:32768
	v_mfma_f32_16x16x32_f16 v[28:31], v[154:157], v[144:147], v[28:31]
	ds_read_b128 v[154:157], v22 offset:53248
	v_mfma_f32_16x16x32_f16 v[76:79], v[158:161], v[116:119], v[76:79]
	ds_read_b128 v[116:119], v32 offset:16384
	v_mfma_f32_16x16x32_f16 v[50:53], v[158:161], v[144:147], v[50:53]
	ds_read_b128 v[144:147], v32 offset:18432
	s_waitcnt lgkmcnt(1)
	v_mfma_f32_16x16x32_f16 v[38:41], v[54:57], v[116:119], v[38:41]
	ds_read_b128 v[158:161], v22 offset:55296
	s_waitcnt lgkmcnt(1)
	v_mfma_f32_16x16x32_f16 v[80:83], v[54:57], v[144:147], v[80:83]
	s_waitcnt vmcnt(1)
	ds_write_b128 v19, v[212:215] offset:32768
	v_mfma_f32_16x16x32_f16 v[46:49], v[58:61], v[116:119], v[46:49]
	s_waitcnt vmcnt(0)
	ds_write_b128 v20, v[220:223] offset:32768
	v_mfma_f32_16x16x32_f16 v[104:107], v[58:61], v[144:147], v[104:107]
	v_mfma_f32_16x16x32_f16 v[108:111], v[154:157], v[116:119], v[108:111]
	v_mfma_f32_16x16x32_f16 v[112:115], v[154:157], v[144:147], v[112:115]
	s_waitcnt lgkmcnt(2)
	v_mfma_f32_16x16x32_f16 v[72:75], v[158:161], v[116:119], v[72:75]
	ds_read_b128 v[116:119], v32 offset:20480
	v_mfma_f32_16x16x32_f16 v[34:37], v[158:161], v[144:147], v[34:37]
	ds_read_b128 v[144:147], v32 offset:22528
	s_waitcnt lgkmcnt(1)
	v_mfma_f32_16x16x32_f16 v[128:131], v[54:57], v[116:119], v[128:131]
	s_waitcnt lgkmcnt(0)
	v_mfma_f32_16x16x32_f16 v[42:45], v[54:57], v[144:147], v[42:45]
	global_load_dwordx4 v[54:57], v[0:1], off offset:1152
	v_mfma_f32_16x16x32_f16 v[132:135], v[58:61], v[116:119], v[132:135]
	v_mfma_f32_16x16x32_f16 v[24:27], v[58:61], v[144:147], v[24:27]
	v_mfma_f32_16x16x32_f16 v[140:143], v[154:157], v[116:119], v[140:143]
	v_mfma_f32_16x16x32_f16 v[28:31], v[154:157], v[144:147], v[28:31]
	v_mfma_f32_16x16x32_f16 v[76:79], v[158:161], v[116:119], v[76:79]
	global_load_dwordx4 v[116:119], v[2:3], off offset:1152
	global_load_dwordx4 v[162:165], v[4:5], off offset:1152
	global_load_dwordx4 v[166:169], v[6:7], off offset:1152
	global_load_dwordx4 v[58:61], v[8:9], off offset:1152
	global_load_dwordx4 v[188:191], v[10:11], off offset:1152
	global_load_dwordx4 v[192:195], v[12:13], off offset:1152
	global_load_dwordx4 v[196:199], v[14:15], off offset:1152
	s_waitcnt lgkmcnt(0)
	s_barrier
; #define GL_LOAD(s_, kt_) if (VAR != 1) { a##s_##0 = GL_A(0, kt_); a##s_##1 = GL_A(1, kt_); a##s_##2 = GL_A(2, kt_); a##s_##3 = GL_A(3, kt_); b##s_##0 = GL_B(0, kt_); b##s_##1 = GL_B(1, kt_); b##s_##2 = GL_B(2, kt_); b##s_##3 = GL_B(3, kt_); }
; #define LDS_STORE(s_, buf_) if (VAR != 2) { LDS_ST1(sA, 0, buf_, a##s_##0) LDS_ST1(sA, 1, buf_, a##s_##1) LDS_ST1(sA, 2, buf_, a##s_##2) LDS_ST1(sA, 3, buf_, a##s_##3) LDS_ST1(sB, 0, buf_, b##s_##0) LDS_ST1(sB, 1, buf_, b##s_##1) LDS_ST1(sB, 2, buf_, b##s_##2) LDS_ST1(sB, 3, buf_, b##s_##3) }
;     ...
;   GL_LOAD(0, 0)
;   GL_LOAD(1, 1)
;   LDS_STORE(0, 0)
;   if (VAR != 4) __syncthreads();
; #pragma unroll
;   for (int kt = 0; kt < nk; kt += 2) {
;     if (kt + 2 < nk) { GL_LOAD(0, kt + 2) }
;     MMA_TILE(0)
;     LDS_STORE(1, 1)
;     if (VAR != 4) __syncthreads();
;     if (kt + 3 < nk) { GL_LOAD(1, kt + 3) }
;     MMA_TILE(1)
;     if (kt + 2 < nk) { LDS_STORE(0, 0) }
;     if (VAR != 4) __syncthreads();
	v_mfma_f32_16x16x32_f16 v[50:53], v[158:161], v[144:147], v[50:53]
	ds_read_b128 v[120:123], v16 offset:32768
	ds_read_b128 v[136:139], v21
	s_waitcnt lgkmcnt(0)
	v_mfma_f32_16x16x32_f16 v[38:41], v[120:123], v[136:139], v[38:41]
	ds_read_b128 v[124:127], v16 offset:34816
	ds_read_b128 v[144:147], v21 offset:2048
	s_waitcnt lgkmcnt(0)
	v_mfma_f32_16x16x32_f16 v[80:83], v[120:123], v[144:147], v[80:83]
	ds_read_b128 v[154:157], v16 offset:36864
	v_mfma_f32_16x16x32_f16 v[46:49], v[124:127], v[136:139], v[46:49]
	ds_read_b128 v[158:161], v16 offset:38912
	v_mfma_f32_16x16x32_f16 v[104:107], v[124:127], v[144:147], v[104:107]
	s_waitcnt vmcnt(7)
	ds_write_b128 v17, v[54:57] offset:16384
	s_waitcnt lgkmcnt(2)
	v_mfma_f32_16x16x32_f16 v[108:111], v[154:157], v[136:139], v[108:111]
	s_waitcnt vmcnt(6)
	ds_write_b128 v18, v[116:119] offset:16384
	v_mfma_f32_16x16x32_f16 v[112:115], v[154:157], v[144:147], v[112:115]
	s_waitcnt vmcnt(5)
	ds_write_b128 v19, v[162:165] offset:16384
	s_waitcnt lgkmcnt(3)
	v_mfma_f32_16x16x32_f16 v[72:75], v[158:161], v[136:139], v[72:75]
	ds_read_b128 v[136:139], v21 offset:4096
	v_mfma_f32_16x16x32_f16 v[34:37], v[158:161], v[144:147], v[34:37]
	ds_read_b128 v[144:147], v21 offset:6144
	s_waitcnt lgkmcnt(1)
	v_mfma_f32_16x16x32_f16 v[128:131], v[120:123], v[136:139], v[128:131]
	s_waitcnt vmcnt(4)
	ds_write_b128 v20, v[166:169] offset:16384
	s_waitcnt lgkmcnt(1)
	v_mfma_f32_16x16x32_f16 v[42:45], v[120:123], v[144:147], v[42:45]
	ds_read_b128 v[120:123], v22 offset:32768
	v_mfma_f32_16x16x32_f16 v[132:135], v[124:127], v[136:139], v[132:135]
	s_waitcnt vmcnt(3)
	ds_write_b128 v17, v[58:61] offset:49152
	v_mfma_f32_16x16x32_f16 v[24:27], v[124:127], v[144:147], v[24:27]
	ds_read_b128 v[124:127], v22 offset:34816
	v_mfma_f32_16x16x32_f16 v[140:143], v[154:157], v[136:139], v[140:143]
	s_waitcnt vmcnt(2)
	ds_write_b128 v18, v[188:191] offset:49152
	v_mfma_f32_16x16x32_f16 v[28:31], v[154:157], v[144:147], v[28:31]
	ds_read_b128 v[154:157], v22 offset:36864
	v_mfma_f32_16x16x32_f16 v[76:79], v[158:161], v[136:139], v[76:79]
	ds_read_b128 v[136:139], v32
	v_mfma_f32_16x16x32_f16 v[50:53], v[158:161], v[144:147], v[50:53]
	ds_read_b128 v[144:147], v32 offset:2048
	s_waitcnt lgkmcnt(1)
	v_mfma_f32_16x16x32_f16 v[38:41], v[120:123], v[136:139], v[38:41]
	ds_read_b128 v[158:161], v22 offset:38912
	s_waitcnt lgkmcnt(1)
	v_mfma_f32_16x16x32_f16 v[80:83], v[120:123], v[144:147], v[80:83]
	s_waitcnt vmcnt(1)
	ds_write_b128 v19, v[192:195] offset:49152
	v_mfma_f32_16x16x32_f16 v[46:49], v[124:127], v[136:139], v[46:49]
	s_waitcnt vmcnt(0)
	ds_write_b128 v20, v[196:199] offset:49152
	v_mfma_f32_16x16x32_f16 v[104:107], v[124:127], v[144:147], v[104:107]
	v_mfma_f32_16x16x32_f16 v[108:111], v[154:157], v[136:139], v[108:111]
	v_mfma_f32_16x16x32_f16 v[112:115], v[154:157], v[144:147], v[112:115]
	s_waitcnt lgkmcnt(2)
	v_mfma_f32_16x16x32_f16 v[72:75], v[158:161], v[136:139], v[72:75]
	ds_read_b128 v[136:139], v32 offset:4096
	v_mfma_f32_16x16x32_f16 v[34:37], v[158:161], v[144:147], v[34:37]
	ds_read_b128 v[144:147], v32 offset:6144
	s_waitcnt lgkmcnt(1)
	v_mfma_f32_16x16x32_f16 v[128:131], v[120:123], v[136:139], v[128:131]
	s_waitcnt lgkmcnt(0)
	v_mfma_f32_16x16x32_f16 v[42:45], v[120:123], v[144:147], v[42:45]
	global_load_dwordx4 v[120:123], v[0:1], off offset:1280
	v_mfma_f32_16x16x32_f16 v[132:135], v[124:127], v[136:139], v[132:135]
	v_mfma_f32_16x16x32_f16 v[24:27], v[124:127], v[144:147], v[24:27]
	v_mfma_f32_16x16x32_f16 v[140:143], v[154:157], v[136:139], v[140:143]
	v_mfma_f32_16x16x32_f16 v[28:31], v[154:157], v[144:147], v[28:31]
	v_mfma_f32_16x16x32_f16 v[76:79], v[158:161], v[136:139], v[76:79]
	global_load_dwordx4 v[136:139], v[2:3], off offset:1280
	global_load_dwordx4 v[200:203], v[4:5], off offset:1280
	global_load_dwordx4 v[204:207], v[6:7], off offset:1280
	global_load_dwordx4 v[124:127], v[8:9], off offset:1280
	global_load_dwordx4 v[208:211], v[10:11], off offset:1280
	global_load_dwordx4 v[212:215], v[12:13], off offset:1280
	global_load_dwordx4 v[220:223], v[14:15], off offset:1280
	s_waitcnt lgkmcnt(0)
	s_barrier
	v_mfma_f32_16x16x32_f16 v[50:53], v[158:161], v[144:147], v[50:53]
	ds_read_b128 v[54:57], v16 offset:49152
	ds_read_b128 v[116:119], v21 offset:16384
	s_waitcnt lgkmcnt(0)
	v_mfma_f32_16x16x32_f16 v[38:41], v[54:57], v[116:119], v[38:41]
	ds_read_b128 v[58:61], v16 offset:51200
	ds_read_b128 v[144:147], v21 offset:18432
	s_waitcnt lgkmcnt(0)
	v_mfma_f32_16x16x32_f16 v[80:83], v[54:57], v[144:147], v[80:83]
	ds_read_b128 v[154:157], v16 offset:53248
	v_mfma_f32_16x16x32_f16 v[46:49], v[58:61], v[116:119], v[46:49]
	ds_read_b128 v[158:161], v16 offset:55296
	v_mfma_f32_16x16x32_f16 v[104:107], v[58:61], v[144:147], v[104:107]
	s_waitcnt vmcnt(7)
	ds_write_b128 v17, v[120:123]
	s_waitcnt lgkmcnt(2)
	v_mfma_f32_16x16x32_f16 v[108:111], v[154:157], v[116:119], v[108:111]
	s_waitcnt vmcnt(6)
	ds_write_b128 v18, v[136:139]
	v_mfma_f32_16x16x32_f16 v[112:115], v[154:157], v[144:147], v[112:115]
	s_waitcnt vmcnt(5)
	ds_write_b128 v19, v[200:203]
	s_waitcnt lgkmcnt(3)
	v_mfma_f32_16x16x32_f16 v[72:75], v[158:161], v[116:119], v[72:75]
	ds_read_b128 v[116:119], v21 offset:20480
	v_mfma_f32_16x16x32_f16 v[34:37], v[158:161], v[144:147], v[34:37]
	ds_read_b128 v[144:147], v21 offset:22528
	s_waitcnt lgkmcnt(1)
	v_mfma_f32_16x16x32_f16 v[128:131], v[54:57], v[116:119], v[128:131]
	s_waitcnt vmcnt(4)
	ds_write_b128 v20, v[204:207]
	s_waitcnt lgkmcnt(1)
	v_mfma_f32_16x16x32_f16 v[42:45], v[54:57], v[144:147], v[42:45]
	ds_read_b128 v[54:57], v22 offset:49152
	v_mfma_f32_16x16x32_f16 v[132:135], v[58:61], v[116:119], v[132:135]
	s_waitcnt vmcnt(3)
; #define GL_LOAD(s_, kt_) if (VAR != 1) { a##s_##0 = GL_A(0, kt_); a##s_##1 = GL_A(1, kt_); a##s_##2 = GL_A(2, kt_); a##s_##3 = GL_A(3, kt_); b##s_##0 = GL_B(0, kt_); b##s_##1 = GL_B(1, kt_); b##s_##2 = GL_B(2, kt_); b##s_##3 = GL_B(3, kt_); }
; #define LDS_STORE(s_, buf_) if (VAR != 2) { LDS_ST1(sA, 0, buf_, a##s_##0) LDS_ST1(sA, 1, buf_, a##s_##1) LDS_ST1(sA, 2, buf_, a##s_##2) LDS_ST1(sA, 3, buf_, a##s_##3) LDS_ST1(sB, 0, buf_, b##s_##0) LDS_ST1(sB, 1, buf_, b##s_##1) LDS_ST1(sB, 2, buf_, b##s_##2) LDS_ST1(sB, 3, buf_, b##s_##3) }
;     ...
;   GL_LOAD(0, 0)
;   GL_LOAD(1, 1)
;   LDS_STORE(0, 0)
;   if (VAR != 4) __syncthreads();
; #pragma unroll
;   for (int kt = 0; kt < nk; kt += 2) {
;     if (kt + 2 < nk) { GL_LOAD(0, kt + 2) }
;     MMA_TILE(0)
;     LDS_STORE(1, 1)
;     if (VAR != 4) __syncthreads();
;     if (kt + 3 < nk) { GL_LOAD(1, kt + 3) }
;     MMA_TILE(1)
;     if (kt + 2 < nk) { LDS_STORE(0, 0) }
;     if (VAR != 4) __syncthreads();
	ds_write_b128 v17, v[124:127] offset:32768
	v_mfma_f32_16x16x32_f16 v[24:27], v[58:61], v[144:147], v[24:27]
	ds_read_b128 v[58:61], v22 offset:51200
	v_mfma_f32_16x16x32_f16 v[140:143], v[154:157], v[116:119], v[140:143]
	s_waitcnt vmcnt(2)
	ds_write_b128 v18, v[208:211] offset:32768
	v_mfma_f32_16x16x32_f16 v[28:31], v[154:157], v[144:147], v[28:31]
	ds_read_b128 v[154:157], v22 offset:53248
	v_mfma_f32_16x16x32_f16 v[76:79], v[158:161], v[116:119], v[76:79]
	ds_read_b128 v[116:119], v32 offset:16384
	v_mfma_f32_16x16x32_f16 v[50:53], v[158:161], v[144:147], v[50:53]
	ds_read_b128 v[144:147], v32 offset:18432
	s_waitcnt lgkmcnt(1)
	v_mfma_f32_16x16x32_f16 v[38:41], v[54:57], v[116:119], v[38:41]
	ds_read_b128 v[158:161], v22 offset:55296
	s_waitcnt lgkmcnt(1)
	v_mfma_f32_16x16x32_f16 v[80:83], v[54:57], v[144:147], v[80:83]
	s_waitcnt vmcnt(1)
	ds_write_b128 v19, v[212:215] offset:32768
	v_mfma_f32_16x16x32_f16 v[46:49], v[58:61], v[116:119], v[46:49]
	s_waitcnt vmcnt(0)
	ds_write_b128 v20, v[220:223] offset:32768
	v_mfma_f32_16x16x32_f16 v[104:107], v[58:61], v[144:147], v[104:107]
	v_mfma_f32_16x16x32_f16 v[108:111], v[154:157], v[116:119], v[108:111]
	v_mfma_f32_16x16x32_f16 v[112:115], v[154:157], v[144:147], v[112:115]
	s_waitcnt lgkmcnt(2)
	v_mfma_f32_16x16x32_f16 v[72:75], v[158:161], v[116:119], v[72:75]
	ds_read_b128 v[116:119], v32 offset:20480
	v_mfma_f32_16x16x32_f16 v[34:37], v[158:161], v[144:147], v[34:37]
	ds_read_b128 v[144:147], v32 offset:22528
	s_waitcnt lgkmcnt(1)
	v_mfma_f32_16x16x32_f16 v[128:131], v[54:57], v[116:119], v[128:131]
	s_waitcnt lgkmcnt(0)
	v_mfma_f32_16x16x32_f16 v[42:45], v[54:57], v[144:147], v[42:45]
	global_load_dwordx4 v[54:57], v[0:1], off offset:1408
	v_mfma_f32_16x16x32_f16 v[132:135], v[58:61], v[116:119], v[132:135]
	v_mfma_f32_16x16x32_f16 v[24:27], v[58:61], v[144:147], v[24:27]
	v_mfma_f32_16x16x32_f16 v[140:143], v[154:157], v[116:119], v[140:143]
	v_mfma_f32_16x16x32_f16 v[28:31], v[154:157], v[144:147], v[28:31]
	v_mfma_f32_16x16x32_f16 v[76:79], v[158:161], v[116:119], v[76:79]
	global_load_dwordx4 v[116:119], v[2:3], off offset:1408
	global_load_dwordx4 v[162:165], v[4:5], off offset:1408
	global_load_dwordx4 v[166:169], v[6:7], off offset:1408
	global_load_dwordx4 v[58:61], v[8:9], off offset:1408
	global_load_dwordx4 v[188:191], v[10:11], off offset:1408
	global_load_dwordx4 v[192:195], v[12:13], off offset:1408
	global_load_dwordx4 v[196:199], v[14:15], off offset:1408
	s_waitcnt lgkmcnt(0)
	s_barrier
	v_mfma_f32_16x16x32_f16 v[50:53], v[158:161], v[144:147], v[50:53]
	ds_read_b128 v[120:123], v16 offset:32768
	ds_read_b128 v[136:139], v21
	s_waitcnt lgkmcnt(0)
	v_mfma_f32_16x16x32_f16 v[38:41], v[120:123], v[136:139], v[38:41]
	ds_read_b128 v[124:127], v16 offset:34816
	ds_read_b128 v[144:147], v21 offset:2048
	s_waitcnt lgkmcnt(0)
	v_mfma_f32_16x16x32_f16 v[80:83], v[120:123], v[144:147], v[80:83]
	ds_read_b128 v[154:157], v16 offset:36864
	v_mfma_f32_16x16x32_f16 v[46:49], v[124:127], v[136:139], v[46:49]
	ds_read_b128 v[158:161], v16 offset:38912
	v_mfma_f32_16x16x32_f16 v[104:107], v[124:127], v[144:147], v[104:107]
	s_waitcnt vmcnt(7)
	ds_write_b128 v17, v[54:57] offset:16384
	s_waitcnt lgkmcnt(2)
	v_mfma_f32_16x16x32_f16 v[108:111], v[154:157], v[136:139], v[108:111]
	s_waitcnt vmcnt(6)
	ds_write_b128 v18, v[116:119] offset:16384
	v_mfma_f32_16x16x32_f16 v[112:115], v[154:157], v[144:147], v[112:115]
	s_waitcnt vmcnt(5)
	ds_write_b128 v19, v[162:165] offset:16384
	s_waitcnt lgkmcnt(3)
	v_mfma_f32_16x16x32_f16 v[72:75], v[158:161], v[136:139], v[72:75]
	ds_read_b128 v[136:139], v21 offset:4096
	v_mfma_f32_16x16x32_f16 v[34:37], v[158:161], v[144:147], v[34:37]
	ds_read_b128 v[144:147], v21 offset:6144
	s_waitcnt lgkmcnt(1)
	v_mfma_f32_16x16x32_f16 v[128:131], v[120:123], v[136:139], v[128:131]
	s_waitcnt vmcnt(4)
	ds_write_b128 v20, v[166:169] offset:16384
	s_waitcnt lgkmcnt(1)
	v_mfma_f32_16x16x32_f16 v[42:45], v[120:123], v[144:147], v[42:45]
	ds_read_b128 v[120:123], v22 offset:32768
	v_mfma_f32_16x16x32_f16 v[132:135], v[124:127], v[136:139], v[132:135]
	s_waitcnt vmcnt(3)
	ds_write_b128 v17, v[58:61] offset:49152
	v_mfma_f32_16x16x32_f16 v[24:27], v[124:127], v[144:147], v[24:27]
	ds_read_b128 v[124:127], v22 offset:34816
	v_mfma_f32_16x16x32_f16 v[140:143], v[154:157], v[136:139], v[140:143]
	s_waitcnt vmcnt(2)
	ds_write_b128 v18, v[188:191] offset:49152
	v_mfma_f32_16x16x32_f16 v[28:31], v[154:157], v[144:147], v[28:31]
	ds_read_b128 v[154:157], v22 offset:36864
	v_mfma_f32_16x16x32_f16 v[76:79], v[158:161], v[136:139], v[76:79]
	ds_read_b128 v[136:139], v32
	v_mfma_f32_16x16x32_f16 v[50:53], v[158:161], v[144:147], v[50:53]
	ds_read_b128 v[144:147], v32 offset:2048
	s_waitcnt lgkmcnt(1)
	v_mfma_f32_16x16x32_f16 v[38:41], v[120:123], v[136:139], v[38:41]
	ds_read_b128 v[158:161], v22 offset:38912
	s_waitcnt lgkmcnt(1)
	v_mfma_f32_16x16x32_f16 v[80:83], v[120:123], v[144:147], v[80:83]
	s_waitcnt vmcnt(1)
	ds_write_b128 v19, v[192:195] offset:49152
	v_mfma_f32_16x16x32_f16 v[46:49], v[124:127], v[136:139], v[46:49]
	s_waitcnt vmcnt(0)
	ds_write_b128 v20, v[196:199] offset:49152
	v_mfma_f32_16x16x32_f16 v[104:107], v[124:127], v[144:147], v[104:107]
	v_mfma_f32_16x16x32_f16 v[108:111], v[154:157], v[136:139], v[108:111]
	v_mfma_f32_16x16x32_f16 v[112:115], v[154:157], v[144:147], v[112:115]
	s_waitcnt lgkmcnt(2)
	v_mfma_f32_16x16x32_f16 v[72:75], v[158:161], v[136:139], v[72:75]
	ds_read_b128 v[136:139], v32 offset:4096
	v_mfma_f32_16x16x32_f16 v[34:37], v[158:161], v[144:147], v[34:37]
	ds_read_b128 v[144:147], v32 offset:6144
	s_waitcnt lgkmcnt(1)
	v_mfma_f32_16x16x32_f16 v[128:131], v[120:123], v[136:139], v[128:131]
	s_waitcnt lgkmcnt(0)
	v_mfma_f32_16x16x32_f16 v[42:45], v[120:123], v[144:147], v[42:45]
	global_load_dwordx4 v[120:123], v[0:1], off offset:1536
	v_mfma_f32_16x16x32_f16 v[132:135], v[124:127], v[136:139], v[132:135]
	v_mfma_f32_16x16x32_f16 v[24:27], v[124:127], v[144:147], v[24:27]
	v_mfma_f32_16x16x32_f16 v[140:143], v[154:157], v[136:139], v[140:143]
	v_mfma_f32_16x16x32_f16 v[28:31], v[154:157], v[144:147], v[28:31]
	v_mfma_f32_16x16x32_f16 v[76:79], v[158:161], v[136:139], v[76:79]
	global_load_dwordx4 v[136:139], v[2:3], off offset:1536
	global_load_dwordx4 v[200:203], v[4:5], off offset:1536
	global_load_dwordx4 v[204:207], v[6:7], off offset:1536
	global_load_dwordx4 v[124:127], v[8:9], off offset:1536
	global_load_dwordx4 v[208:211], v[10:11], off offset:1536
	global_load_dwordx4 v[212:215], v[12:13], off offset:1536
	global_load_dwordx4 v[220:223], v[14:15], off offset:1536
	s_waitcnt lgkmcnt(0)
	s_barrier
; #define GL_LOAD(s_, kt_) if (VAR != 1) { a##s_##0 = GL_A(0, kt_); a##s_##1 = GL_A(1, kt_); a##s_##2 = GL_A(2, kt_); a##s_##3 = GL_A(3, kt_); b##s_##0 = GL_B(0, kt_); b##s_##1 = GL_B(1, kt_); b##s_##2 = GL_B(2, kt_); b##s_##3 = GL_B(3, kt_); }
; #define LDS_STORE(s_, buf_) if (VAR != 2) { LDS_ST1(sA, 0, buf_, a##s_##0) LDS_ST1(sA, 1, buf_, a##s_##1) LDS_ST1(sA, 2, buf_, a##s_##2) LDS_ST1(sA, 3, buf_, a##s_##3) LDS_ST1(sB, 0, buf_, b##s_##0) LDS_ST1(sB, 1, buf_, b##s_##1) LDS_ST1(sB, 2, buf_, b##s_##2) LDS_ST1(sB, 3, buf_, b##s_##3) }
;     ...
;   GL_LOAD(0, 0)
;   GL_LOAD(1, 1)
;   LDS_STORE(0, 0)
;   if (VAR != 4) __syncthreads();
; #pragma unroll
;   for (int kt = 0; kt < nk; kt += 2) {
;     if (kt + 2 < nk) { GL_LOAD(0, kt + 2) }
;     MMA_TILE(0)
;     LDS_STORE(1, 1)
;     if (VAR != 4) __syncthreads();
;     if (kt + 3 < nk) { GL_LOAD(1, kt + 3) }
;     MMA_TILE(1)
;     if (kt + 2 < nk) { LDS_STORE(0, 0) }
;     if (VAR != 4) __syncthreads();
	v_mfma_f32_16x16x32_f16 v[50:53], v[158:161], v[144:147], v[50:53]
	ds_read_b128 v[54:57], v16 offset:49152
	ds_read_b128 v[116:119], v21 offset:16384
	s_waitcnt lgkmcnt(0)
	v_mfma_f32_16x16x32_f16 v[38:41], v[54:57], v[116:119], v[38:41]
	ds_read_b128 v[58:61], v16 offset:51200
	ds_read_b128 v[144:147], v21 offset:18432
	s_waitcnt lgkmcnt(0)
	v_mfma_f32_16x16x32_f16 v[80:83], v[54:57], v[144:147], v[80:83]
	ds_read_b128 v[154:157], v16 offset:53248
	v_mfma_f32_16x16x32_f16 v[46:49], v[58:61], v[116:119], v[46:49]
	ds_read_b128 v[158:161], v16 offset:55296
	v_mfma_f32_16x16x32_f16 v[104:107], v[58:61], v[144:147], v[104:107]
	s_waitcnt vmcnt(7)
	ds_write_b128 v17, v[120:123]
	s_waitcnt lgkmcnt(2)
	v_mfma_f32_16x16x32_f16 v[108:111], v[154:157], v[116:119], v[108:111]
	s_waitcnt vmcnt(6)
	ds_write_b128 v18, v[136:139]
	v_mfma_f32_16x16x32_f16 v[112:115], v[154:157], v[144:147], v[112:115]
	s_waitcnt vmcnt(5)
	ds_write_b128 v19, v[200:203]
	s_waitcnt lgkmcnt(3)
	v_mfma_f32_16x16x32_f16 v[72:75], v[158:161], v[116:119], v[72:75]
	ds_read_b128 v[116:119], v21 offset:20480
	v_mfma_f32_16x16x32_f16 v[34:37], v[158:161], v[144:147], v[34:37]
	ds_read_b128 v[144:147], v21 offset:22528
	s_waitcnt lgkmcnt(1)
	v_mfma_f32_16x16x32_f16 v[128:131], v[54:57], v[116:119], v[128:131]
	s_waitcnt vmcnt(4)
	ds_write_b128 v20, v[204:207]
	s_waitcnt lgkmcnt(1)
	v_mfma_f32_16x16x32_f16 v[42:45], v[54:57], v[144:147], v[42:45]
	ds_read_b128 v[54:57], v22 offset:49152
	v_mfma_f32_16x16x32_f16 v[132:135], v[58:61], v[116:119], v[132:135]
	s_waitcnt vmcnt(3)
	ds_write_b128 v17, v[124:127] offset:32768
	v_mfma_f32_16x16x32_f16 v[24:27], v[58:61], v[144:147], v[24:27]
	ds_read_b128 v[58:61], v22 offset:51200
	v_mfma_f32_16x16x32_f16 v[140:143], v[154:157], v[116:119], v[140:143]
	s_waitcnt vmcnt(2)
	ds_write_b128 v18, v[208:211] offset:32768
	v_mfma_f32_16x16x32_f16 v[28:31], v[154:157], v[144:147], v[28:31]
	ds_read_b128 v[154:157], v22 offset:53248
	v_mfma_f32_16x16x32_f16 v[76:79], v[158:161], v[116:119], v[76:79]
	ds_read_b128 v[116:119], v32 offset:16384
	v_mfma_f32_16x16x32_f16 v[50:53], v[158:161], v[144:147], v[50:53]
	ds_read_b128 v[144:147], v32 offset:18432
	s_waitcnt lgkmcnt(1)
	v_mfma_f32_16x16x32_f16 v[38:41], v[54:57], v[116:119], v[38:41]
	ds_read_b128 v[158:161], v22 offset:55296
	s_waitcnt lgkmcnt(1)
	v_mfma_f32_16x16x32_f16 v[80:83], v[54:57], v[144:147], v[80:83]
	s_waitcnt vmcnt(1)
	ds_write_b128 v19, v[212:215] offset:32768
	v_mfma_f32_16x16x32_f16 v[46:49], v[58:61], v[116:119], v[46:49]
	s_waitcnt vmcnt(0)
	ds_write_b128 v20, v[220:223] offset:32768
	v_mfma_f32_16x16x32_f16 v[104:107], v[58:61], v[144:147], v[104:107]
	v_mfma_f32_16x16x32_f16 v[108:111], v[154:157], v[116:119], v[108:111]
	v_mfma_f32_16x16x32_f16 v[112:115], v[154:157], v[144:147], v[112:115]
	s_waitcnt lgkmcnt(2)
	v_mfma_f32_16x16x32_f16 v[72:75], v[158:161], v[116:119], v[72:75]
	ds_read_b128 v[116:119], v32 offset:20480
	v_mfma_f32_16x16x32_f16 v[34:37], v[158:161], v[144:147], v[34:37]
	ds_read_b128 v[144:147], v32 offset:22528
	s_waitcnt lgkmcnt(1)
	v_mfma_f32_16x16x32_f16 v[128:131], v[54:57], v[116:119], v[128:131]
	s_waitcnt lgkmcnt(0)
	v_mfma_f32_16x16x32_f16 v[42:45], v[54:57], v[144:147], v[42:45]
	global_load_dwordx4 v[54:57], v[0:1], off offset:1664
	v_mfma_f32_16x16x32_f16 v[132:135], v[58:61], v[116:119], v[132:135]
	v_mfma_f32_16x16x32_f16 v[24:27], v[58:61], v[144:147], v[24:27]
	v_mfma_f32_16x16x32_f16 v[140:143], v[154:157], v[116:119], v[140:143]
	v_mfma_f32_16x16x32_f16 v[28:31], v[154:157], v[144:147], v[28:31]
	v_mfma_f32_16x16x32_f16 v[76:79], v[158:161], v[116:119], v[76:79]
	global_load_dwordx4 v[116:119], v[2:3], off offset:1664
	global_load_dwordx4 v[162:165], v[4:5], off offset:1664
	global_load_dwordx4 v[166:169], v[6:7], off offset:1664
	global_load_dwordx4 v[58:61], v[8:9], off offset:1664
	global_load_dwordx4 v[188:191], v[10:11], off offset:1664
	global_load_dwordx4 v[192:195], v[12:13], off offset:1664
	global_load_dwordx4 v[196:199], v[14:15], off offset:1664
	s_waitcnt lgkmcnt(0)
	s_barrier
	v_mfma_f32_16x16x32_f16 v[50:53], v[158:161], v[144:147], v[50:53]
	ds_read_b128 v[120:123], v16 offset:32768
	ds_read_b128 v[136:139], v21
	s_waitcnt lgkmcnt(0)
	v_mfma_f32_16x16x32_f16 v[38:41], v[120:123], v[136:139], v[38:41]
	ds_read_b128 v[124:127], v16 offset:34816
	ds_read_b128 v[144:147], v21 offset:2048
	s_waitcnt lgkmcnt(0)
	v_mfma_f32_16x16x32_f16 v[80:83], v[120:123], v[144:147], v[80:83]
	ds_read_b128 v[154:157], v16 offset:36864
	v_mfma_f32_16x16x32_f16 v[46:49], v[124:127], v[136:139], v[46:49]
	ds_read_b128 v[158:161], v16 offset:38912
	v_mfma_f32_16x16x32_f16 v[104:107], v[124:127], v[144:147], v[104:107]
	s_waitcnt vmcnt(7)
	ds_write_b128 v17, v[54:57] offset:16384
	s_waitcnt lgkmcnt(2)
	v_mfma_f32_16x16x32_f16 v[108:111], v[154:157], v[136:139], v[108:111]
	s_waitcnt vmcnt(6)
	ds_write_b128 v18, v[116:119] offset:16384
	v_mfma_f32_16x16x32_f16 v[112:115], v[154:157], v[144:147], v[112:115]
	s_waitcnt vmcnt(5)
	ds_write_b128 v19, v[162:165] offset:16384
	s_waitcnt lgkmcnt(3)
	v_mfma_f32_16x16x32_f16 v[72:75], v[158:161], v[136:139], v[72:75]
	ds_read_b128 v[136:139], v21 offset:4096
	v_mfma_f32_16x16x32_f16 v[34:37], v[158:161], v[144:147], v[34:37]
	ds_read_b128 v[144:147], v21 offset:6144
	s_waitcnt lgkmcnt(1)
	v_mfma_f32_16x16x32_f16 v[128:131], v[120:123], v[136:139], v[128:131]
	s_waitcnt vmcnt(4)
	ds_write_b128 v20, v[166:169] offset:16384
	s_waitcnt lgkmcnt(1)
	v_mfma_f32_16x16x32_f16 v[42:45], v[120:123], v[144:147], v[42:45]
	ds_read_b128 v[120:123], v22 offset:32768
	v_mfma_f32_16x16x32_f16 v[132:135], v[124:127], v[136:139], v[132:135]
	s_waitcnt vmcnt(3)
; #define GL_LOAD(s_, kt_) if (VAR != 1) { a##s_##0 = GL_A(0, kt_); a##s_##1 = GL_A(1, kt_); a##s_##2 = GL_A(2, kt_); a##s_##3 = GL_A(3, kt_); b##s_##0 = GL_B(0, kt_); b##s_##1 = GL_B(1, kt_); b##s_##2 = GL_B(2, kt_); b##s_##3 = GL_B(3, kt_); }
; #define LDS_STORE(s_, buf_) if (VAR != 2) { LDS_ST1(sA, 0, buf_, a##s_##0) LDS_ST1(sA, 1, buf_, a##s_##1) LDS_ST1(sA, 2, buf_, a##s_##2) LDS_ST1(sA, 3, buf_, a##s_##3) LDS_ST1(sB, 0, buf_, b##s_##0) LDS_ST1(sB, 1, buf_, b##s_##1) LDS_ST1(sB, 2, buf_, b##s_##2) LDS_ST1(sB, 3, buf_, b##s_##3) }
;     ...
;   GL_LOAD(0, 0)
;   GL_LOAD(1, 1)
;   LDS_STORE(0, 0)
;   if (VAR != 4) __syncthreads();
; #pragma unroll
;   for (int kt = 0; kt < nk; kt += 2) {
;     if (kt + 2 < nk) { GL_LOAD(0, kt + 2) }
;     MMA_TILE(0)
;     LDS_STORE(1, 1)
;     if (VAR != 4) __syncthreads();
;     if (kt + 3 < nk) { GL_LOAD(1, kt + 3) }
;     MMA_TILE(1)
;     if (kt + 2 < nk) { LDS_STORE(0, 0) }
;     if (VAR != 4) __syncthreads();
	ds_write_b128 v17, v[58:61] offset:49152
	v_mfma_f32_16x16x32_f16 v[24:27], v[124:127], v[144:147], v[24:27]
	ds_read_b128 v[124:127], v22 offset:34816
	v_mfma_f32_16x16x32_f16 v[140:143], v[154:157], v[136:139], v[140:143]
	s_waitcnt vmcnt(2)
	ds_write_b128 v18, v[188:191] offset:49152
	v_mfma_f32_16x16x32_f16 v[28:31], v[154:157], v[144:147], v[28:31]
	ds_read_b128 v[154:157], v22 offset:36864
	v_mfma_f32_16x16x32_f16 v[76:79], v[158:161], v[136:139], v[76:79]
	ds_read_b128 v[136:139], v32
	v_mfma_f32_16x16x32_f16 v[50:53], v[158:161], v[144:147], v[50:53]
	ds_read_b128 v[144:147], v32 offset:2048
	s_waitcnt lgkmcnt(1)
	v_mfma_f32_16x16x32_f16 v[38:41], v[120:123], v[136:139], v[38:41]
	ds_read_b128 v[158:161], v22 offset:38912
	s_waitcnt lgkmcnt(1)
	v_mfma_f32_16x16x32_f16 v[80:83], v[120:123], v[144:147], v[80:83]
	s_waitcnt vmcnt(1)
	ds_write_b128 v19, v[192:195] offset:49152
	v_mfma_f32_16x16x32_f16 v[46:49], v[124:127], v[136:139], v[46:49]
	s_waitcnt vmcnt(0)
	ds_write_b128 v20, v[196:199] offset:49152
	v_mfma_f32_16x16x32_f16 v[104:107], v[124:127], v[144:147], v[104:107]
	v_mfma_f32_16x16x32_f16 v[108:111], v[154:157], v[136:139], v[108:111]
	v_mfma_f32_16x16x32_f16 v[112:115], v[154:157], v[144:147], v[112:115]
	s_waitcnt lgkmcnt(2)
	v_mfma_f32_16x16x32_f16 v[72:75], v[158:161], v[136:139], v[72:75]
	ds_read_b128 v[136:139], v32 offset:4096
	v_mfma_f32_16x16x32_f16 v[34:37], v[158:161], v[144:147], v[34:37]
	ds_read_b128 v[144:147], v32 offset:6144
	s_waitcnt lgkmcnt(1)
	v_mfma_f32_16x16x32_f16 v[128:131], v[120:123], v[136:139], v[128:131]
	s_waitcnt lgkmcnt(0)
	v_mfma_f32_16x16x32_f16 v[42:45], v[120:123], v[144:147], v[42:45]
	global_load_dwordx4 v[120:123], v[0:1], off offset:1792
	v_mfma_f32_16x16x32_f16 v[132:135], v[124:127], v[136:139], v[132:135]
	v_mfma_f32_16x16x32_f16 v[24:27], v[124:127], v[144:147], v[24:27]
	v_mfma_f32_16x16x32_f16 v[140:143], v[154:157], v[136:139], v[140:143]
	v_mfma_f32_16x16x32_f16 v[28:31], v[154:157], v[144:147], v[28:31]
	v_mfma_f32_16x16x32_f16 v[76:79], v[158:161], v[136:139], v[76:79]
	global_load_dwordx4 v[136:139], v[2:3], off offset:1792
	global_load_dwordx4 v[200:203], v[4:5], off offset:1792
	global_load_dwordx4 v[204:207], v[6:7], off offset:1792
	global_load_dwordx4 v[124:127], v[8:9], off offset:1792
	global_load_dwordx4 v[208:211], v[10:11], off offset:1792
	global_load_dwordx4 v[212:215], v[12:13], off offset:1792
	global_load_dwordx4 v[220:223], v[14:15], off offset:1792
	s_waitcnt lgkmcnt(0)
	s_barrier
	v_mfma_f32_16x16x32_f16 v[50:53], v[158:161], v[144:147], v[50:53]
	ds_read_b128 v[54:57], v16 offset:49152
	ds_read_b128 v[116:119], v21 offset:16384
	s_waitcnt lgkmcnt(0)
	v_mfma_f32_16x16x32_f16 v[38:41], v[54:57], v[116:119], v[38:41]
	ds_read_b128 v[58:61], v16 offset:51200
	ds_read_b128 v[144:147], v21 offset:18432
	s_waitcnt lgkmcnt(0)
	v_mfma_f32_16x16x32_f16 v[80:83], v[54:57], v[144:147], v[80:83]
	ds_read_b128 v[154:157], v16 offset:53248
	v_mfma_f32_16x16x32_f16 v[46:49], v[58:61], v[116:119], v[46:49]
	ds_read_b128 v[158:161], v16 offset:55296
	v_mfma_f32_16x16x32_f16 v[104:107], v[58:61], v[144:147], v[104:107]
	s_waitcnt vmcnt(7)
	ds_write_b128 v17, v[120:123]
	s_waitcnt lgkmcnt(2)
	v_mfma_f32_16x16x32_f16 v[108:111], v[154:157], v[116:119], v[108:111]
	s_waitcnt vmcnt(6)
	ds_write_b128 v18, v[136:139]
	v_mfma_f32_16x16x32_f16 v[112:115], v[154:157], v[144:147], v[112:115]
	s_waitcnt vmcnt(5)
	ds_write_b128 v19, v[200:203]
	s_waitcnt lgkmcnt(3)
	v_mfma_f32_16x16x32_f16 v[72:75], v[158:161], v[116:119], v[72:75]
	ds_read_b128 v[116:119], v21 offset:20480
	v_mfma_f32_16x16x32_f16 v[34:37], v[158:161], v[144:147], v[34:37]
	ds_read_b128 v[144:147], v21 offset:22528
	s_waitcnt lgkmcnt(1)
	v_mfma_f32_16x16x32_f16 v[128:131], v[54:57], v[116:119], v[128:131]
	s_waitcnt vmcnt(4)
	ds_write_b128 v20, v[204:207]
	s_waitcnt lgkmcnt(1)
	v_mfma_f32_16x16x32_f16 v[42:45], v[54:57], v[144:147], v[42:45]
	ds_read_b128 v[54:57], v22 offset:49152
	v_mfma_f32_16x16x32_f16 v[132:135], v[58:61], v[116:119], v[132:135]
	s_waitcnt vmcnt(3)
	ds_write_b128 v17, v[124:127] offset:32768
	v_mfma_f32_16x16x32_f16 v[24:27], v[58:61], v[144:147], v[24:27]
	ds_read_b128 v[58:61], v22 offset:51200
	v_mfma_f32_16x16x32_f16 v[140:143], v[154:157], v[116:119], v[140:143]
	s_waitcnt vmcnt(2)
	ds_write_b128 v18, v[208:211] offset:32768
	v_mfma_f32_16x16x32_f16 v[28:31], v[154:157], v[144:147], v[28:31]
	ds_read_b128 v[154:157], v22 offset:53248
	v_mfma_f32_16x16x32_f16 v[76:79], v[158:161], v[116:119], v[76:79]
	ds_read_b128 v[116:119], v32 offset:16384
	v_mfma_f32_16x16x32_f16 v[50:53], v[158:161], v[144:147], v[50:53]
	ds_read_b128 v[144:147], v32 offset:18432
	s_waitcnt lgkmcnt(1)
	v_mfma_f32_16x16x32_f16 v[38:41], v[54:57], v[116:119], v[38:41]
	ds_read_b128 v[158:161], v22 offset:55296
	s_waitcnt lgkmcnt(1)
	v_mfma_f32_16x16x32_f16 v[80:83], v[54:57], v[144:147], v[80:83]
	s_waitcnt vmcnt(1)
	ds_write_b128 v19, v[212:215] offset:32768
	v_mfma_f32_16x16x32_f16 v[46:49], v[58:61], v[116:119], v[46:49]
	s_waitcnt vmcnt(0)
	ds_write_b128 v20, v[220:223] offset:32768
	v_mfma_f32_16x16x32_f16 v[104:107], v[58:61], v[144:147], v[104:107]
	v_mfma_f32_16x16x32_f16 v[108:111], v[154:157], v[116:119], v[108:111]
	v_mfma_f32_16x16x32_f16 v[112:115], v[154:157], v[144:147], v[112:115]
	s_waitcnt lgkmcnt(2)
	v_mfma_f32_16x16x32_f16 v[72:75], v[158:161], v[116:119], v[72:75]
	ds_read_b128 v[116:119], v32 offset:20480
	v_mfma_f32_16x16x32_f16 v[34:37], v[158:161], v[144:147], v[34:37]
	ds_read_b128 v[144:147], v32 offset:22528
	s_waitcnt lgkmcnt(1)
	v_mfma_f32_16x16x32_f16 v[128:131], v[54:57], v[116:119], v[128:131]
	s_waitcnt lgkmcnt(0)
	v_mfma_f32_16x16x32_f16 v[42:45], v[54:57], v[144:147], v[42:45]
	global_load_dwordx4 v[54:57], v[0:1], off offset:1920
	global_load_dwordx4 v[0:3], v[2:3], off offset:1920
	v_mfma_f32_16x16x32_f16 v[132:135], v[58:61], v[116:119], v[132:135]
	v_mfma_f32_16x16x32_f16 v[24:27], v[58:61], v[144:147], v[24:27]
	v_mfma_f32_16x16x32_f16 v[140:143], v[154:157], v[116:119], v[140:143]
	v_mfma_f32_16x16x32_f16 v[28:31], v[154:157], v[144:147], v[28:31]
	v_mfma_f32_16x16x32_f16 v[76:79], v[158:161], v[116:119], v[76:79]
	global_load_dwordx4 v[116:119], v[4:5], off offset:1920
	global_load_dwordx4 v[4:7], v[6:7], off offset:1920
	global_load_dwordx4 v[58:61], v[8:9], off offset:1920
	global_load_dwordx4 v[8:11], v[10:11], off offset:1920
	global_load_dwordx4 v[162:165], v[12:13], off offset:1920
	global_load_dwordx4 v[12:15], v[14:15], off offset:1920
	s_waitcnt lgkmcnt(0)
	s_barrier
; #define GL_LOAD(s_, kt_) if (VAR != 1) { a##s_##0 = GL_A(0, kt_); a##s_##1 = GL_A(1, kt_); a##s_##2 = GL_A(2, kt_); a##s_##3 = GL_A(3, kt_); b##s_##0 = GL_B(0, kt_); b##s_##1 = GL_B(1, kt_); b##s_##2 = GL_B(2, kt_); b##s_##3 = GL_B(3, kt_); }
; #define LDS_STORE(s_, buf_) if (VAR != 2) { LDS_ST1(sA, 0, buf_, a##s_##0) LDS_ST1(sA, 1, buf_, a##s_##1) LDS_ST1(sA, 2, buf_, a##s_##2) LDS_ST1(sA, 3, buf_, a##s_##3) LDS_ST1(sB, 0, buf_, b##s_##0) LDS_ST1(sB, 1, buf_, b##s_##1) LDS_ST1(sB, 2, buf_, b##s_##2) LDS_ST1(sB, 3, buf_, b##s_##3) }
;     ...
;   GL_LOAD(0, 0)
;   GL_LOAD(1, 1)
;   LDS_STORE(0, 0)
;   if (VAR != 4) __syncthreads();
; #pragma unroll
;   for (int kt = 0; kt < nk; kt += 2) {
;     if (kt + 2 < nk) { GL_LOAD(0, kt + 2) }
;     MMA_TILE(0)
;     LDS_STORE(1, 1)
;     if (VAR != 4) __syncthreads();
;     if (kt + 3 < nk) { GL_LOAD(1, kt + 3) }
;     MMA_TILE(1)
;     if (kt + 2 < nk) { LDS_STORE(0, 0) }
;     if (VAR != 4) __syncthreads();
	ds_read_b128 v[120:123], v16 offset:32768
	v_mfma_f32_16x16x32_f16 v[50:53], v[158:161], v[144:147], v[50:53]
	ds_read_b128 v[124:127], v16 offset:34816
	ds_read_b128 v[136:139], v21
	ds_read_b128 v[144:147], v21 offset:2048
	ds_read_b128 v[154:157], v16 offset:36864
	ds_read_b128 v[158:161], v16 offset:38912
	s_waitcnt lgkmcnt(3)
	v_mfma_f32_16x16x32_f16 v[38:41], v[120:123], v[136:139], v[38:41]
	v_mfma_f32_16x16x32_f16 v[46:49], v[124:127], v[136:139], v[46:49]
	s_waitcnt lgkmcnt(1)
	v_mfma_f32_16x16x32_f16 v[108:111], v[154:157], v[136:139], v[108:111]
	s_waitcnt lgkmcnt(0)
	v_mfma_f32_16x16x32_f16 v[72:75], v[158:161], v[136:139], v[72:75]
	v_mfma_f32_16x16x32_f16 v[80:83], v[120:123], v[144:147], v[80:83]
	v_mfma_f32_16x16x32_f16 v[104:107], v[124:127], v[144:147], v[104:107]
	v_mfma_f32_16x16x32_f16 v[112:115], v[154:157], v[144:147], v[112:115]
	v_mfma_f32_16x16x32_f16 v[34:37], v[158:161], v[144:147], v[34:37]
	ds_read_b128 v[136:139], v21 offset:4096
	ds_read_b128 v[144:147], v21 offset:6144
	s_waitcnt lgkmcnt(1)
	v_mfma_f32_16x16x32_f16 v[128:131], v[120:123], v[136:139], v[128:131]
	v_mfma_f32_16x16x32_f16 v[132:135], v[124:127], v[136:139], v[132:135]
	v_mfma_f32_16x16x32_f16 v[140:143], v[154:157], v[136:139], v[140:143]
	v_mfma_f32_16x16x32_f16 v[76:79], v[158:161], v[136:139], v[76:79]
	s_waitcnt lgkmcnt(0)
	v_mfma_f32_16x16x32_f16 v[42:45], v[120:123], v[144:147], v[42:45]
	ds_read_b128 v[120:123], v22 offset:32768
	v_mfma_f32_16x16x32_f16 v[24:27], v[124:127], v[144:147], v[24:27]
	v_mfma_f32_16x16x32_f16 v[28:31], v[154:157], v[144:147], v[28:31]
	v_mfma_f32_16x16x32_f16 v[50:53], v[158:161], v[144:147], v[50:53]
	ds_read_b128 v[124:127], v22 offset:34816
	ds_read_b128 v[136:139], v32
	ds_read_b128 v[144:147], v32 offset:2048
	ds_read_b128 v[154:157], v22 offset:36864
	ds_read_b128 v[158:161], v22 offset:38912
	s_waitcnt lgkmcnt(3)
	v_mfma_f32_16x16x32_f16 v[38:41], v[120:123], v[136:139], v[38:41]
	v_mfma_f32_16x16x32_f16 v[46:49], v[124:127], v[136:139], v[46:49]
	s_waitcnt lgkmcnt(1)
	v_mfma_f32_16x16x32_f16 v[108:111], v[154:157], v[136:139], v[108:111]
	s_waitcnt lgkmcnt(0)
	v_mfma_f32_16x16x32_f16 v[72:75], v[158:161], v[136:139], v[72:75]
	v_mfma_f32_16x16x32_f16 v[80:83], v[120:123], v[144:147], v[80:83]
	v_mfma_f32_16x16x32_f16 v[104:107], v[124:127], v[144:147], v[104:107]
	v_mfma_f32_16x16x32_f16 v[112:115], v[154:157], v[144:147], v[112:115]
	v_mfma_f32_16x16x32_f16 v[34:37], v[158:161], v[144:147], v[34:37]
	ds_read_b128 v[136:139], v32 offset:4096
	ds_read_b128 v[144:147], v32 offset:6144
	s_waitcnt vmcnt(7)
	ds_write_b128 v17, v[54:57] offset:16384
	s_waitcnt vmcnt(6)
	ds_write_b128 v18, v[0:3] offset:16384
	s_waitcnt vmcnt(5)
	ds_write_b128 v19, v[116:119] offset:16384
	s_waitcnt vmcnt(4)
	ds_write_b128 v20, v[4:7] offset:16384
	s_waitcnt vmcnt(3)
	ds_write_b128 v17, v[58:61] offset:49152
	s_waitcnt vmcnt(2)
	ds_write_b128 v18, v[8:11] offset:49152
	s_waitcnt vmcnt(1)
	ds_write_b128 v19, v[162:165] offset:49152
	s_waitcnt vmcnt(0)
	ds_write_b128 v20, v[12:15] offset:49152
	s_waitcnt lgkmcnt(0)
	s_barrier
; #define GL_LOAD(s_, kt_) if (VAR != 1) { a##s_##0 = GL_A(0, kt_); a##s_##1 = GL_A(1, kt_); a##s_##2 = GL_A(2, kt_); a##s_##3 = GL_A(3, kt_); b##s_##0 = GL_B(0, kt_); b##s_##1 = GL_B(1, kt_); b##s_##2 = GL_B(2, kt_); b##s_##3 = GL_B(3, kt_); }
; #define LDS_STORE(s_, buf_) if (VAR != 2) { LDS_ST1(sA, 0, buf_, a##s_##0) LDS_ST1(sA, 1, buf_, a##s_##1) LDS_ST1(sA, 2, buf_, a##s_##2) LDS_ST1(sA, 3, buf_, a##s_##3) LDS_ST1(sB, 0, buf_, b##s_##0) LDS_ST1(sB, 1, buf_, b##s_##1) LDS_ST1(sB, 2, buf_, b##s_##2) LDS_ST1(sB, 3, buf_, b##s_##3) }
;     ...
;   GL_LOAD(0, 0)
;   GL_LOAD(1, 1)
;   LDS_STORE(0, 0)
;   if (VAR != 4) __syncthreads();
; #pragma unroll
;   for (int kt = 0; kt < nk; kt += 2) {
;     if (kt + 2 < nk) { GL_LOAD(0, kt + 2) }
;     MMA_TILE(0)
;     LDS_STORE(1, 1)
;     if (VAR != 4) __syncthreads();
;     if (kt + 3 < nk) { GL_LOAD(1, kt + 3) }
;     MMA_TILE(1)
;     if (kt + 2 < nk) { LDS_STORE(0, 0) }
;     if (VAR != 4) __syncthreads();
; DI void phase_proj(const Params& P, int l, char* smem) {
;     ...
;       gemm_kloop<false, true, 16>(acc, xb + (size_t)m0 * DM, DM, Wt + (size_t)n0 * DM, DM, smem);
; #pragma unroll
;       for (int mt = 0; mt < 4; ++mt)
; #pragma unroll
;         for (int nt = 0; nt < 4; ++nt) acc[mt][nt] *= rs[mt];
;       const float* gain = nullptr; bool rope = false; float sc = 1.f; bool sig = false;
;       constexpr float QS = 0.125f * 1.4426950408889634f;
;       if (col0 < C_AK) { gain = P.a_q_norm + l * 64; rope = true; sc = QS; }
;       else if (col0 < C_BQ) { gain = P.a_k_norm + l * 64; rope = true; }
;       else if (col0 < C_BK) { sc = QS; }
;       else if (col0 < C_CQ) { }
;       else if (col0 < C_CK) { gain = P.c_q_norm + l * 64; rope = true; sc = QS; }
;       else if (col0 < C_IQ) { gain = P.c_k_norm + l * 64; rope = true; }
;       else if (col0 < C_IK) { rope = true; sc = 0.125f; }
;       else if (col0 < C_IW) { gain = P.idx_k_norm + l * 64; rope = true; }
;       else if (col0 < C_GL) { sc = 0.5f; }
;       else { sig = true; }
	ds_read_b128 v[0:3], v16 offset:49152
	v_mfma_f32_16x16x32_f16 v[4:7], v[158:161], v[144:147], v[50:53]
	ds_read_b128 v[8:11], v16 offset:51200
	ds_read_b128 v[12:15], v21 offset:16384
	s_nop 0
	ds_read_b128 v[50:53], v21 offset:18432
	ds_read_b128 v[54:57], v16 offset:53248
	ds_read_b128 v[16:19], v16 offset:55296
	s_waitcnt lgkmcnt(3)
	v_mfma_f32_16x16x32_f16 v[38:41], v[0:3], v[12:15], v[38:41]
	v_mfma_f32_16x16x32_f16 v[46:49], v[8:11], v[12:15], v[46:49]
	s_waitcnt lgkmcnt(1)
	v_mfma_f32_16x16x32_f16 v[58:61], v[54:57], v[12:15], v[108:111]
	s_waitcnt lgkmcnt(0)
	v_mfma_f32_16x16x32_f16 v[12:15], v[16:19], v[12:15], v[72:75]
	v_mfma_f32_16x16x32_f16 v[72:75], v[0:3], v[50:53], v[80:83]
	v_mfma_f32_16x16x32_f16 v[80:83], v[8:11], v[50:53], v[104:107]
	v_mfma_f32_16x16x32_f16 v[104:107], v[54:57], v[50:53], v[112:115]
	v_mfma_f32_16x16x32_f16 v[34:37], v[16:19], v[50:53], v[34:37]
	ds_read_b128 v[50:53], v21 offset:20480
	ds_read_b128 v[108:111], v21 offset:22528
	v_mfma_f32_16x16x32_f16 v[128:131], v[120:123], v[136:139], v[128:131]
	v_mfma_f32_16x16x32_f16 v[132:135], v[124:127], v[136:139], v[132:135]
	v_mfma_f32_16x16x32_f16 v[140:143], v[154:157], v[136:139], v[140:143]
	v_mfma_f32_16x16x32_f16 v[42:45], v[120:123], v[144:147], v[42:45]
	v_mfma_f32_16x16x32_f16 v[24:27], v[124:127], v[144:147], v[24:27]
	v_mfma_f32_16x16x32_f16 v[28:31], v[154:157], v[144:147], v[28:31]
	v_mfma_f32_16x16x32_f16 v[76:79], v[158:161], v[136:139], v[76:79]
	s_waitcnt lgkmcnt(1)
	v_mfma_f32_16x16x32_f16 v[112:115], v[0:3], v[50:53], v[128:131]
	v_mfma_f32_16x16x32_f16 v[116:119], v[8:11], v[50:53], v[132:135]
	v_mfma_f32_16x16x32_f16 v[120:123], v[54:57], v[50:53], v[140:143]
	s_nop 1
	ds_read_b128 v[132:135], v22 offset:49152
	s_waitcnt lgkmcnt(1)
	v_mfma_f32_16x16x32_f16 v[0:3], v[0:3], v[108:111], v[42:45]
	v_mfma_f32_16x16x32_f16 v[124:127], v[8:11], v[108:111], v[24:27]
	v_mfma_f32_16x16x32_f16 v[128:131], v[54:57], v[108:111], v[28:31]
	v_mfma_f32_16x16x32_f16 v[108:111], v[16:19], v[108:111], v[4:7]
	ds_read_b128 v[136:139], v22 offset:51200
	s_nop 1
	ds_read_b128 v[4:7], v32 offset:16384
	ds_read_b128 v[8:11], v32 offset:18432
	ds_read_b128 v[140:143], v22 offset:53248
	ds_read_b128 v[144:147], v22 offset:55296
	v_mfma_f32_16x16x32_f16 v[76:79], v[16:19], v[50:53], v[76:79]
	s_waitcnt lgkmcnt(3)
	v_mfma_f32_16x16x32_f16 v[28:31], v[132:135], v[4:7], v[38:41]
	v_mfma_f32_16x16x32_f16 v[24:27], v[136:139], v[4:7], v[46:49]
	s_waitcnt lgkmcnt(1)
	v_mfma_f32_16x16x32_f16 v[60:63], v[140:143], v[4:7], v[58:61]
	s_waitcnt lgkmcnt(0)
	v_mfma_f32_16x16x32_f16 v[56:59], v[144:147], v[4:7], v[12:15]
	v_mfma_f32_16x16x32_f16 v[48:51], v[144:147], v[8:11], v[34:37]
	ds_read_b128 v[4:7], v32 offset:20480
	s_nop 1
	ds_read_b128 v[32:35], v32 offset:22528
	s_waitcnt lgkmcnt(0)
	s_barrier
	s_setprio 0
	v_mfma_f32_16x16x32_f16 v[20:23], v[132:135], v[8:11], v[72:75]
	v_mfma_f32_16x16x32_f16 v[16:19], v[136:139], v[8:11], v[80:83]
	s_nop 1
	v_mov_b32_e32 v72, 0x3e38aa3b
	v_mfma_f32_16x16x32_f16 v[52:55], v[140:143], v[8:11], v[104:107]
	v_mfma_f32_16x16x32_f16 v[12:15], v[132:135], v[4:7], v[112:115]
	v_mfma_f32_16x16x32_f16 v[8:11], v[136:139], v[4:7], v[116:119]
	v_mfma_f32_16x16x32_f16 v[44:47], v[140:143], v[4:7], v[120:123]
	v_mfma_f32_16x16x32_f16 v[40:43], v[144:147], v[4:7], v[76:79]
	s_nop 1
	v_mov_b64_e32 v[122:123], s[14:15]
	v_mfma_f32_16x16x32_f16 v[4:7], v[132:135], v[32:35], v[0:3]
	v_mfma_f32_16x16x32_f16 v[0:3], v[136:139], v[32:35], v[124:127]
	v_mfma_f32_16x16x32_f16 v[36:39], v[140:143], v[32:35], v[128:131]
	v_mfma_f32_16x16x32_f16 v[32:35], v[144:147], v[32:35], v[108:111]
	s_and_saveexec_b64 s[4:5], vcc
	s_cbranch_execz .LBB0_654
	s_cmpk_lt_u32 s16, 0x400
	s_cbranch_scc1 .LBB0_649
	s_cmpk_lt_u32 s16, 0x600
	s_cbranch_scc1 .LBB0_650
	s_cmpk_lt_u32 s16, 0x800
	s_cbranch_scc1 .LBB0_651
	s_cmpk_lt_u32 s16, 0xa00
	s_cbranch_scc1 .LBB0_693
	s_cmpk_lt_u32 s16, 0xc00
	s_cbranch_scc1 .LBB0_694
	s_cmpk_lt_u32 s16, 0xd00
	s_cbranch_scc1 .LBB0_695
	s_movk_i32 s1, 0xd3f
	v_cmp_lt_u32_e32 vcc, s1, v94
	v_mov_b32_e32 v72, 1.0
	v_mov_b64_e32 v[122:123], s[6:7]
	s_and_saveexec_b64 s[24:25], vcc
	s_cmpk_gt_u32 s16, 0xd7f
	s_cselect_b64 s[20:21], -1, 0
	v_cndmask_b32_e64 v72, 0.5, 1.0, s[20:21]
	v_mov_b64_e32 v[122:123], 0
	s_xor_b64 s[22:23], exec, -1
	s_and_b64 s[20:21], s[20:21], exec
	s_or_b64 exec, exec, s[24:25]
	v_readlane_b32 s30, v252, 17
	v_readlane_b32 s31, v252, 18
	s_branch .LBB0_653

; #define GL_LOAD(s_, kt_) if (VAR != 1) { a##s_##0 = GL_A(0, kt_); a##s_##1 = GL_A(1, kt_); a##s_##2 = GL_A(2, kt_); a##s_##3 = GL_A(3, kt_); b##s_##0 = GL_B(0, kt_); b##s_##1 = GL_B(1, kt_); b##s_##2 = GL_B(2, kt_); b##s_##3 = GL_B(3, kt_); }
; #define LDS_STORE(s_, buf_) if (VAR != 2) { LDS_ST1(sA, 0, buf_, a##s_##0) LDS_ST1(sA, 1, buf_, a##s_##1) LDS_ST1(sA, 2, buf_, a##s_##2) LDS_ST1(sA, 3, buf_, a##s_##3) LDS_ST1(sB, 0, buf_, b##s_##0) LDS_ST1(sB, 1, buf_, b##s_##1) LDS_ST1(sB, 2, buf_, b##s_##2) LDS_ST1(sB, 3, buf_, b##s_##3) }
;     ...
;   const int sw0 = (g ^ ((lr >> 1) & 7)) << 4, sw1 = sw0 ^ 64;
;   const int r0 = tid >> 3, kc = tid & 7, kcs = kc ^ ((r0 >> 1) & 7);
;     ...
;   GL_LOAD(0, 0)
;   GL_LOAD(1, 1)
;   LDS_STORE(0, 0)
;   if (VAR != 4) __syncthreads();
; #pragma unroll
;   for (int kt = 0; kt < nk; kt += 2) {
;     if (kt + 2 < nk) { GL_LOAD(0, kt + 2) }
;     MMA_TILE(0)
;     LDS_STORE(1, 1)
;     if (VAR != 4) __syncthreads();
;     if (kt + 3 < nk) { GL_LOAD(1, kt + 3) }
;     MMA_TILE(1)
; DI void phase_proj(const Params& P, int l, char* smem) {
;     ...
;     if (n0 >= PW) {
;       gemm_kloop<false, false, 16>(acc, xb + (size_t)m0 * DM, DM, Wt + (size_t)n0 * DM, DM, smem);
;       const int cb = col0 - PW;
;       const int br = cb >> 9, c0 = cb & 511;
;       const int b = row0 >> 12, s0 = row0 & 4095;
.LBB0_691:
	s_and_b64 vcc, exec, s[4:5]
	s_cbranch_vccz .LBB0_636
	v_mov_b32_e32 v18, v148
	s_mov_b32 s17, s27
	s_lshl_b64 s[4:5], s[16:17], 11
	v_ashrrev_i32_e32 v16, 3, v18
	v_readlane_b32 s1, v252, 19
	v_ashrrev_i32_e32 v17, 31, v16
	v_add_u32_e32 v54, 64, v16
	s_add_u32 s4, s1, s4
	v_readlane_b32 s1, v252, 20
	v_lshlrev_b64 v[6:7], 11, v[16:17]
	v_lshlrev_b32_e32 v17, 4, v18
	v_add_u32_e32 v20, 32, v16
	v_ashrrev_i32_e32 v55, 31, v54
	s_addc_u32 s5, s1, s5
	v_lshl_add_u64 v[0:1], s[18:19], 0, v[6:7]
	v_and_b32_e32 v150, 0x70, v17
	v_ashrrev_i32_e32 v21, 31, v20
	v_lshlrev_b64 v[12:13], 11, v[54:55]
	v_lshl_add_u64 v[0:1], v[0:1], 0, v[150:151]
	v_lshlrev_b64 v[10:11], 11, v[20:21]
	v_lshl_add_u64 v[4:5], s[18:19], 0, v[12:13]
	v_add_u32_e32 v56, 0x60, v16
	v_lshl_add_u64 v[6:7], s[4:5], 0, v[6:7]
	global_load_dwordx4 v[22:25], v[0:1], off
	v_lshl_add_u64 v[2:3], s[18:19], 0, v[10:11]
	v_lshl_add_u64 v[4:5], v[4:5], 0, v[150:151]
	v_ashrrev_i32_e32 v57, 31, v56
	v_lshl_add_u64 v[6:7], v[6:7], 0, v[150:151]
	v_lshl_add_u64 v[2:3], v[2:3], 0, v[150:151]
	global_load_dwordx4 v[30:33], v[4:5], off
	global_load_dwordx4 v[38:41], v[6:7], off
	v_lshlrev_b64 v[14:15], 11, v[56:57]
	global_load_dwordx4 v[26:29], v[2:3], off
	v_lshl_add_u64 v[8:9], s[18:19], 0, v[14:15]
	v_lshl_add_u64 v[8:9], v[8:9], 0, v[150:151]
	v_lshl_add_u64 v[10:11], s[4:5], 0, v[10:11]
	global_load_dwordx4 v[34:37], v[8:9], off
	v_lshl_add_u64 v[10:11], v[10:11], 0, v[150:151]
	v_lshl_add_u64 v[12:13], s[4:5], 0, v[12:13]
	global_load_dwordx4 v[42:45], v[10:11], off
	v_lshl_add_u64 v[12:13], v[12:13], 0, v[150:151]
	v_lshl_add_u64 v[14:15], s[4:5], 0, v[14:15]
	global_load_dwordx4 v[46:49], v[12:13], off
	v_lshl_add_u64 v[14:15], v[14:15], 0, v[150:151]
	global_load_dwordx4 v[50:53], v[14:15], off
	v_and_b32_e32 v19, 15, v18
	v_lshrrev_b32_e32 v55, 1, v18
	v_lshlrev_b32_e32 v21, 3, v18
	s_movk_i32 s1, 0x70
	v_and_or_b32 v55, v55, s29, v19
	v_and_b32_e32 v82, 48, v18
	v_and_b32_e32 v57, 0x70, v21
	v_bitop3_b32 v17, v17, s1, v18 bitop3:0x48
	v_lshlrev_b32_e32 v95, 7, v55
	v_lshlrev_b32_e32 v83, 7, v18
	v_lshl_or_b32 v18, v16, 7, v17
	v_lshl_or_b32 v19, v20, 7, v17
	v_lshl_or_b32 v20, v54, 7, v17
	v_lshl_or_b32 v17, v56, 7, v17
	v_bitop3_b32 v16, v95, v57, v82 bitop3:0xf6
	global_load_dwordx4 v[54:57], v[0:1], off offset:128
	global_load_dwordx4 v[58:61], v[6:7], off offset:128
	global_load_dwordx4 v[62:65], v[2:3], off offset:128
	global_load_dwordx4 v[66:69], v[4:5], off offset:128
	global_load_dwordx4 v[70:73], v[8:9], off offset:128
	global_load_dwordx4 v[74:77], v[10:11], off offset:128
	global_load_dwordx4 v[78:81], v[12:13], off offset:128
	global_load_dwordx4 v[104:107], v[14:15], off offset:128
	v_bitop3_b32 v21, v21, v82, s1 bitop3:0x6c
	v_add_u32_e32 v94, 0xffffe680, v94
	s_movk_i32 s1, 0x1c0
	v_and_or_b32 v103, v175, 64, v84
	s_mov_b64 s[4:5], 0x60
	s_waitcnt vmcnt(15)
	ds_write_b128 v18, v[22:25]
	s_waitcnt vmcnt(13)
	ds_write_b128 v18, v[38:41] offset:32768
	s_waitcnt vmcnt(12)
	ds_write_b128 v19, v[26:29]
	ds_write_b128 v20, v[30:33]
	s_waitcnt vmcnt(11)
	ds_write_b128 v17, v[34:37]
	s_waitcnt vmcnt(10)
	ds_write_b128 v19, v[42:45] offset:32768
	s_waitcnt vmcnt(9)
	ds_write_b128 v20, v[46:49] offset:32768
	s_waitcnt vmcnt(8)
	ds_write_b128 v17, v[50:53] offset:32768
	s_waitcnt lgkmcnt(0)
	s_barrier
	s_setprio 1
	ds_read_b128 v[22:25], v16
	v_and_b32_e32 v26, 0x2780, v83
	v_or_b32_e32 v28, v26, v21
	ds_read_b128 v[30:33], v28 offset:32768
	s_waitcnt lgkmcnt(0)
	v_mfma_f32_16x16x32_f16 v[42:45], v[22:25], v[30:33], 0
	ds_read_b128 v[34:37], v16 offset:2048
	s_waitcnt lgkmcnt(0)
	v_mfma_f32_16x16x32_f16 v[116:119], v[34:37], v[30:33], 0
	ds_read_b128 v[38:41], v28 offset:34816
	ds_read_b128 v[128:131], v16 offset:4096
	s_waitcnt lgkmcnt(0)
	v_mfma_f32_16x16x32_f16 v[136:139], v[128:131], v[30:33], 0
	ds_read_b128 v[50:53], v28 offset:36864
	ds_read_b128 v[132:135], v16 offset:6144
	s_waitcnt lgkmcnt(0)
	v_mfma_f32_16x16x32_f16 v[154:157], v[132:135], v[30:33], 0
	ds_read_b128 v[108:111], v28 offset:38912
	v_mfma_f32_16x16x32_f16 v[46:49], v[22:25], v[38:41], 0
	v_bitop3_b32 v29, v95, v21, 64 bitop3:0xf6
	v_mfma_f32_16x16x32_f16 v[112:115], v[22:25], v[50:53], 0
	ds_read_b128 v[158:161], v29
	s_waitcnt lgkmcnt(1)
	v_mfma_f32_16x16x32_f16 v[22:25], v[22:25], v[108:111], 0
	ds_read_b128 v[162:165], v29 offset:2048
	v_mfma_f32_16x16x32_f16 v[120:123], v[34:37], v[38:41], 0
	v_xor_b32_e32 v21, 64, v21
	v_mfma_f32_16x16x32_f16 v[124:127], v[34:37], v[50:53], 0
	v_ashrrev_i32_e32 v95, 12, v99
	v_mfma_f32_16x16x32_f16 v[34:37], v[34:37], v[108:111], 0
	v_and_b32_e32 v99, 0xfc0, v99
	v_mfma_f32_16x16x32_f16 v[140:143], v[128:131], v[38:41], 0
	v_lshlrev_b32_e32 v150, 1, v99
	v_or_b32_e32 v32, v26, v21
	v_mfma_f32_16x16x32_f16 v[144:147], v[128:131], v[50:53], 0
	ds_read_b128 v[166:169], v32 offset:34816
	ds_read_b128 v[188:191], v32 offset:36864
	v_mfma_f32_16x16x32_f16 v[128:131], v[128:131], v[108:111], 0
	ds_read_b128 v[192:195], v32 offset:38912
	s_waitcnt vmcnt(7)
	ds_write_b128 v18, v[54:57] offset:16384
	v_mfma_f32_16x16x32_f16 v[38:41], v[132:135], v[38:41], 0
	s_waitcnt vmcnt(5)
	ds_write_b128 v19, v[62:65] offset:16384
	v_mfma_f32_16x16x32_f16 v[50:53], v[132:135], v[50:53], 0
	s_waitcnt vmcnt(4)
	ds_write_b128 v20, v[66:69] offset:16384
	v_mfma_f32_16x16x32_f16 v[108:111], v[132:135], v[108:111], 0
	ds_read_b128 v[132:135], v32 offset:32768
	s_waitcnt lgkmcnt(6)
	v_mfma_f32_16x16x32_f16 v[46:49], v[158:161], v[166:169], v[46:49]
	s_waitcnt vmcnt(3)
	ds_write_b128 v17, v[70:73] offset:16384
	s_waitcnt lgkmcnt(6)
; #define GL_LOAD(s_, kt_) if (VAR != 1) { a##s_##0 = GL_A(0, kt_); a##s_##1 = GL_A(1, kt_); a##s_##2 = GL_A(2, kt_); a##s_##3 = GL_A(3, kt_); b##s_##0 = GL_B(0, kt_); b##s_##1 = GL_B(1, kt_); b##s_##2 = GL_B(2, kt_); b##s_##3 = GL_B(3, kt_); }
; #define LDS_STORE(s_, buf_) if (VAR != 2) { LDS_ST1(sA, 0, buf_, a##s_##0) LDS_ST1(sA, 1, buf_, a##s_##1) LDS_ST1(sA, 2, buf_, a##s_##2) LDS_ST1(sA, 3, buf_, a##s_##3) LDS_ST1(sB, 0, buf_, b##s_##0) LDS_ST1(sB, 1, buf_, b##s_##1) LDS_ST1(sB, 2, buf_, b##s_##2) LDS_ST1(sB, 3, buf_, b##s_##3) }
;     ...
;   GL_LOAD(0, 0)
;   GL_LOAD(1, 1)
;   LDS_STORE(0, 0)
;   if (VAR != 4) __syncthreads();
; #pragma unroll
;   for (int kt = 0; kt < nk; kt += 2) {
;     if (kt + 2 < nk) { GL_LOAD(0, kt + 2) }
;     MMA_TILE(0)
;     LDS_STORE(1, 1)
;     if (VAR != 4) __syncthreads();
;     if (kt + 3 < nk) { GL_LOAD(1, kt + 3) }
;     MMA_TILE(1)
;     if (kt + 2 < nk) { LDS_STORE(0, 0) }
;     if (VAR != 4) __syncthreads();
	v_mfma_f32_16x16x32_f16 v[112:115], v[158:161], v[188:191], v[112:115]
	ds_write_b128 v18, v[58:61] offset:49152
	s_waitcnt lgkmcnt(6)
	v_mfma_f32_16x16x32_f16 v[22:25], v[158:161], v[192:195], v[22:25]
	s_waitcnt vmcnt(2)
	ds_write_b128 v19, v[74:77] offset:49152
	v_mfma_f32_16x16x32_f16 v[120:123], v[162:165], v[166:169], v[120:123]
	s_waitcnt vmcnt(1)
	ds_write_b128 v20, v[78:81] offset:49152
	v_mfma_f32_16x16x32_f16 v[124:127], v[162:165], v[188:191], v[124:127]
	s_waitcnt vmcnt(0)
	ds_write_b128 v17, v[104:107] offset:49152
	v_mfma_f32_16x16x32_f16 v[34:37], v[162:165], v[192:195], v[34:37]
	s_waitcnt lgkmcnt(5)
	v_mfma_f32_16x16x32_f16 v[42:45], v[158:161], v[132:135], v[42:45]
	ds_read_b128 v[158:161], v29 offset:4096
	v_mfma_f32_16x16x32_f16 v[116:119], v[162:165], v[132:135], v[116:119]
	ds_read_b128 v[162:165], v29 offset:6144
	s_waitcnt lgkmcnt(1)
	v_mfma_f32_16x16x32_f16 v[136:139], v[158:161], v[132:135], v[136:139]
	v_mfma_f32_16x16x32_f16 v[140:143], v[158:161], v[166:169], v[140:143]
	s_waitcnt lgkmcnt(0)
	v_mfma_f32_16x16x32_f16 v[132:135], v[162:165], v[132:135], v[154:157]
	s_nop 2
	global_load_dwordx4 v[154:157], v[0:1], off offset:256
	v_mfma_f32_16x16x32_f16 v[38:41], v[162:165], v[166:169], v[38:41]
	v_mfma_f32_16x16x32_f16 v[144:147], v[158:161], v[188:191], v[144:147]
	v_mfma_f32_16x16x32_f16 v[128:131], v[158:161], v[192:195], v[128:131]
	global_load_dwordx4 v[158:161], v[2:3], off offset:256
	global_load_dwordx4 v[196:199], v[4:5], off offset:256
	global_load_dwordx4 v[200:203], v[8:9], off offset:256
	global_load_dwordx4 v[166:169], v[6:7], off offset:256
	global_load_dwordx4 v[204:207], v[10:11], off offset:256
	global_load_dwordx4 v[208:211], v[12:13], off offset:256
	global_load_dwordx4 v[212:215], v[14:15], off offset:256
	s_waitcnt lgkmcnt(0)
	s_barrier
	v_mfma_f32_16x16x32_f16 v[58:61], v[162:165], v[192:195], v[108:111]
	ds_read_b128 v[54:57], v16 offset:16384
	v_mfma_f32_16x16x32_f16 v[50:53], v[162:165], v[188:191], v[50:53]
	ds_read_b128 v[62:65], v28 offset:49152
	s_waitcnt lgkmcnt(0)
	v_mfma_f32_16x16x32_f16 v[42:45], v[54:57], v[62:65], v[42:45]
	ds_read_b128 v[66:69], v16 offset:18432
	ds_read_b128 v[70:73], v28 offset:51200
	s_waitcnt lgkmcnt(0)
	v_mfma_f32_16x16x32_f16 v[46:49], v[54:57], v[70:73], v[46:49]
	ds_read_b128 v[74:77], v28 offset:53248
	s_waitcnt lgkmcnt(0)
	v_mfma_f32_16x16x32_f16 v[104:107], v[54:57], v[74:77], v[112:115]
	ds_read_b128 v[78:81], v28 offset:55296
	s_waitcnt lgkmcnt(0)
	v_mfma_f32_16x16x32_f16 v[22:25], v[54:57], v[78:81], v[22:25]
	v_mfma_f32_16x16x32_f16 v[54:57], v[66:69], v[62:65], v[116:119]
	s_nop 2
	ds_read_b128 v[116:119], v16 offset:22528
	v_mfma_f32_16x16x32_f16 v[108:111], v[66:69], v[70:73], v[120:123]
	s_waitcnt vmcnt(7)
	ds_write_b128 v18, v[154:157]
	s_waitcnt vmcnt(6)
	ds_write_b128 v19, v[158:161]
	s_waitcnt vmcnt(5)
	ds_write_b128 v20, v[196:199]
	v_mfma_f32_16x16x32_f16 v[112:115], v[66:69], v[74:77], v[124:127]
	s_waitcnt vmcnt(4)
	ds_write_b128 v17, v[200:203]
	v_mfma_f32_16x16x32_f16 v[34:37], v[66:69], v[78:81], v[34:37]
	ds_read_b128 v[66:69], v16 offset:20480
	s_waitcnt lgkmcnt(0)
	v_mfma_f32_16x16x32_f16 v[124:127], v[66:69], v[70:73], v[140:143]
	s_waitcnt vmcnt(3)
	ds_write_b128 v18, v[166:169] offset:32768
	v_mfma_f32_16x16x32_f16 v[120:123], v[66:69], v[62:65], v[136:139]
	s_waitcnt vmcnt(2)
	ds_write_b128 v19, v[204:207] offset:32768
	v_mfma_f32_16x16x32_f16 v[38:41], v[116:119], v[70:73], v[38:41]
	ds_read_b128 v[70:73], v29 offset:16384
	v_mfma_f32_16x16x32_f16 v[62:65], v[116:119], v[62:65], v[132:135]
	s_nop 2
	ds_read_b128 v[132:135], v32 offset:55296
	v_mfma_f32_16x16x32_f16 v[136:139], v[66:69], v[74:77], v[144:147]
	s_waitcnt vmcnt(1)
	ds_write_b128 v20, v[208:211] offset:32768
	v_mfma_f32_16x16x32_f16 v[66:69], v[66:69], v[78:81], v[128:131]
	s_nop 2
	ds_read_b128 v[128:131], v32 offset:53248
	v_mfma_f32_16x16x32_f16 v[50:53], v[116:119], v[74:77], v[50:53]
	ds_read_b128 v[74:77], v32 offset:49152
	v_mfma_f32_16x16x32_f16 v[58:61], v[116:119], v[78:81], v[58:61]
	ds_read_b128 v[78:81], v29 offset:18432
	s_waitcnt lgkmcnt(1)
	v_mfma_f32_16x16x32_f16 v[42:45], v[70:73], v[74:77], v[42:45]
	ds_read_b128 v[116:119], v32 offset:51200
	s_waitcnt lgkmcnt(0)
	v_mfma_f32_16x16x32_f16 v[46:49], v[70:73], v[116:119], v[46:49]
	s_waitcnt vmcnt(0)
	ds_write_b128 v17, v[212:215] offset:32768
	v_mfma_f32_16x16x32_f16 v[54:57], v[78:81], v[74:77], v[54:57]
	v_mfma_f32_16x16x32_f16 v[104:107], v[70:73], v[128:131], v[104:107]
	v_mfma_f32_16x16x32_f16 v[22:25], v[70:73], v[132:135], v[22:25]
	v_mfma_f32_16x16x32_f16 v[70:73], v[78:81], v[116:119], v[108:111]
	v_mfma_f32_16x16x32_f16 v[108:111], v[78:81], v[128:131], v[112:115]
	s_nop 2
	ds_read_b128 v[112:115], v29 offset:22528
	v_mfma_f32_16x16x32_f16 v[34:37], v[78:81], v[132:135], v[34:37]
	ds_read_b128 v[78:81], v29 offset:20480
	s_waitcnt lgkmcnt(0)
	v_mfma_f32_16x16x32_f16 v[120:123], v[78:81], v[74:77], v[120:123]
	v_mfma_f32_16x16x32_f16 v[124:127], v[78:81], v[116:119], v[124:127]
	v_mfma_f32_16x16x32_f16 v[62:65], v[112:115], v[74:77], v[62:65]
	global_load_dwordx4 v[74:77], v[0:1], off offset:384
	v_mfma_f32_16x16x32_f16 v[38:41], v[112:115], v[116:119], v[38:41]
	v_mfma_f32_16x16x32_f16 v[136:139], v[78:81], v[128:131], v[136:139]
	v_mfma_f32_16x16x32_f16 v[66:69], v[78:81], v[132:135], v[66:69]
	global_load_dwordx4 v[78:81], v[2:3], off offset:384
	global_load_dwordx4 v[140:143], v[4:5], off offset:384
	v_mfma_f32_16x16x32_f16 v[50:53], v[112:115], v[128:131], v[50:53]
	global_load_dwordx4 v[144:147], v[8:9], off offset:384
	global_load_dwordx4 v[116:119], v[6:7], off offset:384
	global_load_dwordx4 v[162:165], v[10:11], off offset:384
	global_load_dwordx4 v[188:191], v[12:13], off offset:384
	global_load_dwordx4 v[192:195], v[14:15], off offset:384
	s_waitcnt lgkmcnt(0)
	s_barrier
; #define GL_LOAD(s_, kt_) if (VAR != 1) { a##s_##0 = GL_A(0, kt_); a##s_##1 = GL_A(1, kt_); a##s_##2 = GL_A(2, kt_); a##s_##3 = GL_A(3, kt_); b##s_##0 = GL_B(0, kt_); b##s_##1 = GL_B(1, kt_); b##s_##2 = GL_B(2, kt_); b##s_##3 = GL_B(3, kt_); }
; #define LDS_STORE(s_, buf_) if (VAR != 2) { LDS_ST1(sA, 0, buf_, a##s_##0) LDS_ST1(sA, 1, buf_, a##s_##1) LDS_ST1(sA, 2, buf_, a##s_##2) LDS_ST1(sA, 3, buf_, a##s_##3) LDS_ST1(sB, 0, buf_, b##s_##0) LDS_ST1(sB, 1, buf_, b##s_##1) LDS_ST1(sB, 2, buf_, b##s_##2) LDS_ST1(sB, 3, buf_, b##s_##3) }
;     ...
;   GL_LOAD(0, 0)
;   GL_LOAD(1, 1)
;   LDS_STORE(0, 0)
;   if (VAR != 4) __syncthreads();
; #pragma unroll
;   for (int kt = 0; kt < nk; kt += 2) {
;     if (kt + 2 < nk) { GL_LOAD(0, kt + 2) }
;     MMA_TILE(0)
;     LDS_STORE(1, 1)
;     if (VAR != 4) __syncthreads();
;     if (kt + 3 < nk) { GL_LOAD(1, kt + 3) }
;     MMA_TILE(1)
;     if (kt + 2 < nk) { LDS_STORE(0, 0) }
;     if (VAR != 4) __syncthreads();
	v_mfma_f32_16x16x32_f16 v[58:61], v[112:115], v[132:135], v[58:61]
	ds_read_b128 v[128:131], v16
	ds_read_b128 v[112:115], v28 offset:32768
	s_waitcnt lgkmcnt(0)
	v_mfma_f32_16x16x32_f16 v[42:45], v[128:131], v[112:115], v[42:45]
	ds_read_b128 v[132:135], v16 offset:2048
	ds_read_b128 v[154:157], v28 offset:34816
	s_waitcnt lgkmcnt(0)
	v_mfma_f32_16x16x32_f16 v[46:49], v[128:131], v[154:157], v[46:49]
	ds_read_b128 v[158:161], v28 offset:36864
	v_mfma_f32_16x16x32_f16 v[54:57], v[132:135], v[112:115], v[54:57]
	ds_read_b128 v[166:169], v28 offset:38912
	v_mfma_f32_16x16x32_f16 v[70:73], v[132:135], v[154:157], v[70:73]
	s_waitcnt vmcnt(7)
	ds_write_b128 v18, v[74:77] offset:16384
	s_waitcnt lgkmcnt(2)
	v_mfma_f32_16x16x32_f16 v[104:107], v[128:131], v[158:161], v[104:107]
	s_waitcnt vmcnt(6)
	ds_write_b128 v19, v[78:81] offset:16384
	s_waitcnt lgkmcnt(2)
	v_mfma_f32_16x16x32_f16 v[22:25], v[128:131], v[166:169], v[22:25]
	ds_read_b128 v[128:131], v16 offset:4096
	v_mfma_f32_16x16x32_f16 v[108:111], v[132:135], v[158:161], v[108:111]
	s_waitcnt vmcnt(5)
	ds_write_b128 v20, v[140:143] offset:16384
	v_mfma_f32_16x16x32_f16 v[34:37], v[132:135], v[166:169], v[34:37]
	ds_read_b128 v[132:135], v16 offset:6144
	s_waitcnt lgkmcnt(2)
	v_mfma_f32_16x16x32_f16 v[120:123], v[128:131], v[112:115], v[120:123]
	s_waitcnt vmcnt(4)
	ds_write_b128 v17, v[144:147] offset:16384
	v_mfma_f32_16x16x32_f16 v[124:127], v[128:131], v[154:157], v[124:127]
	s_waitcnt vmcnt(3)
	ds_write_b128 v18, v[116:119] offset:49152
	s_waitcnt lgkmcnt(2)
	v_mfma_f32_16x16x32_f16 v[62:65], v[132:135], v[112:115], v[62:65]
	ds_read_b128 v[112:115], v29
	v_mfma_f32_16x16x32_f16 v[38:41], v[132:135], v[154:157], v[38:41]
	ds_read_b128 v[154:157], v32 offset:34816
	v_mfma_f32_16x16x32_f16 v[136:139], v[128:131], v[158:161], v[136:139]
	s_waitcnt vmcnt(2)
	ds_write_b128 v19, v[162:165] offset:49152
	v_mfma_f32_16x16x32_f16 v[66:69], v[128:131], v[166:169], v[66:69]
	ds_read_b128 v[128:131], v32 offset:32768
	v_mfma_f32_16x16x32_f16 v[50:53], v[132:135], v[158:161], v[50:53]
	ds_read_b128 v[158:161], v32 offset:36864
	v_mfma_f32_16x16x32_f16 v[58:61], v[132:135], v[166:169], v[58:61]
	ds_read_b128 v[132:135], v29 offset:2048
	s_waitcnt lgkmcnt(2)
	v_mfma_f32_16x16x32_f16 v[42:45], v[112:115], v[128:131], v[42:45]
	ds_read_b128 v[166:169], v32 offset:38912
	v_mfma_f32_16x16x32_f16 v[46:49], v[112:115], v[154:157], v[46:49]
	s_waitcnt vmcnt(1)
	ds_write_b128 v20, v[188:191] offset:49152
	s_waitcnt lgkmcnt(2)
	v_mfma_f32_16x16x32_f16 v[54:57], v[132:135], v[128:131], v[54:57]
	s_waitcnt vmcnt(0)
	ds_write_b128 v17, v[192:195] offset:49152
	v_mfma_f32_16x16x32_f16 v[70:73], v[132:135], v[154:157], v[70:73]
	v_mfma_f32_16x16x32_f16 v[104:107], v[112:115], v[158:161], v[104:107]
	s_waitcnt lgkmcnt(2)
	v_mfma_f32_16x16x32_f16 v[22:25], v[112:115], v[166:169], v[22:25]
	ds_read_b128 v[112:115], v29 offset:4096
	v_mfma_f32_16x16x32_f16 v[108:111], v[132:135], v[158:161], v[108:111]
	v_mfma_f32_16x16x32_f16 v[34:37], v[132:135], v[166:169], v[34:37]
	ds_read_b128 v[132:135], v29 offset:6144
	s_waitcnt lgkmcnt(1)
	v_mfma_f32_16x16x32_f16 v[120:123], v[112:115], v[128:131], v[120:123]
	v_mfma_f32_16x16x32_f16 v[124:127], v[112:115], v[154:157], v[124:127]
	s_waitcnt lgkmcnt(0)
	v_mfma_f32_16x16x32_f16 v[62:65], v[132:135], v[128:131], v[62:65]
	v_mfma_f32_16x16x32_f16 v[38:41], v[132:135], v[154:157], v[38:41]
	v_mfma_f32_16x16x32_f16 v[136:139], v[112:115], v[158:161], v[136:139]
	v_mfma_f32_16x16x32_f16 v[66:69], v[112:115], v[166:169], v[66:69]
	global_load_dwordx4 v[112:115], v[0:1], off offset:512
	global_load_dwordx4 v[128:131], v[2:3], off offset:512
	global_load_dwordx4 v[196:199], v[4:5], off offset:512
	global_load_dwordx4 v[200:203], v[8:9], off offset:512
	global_load_dwordx4 v[154:157], v[6:7], off offset:512
	global_load_dwordx4 v[204:207], v[10:11], off offset:512
	global_load_dwordx4 v[208:211], v[12:13], off offset:512
	global_load_dwordx4 v[212:215], v[14:15], off offset:512
	s_waitcnt lgkmcnt(0)
	s_barrier
	v_mfma_f32_16x16x32_f16 v[50:53], v[132:135], v[158:161], v[50:53]
	ds_read_b128 v[74:77], v16 offset:16384
	v_mfma_f32_16x16x32_f16 v[58:61], v[132:135], v[166:169], v[58:61]
	ds_read_b128 v[78:81], v28 offset:49152
	s_waitcnt lgkmcnt(0)
	v_mfma_f32_16x16x32_f16 v[42:45], v[74:77], v[78:81], v[42:45]
	ds_read_b128 v[116:119], v16 offset:18432
	ds_read_b128 v[132:135], v28 offset:51200
	s_waitcnt lgkmcnt(0)
	v_mfma_f32_16x16x32_f16 v[46:49], v[74:77], v[132:135], v[46:49]
	ds_read_b128 v[140:143], v28 offset:53248
	v_mfma_f32_16x16x32_f16 v[54:57], v[116:119], v[78:81], v[54:57]
	ds_read_b128 v[144:147], v28 offset:55296
	v_mfma_f32_16x16x32_f16 v[70:73], v[116:119], v[132:135], v[70:73]
	s_waitcnt vmcnt(7)
	ds_write_b128 v18, v[112:115]
	s_waitcnt lgkmcnt(2)
	v_mfma_f32_16x16x32_f16 v[104:107], v[74:77], v[140:143], v[104:107]
	s_waitcnt vmcnt(6)
	ds_write_b128 v19, v[128:131]
	s_waitcnt lgkmcnt(2)
	v_mfma_f32_16x16x32_f16 v[22:25], v[74:77], v[144:147], v[22:25]
	s_waitcnt vmcnt(5)
	ds_write_b128 v20, v[196:199]
	v_mfma_f32_16x16x32_f16 v[74:77], v[116:119], v[140:143], v[108:111]
	s_nop 2
	ds_read_b128 v[108:111], v16 offset:20480
	v_mfma_f32_16x16x32_f16 v[34:37], v[116:119], v[144:147], v[34:37]
	ds_read_b128 v[116:119], v16 offset:22528
	s_waitcnt lgkmcnt(1)
	v_mfma_f32_16x16x32_f16 v[120:123], v[108:111], v[78:81], v[120:123]
	s_waitcnt vmcnt(4)
	ds_write_b128 v17, v[200:203]
	v_mfma_f32_16x16x32_f16 v[124:127], v[108:111], v[132:135], v[124:127]
	s_waitcnt vmcnt(3)
	ds_write_b128 v18, v[154:157] offset:32768
	s_waitcnt lgkmcnt(2)
; #define GL_LOAD(s_, kt_) if (VAR != 1) { a##s_##0 = GL_A(0, kt_); a##s_##1 = GL_A(1, kt_); a##s_##2 = GL_A(2, kt_); a##s_##3 = GL_A(3, kt_); b##s_##0 = GL_B(0, kt_); b##s_##1 = GL_B(1, kt_); b##s_##2 = GL_B(2, kt_); b##s_##3 = GL_B(3, kt_); }
; #define LDS_STORE(s_, buf_) if (VAR != 2) { LDS_ST1(sA, 0, buf_, a##s_##0) LDS_ST1(sA, 1, buf_, a##s_##1) LDS_ST1(sA, 2, buf_, a##s_##2) LDS_ST1(sA, 3, buf_, a##s_##3) LDS_ST1(sB, 0, buf_, b##s_##0) LDS_ST1(sB, 1, buf_, b##s_##1) LDS_ST1(sB, 2, buf_, b##s_##2) LDS_ST1(sB, 3, buf_, b##s_##3) }
;     ...
;   GL_LOAD(0, 0)
;   GL_LOAD(1, 1)
;   LDS_STORE(0, 0)
;   if (VAR != 4) __syncthreads();
; #pragma unroll
;   for (int kt = 0; kt < nk; kt += 2) {
;     if (kt + 2 < nk) { GL_LOAD(0, kt + 2) }
;     MMA_TILE(0)
;     LDS_STORE(1, 1)
;     if (VAR != 4) __syncthreads();
;     if (kt + 3 < nk) { GL_LOAD(1, kt + 3) }
;     MMA_TILE(1)
;     if (kt + 2 < nk) { LDS_STORE(0, 0) }
;     if (VAR != 4) __syncthreads();
	v_mfma_f32_16x16x32_f16 v[62:65], v[116:119], v[78:81], v[62:65]
	ds_read_b128 v[78:81], v29 offset:16384
	v_mfma_f32_16x16x32_f16 v[38:41], v[116:119], v[132:135], v[38:41]
	ds_read_b128 v[132:135], v32 offset:51200
	v_mfma_f32_16x16x32_f16 v[136:139], v[108:111], v[140:143], v[136:139]
	s_waitcnt vmcnt(2)
	ds_write_b128 v19, v[204:207] offset:32768
	v_mfma_f32_16x16x32_f16 v[66:69], v[108:111], v[144:147], v[66:69]
	ds_read_b128 v[108:111], v32 offset:49152
	v_mfma_f32_16x16x32_f16 v[50:53], v[116:119], v[140:143], v[50:53]
	ds_read_b128 v[140:143], v32 offset:53248
	v_mfma_f32_16x16x32_f16 v[58:61], v[116:119], v[144:147], v[58:61]
	ds_read_b128 v[116:119], v29 offset:18432
	s_waitcnt lgkmcnt(2)
	v_mfma_f32_16x16x32_f16 v[42:45], v[78:81], v[108:111], v[42:45]
	ds_read_b128 v[144:147], v32 offset:55296
	v_mfma_f32_16x16x32_f16 v[46:49], v[78:81], v[132:135], v[46:49]
	s_waitcnt vmcnt(1)
	ds_write_b128 v20, v[208:211] offset:32768
	s_waitcnt lgkmcnt(2)
	v_mfma_f32_16x16x32_f16 v[54:57], v[116:119], v[108:111], v[54:57]
	s_waitcnt vmcnt(0)
	ds_write_b128 v17, v[212:215] offset:32768
	v_mfma_f32_16x16x32_f16 v[70:73], v[116:119], v[132:135], v[70:73]
	v_mfma_f32_16x16x32_f16 v[104:107], v[78:81], v[140:143], v[104:107]
	s_waitcnt lgkmcnt(2)
	v_mfma_f32_16x16x32_f16 v[22:25], v[78:81], v[144:147], v[22:25]
	ds_read_b128 v[78:81], v29 offset:20480
	v_mfma_f32_16x16x32_f16 v[74:77], v[116:119], v[140:143], v[74:77]
	v_mfma_f32_16x16x32_f16 v[34:37], v[116:119], v[144:147], v[34:37]
	ds_read_b128 v[116:119], v29 offset:22528
	s_waitcnt lgkmcnt(1)
	v_mfma_f32_16x16x32_f16 v[120:123], v[78:81], v[108:111], v[120:123]
	v_mfma_f32_16x16x32_f16 v[124:127], v[78:81], v[132:135], v[124:127]
	s_waitcnt lgkmcnt(0)
	v_mfma_f32_16x16x32_f16 v[62:65], v[116:119], v[108:111], v[62:65]
	v_mfma_f32_16x16x32_f16 v[38:41], v[116:119], v[132:135], v[38:41]
	v_mfma_f32_16x16x32_f16 v[136:139], v[78:81], v[140:143], v[136:139]
	v_mfma_f32_16x16x32_f16 v[66:69], v[78:81], v[144:147], v[66:69]
	global_load_dwordx4 v[78:81], v[0:1], off offset:640
	global_load_dwordx4 v[108:111], v[2:3], off offset:640
	global_load_dwordx4 v[158:161], v[4:5], off offset:640
	global_load_dwordx4 v[162:165], v[8:9], off offset:640
	global_load_dwordx4 v[132:135], v[6:7], off offset:640
	global_load_dwordx4 v[166:169], v[10:11], off offset:640
	global_load_dwordx4 v[188:191], v[12:13], off offset:640
	global_load_dwordx4 v[192:195], v[14:15], off offset:640
	s_waitcnt lgkmcnt(0)
	s_barrier
	v_mfma_f32_16x16x32_f16 v[50:53], v[116:119], v[140:143], v[50:53]
	ds_read_b128 v[112:115], v16
	v_mfma_f32_16x16x32_f16 v[58:61], v[116:119], v[144:147], v[58:61]
	ds_read_b128 v[116:119], v28 offset:32768
	s_waitcnt lgkmcnt(0)
	v_mfma_f32_16x16x32_f16 v[42:45], v[112:115], v[116:119], v[42:45]
	ds_read_b128 v[128:131], v16 offset:2048
	ds_read_b128 v[140:143], v28 offset:34816
	s_waitcnt lgkmcnt(0)
	v_mfma_f32_16x16x32_f16 v[46:49], v[112:115], v[140:143], v[46:49]
	ds_read_b128 v[144:147], v28 offset:36864
	v_mfma_f32_16x16x32_f16 v[54:57], v[128:131], v[116:119], v[54:57]
	ds_read_b128 v[154:157], v28 offset:38912
	v_mfma_f32_16x16x32_f16 v[70:73], v[128:131], v[140:143], v[70:73]
	s_waitcnt vmcnt(7)
	ds_write_b128 v18, v[78:81] offset:16384
	s_waitcnt lgkmcnt(2)
	v_mfma_f32_16x16x32_f16 v[104:107], v[112:115], v[144:147], v[104:107]
	s_waitcnt vmcnt(6)
	ds_write_b128 v19, v[108:111] offset:16384
	s_waitcnt lgkmcnt(2)
	v_mfma_f32_16x16x32_f16 v[22:25], v[112:115], v[154:157], v[22:25]
	ds_read_b128 v[112:115], v16 offset:4096
	v_mfma_f32_16x16x32_f16 v[74:77], v[128:131], v[144:147], v[74:77]
	s_waitcnt vmcnt(5)
	ds_write_b128 v20, v[158:161] offset:16384
	v_mfma_f32_16x16x32_f16 v[34:37], v[128:131], v[154:157], v[34:37]
	ds_read_b128 v[128:131], v16 offset:6144
	s_waitcnt lgkmcnt(2)
	v_mfma_f32_16x16x32_f16 v[120:123], v[112:115], v[116:119], v[120:123]
	s_waitcnt vmcnt(4)
	ds_write_b128 v17, v[162:165] offset:16384
	v_mfma_f32_16x16x32_f16 v[124:127], v[112:115], v[140:143], v[124:127]
	s_waitcnt vmcnt(3)
	ds_write_b128 v18, v[132:135] offset:49152
	s_waitcnt lgkmcnt(2)
	v_mfma_f32_16x16x32_f16 v[62:65], v[128:131], v[116:119], v[62:65]
	ds_read_b128 v[116:119], v32 offset:32768
	v_mfma_f32_16x16x32_f16 v[38:41], v[128:131], v[140:143], v[38:41]
	ds_read_b128 v[140:143], v32 offset:34816
	v_mfma_f32_16x16x32_f16 v[136:139], v[112:115], v[144:147], v[136:139]
	s_waitcnt vmcnt(2)
	ds_write_b128 v19, v[166:169] offset:49152
	v_mfma_f32_16x16x32_f16 v[66:69], v[112:115], v[154:157], v[66:69]
	ds_read_b128 v[112:115], v29
	v_mfma_f32_16x16x32_f16 v[50:53], v[128:131], v[144:147], v[50:53]
	ds_read_b128 v[144:147], v32 offset:36864
	v_mfma_f32_16x16x32_f16 v[58:61], v[128:131], v[154:157], v[58:61]
	ds_read_b128 v[128:131], v29 offset:2048
	s_waitcnt lgkmcnt(2)
	v_mfma_f32_16x16x32_f16 v[42:45], v[112:115], v[116:119], v[42:45]
	ds_read_b128 v[154:157], v32 offset:38912
	v_mfma_f32_16x16x32_f16 v[46:49], v[112:115], v[140:143], v[46:49]
	s_waitcnt vmcnt(1)
	ds_write_b128 v20, v[188:191] offset:49152
	s_waitcnt lgkmcnt(2)
	v_mfma_f32_16x16x32_f16 v[54:57], v[128:131], v[116:119], v[54:57]
	s_waitcnt vmcnt(0)
	ds_write_b128 v17, v[192:195] offset:49152
	v_mfma_f32_16x16x32_f16 v[70:73], v[128:131], v[140:143], v[70:73]
	v_mfma_f32_16x16x32_f16 v[104:107], v[112:115], v[144:147], v[104:107]
	s_waitcnt lgkmcnt(2)
	v_mfma_f32_16x16x32_f16 v[22:25], v[112:115], v[154:157], v[22:25]
	ds_read_b128 v[112:115], v29 offset:4096
	v_mfma_f32_16x16x32_f16 v[74:77], v[128:131], v[144:147], v[74:77]
	v_mfma_f32_16x16x32_f16 v[34:37], v[128:131], v[154:157], v[34:37]
	ds_read_b128 v[128:131], v29 offset:6144
	s_waitcnt lgkmcnt(1)
	v_mfma_f32_16x16x32_f16 v[120:123], v[112:115], v[116:119], v[120:123]
	v_mfma_f32_16x16x32_f16 v[124:127], v[112:115], v[140:143], v[124:127]
	s_waitcnt lgkmcnt(0)
	v_mfma_f32_16x16x32_f16 v[62:65], v[128:131], v[116:119], v[62:65]
	v_mfma_f32_16x16x32_f16 v[38:41], v[128:131], v[140:143], v[38:41]
	v_mfma_f32_16x16x32_f16 v[136:139], v[112:115], v[144:147], v[136:139]
	v_mfma_f32_16x16x32_f16 v[66:69], v[112:115], v[154:157], v[66:69]
	global_load_dwordx4 v[112:115], v[0:1], off offset:768
	global_load_dwordx4 v[116:119], v[2:3], off offset:768
	global_load_dwordx4 v[196:199], v[4:5], off offset:768
	global_load_dwordx4 v[200:203], v[8:9], off offset:768
	global_load_dwordx4 v[140:143], v[6:7], off offset:768
	global_load_dwordx4 v[204:207], v[10:11], off offset:768
	global_load_dwordx4 v[208:211], v[12:13], off offset:768
	global_load_dwordx4 v[212:215], v[14:15], off offset:768
	s_waitcnt lgkmcnt(0)
	s_barrier
; #define GL_LOAD(s_, kt_) if (VAR != 1) { a##s_##0 = GL_A(0, kt_); a##s_##1 = GL_A(1, kt_); a##s_##2 = GL_A(2, kt_); a##s_##3 = GL_A(3, kt_); b##s_##0 = GL_B(0, kt_); b##s_##1 = GL_B(1, kt_); b##s_##2 = GL_B(2, kt_); b##s_##3 = GL_B(3, kt_); }
; #define LDS_STORE(s_, buf_) if (VAR != 2) { LDS_ST1(sA, 0, buf_, a##s_##0) LDS_ST1(sA, 1, buf_, a##s_##1) LDS_ST1(sA, 2, buf_, a##s_##2) LDS_ST1(sA, 3, buf_, a##s_##3) LDS_ST1(sB, 0, buf_, b##s_##0) LDS_ST1(sB, 1, buf_, b##s_##1) LDS_ST1(sB, 2, buf_, b##s_##2) LDS_ST1(sB, 3, buf_, b##s_##3) }
;     ...
;   GL_LOAD(0, 0)
;   GL_LOAD(1, 1)
;   LDS_STORE(0, 0)
;   if (VAR != 4) __syncthreads();
; #pragma unroll
;   for (int kt = 0; kt < nk; kt += 2) {
;     if (kt + 2 < nk) { GL_LOAD(0, kt + 2) }
;     MMA_TILE(0)
;     LDS_STORE(1, 1)
;     if (VAR != 4) __syncthreads();
;     if (kt + 3 < nk) { GL_LOAD(1, kt + 3) }
;     MMA_TILE(1)
;     if (kt + 2 < nk) { LDS_STORE(0, 0) }
;     if (VAR != 4) __syncthreads();
	v_mfma_f32_16x16x32_f16 v[50:53], v[128:131], v[144:147], v[50:53]
	ds_read_b128 v[78:81], v16 offset:16384
	v_mfma_f32_16x16x32_f16 v[58:61], v[128:131], v[154:157], v[58:61]
	ds_read_b128 v[108:111], v28 offset:49152
	s_waitcnt lgkmcnt(0)
	v_mfma_f32_16x16x32_f16 v[42:45], v[78:81], v[108:111], v[42:45]
	ds_read_b128 v[128:131], v16 offset:18432
	ds_read_b128 v[132:135], v28 offset:51200
	s_waitcnt lgkmcnt(0)
	v_mfma_f32_16x16x32_f16 v[46:49], v[78:81], v[132:135], v[46:49]
	ds_read_b128 v[144:147], v28 offset:53248
	v_mfma_f32_16x16x32_f16 v[54:57], v[128:131], v[108:111], v[54:57]
	ds_read_b128 v[154:157], v28 offset:55296
	v_mfma_f32_16x16x32_f16 v[70:73], v[128:131], v[132:135], v[70:73]
	s_waitcnt vmcnt(7)
	ds_write_b128 v18, v[112:115]
	s_waitcnt lgkmcnt(2)
	v_mfma_f32_16x16x32_f16 v[104:107], v[78:81], v[144:147], v[104:107]
	s_waitcnt vmcnt(6)
	ds_write_b128 v19, v[116:119]
	s_waitcnt lgkmcnt(2)
	v_mfma_f32_16x16x32_f16 v[22:25], v[78:81], v[154:157], v[22:25]
	ds_read_b128 v[78:81], v16 offset:20480
	v_mfma_f32_16x16x32_f16 v[74:77], v[128:131], v[144:147], v[74:77]
	s_waitcnt vmcnt(5)
	ds_write_b128 v20, v[196:199]
	v_mfma_f32_16x16x32_f16 v[34:37], v[128:131], v[154:157], v[34:37]
	ds_read_b128 v[128:131], v16 offset:22528
	s_waitcnt lgkmcnt(2)
	v_mfma_f32_16x16x32_f16 v[120:123], v[78:81], v[108:111], v[120:123]
	s_waitcnt vmcnt(4)
	ds_write_b128 v17, v[200:203]
	v_mfma_f32_16x16x32_f16 v[124:127], v[78:81], v[132:135], v[124:127]
	s_waitcnt vmcnt(3)
	ds_write_b128 v18, v[140:143] offset:32768
	s_waitcnt lgkmcnt(2)
	v_mfma_f32_16x16x32_f16 v[62:65], v[128:131], v[108:111], v[62:65]
	ds_read_b128 v[108:111], v32 offset:49152
	v_mfma_f32_16x16x32_f16 v[38:41], v[128:131], v[132:135], v[38:41]
	ds_read_b128 v[132:135], v32 offset:51200
	v_mfma_f32_16x16x32_f16 v[136:139], v[78:81], v[144:147], v[136:139]
	s_waitcnt vmcnt(2)
	ds_write_b128 v19, v[204:207] offset:32768
	v_mfma_f32_16x16x32_f16 v[66:69], v[78:81], v[154:157], v[66:69]
	ds_read_b128 v[78:81], v29 offset:16384
	v_mfma_f32_16x16x32_f16 v[50:53], v[128:131], v[144:147], v[50:53]
	ds_read_b128 v[144:147], v32 offset:53248
	v_mfma_f32_16x16x32_f16 v[58:61], v[128:131], v[154:157], v[58:61]
	ds_read_b128 v[128:131], v29 offset:18432
	s_waitcnt lgkmcnt(2)
	v_mfma_f32_16x16x32_f16 v[42:45], v[78:81], v[108:111], v[42:45]
	ds_read_b128 v[154:157], v32 offset:55296
	v_mfma_f32_16x16x32_f16 v[46:49], v[78:81], v[132:135], v[46:49]
	s_waitcnt vmcnt(1)
	ds_write_b128 v20, v[208:211] offset:32768
	s_waitcnt lgkmcnt(2)
	v_mfma_f32_16x16x32_f16 v[54:57], v[128:131], v[108:111], v[54:57]
	s_waitcnt vmcnt(0)
	ds_write_b128 v17, v[212:215] offset:32768
	v_mfma_f32_16x16x32_f16 v[70:73], v[128:131], v[132:135], v[70:73]
	v_mfma_f32_16x16x32_f16 v[104:107], v[78:81], v[144:147], v[104:107]
	s_waitcnt lgkmcnt(2)
	v_mfma_f32_16x16x32_f16 v[22:25], v[78:81], v[154:157], v[22:25]
	ds_read_b128 v[78:81], v29 offset:20480
	v_mfma_f32_16x16x32_f16 v[74:77], v[128:131], v[144:147], v[74:77]
	v_mfma_f32_16x16x32_f16 v[34:37], v[128:131], v[154:157], v[34:37]
	ds_read_b128 v[128:131], v29 offset:22528
	s_waitcnt lgkmcnt(1)
	v_mfma_f32_16x16x32_f16 v[120:123], v[78:81], v[108:111], v[120:123]
	v_mfma_f32_16x16x32_f16 v[124:127], v[78:81], v[132:135], v[124:127]
	s_waitcnt lgkmcnt(0)
	v_mfma_f32_16x16x32_f16 v[62:65], v[128:131], v[108:111], v[62:65]
	v_mfma_f32_16x16x32_f16 v[38:41], v[128:131], v[132:135], v[38:41]
	v_mfma_f32_16x16x32_f16 v[136:139], v[78:81], v[144:147], v[136:139]
	v_mfma_f32_16x16x32_f16 v[66:69], v[78:81], v[154:157], v[66:69]
	global_load_dwordx4 v[78:81], v[0:1], off offset:896
	global_load_dwordx4 v[108:111], v[2:3], off offset:896
	global_load_dwordx4 v[158:161], v[4:5], off offset:896
	global_load_dwordx4 v[162:165], v[8:9], off offset:896
	global_load_dwordx4 v[132:135], v[6:7], off offset:896
	global_load_dwordx4 v[166:169], v[10:11], off offset:896
	global_load_dwordx4 v[188:191], v[12:13], off offset:896
	global_load_dwordx4 v[192:195], v[14:15], off offset:896
	s_waitcnt lgkmcnt(0)
	s_barrier
	v_mfma_f32_16x16x32_f16 v[50:53], v[128:131], v[144:147], v[50:53]
	ds_read_b128 v[112:115], v16
	v_mfma_f32_16x16x32_f16 v[58:61], v[128:131], v[154:157], v[58:61]
	ds_read_b128 v[116:119], v28 offset:32768
	s_waitcnt lgkmcnt(0)
	v_mfma_f32_16x16x32_f16 v[42:45], v[112:115], v[116:119], v[42:45]
	ds_read_b128 v[128:131], v16 offset:2048
	ds_read_b128 v[140:143], v28 offset:34816
	s_waitcnt lgkmcnt(0)
	v_mfma_f32_16x16x32_f16 v[46:49], v[112:115], v[140:143], v[46:49]
	ds_read_b128 v[144:147], v28 offset:36864
	v_mfma_f32_16x16x32_f16 v[54:57], v[128:131], v[116:119], v[54:57]
	ds_read_b128 v[154:157], v28 offset:38912
	v_mfma_f32_16x16x32_f16 v[70:73], v[128:131], v[140:143], v[70:73]
	s_waitcnt vmcnt(7)
	ds_write_b128 v18, v[78:81] offset:16384
	s_waitcnt lgkmcnt(2)
	v_mfma_f32_16x16x32_f16 v[104:107], v[112:115], v[144:147], v[104:107]
	s_waitcnt vmcnt(6)
	ds_write_b128 v19, v[108:111] offset:16384
	s_waitcnt lgkmcnt(2)
	v_mfma_f32_16x16x32_f16 v[22:25], v[112:115], v[154:157], v[22:25]
	ds_read_b128 v[112:115], v16 offset:4096
	v_mfma_f32_16x16x32_f16 v[74:77], v[128:131], v[144:147], v[74:77]
	s_waitcnt vmcnt(5)
	ds_write_b128 v20, v[158:161] offset:16384
	v_mfma_f32_16x16x32_f16 v[34:37], v[128:131], v[154:157], v[34:37]
	ds_read_b128 v[128:131], v16 offset:6144
	s_waitcnt lgkmcnt(2)
	v_mfma_f32_16x16x32_f16 v[120:123], v[112:115], v[116:119], v[120:123]
	s_waitcnt vmcnt(4)
	ds_write_b128 v17, v[162:165] offset:16384
	v_mfma_f32_16x16x32_f16 v[124:127], v[112:115], v[140:143], v[124:127]
	s_waitcnt vmcnt(3)
	ds_write_b128 v18, v[132:135] offset:49152
	s_waitcnt lgkmcnt(2)
; #define GL_LOAD(s_, kt_) if (VAR != 1) { a##s_##0 = GL_A(0, kt_); a##s_##1 = GL_A(1, kt_); a##s_##2 = GL_A(2, kt_); a##s_##3 = GL_A(3, kt_); b##s_##0 = GL_B(0, kt_); b##s_##1 = GL_B(1, kt_); b##s_##2 = GL_B(2, kt_); b##s_##3 = GL_B(3, kt_); }
; #define LDS_STORE(s_, buf_) if (VAR != 2) { LDS_ST1(sA, 0, buf_, a##s_##0) LDS_ST1(sA, 1, buf_, a##s_##1) LDS_ST1(sA, 2, buf_, a##s_##2) LDS_ST1(sA, 3, buf_, a##s_##3) LDS_ST1(sB, 0, buf_, b##s_##0) LDS_ST1(sB, 1, buf_, b##s_##1) LDS_ST1(sB, 2, buf_, b##s_##2) LDS_ST1(sB, 3, buf_, b##s_##3) }
;     ...
;   GL_LOAD(0, 0)
;   GL_LOAD(1, 1)
;   LDS_STORE(0, 0)
;   if (VAR != 4) __syncthreads();
; #pragma unroll
;   for (int kt = 0; kt < nk; kt += 2) {
;     if (kt + 2 < nk) { GL_LOAD(0, kt + 2) }
;     MMA_TILE(0)
;     LDS_STORE(1, 1)
;     if (VAR != 4) __syncthreads();
;     if (kt + 3 < nk) { GL_LOAD(1, kt + 3) }
;     MMA_TILE(1)
;     if (kt + 2 < nk) { LDS_STORE(0, 0) }
;     if (VAR != 4) __syncthreads();
	v_mfma_f32_16x16x32_f16 v[62:65], v[128:131], v[116:119], v[62:65]
	ds_read_b128 v[116:119], v32 offset:32768
	v_mfma_f32_16x16x32_f16 v[38:41], v[128:131], v[140:143], v[38:41]
	ds_read_b128 v[140:143], v32 offset:34816
	v_mfma_f32_16x16x32_f16 v[136:139], v[112:115], v[144:147], v[136:139]
	s_waitcnt vmcnt(2)
	ds_write_b128 v19, v[166:169] offset:49152
	v_mfma_f32_16x16x32_f16 v[66:69], v[112:115], v[154:157], v[66:69]
	ds_read_b128 v[112:115], v29
	v_mfma_f32_16x16x32_f16 v[50:53], v[128:131], v[144:147], v[50:53]
	ds_read_b128 v[144:147], v32 offset:36864
	v_mfma_f32_16x16x32_f16 v[58:61], v[128:131], v[154:157], v[58:61]
	ds_read_b128 v[128:131], v29 offset:2048
	s_waitcnt lgkmcnt(2)
	v_mfma_f32_16x16x32_f16 v[42:45], v[112:115], v[116:119], v[42:45]
	ds_read_b128 v[154:157], v32 offset:38912
	v_mfma_f32_16x16x32_f16 v[46:49], v[112:115], v[140:143], v[46:49]
	s_waitcnt vmcnt(1)
	ds_write_b128 v20, v[188:191] offset:49152
	s_waitcnt lgkmcnt(2)
	v_mfma_f32_16x16x32_f16 v[54:57], v[128:131], v[116:119], v[54:57]
	s_waitcnt vmcnt(0)
	ds_write_b128 v17, v[192:195] offset:49152
	v_mfma_f32_16x16x32_f16 v[70:73], v[128:131], v[140:143], v[70:73]
	v_mfma_f32_16x16x32_f16 v[104:107], v[112:115], v[144:147], v[104:107]
	s_waitcnt lgkmcnt(2)
	v_mfma_f32_16x16x32_f16 v[22:25], v[112:115], v[154:157], v[22:25]
	ds_read_b128 v[112:115], v29 offset:4096
	v_mfma_f32_16x16x32_f16 v[74:77], v[128:131], v[144:147], v[74:77]
	v_mfma_f32_16x16x32_f16 v[34:37], v[128:131], v[154:157], v[34:37]
	ds_read_b128 v[128:131], v29 offset:6144
	s_waitcnt lgkmcnt(1)
	v_mfma_f32_16x16x32_f16 v[120:123], v[112:115], v[116:119], v[120:123]
	v_mfma_f32_16x16x32_f16 v[124:127], v[112:115], v[140:143], v[124:127]
	s_waitcnt lgkmcnt(0)
	v_mfma_f32_16x16x32_f16 v[62:65], v[128:131], v[116:119], v[62:65]
	v_mfma_f32_16x16x32_f16 v[38:41], v[128:131], v[140:143], v[38:41]
	v_mfma_f32_16x16x32_f16 v[136:139], v[112:115], v[144:147], v[136:139]
	v_mfma_f32_16x16x32_f16 v[66:69], v[112:115], v[154:157], v[66:69]
	global_load_dwordx4 v[112:115], v[0:1], off offset:1024
	global_load_dwordx4 v[116:119], v[2:3], off offset:1024
	global_load_dwordx4 v[196:199], v[4:5], off offset:1024
	global_load_dwordx4 v[200:203], v[8:9], off offset:1024
	global_load_dwordx4 v[140:143], v[6:7], off offset:1024
	global_load_dwordx4 v[204:207], v[10:11], off offset:1024
	global_load_dwordx4 v[208:211], v[12:13], off offset:1024
	global_load_dwordx4 v[212:215], v[14:15], off offset:1024
	s_waitcnt lgkmcnt(0)
	s_barrier
	v_mfma_f32_16x16x32_f16 v[50:53], v[128:131], v[144:147], v[50:53]
	ds_read_b128 v[78:81], v16 offset:16384
	v_mfma_f32_16x16x32_f16 v[58:61], v[128:131], v[154:157], v[58:61]
	ds_read_b128 v[108:111], v28 offset:49152
	s_waitcnt lgkmcnt(0)
	v_mfma_f32_16x16x32_f16 v[42:45], v[78:81], v[108:111], v[42:45]
	ds_read_b128 v[128:131], v16 offset:18432
	ds_read_b128 v[132:135], v28 offset:51200
	s_waitcnt lgkmcnt(0)
	v_mfma_f32_16x16x32_f16 v[46:49], v[78:81], v[132:135], v[46:49]
	ds_read_b128 v[144:147], v28 offset:53248
	v_mfma_f32_16x16x32_f16 v[54:57], v[128:131], v[108:111], v[54:57]
	ds_read_b128 v[154:157], v28 offset:55296
	v_mfma_f32_16x16x32_f16 v[70:73], v[128:131], v[132:135], v[70:73]
	s_waitcnt vmcnt(7)
	ds_write_b128 v18, v[112:115]
	s_waitcnt lgkmcnt(2)
	v_mfma_f32_16x16x32_f16 v[104:107], v[78:81], v[144:147], v[104:107]
	s_waitcnt vmcnt(6)
	ds_write_b128 v19, v[116:119]
	s_waitcnt lgkmcnt(2)
	v_mfma_f32_16x16x32_f16 v[22:25], v[78:81], v[154:157], v[22:25]
	ds_read_b128 v[78:81], v16 offset:20480
	v_mfma_f32_16x16x32_f16 v[74:77], v[128:131], v[144:147], v[74:77]
	s_waitcnt vmcnt(5)
	ds_write_b128 v20, v[196:199]
	v_mfma_f32_16x16x32_f16 v[34:37], v[128:131], v[154:157], v[34:37]
	ds_read_b128 v[128:131], v16 offset:22528
	s_waitcnt lgkmcnt(2)
	v_mfma_f32_16x16x32_f16 v[120:123], v[78:81], v[108:111], v[120:123]
	s_waitcnt vmcnt(4)
	ds_write_b128 v17, v[200:203]
	v_mfma_f32_16x16x32_f16 v[124:127], v[78:81], v[132:135], v[124:127]
	s_waitcnt vmcnt(3)
	ds_write_b128 v18, v[140:143] offset:32768
	s_waitcnt lgkmcnt(2)
	v_mfma_f32_16x16x32_f16 v[62:65], v[128:131], v[108:111], v[62:65]
	ds_read_b128 v[108:111], v32 offset:49152
	v_mfma_f32_16x16x32_f16 v[38:41], v[128:131], v[132:135], v[38:41]
	ds_read_b128 v[132:135], v32 offset:51200
	v_mfma_f32_16x16x32_f16 v[136:139], v[78:81], v[144:147], v[136:139]
	s_waitcnt vmcnt(2)
	ds_write_b128 v19, v[204:207] offset:32768
	v_mfma_f32_16x16x32_f16 v[66:69], v[78:81], v[154:157], v[66:69]
	ds_read_b128 v[78:81], v29 offset:16384
	v_mfma_f32_16x16x32_f16 v[50:53], v[128:131], v[144:147], v[50:53]
	ds_read_b128 v[144:147], v32 offset:53248
	v_mfma_f32_16x16x32_f16 v[58:61], v[128:131], v[154:157], v[58:61]
	ds_read_b128 v[128:131], v29 offset:18432
	s_waitcnt lgkmcnt(2)
	v_mfma_f32_16x16x32_f16 v[42:45], v[78:81], v[108:111], v[42:45]
	ds_read_b128 v[154:157], v32 offset:55296
	v_mfma_f32_16x16x32_f16 v[46:49], v[78:81], v[132:135], v[46:49]
	s_waitcnt vmcnt(1)
	ds_write_b128 v20, v[208:211] offset:32768
	s_waitcnt lgkmcnt(2)
	v_mfma_f32_16x16x32_f16 v[54:57], v[128:131], v[108:111], v[54:57]
	s_waitcnt vmcnt(0)
	ds_write_b128 v17, v[212:215] offset:32768
	v_mfma_f32_16x16x32_f16 v[70:73], v[128:131], v[132:135], v[70:73]
	v_mfma_f32_16x16x32_f16 v[104:107], v[78:81], v[144:147], v[104:107]
	s_waitcnt lgkmcnt(2)
	v_mfma_f32_16x16x32_f16 v[22:25], v[78:81], v[154:157], v[22:25]
	ds_read_b128 v[78:81], v29 offset:20480
	v_mfma_f32_16x16x32_f16 v[74:77], v[128:131], v[144:147], v[74:77]
	v_mfma_f32_16x16x32_f16 v[34:37], v[128:131], v[154:157], v[34:37]
	ds_read_b128 v[128:131], v29 offset:22528
	s_waitcnt lgkmcnt(1)
	v_mfma_f32_16x16x32_f16 v[120:123], v[78:81], v[108:111], v[120:123]
	v_mfma_f32_16x16x32_f16 v[124:127], v[78:81], v[132:135], v[124:127]
	s_waitcnt lgkmcnt(0)
	v_mfma_f32_16x16x32_f16 v[62:65], v[128:131], v[108:111], v[62:65]
	v_mfma_f32_16x16x32_f16 v[38:41], v[128:131], v[132:135], v[38:41]
	v_mfma_f32_16x16x32_f16 v[136:139], v[78:81], v[144:147], v[136:139]
	v_mfma_f32_16x16x32_f16 v[66:69], v[78:81], v[154:157], v[66:69]
	global_load_dwordx4 v[78:81], v[0:1], off offset:1152
	global_load_dwordx4 v[108:111], v[2:3], off offset:1152
	global_load_dwordx4 v[158:161], v[4:5], off offset:1152
	global_load_dwordx4 v[162:165], v[8:9], off offset:1152
	global_load_dwordx4 v[132:135], v[6:7], off offset:1152
	global_load_dwordx4 v[166:169], v[10:11], off offset:1152
	global_load_dwordx4 v[188:191], v[12:13], off offset:1152
	global_load_dwordx4 v[192:195], v[14:15], off offset:1152
	s_waitcnt lgkmcnt(0)
	s_barrier
; #define GL_LOAD(s_, kt_) if (VAR != 1) { a##s_##0 = GL_A(0, kt_); a##s_##1 = GL_A(1, kt_); a##s_##2 = GL_A(2, kt_); a##s_##3 = GL_A(3, kt_); b##s_##0 = GL_B(0, kt_); b##s_##1 = GL_B(1, kt_); b##s_##2 = GL_B(2, kt_); b##s_##3 = GL_B(3, kt_); }
; #define LDS_STORE(s_, buf_) if (VAR != 2) { LDS_ST1(sA, 0, buf_, a##s_##0) LDS_ST1(sA, 1, buf_, a##s_##1) LDS_ST1(sA, 2, buf_, a##s_##2) LDS_ST1(sA, 3, buf_, a##s_##3) LDS_ST1(sB, 0, buf_, b##s_##0) LDS_ST1(sB, 1, buf_, b##s_##1) LDS_ST1(sB, 2, buf_, b##s_##2) LDS_ST1(sB, 3, buf_, b##s_##3) }
;     ...
;   GL_LOAD(0, 0)
;   GL_LOAD(1, 1)
;   LDS_STORE(0, 0)
;   if (VAR != 4) __syncthreads();
; #pragma unroll
;   for (int kt = 0; kt < nk; kt += 2) {
;     if (kt + 2 < nk) { GL_LOAD(0, kt + 2) }
;     MMA_TILE(0)
;     LDS_STORE(1, 1)
;     if (VAR != 4) __syncthreads();
;     if (kt + 3 < nk) { GL_LOAD(1, kt + 3) }
;     MMA_TILE(1)
;     if (kt + 2 < nk) { LDS_STORE(0, 0) }
;     if (VAR != 4) __syncthreads();
	v_mfma_f32_16x16x32_f16 v[50:53], v[128:131], v[144:147], v[50:53]
	ds_read_b128 v[112:115], v16
	v_mfma_f32_16x16x32_f16 v[58:61], v[128:131], v[154:157], v[58:61]
	ds_read_b128 v[116:119], v28 offset:32768
	s_waitcnt lgkmcnt(0)
	v_mfma_f32_16x16x32_f16 v[42:45], v[112:115], v[116:119], v[42:45]
	ds_read_b128 v[128:131], v16 offset:2048
	ds_read_b128 v[140:143], v28 offset:34816
	s_waitcnt lgkmcnt(0)
	v_mfma_f32_16x16x32_f16 v[46:49], v[112:115], v[140:143], v[46:49]
	ds_read_b128 v[144:147], v28 offset:36864
	v_mfma_f32_16x16x32_f16 v[54:57], v[128:131], v[116:119], v[54:57]
	ds_read_b128 v[154:157], v28 offset:38912
	v_mfma_f32_16x16x32_f16 v[70:73], v[128:131], v[140:143], v[70:73]
	s_waitcnt vmcnt(7)
	ds_write_b128 v18, v[78:81] offset:16384
	s_waitcnt lgkmcnt(2)
	v_mfma_f32_16x16x32_f16 v[104:107], v[112:115], v[144:147], v[104:107]
	s_waitcnt vmcnt(6)
	ds_write_b128 v19, v[108:111] offset:16384
	s_waitcnt lgkmcnt(2)
	v_mfma_f32_16x16x32_f16 v[22:25], v[112:115], v[154:157], v[22:25]
	ds_read_b128 v[112:115], v16 offset:4096
	v_mfma_f32_16x16x32_f16 v[74:77], v[128:131], v[144:147], v[74:77]
	s_waitcnt vmcnt(5)
	ds_write_b128 v20, v[158:161] offset:16384
	v_mfma_f32_16x16x32_f16 v[34:37], v[128:131], v[154:157], v[34:37]
	ds_read_b128 v[128:131], v16 offset:6144
	s_waitcnt lgkmcnt(2)
	v_mfma_f32_16x16x32_f16 v[120:123], v[112:115], v[116:119], v[120:123]
	s_waitcnt vmcnt(4)
	ds_write_b128 v17, v[162:165] offset:16384
	v_mfma_f32_16x16x32_f16 v[124:127], v[112:115], v[140:143], v[124:127]
	s_waitcnt vmcnt(3)
	ds_write_b128 v18, v[132:135] offset:49152
	s_waitcnt lgkmcnt(2)
	v_mfma_f32_16x16x32_f16 v[62:65], v[128:131], v[116:119], v[62:65]
	ds_read_b128 v[116:119], v32 offset:32768
	v_mfma_f32_16x16x32_f16 v[38:41], v[128:131], v[140:143], v[38:41]
	ds_read_b128 v[140:143], v32 offset:34816
	v_mfma_f32_16x16x32_f16 v[136:139], v[112:115], v[144:147], v[136:139]
	s_waitcnt vmcnt(2)
	ds_write_b128 v19, v[166:169] offset:49152
	v_mfma_f32_16x16x32_f16 v[66:69], v[112:115], v[154:157], v[66:69]
	ds_read_b128 v[112:115], v29
	v_mfma_f32_16x16x32_f16 v[50:53], v[128:131], v[144:147], v[50:53]
	ds_read_b128 v[144:147], v32 offset:36864
	v_mfma_f32_16x16x32_f16 v[58:61], v[128:131], v[154:157], v[58:61]
	ds_read_b128 v[128:131], v29 offset:2048
	s_waitcnt lgkmcnt(2)
	v_mfma_f32_16x16x32_f16 v[42:45], v[112:115], v[116:119], v[42:45]
	ds_read_b128 v[154:157], v32 offset:38912
	v_mfma_f32_16x16x32_f16 v[46:49], v[112:115], v[140:143], v[46:49]
	s_waitcnt vmcnt(1)
	ds_write_b128 v20, v[188:191] offset:49152
	s_waitcnt lgkmcnt(2)
	v_mfma_f32_16x16x32_f16 v[54:57], v[128:131], v[116:119], v[54:57]
	s_waitcnt vmcnt(0)
	ds_write_b128 v17, v[192:195] offset:49152
	v_mfma_f32_16x16x32_f16 v[70:73], v[128:131], v[140:143], v[70:73]
	v_mfma_f32_16x16x32_f16 v[104:107], v[112:115], v[144:147], v[104:107]
	s_waitcnt lgkmcnt(2)
	v_mfma_f32_16x16x32_f16 v[22:25], v[112:115], v[154:157], v[22:25]
	ds_read_b128 v[112:115], v29 offset:4096
	v_mfma_f32_16x16x32_f16 v[74:77], v[128:131], v[144:147], v[74:77]
	v_mfma_f32_16x16x32_f16 v[34:37], v[128:131], v[154:157], v[34:37]
	ds_read_b128 v[128:131], v29 offset:6144
	s_waitcnt lgkmcnt(1)
	v_mfma_f32_16x16x32_f16 v[120:123], v[112:115], v[116:119], v[120:123]
	v_mfma_f32_16x16x32_f16 v[124:127], v[112:115], v[140:143], v[124:127]
	s_waitcnt lgkmcnt(0)
	v_mfma_f32_16x16x32_f16 v[62:65], v[128:131], v[116:119], v[62:65]
	v_mfma_f32_16x16x32_f16 v[38:41], v[128:131], v[140:143], v[38:41]
	v_mfma_f32_16x16x32_f16 v[136:139], v[112:115], v[144:147], v[136:139]
	v_mfma_f32_16x16x32_f16 v[66:69], v[112:115], v[154:157], v[66:69]
	global_load_dwordx4 v[112:115], v[0:1], off offset:1280
	global_load_dwordx4 v[116:119], v[2:3], off offset:1280
	global_load_dwordx4 v[196:199], v[4:5], off offset:1280
	global_load_dwordx4 v[200:203], v[8:9], off offset:1280
	global_load_dwordx4 v[140:143], v[6:7], off offset:1280
	global_load_dwordx4 v[204:207], v[10:11], off offset:1280
	global_load_dwordx4 v[208:211], v[12:13], off offset:1280
	global_load_dwordx4 v[212:215], v[14:15], off offset:1280
	s_waitcnt lgkmcnt(0)
	s_barrier
	v_mfma_f32_16x16x32_f16 v[50:53], v[128:131], v[144:147], v[50:53]
	ds_read_b128 v[78:81], v16 offset:16384
	v_mfma_f32_16x16x32_f16 v[58:61], v[128:131], v[154:157], v[58:61]
	ds_read_b128 v[108:111], v28 offset:49152
	s_waitcnt lgkmcnt(0)
	v_mfma_f32_16x16x32_f16 v[42:45], v[78:81], v[108:111], v[42:45]
	ds_read_b128 v[128:131], v16 offset:18432
	ds_read_b128 v[132:135], v28 offset:51200
	s_waitcnt lgkmcnt(0)
	v_mfma_f32_16x16x32_f16 v[46:49], v[78:81], v[132:135], v[46:49]
	ds_read_b128 v[144:147], v28 offset:53248
	v_mfma_f32_16x16x32_f16 v[54:57], v[128:131], v[108:111], v[54:57]
	ds_read_b128 v[154:157], v28 offset:55296
	v_mfma_f32_16x16x32_f16 v[70:73], v[128:131], v[132:135], v[70:73]
	s_waitcnt vmcnt(7)
	ds_write_b128 v18, v[112:115]
	s_waitcnt lgkmcnt(2)
	v_mfma_f32_16x16x32_f16 v[104:107], v[78:81], v[144:147], v[104:107]
	s_waitcnt vmcnt(6)
	ds_write_b128 v19, v[116:119]
	s_waitcnt lgkmcnt(2)
	v_mfma_f32_16x16x32_f16 v[22:25], v[78:81], v[154:157], v[22:25]
	ds_read_b128 v[78:81], v16 offset:20480
	v_mfma_f32_16x16x32_f16 v[74:77], v[128:131], v[144:147], v[74:77]
	s_waitcnt vmcnt(5)
	ds_write_b128 v20, v[196:199]
	v_mfma_f32_16x16x32_f16 v[34:37], v[128:131], v[154:157], v[34:37]
	ds_read_b128 v[128:131], v16 offset:22528
	s_waitcnt lgkmcnt(2)
	v_mfma_f32_16x16x32_f16 v[120:123], v[78:81], v[108:111], v[120:123]
	s_waitcnt vmcnt(4)
	ds_write_b128 v17, v[200:203]
	v_mfma_f32_16x16x32_f16 v[124:127], v[78:81], v[132:135], v[124:127]
	s_waitcnt vmcnt(3)
	ds_write_b128 v18, v[140:143] offset:32768
	s_waitcnt lgkmcnt(2)
; #define GL_LOAD(s_, kt_) if (VAR != 1) { a##s_##0 = GL_A(0, kt_); a##s_##1 = GL_A(1, kt_); a##s_##2 = GL_A(2, kt_); a##s_##3 = GL_A(3, kt_); b##s_##0 = GL_B(0, kt_); b##s_##1 = GL_B(1, kt_); b##s_##2 = GL_B(2, kt_); b##s_##3 = GL_B(3, kt_); }
; #define LDS_STORE(s_, buf_) if (VAR != 2) { LDS_ST1(sA, 0, buf_, a##s_##0) LDS_ST1(sA, 1, buf_, a##s_##1) LDS_ST1(sA, 2, buf_, a##s_##2) LDS_ST1(sA, 3, buf_, a##s_##3) LDS_ST1(sB, 0, buf_, b##s_##0) LDS_ST1(sB, 1, buf_, b##s_##1) LDS_ST1(sB, 2, buf_, b##s_##2) LDS_ST1(sB, 3, buf_, b##s_##3) }
;     ...
;   GL_LOAD(0, 0)
;   GL_LOAD(1, 1)
;   LDS_STORE(0, 0)
;   if (VAR != 4) __syncthreads();
; #pragma unroll
;   for (int kt = 0; kt < nk; kt += 2) {
;     if (kt + 2 < nk) { GL_LOAD(0, kt + 2) }
;     MMA_TILE(0)
;     LDS_STORE(1, 1)
;     if (VAR != 4) __syncthreads();
;     if (kt + 3 < nk) { GL_LOAD(1, kt + 3) }
;     MMA_TILE(1)
;     if (kt + 2 < nk) { LDS_STORE(0, 0) }
;     if (VAR != 4) __syncthreads();
	v_mfma_f32_16x16x32_f16 v[62:65], v[128:131], v[108:111], v[62:65]
	ds_read_b128 v[108:111], v32 offset:49152
	v_mfma_f32_16x16x32_f16 v[38:41], v[128:131], v[132:135], v[38:41]
	ds_read_b128 v[132:135], v32 offset:51200
	v_mfma_f32_16x16x32_f16 v[136:139], v[78:81], v[144:147], v[136:139]
	s_waitcnt vmcnt(2)
	ds_write_b128 v19, v[204:207] offset:32768
	v_mfma_f32_16x16x32_f16 v[66:69], v[78:81], v[154:157], v[66:69]
	ds_read_b128 v[78:81], v29 offset:16384
	v_mfma_f32_16x16x32_f16 v[50:53], v[128:131], v[144:147], v[50:53]
	ds_read_b128 v[144:147], v32 offset:53248
	v_mfma_f32_16x16x32_f16 v[58:61], v[128:131], v[154:157], v[58:61]
	ds_read_b128 v[128:131], v29 offset:18432
	s_waitcnt lgkmcnt(2)
	v_mfma_f32_16x16x32_f16 v[42:45], v[78:81], v[108:111], v[42:45]
	ds_read_b128 v[154:157], v32 offset:55296
	v_mfma_f32_16x16x32_f16 v[46:49], v[78:81], v[132:135], v[46:49]
	s_waitcnt vmcnt(1)
	ds_write_b128 v20, v[208:211] offset:32768
	s_waitcnt lgkmcnt(2)
	v_mfma_f32_16x16x32_f16 v[54:57], v[128:131], v[108:111], v[54:57]
	s_waitcnt vmcnt(0)
	ds_write_b128 v17, v[212:215] offset:32768
	v_mfma_f32_16x16x32_f16 v[70:73], v[128:131], v[132:135], v[70:73]
	v_mfma_f32_16x16x32_f16 v[104:107], v[78:81], v[144:147], v[104:107]
	s_waitcnt lgkmcnt(2)
	v_mfma_f32_16x16x32_f16 v[22:25], v[78:81], v[154:157], v[22:25]
	ds_read_b128 v[78:81], v29 offset:20480
	v_mfma_f32_16x16x32_f16 v[74:77], v[128:131], v[144:147], v[74:77]
	v_mfma_f32_16x16x32_f16 v[34:37], v[128:131], v[154:157], v[34:37]
	ds_read_b128 v[128:131], v29 offset:22528
	s_waitcnt lgkmcnt(1)
	v_mfma_f32_16x16x32_f16 v[120:123], v[78:81], v[108:111], v[120:123]
	v_mfma_f32_16x16x32_f16 v[124:127], v[78:81], v[132:135], v[124:127]
	s_waitcnt lgkmcnt(0)
	v_mfma_f32_16x16x32_f16 v[62:65], v[128:131], v[108:111], v[62:65]
	v_mfma_f32_16x16x32_f16 v[38:41], v[128:131], v[132:135], v[38:41]
	v_mfma_f32_16x16x32_f16 v[136:139], v[78:81], v[144:147], v[136:139]
	v_mfma_f32_16x16x32_f16 v[66:69], v[78:81], v[154:157], v[66:69]
	global_load_dwordx4 v[78:81], v[0:1], off offset:1408
	global_load_dwordx4 v[108:111], v[2:3], off offset:1408
	global_load_dwordx4 v[158:161], v[4:5], off offset:1408
	global_load_dwordx4 v[162:165], v[8:9], off offset:1408
	global_load_dwordx4 v[132:135], v[6:7], off offset:1408
	global_load_dwordx4 v[166:169], v[10:11], off offset:1408
	global_load_dwordx4 v[188:191], v[12:13], off offset:1408
	global_load_dwordx4 v[192:195], v[14:15], off offset:1408
	s_waitcnt lgkmcnt(0)
	s_barrier
	v_mfma_f32_16x16x32_f16 v[50:53], v[128:131], v[144:147], v[50:53]
	ds_read_b128 v[112:115], v16
	v_mfma_f32_16x16x32_f16 v[58:61], v[128:131], v[154:157], v[58:61]
	ds_read_b128 v[116:119], v28 offset:32768
	s_waitcnt lgkmcnt(0)
	v_mfma_f32_16x16x32_f16 v[42:45], v[112:115], v[116:119], v[42:45]
	ds_read_b128 v[128:131], v16 offset:2048
	ds_read_b128 v[140:143], v28 offset:34816
	s_waitcnt lgkmcnt(0)
	v_mfma_f32_16x16x32_f16 v[46:49], v[112:115], v[140:143], v[46:49]
	ds_read_b128 v[144:147], v28 offset:36864
	v_mfma_f32_16x16x32_f16 v[54:57], v[128:131], v[116:119], v[54:57]
	ds_read_b128 v[154:157], v28 offset:38912
	v_mfma_f32_16x16x32_f16 v[70:73], v[128:131], v[140:143], v[70:73]
	s_waitcnt vmcnt(7)
	ds_write_b128 v18, v[78:81] offset:16384
	s_waitcnt lgkmcnt(2)
	v_mfma_f32_16x16x32_f16 v[104:107], v[112:115], v[144:147], v[104:107]
	s_waitcnt vmcnt(6)
	ds_write_b128 v19, v[108:111] offset:16384
	s_waitcnt lgkmcnt(2)
	v_mfma_f32_16x16x32_f16 v[22:25], v[112:115], v[154:157], v[22:25]
	ds_read_b128 v[112:115], v16 offset:4096
	v_mfma_f32_16x16x32_f16 v[74:77], v[128:131], v[144:147], v[74:77]
	s_waitcnt vmcnt(5)
	ds_write_b128 v20, v[158:161] offset:16384
	v_mfma_f32_16x16x32_f16 v[34:37], v[128:131], v[154:157], v[34:37]
	ds_read_b128 v[128:131], v16 offset:6144
	s_waitcnt lgkmcnt(2)
	v_mfma_f32_16x16x32_f16 v[120:123], v[112:115], v[116:119], v[120:123]
	s_waitcnt vmcnt(4)
	ds_write_b128 v17, v[162:165] offset:16384
	v_mfma_f32_16x16x32_f16 v[124:127], v[112:115], v[140:143], v[124:127]
	s_waitcnt vmcnt(3)
	ds_write_b128 v18, v[132:135] offset:49152
	s_waitcnt lgkmcnt(2)
	v_mfma_f32_16x16x32_f16 v[62:65], v[128:131], v[116:119], v[62:65]
	ds_read_b128 v[116:119], v32 offset:32768
	v_mfma_f32_16x16x32_f16 v[38:41], v[128:131], v[140:143], v[38:41]
	ds_read_b128 v[140:143], v32 offset:34816
	v_mfma_f32_16x16x32_f16 v[136:139], v[112:115], v[144:147], v[136:139]
	s_waitcnt vmcnt(2)
	ds_write_b128 v19, v[166:169] offset:49152
	v_mfma_f32_16x16x32_f16 v[66:69], v[112:115], v[154:157], v[66:69]
	ds_read_b128 v[112:115], v29
	v_mfma_f32_16x16x32_f16 v[50:53], v[128:131], v[144:147], v[50:53]
	ds_read_b128 v[144:147], v32 offset:36864
	v_mfma_f32_16x16x32_f16 v[58:61], v[128:131], v[154:157], v[58:61]
	ds_read_b128 v[128:131], v29 offset:2048
	s_waitcnt lgkmcnt(2)
	v_mfma_f32_16x16x32_f16 v[42:45], v[112:115], v[116:119], v[42:45]
	ds_read_b128 v[154:157], v32 offset:38912
	v_mfma_f32_16x16x32_f16 v[46:49], v[112:115], v[140:143], v[46:49]
	s_waitcnt vmcnt(1)
	ds_write_b128 v20, v[188:191] offset:49152
	s_waitcnt lgkmcnt(2)
	v_mfma_f32_16x16x32_f16 v[54:57], v[128:131], v[116:119], v[54:57]
	s_waitcnt vmcnt(0)
	ds_write_b128 v17, v[192:195] offset:49152
	v_mfma_f32_16x16x32_f16 v[70:73], v[128:131], v[140:143], v[70:73]
	v_mfma_f32_16x16x32_f16 v[104:107], v[112:115], v[144:147], v[104:107]
	s_waitcnt lgkmcnt(2)
	v_mfma_f32_16x16x32_f16 v[22:25], v[112:115], v[154:157], v[22:25]
	ds_read_b128 v[112:115], v29 offset:4096
	v_mfma_f32_16x16x32_f16 v[74:77], v[128:131], v[144:147], v[74:77]
	v_mfma_f32_16x16x32_f16 v[34:37], v[128:131], v[154:157], v[34:37]
	ds_read_b128 v[128:131], v29 offset:6144
	s_waitcnt lgkmcnt(1)
	v_mfma_f32_16x16x32_f16 v[120:123], v[112:115], v[116:119], v[120:123]
	v_mfma_f32_16x16x32_f16 v[124:127], v[112:115], v[140:143], v[124:127]
	s_waitcnt lgkmcnt(0)
	v_mfma_f32_16x16x32_f16 v[62:65], v[128:131], v[116:119], v[62:65]
	v_mfma_f32_16x16x32_f16 v[38:41], v[128:131], v[140:143], v[38:41]
	v_mfma_f32_16x16x32_f16 v[136:139], v[112:115], v[144:147], v[136:139]
	v_mfma_f32_16x16x32_f16 v[66:69], v[112:115], v[154:157], v[66:69]
	global_load_dwordx4 v[112:115], v[0:1], off offset:1536
	global_load_dwordx4 v[116:119], v[2:3], off offset:1536
	global_load_dwordx4 v[196:199], v[4:5], off offset:1536
	global_load_dwordx4 v[200:203], v[8:9], off offset:1536
	global_load_dwordx4 v[140:143], v[6:7], off offset:1536
	global_load_dwordx4 v[204:207], v[10:11], off offset:1536
	global_load_dwordx4 v[208:211], v[12:13], off offset:1536
	global_load_dwordx4 v[212:215], v[14:15], off offset:1536
	s_waitcnt lgkmcnt(0)
	s_barrier
; #define GL_LOAD(s_, kt_) if (VAR != 1) { a##s_##0 = GL_A(0, kt_); a##s_##1 = GL_A(1, kt_); a##s_##2 = GL_A(2, kt_); a##s_##3 = GL_A(3, kt_); b##s_##0 = GL_B(0, kt_); b##s_##1 = GL_B(1, kt_); b##s_##2 = GL_B(2, kt_); b##s_##3 = GL_B(3, kt_); }
; #define LDS_STORE(s_, buf_) if (VAR != 2) { LDS_ST1(sA, 0, buf_, a##s_##0) LDS_ST1(sA, 1, buf_, a##s_##1) LDS_ST1(sA, 2, buf_, a##s_##2) LDS_ST1(sA, 3, buf_, a##s_##3) LDS_ST1(sB, 0, buf_, b##s_##0) LDS_ST1(sB, 1, buf_, b##s_##1) LDS_ST1(sB, 2, buf_, b##s_##2) LDS_ST1(sB, 3, buf_, b##s_##3) }
;     ...
;   GL_LOAD(0, 0)
;   GL_LOAD(1, 1)
;   LDS_STORE(0, 0)
;   if (VAR != 4) __syncthreads();
; #pragma unroll
;   for (int kt = 0; kt < nk; kt += 2) {
;     if (kt + 2 < nk) { GL_LOAD(0, kt + 2) }
;     MMA_TILE(0)
;     LDS_STORE(1, 1)
;     if (VAR != 4) __syncthreads();
;     if (kt + 3 < nk) { GL_LOAD(1, kt + 3) }
;     MMA_TILE(1)
;     if (kt + 2 < nk) { LDS_STORE(0, 0) }
;     if (VAR != 4) __syncthreads();
	v_mfma_f32_16x16x32_f16 v[50:53], v[128:131], v[144:147], v[50:53]
	ds_read_b128 v[78:81], v16 offset:16384
	v_mfma_f32_16x16x32_f16 v[58:61], v[128:131], v[154:157], v[58:61]
	ds_read_b128 v[108:111], v28 offset:49152
	s_waitcnt lgkmcnt(0)
	v_mfma_f32_16x16x32_f16 v[42:45], v[78:81], v[108:111], v[42:45]
	ds_read_b128 v[128:131], v16 offset:18432
	ds_read_b128 v[132:135], v28 offset:51200
	s_waitcnt lgkmcnt(0)
	v_mfma_f32_16x16x32_f16 v[46:49], v[78:81], v[132:135], v[46:49]
	ds_read_b128 v[144:147], v28 offset:53248
	v_mfma_f32_16x16x32_f16 v[54:57], v[128:131], v[108:111], v[54:57]
	ds_read_b128 v[154:157], v28 offset:55296
	v_mfma_f32_16x16x32_f16 v[70:73], v[128:131], v[132:135], v[70:73]
	s_waitcnt vmcnt(7)
	ds_write_b128 v18, v[112:115]
	s_waitcnt lgkmcnt(2)
	v_mfma_f32_16x16x32_f16 v[104:107], v[78:81], v[144:147], v[104:107]
	s_waitcnt vmcnt(6)
	ds_write_b128 v19, v[116:119]
	s_waitcnt lgkmcnt(2)
	v_mfma_f32_16x16x32_f16 v[22:25], v[78:81], v[154:157], v[22:25]
	ds_read_b128 v[78:81], v16 offset:20480
	v_mfma_f32_16x16x32_f16 v[74:77], v[128:131], v[144:147], v[74:77]
	s_waitcnt vmcnt(5)
	ds_write_b128 v20, v[196:199]
	v_mfma_f32_16x16x32_f16 v[34:37], v[128:131], v[154:157], v[34:37]
	ds_read_b128 v[128:131], v16 offset:22528
	s_waitcnt lgkmcnt(2)
	v_mfma_f32_16x16x32_f16 v[120:123], v[78:81], v[108:111], v[120:123]
	s_waitcnt vmcnt(4)
	ds_write_b128 v17, v[200:203]
	v_mfma_f32_16x16x32_f16 v[124:127], v[78:81], v[132:135], v[124:127]
	s_waitcnt vmcnt(3)
	ds_write_b128 v18, v[140:143] offset:32768
	s_waitcnt lgkmcnt(2)
	v_mfma_f32_16x16x32_f16 v[62:65], v[128:131], v[108:111], v[62:65]
	ds_read_b128 v[108:111], v32 offset:49152
	v_mfma_f32_16x16x32_f16 v[38:41], v[128:131], v[132:135], v[38:41]
	ds_read_b128 v[132:135], v32 offset:51200
	v_mfma_f32_16x16x32_f16 v[136:139], v[78:81], v[144:147], v[136:139]
	s_waitcnt vmcnt(2)
	ds_write_b128 v19, v[204:207] offset:32768
	v_mfma_f32_16x16x32_f16 v[66:69], v[78:81], v[154:157], v[66:69]
	ds_read_b128 v[78:81], v29 offset:16384
	v_mfma_f32_16x16x32_f16 v[50:53], v[128:131], v[144:147], v[50:53]
	ds_read_b128 v[144:147], v32 offset:53248
	v_mfma_f32_16x16x32_f16 v[58:61], v[128:131], v[154:157], v[58:61]
	ds_read_b128 v[128:131], v29 offset:18432
	s_waitcnt lgkmcnt(2)
	v_mfma_f32_16x16x32_f16 v[42:45], v[78:81], v[108:111], v[42:45]
	ds_read_b128 v[154:157], v32 offset:55296
	v_mfma_f32_16x16x32_f16 v[46:49], v[78:81], v[132:135], v[46:49]
	s_waitcnt vmcnt(1)
	ds_write_b128 v20, v[208:211] offset:32768
	s_waitcnt lgkmcnt(2)
	v_mfma_f32_16x16x32_f16 v[54:57], v[128:131], v[108:111], v[54:57]
	s_waitcnt vmcnt(0)
	ds_write_b128 v17, v[212:215] offset:32768
	v_mfma_f32_16x16x32_f16 v[70:73], v[128:131], v[132:135], v[70:73]
	v_mfma_f32_16x16x32_f16 v[104:107], v[78:81], v[144:147], v[104:107]
	s_waitcnt lgkmcnt(2)
	v_mfma_f32_16x16x32_f16 v[22:25], v[78:81], v[154:157], v[22:25]
	ds_read_b128 v[78:81], v29 offset:20480
	v_mfma_f32_16x16x32_f16 v[74:77], v[128:131], v[144:147], v[74:77]
	v_mfma_f32_16x16x32_f16 v[34:37], v[128:131], v[154:157], v[34:37]
	ds_read_b128 v[128:131], v29 offset:22528
	s_waitcnt lgkmcnt(1)
	v_mfma_f32_16x16x32_f16 v[120:123], v[78:81], v[108:111], v[120:123]
	v_mfma_f32_16x16x32_f16 v[124:127], v[78:81], v[132:135], v[124:127]
	s_waitcnt lgkmcnt(0)
	v_mfma_f32_16x16x32_f16 v[62:65], v[128:131], v[108:111], v[62:65]
	v_mfma_f32_16x16x32_f16 v[38:41], v[128:131], v[132:135], v[38:41]
	v_mfma_f32_16x16x32_f16 v[136:139], v[78:81], v[144:147], v[136:139]
	v_mfma_f32_16x16x32_f16 v[66:69], v[78:81], v[154:157], v[66:69]
	global_load_dwordx4 v[78:81], v[0:1], off offset:1664
	global_load_dwordx4 v[108:111], v[2:3], off offset:1664
	global_load_dwordx4 v[158:161], v[4:5], off offset:1664
	global_load_dwordx4 v[162:165], v[8:9], off offset:1664
	global_load_dwordx4 v[132:135], v[6:7], off offset:1664
	global_load_dwordx4 v[166:169], v[10:11], off offset:1664
	global_load_dwordx4 v[188:191], v[12:13], off offset:1664
	global_load_dwordx4 v[192:195], v[14:15], off offset:1664
	s_waitcnt lgkmcnt(0)
	s_barrier
	v_mfma_f32_16x16x32_f16 v[50:53], v[128:131], v[144:147], v[50:53]
	ds_read_b128 v[112:115], v16
	v_mfma_f32_16x16x32_f16 v[58:61], v[128:131], v[154:157], v[58:61]
	ds_read_b128 v[116:119], v28 offset:32768
	s_waitcnt lgkmcnt(0)
	v_mfma_f32_16x16x32_f16 v[42:45], v[112:115], v[116:119], v[42:45]
	ds_read_b128 v[128:131], v16 offset:2048
	ds_read_b128 v[140:143], v28 offset:34816
	s_waitcnt lgkmcnt(0)
	v_mfma_f32_16x16x32_f16 v[46:49], v[112:115], v[140:143], v[46:49]
	ds_read_b128 v[144:147], v28 offset:36864
	v_mfma_f32_16x16x32_f16 v[54:57], v[128:131], v[116:119], v[54:57]
	ds_read_b128 v[154:157], v28 offset:38912
	v_mfma_f32_16x16x32_f16 v[70:73], v[128:131], v[140:143], v[70:73]
	s_waitcnt vmcnt(7)
	ds_write_b128 v18, v[78:81] offset:16384
	s_waitcnt lgkmcnt(2)
	v_mfma_f32_16x16x32_f16 v[104:107], v[112:115], v[144:147], v[104:107]
	s_waitcnt vmcnt(6)
	ds_write_b128 v19, v[108:111] offset:16384
	s_waitcnt lgkmcnt(2)
	v_mfma_f32_16x16x32_f16 v[22:25], v[112:115], v[154:157], v[22:25]
	ds_read_b128 v[112:115], v16 offset:4096
	v_mfma_f32_16x16x32_f16 v[74:77], v[128:131], v[144:147], v[74:77]
	s_waitcnt vmcnt(5)
	ds_write_b128 v20, v[158:161] offset:16384
	v_mfma_f32_16x16x32_f16 v[34:37], v[128:131], v[154:157], v[34:37]
	ds_read_b128 v[128:131], v16 offset:6144
	s_waitcnt lgkmcnt(2)
	v_mfma_f32_16x16x32_f16 v[120:123], v[112:115], v[116:119], v[120:123]
	s_waitcnt vmcnt(4)
	ds_write_b128 v17, v[162:165] offset:16384
	v_mfma_f32_16x16x32_f16 v[124:127], v[112:115], v[140:143], v[124:127]
	s_waitcnt vmcnt(3)
	ds_write_b128 v18, v[132:135] offset:49152
	s_waitcnt lgkmcnt(2)
; #define GL_LOAD(s_, kt_) if (VAR != 1) { a##s_##0 = GL_A(0, kt_); a##s_##1 = GL_A(1, kt_); a##s_##2 = GL_A(2, kt_); a##s_##3 = GL_A(3, kt_); b##s_##0 = GL_B(0, kt_); b##s_##1 = GL_B(1, kt_); b##s_##2 = GL_B(2, kt_); b##s_##3 = GL_B(3, kt_); }
; #define LDS_STORE(s_, buf_) if (VAR != 2) { LDS_ST1(sA, 0, buf_, a##s_##0) LDS_ST1(sA, 1, buf_, a##s_##1) LDS_ST1(sA, 2, buf_, a##s_##2) LDS_ST1(sA, 3, buf_, a##s_##3) LDS_ST1(sB, 0, buf_, b##s_##0) LDS_ST1(sB, 1, buf_, b##s_##1) LDS_ST1(sB, 2, buf_, b##s_##2) LDS_ST1(sB, 3, buf_, b##s_##3) }
;     ...
;   GL_LOAD(0, 0)
;   GL_LOAD(1, 1)
;   LDS_STORE(0, 0)
;   if (VAR != 4) __syncthreads();
; #pragma unroll
;   for (int kt = 0; kt < nk; kt += 2) {
;     if (kt + 2 < nk) { GL_LOAD(0, kt + 2) }
;     MMA_TILE(0)
;     LDS_STORE(1, 1)
;     if (VAR != 4) __syncthreads();
;     if (kt + 3 < nk) { GL_LOAD(1, kt + 3) }
;     MMA_TILE(1)
;     if (kt + 2 < nk) { LDS_STORE(0, 0) }
;     if (VAR != 4) __syncthreads();
	v_mfma_f32_16x16x32_f16 v[62:65], v[128:131], v[116:119], v[62:65]
	ds_read_b128 v[116:119], v32 offset:32768
	v_mfma_f32_16x16x32_f16 v[38:41], v[128:131], v[140:143], v[38:41]
	ds_read_b128 v[140:143], v32 offset:34816
	v_mfma_f32_16x16x32_f16 v[136:139], v[112:115], v[144:147], v[136:139]
	s_waitcnt vmcnt(2)
	ds_write_b128 v19, v[166:169] offset:49152
	v_mfma_f32_16x16x32_f16 v[66:69], v[112:115], v[154:157], v[66:69]
	ds_read_b128 v[112:115], v29
	v_mfma_f32_16x16x32_f16 v[50:53], v[128:131], v[144:147], v[50:53]
	ds_read_b128 v[144:147], v32 offset:36864
	v_mfma_f32_16x16x32_f16 v[58:61], v[128:131], v[154:157], v[58:61]
	ds_read_b128 v[128:131], v29 offset:2048
	s_waitcnt lgkmcnt(2)
	v_mfma_f32_16x16x32_f16 v[42:45], v[112:115], v[116:119], v[42:45]
	ds_read_b128 v[154:157], v32 offset:38912
	v_mfma_f32_16x16x32_f16 v[46:49], v[112:115], v[140:143], v[46:49]
	s_waitcnt vmcnt(1)
	ds_write_b128 v20, v[188:191] offset:49152
	s_waitcnt lgkmcnt(2)
	v_mfma_f32_16x16x32_f16 v[54:57], v[128:131], v[116:119], v[54:57]
	s_waitcnt vmcnt(0)
	ds_write_b128 v17, v[192:195] offset:49152
	v_mfma_f32_16x16x32_f16 v[70:73], v[128:131], v[140:143], v[70:73]
	v_mfma_f32_16x16x32_f16 v[104:107], v[112:115], v[144:147], v[104:107]
	s_waitcnt lgkmcnt(2)
	v_mfma_f32_16x16x32_f16 v[22:25], v[112:115], v[154:157], v[22:25]
	ds_read_b128 v[112:115], v29 offset:4096
	v_mfma_f32_16x16x32_f16 v[74:77], v[128:131], v[144:147], v[74:77]
	v_mfma_f32_16x16x32_f16 v[34:37], v[128:131], v[154:157], v[34:37]
	ds_read_b128 v[128:131], v29 offset:6144
	s_waitcnt lgkmcnt(1)
	v_mfma_f32_16x16x32_f16 v[120:123], v[112:115], v[116:119], v[120:123]
	v_mfma_f32_16x16x32_f16 v[124:127], v[112:115], v[140:143], v[124:127]
	s_waitcnt lgkmcnt(0)
	v_mfma_f32_16x16x32_f16 v[62:65], v[128:131], v[116:119], v[62:65]
	v_mfma_f32_16x16x32_f16 v[38:41], v[128:131], v[140:143], v[38:41]
	v_mfma_f32_16x16x32_f16 v[136:139], v[112:115], v[144:147], v[136:139]
	v_mfma_f32_16x16x32_f16 v[66:69], v[112:115], v[154:157], v[66:69]
	global_load_dwordx4 v[112:115], v[0:1], off offset:1792
	global_load_dwordx4 v[116:119], v[2:3], off offset:1792
	global_load_dwordx4 v[196:199], v[4:5], off offset:1792
	global_load_dwordx4 v[200:203], v[8:9], off offset:1792
	global_load_dwordx4 v[140:143], v[6:7], off offset:1792
	global_load_dwordx4 v[204:207], v[10:11], off offset:1792
	global_load_dwordx4 v[208:211], v[12:13], off offset:1792
	global_load_dwordx4 v[212:215], v[14:15], off offset:1792
	s_waitcnt lgkmcnt(0)
	s_barrier
	v_mfma_f32_16x16x32_f16 v[50:53], v[128:131], v[144:147], v[50:53]
	ds_read_b128 v[78:81], v16 offset:16384
	v_mfma_f32_16x16x32_f16 v[58:61], v[128:131], v[154:157], v[58:61]
	ds_read_b128 v[108:111], v28 offset:49152
	s_waitcnt lgkmcnt(0)
	v_mfma_f32_16x16x32_f16 v[42:45], v[78:81], v[108:111], v[42:45]
	ds_read_b128 v[128:131], v16 offset:18432
	ds_read_b128 v[132:135], v28 offset:51200
	s_waitcnt lgkmcnt(0)
	v_mfma_f32_16x16x32_f16 v[46:49], v[78:81], v[132:135], v[46:49]
	ds_read_b128 v[144:147], v28 offset:53248
	v_mfma_f32_16x16x32_f16 v[54:57], v[128:131], v[108:111], v[54:57]
	ds_read_b128 v[154:157], v28 offset:55296
	v_mfma_f32_16x16x32_f16 v[70:73], v[128:131], v[132:135], v[70:73]
	s_waitcnt vmcnt(7)
	ds_write_b128 v18, v[112:115]
	s_waitcnt lgkmcnt(2)
	v_mfma_f32_16x16x32_f16 v[104:107], v[78:81], v[144:147], v[104:107]
	s_waitcnt vmcnt(6)
	ds_write_b128 v19, v[116:119]
	s_waitcnt lgkmcnt(2)
	v_mfma_f32_16x16x32_f16 v[22:25], v[78:81], v[154:157], v[22:25]
	ds_read_b128 v[78:81], v16 offset:20480
	v_mfma_f32_16x16x32_f16 v[74:77], v[128:131], v[144:147], v[74:77]
	s_waitcnt vmcnt(5)
	ds_write_b128 v20, v[196:199]
	v_mfma_f32_16x16x32_f16 v[34:37], v[128:131], v[154:157], v[34:37]
	ds_read_b128 v[128:131], v16 offset:22528
	s_waitcnt lgkmcnt(2)
	v_mfma_f32_16x16x32_f16 v[120:123], v[78:81], v[108:111], v[120:123]
	s_waitcnt vmcnt(4)
	ds_write_b128 v17, v[200:203]
	v_mfma_f32_16x16x32_f16 v[124:127], v[78:81], v[132:135], v[124:127]
	s_waitcnt vmcnt(3)
	ds_write_b128 v18, v[140:143] offset:32768
	s_waitcnt lgkmcnt(2)
	v_mfma_f32_16x16x32_f16 v[62:65], v[128:131], v[108:111], v[62:65]
	ds_read_b128 v[108:111], v32 offset:49152
	v_mfma_f32_16x16x32_f16 v[38:41], v[128:131], v[132:135], v[38:41]
	ds_read_b128 v[132:135], v32 offset:51200
	v_mfma_f32_16x16x32_f16 v[136:139], v[78:81], v[144:147], v[136:139]
	s_waitcnt vmcnt(2)
	ds_write_b128 v19, v[204:207] offset:32768
	v_mfma_f32_16x16x32_f16 v[66:69], v[78:81], v[154:157], v[66:69]
	ds_read_b128 v[78:81], v29 offset:16384
	v_mfma_f32_16x16x32_f16 v[50:53], v[128:131], v[144:147], v[50:53]
	ds_read_b128 v[144:147], v32 offset:53248
	v_mfma_f32_16x16x32_f16 v[58:61], v[128:131], v[154:157], v[58:61]
	ds_read_b128 v[128:131], v29 offset:18432
	s_waitcnt lgkmcnt(2)
	v_mfma_f32_16x16x32_f16 v[42:45], v[78:81], v[108:111], v[42:45]
	ds_read_b128 v[154:157], v32 offset:55296
	v_mfma_f32_16x16x32_f16 v[46:49], v[78:81], v[132:135], v[46:49]
	s_waitcnt vmcnt(1)
	ds_write_b128 v20, v[208:211] offset:32768
	s_waitcnt lgkmcnt(2)
	v_mfma_f32_16x16x32_f16 v[54:57], v[128:131], v[108:111], v[54:57]
	s_waitcnt vmcnt(0)
	ds_write_b128 v17, v[212:215] offset:32768
	v_mfma_f32_16x16x32_f16 v[70:73], v[128:131], v[132:135], v[70:73]
	v_mfma_f32_16x16x32_f16 v[104:107], v[78:81], v[144:147], v[104:107]
	s_waitcnt lgkmcnt(2)
	v_mfma_f32_16x16x32_f16 v[22:25], v[78:81], v[154:157], v[22:25]
	ds_read_b128 v[78:81], v29 offset:20480
	v_mfma_f32_16x16x32_f16 v[74:77], v[128:131], v[144:147], v[74:77]
	v_mfma_f32_16x16x32_f16 v[34:37], v[128:131], v[154:157], v[34:37]
	ds_read_b128 v[128:131], v29 offset:22528
	s_waitcnt lgkmcnt(1)
	v_mfma_f32_16x16x32_f16 v[120:123], v[78:81], v[108:111], v[120:123]
	v_mfma_f32_16x16x32_f16 v[124:127], v[78:81], v[132:135], v[124:127]
	s_waitcnt lgkmcnt(0)
	v_mfma_f32_16x16x32_f16 v[62:65], v[128:131], v[108:111], v[62:65]
	v_mfma_f32_16x16x32_f16 v[38:41], v[128:131], v[132:135], v[38:41]
	v_mfma_f32_16x16x32_f16 v[136:139], v[78:81], v[144:147], v[136:139]
	v_mfma_f32_16x16x32_f16 v[66:69], v[78:81], v[154:157], v[66:69]
	global_load_dwordx4 v[80:83], v[0:1], off offset:1920
	global_load_dwordx4 v[108:111], v[2:3], off offset:1920
	global_load_dwordx4 v[158:161], v[4:5], off offset:1920
	global_load_dwordx4 v[162:165], v[8:9], off offset:1920
	global_load_dwordx4 v[132:135], v[6:7], off offset:1920
	global_load_dwordx4 v[166:169], v[10:11], off offset:1920
	global_load_dwordx4 v[188:191], v[12:13], off offset:1920
	global_load_dwordx4 v[12:15], v[14:15], off offset:1920
	s_waitcnt lgkmcnt(0)
	s_barrier
; DI unsigned pack2(float lo, float hi) { f2_t v = {lo, hi}; h2_t b = __builtin_convertvector(v, h2_t); return __builtin_bit_cast(unsigned, b); }
; #define GL_LOAD(s_, kt_) if (VAR != 1) { a##s_##0 = GL_A(0, kt_); a##s_##1 = GL_A(1, kt_); a##s_##2 = GL_A(2, kt_); a##s_##3 = GL_A(3, kt_); b##s_##0 = GL_B(0, kt_); b##s_##1 = GL_B(1, kt_); b##s_##2 = GL_B(2, kt_); b##s_##3 = GL_B(3, kt_); }
; #define LDS_STORE(s_, buf_) if (VAR != 2) { LDS_ST1(sA, 0, buf_, a##s_##0) LDS_ST1(sA, 1, buf_, a##s_##1) LDS_ST1(sA, 2, buf_, a##s_##2) LDS_ST1(sA, 3, buf_, a##s_##3) LDS_ST1(sB, 0, buf_, b##s_##0) LDS_ST1(sB, 1, buf_, b##s_##1) LDS_ST1(sB, 2, buf_, b##s_##2) LDS_ST1(sB, 3, buf_, b##s_##3) }
;     ...
;   GL_LOAD(0, 0)
;   GL_LOAD(1, 1)
;   LDS_STORE(0, 0)
;   if (VAR != 4) __syncthreads();
; #pragma unroll
;   for (int kt = 0; kt < nk; kt += 2) {
;     if (kt + 2 < nk) { GL_LOAD(0, kt + 2) }
;     MMA_TILE(0)
;     LDS_STORE(1, 1)
;     if (VAR != 4) __syncthreads();
;     if (kt + 3 < nk) { GL_LOAD(1, kt + 3) }
;     MMA_TILE(1)
;     if (kt + 2 < nk) { LDS_STORE(0, 0) }
;     if (VAR != 4) __syncthreads();
; DI void phase_proj(const Params& P, int l, char* smem) {
;     ...
;       const int b = row0 >> 12, s0 = row0 & 4095;
; #pragma unroll
;       for (int mt = 0; mt < 4; ++mt) {
;         float r4[4];
; #pragma unroll
;         for (int j = 0; j < 4; ++j) r4[j] = __shfl(rs[mt], 4 * g + j);
; #pragma unroll
;         for (int nt = 0; nt < 4; ++nt) {
;           const int c = c0 + nt * 16 + lr;
;           bf16_t* dst = VT + ((size_t)(br * NB + b) * 512 + c) * SEQ + s0 + mt * 16 + 4 * g;
;           *(uint2*)dst = make_uint2(pack2(acc[mt][nt][0] * r4[0], acc[mt][nt][1] * r4[1]), pack2(acc[mt][nt][2] * r4[2], acc[mt][nt][3] * r4[3]));
;         }
;       }
	ds_read_b128 v[0:3], v16
	v_mfma_f32_16x16x32_f16 v[50:53], v[128:131], v[144:147], v[50:53]
	v_mfma_f32_16x16x32_f16 v[112:115], v[128:131], v[154:157], v[58:61]
	ds_read_b128 v[116:119], v28 offset:32768
	ds_read_b128 v[4:7], v16 offset:2048
	ds_read_b128 v[128:131], v28 offset:34816
	s_waitcnt lgkmcnt(2)
	v_mfma_f32_16x16x32_f16 v[140:143], v[0:3], v[116:119], v[42:45]
	s_waitcnt lgkmcnt(0)
	v_mfma_f32_16x16x32_f16 v[144:147], v[0:3], v[128:131], v[46:49]
	s_nop 0
	ds_read_b128 v[42:45], v28 offset:36864
	s_nop 0
	ds_read_b128 v[46:49], v28 offset:38912
	s_waitcnt lgkmcnt(0)
	v_mfma_f32_16x16x32_f16 v[154:157], v[0:3], v[46:49], v[22:25]
	v_mfma_f32_16x16x32_f16 v[204:207], v[4:7], v[46:49], v[34:37]
	s_nop 1
	ds_read_b128 v[22:25], v16 offset:4096
	ds_read_b128 v[34:37], v16 offset:6144
	ds_read_b128 v[208:211], v29
	ds_read_b128 v[212:215], v29 offset:2048
	v_mfma_f32_16x16x32_f16 v[104:107], v[0:3], v[42:45], v[104:107]
	v_mfma_f32_16x16x32_f16 v[192:195], v[4:7], v[116:119], v[54:57]
	v_mfma_f32_16x16x32_f16 v[200:203], v[4:7], v[42:45], v[74:77]
	s_nop 2
	ds_read_b128 v[76:79], v32 offset:32768
	ds_read_b128 v[56:59], v32 offset:34816
	ds_read_b128 v[220:223], v29 offset:4096
	ds_read_b128 v[0:3], v29 offset:6144
	v_mfma_f32_16x16x32_f16 v[196:199], v[4:7], v[128:131], v[70:73]
	ds_read_b128 v[8:11], v32 offset:36864
	ds_read_b128 v[4:7], v32 offset:38912
	s_waitcnt vmcnt(7)
	ds_write_b128 v18, v[80:83] offset:16384
	s_waitcnt lgkmcnt(10)
	v_mfma_f32_16x16x32_f16 v[120:123], v[22:25], v[116:119], v[120:123]
	s_waitcnt vmcnt(6)
	ds_write_b128 v19, v[108:111] offset:16384
	s_waitcnt vmcnt(5)
	ds_write_b128 v20, v[158:161] offset:16384
	s_waitcnt vmcnt(4)
	ds_write_b128 v17, v[162:165] offset:16384
	s_waitcnt vmcnt(3)
	ds_write_b128 v18, v[132:135] offset:49152
	s_waitcnt vmcnt(2)
	ds_write_b128 v19, v[166:169] offset:49152
	s_waitcnt vmcnt(1)
	ds_write_b128 v20, v[188:191] offset:49152
	v_mfma_f32_16x16x32_f16 v[136:139], v[22:25], v[42:45], v[136:139]
	s_waitcnt vmcnt(0)
	ds_write_b128 v17, v[12:15] offset:49152
	s_waitcnt lgkmcnt(0)
	s_barrier
	v_mfma_f32_16x16x32_f16 v[224:227], v[22:25], v[46:49], v[66:69]
	v_and_or_b32 v188, v94, s1, v97
	v_ashrrev_i32_e32 v94, 7, v94
	v_mfma_f32_16x16x32_f16 v[108:111], v[34:37], v[116:119], v[62:65]
	ds_read_b128 v[116:119], v16 offset:16384
	ds_read_b128 v[80:83], v16 offset:18432
	v_and_b32_e32 v94, -4, v94
	v_add_u32_e32 v94, v94, v95
	v_mfma_f32_16x16x32_f16 v[72:75], v[34:37], v[128:131], v[38:41]
	v_ashrrev_i32_e32 v95, 31, v94
	v_lshlrev_b64 v[170:171], 21, v[94:95]
	v_lshl_add_u64 v[94:95], v[92:93], 0, v[150:151]
	v_mfma_f32_16x16x32_f16 v[40:43], v[34:37], v[42:45], v[50:53]
	v_lshlrev_b32_e32 v150, 2, v103
	v_lshl_or_b32 v170, v188, 12, v170
	ds_bpermute_b32 v188, v150, v98
	v_mfma_f32_16x16x32_f16 v[44:47], v[34:37], v[46:49], v[112:115]
	ds_bpermute_b32 v189, v150, v98 offset:4
	ds_bpermute_b32 v190, v150, v98 offset:8
	v_mfma_f32_16x16x32_f16 v[112:115], v[208:211], v[76:79], v[140:143]
	v_mfma_f32_16x16x32_f16 v[124:127], v[22:25], v[128:131], v[124:127]
	ds_read_b128 v[36:39], v28 offset:49152
	ds_read_b128 v[24:27], v28 offset:51200
	ds_read_b128 v[64:67], v16 offset:20480
	ds_read_b128 v[12:15], v16 offset:22528
	ds_read_b128 v[20:23], v28 offset:53248
	ds_read_b128 v[16:19], v28 offset:55296
	ds_read_b128 v[128:131], v29 offset:16384
	ds_read_b128 v[132:135], v29 offset:18432
	ds_read_b128 v[60:63], v32 offset:49152
	ds_read_b128 v[52:55], v32 offset:51200
	ds_read_b128 v[68:71], v29 offset:20480
	ds_read_b128 v[28:31], v29 offset:22528
	s_waitcnt lgkmcnt(11)
	v_mfma_f32_16x16x32_f16 v[112:115], v[116:119], v[36:39], v[112:115]
	ds_read_b128 v[48:51], v32 offset:53248
	ds_read_b128 v[32:35], v32 offset:55296
	s_waitcnt lgkmcnt(0)
	s_barrier
	s_setprio 0
	v_mfma_f32_16x16x32_f16 v[140:143], v[208:211], v[56:59], v[144:147]
	v_mfma_f32_16x16x32_f16 v[144:147], v[208:211], v[4:7], v[154:157]
	v_mfma_f32_16x16x32_f16 v[154:157], v[212:215], v[76:79], v[192:195]
	s_nop 2
	v_or_b32_e32 v194, 12, v150
	ds_bpermute_b32 v191, v194, v98
	v_mfma_f32_16x16x32_f16 v[112:115], v[128:131], v[60:63], v[112:115]
	v_lshl_add_u64 v[98:99], v[170:171], 1, v[94:95]
	v_mfma_f32_16x16x32_f16 v[104:107], v[208:211], v[8:11], v[104:107]
	v_mfma_f32_16x16x32_f16 v[104:107], v[116:119], v[20:23], v[104:107]
	s_nop 4
	v_mul_f32_e64 v112, v112, v188
	v_mul_f32_e64 v113, v113, v189
	s_waitcnt lgkmcnt(0)
	v_pk_mul_f32 v[114:115], v[114:115], v[190:191]
	v_cvt_pk_f16_f32 v112, v112, v113
	v_cvt_pk_f16_f32 v113, v114, v115
	global_store_dwordx2 v[98:99], v[112:113], off
	v_mfma_f32_16x16x32_f16 v[112:115], v[116:119], v[24:27], v[140:143]
	v_mfma_f32_16x16x32_f16 v[112:115], v[128:131], v[52:55], v[112:115]
	s_nop 1
	v_or_b32_e32 v140, 0x10000, v170
	v_mov_b32_e32 v141, v171
	v_lshlrev_b64 v[140:141], 1, v[140:141]
	v_mfma_f32_16x16x32_f16 v[104:107], v[128:131], v[48:51], v[104:107]
	v_lshl_add_u64 v[142:143], v[94:95], 0, v[140:141]
	s_nop 0
	v_pk_mul_f32 v[112:113], v[112:113], v[188:189]
	v_pk_mul_f32 v[114:115], v[114:115], v[190:191]
	v_cvt_pk_f16_f32 v112, v112, v113
	v_cvt_pk_f16_f32 v113, v114, v115
	global_store_dwordx2 v[142:143], v[112:113], off
	v_or_b32_e32 v112, 0x20000, v170
	v_mov_b32_e32 v113, v171
	v_lshlrev_b64 v[142:143], 1, v[112:113]
	v_pk_mul_f32 v[104:105], v[104:105], v[188:189]
	v_pk_mul_f32 v[106:107], v[106:107], v[190:191]
	v_lshl_add_u64 v[192:193], v[94:95], 0, v[142:143]
	v_cvt_pk_f16_f32 v104, v104, v105
	v_cvt_pk_f16_f32 v105, v106, v107
	global_store_dwordx2 v[192:193], v[104:105], off
	v_mfma_f32_16x16x32_f16 v[104:107], v[116:119], v[16:19], v[144:147]
	v_or_b32_e32 v170, 0x30000, v170
	v_lshlrev_b64 v[116:117], 1, v[170:171]
	v_lshl_add_u64 v[118:119], v[94:95], 0, v[116:117]
	v_mfma_f32_16x16x32_f16 v[104:107], v[128:131], v[32:35], v[104:107]
	ds_bpermute_b32 v128, v150, v96 offset:8
	ds_bpermute_b32 v129, v194, v96
	v_lshl_add_u64 v[130:131], v[94:95], 0, 32
	v_mfma_f32_16x16x32_f16 v[158:161], v[212:215], v[56:59], v[196:199]
	v_lshl_add_u64 v[144:145], v[130:131], 0, v[140:141]
	s_nop 2
	v_pk_mul_f32 v[104:105], v[104:105], v[188:189]
	v_pk_mul_f32 v[106:107], v[106:107], v[190:191]
	v_cvt_pk_f16_f32 v104, v104, v105
	v_cvt_pk_f16_f32 v105, v106, v107
	global_store_dwordx2 v[118:119], v[104:105], off
	v_mfma_f32_16x16x32_f16 v[104:107], v[80:83], v[36:39], v[154:157]
	ds_bpermute_b32 v118, v150, v96
	ds_bpermute_b32 v119, v150, v96 offset:4
	v_mfma_f32_16x16x32_f16 v[104:107], v[132:135], v[60:63], v[104:107]
	v_mfma_f32_16x16x32_f16 v[120:123], v[220:223], v[76:79], v[120:123]
	v_mfma_f32_16x16x32_f16 v[76:79], v[0:3], v[76:79], v[108:111]
	s_waitcnt lgkmcnt(0)
; DI unsigned pack2(float lo, float hi) { f2_t v = {lo, hi}; h2_t b = __builtin_convertvector(v, h2_t); return __builtin_bit_cast(unsigned, b); }
; DI void phase_proj(const Params& P, int l, char* smem) {
;     ...
; #pragma unroll
;       for (int mt = 0; mt < 4; ++mt) {
;         float r4[4];
; #pragma unroll
;         for (int j = 0; j < 4; ++j) r4[j] = __shfl(rs[mt], 4 * g + j);
; #pragma unroll
;         for (int nt = 0; nt < 4; ++nt) {
;           const int c = c0 + nt * 16 + lr;
;           bf16_t* dst = VT + ((size_t)(br * NB + b) * 512 + c) * SEQ + s0 + mt * 16 + 4 * g;
;           *(uint2*)dst = make_uint2(pack2(acc[mt][nt][0] * r4[0], acc[mt][nt][1] * r4[1]), pack2(acc[mt][nt][2] * r4[2], acc[mt][nt][3] * r4[3]));
;         }
;       }
	s_nop 4
	v_pk_mul_f32 v[104:105], v[104:105], v[118:119]
	v_pk_mul_f32 v[106:107], v[106:107], v[128:129]
	v_cvt_pk_f16_f32 v104, v104, v105
	v_mfma_f32_16x16x32_f16 v[108:111], v[80:83], v[24:27], v[158:161]
	v_cvt_pk_f16_f32 v105, v106, v107
	global_store_dwordx2 v[98:99], v[104:105], off offset:32
	v_mfma_f32_16x16x32_f16 v[162:165], v[212:215], v[8:11], v[200:203]
	v_mfma_f32_16x16x32_f16 v[166:169], v[212:215], v[4:7], v[204:207]
	v_mfma_f32_16x16x32_f16 v[104:107], v[132:135], v[52:55], v[108:111]
	v_mfma_f32_16x16x32_f16 v[108:111], v[80:83], v[20:23], v[162:165]
	v_mfma_f32_16x16x32_f16 v[80:83], v[80:83], v[16:19], v[166:169]
	s_nop 5
	v_mul_f32_e64 v104, v104, v118
	v_mul_f32_e64 v105, v105, v119
	v_pk_mul_f32 v[106:107], v[106:107], v[128:129]
	v_cvt_pk_f16_f32 v104, v104, v105
	v_cvt_pk_f16_f32 v105, v106, v107
	v_mfma_f32_16x16x32_f16 v[80:83], v[132:135], v[32:35], v[80:83]
	global_store_dwordx2 v[144:145], v[104:105], off
	v_mfma_f32_16x16x32_f16 v[104:107], v[132:135], v[48:51], v[108:111]
	v_mfma_f32_16x16x32_f16 v[124:127], v[220:223], v[56:59], v[124:127]
	s_nop 4
	v_mul_f32_e64 v80, v80, v118
	v_mul_f32_e64 v81, v81, v119
	v_pk_mul_f32 v[104:105], v[104:105], v[118:119]
	v_pk_mul_f32 v[106:107], v[106:107], v[128:129]
	v_mfma_f32_16x16x32_f16 v[56:59], v[0:3], v[56:59], v[72:75]
	v_cvt_pk_f16_f32 v80, v80, v81
	v_lshl_add_u64 v[108:109], v[130:131], 0, v[142:143]
	v_cvt_pk_f16_f32 v104, v104, v105
	v_pk_mul_f32 v[72:73], v[82:83], v[128:129]
	v_cvt_pk_f16_f32 v105, v106, v107
	v_cvt_pk_f16_f32 v81, v72, v73
	v_mfma_f32_16x16x32_f16 v[72:75], v[64:67], v[36:39], v[120:123]
	global_store_dwordx2 v[108:109], v[104:105], off
	v_lshl_add_u64 v[104:105], v[130:131], 0, v[116:117]
	global_store_dwordx2 v[104:105], v[80:81], off
	ds_bpermute_b32 v104, v150, v102
	ds_bpermute_b32 v105, v150, v102 offset:4
	ds_bpermute_b32 v106, v150, v102 offset:8
	v_mfma_f32_16x16x32_f16 v[72:75], v[68:71], v[60:63], v[72:75]
	ds_bpermute_b32 v107, v194, v102
	v_lshl_add_u64 v[102:103], v[94:95], 0, 64
	v_mfma_f32_16x16x32_f16 v[80:83], v[64:67], v[24:27], v[124:127]
	v_mfma_f32_16x16x32_f16 v[136:139], v[220:223], v[8:11], v[136:139]
	s_waitcnt lgkmcnt(2)
	s_nop 2
	v_pk_mul_f32 v[72:73], v[72:73], v[104:105]
	s_nop 0
	v_cvt_pk_f16_f32 v108, v72, v73
	v_mfma_f32_16x16x32_f16 v[112:115], v[220:223], v[4:7], v[224:227]
	s_waitcnt lgkmcnt(0)
	v_pk_mul_f32 v[72:73], v[74:75], v[106:107]
	s_nop 0
	v_cvt_pk_f16_f32 v109, v72, v73
	v_mfma_f32_16x16x32_f16 v[72:75], v[68:71], v[52:55], v[80:83]
	global_store_dwordx2 v[98:99], v[108:109], off offset:64
	v_lshl_add_u64 v[108:109], v[102:103], 0, v[140:141]
	v_mfma_f32_16x16x32_f16 v[80:83], v[64:67], v[20:23], v[136:139]
	v_mfma_f32_16x16x32_f16 v[64:67], v[64:67], v[16:19], v[112:115]
	s_nop 3
	v_mul_f32_e64 v72, v72, v104
	v_mul_f32_e64 v73, v73, v105
	v_cvt_pk_f16_f32 v110, v72, v73
	v_pk_mul_f32 v[72:73], v[74:75], v[106:107]
	v_mfma_f32_16x16x32_f16 v[64:67], v[68:71], v[32:35], v[64:67]
	v_cvt_pk_f16_f32 v111, v72, v73
	global_store_dwordx2 v[108:109], v[110:111], off
	v_mfma_f32_16x16x32_f16 v[72:75], v[68:71], v[48:51], v[80:83]
	v_lshl_add_u64 v[68:69], v[102:103], 0, v[116:117]
	s_nop 3
	v_pk_mul_f32 v[64:65], v[64:65], v[104:105]
	v_mfma_f32_16x16x32_f16 v[8:11], v[0:3], v[8:11], v[40:43]
	v_lshl_add_u64 v[80:81], v[102:103], 0, v[142:143]
	v_pk_mul_f32 v[72:73], v[72:73], v[104:105]
	v_pk_mul_f32 v[74:75], v[74:75], v[106:107]
	v_mfma_f32_16x16x32_f16 v[0:3], v[0:3], v[4:7], v[44:47]
	v_mul_f32_e64 v42, v66, v106
	v_mul_f32_e64 v43, v67, v107
	v_cvt_pk_f16_f32 v72, v72, v73
	v_cvt_pk_f16_f32 v73, v74, v75
	v_mfma_f32_16x16x32_f16 v[4:7], v[12:15], v[36:39], v[76:79]
	v_cvt_pk_f16_f32 v40, v64, v65
	v_cvt_pk_f16_f32 v41, v42, v43
	global_store_dwordx2 v[80:81], v[72:73], off
	global_store_dwordx2 v[68:69], v[40:41], off
	ds_bpermute_b32 v40, v150, v100
	ds_bpermute_b32 v41, v150, v100 offset:4
	ds_bpermute_b32 v36, v150, v100 offset:8
	ds_bpermute_b32 v37, v194, v100
	v_mfma_f32_16x16x32_f16 v[4:7], v[28:31], v[60:63], v[4:7]
	v_lshl_add_u64 v[38:39], v[94:95], 0, s[4:5]
	v_mfma_f32_16x16x32_f16 v[0:3], v[12:15], v[16:19], v[0:3]
	v_mfma_f32_16x16x32_f16 v[0:3], v[28:31], v[32:35], v[0:3]
	s_waitcnt lgkmcnt(2)
	s_nop 3
	v_pk_mul_f32 v[4:5], v[4:5], v[40:41]
	s_waitcnt lgkmcnt(0)
	v_pk_mul_f32 v[44:45], v[6:7], v[36:37]
	v_cvt_pk_f16_f32 v42, v4, v5
	v_mfma_f32_16x16x32_f16 v[4:7], v[12:15], v[24:27], v[56:59]
	v_cvt_pk_f16_f32 v43, v44, v45
	global_store_dwordx2 v[98:99], v[42:43], off offset:96
	v_lshl_add_u64 v[24:25], v[38:39], 0, v[140:141]
	v_mfma_f32_16x16x32_f16 v[4:7], v[28:31], v[52:55], v[4:7]
	v_mul_f32_e64 v0, v0, v40
	v_mul_f32_e64 v1, v1, v41
	v_pk_mul_f32 v[2:3], v[2:3], v[36:37]
	v_cvt_pk_f16_f32 v0, v0, v1
	v_cvt_pk_f16_f32 v1, v2, v3
	s_nop 2
	v_pk_mul_f32 v[4:5], v[4:5], v[40:41]
	v_pk_mul_f32 v[42:43], v[6:7], v[36:37]
	v_cvt_pk_f16_f32 v26, v4, v5
	v_mfma_f32_16x16x32_f16 v[4:7], v[12:15], v[20:23], v[8:11]
	v_cvt_pk_f16_f32 v27, v42, v43
	global_store_dwordx2 v[24:25], v[26:27], off
	v_mfma_f32_16x16x32_f16 v[4:7], v[28:31], v[48:51], v[4:7]
	v_lshl_add_u64 v[8:9], v[38:39], 0, v[142:143]
	s_nop 6
	v_pk_mul_f32 v[4:5], v[4:5], v[40:41]
	v_pk_mul_f32 v[6:7], v[6:7], v[36:37]
	v_cvt_pk_f16_f32 v4, v4, v5
	v_cvt_pk_f16_f32 v5, v6, v7
	global_store_dwordx2 v[8:9], v[4:5], off
	v_lshl_add_u64 v[4:5], v[38:39], 0, v[116:117]
	global_store_dwordx2 v[4:5], v[0:1], off
	s_branch .LBB0_636

; DI int TIDX() { int t = threadIdx.x; asm volatile("" : "+v"(t)); return t; }
; #define GL_LOAD(s_, kt_) if (VAR != 1) { a##s_##0 = GL_A(0, kt_); a##s_##1 = GL_A(1, kt_); a##s_##2 = GL_A(2, kt_); a##s_##3 = GL_A(3, kt_); b##s_##0 = GL_B(0, kt_); b##s_##1 = GL_B(1, kt_); b##s_##2 = GL_B(2, kt_); b##s_##3 = GL_B(3, kt_); }
; #define LDS_STORE(s_, buf_) if (VAR != 2) { LDS_ST1(sA, 0, buf_, a##s_##0) LDS_ST1(sA, 1, buf_, a##s_##1) LDS_ST1(sA, 2, buf_, a##s_##2) LDS_ST1(sA, 3, buf_, a##s_##3) LDS_ST1(sB, 0, buf_, b##s_##0) LDS_ST1(sB, 1, buf_, b##s_##1) LDS_ST1(sB, 2, buf_, b##s_##2) LDS_ST1(sB, 3, buf_, b##s_##3) }
;   const int tid = TIDX(), lane = tid & 63, wid = tid >> 6, wm = wid >> 1, wn = wid & 1, lr = lane & 15, g = lane >> 4;
;   char* sA = smem; char* sB = smem + 2 * LTILE;
;   uint4 a00 = {}, a01 = {}, a02 = {}, a03 = {}, b00 = {}, b01 = {}, b02 = {}, b03 = {}, a10 = {}, a11 = {}, a12 = {}, a13 = {}, b10 = {}, b11 = {}, b12 = {}, b13 = {};
;   constexpr int nk = NK;
;   const int sw0 = (g ^ ((lr >> 1) & 7)) << 4, sw1 = sw0 ^ 64;
;   const int r0 = tid >> 3, kc = tid & 7, kcs = kc ^ ((r0 >> 1) & 7);
;     ...
;   GL_LOAD(0, 0)
;   GL_LOAD(1, 1)
;   LDS_STORE(0, 0)
;   if (VAR != 4) __syncthreads();
; #pragma unroll
;   for (int kt = 0; kt < nk; kt += 2) {
;     if (kt + 2 < nk) { GL_LOAD(0, kt + 2) }
;     MMA_TILE(0)
;     LDS_STORE(1, 1)
;     if (VAR != 4) __syncthreads();
;     if (kt + 3 < nk) { GL_LOAD(1, kt + 3) }
;     MMA_TILE(1)
;     if (kt + 2 < nk) { LDS_STORE(0, 0) }
;     if (VAR != 4) __syncthreads();
; DI void phase_merge(const Params& P, int l, char* smem) {
;     ...
;     for (int br = 0; br < 3; ++br) {
;       f32x4 acc[4][4]; zero_acc(acc);
;       const int ycol = br == 0 ? C_AQ : (br == 1 ? C_BQ : C_CQ);
;       const bf16_t* Wb = W + (br == 0 ? WO_BRA : (br == 1 ? WO_BRB : WO_BRC));
;       gemm_kloop<false, true, 8>(acc, Pb + (size_t)m0 * PW + ycol, PW, Wb + (size_t)n0 * 512, 512, smem);
.LBB0_1161:
	s_cmp_lg_u32 s4, 0
	s_cselect_b64 s[6:7], -1, 0
	s_cmpk_eq_i32 s4, 0x800
	s_mov_b32 s8, 0x860000
	s_cselect_b32 s17, 0x400, s36
	s_cselect_b32 s20, s8, 0x8e0000
	s_cmp_eq_u32 s4, 0
	s_cselect_b64 s[8:9], -1, 0
	s_and_b64 s[18:19], s[8:9], exec
	s_cselect_b32 s17, 0, s17
	s_cselect_b32 s20, 0x7e0000, s20
	s_lshl_b32 s17, s17, 1
	s_add_u32 s18, s13, s17
	s_addc_u32 s19, s14, 0
	v_mov_b32_e32 v56, v148
	v_mov_b64_e32 v[6:7], s[18:19]
	v_ashrrev_i32_e32 v16, 3, v56
	v_lshlrev_b32_e32 v57, 4, v56
	v_mad_i64_i32 v[0:1], s[18:19], v16, s0, v[6:7]
	v_and_b32_e32 v150, 0x70, v57
	v_add_u32_e32 v18, 32, v16
	s_lshl_b32 s17, s20, 1
	v_lshl_add_u64 v[0:1], v[0:1], 0, v[150:151]
	v_mad_i64_i32 v[2:3], s[18:19], v18, s0, v[6:7]
	v_add_u32_e32 v52, 64, v16
	s_add_u32 s20, s15, s17
	v_ashrrev_i32_e32 v17, 31, v16
	global_load_dwordx4 v[20:23], v[0:1], off
	v_lshl_add_u64 v[2:3], v[2:3], 0, v[150:151]
	v_mad_i64_i32 v[4:5], s[18:19], v52, s0, v[6:7]
	v_add_u32_e32 v54, 0x60, v16
	s_addc_u32 s21, s16, 0
	v_ashrrev_i32_e32 v19, 31, v18
	global_load_dwordx4 v[24:27], v[2:3], off
	v_lshl_add_u64 v[4:5], v[4:5], 0, v[150:151]
	v_mad_i64_i32 v[6:7], s[18:19], v54, s0, v[6:7]
	v_lshlrev_b64 v[8:9], 10, v[16:17]
	v_ashrrev_i32_e32 v53, 31, v52
	global_load_dwordx4 v[28:31], v[4:5], off
	v_lshl_add_u64 v[6:7], v[6:7], 0, v[150:151]
	v_lshl_add_u64 v[8:9], s[20:21], 0, v[8:9]
	v_lshlrev_b64 v[10:11], 10, v[18:19]
	v_ashrrev_i32_e32 v55, 31, v54
	global_load_dwordx4 v[32:35], v[6:7], off
	v_lshl_add_u64 v[8:9], v[8:9], 0, v[150:151]
	v_lshl_add_u64 v[10:11], s[20:21], 0, v[10:11]
	v_lshlrev_b64 v[12:13], 10, v[52:53]
	global_load_dwordx4 v[36:39], v[8:9], off
	v_lshl_add_u64 v[10:11], v[10:11], 0, v[150:151]
	v_lshl_add_u64 v[12:13], s[20:21], 0, v[12:13]
	v_lshlrev_b64 v[14:15], 10, v[54:55]
	global_load_dwordx4 v[40:43], v[10:11], off
	v_lshl_add_u64 v[12:13], v[12:13], 0, v[150:151]
	v_lshl_add_u64 v[14:15], s[20:21], 0, v[14:15]
	global_load_dwordx4 v[44:47], v[12:13], off
	v_lshl_add_u64 v[14:15], v[14:15], 0, v[150:151]
	global_load_dwordx4 v[48:51], v[14:15], off
	v_lshlrev_b32_e32 v19, 3, v56
	v_and_b32_e32 v108, 48, v56
	v_and_b32_e32 v17, 15, v56
	v_lshrrev_b32_e32 v53, 1, v56
	v_lshlrev_b32_e32 v55, 7, v56
	v_and_b32_e32 v109, 0x70, v19
	v_bitop3_b32 v115, v19, v108, s23 bitop3:0x6c
	v_bitop3_b32 v19, v57, s23, v56 bitop3:0x48
	v_and_or_b32 v136, v53, s24, v17
	v_and_b32_e32 v150, 0x2780, v55
	v_lshl_or_b32 v16, v16, 7, v19
	v_lshl_or_b32 v17, v18, 7, v19
	v_lshl_or_b32 v18, v52, 7, v19
	v_lshl_or_b32 v19, v54, 7, v19
	global_load_dwordx4 v[52:55], v[0:1], off offset:128
	global_load_dwordx4 v[56:59], v[2:3], off offset:128
	global_load_dwordx4 v[104:107], v[4:5], off offset:128
	global_load_dwordx4 v[116:119], v[6:7], off offset:128
	global_load_dwordx4 v[120:123], v[8:9], off offset:128
	global_load_dwordx4 v[124:127], v[10:11], off offset:128
	global_load_dwordx4 v[128:131], v[12:13], off offset:128
	global_load_dwordx4 v[132:135], v[14:15], off offset:128
	s_and_b64 vcc, s[8:9], exec
	s_waitcnt vmcnt(15)
	ds_write_b128 v16, v[20:23]
	s_waitcnt vmcnt(14)
	ds_write_b128 v17, v[24:27]
	s_waitcnt vmcnt(13)
	ds_write_b128 v18, v[28:31]
	s_waitcnt vmcnt(12)
	ds_write_b128 v19, v[32:35]
	s_waitcnt vmcnt(11)
	ds_write_b128 v16, v[36:39] offset:32768
	s_waitcnt vmcnt(10)
	ds_write_b128 v17, v[40:43] offset:32768
	s_waitcnt vmcnt(9)
	ds_write_b128 v18, v[44:47] offset:32768
	s_waitcnt vmcnt(8)
	ds_write_b128 v19, v[48:51] offset:32768
	v_or_b32_e32 v20, v150, v115
	s_waitcnt lgkmcnt(0)
	s_barrier
	s_setprio 1
	ds_read_b128 v[22:25], v20 offset:32768
	v_lshlrev_b32_e32 v50, 7, v136
	v_bitop3_b32 v21, v50, v109, v108 bitop3:0xf6
	ds_read_b128 v[30:33], v21
	s_waitcnt lgkmcnt(0)
	v_mfma_f32_16x16x32_f16 v[38:41], v[22:25], v[30:33], 0
	ds_read_b128 v[26:29], v20 offset:34816
	ds_read_b128 v[34:37], v21 offset:2048
	s_waitcnt lgkmcnt(0)
	v_mfma_f32_16x16x32_f16 v[144:147], v[22:25], v[34:37], 0
	ds_read_b128 v[42:45], v20 offset:36864
	ds_read_b128 v[162:165], v21 offset:4096
	s_waitcnt lgkmcnt(0)
	v_mfma_f32_16x16x32_f16 v[190:193], v[22:25], v[162:165], 0
	ds_read_b128 v[136:139], v20 offset:38912
	ds_read_b128 v[166:169], v21 offset:6144
	s_waitcnt lgkmcnt(0)
	v_mfma_f32_16x16x32_f16 v[202:205], v[22:25], v[166:169], 0
	v_lshl_add_u64 v[108:109], v[80:81], 0, s[4:5]
	v_mfma_f32_16x16x32_f16 v[46:49], v[26:29], v[30:33], 0
	v_xor_b32_e32 v22, 64, v115
	v_mfma_f32_16x16x32_f16 v[140:143], v[42:45], v[30:33], 0
	v_or_b32_e32 v23, v150, v22
	v_mfma_f32_16x16x32_f16 v[30:33], v[136:139], v[30:33], 0
	ds_read_b128 v[206:209], v23 offset:32768
	v_mfma_f32_16x16x32_f16 v[154:157], v[26:29], v[34:37], 0
	ds_read_b128 v[224:227], v23 offset:36864
	v_mfma_f32_16x16x32_f16 v[158:161], v[42:45], v[34:37], 0
	ds_read_b128 v[228:231], v23 offset:38912
	v_mfma_f32_16x16x32_f16 v[34:37], v[136:139], v[34:37], 0
	v_bitop3_b32 v22, v50, v115, 64 bitop3:0xf6
	v_mfma_f32_16x16x32_f16 v[194:197], v[26:29], v[162:165], 0
	ds_read_b128 v[210:213], v22
	v_mfma_f32_16x16x32_f16 v[198:201], v[42:45], v[162:165], 0
	ds_read_b128 v[220:223], v22 offset:2048
	v_mfma_f32_16x16x32_f16 v[162:165], v[136:139], v[162:165], 0
	s_waitcnt vmcnt(7)
	ds_write_b128 v16, v[52:55] offset:16384
	v_mfma_f32_16x16x32_f16 v[24:27], v[26:29], v[166:169], 0
	s_waitcnt vmcnt(6)
	ds_write_b128 v17, v[56:59] offset:16384
	v_mfma_f32_16x16x32_f16 v[42:45], v[42:45], v[166:169], 0
	s_waitcnt vmcnt(5)
	ds_write_b128 v18, v[104:107] offset:16384
	v_mfma_f32_16x16x32_f16 v[136:139], v[136:139], v[166:169], 0
	ds_read_b128 v[166:169], v23 offset:34816
	s_waitcnt lgkmcnt(5)
; #define GL_LOAD(s_, kt_) if (VAR != 1) { a##s_##0 = GL_A(0, kt_); a##s_##1 = GL_A(1, kt_); a##s_##2 = GL_A(2, kt_); a##s_##3 = GL_A(3, kt_); b##s_##0 = GL_B(0, kt_); b##s_##1 = GL_B(1, kt_); b##s_##2 = GL_B(2, kt_); b##s_##3 = GL_B(3, kt_); }
; #define LDS_STORE(s_, buf_) if (VAR != 2) { LDS_ST1(sA, 0, buf_, a##s_##0) LDS_ST1(sA, 1, buf_, a##s_##1) LDS_ST1(sA, 2, buf_, a##s_##2) LDS_ST1(sA, 3, buf_, a##s_##3) LDS_ST1(sB, 0, buf_, b##s_##0) LDS_ST1(sB, 1, buf_, b##s_##1) LDS_ST1(sB, 2, buf_, b##s_##2) LDS_ST1(sB, 3, buf_, b##s_##3) }
;     ...
;   GL_LOAD(0, 0)
;   GL_LOAD(1, 1)
;   LDS_STORE(0, 0)
;   if (VAR != 4) __syncthreads();
; #pragma unroll
;   for (int kt = 0; kt < nk; kt += 2) {
;     if (kt + 2 < nk) { GL_LOAD(0, kt + 2) }
;     MMA_TILE(0)
;     LDS_STORE(1, 1)
;     if (VAR != 4) __syncthreads();
;     if (kt + 3 < nk) { GL_LOAD(1, kt + 3) }
;     MMA_TILE(1)
;     if (kt + 2 < nk) { LDS_STORE(0, 0) }
;     if (VAR != 4) __syncthreads();
	v_mfma_f32_16x16x32_f16 v[38:41], v[206:209], v[210:213], v[38:41]
	s_waitcnt vmcnt(4)
	ds_write_b128 v19, v[116:119] offset:16384
	v_mfma_f32_16x16x32_f16 v[140:143], v[224:227], v[210:213], v[140:143]
	s_waitcnt vmcnt(3)
	ds_write_b128 v16, v[120:123] offset:49152
	v_mfma_f32_16x16x32_f16 v[28:31], v[228:231], v[210:213], v[30:33]
	s_waitcnt vmcnt(2)
	ds_write_b128 v17, v[124:127] offset:49152
	s_waitcnt lgkmcnt(7)
	v_mfma_f32_16x16x32_f16 v[144:147], v[206:209], v[220:223], v[144:147]
	s_waitcnt vmcnt(1)
	ds_write_b128 v18, v[128:131] offset:49152
	v_mfma_f32_16x16x32_f16 v[158:161], v[224:227], v[220:223], v[158:161]
	s_waitcnt vmcnt(0)
	ds_write_b128 v19, v[132:135] offset:49152
	v_mfma_f32_16x16x32_f16 v[32:35], v[228:231], v[220:223], v[34:37]
	s_waitcnt lgkmcnt(5)
	v_mfma_f32_16x16x32_f16 v[46:49], v[166:169], v[210:213], v[46:49]
	ds_read_b128 v[210:213], v22 offset:4096
	v_mfma_f32_16x16x32_f16 v[154:157], v[166:169], v[220:223], v[154:157]
	ds_read_b128 v[220:223], v22 offset:6144
	s_waitcnt lgkmcnt(1)
	v_mfma_f32_16x16x32_f16 v[190:193], v[206:209], v[210:213], v[190:193]
	s_waitcnt lgkmcnt(0)
	v_mfma_f32_16x16x32_f16 v[202:205], v[206:209], v[220:223], v[202:205]
	global_load_dwordx4 v[206:209], v[0:1], off offset:256
	v_mfma_f32_16x16x32_f16 v[194:197], v[166:169], v[210:213], v[194:197]
	v_mfma_f32_16x16x32_f16 v[24:27], v[166:169], v[220:223], v[24:27]
	v_mfma_f32_16x16x32_f16 v[198:201], v[224:227], v[210:213], v[198:201]
	v_mfma_f32_16x16x32_f16 v[162:165], v[228:231], v[210:213], v[162:165]
	global_load_dwordx4 v[210:213], v[2:3], off offset:256
	global_load_dwordx4 v[232:235], v[4:5], off offset:256
	global_load_dwordx4 v[236:239], v[6:7], off offset:256
	global_load_dwordx4 v[166:169], v[8:9], off offset:256
	global_load_dwordx4 v[240:243], v[10:11], off offset:256
	global_load_dwordx4 v[244:247], v[12:13], off offset:256
	global_load_dwordx4 v[248:251], v[14:15], off offset:256
	s_waitcnt lgkmcnt(0)
	s_barrier
	v_mfma_f32_16x16x32_f16 v[54:57], v[228:231], v[220:223], v[136:139]
	ds_read_b128 v[50:53], v20 offset:49152
	v_mfma_f32_16x16x32_f16 v[42:45], v[224:227], v[220:223], v[42:45]
	ds_read_b128 v[104:107], v20 offset:51200
	ds_read_b128 v[116:119], v21 offset:16384
	s_waitcnt lgkmcnt(0)
	v_mfma_f32_16x16x32_f16 v[36:39], v[50:53], v[116:119], v[38:41]
	ds_read_b128 v[120:123], v21 offset:18432
	v_mfma_f32_16x16x32_f16 v[46:49], v[104:107], v[116:119], v[46:49]
	ds_read_b128 v[124:127], v20 offset:53248
	s_waitcnt lgkmcnt(0)
	v_mfma_f32_16x16x32_f16 v[132:135], v[124:127], v[116:119], v[140:143]
	ds_read_b128 v[128:131], v20 offset:55296
	s_waitcnt lgkmcnt(0)
	v_mfma_f32_16x16x32_f16 v[28:31], v[128:131], v[116:119], v[28:31]
	v_mfma_f32_16x16x32_f16 v[116:119], v[50:53], v[120:123], v[144:147]
	s_nop 2
	ds_read_b128 v[144:147], v21 offset:22528
	s_waitcnt vmcnt(7)
	ds_write_b128 v16, v[206:209]
	v_mfma_f32_16x16x32_f16 v[136:139], v[104:107], v[120:123], v[154:157]
	s_waitcnt vmcnt(6)
	ds_write_b128 v17, v[210:213]
	s_waitcnt vmcnt(5)
	ds_write_b128 v18, v[232:235]
	v_mfma_f32_16x16x32_f16 v[140:143], v[124:127], v[120:123], v[158:161]
	s_waitcnt vmcnt(4)
	ds_write_b128 v19, v[236:239]
	s_waitcnt vmcnt(3)
	ds_write_b128 v16, v[166:169] offset:32768
	v_mfma_f32_16x16x32_f16 v[32:35], v[128:131], v[120:123], v[32:35]
	ds_read_b128 v[120:123], v21 offset:20480
	s_waitcnt lgkmcnt(0)
	v_mfma_f32_16x16x32_f16 v[154:157], v[50:53], v[120:123], v[190:193]
	s_waitcnt vmcnt(2)
	ds_write_b128 v17, v[240:243] offset:32768
	v_mfma_f32_16x16x32_f16 v[50:53], v[50:53], v[144:147], v[202:205]
	s_waitcnt vmcnt(1)
	ds_write_b128 v18, v[244:247] offset:32768
	v_mfma_f32_16x16x32_f16 v[158:161], v[104:107], v[120:123], v[194:197]
	s_nop 2
	ds_read_b128 v[194:197], v23 offset:55296
	v_mfma_f32_16x16x32_f16 v[24:27], v[104:107], v[144:147], v[24:27]
	ds_read_b128 v[104:107], v23 offset:49152
	v_mfma_f32_16x16x32_f16 v[190:193], v[124:127], v[120:123], v[198:201]
	s_waitcnt vmcnt(0)
	ds_write_b128 v19, v[248:251] offset:32768
	v_mfma_f32_16x16x32_f16 v[40:43], v[124:127], v[144:147], v[42:45]
	ds_read_b128 v[124:127], v23 offset:51200
	v_mfma_f32_16x16x32_f16 v[120:123], v[128:131], v[120:123], v[162:165]
	s_nop 2
	ds_read_b128 v[162:165], v23 offset:53248
	v_mfma_f32_16x16x32_f16 v[54:57], v[128:131], v[144:147], v[54:57]
	ds_read_b128 v[128:131], v22 offset:16384
	s_waitcnt lgkmcnt(0)
	v_mfma_f32_16x16x32_f16 v[36:39], v[104:107], v[128:131], v[36:39]
	ds_read_b128 v[144:147], v22 offset:18432
	s_waitcnt lgkmcnt(0)
	v_mfma_f32_16x16x32_f16 v[116:119], v[104:107], v[144:147], v[116:119]
	v_mfma_f32_16x16x32_f16 v[44:47], v[124:127], v[128:131], v[46:49]
	v_mfma_f32_16x16x32_f16 v[132:135], v[162:165], v[128:131], v[132:135]
	v_mfma_f32_16x16x32_f16 v[28:31], v[194:197], v[128:131], v[28:31]
	v_mfma_f32_16x16x32_f16 v[128:131], v[124:127], v[144:147], v[136:139]
	v_mfma_f32_16x16x32_f16 v[136:139], v[162:165], v[144:147], v[140:143]
	s_nop 2
	ds_read_b128 v[140:143], v22 offset:20480
	v_mfma_f32_16x16x32_f16 v[32:35], v[194:197], v[144:147], v[32:35]
	ds_read_b128 v[144:147], v22 offset:22528
	s_waitcnt lgkmcnt(1)
	v_mfma_f32_16x16x32_f16 v[154:157], v[104:107], v[140:143], v[154:157]
	s_waitcnt lgkmcnt(0)
	v_mfma_f32_16x16x32_f16 v[48:51], v[104:107], v[144:147], v[50:53]
	global_load_dwordx4 v[104:107], v[0:1], off offset:384
	v_mfma_f32_16x16x32_f16 v[158:161], v[124:127], v[140:143], v[158:161]
	v_mfma_f32_16x16x32_f16 v[24:27], v[124:127], v[144:147], v[24:27]
	v_mfma_f32_16x16x32_f16 v[190:193], v[162:165], v[140:143], v[190:193]
	v_mfma_f32_16x16x32_f16 v[40:43], v[162:165], v[144:147], v[40:43]
	v_mfma_f32_16x16x32_f16 v[120:123], v[194:197], v[140:143], v[120:123]
	global_load_dwordx4 v[140:143], v[2:3], off offset:384
	global_load_dwordx4 v[198:201], v[4:5], off offset:384
	global_load_dwordx4 v[202:205], v[6:7], off offset:384
	global_load_dwordx4 v[124:127], v[8:9], off offset:384
	global_load_dwordx4 v[220:223], v[10:11], off offset:384
	global_load_dwordx4 v[224:227], v[12:13], off offset:384
	global_load_dwordx4 v[228:231], v[14:15], off offset:384
	s_waitcnt lgkmcnt(0)
	s_barrier
; #define GL_LOAD(s_, kt_) if (VAR != 1) { a##s_##0 = GL_A(0, kt_); a##s_##1 = GL_A(1, kt_); a##s_##2 = GL_A(2, kt_); a##s_##3 = GL_A(3, kt_); b##s_##0 = GL_B(0, kt_); b##s_##1 = GL_B(1, kt_); b##s_##2 = GL_B(2, kt_); b##s_##3 = GL_B(3, kt_); }
; #define LDS_STORE(s_, buf_) if (VAR != 2) { LDS_ST1(sA, 0, buf_, a##s_##0) LDS_ST1(sA, 1, buf_, a##s_##1) LDS_ST1(sA, 2, buf_, a##s_##2) LDS_ST1(sA, 3, buf_, a##s_##3) LDS_ST1(sB, 0, buf_, b##s_##0) LDS_ST1(sB, 1, buf_, b##s_##1) LDS_ST1(sB, 2, buf_, b##s_##2) LDS_ST1(sB, 3, buf_, b##s_##3) }
;     ...
;   GL_LOAD(0, 0)
;   GL_LOAD(1, 1)
;   LDS_STORE(0, 0)
;   if (VAR != 4) __syncthreads();
; #pragma unroll
;   for (int kt = 0; kt < nk; kt += 2) {
;     if (kt + 2 < nk) { GL_LOAD(0, kt + 2) }
;     MMA_TILE(0)
;     LDS_STORE(1, 1)
;     if (VAR != 4) __syncthreads();
;     if (kt + 3 < nk) { GL_LOAD(1, kt + 3) }
;     MMA_TILE(1)
;     if (kt + 2 < nk) { LDS_STORE(0, 0) }
;     if (VAR != 4) __syncthreads();
	v_mfma_f32_16x16x32_f16 v[52:55], v[194:197], v[144:147], v[54:57]
	ds_read_b128 v[162:165], v20 offset:32768
	ds_read_b128 v[144:147], v21
	s_waitcnt lgkmcnt(0)
	v_mfma_f32_16x16x32_f16 v[36:39], v[162:165], v[144:147], v[36:39]
	ds_read_b128 v[56:59], v20 offset:34816
	ds_read_b128 v[166:169], v21 offset:2048
	s_waitcnt lgkmcnt(0)
	v_mfma_f32_16x16x32_f16 v[116:119], v[162:165], v[166:169], v[116:119]
	ds_read_b128 v[194:197], v20 offset:36864
	v_mfma_f32_16x16x32_f16 v[44:47], v[56:59], v[144:147], v[44:47]
	ds_read_b128 v[206:209], v20 offset:38912
	v_mfma_f32_16x16x32_f16 v[128:131], v[56:59], v[166:169], v[128:131]
	s_waitcnt vmcnt(7)
	ds_write_b128 v16, v[104:107] offset:16384
	s_waitcnt lgkmcnt(2)
	v_mfma_f32_16x16x32_f16 v[132:135], v[194:197], v[144:147], v[132:135]
	s_waitcnt vmcnt(6)
	ds_write_b128 v17, v[140:143] offset:16384
	v_mfma_f32_16x16x32_f16 v[136:139], v[194:197], v[166:169], v[136:139]
	s_waitcnt vmcnt(5)
	ds_write_b128 v18, v[198:201] offset:16384
	s_waitcnt lgkmcnt(3)
	v_mfma_f32_16x16x32_f16 v[28:31], v[206:209], v[144:147], v[28:31]
	ds_read_b128 v[144:147], v21 offset:4096
	v_mfma_f32_16x16x32_f16 v[32:35], v[206:209], v[166:169], v[32:35]
	ds_read_b128 v[166:169], v21 offset:6144
	s_waitcnt lgkmcnt(1)
	v_mfma_f32_16x16x32_f16 v[154:157], v[162:165], v[144:147], v[154:157]
	s_waitcnt vmcnt(4)
	ds_write_b128 v19, v[202:205] offset:16384
	s_waitcnt lgkmcnt(1)
	v_mfma_f32_16x16x32_f16 v[48:51], v[162:165], v[166:169], v[48:51]
	ds_read_b128 v[162:165], v22
	v_mfma_f32_16x16x32_f16 v[158:161], v[56:59], v[144:147], v[158:161]
	s_waitcnt vmcnt(3)
	ds_write_b128 v16, v[124:127] offset:49152
	v_mfma_f32_16x16x32_f16 v[24:27], v[56:59], v[166:169], v[24:27]
	ds_read_b128 v[56:59], v23 offset:32768
	v_mfma_f32_16x16x32_f16 v[190:193], v[194:197], v[144:147], v[190:193]
	s_waitcnt vmcnt(2)
	ds_write_b128 v17, v[220:223] offset:49152
	v_mfma_f32_16x16x32_f16 v[40:43], v[194:197], v[166:169], v[40:43]
	ds_read_b128 v[194:197], v23 offset:36864
	v_mfma_f32_16x16x32_f16 v[120:123], v[206:209], v[144:147], v[120:123]
	ds_read_b128 v[144:147], v23 offset:34816
	v_mfma_f32_16x16x32_f16 v[52:55], v[206:209], v[166:169], v[52:55]
	ds_read_b128 v[166:169], v22 offset:2048
	s_waitcnt lgkmcnt(4)
	v_mfma_f32_16x16x32_f16 v[36:39], v[56:59], v[162:165], v[36:39]
	ds_read_b128 v[206:209], v23 offset:38912
	s_waitcnt lgkmcnt(1)
	v_mfma_f32_16x16x32_f16 v[116:119], v[56:59], v[166:169], v[116:119]
	s_waitcnt vmcnt(1)
	ds_write_b128 v18, v[224:227] offset:49152
	v_mfma_f32_16x16x32_f16 v[44:47], v[144:147], v[162:165], v[44:47]
	s_waitcnt vmcnt(0)
	ds_write_b128 v19, v[228:231] offset:49152
	v_mfma_f32_16x16x32_f16 v[128:131], v[144:147], v[166:169], v[128:131]
	v_mfma_f32_16x16x32_f16 v[132:135], v[194:197], v[162:165], v[132:135]
	v_mfma_f32_16x16x32_f16 v[136:139], v[194:197], v[166:169], v[136:139]
	s_waitcnt lgkmcnt(2)
	v_mfma_f32_16x16x32_f16 v[28:31], v[206:209], v[162:165], v[28:31]
	ds_read_b128 v[162:165], v22 offset:4096
	v_mfma_f32_16x16x32_f16 v[32:35], v[206:209], v[166:169], v[32:35]
	ds_read_b128 v[166:169], v22 offset:6144
	s_waitcnt lgkmcnt(1)
	v_mfma_f32_16x16x32_f16 v[154:157], v[56:59], v[162:165], v[154:157]
	s_waitcnt lgkmcnt(0)
	v_mfma_f32_16x16x32_f16 v[48:51], v[56:59], v[166:169], v[48:51]
	global_load_dwordx4 v[56:59], v[0:1], off offset:512
	v_mfma_f32_16x16x32_f16 v[158:161], v[144:147], v[162:165], v[158:161]
	v_mfma_f32_16x16x32_f16 v[24:27], v[144:147], v[166:169], v[24:27]
	v_mfma_f32_16x16x32_f16 v[190:193], v[194:197], v[162:165], v[190:193]
	v_mfma_f32_16x16x32_f16 v[40:43], v[194:197], v[166:169], v[40:43]
	v_mfma_f32_16x16x32_f16 v[120:123], v[206:209], v[162:165], v[120:123]
	global_load_dwordx4 v[162:165], v[2:3], off offset:512
	global_load_dwordx4 v[210:213], v[4:5], off offset:512
	global_load_dwordx4 v[232:235], v[6:7], off offset:512
	global_load_dwordx4 v[144:147], v[8:9], off offset:512
	global_load_dwordx4 v[236:239], v[10:11], off offset:512
	global_load_dwordx4 v[240:243], v[12:13], off offset:512
	global_load_dwordx4 v[244:247], v[14:15], off offset:512
	s_waitcnt lgkmcnt(0)
	s_barrier
	v_mfma_f32_16x16x32_f16 v[52:55], v[206:209], v[166:169], v[52:55]
	ds_read_b128 v[104:107], v20 offset:49152
	ds_read_b128 v[140:143], v21 offset:16384
	s_waitcnt lgkmcnt(0)
	v_mfma_f32_16x16x32_f16 v[36:39], v[104:107], v[140:143], v[36:39]
	ds_read_b128 v[124:127], v20 offset:51200
	ds_read_b128 v[166:169], v21 offset:18432
	s_waitcnt lgkmcnt(0)
	v_mfma_f32_16x16x32_f16 v[116:119], v[104:107], v[166:169], v[116:119]
	ds_read_b128 v[194:197], v20 offset:53248
	v_mfma_f32_16x16x32_f16 v[44:47], v[124:127], v[140:143], v[44:47]
	ds_read_b128 v[198:201], v20 offset:55296
	v_mfma_f32_16x16x32_f16 v[128:131], v[124:127], v[166:169], v[128:131]
	s_waitcnt vmcnt(7)
	ds_write_b128 v16, v[56:59]
	s_waitcnt lgkmcnt(2)
	v_mfma_f32_16x16x32_f16 v[132:135], v[194:197], v[140:143], v[132:135]
	s_waitcnt vmcnt(6)
	ds_write_b128 v17, v[162:165]
	v_mfma_f32_16x16x32_f16 v[136:139], v[194:197], v[166:169], v[136:139]
	s_waitcnt vmcnt(5)
	ds_write_b128 v18, v[210:213]
	s_waitcnt lgkmcnt(3)
	v_mfma_f32_16x16x32_f16 v[28:31], v[198:201], v[140:143], v[28:31]
	ds_read_b128 v[140:143], v21 offset:20480
	v_mfma_f32_16x16x32_f16 v[32:35], v[198:201], v[166:169], v[32:35]
	ds_read_b128 v[166:169], v21 offset:22528
	s_waitcnt lgkmcnt(1)
	v_mfma_f32_16x16x32_f16 v[154:157], v[104:107], v[140:143], v[154:157]
	s_waitcnt vmcnt(4)
	ds_write_b128 v19, v[232:235]
	s_waitcnt lgkmcnt(1)
	v_mfma_f32_16x16x32_f16 v[48:51], v[104:107], v[166:169], v[48:51]
	ds_read_b128 v[104:107], v23 offset:49152
	v_mfma_f32_16x16x32_f16 v[158:161], v[124:127], v[140:143], v[158:161]
	s_waitcnt vmcnt(3)
; #define GL_LOAD(s_, kt_) if (VAR != 1) { a##s_##0 = GL_A(0, kt_); a##s_##1 = GL_A(1, kt_); a##s_##2 = GL_A(2, kt_); a##s_##3 = GL_A(3, kt_); b##s_##0 = GL_B(0, kt_); b##s_##1 = GL_B(1, kt_); b##s_##2 = GL_B(2, kt_); b##s_##3 = GL_B(3, kt_); }
; #define LDS_STORE(s_, buf_) if (VAR != 2) { LDS_ST1(sA, 0, buf_, a##s_##0) LDS_ST1(sA, 1, buf_, a##s_##1) LDS_ST1(sA, 2, buf_, a##s_##2) LDS_ST1(sA, 3, buf_, a##s_##3) LDS_ST1(sB, 0, buf_, b##s_##0) LDS_ST1(sB, 1, buf_, b##s_##1) LDS_ST1(sB, 2, buf_, b##s_##2) LDS_ST1(sB, 3, buf_, b##s_##3) }
;     ...
;   GL_LOAD(0, 0)
;   GL_LOAD(1, 1)
;   LDS_STORE(0, 0)
;   if (VAR != 4) __syncthreads();
; #pragma unroll
;   for (int kt = 0; kt < nk; kt += 2) {
;     if (kt + 2 < nk) { GL_LOAD(0, kt + 2) }
;     MMA_TILE(0)
;     LDS_STORE(1, 1)
;     if (VAR != 4) __syncthreads();
;     if (kt + 3 < nk) { GL_LOAD(1, kt + 3) }
;     MMA_TILE(1)
;     if (kt + 2 < nk) { LDS_STORE(0, 0) }
;     if (VAR != 4) __syncthreads();
	ds_write_b128 v16, v[144:147] offset:32768
	v_mfma_f32_16x16x32_f16 v[24:27], v[124:127], v[166:169], v[24:27]
	ds_read_b128 v[124:127], v23 offset:51200
	v_mfma_f32_16x16x32_f16 v[190:193], v[194:197], v[140:143], v[190:193]
	s_waitcnt vmcnt(2)
	ds_write_b128 v17, v[236:239] offset:32768
	v_mfma_f32_16x16x32_f16 v[40:43], v[194:197], v[166:169], v[40:43]
	ds_read_b128 v[194:197], v23 offset:53248
	v_mfma_f32_16x16x32_f16 v[120:123], v[198:201], v[140:143], v[120:123]
	ds_read_b128 v[140:143], v22 offset:16384
	v_mfma_f32_16x16x32_f16 v[52:55], v[198:201], v[166:169], v[52:55]
	ds_read_b128 v[166:169], v22 offset:18432
	s_waitcnt lgkmcnt(1)
	v_mfma_f32_16x16x32_f16 v[36:39], v[104:107], v[140:143], v[36:39]
	ds_read_b128 v[198:201], v23 offset:55296
	s_waitcnt lgkmcnt(1)
	v_mfma_f32_16x16x32_f16 v[116:119], v[104:107], v[166:169], v[116:119]
	s_waitcnt vmcnt(1)
	ds_write_b128 v18, v[240:243] offset:32768
	v_mfma_f32_16x16x32_f16 v[44:47], v[124:127], v[140:143], v[44:47]
	s_waitcnt vmcnt(0)
	ds_write_b128 v19, v[244:247] offset:32768
	v_mfma_f32_16x16x32_f16 v[128:131], v[124:127], v[166:169], v[128:131]
	v_mfma_f32_16x16x32_f16 v[132:135], v[194:197], v[140:143], v[132:135]
	v_mfma_f32_16x16x32_f16 v[136:139], v[194:197], v[166:169], v[136:139]
	s_waitcnt lgkmcnt(2)
	v_mfma_f32_16x16x32_f16 v[28:31], v[198:201], v[140:143], v[28:31]
	ds_read_b128 v[140:143], v22 offset:20480
	v_mfma_f32_16x16x32_f16 v[32:35], v[198:201], v[166:169], v[32:35]
	ds_read_b128 v[166:169], v22 offset:22528
	s_waitcnt lgkmcnt(1)
	v_mfma_f32_16x16x32_f16 v[154:157], v[104:107], v[140:143], v[154:157]
	s_waitcnt lgkmcnt(0)
	v_mfma_f32_16x16x32_f16 v[48:51], v[104:107], v[166:169], v[48:51]
	global_load_dwordx4 v[104:107], v[0:1], off offset:640
	v_mfma_f32_16x16x32_f16 v[158:161], v[124:127], v[140:143], v[158:161]
	v_mfma_f32_16x16x32_f16 v[24:27], v[124:127], v[166:169], v[24:27]
	v_mfma_f32_16x16x32_f16 v[190:193], v[194:197], v[140:143], v[190:193]
	v_mfma_f32_16x16x32_f16 v[40:43], v[194:197], v[166:169], v[40:43]
	v_mfma_f32_16x16x32_f16 v[120:123], v[198:201], v[140:143], v[120:123]
	global_load_dwordx4 v[140:143], v[2:3], off offset:640
	global_load_dwordx4 v[202:205], v[4:5], off offset:640
	global_load_dwordx4 v[206:209], v[6:7], off offset:640
	global_load_dwordx4 v[124:127], v[8:9], off offset:640
	global_load_dwordx4 v[220:223], v[10:11], off offset:640
	global_load_dwordx4 v[224:227], v[12:13], off offset:640
	global_load_dwordx4 v[228:231], v[14:15], off offset:640
	s_waitcnt lgkmcnt(0)
	s_barrier
	v_mfma_f32_16x16x32_f16 v[52:55], v[198:201], v[166:169], v[52:55]
	ds_read_b128 v[56:59], v20 offset:32768
	ds_read_b128 v[162:165], v21
	s_waitcnt lgkmcnt(0)
	v_mfma_f32_16x16x32_f16 v[36:39], v[56:59], v[162:165], v[36:39]
	ds_read_b128 v[144:147], v20 offset:34816
	ds_read_b128 v[166:169], v21 offset:2048
	s_waitcnt lgkmcnt(0)
	v_mfma_f32_16x16x32_f16 v[116:119], v[56:59], v[166:169], v[116:119]
	ds_read_b128 v[194:197], v20 offset:36864
	v_mfma_f32_16x16x32_f16 v[44:47], v[144:147], v[162:165], v[44:47]
	ds_read_b128 v[198:201], v20 offset:38912
	v_mfma_f32_16x16x32_f16 v[128:131], v[144:147], v[166:169], v[128:131]
	s_waitcnt vmcnt(7)
	ds_write_b128 v16, v[104:107] offset:16384
	s_waitcnt lgkmcnt(2)
	v_mfma_f32_16x16x32_f16 v[132:135], v[194:197], v[162:165], v[132:135]
	s_waitcnt vmcnt(6)
	ds_write_b128 v17, v[140:143] offset:16384
	v_mfma_f32_16x16x32_f16 v[136:139], v[194:197], v[166:169], v[136:139]
	s_waitcnt vmcnt(5)
	ds_write_b128 v18, v[202:205] offset:16384
	s_waitcnt lgkmcnt(3)
	v_mfma_f32_16x16x32_f16 v[28:31], v[198:201], v[162:165], v[28:31]
	ds_read_b128 v[162:165], v21 offset:4096
	v_mfma_f32_16x16x32_f16 v[32:35], v[198:201], v[166:169], v[32:35]
	ds_read_b128 v[166:169], v21 offset:6144
	s_waitcnt lgkmcnt(1)
	v_mfma_f32_16x16x32_f16 v[154:157], v[56:59], v[162:165], v[154:157]
	s_waitcnt vmcnt(4)
	ds_write_b128 v19, v[206:209] offset:16384
	s_waitcnt lgkmcnt(1)
	v_mfma_f32_16x16x32_f16 v[48:51], v[56:59], v[166:169], v[48:51]
	ds_read_b128 v[56:59], v23 offset:32768
	v_mfma_f32_16x16x32_f16 v[158:161], v[144:147], v[162:165], v[158:161]
	s_waitcnt vmcnt(3)
	ds_write_b128 v16, v[124:127] offset:49152
	v_mfma_f32_16x16x32_f16 v[24:27], v[144:147], v[166:169], v[24:27]
	ds_read_b128 v[144:147], v23 offset:34816
	v_mfma_f32_16x16x32_f16 v[190:193], v[194:197], v[162:165], v[190:193]
	s_waitcnt vmcnt(2)
	ds_write_b128 v17, v[220:223] offset:49152
	v_mfma_f32_16x16x32_f16 v[40:43], v[194:197], v[166:169], v[40:43]
	ds_read_b128 v[194:197], v23 offset:36864
	v_mfma_f32_16x16x32_f16 v[120:123], v[198:201], v[162:165], v[120:123]
	ds_read_b128 v[162:165], v22
	v_mfma_f32_16x16x32_f16 v[52:55], v[198:201], v[166:169], v[52:55]
	ds_read_b128 v[166:169], v22 offset:2048
	s_waitcnt lgkmcnt(1)
	v_mfma_f32_16x16x32_f16 v[36:39], v[56:59], v[162:165], v[36:39]
	ds_read_b128 v[198:201], v23 offset:38912
	s_waitcnt lgkmcnt(1)
	v_mfma_f32_16x16x32_f16 v[116:119], v[56:59], v[166:169], v[116:119]
	s_waitcnt vmcnt(1)
	ds_write_b128 v18, v[224:227] offset:49152
	v_mfma_f32_16x16x32_f16 v[44:47], v[144:147], v[162:165], v[44:47]
	s_waitcnt vmcnt(0)
	ds_write_b128 v19, v[228:231] offset:49152
	v_mfma_f32_16x16x32_f16 v[128:131], v[144:147], v[166:169], v[128:131]
	v_mfma_f32_16x16x32_f16 v[132:135], v[194:197], v[162:165], v[132:135]
	v_mfma_f32_16x16x32_f16 v[136:139], v[194:197], v[166:169], v[136:139]
	s_waitcnt lgkmcnt(2)
	v_mfma_f32_16x16x32_f16 v[28:31], v[198:201], v[162:165], v[28:31]
	ds_read_b128 v[162:165], v22 offset:4096
	v_mfma_f32_16x16x32_f16 v[32:35], v[198:201], v[166:169], v[32:35]
	ds_read_b128 v[166:169], v22 offset:6144
	s_waitcnt lgkmcnt(1)
	v_mfma_f32_16x16x32_f16 v[154:157], v[56:59], v[162:165], v[154:157]
	s_waitcnt lgkmcnt(0)
	v_mfma_f32_16x16x32_f16 v[48:51], v[56:59], v[166:169], v[48:51]
	global_load_dwordx4 v[56:59], v[0:1], off offset:768
	v_mfma_f32_16x16x32_f16 v[158:161], v[144:147], v[162:165], v[158:161]
	v_mfma_f32_16x16x32_f16 v[24:27], v[144:147], v[166:169], v[24:27]
	v_mfma_f32_16x16x32_f16 v[190:193], v[194:197], v[162:165], v[190:193]
	v_mfma_f32_16x16x32_f16 v[40:43], v[194:197], v[166:169], v[40:43]
	v_mfma_f32_16x16x32_f16 v[120:123], v[198:201], v[162:165], v[120:123]
	global_load_dwordx4 v[162:165], v[2:3], off offset:768
	global_load_dwordx4 v[210:213], v[4:5], off offset:768
	global_load_dwordx4 v[232:235], v[6:7], off offset:768
	global_load_dwordx4 v[144:147], v[8:9], off offset:768
	global_load_dwordx4 v[236:239], v[10:11], off offset:768
	global_load_dwordx4 v[240:243], v[12:13], off offset:768
	global_load_dwordx4 v[244:247], v[14:15], off offset:768
	s_waitcnt lgkmcnt(0)
	s_barrier
; #define GL_LOAD(s_, kt_) if (VAR != 1) { a##s_##0 = GL_A(0, kt_); a##s_##1 = GL_A(1, kt_); a##s_##2 = GL_A(2, kt_); a##s_##3 = GL_A(3, kt_); b##s_##0 = GL_B(0, kt_); b##s_##1 = GL_B(1, kt_); b##s_##2 = GL_B(2, kt_); b##s_##3 = GL_B(3, kt_); }
; #define LDS_STORE(s_, buf_) if (VAR != 2) { LDS_ST1(sA, 0, buf_, a##s_##0) LDS_ST1(sA, 1, buf_, a##s_##1) LDS_ST1(sA, 2, buf_, a##s_##2) LDS_ST1(sA, 3, buf_, a##s_##3) LDS_ST1(sB, 0, buf_, b##s_##0) LDS_ST1(sB, 1, buf_, b##s_##1) LDS_ST1(sB, 2, buf_, b##s_##2) LDS_ST1(sB, 3, buf_, b##s_##3) }
;     ...
;   GL_LOAD(0, 0)
;   GL_LOAD(1, 1)
;   LDS_STORE(0, 0)
;   if (VAR != 4) __syncthreads();
; #pragma unroll
;   for (int kt = 0; kt < nk; kt += 2) {
;     if (kt + 2 < nk) { GL_LOAD(0, kt + 2) }
;     MMA_TILE(0)
;     LDS_STORE(1, 1)
;     if (VAR != 4) __syncthreads();
;     if (kt + 3 < nk) { GL_LOAD(1, kt + 3) }
;     MMA_TILE(1)
;     if (kt + 2 < nk) { LDS_STORE(0, 0) }
;     if (VAR != 4) __syncthreads();
	v_mfma_f32_16x16x32_f16 v[52:55], v[198:201], v[166:169], v[52:55]
	ds_read_b128 v[104:107], v20 offset:49152
	ds_read_b128 v[140:143], v21 offset:16384
	s_waitcnt lgkmcnt(0)
	v_mfma_f32_16x16x32_f16 v[36:39], v[104:107], v[140:143], v[36:39]
	ds_read_b128 v[124:127], v20 offset:51200
	ds_read_b128 v[166:169], v21 offset:18432
	s_waitcnt lgkmcnt(0)
	v_mfma_f32_16x16x32_f16 v[116:119], v[104:107], v[166:169], v[116:119]
	ds_read_b128 v[194:197], v20 offset:53248
	v_mfma_f32_16x16x32_f16 v[44:47], v[124:127], v[140:143], v[44:47]
	ds_read_b128 v[198:201], v20 offset:55296
	v_mfma_f32_16x16x32_f16 v[128:131], v[124:127], v[166:169], v[128:131]
	s_waitcnt vmcnt(7)
	ds_write_b128 v16, v[56:59]
	s_waitcnt lgkmcnt(2)
	v_mfma_f32_16x16x32_f16 v[132:135], v[194:197], v[140:143], v[132:135]
	s_waitcnt vmcnt(6)
	ds_write_b128 v17, v[162:165]
	v_mfma_f32_16x16x32_f16 v[136:139], v[194:197], v[166:169], v[136:139]
	s_waitcnt vmcnt(5)
	ds_write_b128 v18, v[210:213]
	s_waitcnt lgkmcnt(3)
	v_mfma_f32_16x16x32_f16 v[28:31], v[198:201], v[140:143], v[28:31]
	ds_read_b128 v[140:143], v21 offset:20480
	v_mfma_f32_16x16x32_f16 v[32:35], v[198:201], v[166:169], v[32:35]
	ds_read_b128 v[166:169], v21 offset:22528
	s_waitcnt lgkmcnt(1)
	v_mfma_f32_16x16x32_f16 v[154:157], v[104:107], v[140:143], v[154:157]
	s_waitcnt vmcnt(4)
	ds_write_b128 v19, v[232:235]
	s_waitcnt lgkmcnt(1)
	v_mfma_f32_16x16x32_f16 v[48:51], v[104:107], v[166:169], v[48:51]
	ds_read_b128 v[104:107], v23 offset:49152
	v_mfma_f32_16x16x32_f16 v[158:161], v[124:127], v[140:143], v[158:161]
	s_waitcnt vmcnt(3)
	ds_write_b128 v16, v[144:147] offset:32768
	v_mfma_f32_16x16x32_f16 v[24:27], v[124:127], v[166:169], v[24:27]
	ds_read_b128 v[124:127], v23 offset:51200
	v_mfma_f32_16x16x32_f16 v[190:193], v[194:197], v[140:143], v[190:193]
	s_waitcnt vmcnt(2)
	ds_write_b128 v17, v[236:239] offset:32768
	v_mfma_f32_16x16x32_f16 v[40:43], v[194:197], v[166:169], v[40:43]
	ds_read_b128 v[194:197], v23 offset:53248
	v_mfma_f32_16x16x32_f16 v[120:123], v[198:201], v[140:143], v[120:123]
	ds_read_b128 v[140:143], v22 offset:16384
	v_mfma_f32_16x16x32_f16 v[52:55], v[198:201], v[166:169], v[52:55]
	ds_read_b128 v[166:169], v22 offset:18432
	s_waitcnt lgkmcnt(1)
	v_mfma_f32_16x16x32_f16 v[36:39], v[104:107], v[140:143], v[36:39]
	ds_read_b128 v[198:201], v23 offset:55296
	s_waitcnt lgkmcnt(1)
	v_mfma_f32_16x16x32_f16 v[116:119], v[104:107], v[166:169], v[116:119]
	s_waitcnt vmcnt(1)
	ds_write_b128 v18, v[240:243] offset:32768
	v_mfma_f32_16x16x32_f16 v[44:47], v[124:127], v[140:143], v[44:47]
	s_waitcnt vmcnt(0)
	ds_write_b128 v19, v[244:247] offset:32768
	v_mfma_f32_16x16x32_f16 v[128:131], v[124:127], v[166:169], v[128:131]
	v_mfma_f32_16x16x32_f16 v[132:135], v[194:197], v[140:143], v[132:135]
	v_mfma_f32_16x16x32_f16 v[136:139], v[194:197], v[166:169], v[136:139]
	s_waitcnt lgkmcnt(2)
	v_mfma_f32_16x16x32_f16 v[28:31], v[198:201], v[140:143], v[28:31]
	ds_read_b128 v[140:143], v22 offset:20480
	v_mfma_f32_16x16x32_f16 v[32:35], v[198:201], v[166:169], v[32:35]
	ds_read_b128 v[166:169], v22 offset:22528
	s_waitcnt lgkmcnt(1)
	v_mfma_f32_16x16x32_f16 v[154:157], v[104:107], v[140:143], v[154:157]
	s_waitcnt lgkmcnt(0)
	v_mfma_f32_16x16x32_f16 v[48:51], v[104:107], v[166:169], v[48:51]
	global_load_dwordx4 v[104:107], v[0:1], off offset:896
	global_load_dwordx4 v[0:3], v[2:3], off offset:896
	v_mfma_f32_16x16x32_f16 v[158:161], v[124:127], v[140:143], v[158:161]
	v_mfma_f32_16x16x32_f16 v[24:27], v[124:127], v[166:169], v[24:27]
	v_mfma_f32_16x16x32_f16 v[190:193], v[194:197], v[140:143], v[190:193]
	v_mfma_f32_16x16x32_f16 v[40:43], v[194:197], v[166:169], v[40:43]
	v_mfma_f32_16x16x32_f16 v[120:123], v[198:201], v[140:143], v[120:123]
	global_load_dwordx4 v[140:143], v[4:5], off offset:896
	global_load_dwordx4 v[4:7], v[6:7], off offset:896
	global_load_dwordx4 v[124:127], v[8:9], off offset:896
	global_load_dwordx4 v[8:11], v[10:11], off offset:896
	global_load_dwordx4 v[202:205], v[12:13], off offset:896
	global_load_dwordx4 v[12:15], v[14:15], off offset:896
	s_waitcnt lgkmcnt(0)
	s_barrier
	ds_read_b128 v[56:59], v20 offset:32768
	v_mfma_f32_16x16x32_f16 v[52:55], v[198:201], v[166:169], v[52:55]
	ds_read_b128 v[144:147], v20 offset:34816
	ds_read_b128 v[162:165], v21
	ds_read_b128 v[166:169], v21 offset:2048
	ds_read_b128 v[194:197], v20 offset:36864
	ds_read_b128 v[198:201], v20 offset:38912
	s_waitcnt lgkmcnt(3)
	v_mfma_f32_16x16x32_f16 v[36:39], v[56:59], v[162:165], v[36:39]
	v_mfma_f32_16x16x32_f16 v[44:47], v[144:147], v[162:165], v[44:47]
	s_waitcnt lgkmcnt(1)
	v_mfma_f32_16x16x32_f16 v[132:135], v[194:197], v[162:165], v[132:135]
	s_waitcnt lgkmcnt(0)
	v_mfma_f32_16x16x32_f16 v[28:31], v[198:201], v[162:165], v[28:31]
	v_mfma_f32_16x16x32_f16 v[116:119], v[56:59], v[166:169], v[116:119]
	v_mfma_f32_16x16x32_f16 v[128:131], v[144:147], v[166:169], v[128:131]
	v_mfma_f32_16x16x32_f16 v[136:139], v[194:197], v[166:169], v[136:139]
	v_mfma_f32_16x16x32_f16 v[32:35], v[198:201], v[166:169], v[32:35]
	ds_read_b128 v[162:165], v21 offset:4096
	ds_read_b128 v[166:169], v21 offset:6144
	s_waitcnt lgkmcnt(1)
	v_mfma_f32_16x16x32_f16 v[154:157], v[56:59], v[162:165], v[154:157]
	v_mfma_f32_16x16x32_f16 v[158:161], v[144:147], v[162:165], v[158:161]
	v_mfma_f32_16x16x32_f16 v[190:193], v[194:197], v[162:165], v[190:193]
	v_mfma_f32_16x16x32_f16 v[120:123], v[198:201], v[162:165], v[120:123]
	s_waitcnt lgkmcnt(0)
; DI unsigned pack2(float lo, float hi) { f2_t v = {lo, hi}; h2_t b = __builtin_convertvector(v, h2_t); return __builtin_bit_cast(unsigned, b); }
; DI float lo_f(unsigned u) { return (float)(__builtin_bit_cast(h2_t, u)[0]); }
; DI float hi_f(unsigned u) { return (float)(__builtin_bit_cast(h2_t, u)[1]); }
; #define GL_LOAD(s_, kt_) if (VAR != 1) { a##s_##0 = GL_A(0, kt_); a##s_##1 = GL_A(1, kt_); a##s_##2 = GL_A(2, kt_); a##s_##3 = GL_A(3, kt_); b##s_##0 = GL_B(0, kt_); b##s_##1 = GL_B(1, kt_); b##s_##2 = GL_B(2, kt_); b##s_##3 = GL_B(3, kt_); }
; #define LDS_STORE(s_, buf_) if (VAR != 2) { LDS_ST1(sA, 0, buf_, a##s_##0) LDS_ST1(sA, 1, buf_, a##s_##1) LDS_ST1(sA, 2, buf_, a##s_##2) LDS_ST1(sA, 3, buf_, a##s_##3) LDS_ST1(sB, 0, buf_, b##s_##0) LDS_ST1(sB, 1, buf_, b##s_##1) LDS_ST1(sB, 2, buf_, b##s_##2) LDS_ST1(sB, 3, buf_, b##s_##3) }
;     ...
;   GL_LOAD(0, 0)
;   GL_LOAD(1, 1)
;   LDS_STORE(0, 0)
;   if (VAR != 4) __syncthreads();
; #pragma unroll
;   for (int kt = 0; kt < nk; kt += 2) {
;     if (kt + 2 < nk) { GL_LOAD(0, kt + 2) }
;     MMA_TILE(0)
;     LDS_STORE(1, 1)
;     if (VAR != 4) __syncthreads();
;     if (kt + 3 < nk) { GL_LOAD(1, kt + 3) }
;     MMA_TILE(1)
;     if (kt + 2 < nk) { LDS_STORE(0, 0) }
;     if (VAR != 4) __syncthreads();
; DI void phase_merge(const Params& P, int l, char* smem) {
;     ...
;       gemm_kloop<false, true, 8>(acc, Pb + (size_t)m0 * PW + ycol, PW, Wb + (size_t)n0 * 512, 512, smem);
; #pragma unroll
;       for (int mt = 0; mt < 4; ++mt) {
;         const int row = row0 + mt * 16 + lr;
; #pragma unroll
;         for (int nt = 0; nt < 4; ++nt) {
;           const uint2 gu = *(const uint2*)(Pb + (size_t)row * PW + C_GL + br * 1024 + col0 + nt * 16 + 4 * g);
;           float t0 = lo_f(gu.x) * acc[mt][nt][0], t1 = hi_f(gu.x) * acc[mt][nt][1], t2 = lo_f(gu.y) * acc[mt][nt][2], t3 = hi_f(gu.y) * acc[mt][nt][3];
;           if (br > 0) { t0 += lo_f(tot[mt][nt][0]); t1 += hi_f(tot[mt][nt][0]); t2 += lo_f(tot[mt][nt][1]); t3 += hi_f(tot[mt][nt][1]); }
;           tot[mt][nt][0] = pack2(t0, t1); tot[mt][nt][1] = pack2(t2, t3);
;         }
	v_mfma_f32_16x16x32_f16 v[48:51], v[56:59], v[166:169], v[48:51]
	ds_read_b128 v[56:59], v23 offset:32768
	v_mfma_f32_16x16x32_f16 v[24:27], v[144:147], v[166:169], v[24:27]
	v_mfma_f32_16x16x32_f16 v[40:43], v[194:197], v[166:169], v[40:43]
	v_mfma_f32_16x16x32_f16 v[52:55], v[198:201], v[166:169], v[52:55]
	ds_read_b128 v[144:147], v23 offset:34816
	ds_read_b128 v[162:165], v22
	ds_read_b128 v[166:169], v22 offset:2048
	ds_read_b128 v[194:197], v23 offset:36864
	ds_read_b128 v[198:201], v23 offset:38912
	s_waitcnt lgkmcnt(3)
	v_mfma_f32_16x16x32_f16 v[36:39], v[56:59], v[162:165], v[36:39]
	v_mfma_f32_16x16x32_f16 v[44:47], v[144:147], v[162:165], v[44:47]
	s_waitcnt lgkmcnt(1)
	v_mfma_f32_16x16x32_f16 v[132:135], v[194:197], v[162:165], v[132:135]
	s_waitcnt lgkmcnt(0)
	v_mfma_f32_16x16x32_f16 v[28:31], v[198:201], v[162:165], v[28:31]
	v_mfma_f32_16x16x32_f16 v[116:119], v[56:59], v[166:169], v[116:119]
	v_mfma_f32_16x16x32_f16 v[128:131], v[144:147], v[166:169], v[128:131]
	v_mfma_f32_16x16x32_f16 v[136:139], v[194:197], v[166:169], v[136:139]
	v_mfma_f32_16x16x32_f16 v[32:35], v[198:201], v[166:169], v[32:35]
	ds_read_b128 v[162:165], v22 offset:4096
	ds_read_b128 v[166:169], v22 offset:6144
	s_waitcnt vmcnt(7)
	ds_write_b128 v16, v[104:107] offset:16384
	s_waitcnt vmcnt(6)
	ds_write_b128 v17, v[0:3] offset:16384
	s_waitcnt vmcnt(5)
	ds_write_b128 v18, v[140:143] offset:16384
	s_waitcnt vmcnt(4)
	ds_write_b128 v19, v[4:7] offset:16384
	s_waitcnt vmcnt(3)
	ds_write_b128 v16, v[124:127] offset:49152
	s_waitcnt vmcnt(2)
	ds_write_b128 v17, v[8:11] offset:49152
	s_waitcnt vmcnt(1)
	ds_write_b128 v18, v[202:205] offset:49152
	s_waitcnt vmcnt(0)
	ds_write_b128 v19, v[12:15] offset:49152
	s_waitcnt lgkmcnt(0)
	v_mfma_f32_16x16x32_f16 v[154:157], v[56:59], v[162:165], v[154:157]
	s_barrier
	ds_read_b128 v[0:3], v20 offset:49152
	v_mfma_f32_16x16x32_f16 v[48:51], v[56:59], v[166:169], v[48:51]
	ds_read_b128 v[8:11], v20 offset:51200
	ds_read_b128 v[12:15], v21 offset:16384
	ds_read_b128 v[16:19], v21 offset:18432
	ds_read_b128 v[56:59], v20 offset:55296
	v_mfma_f32_16x16x32_f16 v[4:7], v[198:201], v[166:169], v[52:55]
	s_nop 2
	ds_read_b128 v[52:55], v20 offset:53248
	s_waitcnt lgkmcnt(3)
	v_mfma_f32_16x16x32_f16 v[36:39], v[0:3], v[12:15], v[36:39]
	v_mfma_f32_16x16x32_f16 v[44:47], v[8:11], v[12:15], v[44:47]
	s_waitcnt lgkmcnt(0)
	v_mfma_f32_16x16x32_f16 v[104:107], v[52:55], v[12:15], v[132:135]
	v_mfma_f32_16x16x32_f16 v[12:15], v[56:59], v[12:15], v[28:31]
	v_mfma_f32_16x16x32_f16 v[28:31], v[0:3], v[16:19], v[116:119]
	v_mfma_f32_16x16x32_f16 v[116:119], v[8:11], v[16:19], v[128:131]
	v_mfma_f32_16x16x32_f16 v[124:127], v[52:55], v[16:19], v[136:139]
	v_mfma_f32_16x16x32_f16 v[16:19], v[56:59], v[16:19], v[32:35]
	s_nop 2
	ds_read_b128 v[32:35], v21 offset:20480
	ds_read_b128 v[128:131], v21 offset:22528
	v_mfma_f32_16x16x32_f16 v[158:161], v[144:147], v[162:165], v[158:161]
	v_mfma_f32_16x16x32_f16 v[190:193], v[194:197], v[162:165], v[190:193]
	v_mfma_f32_16x16x32_f16 v[120:123], v[198:201], v[162:165], v[120:123]
	v_mfma_f32_16x16x32_f16 v[24:27], v[144:147], v[166:169], v[24:27]
	v_mfma_f32_16x16x32_f16 v[40:43], v[194:197], v[166:169], v[40:43]
	s_waitcnt lgkmcnt(1)
	v_mfma_f32_16x16x32_f16 v[132:135], v[0:3], v[32:35], v[154:157]
	v_mfma_f32_16x16x32_f16 v[136:139], v[8:11], v[32:35], v[158:161]
	s_nop 1
	ds_read_b128 v[154:157], v23 offset:49152
	v_mfma_f32_16x16x32_f16 v[140:143], v[52:55], v[32:35], v[190:193]
	v_mfma_f32_16x16x32_f16 v[120:123], v[56:59], v[32:35], v[120:123]
	s_waitcnt lgkmcnt(1)
	v_mfma_f32_16x16x32_f16 v[0:3], v[0:3], v[128:131], v[48:51]
	v_mfma_f32_16x16x32_f16 v[8:11], v[8:11], v[128:131], v[24:27]
	v_mfma_f32_16x16x32_f16 v[144:147], v[52:55], v[128:131], v[40:43]
	v_mfma_f32_16x16x32_f16 v[128:131], v[56:59], v[128:131], v[4:7]
	s_nop 2
	ds_read_b128 v[4:7], v23 offset:51200
	ds_read_b128 v[24:27], v22 offset:16384
	ds_read_b128 v[32:35], v22 offset:18432
	ds_read_b128 v[162:165], v23 offset:53248
	ds_read_b128 v[166:169], v23 offset:55296
	s_waitcnt lgkmcnt(0)
	v_mfma_f32_16x16x32_f16 v[48:51], v[166:169], v[24:27], v[12:15]
	v_mfma_f32_16x16x32_f16 v[40:43], v[4:7], v[32:35], v[116:119]
	s_nop 1
	ds_read_b128 v[12:15], v22 offset:20480
	ds_read_b128 v[116:119], v22 offset:22528
	s_waitcnt lgkmcnt(0)
	s_barrier
	s_setprio 0
	v_mfma_f32_16x16x32_f16 v[158:161], v[154:157], v[24:27], v[36:39]
	v_mfma_f32_16x16x32_f16 v[56:59], v[4:7], v[24:27], v[44:47]
	v_mfma_f32_16x16x32_f16 v[52:55], v[162:165], v[24:27], v[104:107]
	v_mfma_f32_16x16x32_f16 v[44:47], v[154:157], v[32:35], v[28:31]
	v_mfma_f32_16x16x32_f16 v[36:39], v[162:165], v[32:35], v[124:127]
	v_mfma_f32_16x16x32_f16 v[32:35], v[166:169], v[32:35], v[16:19]
	v_mfma_f32_16x16x32_f16 v[28:31], v[154:157], v[12:15], v[132:135]
	v_mfma_f32_16x16x32_f16 v[24:27], v[4:7], v[12:15], v[136:139]
	v_mfma_f32_16x16x32_f16 v[20:23], v[162:165], v[12:15], v[140:143]
	v_mfma_f32_16x16x32_f16 v[16:19], v[166:169], v[12:15], v[120:123]
	v_mfma_f32_16x16x32_f16 v[12:15], v[154:157], v[116:119], v[0:3]
	s_nop 2
	global_load_dwordx2 v[0:1], v[108:109], off offset:-64
	v_mfma_f32_16x16x32_f16 v[8:11], v[4:7], v[116:119], v[8:11]
	s_waitcnt vmcnt(0)
	v_cvt_f32_f16_e32 v2, v0
	v_cvt_f32_f16_sdwa v3, v0 dst_sel:DWORD dst_unused:UNUSED_PAD src0_sel:WORD_1
	v_cvt_f32_f16_e32 v0, v1
	v_cvt_f32_f16_sdwa v1, v1 dst_sel:DWORD dst_unused:UNUSED_PAD src0_sel:WORD_1
	v_mfma_f32_16x16x32_f16 v[4:7], v[162:165], v[116:119], v[144:147]
	v_mul_f32_e64 v104, v158, v2
	v_mul_f32_e64 v105, v159, v3
	v_pk_mul_f32 v[106:107], v[160:161], v[0:1]
	v_mfma_f32_16x16x32_f16 v[0:3], v[166:169], v[116:119], v[128:131]
	s_cbranch_vccnz .LBB0_1163
	v_cvt_f32_f16_sdwa v117, v102 dst_sel:DWORD dst_unused:UNUSED_PAD src0_sel:WORD_1
	v_cvt_f32_f16_e32 v116, v102
	v_pk_add_f32 v[104:105], v[104:105], v[116:117]
	v_cvt_f32_f16_sdwa v117, v103 dst_sel:DWORD dst_unused:UNUSED_PAD src0_sel:WORD_1
	v_cvt_f32_f16_e32 v116, v103
	v_pk_add_f32 v[106:107], v[106:107], v[116:117]

; DI int TIDX() { int t = threadIdx.x; asm volatile("" : "+v"(t)); return t; }
; DI int BIDX() { int b = blockIdx.x; asm volatile("" : "+s"(b)); return b; }
; #define GL_LOAD(s_, kt_) if (VAR != 1) { a##s_##0 = GL_A(0, kt_); a##s_##1 = GL_A(1, kt_); a##s_##2 = GL_A(2, kt_); a##s_##3 = GL_A(3, kt_); b##s_##0 = GL_B(0, kt_); b##s_##1 = GL_B(1, kt_); b##s_##2 = GL_B(2, kt_); b##s_##3 = GL_B(3, kt_); }
; #define LDS_STORE(s_, buf_) if (VAR != 2) { LDS_ST1(sA, 0, buf_, a##s_##0) LDS_ST1(sA, 1, buf_, a##s_##1) LDS_ST1(sA, 2, buf_, a##s_##2) LDS_ST1(sA, 3, buf_, a##s_##3) LDS_ST1(sB, 0, buf_, b##s_##0) LDS_ST1(sB, 1, buf_, b##s_##1) LDS_ST1(sB, 2, buf_, b##s_##2) LDS_ST1(sB, 3, buf_, b##s_##3) }
; DI int tile_groups(int MT, int NT) { return (MT >> 6) * ((NT + 7) >> 3) * 512; }
;   const int tid = TIDX(), lane = tid & 63, wid = tid >> 6, wm = wid >> 1, wn = wid & 1, lr = lane & 15, g = lane >> 4;
;   char* sA = smem; char* sB = smem + 2 * LTILE;
;   uint4 a00 = {}, a01 = {}, a02 = {}, a03 = {}, b00 = {}, b01 = {}, b02 = {}, b03 = {}, a10 = {}, a11 = {}, a12 = {}, a13 = {}, b10 = {}, b11 = {}, b12 = {}, b13 = {};
;   constexpr int nk = NK;
;   const int sw0 = (g ^ ((lr >> 1) & 7)) << 4, sw1 = sw0 ^ 64;
;   const int r0 = tid >> 3, kc = tid & 7, kcs = kc ^ ((r0 >> 1) & 7);
;     ...
;   GL_LOAD(0, 0)
;   GL_LOAD(1, 1)
;   LDS_STORE(0, 0)
;   if (VAR != 4) __syncthreads();
; #pragma unroll
;   for (int kt = 0; kt < nk; kt += 2) {
;     if (kt + 2 < nk) { GL_LOAD(0, kt + 2) }
;     MMA_TILE(0)
;     LDS_STORE(1, 1)
;     if (VAR != 4) __syncthreads();
;     if (kt + 3 < nk) { GL_LOAD(1, kt + 3) }
;     MMA_TILE(1)
;     if (kt + 2 < nk) { LDS_STORE(0, 0) }
;     if (VAR != 4) __syncthreads();
; DI void phase_resgemm(const Params& P, const bf16_t* A, int K, const bf16_t* Wt, float* ssq_out, const float* xsrc, char* smem) {
;     ...
;   for (int vb = BIDX(); vb < tile_groups(128, 8); vb += gridDim.x) {
;     int tm, tn; if (!tile_of(vb, 128, 8, tm, tn)) continue;
;     const int m0 = tm * 128, n0 = tn * 128;
;     f32x4 acc[4][4]; zero_acc(acc);
;     if (K == 1024) gemm_kloop<false, true, 16>(acc, A + (size_t)m0 * K, K, Wt + (size_t)n0 * K, K, smem);
.LBB0_1249:
	s_ashr_i32 s6, s1, 3
	s_andn2_b32 s6, s6, 63
	s_and_b32 s7, s10, 56
	s_or_b32 s6, s6, s7
	s_bfe_u32 s7, s1, 0x30003
	s_or_b32 s6, s6, s7
	s_cmpk_gt_i32 s6, 0x7f
	s_cbranch_scc1 .LBB0_1248
	s_lshl_b32 s6, s6, 7
	s_ashr_i32 s7, s6, 31
	v_mov_b32_e32 v20, v148
	s_and_b32 s11, s9, 0x380
	s_lshl_b64 s[12:13], s[6:7], 11
	v_readlane_b32 s14, v253, 19
	v_readlane_b32 s15, v253, 20
	v_ashrrev_i32_e32 v16, 3, v20
	s_add_u32 s12, s14, s12
	v_ashrrev_i32_e32 v17, 31, v16
	v_add_u32_e32 v18, 32, v16
	s_addc_u32 s13, s15, s13
	v_lshlrev_b64 v[8:9], 11, v[16:17]
	v_lshlrev_b32_e32 v17, 4, v20
	v_ashrrev_i32_e32 v19, 31, v18
	v_add_u32_e32 v54, 64, v16
	s_waitcnt lgkmcnt(0)
	v_lshl_add_u64 v[0:1], s[12:13], 0, v[8:9]
	v_and_b32_e32 v150, 0x70, v17
	v_lshlrev_b64 v[10:11], 11, v[18:19]
	v_ashrrev_i32_e32 v55, 31, v54
	v_add_u32_e32 v58, 0x60, v16
	s_lshl_b32 s7, s11, 11
	v_lshl_add_u64 v[0:1], v[0:1], 0, v[150:151]
	v_lshl_add_u64 v[2:3], s[12:13], 0, v[10:11]
	v_lshlrev_b64 v[12:13], 11, v[54:55]
	v_ashrrev_i32_e32 v59, 31, v58
	s_add_u32 s14, s2, s7
	global_load_dwordx4 v[22:25], v[0:1], off
	v_lshl_add_u64 v[2:3], v[2:3], 0, v[150:151]
	v_lshl_add_u64 v[4:5], s[12:13], 0, v[12:13]
	v_lshlrev_b64 v[14:15], 11, v[58:59]
	s_addc_u32 s15, s8, 0
	global_load_dwordx4 v[26:29], v[2:3], off
	v_lshl_add_u64 v[4:5], v[4:5], 0, v[150:151]
	v_lshl_add_u64 v[6:7], s[12:13], 0, v[14:15]
	global_load_dwordx4 v[30:33], v[4:5], off
	v_lshl_add_u64 v[6:7], v[6:7], 0, v[150:151]
	v_lshl_add_u64 v[8:9], s[14:15], 0, v[8:9]
	global_load_dwordx4 v[34:37], v[6:7], off
	v_lshl_add_u64 v[8:9], v[8:9], 0, v[150:151]
	v_lshl_add_u64 v[10:11], s[14:15], 0, v[10:11]
	global_load_dwordx4 v[38:41], v[8:9], off
	v_lshl_add_u64 v[10:11], v[10:11], 0, v[150:151]
	v_lshl_add_u64 v[12:13], s[14:15], 0, v[12:13]
	global_load_dwordx4 v[42:45], v[10:11], off
	v_lshl_add_u64 v[12:13], v[12:13], 0, v[150:151]
	v_lshl_add_u64 v[14:15], s[14:15], 0, v[14:15]
	global_load_dwordx4 v[46:49], v[12:13], off
	v_lshl_add_u64 v[14:15], v[14:15], 0, v[150:151]
	global_load_dwordx4 v[50:53], v[14:15], off
	v_lshlrev_b32_e32 v21, 3, v20
	v_and_b32_e32 v55, 48, v20
	v_and_b32_e32 v19, 15, v20
	v_lshrrev_b32_e32 v59, 1, v20
	s_waitcnt vmcnt(10)
	v_lshlrev_b32_e32 v60, 7, v20
	v_and_b32_e32 v90, 0x70, v21
	v_bitop3_b32 v134, v21, v55, s23 bitop3:0x6c
	v_bitop3_b32 v21, v17, s23, v20 bitop3:0x48
	v_and_or_b32 v91, v59, s24, v19
	v_and_b32_e32 v130, 0x2780, v60
	v_lshl_or_b32 v20, v18, 7, v21
	v_lshl_or_b32 v18, v58, 7, v21
	global_load_dwordx4 v[58:61], v[0:1], off offset:128
	global_load_dwordx4 v[62:65], v[2:3], off offset:128
	global_load_dwordx4 v[66:69], v[4:5], off offset:128
	global_load_dwordx4 v[70:73], v[6:7], off offset:128
	global_load_dwordx4 v[74:77], v[8:9], off offset:128
	global_load_dwordx4 v[78:81], v[10:11], off offset:128
	global_load_dwordx4 v[82:85], v[12:13], off offset:128
	global_load_dwordx4 v[86:89], v[14:15], off offset:128
	v_lshl_or_b32 v19, v16, 7, v21
	v_or_b32_e32 v16, v130, v134
	v_lshl_or_b32 v17, v54, 7, v21
	v_lshlrev_b32_e32 v54, 7, v91
	v_bitop3_b32 v21, v54, v90, v55 bitop3:0xf6
	v_readlane_b32 s12, v254, 55
	v_readlane_b32 s13, v254, 56
	v_readlane_b32 s14, v254, 57
	v_readlane_b32 s15, v254, 58
	s_waitcnt vmcnt(15)
	ds_write_b128 v19, v[22:25]
	s_waitcnt vmcnt(14)
	ds_write_b128 v20, v[26:29]
	s_waitcnt vmcnt(13)
	ds_write_b128 v17, v[30:33]
	s_waitcnt vmcnt(12)
	ds_write_b128 v18, v[34:37]
	s_waitcnt vmcnt(11)
	ds_write_b128 v19, v[38:41] offset:32768
	s_waitcnt vmcnt(10)
	ds_write_b128 v20, v[42:45] offset:32768
	s_waitcnt vmcnt(9)
	ds_write_b128 v17, v[46:49] offset:32768
	s_waitcnt vmcnt(8)
	ds_write_b128 v18, v[50:53] offset:32768
	s_waitcnt lgkmcnt(0)
	s_barrier
	s_setprio 1
	ds_read_b128 v[22:25], v16 offset:32768
	ds_read_b128 v[30:33], v21
	s_waitcnt lgkmcnt(0)
	v_mfma_f32_16x16x32_f16 v[38:41], v[22:25], v[30:33], 0
	ds_read_b128 v[26:29], v16 offset:34816
	ds_read_b128 v[34:37], v21 offset:2048
	s_waitcnt lgkmcnt(0)
	v_mfma_f32_16x16x32_f16 v[94:97], v[22:25], v[34:37], 0
	ds_read_b128 v[42:45], v16 offset:36864
	ds_read_b128 v[106:109], v21 offset:4096
	s_waitcnt lgkmcnt(0)
	v_mfma_f32_16x16x32_f16 v[114:117], v[22:25], v[106:109], 0
	ds_read_b128 v[50:53], v16 offset:38912
	ds_read_b128 v[110:113], v21 offset:6144
	s_waitcnt lgkmcnt(0)
	v_mfma_f32_16x16x32_f16 v[126:129], v[22:25], v[110:113], 0
	v_xor_b32_e32 v22, 64, v134
	v_mfma_f32_16x16x32_f16 v[46:49], v[26:29], v[30:33], 0
	v_or_b32_e32 v22, v130, v22
	v_mfma_f32_16x16x32_f16 v[90:93], v[42:45], v[30:33], 0
	ds_read_b128 v[130:133], v22 offset:32768
	v_mfma_f32_16x16x32_f16 v[30:33], v[50:53], v[30:33], 0
	ds_read_b128 v[142:145], v22 offset:36864
	v_mfma_f32_16x16x32_f16 v[98:101], v[26:29], v[34:37], 0
	ds_read_b128 v[154:157], v22 offset:38912
	v_mfma_f32_16x16x32_f16 v[102:105], v[42:45], v[34:37], 0
	v_bitop3_b32 v23, v54, v134, 64 bitop3:0xf6
	v_mfma_f32_16x16x32_f16 v[34:37], v[50:53], v[34:37], 0
	ds_read_b128 v[134:137], v23
	v_mfma_f32_16x16x32_f16 v[118:121], v[26:29], v[106:109], 0
	ds_read_b128 v[138:141], v23 offset:2048
	v_mfma_f32_16x16x32_f16 v[122:125], v[42:45], v[106:109], 0
	s_waitcnt vmcnt(7)
	ds_write_b128 v19, v[58:61] offset:16384
	v_mfma_f32_16x16x32_f16 v[106:109], v[50:53], v[106:109], 0
	s_waitcnt vmcnt(6)
	ds_write_b128 v20, v[62:65] offset:16384
	v_mfma_f32_16x16x32_f16 v[24:27], v[26:29], v[110:113], 0
	s_waitcnt vmcnt(5)
	ds_write_b128 v17, v[66:69] offset:16384
	v_mfma_f32_16x16x32_f16 v[42:45], v[42:45], v[110:113], 0
	s_waitcnt vmcnt(4)
	ds_write_b128 v18, v[70:73] offset:16384
	v_mfma_f32_16x16x32_f16 v[50:53], v[50:53], v[110:113], 0
	ds_read_b128 v[110:113], v22 offset:34816
	s_waitcnt lgkmcnt(6)
; #define GL_LOAD(s_, kt_) if (VAR != 1) { a##s_##0 = GL_A(0, kt_); a##s_##1 = GL_A(1, kt_); a##s_##2 = GL_A(2, kt_); a##s_##3 = GL_A(3, kt_); b##s_##0 = GL_B(0, kt_); b##s_##1 = GL_B(1, kt_); b##s_##2 = GL_B(2, kt_); b##s_##3 = GL_B(3, kt_); }
; #define LDS_STORE(s_, buf_) if (VAR != 2) { LDS_ST1(sA, 0, buf_, a##s_##0) LDS_ST1(sA, 1, buf_, a##s_##1) LDS_ST1(sA, 2, buf_, a##s_##2) LDS_ST1(sA, 3, buf_, a##s_##3) LDS_ST1(sB, 0, buf_, b##s_##0) LDS_ST1(sB, 1, buf_, b##s_##1) LDS_ST1(sB, 2, buf_, b##s_##2) LDS_ST1(sB, 3, buf_, b##s_##3) }
;     ...
;   GL_LOAD(0, 0)
;   GL_LOAD(1, 1)
;   LDS_STORE(0, 0)
;   if (VAR != 4) __syncthreads();
; #pragma unroll
;   for (int kt = 0; kt < nk; kt += 2) {
;     if (kt + 2 < nk) { GL_LOAD(0, kt + 2) }
;     MMA_TILE(0)
;     LDS_STORE(1, 1)
;     if (VAR != 4) __syncthreads();
;     if (kt + 3 < nk) { GL_LOAD(1, kt + 3) }
;     MMA_TILE(1)
;     if (kt + 2 < nk) { LDS_STORE(0, 0) }
;     if (VAR != 4) __syncthreads();
	v_mfma_f32_16x16x32_f16 v[38:41], v[130:133], v[134:137], v[38:41]
	s_waitcnt vmcnt(3)
	ds_write_b128 v19, v[74:77] offset:49152
	v_mfma_f32_16x16x32_f16 v[90:93], v[142:145], v[134:137], v[90:93]
	s_waitcnt vmcnt(2)
	ds_write_b128 v20, v[78:81] offset:49152
	v_mfma_f32_16x16x32_f16 v[28:31], v[154:157], v[134:137], v[30:33]
	s_waitcnt vmcnt(1)
	ds_write_b128 v17, v[82:85] offset:49152
	s_waitcnt lgkmcnt(8)
	v_mfma_f32_16x16x32_f16 v[94:97], v[130:133], v[138:141], v[94:97]
	s_waitcnt vmcnt(0)
	ds_write_b128 v18, v[86:89] offset:49152
	v_mfma_f32_16x16x32_f16 v[102:105], v[142:145], v[138:141], v[102:105]
	v_mfma_f32_16x16x32_f16 v[32:35], v[154:157], v[138:141], v[34:37]
	s_waitcnt lgkmcnt(4)
	v_mfma_f32_16x16x32_f16 v[46:49], v[110:113], v[134:137], v[46:49]
	ds_read_b128 v[134:137], v23 offset:4096
	v_mfma_f32_16x16x32_f16 v[98:101], v[110:113], v[138:141], v[98:101]
	ds_read_b128 v[138:141], v23 offset:6144
	s_waitcnt lgkmcnt(1)
	v_mfma_f32_16x16x32_f16 v[114:117], v[130:133], v[134:137], v[114:117]
	s_waitcnt lgkmcnt(0)
	v_mfma_f32_16x16x32_f16 v[126:129], v[130:133], v[138:141], v[126:129]
	global_load_dwordx4 v[130:133], v[0:1], off offset:256
	v_mfma_f32_16x16x32_f16 v[118:121], v[110:113], v[134:137], v[118:121]
	v_mfma_f32_16x16x32_f16 v[24:27], v[110:113], v[138:141], v[24:27]
	v_mfma_f32_16x16x32_f16 v[122:125], v[142:145], v[134:137], v[122:125]
	v_mfma_f32_16x16x32_f16 v[106:109], v[154:157], v[134:137], v[106:109]
	global_load_dwordx4 v[134:137], v[2:3], off offset:256
	global_load_dwordx4 v[158:161], v[4:5], off offset:256
	global_load_dwordx4 v[162:165], v[6:7], off offset:256
	global_load_dwordx4 v[110:113], v[8:9], off offset:256
	global_load_dwordx4 v[166:169], v[10:11], off offset:256
	global_load_dwordx4 v[190:193], v[12:13], off offset:256
	global_load_dwordx4 v[194:197], v[14:15], off offset:256
	s_waitcnt lgkmcnt(0)
	s_barrier
	v_mfma_f32_16x16x32_f16 v[42:45], v[142:145], v[138:141], v[42:45]
	ds_read_b128 v[58:61], v16 offset:49152
	v_mfma_f32_16x16x32_f16 v[50:53], v[154:157], v[138:141], v[50:53]
	ds_read_b128 v[62:65], v16 offset:51200
	ds_read_b128 v[66:69], v21 offset:16384
	s_waitcnt lgkmcnt(0)
	v_mfma_f32_16x16x32_f16 v[36:39], v[58:61], v[66:69], v[38:41]
	ds_read_b128 v[70:73], v21 offset:18432
	v_mfma_f32_16x16x32_f16 v[46:49], v[62:65], v[66:69], v[46:49]
	ds_read_b128 v[74:77], v16 offset:53248
	s_waitcnt lgkmcnt(0)
	v_mfma_f32_16x16x32_f16 v[82:85], v[74:77], v[66:69], v[90:93]
	ds_read_b128 v[78:81], v16 offset:55296
	s_waitcnt lgkmcnt(0)
	v_mfma_f32_16x16x32_f16 v[28:31], v[78:81], v[66:69], v[28:31]
	v_mfma_f32_16x16x32_f16 v[66:69], v[58:61], v[70:73], v[94:97]
	s_nop 2
	ds_read_b128 v[94:97], v21 offset:22528
	s_waitcnt vmcnt(7)
	ds_write_b128 v19, v[130:133]
	v_mfma_f32_16x16x32_f16 v[86:89], v[62:65], v[70:73], v[98:101]
	s_waitcnt vmcnt(6)
	ds_write_b128 v20, v[134:137]
	s_waitcnt vmcnt(5)
	ds_write_b128 v17, v[158:161]
	v_mfma_f32_16x16x32_f16 v[90:93], v[74:77], v[70:73], v[102:105]
	s_waitcnt vmcnt(4)
	ds_write_b128 v18, v[162:165]
	s_waitcnt vmcnt(3)
	ds_write_b128 v19, v[110:113] offset:32768
	v_mfma_f32_16x16x32_f16 v[32:35], v[78:81], v[70:73], v[32:35]
	ds_read_b128 v[70:73], v21 offset:20480
	s_waitcnt lgkmcnt(0)
	v_mfma_f32_16x16x32_f16 v[98:101], v[58:61], v[70:73], v[114:117]
	s_waitcnt vmcnt(2)
	ds_write_b128 v20, v[166:169] offset:32768
	v_mfma_f32_16x16x32_f16 v[58:61], v[58:61], v[94:97], v[126:129]
	s_waitcnt vmcnt(1)
	ds_write_b128 v17, v[190:193] offset:32768
	v_mfma_f32_16x16x32_f16 v[102:105], v[62:65], v[70:73], v[118:121]
	s_nop 2
	ds_read_b128 v[118:121], v22 offset:55296
	v_mfma_f32_16x16x32_f16 v[24:27], v[62:65], v[94:97], v[24:27]
	ds_read_b128 v[62:65], v22 offset:49152
	v_mfma_f32_16x16x32_f16 v[114:117], v[74:77], v[70:73], v[122:125]
	s_waitcnt vmcnt(0)
	ds_write_b128 v18, v[194:197] offset:32768
	v_mfma_f32_16x16x32_f16 v[40:43], v[74:77], v[94:97], v[42:45]
	ds_read_b128 v[74:77], v22 offset:51200
	v_mfma_f32_16x16x32_f16 v[70:73], v[78:81], v[70:73], v[106:109]
	s_nop 2
	ds_read_b128 v[106:109], v22 offset:53248
	v_mfma_f32_16x16x32_f16 v[50:53], v[78:81], v[94:97], v[50:53]
	ds_read_b128 v[78:81], v23 offset:16384
	s_waitcnt lgkmcnt(0)
	v_mfma_f32_16x16x32_f16 v[36:39], v[62:65], v[78:81], v[36:39]
	ds_read_b128 v[94:97], v23 offset:18432
	s_waitcnt lgkmcnt(0)
	v_mfma_f32_16x16x32_f16 v[66:69], v[62:65], v[94:97], v[66:69]
	v_mfma_f32_16x16x32_f16 v[44:47], v[74:77], v[78:81], v[46:49]
	v_mfma_f32_16x16x32_f16 v[82:85], v[106:109], v[78:81], v[82:85]
	v_mfma_f32_16x16x32_f16 v[28:31], v[118:121], v[78:81], v[28:31]
	v_mfma_f32_16x16x32_f16 v[78:81], v[74:77], v[94:97], v[86:89]
	v_mfma_f32_16x16x32_f16 v[86:89], v[106:109], v[94:97], v[90:93]
	s_nop 2
	ds_read_b128 v[90:93], v23 offset:20480
	v_mfma_f32_16x16x32_f16 v[32:35], v[118:121], v[94:97], v[32:35]
	ds_read_b128 v[94:97], v23 offset:22528
	s_waitcnt lgkmcnt(1)
	v_mfma_f32_16x16x32_f16 v[98:101], v[62:65], v[90:93], v[98:101]
	s_waitcnt lgkmcnt(0)
	v_mfma_f32_16x16x32_f16 v[58:61], v[62:65], v[94:97], v[58:61]
	global_load_dwordx4 v[62:65], v[0:1], off offset:384
	v_mfma_f32_16x16x32_f16 v[102:105], v[74:77], v[90:93], v[102:105]
	v_mfma_f32_16x16x32_f16 v[24:27], v[74:77], v[94:97], v[24:27]
	v_mfma_f32_16x16x32_f16 v[114:117], v[106:109], v[90:93], v[114:117]
	v_mfma_f32_16x16x32_f16 v[40:43], v[106:109], v[94:97], v[40:43]
	v_mfma_f32_16x16x32_f16 v[70:73], v[118:121], v[90:93], v[70:73]
	global_load_dwordx4 v[90:93], v[2:3], off offset:384
	global_load_dwordx4 v[122:125], v[4:5], off offset:384
	global_load_dwordx4 v[126:129], v[6:7], off offset:384
	global_load_dwordx4 v[74:77], v[8:9], off offset:384
	global_load_dwordx4 v[138:141], v[10:11], off offset:384
	global_load_dwordx4 v[142:145], v[12:13], off offset:384
	global_load_dwordx4 v[154:157], v[14:15], off offset:384
	s_waitcnt lgkmcnt(0)
	s_barrier
; #define GL_LOAD(s_, kt_) if (VAR != 1) { a##s_##0 = GL_A(0, kt_); a##s_##1 = GL_A(1, kt_); a##s_##2 = GL_A(2, kt_); a##s_##3 = GL_A(3, kt_); b##s_##0 = GL_B(0, kt_); b##s_##1 = GL_B(1, kt_); b##s_##2 = GL_B(2, kt_); b##s_##3 = GL_B(3, kt_); }
; #define LDS_STORE(s_, buf_) if (VAR != 2) { LDS_ST1(sA, 0, buf_, a##s_##0) LDS_ST1(sA, 1, buf_, a##s_##1) LDS_ST1(sA, 2, buf_, a##s_##2) LDS_ST1(sA, 3, buf_, a##s_##3) LDS_ST1(sB, 0, buf_, b##s_##0) LDS_ST1(sB, 1, buf_, b##s_##1) LDS_ST1(sB, 2, buf_, b##s_##2) LDS_ST1(sB, 3, buf_, b##s_##3) }
;     ...
;   GL_LOAD(0, 0)
;   GL_LOAD(1, 1)
;   LDS_STORE(0, 0)
;   if (VAR != 4) __syncthreads();
; #pragma unroll
;   for (int kt = 0; kt < nk; kt += 2) {
;     if (kt + 2 < nk) { GL_LOAD(0, kt + 2) }
;     MMA_TILE(0)
;     LDS_STORE(1, 1)
;     if (VAR != 4) __syncthreads();
;     if (kt + 3 < nk) { GL_LOAD(1, kt + 3) }
;     MMA_TILE(1)
;     if (kt + 2 < nk) { LDS_STORE(0, 0) }
;     if (VAR != 4) __syncthreads();
	v_mfma_f32_16x16x32_f16 v[48:51], v[118:121], v[94:97], v[50:53]
	ds_read_b128 v[106:109], v16 offset:32768
	ds_read_b128 v[94:97], v21
	s_waitcnt lgkmcnt(0)
	v_mfma_f32_16x16x32_f16 v[36:39], v[106:109], v[94:97], v[36:39]
	ds_read_b128 v[52:55], v16 offset:34816
	ds_read_b128 v[110:113], v21 offset:2048
	s_waitcnt lgkmcnt(0)
	v_mfma_f32_16x16x32_f16 v[66:69], v[106:109], v[110:113], v[66:69]
	ds_read_b128 v[118:121], v16 offset:36864
	v_mfma_f32_16x16x32_f16 v[44:47], v[52:55], v[94:97], v[44:47]
	ds_read_b128 v[130:133], v16 offset:38912
	v_mfma_f32_16x16x32_f16 v[78:81], v[52:55], v[110:113], v[78:81]
	s_waitcnt vmcnt(7)
	ds_write_b128 v19, v[62:65] offset:16384
	s_waitcnt lgkmcnt(2)
	v_mfma_f32_16x16x32_f16 v[82:85], v[118:121], v[94:97], v[82:85]
	s_waitcnt vmcnt(6)
	ds_write_b128 v20, v[90:93] offset:16384
	v_mfma_f32_16x16x32_f16 v[86:89], v[118:121], v[110:113], v[86:89]
	s_waitcnt vmcnt(5)
	ds_write_b128 v17, v[122:125] offset:16384
	s_waitcnt lgkmcnt(3)
	v_mfma_f32_16x16x32_f16 v[28:31], v[130:133], v[94:97], v[28:31]
	ds_read_b128 v[94:97], v21 offset:4096
	v_mfma_f32_16x16x32_f16 v[32:35], v[130:133], v[110:113], v[32:35]
	ds_read_b128 v[110:113], v21 offset:6144
	s_waitcnt lgkmcnt(1)
	v_mfma_f32_16x16x32_f16 v[98:101], v[106:109], v[94:97], v[98:101]
	s_waitcnt vmcnt(4)
	ds_write_b128 v18, v[126:129] offset:16384
	s_waitcnt lgkmcnt(1)
	v_mfma_f32_16x16x32_f16 v[58:61], v[106:109], v[110:113], v[58:61]
	ds_read_b128 v[106:109], v23
	v_mfma_f32_16x16x32_f16 v[102:105], v[52:55], v[94:97], v[102:105]
	s_waitcnt vmcnt(3)
	ds_write_b128 v19, v[74:77] offset:49152
	v_mfma_f32_16x16x32_f16 v[24:27], v[52:55], v[110:113], v[24:27]
	ds_read_b128 v[52:55], v22 offset:32768
	v_mfma_f32_16x16x32_f16 v[114:117], v[118:121], v[94:97], v[114:117]
	s_waitcnt vmcnt(2)
	ds_write_b128 v20, v[138:141] offset:49152
	v_mfma_f32_16x16x32_f16 v[40:43], v[118:121], v[110:113], v[40:43]
	ds_read_b128 v[118:121], v22 offset:36864
	v_mfma_f32_16x16x32_f16 v[70:73], v[130:133], v[94:97], v[70:73]
	ds_read_b128 v[94:97], v22 offset:34816
	v_mfma_f32_16x16x32_f16 v[48:51], v[130:133], v[110:113], v[48:51]
	ds_read_b128 v[110:113], v23 offset:2048
	s_waitcnt lgkmcnt(4)
	v_mfma_f32_16x16x32_f16 v[36:39], v[52:55], v[106:109], v[36:39]
	ds_read_b128 v[130:133], v22 offset:38912
	s_waitcnt lgkmcnt(1)
	v_mfma_f32_16x16x32_f16 v[66:69], v[52:55], v[110:113], v[66:69]
	s_waitcnt vmcnt(1)
	ds_write_b128 v17, v[142:145] offset:49152
	v_mfma_f32_16x16x32_f16 v[44:47], v[94:97], v[106:109], v[44:47]
	s_waitcnt vmcnt(0)
	ds_write_b128 v18, v[154:157] offset:49152
	v_mfma_f32_16x16x32_f16 v[78:81], v[94:97], v[110:113], v[78:81]
	v_mfma_f32_16x16x32_f16 v[82:85], v[118:121], v[106:109], v[82:85]
	v_mfma_f32_16x16x32_f16 v[86:89], v[118:121], v[110:113], v[86:89]
	s_waitcnt lgkmcnt(2)
	v_mfma_f32_16x16x32_f16 v[28:31], v[130:133], v[106:109], v[28:31]
	ds_read_b128 v[106:109], v23 offset:4096
	v_mfma_f32_16x16x32_f16 v[32:35], v[130:133], v[110:113], v[32:35]
	ds_read_b128 v[110:113], v23 offset:6144
	s_waitcnt lgkmcnt(1)
	v_mfma_f32_16x16x32_f16 v[98:101], v[52:55], v[106:109], v[98:101]
	s_waitcnt lgkmcnt(0)
	v_mfma_f32_16x16x32_f16 v[52:55], v[52:55], v[110:113], v[58:61]
	s_nop 2
	global_load_dwordx4 v[58:61], v[0:1], off offset:512
	v_mfma_f32_16x16x32_f16 v[102:105], v[94:97], v[106:109], v[102:105]
	v_mfma_f32_16x16x32_f16 v[24:27], v[94:97], v[110:113], v[24:27]
	v_mfma_f32_16x16x32_f16 v[114:117], v[118:121], v[106:109], v[114:117]
	v_mfma_f32_16x16x32_f16 v[40:43], v[118:121], v[110:113], v[40:43]
	v_mfma_f32_16x16x32_f16 v[70:73], v[130:133], v[106:109], v[70:73]
	global_load_dwordx4 v[106:109], v[2:3], off offset:512
	global_load_dwordx4 v[134:137], v[4:5], off offset:512
	global_load_dwordx4 v[158:161], v[6:7], off offset:512
	global_load_dwordx4 v[94:97], v[8:9], off offset:512
	global_load_dwordx4 v[162:165], v[10:11], off offset:512
	global_load_dwordx4 v[166:169], v[12:13], off offset:512
	global_load_dwordx4 v[190:193], v[14:15], off offset:512
	s_waitcnt lgkmcnt(0)
	s_barrier
	v_mfma_f32_16x16x32_f16 v[48:51], v[130:133], v[110:113], v[48:51]
	ds_read_b128 v[62:65], v16 offset:49152
	ds_read_b128 v[90:93], v21 offset:16384
	s_waitcnt lgkmcnt(0)
	v_mfma_f32_16x16x32_f16 v[36:39], v[62:65], v[90:93], v[36:39]
	ds_read_b128 v[74:77], v16 offset:51200
	ds_read_b128 v[110:113], v21 offset:18432
	s_waitcnt lgkmcnt(0)
	v_mfma_f32_16x16x32_f16 v[66:69], v[62:65], v[110:113], v[66:69]
	ds_read_b128 v[118:121], v16 offset:53248
	v_mfma_f32_16x16x32_f16 v[44:47], v[74:77], v[90:93], v[44:47]
	ds_read_b128 v[122:125], v16 offset:55296
	v_mfma_f32_16x16x32_f16 v[78:81], v[74:77], v[110:113], v[78:81]
	s_waitcnt vmcnt(7)
	ds_write_b128 v19, v[58:61]
	s_waitcnt lgkmcnt(2)
	v_mfma_f32_16x16x32_f16 v[82:85], v[118:121], v[90:93], v[82:85]
	s_waitcnt vmcnt(6)
	ds_write_b128 v20, v[106:109]
	v_mfma_f32_16x16x32_f16 v[86:89], v[118:121], v[110:113], v[86:89]
	s_waitcnt vmcnt(5)
	ds_write_b128 v17, v[134:137]
	s_waitcnt lgkmcnt(3)
	v_mfma_f32_16x16x32_f16 v[28:31], v[122:125], v[90:93], v[28:31]
	ds_read_b128 v[90:93], v21 offset:20480
	v_mfma_f32_16x16x32_f16 v[32:35], v[122:125], v[110:113], v[32:35]
	ds_read_b128 v[110:113], v21 offset:22528
	s_waitcnt lgkmcnt(1)
	v_mfma_f32_16x16x32_f16 v[98:101], v[62:65], v[90:93], v[98:101]
	s_waitcnt vmcnt(4)
	ds_write_b128 v18, v[158:161]
	s_waitcnt lgkmcnt(1)
	v_mfma_f32_16x16x32_f16 v[52:55], v[62:65], v[110:113], v[52:55]
	ds_read_b128 v[62:65], v22 offset:49152
	v_mfma_f32_16x16x32_f16 v[102:105], v[74:77], v[90:93], v[102:105]
	s_waitcnt vmcnt(3)
; #define GL_LOAD(s_, kt_) if (VAR != 1) { a##s_##0 = GL_A(0, kt_); a##s_##1 = GL_A(1, kt_); a##s_##2 = GL_A(2, kt_); a##s_##3 = GL_A(3, kt_); b##s_##0 = GL_B(0, kt_); b##s_##1 = GL_B(1, kt_); b##s_##2 = GL_B(2, kt_); b##s_##3 = GL_B(3, kt_); }
; #define LDS_STORE(s_, buf_) if (VAR != 2) { LDS_ST1(sA, 0, buf_, a##s_##0) LDS_ST1(sA, 1, buf_, a##s_##1) LDS_ST1(sA, 2, buf_, a##s_##2) LDS_ST1(sA, 3, buf_, a##s_##3) LDS_ST1(sB, 0, buf_, b##s_##0) LDS_ST1(sB, 1, buf_, b##s_##1) LDS_ST1(sB, 2, buf_, b##s_##2) LDS_ST1(sB, 3, buf_, b##s_##3) }
;     ...
;   GL_LOAD(0, 0)
;   GL_LOAD(1, 1)
;   LDS_STORE(0, 0)
;   if (VAR != 4) __syncthreads();
; #pragma unroll
;   for (int kt = 0; kt < nk; kt += 2) {
;     if (kt + 2 < nk) { GL_LOAD(0, kt + 2) }
;     MMA_TILE(0)
;     LDS_STORE(1, 1)
;     if (VAR != 4) __syncthreads();
;     if (kt + 3 < nk) { GL_LOAD(1, kt + 3) }
;     MMA_TILE(1)
;     if (kt + 2 < nk) { LDS_STORE(0, 0) }
;     if (VAR != 4) __syncthreads();
	ds_write_b128 v19, v[94:97] offset:32768
	v_mfma_f32_16x16x32_f16 v[24:27], v[74:77], v[110:113], v[24:27]
	ds_read_b128 v[74:77], v22 offset:51200
	v_mfma_f32_16x16x32_f16 v[114:117], v[118:121], v[90:93], v[114:117]
	s_waitcnt vmcnt(2)
	ds_write_b128 v20, v[162:165] offset:32768
	v_mfma_f32_16x16x32_f16 v[40:43], v[118:121], v[110:113], v[40:43]
	ds_read_b128 v[118:121], v22 offset:53248
	v_mfma_f32_16x16x32_f16 v[70:73], v[122:125], v[90:93], v[70:73]
	ds_read_b128 v[90:93], v23 offset:16384
	v_mfma_f32_16x16x32_f16 v[48:51], v[122:125], v[110:113], v[48:51]
	ds_read_b128 v[110:113], v23 offset:18432
	s_waitcnt lgkmcnt(1)
	v_mfma_f32_16x16x32_f16 v[36:39], v[62:65], v[90:93], v[36:39]
	ds_read_b128 v[122:125], v22 offset:55296
	s_waitcnt lgkmcnt(1)
	v_mfma_f32_16x16x32_f16 v[66:69], v[62:65], v[110:113], v[66:69]
	s_waitcnt vmcnt(1)
	ds_write_b128 v17, v[166:169] offset:32768
	v_mfma_f32_16x16x32_f16 v[44:47], v[74:77], v[90:93], v[44:47]
	s_waitcnt vmcnt(0)
	ds_write_b128 v18, v[190:193] offset:32768
	v_mfma_f32_16x16x32_f16 v[78:81], v[74:77], v[110:113], v[78:81]
	v_mfma_f32_16x16x32_f16 v[82:85], v[118:121], v[90:93], v[82:85]
	v_mfma_f32_16x16x32_f16 v[86:89], v[118:121], v[110:113], v[86:89]
	s_waitcnt lgkmcnt(2)
	v_mfma_f32_16x16x32_f16 v[28:31], v[122:125], v[90:93], v[28:31]
	ds_read_b128 v[90:93], v23 offset:20480
	v_mfma_f32_16x16x32_f16 v[32:35], v[122:125], v[110:113], v[32:35]
	ds_read_b128 v[110:113], v23 offset:22528
	s_waitcnt lgkmcnt(1)
	v_mfma_f32_16x16x32_f16 v[98:101], v[62:65], v[90:93], v[98:101]
	s_waitcnt lgkmcnt(0)
	v_mfma_f32_16x16x32_f16 v[52:55], v[62:65], v[110:113], v[52:55]
	global_load_dwordx4 v[62:65], v[0:1], off offset:640
	v_mfma_f32_16x16x32_f16 v[102:105], v[74:77], v[90:93], v[102:105]
	v_mfma_f32_16x16x32_f16 v[24:27], v[74:77], v[110:113], v[24:27]
	v_mfma_f32_16x16x32_f16 v[114:117], v[118:121], v[90:93], v[114:117]
	v_mfma_f32_16x16x32_f16 v[40:43], v[118:121], v[110:113], v[40:43]
	v_mfma_f32_16x16x32_f16 v[70:73], v[122:125], v[90:93], v[70:73]
	global_load_dwordx4 v[90:93], v[2:3], off offset:640
	global_load_dwordx4 v[126:129], v[4:5], off offset:640
	global_load_dwordx4 v[130:133], v[6:7], off offset:640
	global_load_dwordx4 v[74:77], v[8:9], off offset:640
	global_load_dwordx4 v[138:141], v[10:11], off offset:640
	global_load_dwordx4 v[142:145], v[12:13], off offset:640
	global_load_dwordx4 v[154:157], v[14:15], off offset:640
	s_waitcnt lgkmcnt(0)
	s_barrier
	v_mfma_f32_16x16x32_f16 v[48:51], v[122:125], v[110:113], v[48:51]
	ds_read_b128 v[58:61], v16 offset:32768
	ds_read_b128 v[106:109], v21
	s_waitcnt lgkmcnt(0)
	v_mfma_f32_16x16x32_f16 v[36:39], v[58:61], v[106:109], v[36:39]
	ds_read_b128 v[94:97], v16 offset:34816
	ds_read_b128 v[110:113], v21 offset:2048
	s_waitcnt lgkmcnt(0)
	v_mfma_f32_16x16x32_f16 v[66:69], v[58:61], v[110:113], v[66:69]
	ds_read_b128 v[118:121], v16 offset:36864
	v_mfma_f32_16x16x32_f16 v[44:47], v[94:97], v[106:109], v[44:47]
	ds_read_b128 v[122:125], v16 offset:38912
	v_mfma_f32_16x16x32_f16 v[78:81], v[94:97], v[110:113], v[78:81]
	s_waitcnt vmcnt(7)
	ds_write_b128 v19, v[62:65] offset:16384
	s_waitcnt lgkmcnt(2)
	v_mfma_f32_16x16x32_f16 v[82:85], v[118:121], v[106:109], v[82:85]
	s_waitcnt vmcnt(6)
	ds_write_b128 v20, v[90:93] offset:16384
	v_mfma_f32_16x16x32_f16 v[86:89], v[118:121], v[110:113], v[86:89]
	s_waitcnt vmcnt(5)
	ds_write_b128 v17, v[126:129] offset:16384
	s_waitcnt lgkmcnt(3)
	v_mfma_f32_16x16x32_f16 v[28:31], v[122:125], v[106:109], v[28:31]
	ds_read_b128 v[106:109], v21 offset:4096
	v_mfma_f32_16x16x32_f16 v[32:35], v[122:125], v[110:113], v[32:35]
	ds_read_b128 v[110:113], v21 offset:6144
	s_waitcnt lgkmcnt(1)
	v_mfma_f32_16x16x32_f16 v[98:101], v[58:61], v[106:109], v[98:101]
	s_waitcnt vmcnt(4)
	ds_write_b128 v18, v[130:133] offset:16384
	s_waitcnt lgkmcnt(1)
	v_mfma_f32_16x16x32_f16 v[52:55], v[58:61], v[110:113], v[52:55]
	ds_read_b128 v[58:61], v22 offset:32768
	v_mfma_f32_16x16x32_f16 v[102:105], v[94:97], v[106:109], v[102:105]
	s_waitcnt vmcnt(3)
	ds_write_b128 v19, v[74:77] offset:49152
	v_mfma_f32_16x16x32_f16 v[24:27], v[94:97], v[110:113], v[24:27]
	ds_read_b128 v[94:97], v22 offset:34816
	v_mfma_f32_16x16x32_f16 v[114:117], v[118:121], v[106:109], v[114:117]
	s_waitcnt vmcnt(2)
	ds_write_b128 v20, v[138:141] offset:49152
	v_mfma_f32_16x16x32_f16 v[40:43], v[118:121], v[110:113], v[40:43]
	ds_read_b128 v[118:121], v22 offset:36864
	v_mfma_f32_16x16x32_f16 v[70:73], v[122:125], v[106:109], v[70:73]
	ds_read_b128 v[106:109], v23
	v_mfma_f32_16x16x32_f16 v[48:51], v[122:125], v[110:113], v[48:51]
	ds_read_b128 v[110:113], v23 offset:2048
	s_waitcnt lgkmcnt(1)
	v_mfma_f32_16x16x32_f16 v[36:39], v[58:61], v[106:109], v[36:39]
	ds_read_b128 v[122:125], v22 offset:38912
	s_waitcnt lgkmcnt(1)
	v_mfma_f32_16x16x32_f16 v[66:69], v[58:61], v[110:113], v[66:69]
	s_waitcnt vmcnt(1)
	ds_write_b128 v17, v[142:145] offset:49152
	v_mfma_f32_16x16x32_f16 v[44:47], v[94:97], v[106:109], v[44:47]
	s_waitcnt vmcnt(0)
	ds_write_b128 v18, v[154:157] offset:49152
	v_mfma_f32_16x16x32_f16 v[78:81], v[94:97], v[110:113], v[78:81]
	v_mfma_f32_16x16x32_f16 v[82:85], v[118:121], v[106:109], v[82:85]
	v_mfma_f32_16x16x32_f16 v[86:89], v[118:121], v[110:113], v[86:89]
	s_waitcnt lgkmcnt(2)
	v_mfma_f32_16x16x32_f16 v[28:31], v[122:125], v[106:109], v[28:31]
	ds_read_b128 v[106:109], v23 offset:4096
	v_mfma_f32_16x16x32_f16 v[32:35], v[122:125], v[110:113], v[32:35]
	ds_read_b128 v[110:113], v23 offset:6144
	s_waitcnt lgkmcnt(1)
	v_mfma_f32_16x16x32_f16 v[98:101], v[58:61], v[106:109], v[98:101]
	s_waitcnt lgkmcnt(0)
	v_mfma_f32_16x16x32_f16 v[52:55], v[58:61], v[110:113], v[52:55]
	global_load_dwordx4 v[58:61], v[0:1], off offset:768
	v_mfma_f32_16x16x32_f16 v[102:105], v[94:97], v[106:109], v[102:105]
	v_mfma_f32_16x16x32_f16 v[24:27], v[94:97], v[110:113], v[24:27]
	v_mfma_f32_16x16x32_f16 v[114:117], v[118:121], v[106:109], v[114:117]
	v_mfma_f32_16x16x32_f16 v[40:43], v[118:121], v[110:113], v[40:43]
	v_mfma_f32_16x16x32_f16 v[70:73], v[122:125], v[106:109], v[70:73]
	global_load_dwordx4 v[106:109], v[2:3], off offset:768
	global_load_dwordx4 v[134:137], v[4:5], off offset:768
	global_load_dwordx4 v[158:161], v[6:7], off offset:768
	global_load_dwordx4 v[94:97], v[8:9], off offset:768
	global_load_dwordx4 v[162:165], v[10:11], off offset:768
	global_load_dwordx4 v[166:169], v[12:13], off offset:768
	global_load_dwordx4 v[190:193], v[14:15], off offset:768
	s_waitcnt lgkmcnt(0)
	s_barrier
; #define GL_LOAD(s_, kt_) if (VAR != 1) { a##s_##0 = GL_A(0, kt_); a##s_##1 = GL_A(1, kt_); a##s_##2 = GL_A(2, kt_); a##s_##3 = GL_A(3, kt_); b##s_##0 = GL_B(0, kt_); b##s_##1 = GL_B(1, kt_); b##s_##2 = GL_B(2, kt_); b##s_##3 = GL_B(3, kt_); }
; #define LDS_STORE(s_, buf_) if (VAR != 2) { LDS_ST1(sA, 0, buf_, a##s_##0) LDS_ST1(sA, 1, buf_, a##s_##1) LDS_ST1(sA, 2, buf_, a##s_##2) LDS_ST1(sA, 3, buf_, a##s_##3) LDS_ST1(sB, 0, buf_, b##s_##0) LDS_ST1(sB, 1, buf_, b##s_##1) LDS_ST1(sB, 2, buf_, b##s_##2) LDS_ST1(sB, 3, buf_, b##s_##3) }
;     ...
;   GL_LOAD(0, 0)
;   GL_LOAD(1, 1)
;   LDS_STORE(0, 0)
;   if (VAR != 4) __syncthreads();
; #pragma unroll
;   for (int kt = 0; kt < nk; kt += 2) {
;     if (kt + 2 < nk) { GL_LOAD(0, kt + 2) }
;     MMA_TILE(0)
;     LDS_STORE(1, 1)
;     if (VAR != 4) __syncthreads();
;     if (kt + 3 < nk) { GL_LOAD(1, kt + 3) }
;     MMA_TILE(1)
;     if (kt + 2 < nk) { LDS_STORE(0, 0) }
;     if (VAR != 4) __syncthreads();
	v_mfma_f32_16x16x32_f16 v[48:51], v[122:125], v[110:113], v[48:51]
	ds_read_b128 v[62:65], v16 offset:49152
	ds_read_b128 v[90:93], v21 offset:16384
	s_waitcnt lgkmcnt(0)
	v_mfma_f32_16x16x32_f16 v[36:39], v[62:65], v[90:93], v[36:39]
	ds_read_b128 v[74:77], v16 offset:51200
	ds_read_b128 v[110:113], v21 offset:18432
	s_waitcnt lgkmcnt(0)
	v_mfma_f32_16x16x32_f16 v[66:69], v[62:65], v[110:113], v[66:69]
	ds_read_b128 v[118:121], v16 offset:53248
	v_mfma_f32_16x16x32_f16 v[44:47], v[74:77], v[90:93], v[44:47]
	ds_read_b128 v[122:125], v16 offset:55296
	v_mfma_f32_16x16x32_f16 v[78:81], v[74:77], v[110:113], v[78:81]
	s_waitcnt vmcnt(7)
	ds_write_b128 v19, v[58:61]
	s_waitcnt lgkmcnt(2)
	v_mfma_f32_16x16x32_f16 v[82:85], v[118:121], v[90:93], v[82:85]
	s_waitcnt vmcnt(6)
	ds_write_b128 v20, v[106:109]
	v_mfma_f32_16x16x32_f16 v[86:89], v[118:121], v[110:113], v[86:89]
	s_waitcnt vmcnt(5)
	ds_write_b128 v17, v[134:137]
	s_waitcnt lgkmcnt(3)
	v_mfma_f32_16x16x32_f16 v[28:31], v[122:125], v[90:93], v[28:31]
	ds_read_b128 v[90:93], v21 offset:20480
	v_mfma_f32_16x16x32_f16 v[32:35], v[122:125], v[110:113], v[32:35]
	ds_read_b128 v[110:113], v21 offset:22528
	s_waitcnt lgkmcnt(1)
	v_mfma_f32_16x16x32_f16 v[98:101], v[62:65], v[90:93], v[98:101]
	s_waitcnt vmcnt(4)
	ds_write_b128 v18, v[158:161]
	s_waitcnt lgkmcnt(1)
	v_mfma_f32_16x16x32_f16 v[52:55], v[62:65], v[110:113], v[52:55]
	ds_read_b128 v[62:65], v22 offset:49152
	v_mfma_f32_16x16x32_f16 v[102:105], v[74:77], v[90:93], v[102:105]
	s_waitcnt vmcnt(3)
	ds_write_b128 v19, v[94:97] offset:32768
	v_mfma_f32_16x16x32_f16 v[24:27], v[74:77], v[110:113], v[24:27]
	ds_read_b128 v[74:77], v22 offset:51200
	v_mfma_f32_16x16x32_f16 v[114:117], v[118:121], v[90:93], v[114:117]
	s_waitcnt vmcnt(2)
	ds_write_b128 v20, v[162:165] offset:32768
	v_mfma_f32_16x16x32_f16 v[40:43], v[118:121], v[110:113], v[40:43]
	ds_read_b128 v[118:121], v22 offset:53248
	v_mfma_f32_16x16x32_f16 v[70:73], v[122:125], v[90:93], v[70:73]
	ds_read_b128 v[90:93], v23 offset:16384
	v_mfma_f32_16x16x32_f16 v[48:51], v[122:125], v[110:113], v[48:51]
	ds_read_b128 v[110:113], v23 offset:18432
	s_waitcnt lgkmcnt(1)
	v_mfma_f32_16x16x32_f16 v[36:39], v[62:65], v[90:93], v[36:39]
	ds_read_b128 v[122:125], v22 offset:55296
	s_waitcnt lgkmcnt(1)
	v_mfma_f32_16x16x32_f16 v[66:69], v[62:65], v[110:113], v[66:69]
	s_waitcnt vmcnt(1)
	ds_write_b128 v17, v[166:169] offset:32768
	v_mfma_f32_16x16x32_f16 v[44:47], v[74:77], v[90:93], v[44:47]
	s_waitcnt vmcnt(0)
	ds_write_b128 v18, v[190:193] offset:32768
	v_mfma_f32_16x16x32_f16 v[78:81], v[74:77], v[110:113], v[78:81]
	v_mfma_f32_16x16x32_f16 v[82:85], v[118:121], v[90:93], v[82:85]
	v_mfma_f32_16x16x32_f16 v[86:89], v[118:121], v[110:113], v[86:89]
	s_waitcnt lgkmcnt(2)
	v_mfma_f32_16x16x32_f16 v[28:31], v[122:125], v[90:93], v[28:31]
	ds_read_b128 v[90:93], v23 offset:20480
	v_mfma_f32_16x16x32_f16 v[32:35], v[122:125], v[110:113], v[32:35]
	ds_read_b128 v[110:113], v23 offset:22528
	s_waitcnt lgkmcnt(1)
	v_mfma_f32_16x16x32_f16 v[98:101], v[62:65], v[90:93], v[98:101]
	s_waitcnt lgkmcnt(0)
	v_mfma_f32_16x16x32_f16 v[52:55], v[62:65], v[110:113], v[52:55]
	global_load_dwordx4 v[62:65], v[0:1], off offset:896
	v_mfma_f32_16x16x32_f16 v[102:105], v[74:77], v[90:93], v[102:105]
	v_mfma_f32_16x16x32_f16 v[24:27], v[74:77], v[110:113], v[24:27]
	v_mfma_f32_16x16x32_f16 v[114:117], v[118:121], v[90:93], v[114:117]
	v_mfma_f32_16x16x32_f16 v[40:43], v[118:121], v[110:113], v[40:43]
	v_mfma_f32_16x16x32_f16 v[70:73], v[122:125], v[90:93], v[70:73]
	global_load_dwordx4 v[90:93], v[2:3], off offset:896
	global_load_dwordx4 v[126:129], v[4:5], off offset:896
	global_load_dwordx4 v[130:133], v[6:7], off offset:896
	global_load_dwordx4 v[74:77], v[8:9], off offset:896
	global_load_dwordx4 v[138:141], v[10:11], off offset:896
	global_load_dwordx4 v[142:145], v[12:13], off offset:896
	global_load_dwordx4 v[154:157], v[14:15], off offset:896
	s_waitcnt lgkmcnt(0)
	s_barrier
	v_mfma_f32_16x16x32_f16 v[48:51], v[122:125], v[110:113], v[48:51]
	ds_read_b128 v[58:61], v16 offset:32768
	ds_read_b128 v[106:109], v21
	s_waitcnt lgkmcnt(0)
	v_mfma_f32_16x16x32_f16 v[36:39], v[58:61], v[106:109], v[36:39]
	ds_read_b128 v[94:97], v16 offset:34816
	ds_read_b128 v[110:113], v21 offset:2048
	s_waitcnt lgkmcnt(0)
	v_mfma_f32_16x16x32_f16 v[66:69], v[58:61], v[110:113], v[66:69]
	ds_read_b128 v[118:121], v16 offset:36864
	v_mfma_f32_16x16x32_f16 v[44:47], v[94:97], v[106:109], v[44:47]
	ds_read_b128 v[122:125], v16 offset:38912
	v_mfma_f32_16x16x32_f16 v[78:81], v[94:97], v[110:113], v[78:81]
	s_waitcnt vmcnt(7)
	ds_write_b128 v19, v[62:65] offset:16384
	s_waitcnt lgkmcnt(2)
	v_mfma_f32_16x16x32_f16 v[82:85], v[118:121], v[106:109], v[82:85]
	s_waitcnt vmcnt(6)
	ds_write_b128 v20, v[90:93] offset:16384
	v_mfma_f32_16x16x32_f16 v[86:89], v[118:121], v[110:113], v[86:89]
	s_waitcnt vmcnt(5)
	ds_write_b128 v17, v[126:129] offset:16384
	s_waitcnt lgkmcnt(3)
	v_mfma_f32_16x16x32_f16 v[28:31], v[122:125], v[106:109], v[28:31]
	ds_read_b128 v[106:109], v21 offset:4096
	v_mfma_f32_16x16x32_f16 v[32:35], v[122:125], v[110:113], v[32:35]
	ds_read_b128 v[110:113], v21 offset:6144
	s_waitcnt lgkmcnt(1)
	v_mfma_f32_16x16x32_f16 v[98:101], v[58:61], v[106:109], v[98:101]
	s_waitcnt vmcnt(4)
	ds_write_b128 v18, v[130:133] offset:16384
	s_waitcnt lgkmcnt(1)
	v_mfma_f32_16x16x32_f16 v[52:55], v[58:61], v[110:113], v[52:55]
	ds_read_b128 v[58:61], v22 offset:32768
	v_mfma_f32_16x16x32_f16 v[102:105], v[94:97], v[106:109], v[102:105]
	s_waitcnt vmcnt(3)
; #define GL_LOAD(s_, kt_) if (VAR != 1) { a##s_##0 = GL_A(0, kt_); a##s_##1 = GL_A(1, kt_); a##s_##2 = GL_A(2, kt_); a##s_##3 = GL_A(3, kt_); b##s_##0 = GL_B(0, kt_); b##s_##1 = GL_B(1, kt_); b##s_##2 = GL_B(2, kt_); b##s_##3 = GL_B(3, kt_); }
; #define LDS_STORE(s_, buf_) if (VAR != 2) { LDS_ST1(sA, 0, buf_, a##s_##0) LDS_ST1(sA, 1, buf_, a##s_##1) LDS_ST1(sA, 2, buf_, a##s_##2) LDS_ST1(sA, 3, buf_, a##s_##3) LDS_ST1(sB, 0, buf_, b##s_##0) LDS_ST1(sB, 1, buf_, b##s_##1) LDS_ST1(sB, 2, buf_, b##s_##2) LDS_ST1(sB, 3, buf_, b##s_##3) }
;     ...
;   GL_LOAD(0, 0)
;   GL_LOAD(1, 1)
;   LDS_STORE(0, 0)
;   if (VAR != 4) __syncthreads();
; #pragma unroll
;   for (int kt = 0; kt < nk; kt += 2) {
;     if (kt + 2 < nk) { GL_LOAD(0, kt + 2) }
;     MMA_TILE(0)
;     LDS_STORE(1, 1)
;     if (VAR != 4) __syncthreads();
;     if (kt + 3 < nk) { GL_LOAD(1, kt + 3) }
;     MMA_TILE(1)
;     if (kt + 2 < nk) { LDS_STORE(0, 0) }
;     if (VAR != 4) __syncthreads();
	ds_write_b128 v19, v[74:77] offset:49152
	v_mfma_f32_16x16x32_f16 v[24:27], v[94:97], v[110:113], v[24:27]
	ds_read_b128 v[94:97], v22 offset:34816
	v_mfma_f32_16x16x32_f16 v[114:117], v[118:121], v[106:109], v[114:117]
	s_waitcnt vmcnt(2)
	ds_write_b128 v20, v[138:141] offset:49152
	v_mfma_f32_16x16x32_f16 v[40:43], v[118:121], v[110:113], v[40:43]
	ds_read_b128 v[118:121], v22 offset:36864
	v_mfma_f32_16x16x32_f16 v[70:73], v[122:125], v[106:109], v[70:73]
	ds_read_b128 v[106:109], v23
	v_mfma_f32_16x16x32_f16 v[48:51], v[122:125], v[110:113], v[48:51]
	ds_read_b128 v[110:113], v23 offset:2048
	s_waitcnt lgkmcnt(1)
	v_mfma_f32_16x16x32_f16 v[36:39], v[58:61], v[106:109], v[36:39]
	ds_read_b128 v[122:125], v22 offset:38912
	s_waitcnt lgkmcnt(1)
	v_mfma_f32_16x16x32_f16 v[66:69], v[58:61], v[110:113], v[66:69]
	s_waitcnt vmcnt(1)
	ds_write_b128 v17, v[142:145] offset:49152
	v_mfma_f32_16x16x32_f16 v[44:47], v[94:97], v[106:109], v[44:47]
	s_waitcnt vmcnt(0)
	ds_write_b128 v18, v[154:157] offset:49152
	v_mfma_f32_16x16x32_f16 v[78:81], v[94:97], v[110:113], v[78:81]
	v_mfma_f32_16x16x32_f16 v[82:85], v[118:121], v[106:109], v[82:85]
	v_mfma_f32_16x16x32_f16 v[86:89], v[118:121], v[110:113], v[86:89]
	s_waitcnt lgkmcnt(2)
	v_mfma_f32_16x16x32_f16 v[28:31], v[122:125], v[106:109], v[28:31]
	ds_read_b128 v[106:109], v23 offset:4096
	v_mfma_f32_16x16x32_f16 v[32:35], v[122:125], v[110:113], v[32:35]
	ds_read_b128 v[110:113], v23 offset:6144
	s_waitcnt lgkmcnt(1)
	v_mfma_f32_16x16x32_f16 v[98:101], v[58:61], v[106:109], v[98:101]
	s_waitcnt lgkmcnt(0)
	v_mfma_f32_16x16x32_f16 v[52:55], v[58:61], v[110:113], v[52:55]
	global_load_dwordx4 v[58:61], v[0:1], off offset:1024
	v_mfma_f32_16x16x32_f16 v[102:105], v[94:97], v[106:109], v[102:105]
	v_mfma_f32_16x16x32_f16 v[24:27], v[94:97], v[110:113], v[24:27]
	v_mfma_f32_16x16x32_f16 v[114:117], v[118:121], v[106:109], v[114:117]
	v_mfma_f32_16x16x32_f16 v[40:43], v[118:121], v[110:113], v[40:43]
	v_mfma_f32_16x16x32_f16 v[70:73], v[122:125], v[106:109], v[70:73]
	global_load_dwordx4 v[106:109], v[2:3], off offset:1024
	global_load_dwordx4 v[134:137], v[4:5], off offset:1024
	global_load_dwordx4 v[158:161], v[6:7], off offset:1024
	global_load_dwordx4 v[94:97], v[8:9], off offset:1024
	global_load_dwordx4 v[162:165], v[10:11], off offset:1024
	global_load_dwordx4 v[166:169], v[12:13], off offset:1024
	global_load_dwordx4 v[190:193], v[14:15], off offset:1024
	s_waitcnt lgkmcnt(0)
	s_barrier
	v_mfma_f32_16x16x32_f16 v[48:51], v[122:125], v[110:113], v[48:51]
	ds_read_b128 v[62:65], v16 offset:49152
	ds_read_b128 v[90:93], v21 offset:16384
	s_waitcnt lgkmcnt(0)
	v_mfma_f32_16x16x32_f16 v[36:39], v[62:65], v[90:93], v[36:39]
	ds_read_b128 v[74:77], v16 offset:51200
	ds_read_b128 v[110:113], v21 offset:18432
	s_waitcnt lgkmcnt(0)
	v_mfma_f32_16x16x32_f16 v[66:69], v[62:65], v[110:113], v[66:69]
	ds_read_b128 v[118:121], v16 offset:53248
	v_mfma_f32_16x16x32_f16 v[44:47], v[74:77], v[90:93], v[44:47]
	ds_read_b128 v[122:125], v16 offset:55296
	v_mfma_f32_16x16x32_f16 v[78:81], v[74:77], v[110:113], v[78:81]
	s_waitcnt vmcnt(7)
	ds_write_b128 v19, v[58:61]
	s_waitcnt lgkmcnt(2)
	v_mfma_f32_16x16x32_f16 v[82:85], v[118:121], v[90:93], v[82:85]
	s_waitcnt vmcnt(6)
	ds_write_b128 v20, v[106:109]
	v_mfma_f32_16x16x32_f16 v[86:89], v[118:121], v[110:113], v[86:89]
	s_waitcnt vmcnt(5)
	ds_write_b128 v17, v[134:137]
	s_waitcnt lgkmcnt(3)
	v_mfma_f32_16x16x32_f16 v[28:31], v[122:125], v[90:93], v[28:31]
	ds_read_b128 v[90:93], v21 offset:20480
	v_mfma_f32_16x16x32_f16 v[32:35], v[122:125], v[110:113], v[32:35]
	ds_read_b128 v[110:113], v21 offset:22528
	s_waitcnt lgkmcnt(1)
	v_mfma_f32_16x16x32_f16 v[98:101], v[62:65], v[90:93], v[98:101]
	s_waitcnt vmcnt(4)
	ds_write_b128 v18, v[158:161]
	s_waitcnt lgkmcnt(1)
	v_mfma_f32_16x16x32_f16 v[52:55], v[62:65], v[110:113], v[52:55]
	ds_read_b128 v[62:65], v22 offset:49152
	v_mfma_f32_16x16x32_f16 v[102:105], v[74:77], v[90:93], v[102:105]
	s_waitcnt vmcnt(3)
	ds_write_b128 v19, v[94:97] offset:32768
	v_mfma_f32_16x16x32_f16 v[24:27], v[74:77], v[110:113], v[24:27]
	ds_read_b128 v[74:77], v22 offset:51200
	v_mfma_f32_16x16x32_f16 v[114:117], v[118:121], v[90:93], v[114:117]
	s_waitcnt vmcnt(2)
	ds_write_b128 v20, v[162:165] offset:32768
	v_mfma_f32_16x16x32_f16 v[40:43], v[118:121], v[110:113], v[40:43]
	ds_read_b128 v[118:121], v22 offset:53248
	v_mfma_f32_16x16x32_f16 v[70:73], v[122:125], v[90:93], v[70:73]
	ds_read_b128 v[90:93], v23 offset:16384
	v_mfma_f32_16x16x32_f16 v[48:51], v[122:125], v[110:113], v[48:51]
	ds_read_b128 v[110:113], v23 offset:18432
	s_waitcnt lgkmcnt(1)
	v_mfma_f32_16x16x32_f16 v[36:39], v[62:65], v[90:93], v[36:39]
	ds_read_b128 v[122:125], v22 offset:55296
	s_waitcnt lgkmcnt(1)
	v_mfma_f32_16x16x32_f16 v[66:69], v[62:65], v[110:113], v[66:69]
	s_waitcnt vmcnt(1)
	ds_write_b128 v17, v[166:169] offset:32768
	v_mfma_f32_16x16x32_f16 v[44:47], v[74:77], v[90:93], v[44:47]
	s_waitcnt vmcnt(0)
	ds_write_b128 v18, v[190:193] offset:32768
	v_mfma_f32_16x16x32_f16 v[78:81], v[74:77], v[110:113], v[78:81]
	v_mfma_f32_16x16x32_f16 v[82:85], v[118:121], v[90:93], v[82:85]
	v_mfma_f32_16x16x32_f16 v[86:89], v[118:121], v[110:113], v[86:89]
	s_waitcnt lgkmcnt(2)
	v_mfma_f32_16x16x32_f16 v[28:31], v[122:125], v[90:93], v[28:31]
	ds_read_b128 v[90:93], v23 offset:20480
	v_mfma_f32_16x16x32_f16 v[32:35], v[122:125], v[110:113], v[32:35]
	ds_read_b128 v[110:113], v23 offset:22528
	s_waitcnt lgkmcnt(1)
	v_mfma_f32_16x16x32_f16 v[98:101], v[62:65], v[90:93], v[98:101]
	s_waitcnt lgkmcnt(0)
	v_mfma_f32_16x16x32_f16 v[52:55], v[62:65], v[110:113], v[52:55]
	global_load_dwordx4 v[62:65], v[0:1], off offset:1152
	v_mfma_f32_16x16x32_f16 v[102:105], v[74:77], v[90:93], v[102:105]
	v_mfma_f32_16x16x32_f16 v[24:27], v[74:77], v[110:113], v[24:27]
	v_mfma_f32_16x16x32_f16 v[114:117], v[118:121], v[90:93], v[114:117]
	v_mfma_f32_16x16x32_f16 v[40:43], v[118:121], v[110:113], v[40:43]
	v_mfma_f32_16x16x32_f16 v[70:73], v[122:125], v[90:93], v[70:73]
	global_load_dwordx4 v[90:93], v[2:3], off offset:1152
	global_load_dwordx4 v[126:129], v[4:5], off offset:1152
	global_load_dwordx4 v[130:133], v[6:7], off offset:1152
	global_load_dwordx4 v[74:77], v[8:9], off offset:1152
	global_load_dwordx4 v[138:141], v[10:11], off offset:1152
	global_load_dwordx4 v[142:145], v[12:13], off offset:1152
	global_load_dwordx4 v[154:157], v[14:15], off offset:1152
	s_waitcnt lgkmcnt(0)
	s_barrier
; #define GL_LOAD(s_, kt_) if (VAR != 1) { a##s_##0 = GL_A(0, kt_); a##s_##1 = GL_A(1, kt_); a##s_##2 = GL_A(2, kt_); a##s_##3 = GL_A(3, kt_); b##s_##0 = GL_B(0, kt_); b##s_##1 = GL_B(1, kt_); b##s_##2 = GL_B(2, kt_); b##s_##3 = GL_B(3, kt_); }
; #define LDS_STORE(s_, buf_) if (VAR != 2) { LDS_ST1(sA, 0, buf_, a##s_##0) LDS_ST1(sA, 1, buf_, a##s_##1) LDS_ST1(sA, 2, buf_, a##s_##2) LDS_ST1(sA, 3, buf_, a##s_##3) LDS_ST1(sB, 0, buf_, b##s_##0) LDS_ST1(sB, 1, buf_, b##s_##1) LDS_ST1(sB, 2, buf_, b##s_##2) LDS_ST1(sB, 3, buf_, b##s_##3) }
;     ...
;   GL_LOAD(0, 0)
;   GL_LOAD(1, 1)
;   LDS_STORE(0, 0)
;   if (VAR != 4) __syncthreads();
; #pragma unroll
;   for (int kt = 0; kt < nk; kt += 2) {
;     if (kt + 2 < nk) { GL_LOAD(0, kt + 2) }
;     MMA_TILE(0)
;     LDS_STORE(1, 1)
;     if (VAR != 4) __syncthreads();
;     if (kt + 3 < nk) { GL_LOAD(1, kt + 3) }
;     MMA_TILE(1)
;     if (kt + 2 < nk) { LDS_STORE(0, 0) }
;     if (VAR != 4) __syncthreads();
	v_mfma_f32_16x16x32_f16 v[48:51], v[122:125], v[110:113], v[48:51]
	ds_read_b128 v[58:61], v16 offset:32768
	ds_read_b128 v[106:109], v21
	s_waitcnt lgkmcnt(0)
	v_mfma_f32_16x16x32_f16 v[36:39], v[58:61], v[106:109], v[36:39]
	ds_read_b128 v[94:97], v16 offset:34816
	ds_read_b128 v[110:113], v21 offset:2048
	s_waitcnt lgkmcnt(0)
	v_mfma_f32_16x16x32_f16 v[66:69], v[58:61], v[110:113], v[66:69]
	ds_read_b128 v[118:121], v16 offset:36864
	v_mfma_f32_16x16x32_f16 v[44:47], v[94:97], v[106:109], v[44:47]
	ds_read_b128 v[122:125], v16 offset:38912
	v_mfma_f32_16x16x32_f16 v[78:81], v[94:97], v[110:113], v[78:81]
	s_waitcnt vmcnt(7)
	ds_write_b128 v19, v[62:65] offset:16384
	s_waitcnt lgkmcnt(2)
	v_mfma_f32_16x16x32_f16 v[82:85], v[118:121], v[106:109], v[82:85]
	s_waitcnt vmcnt(6)
	ds_write_b128 v20, v[90:93] offset:16384
	v_mfma_f32_16x16x32_f16 v[86:89], v[118:121], v[110:113], v[86:89]
	s_waitcnt vmcnt(5)
	ds_write_b128 v17, v[126:129] offset:16384
	s_waitcnt lgkmcnt(3)
	v_mfma_f32_16x16x32_f16 v[28:31], v[122:125], v[106:109], v[28:31]
	ds_read_b128 v[106:109], v21 offset:4096
	v_mfma_f32_16x16x32_f16 v[32:35], v[122:125], v[110:113], v[32:35]
	ds_read_b128 v[110:113], v21 offset:6144
	s_waitcnt lgkmcnt(1)
	v_mfma_f32_16x16x32_f16 v[98:101], v[58:61], v[106:109], v[98:101]
	s_waitcnt vmcnt(4)
	ds_write_b128 v18, v[130:133] offset:16384
	s_waitcnt lgkmcnt(1)
	v_mfma_f32_16x16x32_f16 v[52:55], v[58:61], v[110:113], v[52:55]
	ds_read_b128 v[58:61], v22 offset:32768
	v_mfma_f32_16x16x32_f16 v[102:105], v[94:97], v[106:109], v[102:105]
	s_waitcnt vmcnt(3)
	ds_write_b128 v19, v[74:77] offset:49152
	v_mfma_f32_16x16x32_f16 v[24:27], v[94:97], v[110:113], v[24:27]
	ds_read_b128 v[94:97], v22 offset:34816
	v_mfma_f32_16x16x32_f16 v[114:117], v[118:121], v[106:109], v[114:117]
	s_waitcnt vmcnt(2)
	ds_write_b128 v20, v[138:141] offset:49152
	v_mfma_f32_16x16x32_f16 v[40:43], v[118:121], v[110:113], v[40:43]
	ds_read_b128 v[118:121], v22 offset:36864
	v_mfma_f32_16x16x32_f16 v[70:73], v[122:125], v[106:109], v[70:73]
	ds_read_b128 v[106:109], v23
	v_mfma_f32_16x16x32_f16 v[48:51], v[122:125], v[110:113], v[48:51]
	ds_read_b128 v[110:113], v23 offset:2048
	s_waitcnt lgkmcnt(1)
	v_mfma_f32_16x16x32_f16 v[36:39], v[58:61], v[106:109], v[36:39]
	ds_read_b128 v[122:125], v22 offset:38912
	s_waitcnt lgkmcnt(1)
	v_mfma_f32_16x16x32_f16 v[66:69], v[58:61], v[110:113], v[66:69]
	s_waitcnt vmcnt(1)
	ds_write_b128 v17, v[142:145] offset:49152
	v_mfma_f32_16x16x32_f16 v[44:47], v[94:97], v[106:109], v[44:47]
	s_waitcnt vmcnt(0)
	ds_write_b128 v18, v[154:157] offset:49152
	v_mfma_f32_16x16x32_f16 v[78:81], v[94:97], v[110:113], v[78:81]
	v_mfma_f32_16x16x32_f16 v[82:85], v[118:121], v[106:109], v[82:85]
	v_mfma_f32_16x16x32_f16 v[86:89], v[118:121], v[110:113], v[86:89]
	s_waitcnt lgkmcnt(2)
	v_mfma_f32_16x16x32_f16 v[28:31], v[122:125], v[106:109], v[28:31]
	ds_read_b128 v[106:109], v23 offset:4096
	v_mfma_f32_16x16x32_f16 v[32:35], v[122:125], v[110:113], v[32:35]
	ds_read_b128 v[110:113], v23 offset:6144
	s_waitcnt lgkmcnt(1)
	v_mfma_f32_16x16x32_f16 v[98:101], v[58:61], v[106:109], v[98:101]
	s_waitcnt lgkmcnt(0)
	v_mfma_f32_16x16x32_f16 v[52:55], v[58:61], v[110:113], v[52:55]
	global_load_dwordx4 v[58:61], v[0:1], off offset:1280
	v_mfma_f32_16x16x32_f16 v[102:105], v[94:97], v[106:109], v[102:105]
	v_mfma_f32_16x16x32_f16 v[24:27], v[94:97], v[110:113], v[24:27]
	v_mfma_f32_16x16x32_f16 v[114:117], v[118:121], v[106:109], v[114:117]
	v_mfma_f32_16x16x32_f16 v[40:43], v[118:121], v[110:113], v[40:43]
	v_mfma_f32_16x16x32_f16 v[70:73], v[122:125], v[106:109], v[70:73]
	global_load_dwordx4 v[106:109], v[2:3], off offset:1280
	global_load_dwordx4 v[134:137], v[4:5], off offset:1280
	global_load_dwordx4 v[158:161], v[6:7], off offset:1280
	global_load_dwordx4 v[94:97], v[8:9], off offset:1280
	global_load_dwordx4 v[162:165], v[10:11], off offset:1280
	global_load_dwordx4 v[166:169], v[12:13], off offset:1280
	global_load_dwordx4 v[190:193], v[14:15], off offset:1280
	s_waitcnt lgkmcnt(0)
	s_barrier
	v_mfma_f32_16x16x32_f16 v[48:51], v[122:125], v[110:113], v[48:51]
	ds_read_b128 v[62:65], v16 offset:49152
	ds_read_b128 v[90:93], v21 offset:16384
	s_waitcnt lgkmcnt(0)
	v_mfma_f32_16x16x32_f16 v[36:39], v[62:65], v[90:93], v[36:39]
	ds_read_b128 v[74:77], v16 offset:51200
	ds_read_b128 v[110:113], v21 offset:18432
	s_waitcnt lgkmcnt(0)
	v_mfma_f32_16x16x32_f16 v[66:69], v[62:65], v[110:113], v[66:69]
	ds_read_b128 v[118:121], v16 offset:53248
	v_mfma_f32_16x16x32_f16 v[44:47], v[74:77], v[90:93], v[44:47]
	ds_read_b128 v[122:125], v16 offset:55296
	v_mfma_f32_16x16x32_f16 v[78:81], v[74:77], v[110:113], v[78:81]
	s_waitcnt vmcnt(7)
	ds_write_b128 v19, v[58:61]
	s_waitcnt lgkmcnt(2)
	v_mfma_f32_16x16x32_f16 v[82:85], v[118:121], v[90:93], v[82:85]
	s_waitcnt vmcnt(6)
	ds_write_b128 v20, v[106:109]
	v_mfma_f32_16x16x32_f16 v[86:89], v[118:121], v[110:113], v[86:89]
	s_waitcnt vmcnt(5)
	ds_write_b128 v17, v[134:137]
	s_waitcnt lgkmcnt(3)
	v_mfma_f32_16x16x32_f16 v[28:31], v[122:125], v[90:93], v[28:31]
	ds_read_b128 v[90:93], v21 offset:20480
	v_mfma_f32_16x16x32_f16 v[32:35], v[122:125], v[110:113], v[32:35]
	ds_read_b128 v[110:113], v21 offset:22528
	s_waitcnt lgkmcnt(1)
	v_mfma_f32_16x16x32_f16 v[98:101], v[62:65], v[90:93], v[98:101]
	s_waitcnt vmcnt(4)
	ds_write_b128 v18, v[158:161]
	s_waitcnt lgkmcnt(1)
	v_mfma_f32_16x16x32_f16 v[52:55], v[62:65], v[110:113], v[52:55]
	ds_read_b128 v[62:65], v22 offset:49152
	v_mfma_f32_16x16x32_f16 v[102:105], v[74:77], v[90:93], v[102:105]
	s_waitcnt vmcnt(3)
; #define GL_LOAD(s_, kt_) if (VAR != 1) { a##s_##0 = GL_A(0, kt_); a##s_##1 = GL_A(1, kt_); a##s_##2 = GL_A(2, kt_); a##s_##3 = GL_A(3, kt_); b##s_##0 = GL_B(0, kt_); b##s_##1 = GL_B(1, kt_); b##s_##2 = GL_B(2, kt_); b##s_##3 = GL_B(3, kt_); }
; #define LDS_STORE(s_, buf_) if (VAR != 2) { LDS_ST1(sA, 0, buf_, a##s_##0) LDS_ST1(sA, 1, buf_, a##s_##1) LDS_ST1(sA, 2, buf_, a##s_##2) LDS_ST1(sA, 3, buf_, a##s_##3) LDS_ST1(sB, 0, buf_, b##s_##0) LDS_ST1(sB, 1, buf_, b##s_##1) LDS_ST1(sB, 2, buf_, b##s_##2) LDS_ST1(sB, 3, buf_, b##s_##3) }
;     ...
;   GL_LOAD(0, 0)
;   GL_LOAD(1, 1)
;   LDS_STORE(0, 0)
;   if (VAR != 4) __syncthreads();
; #pragma unroll
;   for (int kt = 0; kt < nk; kt += 2) {
;     if (kt + 2 < nk) { GL_LOAD(0, kt + 2) }
;     MMA_TILE(0)
;     LDS_STORE(1, 1)
;     if (VAR != 4) __syncthreads();
;     if (kt + 3 < nk) { GL_LOAD(1, kt + 3) }
;     MMA_TILE(1)
;     if (kt + 2 < nk) { LDS_STORE(0, 0) }
;     if (VAR != 4) __syncthreads();
	ds_write_b128 v19, v[94:97] offset:32768
	v_mfma_f32_16x16x32_f16 v[24:27], v[74:77], v[110:113], v[24:27]
	ds_read_b128 v[74:77], v22 offset:51200
	v_mfma_f32_16x16x32_f16 v[114:117], v[118:121], v[90:93], v[114:117]
	s_waitcnt vmcnt(2)
	ds_write_b128 v20, v[162:165] offset:32768
	v_mfma_f32_16x16x32_f16 v[40:43], v[118:121], v[110:113], v[40:43]
	ds_read_b128 v[118:121], v22 offset:53248
	v_mfma_f32_16x16x32_f16 v[70:73], v[122:125], v[90:93], v[70:73]
	ds_read_b128 v[90:93], v23 offset:16384
	v_mfma_f32_16x16x32_f16 v[48:51], v[122:125], v[110:113], v[48:51]
	ds_read_b128 v[110:113], v23 offset:18432
	s_waitcnt lgkmcnt(1)
	v_mfma_f32_16x16x32_f16 v[36:39], v[62:65], v[90:93], v[36:39]
	ds_read_b128 v[122:125], v22 offset:55296
	s_waitcnt lgkmcnt(1)
	v_mfma_f32_16x16x32_f16 v[66:69], v[62:65], v[110:113], v[66:69]
	s_waitcnt vmcnt(1)
	ds_write_b128 v17, v[166:169] offset:32768
	v_mfma_f32_16x16x32_f16 v[44:47], v[74:77], v[90:93], v[44:47]
	s_waitcnt vmcnt(0)
	ds_write_b128 v18, v[190:193] offset:32768
	v_mfma_f32_16x16x32_f16 v[78:81], v[74:77], v[110:113], v[78:81]
	v_mfma_f32_16x16x32_f16 v[82:85], v[118:121], v[90:93], v[82:85]
	v_mfma_f32_16x16x32_f16 v[86:89], v[118:121], v[110:113], v[86:89]
	s_waitcnt lgkmcnt(2)
	v_mfma_f32_16x16x32_f16 v[28:31], v[122:125], v[90:93], v[28:31]
	ds_read_b128 v[90:93], v23 offset:20480
	v_mfma_f32_16x16x32_f16 v[32:35], v[122:125], v[110:113], v[32:35]
	ds_read_b128 v[110:113], v23 offset:22528
	s_waitcnt lgkmcnt(1)
	v_mfma_f32_16x16x32_f16 v[98:101], v[62:65], v[90:93], v[98:101]
	s_waitcnt lgkmcnt(0)
	v_mfma_f32_16x16x32_f16 v[52:55], v[62:65], v[110:113], v[52:55]
	global_load_dwordx4 v[62:65], v[0:1], off offset:1408
	v_mfma_f32_16x16x32_f16 v[102:105], v[74:77], v[90:93], v[102:105]
	v_mfma_f32_16x16x32_f16 v[24:27], v[74:77], v[110:113], v[24:27]
	v_mfma_f32_16x16x32_f16 v[114:117], v[118:121], v[90:93], v[114:117]
	v_mfma_f32_16x16x32_f16 v[40:43], v[118:121], v[110:113], v[40:43]
	v_mfma_f32_16x16x32_f16 v[70:73], v[122:125], v[90:93], v[70:73]
	global_load_dwordx4 v[90:93], v[2:3], off offset:1408
	global_load_dwordx4 v[126:129], v[4:5], off offset:1408
	global_load_dwordx4 v[130:133], v[6:7], off offset:1408
	global_load_dwordx4 v[74:77], v[8:9], off offset:1408
	global_load_dwordx4 v[138:141], v[10:11], off offset:1408
	global_load_dwordx4 v[142:145], v[12:13], off offset:1408
	global_load_dwordx4 v[154:157], v[14:15], off offset:1408
	s_waitcnt lgkmcnt(0)
	s_barrier
	v_mfma_f32_16x16x32_f16 v[48:51], v[122:125], v[110:113], v[48:51]
	ds_read_b128 v[58:61], v16 offset:32768
	ds_read_b128 v[106:109], v21
	s_waitcnt lgkmcnt(0)
	v_mfma_f32_16x16x32_f16 v[36:39], v[58:61], v[106:109], v[36:39]
	ds_read_b128 v[94:97], v16 offset:34816
	ds_read_b128 v[110:113], v21 offset:2048
	s_waitcnt lgkmcnt(0)
	v_mfma_f32_16x16x32_f16 v[66:69], v[58:61], v[110:113], v[66:69]
	ds_read_b128 v[118:121], v16 offset:36864
	v_mfma_f32_16x16x32_f16 v[44:47], v[94:97], v[106:109], v[44:47]
	ds_read_b128 v[122:125], v16 offset:38912
	v_mfma_f32_16x16x32_f16 v[78:81], v[94:97], v[110:113], v[78:81]
	s_waitcnt vmcnt(7)
	ds_write_b128 v19, v[62:65] offset:16384
	s_waitcnt lgkmcnt(2)
	v_mfma_f32_16x16x32_f16 v[82:85], v[118:121], v[106:109], v[82:85]
	s_waitcnt vmcnt(6)
	ds_write_b128 v20, v[90:93] offset:16384
	v_mfma_f32_16x16x32_f16 v[86:89], v[118:121], v[110:113], v[86:89]
	s_waitcnt vmcnt(5)
	ds_write_b128 v17, v[126:129] offset:16384
	s_waitcnt lgkmcnt(3)
	v_mfma_f32_16x16x32_f16 v[28:31], v[122:125], v[106:109], v[28:31]
	ds_read_b128 v[106:109], v21 offset:4096
	v_mfma_f32_16x16x32_f16 v[32:35], v[122:125], v[110:113], v[32:35]
	ds_read_b128 v[110:113], v21 offset:6144
	s_waitcnt lgkmcnt(1)
	v_mfma_f32_16x16x32_f16 v[98:101], v[58:61], v[106:109], v[98:101]
	s_waitcnt vmcnt(4)
	ds_write_b128 v18, v[130:133] offset:16384
	s_waitcnt lgkmcnt(1)
	v_mfma_f32_16x16x32_f16 v[52:55], v[58:61], v[110:113], v[52:55]
	ds_read_b128 v[58:61], v22 offset:32768
	v_mfma_f32_16x16x32_f16 v[102:105], v[94:97], v[106:109], v[102:105]
	s_waitcnt vmcnt(3)
	ds_write_b128 v19, v[74:77] offset:49152
	v_mfma_f32_16x16x32_f16 v[24:27], v[94:97], v[110:113], v[24:27]
	ds_read_b128 v[94:97], v22 offset:34816
	v_mfma_f32_16x16x32_f16 v[114:117], v[118:121], v[106:109], v[114:117]
	s_waitcnt vmcnt(2)
	ds_write_b128 v20, v[138:141] offset:49152
	v_mfma_f32_16x16x32_f16 v[40:43], v[118:121], v[110:113], v[40:43]
	ds_read_b128 v[118:121], v22 offset:36864
	v_mfma_f32_16x16x32_f16 v[70:73], v[122:125], v[106:109], v[70:73]
	ds_read_b128 v[106:109], v23
	v_mfma_f32_16x16x32_f16 v[48:51], v[122:125], v[110:113], v[48:51]
	ds_read_b128 v[110:113], v23 offset:2048
	s_waitcnt lgkmcnt(1)
	v_mfma_f32_16x16x32_f16 v[36:39], v[58:61], v[106:109], v[36:39]
	ds_read_b128 v[122:125], v22 offset:38912
	s_waitcnt lgkmcnt(1)
	v_mfma_f32_16x16x32_f16 v[66:69], v[58:61], v[110:113], v[66:69]
	s_waitcnt vmcnt(1)
	ds_write_b128 v17, v[142:145] offset:49152
	v_mfma_f32_16x16x32_f16 v[44:47], v[94:97], v[106:109], v[44:47]
	s_waitcnt vmcnt(0)
	ds_write_b128 v18, v[154:157] offset:49152
	v_mfma_f32_16x16x32_f16 v[78:81], v[94:97], v[110:113], v[78:81]
	v_mfma_f32_16x16x32_f16 v[82:85], v[118:121], v[106:109], v[82:85]
	v_mfma_f32_16x16x32_f16 v[86:89], v[118:121], v[110:113], v[86:89]
	s_waitcnt lgkmcnt(2)
	v_mfma_f32_16x16x32_f16 v[28:31], v[122:125], v[106:109], v[28:31]
	ds_read_b128 v[106:109], v23 offset:4096
	v_mfma_f32_16x16x32_f16 v[32:35], v[122:125], v[110:113], v[32:35]
	ds_read_b128 v[110:113], v23 offset:6144
	s_waitcnt lgkmcnt(1)
	v_mfma_f32_16x16x32_f16 v[98:101], v[58:61], v[106:109], v[98:101]
	s_waitcnt lgkmcnt(0)
	v_mfma_f32_16x16x32_f16 v[52:55], v[58:61], v[110:113], v[52:55]
	global_load_dwordx4 v[58:61], v[0:1], off offset:1536
	v_mfma_f32_16x16x32_f16 v[102:105], v[94:97], v[106:109], v[102:105]
	v_mfma_f32_16x16x32_f16 v[24:27], v[94:97], v[110:113], v[24:27]
	v_mfma_f32_16x16x32_f16 v[114:117], v[118:121], v[106:109], v[114:117]
	v_mfma_f32_16x16x32_f16 v[40:43], v[118:121], v[110:113], v[40:43]
	v_mfma_f32_16x16x32_f16 v[70:73], v[122:125], v[106:109], v[70:73]
	global_load_dwordx4 v[106:109], v[2:3], off offset:1536
	global_load_dwordx4 v[134:137], v[4:5], off offset:1536
	global_load_dwordx4 v[158:161], v[6:7], off offset:1536
	global_load_dwordx4 v[94:97], v[8:9], off offset:1536
	global_load_dwordx4 v[162:165], v[10:11], off offset:1536
	global_load_dwordx4 v[166:169], v[12:13], off offset:1536
	global_load_dwordx4 v[190:193], v[14:15], off offset:1536
	s_waitcnt lgkmcnt(0)
	s_barrier
; #define GL_LOAD(s_, kt_) if (VAR != 1) { a##s_##0 = GL_A(0, kt_); a##s_##1 = GL_A(1, kt_); a##s_##2 = GL_A(2, kt_); a##s_##3 = GL_A(3, kt_); b##s_##0 = GL_B(0, kt_); b##s_##1 = GL_B(1, kt_); b##s_##2 = GL_B(2, kt_); b##s_##3 = GL_B(3, kt_); }
; #define LDS_STORE(s_, buf_) if (VAR != 2) { LDS_ST1(sA, 0, buf_, a##s_##0) LDS_ST1(sA, 1, buf_, a##s_##1) LDS_ST1(sA, 2, buf_, a##s_##2) LDS_ST1(sA, 3, buf_, a##s_##3) LDS_ST1(sB, 0, buf_, b##s_##0) LDS_ST1(sB, 1, buf_, b##s_##1) LDS_ST1(sB, 2, buf_, b##s_##2) LDS_ST1(sB, 3, buf_, b##s_##3) }
;     ...
;   GL_LOAD(0, 0)
;   GL_LOAD(1, 1)
;   LDS_STORE(0, 0)
;   if (VAR != 4) __syncthreads();
; #pragma unroll
;   for (int kt = 0; kt < nk; kt += 2) {
;     if (kt + 2 < nk) { GL_LOAD(0, kt + 2) }
;     MMA_TILE(0)
;     LDS_STORE(1, 1)
;     if (VAR != 4) __syncthreads();
;     if (kt + 3 < nk) { GL_LOAD(1, kt + 3) }
;     MMA_TILE(1)
;     if (kt + 2 < nk) { LDS_STORE(0, 0) }
;     if (VAR != 4) __syncthreads();
	v_mfma_f32_16x16x32_f16 v[48:51], v[122:125], v[110:113], v[48:51]
	ds_read_b128 v[62:65], v16 offset:49152
	ds_read_b128 v[90:93], v21 offset:16384
	s_waitcnt lgkmcnt(0)
	v_mfma_f32_16x16x32_f16 v[36:39], v[62:65], v[90:93], v[36:39]
	ds_read_b128 v[74:77], v16 offset:51200
	ds_read_b128 v[110:113], v21 offset:18432
	s_waitcnt lgkmcnt(0)
	v_mfma_f32_16x16x32_f16 v[66:69], v[62:65], v[110:113], v[66:69]
	ds_read_b128 v[118:121], v16 offset:53248
	v_mfma_f32_16x16x32_f16 v[44:47], v[74:77], v[90:93], v[44:47]
	ds_read_b128 v[122:125], v16 offset:55296
	v_mfma_f32_16x16x32_f16 v[78:81], v[74:77], v[110:113], v[78:81]
	s_waitcnt vmcnt(7)
	ds_write_b128 v19, v[58:61]
	s_waitcnt lgkmcnt(2)
	v_mfma_f32_16x16x32_f16 v[82:85], v[118:121], v[90:93], v[82:85]
	s_waitcnt vmcnt(6)
	ds_write_b128 v20, v[106:109]
	v_mfma_f32_16x16x32_f16 v[86:89], v[118:121], v[110:113], v[86:89]
	s_waitcnt vmcnt(5)
	ds_write_b128 v17, v[134:137]
	s_waitcnt lgkmcnt(3)
	v_mfma_f32_16x16x32_f16 v[28:31], v[122:125], v[90:93], v[28:31]
	ds_read_b128 v[90:93], v21 offset:20480
	v_mfma_f32_16x16x32_f16 v[32:35], v[122:125], v[110:113], v[32:35]
	ds_read_b128 v[110:113], v21 offset:22528
	s_waitcnt lgkmcnt(1)
	v_mfma_f32_16x16x32_f16 v[98:101], v[62:65], v[90:93], v[98:101]
	s_waitcnt vmcnt(4)
	ds_write_b128 v18, v[158:161]
	s_waitcnt lgkmcnt(1)
	v_mfma_f32_16x16x32_f16 v[52:55], v[62:65], v[110:113], v[52:55]
	ds_read_b128 v[62:65], v22 offset:49152
	v_mfma_f32_16x16x32_f16 v[102:105], v[74:77], v[90:93], v[102:105]
	s_waitcnt vmcnt(3)
	ds_write_b128 v19, v[94:97] offset:32768
	v_mfma_f32_16x16x32_f16 v[24:27], v[74:77], v[110:113], v[24:27]
	ds_read_b128 v[74:77], v22 offset:51200
	v_mfma_f32_16x16x32_f16 v[114:117], v[118:121], v[90:93], v[114:117]
	s_waitcnt vmcnt(2)
	ds_write_b128 v20, v[162:165] offset:32768
	v_mfma_f32_16x16x32_f16 v[40:43], v[118:121], v[110:113], v[40:43]
	ds_read_b128 v[118:121], v22 offset:53248
	v_mfma_f32_16x16x32_f16 v[70:73], v[122:125], v[90:93], v[70:73]
	ds_read_b128 v[90:93], v23 offset:16384
	v_mfma_f32_16x16x32_f16 v[48:51], v[122:125], v[110:113], v[48:51]
	ds_read_b128 v[110:113], v23 offset:18432
	s_waitcnt lgkmcnt(1)
	v_mfma_f32_16x16x32_f16 v[36:39], v[62:65], v[90:93], v[36:39]
	ds_read_b128 v[122:125], v22 offset:55296
	s_waitcnt lgkmcnt(1)
	v_mfma_f32_16x16x32_f16 v[66:69], v[62:65], v[110:113], v[66:69]
	s_waitcnt vmcnt(1)
	ds_write_b128 v17, v[166:169] offset:32768
	v_mfma_f32_16x16x32_f16 v[44:47], v[74:77], v[90:93], v[44:47]
	s_waitcnt vmcnt(0)
	ds_write_b128 v18, v[190:193] offset:32768
	v_mfma_f32_16x16x32_f16 v[78:81], v[74:77], v[110:113], v[78:81]
	v_mfma_f32_16x16x32_f16 v[82:85], v[118:121], v[90:93], v[82:85]
	v_mfma_f32_16x16x32_f16 v[86:89], v[118:121], v[110:113], v[86:89]
	s_waitcnt lgkmcnt(2)
	v_mfma_f32_16x16x32_f16 v[28:31], v[122:125], v[90:93], v[28:31]
	ds_read_b128 v[90:93], v23 offset:20480
	v_mfma_f32_16x16x32_f16 v[32:35], v[122:125], v[110:113], v[32:35]
	ds_read_b128 v[110:113], v23 offset:22528
	s_waitcnt lgkmcnt(1)
	v_mfma_f32_16x16x32_f16 v[98:101], v[62:65], v[90:93], v[98:101]
	s_waitcnt lgkmcnt(0)
	v_mfma_f32_16x16x32_f16 v[52:55], v[62:65], v[110:113], v[52:55]
	global_load_dwordx4 v[62:65], v[0:1], off offset:1664
	v_mfma_f32_16x16x32_f16 v[102:105], v[74:77], v[90:93], v[102:105]
	v_mfma_f32_16x16x32_f16 v[24:27], v[74:77], v[110:113], v[24:27]
	v_mfma_f32_16x16x32_f16 v[114:117], v[118:121], v[90:93], v[114:117]
	v_mfma_f32_16x16x32_f16 v[40:43], v[118:121], v[110:113], v[40:43]
	v_mfma_f32_16x16x32_f16 v[70:73], v[122:125], v[90:93], v[70:73]
	global_load_dwordx4 v[90:93], v[2:3], off offset:1664
	global_load_dwordx4 v[126:129], v[4:5], off offset:1664
	global_load_dwordx4 v[130:133], v[6:7], off offset:1664
	global_load_dwordx4 v[74:77], v[8:9], off offset:1664
	global_load_dwordx4 v[138:141], v[10:11], off offset:1664
	global_load_dwordx4 v[142:145], v[12:13], off offset:1664
	global_load_dwordx4 v[154:157], v[14:15], off offset:1664
	s_waitcnt lgkmcnt(0)
	s_barrier
	v_mfma_f32_16x16x32_f16 v[48:51], v[122:125], v[110:113], v[48:51]
	ds_read_b128 v[58:61], v16 offset:32768
	ds_read_b128 v[106:109], v21
	s_waitcnt lgkmcnt(0)
	v_mfma_f32_16x16x32_f16 v[36:39], v[58:61], v[106:109], v[36:39]
	ds_read_b128 v[94:97], v16 offset:34816
	ds_read_b128 v[110:113], v21 offset:2048
	s_waitcnt lgkmcnt(0)
	v_mfma_f32_16x16x32_f16 v[66:69], v[58:61], v[110:113], v[66:69]
	ds_read_b128 v[118:121], v16 offset:36864
	v_mfma_f32_16x16x32_f16 v[44:47], v[94:97], v[106:109], v[44:47]
	ds_read_b128 v[122:125], v16 offset:38912
	v_mfma_f32_16x16x32_f16 v[78:81], v[94:97], v[110:113], v[78:81]
	s_waitcnt vmcnt(7)
	ds_write_b128 v19, v[62:65] offset:16384
	s_waitcnt lgkmcnt(2)
	v_mfma_f32_16x16x32_f16 v[82:85], v[118:121], v[106:109], v[82:85]
	s_waitcnt vmcnt(6)
	ds_write_b128 v20, v[90:93] offset:16384
	v_mfma_f32_16x16x32_f16 v[86:89], v[118:121], v[110:113], v[86:89]
	s_waitcnt vmcnt(5)
	ds_write_b128 v17, v[126:129] offset:16384
	s_waitcnt lgkmcnt(3)
	v_mfma_f32_16x16x32_f16 v[28:31], v[122:125], v[106:109], v[28:31]
	ds_read_b128 v[106:109], v21 offset:4096
	v_mfma_f32_16x16x32_f16 v[32:35], v[122:125], v[110:113], v[32:35]
	ds_read_b128 v[110:113], v21 offset:6144
	s_waitcnt lgkmcnt(1)
	v_mfma_f32_16x16x32_f16 v[98:101], v[58:61], v[106:109], v[98:101]
	s_waitcnt vmcnt(4)
	ds_write_b128 v18, v[130:133] offset:16384
	s_waitcnt lgkmcnt(1)
	v_mfma_f32_16x16x32_f16 v[52:55], v[58:61], v[110:113], v[52:55]
	ds_read_b128 v[58:61], v22 offset:32768
	v_mfma_f32_16x16x32_f16 v[102:105], v[94:97], v[106:109], v[102:105]
	s_waitcnt vmcnt(3)
; #define GL_LOAD(s_, kt_) if (VAR != 1) { a##s_##0 = GL_A(0, kt_); a##s_##1 = GL_A(1, kt_); a##s_##2 = GL_A(2, kt_); a##s_##3 = GL_A(3, kt_); b##s_##0 = GL_B(0, kt_); b##s_##1 = GL_B(1, kt_); b##s_##2 = GL_B(2, kt_); b##s_##3 = GL_B(3, kt_); }
; #define LDS_STORE(s_, buf_) if (VAR != 2) { LDS_ST1(sA, 0, buf_, a##s_##0) LDS_ST1(sA, 1, buf_, a##s_##1) LDS_ST1(sA, 2, buf_, a##s_##2) LDS_ST1(sA, 3, buf_, a##s_##3) LDS_ST1(sB, 0, buf_, b##s_##0) LDS_ST1(sB, 1, buf_, b##s_##1) LDS_ST1(sB, 2, buf_, b##s_##2) LDS_ST1(sB, 3, buf_, b##s_##3) }
;     ...
;   GL_LOAD(0, 0)
;   GL_LOAD(1, 1)
;   LDS_STORE(0, 0)
;   if (VAR != 4) __syncthreads();
; #pragma unroll
;   for (int kt = 0; kt < nk; kt += 2) {
;     if (kt + 2 < nk) { GL_LOAD(0, kt + 2) }
;     MMA_TILE(0)
;     LDS_STORE(1, 1)
;     if (VAR != 4) __syncthreads();
;     if (kt + 3 < nk) { GL_LOAD(1, kt + 3) }
;     MMA_TILE(1)
;     if (kt + 2 < nk) { LDS_STORE(0, 0) }
;     if (VAR != 4) __syncthreads();
	ds_write_b128 v19, v[74:77] offset:49152
	v_mfma_f32_16x16x32_f16 v[24:27], v[94:97], v[110:113], v[24:27]
	ds_read_b128 v[94:97], v22 offset:34816
	v_mfma_f32_16x16x32_f16 v[114:117], v[118:121], v[106:109], v[114:117]
	s_waitcnt vmcnt(2)
	ds_write_b128 v20, v[138:141] offset:49152
	v_mfma_f32_16x16x32_f16 v[40:43], v[118:121], v[110:113], v[40:43]
	ds_read_b128 v[118:121], v22 offset:36864
	v_mfma_f32_16x16x32_f16 v[70:73], v[122:125], v[106:109], v[70:73]
	ds_read_b128 v[106:109], v23
	v_mfma_f32_16x16x32_f16 v[48:51], v[122:125], v[110:113], v[48:51]
	ds_read_b128 v[110:113], v23 offset:2048
	s_waitcnt lgkmcnt(1)
	v_mfma_f32_16x16x32_f16 v[36:39], v[58:61], v[106:109], v[36:39]
	ds_read_b128 v[122:125], v22 offset:38912
	s_waitcnt lgkmcnt(1)
	v_mfma_f32_16x16x32_f16 v[66:69], v[58:61], v[110:113], v[66:69]
	s_waitcnt vmcnt(1)
	ds_write_b128 v17, v[142:145] offset:49152
	v_mfma_f32_16x16x32_f16 v[44:47], v[94:97], v[106:109], v[44:47]
	s_waitcnt vmcnt(0)
	ds_write_b128 v18, v[154:157] offset:49152
	v_mfma_f32_16x16x32_f16 v[78:81], v[94:97], v[110:113], v[78:81]
	v_mfma_f32_16x16x32_f16 v[82:85], v[118:121], v[106:109], v[82:85]
	v_mfma_f32_16x16x32_f16 v[86:89], v[118:121], v[110:113], v[86:89]
	s_waitcnt lgkmcnt(2)
	v_mfma_f32_16x16x32_f16 v[28:31], v[122:125], v[106:109], v[28:31]
	ds_read_b128 v[106:109], v23 offset:4096
	v_mfma_f32_16x16x32_f16 v[32:35], v[122:125], v[110:113], v[32:35]
	ds_read_b128 v[110:113], v23 offset:6144
	s_waitcnt lgkmcnt(1)
	v_mfma_f32_16x16x32_f16 v[98:101], v[58:61], v[106:109], v[98:101]
	s_waitcnt lgkmcnt(0)
	v_mfma_f32_16x16x32_f16 v[52:55], v[58:61], v[110:113], v[52:55]
	global_load_dwordx4 v[58:61], v[0:1], off offset:1792
	v_mfma_f32_16x16x32_f16 v[102:105], v[94:97], v[106:109], v[102:105]
	v_mfma_f32_16x16x32_f16 v[24:27], v[94:97], v[110:113], v[24:27]
	v_mfma_f32_16x16x32_f16 v[114:117], v[118:121], v[106:109], v[114:117]
	v_mfma_f32_16x16x32_f16 v[40:43], v[118:121], v[110:113], v[40:43]
	v_mfma_f32_16x16x32_f16 v[70:73], v[122:125], v[106:109], v[70:73]
	global_load_dwordx4 v[106:109], v[2:3], off offset:1792
	global_load_dwordx4 v[134:137], v[4:5], off offset:1792
	global_load_dwordx4 v[158:161], v[6:7], off offset:1792
	global_load_dwordx4 v[94:97], v[8:9], off offset:1792
	global_load_dwordx4 v[162:165], v[10:11], off offset:1792
	global_load_dwordx4 v[166:169], v[12:13], off offset:1792
	global_load_dwordx4 v[190:193], v[14:15], off offset:1792
	s_waitcnt lgkmcnt(0)
	s_barrier
	v_mfma_f32_16x16x32_f16 v[48:51], v[122:125], v[110:113], v[48:51]
	ds_read_b128 v[62:65], v16 offset:49152
	ds_read_b128 v[90:93], v21 offset:16384
	s_waitcnt lgkmcnt(0)
	v_mfma_f32_16x16x32_f16 v[36:39], v[62:65], v[90:93], v[36:39]
	ds_read_b128 v[74:77], v16 offset:51200
	ds_read_b128 v[110:113], v21 offset:18432
	s_waitcnt lgkmcnt(0)
	v_mfma_f32_16x16x32_f16 v[66:69], v[62:65], v[110:113], v[66:69]
	ds_read_b128 v[118:121], v16 offset:53248
	v_mfma_f32_16x16x32_f16 v[44:47], v[74:77], v[90:93], v[44:47]
	ds_read_b128 v[122:125], v16 offset:55296
	v_mfma_f32_16x16x32_f16 v[78:81], v[74:77], v[110:113], v[78:81]
	v_or_b32_e32 v130, s11, v56
	s_waitcnt lgkmcnt(1)
	v_mfma_f32_16x16x32_f16 v[82:85], v[118:121], v[90:93], v[82:85]
	v_lshrrev_b32_e32 v150, 4, v130
	v_mfma_f32_16x16x32_f16 v[86:89], v[118:121], v[110:113], v[86:89]
	s_waitcnt vmcnt(7)
	ds_write_b128 v19, v[58:61]
	s_waitcnt lgkmcnt(1)
	v_mfma_f32_16x16x32_f16 v[28:31], v[122:125], v[90:93], v[28:31]
	ds_read_b128 v[90:93], v21 offset:20480
	v_mfma_f32_16x16x32_f16 v[32:35], v[122:125], v[110:113], v[32:35]
	ds_read_b128 v[110:113], v21 offset:22528
	s_waitcnt lgkmcnt(1)
	v_mfma_f32_16x16x32_f16 v[98:101], v[62:65], v[90:93], v[98:101]
	s_waitcnt vmcnt(6)
	ds_write_b128 v20, v[106:109]
	s_waitcnt lgkmcnt(1)
	v_mfma_f32_16x16x32_f16 v[52:55], v[62:65], v[110:113], v[52:55]
	ds_read_b128 v[62:65], v22 offset:49152
	v_mfma_f32_16x16x32_f16 v[102:105], v[74:77], v[90:93], v[102:105]
	s_waitcnt vmcnt(5)
	ds_write_b128 v17, v[134:137]
	v_mfma_f32_16x16x32_f16 v[24:27], v[74:77], v[110:113], v[24:27]
	ds_read_b128 v[74:77], v22 offset:51200
	v_mfma_f32_16x16x32_f16 v[114:117], v[118:121], v[90:93], v[114:117]
	s_waitcnt vmcnt(4)
	ds_write_b128 v18, v[158:161]
	v_mfma_f32_16x16x32_f16 v[40:43], v[118:121], v[110:113], v[40:43]
	ds_read_b128 v[118:121], v22 offset:53248
	v_mfma_f32_16x16x32_f16 v[70:73], v[122:125], v[90:93], v[70:73]
	ds_read_b128 v[90:93], v23 offset:16384
	v_mfma_f32_16x16x32_f16 v[48:51], v[122:125], v[110:113], v[48:51]
	ds_read_b128 v[110:113], v23 offset:18432
	s_waitcnt lgkmcnt(1)
	v_mfma_f32_16x16x32_f16 v[36:39], v[62:65], v[90:93], v[36:39]
	ds_read_b128 v[122:125], v22 offset:55296
	s_waitcnt lgkmcnt(1)
	v_mfma_f32_16x16x32_f16 v[66:69], v[62:65], v[110:113], v[66:69]
	s_waitcnt vmcnt(3)
	ds_write_b128 v19, v[94:97] offset:32768
	v_mfma_f32_16x16x32_f16 v[44:47], v[74:77], v[90:93], v[44:47]
	s_waitcnt vmcnt(2)
	ds_write_b128 v20, v[162:165] offset:32768
	v_mfma_f32_16x16x32_f16 v[78:81], v[74:77], v[110:113], v[78:81]
	s_waitcnt vmcnt(1)
	ds_write_b128 v17, v[166:169] offset:32768
	v_mfma_f32_16x16x32_f16 v[82:85], v[118:121], v[90:93], v[82:85]
	s_waitcnt vmcnt(0)
	ds_write_b128 v18, v[190:193] offset:32768
	v_mfma_f32_16x16x32_f16 v[86:89], v[118:121], v[110:113], v[86:89]
	s_waitcnt lgkmcnt(4)
	v_mfma_f32_16x16x32_f16 v[28:31], v[122:125], v[90:93], v[28:31]
	ds_read_b128 v[90:93], v23 offset:20480
	v_mfma_f32_16x16x32_f16 v[32:35], v[122:125], v[110:113], v[32:35]
	ds_read_b128 v[110:113], v23 offset:22528
	s_waitcnt lgkmcnt(1)
	v_mfma_f32_16x16x32_f16 v[98:101], v[62:65], v[90:93], v[98:101]
	s_waitcnt lgkmcnt(0)
	v_mfma_f32_16x16x32_f16 v[52:55], v[62:65], v[110:113], v[52:55]
	global_load_dwordx4 v[62:65], v[0:1], off offset:1920
	global_load_dwordx4 v[0:3], v[2:3], off offset:1920
	v_mfma_f32_16x16x32_f16 v[102:105], v[74:77], v[90:93], v[102:105]
	v_mfma_f32_16x16x32_f16 v[24:27], v[74:77], v[110:113], v[24:27]
	v_mfma_f32_16x16x32_f16 v[114:117], v[118:121], v[90:93], v[114:117]
	v_mfma_f32_16x16x32_f16 v[40:43], v[118:121], v[110:113], v[40:43]
	v_mfma_f32_16x16x32_f16 v[70:73], v[122:125], v[90:93], v[70:73]
	global_load_dwordx4 v[90:93], v[4:5], off offset:1920
	global_load_dwordx4 v[4:7], v[6:7], off offset:1920
	global_load_dwordx4 v[74:77], v[8:9], off offset:1920
	global_load_dwordx4 v[8:11], v[10:11], off offset:1920
	global_load_dwordx4 v[126:129], v[12:13], off offset:1920
	global_load_dwordx4 v[12:15], v[14:15], off offset:1920
	s_waitcnt lgkmcnt(0)
	s_barrier
; #define GL_LOAD(s_, kt_) if (VAR != 1) { a##s_##0 = GL_A(0, kt_); a##s_##1 = GL_A(1, kt_); a##s_##2 = GL_A(2, kt_); a##s_##3 = GL_A(3, kt_); b##s_##0 = GL_B(0, kt_); b##s_##1 = GL_B(1, kt_); b##s_##2 = GL_B(2, kt_); b##s_##3 = GL_B(3, kt_); }
; #define LDS_STORE(s_, buf_) if (VAR != 2) { LDS_ST1(sA, 0, buf_, a##s_##0) LDS_ST1(sA, 1, buf_, a##s_##1) LDS_ST1(sA, 2, buf_, a##s_##2) LDS_ST1(sA, 3, buf_, a##s_##3) LDS_ST1(sB, 0, buf_, b##s_##0) LDS_ST1(sB, 1, buf_, b##s_##1) LDS_ST1(sB, 2, buf_, b##s_##2) LDS_ST1(sB, 3, buf_, b##s_##3) }
;     ...
;   for (int kt = 0; kt < nk; kt += 2) {
;     if (kt + 2 < nk) { GL_LOAD(0, kt + 2) }
;     MMA_TILE(0)
;     LDS_STORE(1, 1)
;     if (VAR != 4) __syncthreads();
;     if (kt + 3 < nk) { GL_LOAD(1, kt + 3) }
;     MMA_TILE(1)
;     if (kt + 2 < nk) { LDS_STORE(0, 0) }
;     if (VAR != 4) __syncthreads();
;   }
	ds_read_b128 v[58:61], v16 offset:32768
	v_mfma_f32_16x16x32_f16 v[48:51], v[122:125], v[110:113], v[48:51]
	ds_read_b128 v[94:97], v16 offset:34816
	ds_read_b128 v[106:109], v21
	ds_read_b128 v[110:113], v21 offset:2048
	ds_read_b128 v[118:121], v16 offset:36864
	ds_read_b128 v[122:125], v16 offset:38912
	s_waitcnt lgkmcnt(3)
	v_mfma_f32_16x16x32_f16 v[36:39], v[58:61], v[106:109], v[36:39]
	v_mfma_f32_16x16x32_f16 v[44:47], v[94:97], v[106:109], v[44:47]
	s_waitcnt lgkmcnt(1)
	v_mfma_f32_16x16x32_f16 v[82:85], v[118:121], v[106:109], v[82:85]
	s_waitcnt lgkmcnt(0)
	v_mfma_f32_16x16x32_f16 v[28:31], v[122:125], v[106:109], v[28:31]
	v_mfma_f32_16x16x32_f16 v[66:69], v[58:61], v[110:113], v[66:69]
	v_mfma_f32_16x16x32_f16 v[78:81], v[94:97], v[110:113], v[78:81]
	v_mfma_f32_16x16x32_f16 v[86:89], v[118:121], v[110:113], v[86:89]
	v_mfma_f32_16x16x32_f16 v[32:35], v[122:125], v[110:113], v[32:35]
	ds_read_b128 v[106:109], v21 offset:4096
	ds_read_b128 v[110:113], v21 offset:6144
	s_waitcnt lgkmcnt(1)
	v_mfma_f32_16x16x32_f16 v[98:101], v[58:61], v[106:109], v[98:101]
	v_mfma_f32_16x16x32_f16 v[102:105], v[94:97], v[106:109], v[102:105]
	v_mfma_f32_16x16x32_f16 v[114:117], v[118:121], v[106:109], v[114:117]
	v_mfma_f32_16x16x32_f16 v[70:73], v[122:125], v[106:109], v[70:73]
	s_waitcnt lgkmcnt(0)
	v_mfma_f32_16x16x32_f16 v[52:55], v[58:61], v[110:113], v[52:55]
	ds_read_b128 v[58:61], v22 offset:32768
	v_mfma_f32_16x16x32_f16 v[24:27], v[94:97], v[110:113], v[24:27]
	v_mfma_f32_16x16x32_f16 v[40:43], v[118:121], v[110:113], v[40:43]
	v_mfma_f32_16x16x32_f16 v[48:51], v[122:125], v[110:113], v[48:51]
	ds_read_b128 v[94:97], v22 offset:34816
	ds_read_b128 v[106:109], v23
	ds_read_b128 v[110:113], v23 offset:2048
	ds_read_b128 v[118:121], v22 offset:36864
	ds_read_b128 v[122:125], v22 offset:38912
	s_waitcnt lgkmcnt(3)
	v_mfma_f32_16x16x32_f16 v[36:39], v[58:61], v[106:109], v[36:39]
	v_mfma_f32_16x16x32_f16 v[44:47], v[94:97], v[106:109], v[44:47]
	s_waitcnt lgkmcnt(1)
	v_mfma_f32_16x16x32_f16 v[82:85], v[118:121], v[106:109], v[82:85]
	s_waitcnt lgkmcnt(0)
	v_mfma_f32_16x16x32_f16 v[28:31], v[122:125], v[106:109], v[28:31]
	v_mfma_f32_16x16x32_f16 v[66:69], v[58:61], v[110:113], v[66:69]
	v_mfma_f32_16x16x32_f16 v[78:81], v[94:97], v[110:113], v[78:81]
	v_mfma_f32_16x16x32_f16 v[86:89], v[118:121], v[110:113], v[86:89]
	v_mfma_f32_16x16x32_f16 v[32:35], v[122:125], v[110:113], v[32:35]
	ds_read_b128 v[106:109], v23 offset:4096
	ds_read_b128 v[110:113], v23 offset:6144
	s_waitcnt vmcnt(7)
	ds_write_b128 v19, v[62:65] offset:16384
	s_waitcnt vmcnt(6)
	ds_write_b128 v20, v[0:3] offset:16384
	s_waitcnt vmcnt(5)
	ds_write_b128 v17, v[90:93] offset:16384
	s_waitcnt vmcnt(4)
	ds_write_b128 v18, v[4:7] offset:16384
	s_waitcnt vmcnt(3)
	ds_write_b128 v19, v[74:77] offset:49152
	s_waitcnt vmcnt(2)
	ds_write_b128 v20, v[8:11] offset:49152
	s_waitcnt lgkmcnt(7)
	v_mfma_f32_16x16x32_f16 v[98:101], v[58:61], v[106:109], v[98:101]
	s_waitcnt vmcnt(1)
	ds_write_b128 v17, v[126:129] offset:49152
	s_waitcnt vmcnt(0)
	ds_write_b128 v18, v[12:15] offset:49152
	s_waitcnt lgkmcnt(0)
	s_barrier
	v_mfma_f32_16x16x32_f16 v[52:55], v[58:61], v[110:113], v[52:55]
	ds_read_b128 v[8:11], v16 offset:49152
	v_mfma_f32_16x16x32_f16 v[0:3], v[94:97], v[110:113], v[24:27]
	v_mfma_f32_16x16x32_f16 v[4:7], v[118:121], v[110:113], v[40:43]
	v_mfma_f32_16x16x32_f16 v[12:15], v[122:125], v[110:113], v[48:51]
	s_nop 0
	ds_read_b128 v[24:27], v16 offset:51200
	ds_read_b128 v[40:43], v21 offset:16384
	ds_read_b128 v[48:51], v21 offset:18432
	ds_read_b128 v[58:61], v16 offset:53248
	ds_read_b128 v[16:19], v16 offset:55296
	v_mfma_f32_16x16x32_f16 v[102:105], v[94:97], v[106:109], v[102:105]
	v_mfma_f32_16x16x32_f16 v[114:117], v[118:121], v[106:109], v[114:117]
	v_mfma_f32_16x16x32_f16 v[70:73], v[122:125], v[106:109], v[70:73]
	s_waitcnt lgkmcnt(3)
	v_mfma_f32_16x16x32_f16 v[36:39], v[8:11], v[40:43], v[36:39]
	v_mfma_f32_16x16x32_f16 v[44:47], v[24:27], v[40:43], v[44:47]
	s_waitcnt lgkmcnt(1)
	v_mfma_f32_16x16x32_f16 v[62:65], v[58:61], v[40:43], v[82:85]
	ds_read_b128 v[74:77], v21 offset:20480
	s_nop 1
	ds_read_b128 v[82:85], v21 offset:22528
	s_waitcnt lgkmcnt(2)
	v_mfma_f32_16x16x32_f16 v[28:31], v[16:19], v[40:43], v[28:31]
	ds_read_b128 v[40:43], v23 offset:16384
	ds_read_b128 v[90:93], v23 offset:18432
	ds_read_b128 v[94:97], v22 offset:49152
	ds_read_b128 v[106:109], v22 offset:51200
	ds_read_b128 v[110:113], v23 offset:20480
	ds_read_b128 v[118:121], v23 offset:22528
	ds_read_b128 v[122:125], v22 offset:53248
	ds_read_b128 v[126:129], v22 offset:55296
	s_waitcnt lgkmcnt(0)
	v_mfma_f32_16x16x32_f16 v[20:23], v[24:27], v[48:51], v[78:81]
	s_barrier
; DI int TIDX() { int t = threadIdx.x; asm volatile("" : "+v"(t)); return t; }
; DI unsigned pack2(float lo, float hi) { f2_t v = {lo, hi}; h2_t b = __builtin_convertvector(v, h2_t); return __builtin_bit_cast(unsigned, b); }
; DI void epi_residual(const f32x4 (&v)[4][4], int row0, int col0, const float* xsrc, float* x, bf16_t* xb, float* ssq_out, bool write_xb, bool write_ssq) {
;   const int lane = TIDX() & 63, lr = lane & 15, g = lane >> 4;
; #pragma unroll
;   for (int mt = 0; mt < 4; ++mt) {
;     const int row = row0 + mt * 16 + lr;
;     float ss = 0.f;
; #pragma unroll
;     for (int nt = 0; nt < 4; ++nt) {
;       const int col = col0 + nt * 16 + 4 * g;
;       float4* px = (float4*)(x + (size_t)row * DM + col);
;       float4 o = *(const float4*)(xsrc + (size_t)row * DM + col);
;       o.x += v[mt][nt][0]; o.y += v[mt][nt][1]; o.z += v[mt][nt][2]; o.w += v[mt][nt][3];
;       *px = o;
;       ss += (o.x * o.x + o.y * o.y) + (o.z * o.z + o.w * o.w);
;       if (write_xb) *(uint2*)(xb + (size_t)row * DM + col) = make_uint2(pack2(o.x, o.y), pack2(o.z, o.w));
;     }
;     if (write_ssq) {
;       ss += __shfl_xor(ss, 16); ss += __shfl_xor(ss, 32);
;       if (g == 0) ssq_out[(size_t)row * 16 + (col0 >> 6)] = ss;
;     }
;   }
; }
	s_setprio 0
	v_mfma_f32_16x16x32_f16 v[78:81], v[58:61], v[48:51], v[86:89]
	s_nop 2
	v_add_u32_e32 v86, s6, v57
	v_mov_b32_e32 v87, v148
	v_mfma_f32_16x16x32_f16 v[66:69], v[8:11], v[48:51], v[66:69]
	v_readlane_b32 s6, v254, 41
	v_bfe_u32 v134, v87, 4, 2
	v_mfma_f32_16x16x32_f16 v[32:35], v[16:19], v[48:51], v[32:35]
	v_and_or_b32 v50, v87, 15, v86
	v_ashrrev_i32_e32 v51, 31, v50
	v_lshl_or_b32 v135, v134, 2, v130
	v_readlane_b32 s7, v254, 42
	v_lshlrev_b64 v[130:131], 12, v[50:51]
	v_lshl_add_u64 v[132:133], s[4:5], 0, v[130:131]
	v_lshl_add_u64 v[48:49], s[6:7], 0, v[150:151]
	v_lshlrev_b32_e32 v150, 2, v135
	v_lshl_add_u64 v[132:133], v[132:133], 0, v[150:151]
	v_mfma_f32_16x16x32_f16 v[86:89], v[8:11], v[74:77], v[98:101]
	v_readlane_b32 s6, v254, 43
	v_readlane_b32 s7, v254, 44
	v_cmp_eq_u32_e32 vcc, 0, v134
	v_mfma_f32_16x16x32_f16 v[98:101], v[24:27], v[74:77], v[102:105]
	v_mfma_f32_16x16x32_f16 v[102:105], v[58:61], v[74:77], v[114:117]
	s_nop 2
	global_load_dwordx4 v[114:117], v[132:133], off
	v_mfma_f32_16x16x32_f16 v[36:39], v[94:97], v[40:43], v[36:39]
	v_mfma_f32_16x16x32_f16 v[70:73], v[16:19], v[74:77], v[70:73]
	v_lshlrev_b64 v[76:77], 11, v[50:51]
	v_lshl_add_u64 v[74:75], s[12:13], 0, v[130:131]
	v_lshl_add_u64 v[76:77], s[6:7], 0, v[76:77]
	v_mfma_f32_16x16x32_f16 v[8:11], v[8:11], v[82:85], v[52:55]
	v_lshl_add_u64 v[74:75], v[74:75], 0, v[150:151]
	s_waitcnt vmcnt(0)
	s_nop 0
	v_pk_add_f32 v[36:37], v[36:37], v[114:115]
	v_pk_add_f32 v[38:39], v[38:39], v[116:117]
	v_lshlrev_b32_e32 v52, 1, v135
	v_mov_b32_e32 v53, v151
	v_cvt_pk_f16_f32 v54, v36, v37
	v_cvt_pk_f16_f32 v55, v38, v39
	v_lshl_add_u64 v[76:77], v[76:77], 0, v[52:53]
	global_store_dwordx4 v[74:75], v[36:39], off
	global_store_dwordx2 v[76:77], v[54:55], off
	v_mfma_f32_16x16x32_f16 v[0:3], v[24:27], v[82:85], v[0:3]
	v_mul_f32_e64 v54, v36, v36
	v_mul_f32_e64 v55, v37, v37
	v_mfma_f32_16x16x32_f16 v[24:27], v[106:109], v[40:43], v[44:47]
	s_nop 2
	global_load_dwordx4 v[44:47], v[132:133], off offset:64
	v_mfma_f32_16x16x32_f16 v[4:7], v[58:61], v[82:85], v[4:7]
	s_waitcnt vmcnt(0)
	s_nop 1
	v_pk_add_f32 v[24:25], v[24:25], v[44:45]
	v_pk_add_f32 v[26:27], v[26:27], v[46:47]
	v_cvt_pk_f16_f32 v44, v24, v25
	v_cvt_pk_f16_f32 v45, v26, v27
	global_store_dwordx4 v[74:75], v[24:27], off offset:64
	global_store_dwordx2 v[76:77], v[44:45], off offset:32
	v_mfma_f32_16x16x32_f16 v[58:61], v[16:19], v[82:85], v[12:15]
	s_nop 2
	global_load_dwordx4 v[12:15], v[132:133], off offset:128
	v_mfma_f32_16x16x32_f16 v[16:19], v[122:125], v[40:43], v[62:65]
	v_mfma_f32_16x16x32_f16 v[44:47], v[94:97], v[90:93], v[66:69]
	s_nop 2
	v_mul_f32_e64 v66, v26, v26
	v_mul_f32_e64 v67, v27, v27
	v_mfma_f32_16x16x32_f16 v[32:35], v[126:129], v[90:93], v[32:35]
	s_waitcnt vmcnt(0)
	v_pk_add_f32 v[12:13], v[16:17], v[12:13]
	v_pk_add_f32 v[14:15], v[18:19], v[14:15]
	v_mfma_f32_16x16x32_f16 v[16:19], v[126:129], v[40:43], v[28:31]
	global_store_dwordx4 v[74:75], v[12:15], off offset:128
	s_nop 1
	v_cvt_pk_f16_f32 v28, v12, v13
	v_cvt_pk_f16_f32 v29, v14, v15
	global_store_dwordx2 v[76:77], v[28:29], off offset:64
	global_load_dwordx4 v[28:31], v[132:133], off offset:192
	v_mfma_f32_16x16x32_f16 v[40:43], v[106:109], v[90:93], v[20:23]
	v_mul_f32_e64 v12, v12, v12
	v_mul_f32_e64 v13, v13, v13
	v_pk_mul_f32 v[14:15], v[14:15], v[14:15]
	v_add_f32_e32 v12, v12, v13
	v_pk_mul_f32 v[20:21], v[38:39], v[38:39]
	v_pk_mul_f32 v[22:23], v[24:25], v[24:25]
	v_add_f32_e32 v14, v14, v15
	v_add_f32_e32 v12, v12, v14
	v_mfma_f32_16x16x32_f16 v[36:39], v[122:125], v[90:93], v[78:81]
	s_waitcnt vmcnt(0)
	v_pk_add_f32 v[62:63], v[16:17], v[28:29]
	v_add_f32_e32 v16, v20, v21
	v_add_f32_e32 v17, v54, v55
	v_pk_add_f32 v[64:65], v[18:19], v[30:31]
	v_add_f32_e32 v16, v17, v16
	v_add_f32_e32 v17, v66, v67
	v_add_f32_e32 v18, v22, v23
	v_add_f32_e32 v17, v18, v17
	global_store_dwordx4 v[74:75], v[62:65], off offset:192
	v_pk_mul_f32 v[68:69], v[62:63], v[62:63]
	v_pk_mul_f32 v[74:75], v[64:65], v[64:65]
	v_add_f32_e32 v54, v16, v17
	v_add_f32_e32 v54, v54, v12
	v_mfma_f32_16x16x32_f16 v[12:15], v[94:97], v[118:121], v[8:11]
	s_nop 2
	v_add_f32_e32 v8, v74, v75
	v_add_f32_e32 v9, v68, v69
	v_add_f32_e32 v55, v9, v8
	v_mfma_f32_16x16x32_f16 v[8:11], v[106:109], v[118:121], v[0:3]
	s_nop 2
	v_add_f32_e32 v2, v54, v55
	ds_bpermute_b32 v3, v189, v2
	v_cvt_pk_f16_f32 v0, v62, v63
	v_cvt_pk_f16_f32 v1, v64, v65
	v_mfma_f32_16x16x32_f16 v[28:31], v[94:97], v[110:113], v[86:89]
	global_store_dwordx2 v[76:77], v[0:1], off offset:96
	s_waitcnt lgkmcnt(0)
	v_add_f32_e32 v54, v2, v3
	ds_bpermute_b32 v55, v188, v54
	v_mfma_f32_16x16x32_f16 v[24:27], v[106:109], v[110:113], v[98:101]
	v_mfma_f32_16x16x32_f16 v[20:23], v[122:125], v[110:113], v[102:105]
	v_mfma_f32_16x16x32_f16 v[16:19], v[126:129], v[110:113], v[70:73]
	v_mfma_f32_16x16x32_f16 v[4:7], v[122:125], v[118:121], v[4:7]
	v_mfma_f32_16x16x32_f16 v[0:3], v[126:129], v[118:121], v[58:61]
	s_and_saveexec_b64 s[6:7], vcc
	s_cbranch_execz .LBB0_1252
	s_waitcnt lgkmcnt(0)
	v_add_f32_e32 v58, v54, v55
	v_lshlrev_b64 v[54:55], 6, v[50:51]
	v_lshl_add_u64 v[54:55], v[48:49], 0, v[54:55]
	global_store_dword v[54:55], v58, off

; DI void load_rstd(float (&rs)[4], const float* ssq, int row0, int lr) {
; #pragma unroll
;   for (int mt = 0; mt < 4; ++mt) {
;     const float4* q = (const float4*)(ssq + (size_t)(row0 + mt * 16 + lr) * 16);
;     const float4 a = q[0], b = q[1], c = q[2], d = q[3];
;     const float s = ((a.x + a.y) + (a.z + a.w)) + ((b.x + b.y) + (b.z + b.w)) + ((c.x + c.y) + (c.z + c.w)) + ((d.x + d.y) + (d.z + d.w));
;     rs[mt] = rsqrtf(s * (1.0f / 1024.0f) + EPS);
;   }
; }
.LBB0_1313:
	s_ashr_i32 s4, s2, 9
	s_lshr_b32 s1, s4, 30
	s_add_i32 s1, s4, s1
	s_ashr_i32 s5, s1, 2
	s_lshl_b32 s1, s5, 6
	s_and_b32 s6, s12, 56
	s_lshl_b32 s5, s5, 5
	s_lshl_b32 s4, s4, 3
	s_or_b32 s1, s1, s6
	s_bfe_u32 s6, s2, 0x30003
	s_sub_i32 s4, s4, s5
	s_bfe_u32 s5, s2, 0x30006
	s_or_b32 s1, s1, s6
	s_or_b32 s4, s4, s5
	s_cmpk_lt_i32 s1, 0x80
	s_cselect_b64 s[6:7], -1, 0
	s_cmp_lt_i32 s4, 32
	s_cselect_b64 s[8:9], -1, 0
	s_and_b64 s[6:7], s[6:7], s[8:9]
	s_andn2_b64 vcc, exec, s[6:7]
	s_cbranch_vccnz .LBB0_1312
	s_lshl_b32 s8, s1, 7
	v_add_u32_e32 v102, s8, v125
	v_ashrrev_i32_e32 v103, 31, v102
	v_readlane_b32 s14, v254, 41
	v_lshlrev_b64 v[0:1], 6, v[102:103]
	v_readlane_b32 s15, v254, 42
	v_or_b32_e32 v98, 16, v102
	v_ashrrev_i32_e32 v99, 31, v98
	v_lshl_add_u64 v[12:13], s[14:15], 0, v[0:1]
	global_load_dwordx4 v[0:3], v[12:13], off offset:32
	global_load_dwordx4 v[4:7], v[12:13], off offset:16
	global_load_dwordx4 v[8:11], v[12:13], off
	s_nop 0
	global_load_dwordx4 v[12:15], v[12:13], off offset:48
	s_lshl_b32 s6, s4, 7
	s_mov_b32 s4, 0x358637bd
	s_mov_b32 s16, 0x3a800000
	s_mov_b32 s1, 0x800000
	v_or_b32_e32 v106, 32, v102
	v_ashrrev_i32_e32 v107, 31, v106
	v_or_b32_e32 v104, 48, v102
	v_ashrrev_i32_e32 v105, 31, v104
	s_ashr_i32 s9, s8, 31
	s_waitcnt vmcnt(7)
	v_mov_b32_e32 v72, v148
	v_or_b32_e32 v100, s6, v124
	s_waitcnt vmcnt(2)
	v_mov_b32_e32 v18, v5
	s_waitcnt vmcnt(1)
	v_mov_b32_e32 v16, v9
	v_mov_b32_e32 v17, v10
	v_mov_b32_e32 v19, v6
	v_mov_b32_e32 v9, v11
	v_mov_b32_e32 v5, v7
	v_mov_b32_e32 v6, v1
	v_pk_add_f32 v[8:9], v[16:17], v[8:9]
	v_pk_add_f32 v[4:5], v[18:19], v[4:5]
	v_pk_add_f32 v[0:1], v[0:1], v[6:7]
	v_mov_b32_e32 v6, v3
	v_pk_add_f32 v[8:9], v[8:9], v[8:9] op_sel:[0,1] op_sel_hi:[1,0]
	v_pk_add_f32 v[4:5], v[4:5], v[4:5] op_sel:[0,1] op_sel_hi:[1,0]
	v_pk_add_f32 v[2:3], v[2:3], v[6:7]
	s_waitcnt vmcnt(0)
	v_mov_b32_e32 v9, v12
	v_mov_b32_e32 v5, v13
	v_mov_b32_e32 v1, v14
	v_mov_b32_e32 v3, v15
	v_pk_add_f32 v[4:5], v[8:9], v[4:5]
	v_pk_add_f32 v[0:1], v[0:1], v[2:3]
	s_nop 0
	v_pk_add_f32 v[16:17], v[4:5], v[0:1]
	v_lshlrev_b64 v[0:1], 6, v[98:99]
	v_lshl_add_u64 v[12:13], s[14:15], 0, v[0:1]
	global_load_dwordx4 v[0:3], v[12:13], off offset:32
	global_load_dwordx4 v[4:7], v[12:13], off offset:16
	global_load_dwordx4 v[8:11], v[12:13], off
	s_nop 0
	global_load_dwordx4 v[12:15], v[12:13], off offset:48
	s_waitcnt vmcnt(2)
	v_mov_b32_e32 v20, v5
	s_waitcnt vmcnt(1)
	v_mov_b32_e32 v18, v9
	v_mov_b32_e32 v19, v10
	v_mov_b32_e32 v21, v6
	v_mov_b32_e32 v9, v11
	v_mov_b32_e32 v5, v7
	v_mov_b32_e32 v6, v1
	v_pk_add_f32 v[8:9], v[18:19], v[8:9]
	v_pk_add_f32 v[4:5], v[20:21], v[4:5]
	v_pk_add_f32 v[0:1], v[0:1], v[6:7]
	v_mov_b32_e32 v6, v3
	v_pk_add_f32 v[8:9], v[8:9], v[8:9] op_sel:[0,1] op_sel_hi:[1,0]
	v_pk_add_f32 v[4:5], v[4:5], v[4:5] op_sel:[0,1] op_sel_hi:[1,0]
	v_pk_add_f32 v[2:3], v[2:3], v[6:7]
	s_waitcnt vmcnt(0)
	v_mov_b32_e32 v9, v12
	v_mov_b32_e32 v5, v13
	v_mov_b32_e32 v1, v14
	v_mov_b32_e32 v3, v15
	v_pk_add_f32 v[4:5], v[8:9], v[4:5]
	v_pk_add_f32 v[0:1], v[0:1], v[2:3]
	v_mov_b32_e32 v3, v16
	v_pk_add_f32 v[0:1], v[4:5], v[0:1]
	s_nop 0
	v_mov_b32_e32 v2, v0
	v_mov_b32_e32 v16, v1
	v_pk_add_f32 v[2:3], v[2:3], v[16:17]
	v_mov_b64_e32 v[0:1], s[4:5]
	v_pk_fma_f32 v[2:3], v[2:3], s[16:17], v[0:1] op_sel_hi:[1,0,0]
	s_nop 0
	v_mul_f32_e32 v4, 0x4b800000, v3
	v_cmp_gt_f32_e64 s[4:5], s1, v3
	v_cmp_gt_f32_e32 vcc, s1, v2
	s_nop 0
	v_cndmask_b32_e64 v3, v3, v4, s[4:5]
	v_rsq_f32_e32 v3, v3
	s_nop 0
	v_mul_f32_e32 v4, 0x45800000, v3
	v_cndmask_b32_e64 v128, v3, v4, s[4:5]
	v_mul_f32_e32 v3, 0x4b800000, v2
	v_cndmask_b32_e32 v2, v2, v3, vcc
	v_rsq_f32_e32 v2, v2
	s_nop 0
	v_mul_f32_e32 v3, 0x45800000, v2
	v_cndmask_b32_e32 v126, v2, v3, vcc
	v_lshlrev_b64 v[2:3], 6, v[106:107]
	v_lshl_add_u64 v[14:15], s[14:15], 0, v[2:3]
	global_load_dwordx4 v[2:5], v[14:15], off offset:32
	global_load_dwordx4 v[6:9], v[14:15], off offset:16
	global_load_dwordx4 v[10:13], v[14:15], off
	s_nop 0
	global_load_dwordx4 v[14:17], v[14:15], off offset:48
	s_waitcnt vmcnt(2)
	v_mov_b32_e32 v20, v7
	s_waitcnt vmcnt(1)
	v_mov_b32_e32 v18, v11
	v_mov_b32_e32 v19, v12
	v_mov_b32_e32 v21, v8
	v_mov_b32_e32 v11, v13
	v_mov_b32_e32 v7, v9
	v_mov_b32_e32 v8, v3
	v_pk_add_f32 v[10:11], v[18:19], v[10:11]
	v_pk_add_f32 v[6:7], v[20:21], v[6:7]
	v_pk_add_f32 v[2:3], v[2:3], v[8:9]
	v_mov_b32_e32 v8, v5
	v_pk_add_f32 v[10:11], v[10:11], v[10:11] op_sel:[0,1] op_sel_hi:[1,0]
	v_pk_add_f32 v[6:7], v[6:7], v[6:7] op_sel:[0,1] op_sel_hi:[1,0]
	v_pk_add_f32 v[4:5], v[4:5], v[8:9]
	s_waitcnt vmcnt(0)
	v_mov_b32_e32 v11, v14
	v_mov_b32_e32 v7, v15
	v_mov_b32_e32 v3, v16
	v_mov_b32_e32 v5, v17
	v_pk_add_f32 v[6:7], v[10:11], v[6:7]
	v_pk_add_f32 v[2:3], v[2:3], v[4:5]
	s_nop 0
	v_pk_add_f32 v[18:19], v[6:7], v[2:3]
	v_lshlrev_b64 v[2:3], 6, v[104:105]
	v_lshl_add_u64 v[14:15], s[14:15], 0, v[2:3]
	global_load_dwordx4 v[2:5], v[14:15], off offset:32
	global_load_dwordx4 v[6:9], v[14:15], off offset:16
	global_load_dwordx4 v[10:13], v[14:15], off
	s_nop 0
	global_load_dwordx4 v[14:17], v[14:15], off offset:48
	s_waitcnt vmcnt(2)
	v_mov_b32_e32 v22, v7
	s_waitcnt vmcnt(1)
	v_mov_b32_e32 v20, v11
	v_mov_b32_e32 v21, v12
	v_mov_b32_e32 v23, v8
	v_mov_b32_e32 v11, v13
	v_mov_b32_e32 v7, v9
	v_mov_b32_e32 v8, v3
	v_pk_add_f32 v[10:11], v[20:21], v[10:11]
	v_pk_add_f32 v[6:7], v[22:23], v[6:7]
	v_pk_add_f32 v[2:3], v[2:3], v[8:9]
	v_mov_b32_e32 v8, v5
	v_pk_add_f32 v[10:11], v[10:11], v[10:11] op_sel:[0,1] op_sel_hi:[1,0]
	v_pk_add_f32 v[6:7], v[6:7], v[6:7] op_sel:[0,1] op_sel_hi:[1,0]
	v_pk_add_f32 v[4:5], v[4:5], v[8:9]
	s_waitcnt vmcnt(0)
; DI int TIDX() { int t = threadIdx.x; asm volatile("" : "+v"(t)); return t; }
; #define GL_LOAD(s_, kt_) if (VAR != 1) { a##s_##0 = GL_A(0, kt_); a##s_##1 = GL_A(1, kt_); a##s_##2 = GL_A(2, kt_); a##s_##3 = GL_A(3, kt_); b##s_##0 = GL_B(0, kt_); b##s_##1 = GL_B(1, kt_); b##s_##2 = GL_B(2, kt_); b##s_##3 = GL_B(3, kt_); }
; #define LDS_STORE(s_, buf_) if (VAR != 2) { LDS_ST1(sA, 0, buf_, a##s_##0) LDS_ST1(sA, 1, buf_, a##s_##1) LDS_ST1(sA, 2, buf_, a##s_##2) LDS_ST1(sA, 3, buf_, a##s_##3) LDS_ST1(sB, 0, buf_, b##s_##0) LDS_ST1(sB, 1, buf_, b##s_##1) LDS_ST1(sB, 2, buf_, b##s_##2) LDS_ST1(sB, 3, buf_, b##s_##3) }
;   const int tid = TIDX(), lane = tid & 63, wid = tid >> 6, wm = wid >> 1, wn = wid & 1, lr = lane & 15, g = lane >> 4;
;   char* sA = smem; char* sB = smem + 2 * LTILE;
;   uint4 a00 = {}, a01 = {}, a02 = {}, a03 = {}, b00 = {}, b01 = {}, b02 = {}, b03 = {}, a10 = {}, a11 = {}, a12 = {}, a13 = {}, b10 = {}, b11 = {}, b12 = {}, b13 = {};
;   constexpr int nk = NK;
;   const int sw0 = (g ^ ((lr >> 1) & 7)) << 4, sw1 = sw0 ^ 64;
;   const int r0 = tid >> 3, kc = tid & 7, kcs = kc ^ ((r0 >> 1) & 7);
;     ...
;   GL_LOAD(0, 0)
;   GL_LOAD(1, 1)
;   LDS_STORE(0, 0)
;   if (VAR != 4) __syncthreads();
; DI void load_rstd(float (&rs)[4], const float* ssq, int row0, int lr) {
; #pragma unroll
;   for (int mt = 0; mt < 4; ++mt) {
;     const float4* q = (const float4*)(ssq + (size_t)(row0 + mt * 16 + lr) * 16);
;     const float4 a = q[0], b = q[1], c = q[2], d = q[3];
;     const float s = ((a.x + a.y) + (a.z + a.w)) + ((b.x + b.y) + (b.z + b.w)) + ((c.x + c.y) + (c.z + c.w)) + ((d.x + d.y) + (d.z + d.w));
;     rs[mt] = rsqrtf(s * (1.0f / 1024.0f) + EPS);
;   }
; }
	v_mov_b32_e32 v11, v14
	v_mov_b32_e32 v7, v15
	v_mov_b32_e32 v3, v16
	v_mov_b32_e32 v5, v17
	v_pk_add_f32 v[6:7], v[10:11], v[6:7]
	v_pk_add_f32 v[2:3], v[2:3], v[4:5]
	v_mov_b32_e32 v5, v18
	v_pk_add_f32 v[2:3], v[6:7], v[2:3]
	v_ashrrev_i32_e32 v64, 3, v72
	v_mov_b32_e32 v4, v2
	v_mov_b32_e32 v18, v3
	v_pk_add_f32 v[2:3], v[4:5], v[18:19]
	v_ashrrev_i32_e32 v65, 31, v64
	v_pk_fma_f32 v[0:1], v[2:3], s[16:17], v[0:1] op_sel_hi:[1,0,0]
	v_and_b32_e32 v75, 48, v72
	v_mul_f32_e32 v2, 0x4b800000, v1
	v_cmp_gt_f32_e64 s[4:5], s1, v1
	v_cmp_gt_f32_e32 vcc, s1, v0
	v_lshlrev_b64 v[16:17], 11, v[64:65]
	v_cndmask_b32_e64 v1, v1, v2, s[4:5]
	v_rsq_f32_e32 v1, v1
	v_lshlrev_b32_e32 v65, 4, v72
	v_and_b32_e32 v150, 0x70, v65
	v_add_u32_e32 v66, 32, v64
	v_mul_f32_e32 v2, 0x45800000, v1
	v_cndmask_b32_e64 v129, v1, v2, s[4:5]
	v_mul_f32_e32 v1, 0x4b800000, v0
	v_cndmask_b32_e32 v0, v0, v1, vcc
	v_rsq_f32_e32 v0, v0
	s_lshl_b64 s[4:5], s[8:9], 11
	v_readlane_b32 s8, v254, 43
	v_readlane_b32 s9, v254, 44
	v_mul_f32_e32 v1, 0x45800000, v0
	s_add_u32 s4, s8, s4
	v_cndmask_b32_e32 v127, v0, v1, vcc
	s_addc_u32 s5, s9, s5
	v_lshlrev_b32_e32 v0, 3, v72
	s_ashr_i32 s7, s6, 31
	v_and_b32_e32 v74, 0x70, v0
	v_bitop3_b32 v134, v0, v75, s23 bitop3:0x6c
	v_lshl_add_u64 v[0:1], s[4:5], 0, v[16:17]
	v_add_u32_e32 v68, 64, v64
	v_add_u32_e32 v70, 0x60, v64
	s_lshl_b64 s[6:7], s[6:7], 11
	v_lshl_add_u64 v[108:109], v[0:1], 0, v[150:151]
	v_ashrrev_i32_e32 v67, 31, v66
	v_ashrrev_i32_e32 v69, 31, v68
	v_ashrrev_i32_e32 v71, 31, v70
	s_add_u32 s6, s10, s6
	v_lshlrev_b64 v[20:21], 11, v[66:67]
	v_lshlrev_b64 v[24:25], 11, v[68:69]
	v_lshlrev_b64 v[28:29], 11, v[70:71]
	s_addc_u32 s7, s11, s7
	v_lshl_add_u64 v[4:5], s[4:5], 0, v[20:21]
	v_lshl_add_u64 v[8:9], s[4:5], 0, v[24:25]
	v_lshl_add_u64 v[12:13], s[4:5], 0, v[28:29]
	v_lshl_add_u64 v[110:111], v[4:5], 0, v[150:151]
	v_lshl_add_u64 v[112:113], v[8:9], 0, v[150:151]
	v_lshl_add_u64 v[114:115], v[12:13], 0, v[150:151]
	v_lshl_add_u64 v[16:17], s[6:7], 0, v[16:17]
	v_lshl_add_u64 v[116:117], v[16:17], 0, v[150:151]
	v_lshl_add_u64 v[20:21], s[6:7], 0, v[20:21]
	v_lshl_add_u64 v[118:119], v[20:21], 0, v[150:151]
	v_lshl_add_u64 v[24:25], s[6:7], 0, v[24:25]
	v_lshl_add_u64 v[120:121], v[24:25], 0, v[150:151]
	v_lshl_add_u64 v[28:29], s[6:7], 0, v[28:29]
	v_lshl_add_u64 v[122:123], v[28:29], 0, v[150:151]
	v_bitop3_b32 v65, v65, s23, v72 bitop3:0x48
	v_lshl_or_b32 v101, v64, 7, v65
	v_and_b32_e32 v73, 15, v72
	v_lshl_or_b32 v131, v66, 7, v65
	v_lshl_or_b32 v132, v68, 7, v65
	v_lshl_or_b32 v130, v70, 7, v65
	v_xor_b32_e32 v135, 64, v134
	v_and_b32_e32 v30, 7, v148
	v_bfe_u32 v31, v148, 4, 3
	v_xor_b32_e32 v31, v31, v30
	v_sub_u32_e32 v31, v31, v30
	v_lshlrev_b32_e32 v30, 4, v31
	v_ashrrev_i32_e32 v31, 31, v30
	v_mov_b32_e32 v0, v101
	v_and_b32_e32 v0, 0xffffff80, v0
	s_nop 0
	v_readfirstlane_b32 s101, v0
	v_lshl_add_u64 v[0:1], v[108:109], 0, v[30:31]
	s_mov_b32 m0, s101
	s_nop 0
	global_load_lds_dwordx4 v[0:1], off
	v_lshrrev_b32_e32 v0, 1, v72
	v_and_or_b32 v0, v0, s24, v73
	v_lshlrev_b32_e32 v137, 7, v0
	v_lshlrev_b32_e32 v0, 7, v72
	v_and_b32_e32 v146, 0x2780, v0
	v_bitop3_b32 v133, v137, v74, v75 bitop3:0xf6
	v_or_b32_e32 v136, v146, v134
	v_bitop3_b32 v134, v137, v134, 64 bitop3:0xf6
	v_or_b32_e32 v135, v146, v135
	v_mov_b32_e32 v4, v131
	v_and_b32_e32 v4, 0xffffff80, v4
	s_nop 0
	v_readfirstlane_b32 s101, v4
	v_lshl_add_u64 v[4:5], v[110:111], 0, v[30:31]
	s_mov_b32 m0, s101
	s_nop 0
	global_load_lds_dwordx4 v[4:5], off
	v_mov_b32_e32 v8, v132
	v_and_b32_e32 v8, 0xffffff80, v8
	s_nop 0
	v_readfirstlane_b32 s101, v8
	v_lshl_add_u64 v[8:9], v[112:113], 0, v[30:31]
	s_mov_b32 m0, s101
	s_nop 0
	global_load_lds_dwordx4 v[8:9], off
	v_mov_b32_e32 v12, v130
	v_and_b32_e32 v12, 0xffffff80, v12
	s_nop 0
	v_readfirstlane_b32 s101, v12
	v_lshl_add_u64 v[12:13], v[114:115], 0, v[30:31]
	s_mov_b32 m0, s101
	s_nop 0
	global_load_lds_dwordx4 v[12:13], off
	v_add_u32_e32 v16, 0x8000, v101
	v_and_b32_e32 v16, 0xffffff80, v16
	s_nop 0
	v_readfirstlane_b32 s101, v16
	v_lshl_add_u64 v[16:17], v[116:117], 0, v[30:31]
	s_mov_b32 m0, s101
	s_nop 0
	global_load_lds_dwordx4 v[16:17], off
	v_add_u32_e32 v20, 0x8000, v131
	v_and_b32_e32 v20, 0xffffff80, v20
	s_nop 0
	v_readfirstlane_b32 s101, v20
	v_lshl_add_u64 v[20:21], v[118:119], 0, v[30:31]
	s_mov_b32 m0, s101
	s_nop 0
	global_load_lds_dwordx4 v[20:21], off
	v_add_u32_e32 v24, 0x8000, v132
	v_and_b32_e32 v24, 0xffffff80, v24
	s_nop 0
	v_readfirstlane_b32 s101, v24
	v_lshl_add_u64 v[24:25], v[120:121], 0, v[30:31]
	s_mov_b32 m0, s101
	s_nop 0
	global_load_lds_dwordx4 v[24:25], off
	v_add_u32_e32 v28, 0x8000, v130
	v_and_b32_e32 v28, 0xffffff80, v28
	s_nop 0
	v_readfirstlane_b32 s101, v28
	v_lshl_add_u64 v[28:29], v[122:123], 0, v[30:31]
	s_mov_b32 m0, s101
	s_nop 0
	global_load_lds_dwordx4 v[28:29], off
	s_waitcnt lgkmcnt(0)
	s_waitcnt vmcnt(0)
	s_barrier
; #define GL_LOAD(s_, kt_) if (VAR != 1) { a##s_##0 = GL_A(0, kt_); a##s_##1 = GL_A(1, kt_); a##s_##2 = GL_A(2, kt_); a##s_##3 = GL_A(3, kt_); b##s_##0 = GL_B(0, kt_); b##s_##1 = GL_B(1, kt_); b##s_##2 = GL_B(2, kt_); b##s_##3 = GL_B(3, kt_); }
; #define LDS_STORE(s_, buf_) if (VAR != 2) { LDS_ST1(sA, 0, buf_, a##s_##0) LDS_ST1(sA, 1, buf_, a##s_##1) LDS_ST1(sA, 2, buf_, a##s_##2) LDS_ST1(sA, 3, buf_, a##s_##3) LDS_ST1(sB, 0, buf_, b##s_##0) LDS_ST1(sB, 1, buf_, b##s_##1) LDS_ST1(sB, 2, buf_, b##s_##2) LDS_ST1(sB, 3, buf_, b##s_##3) }
;     ...
;   GL_LOAD(0, 0)
;   GL_LOAD(1, 1)
;   LDS_STORE(0, 0)
;   if (VAR != 4) __syncthreads();
; #pragma unroll
;   for (int kt = 0; kt < nk; kt += 2) {
;     if (kt + 2 < nk) { GL_LOAD(0, kt + 2) }
;     MMA_TILE(0)
;     LDS_STORE(1, 1)
;     if (VAR != 4) __syncthreads();
;     if (kt + 3 < nk) { GL_LOAD(1, kt + 3) }
;     MMA_TILE(1)
;     if (kt + 2 < nk) { LDS_STORE(0, 0) }
;     if (VAR != 4) __syncthreads();
;   }
	s_setprio 1
	ds_read_b128 v[64:67], v133
	ds_read_b128 v[68:71], v136 offset:32768
	s_waitcnt lgkmcnt(0)
	v_mfma_f32_16x16x32_f16 v[138:141], v[68:71], v[64:67], 0
	ds_read_b128 v[72:75], v133 offset:2048
	ds_read_b128 v[76:79], v136 offset:34816
	s_waitcnt lgkmcnt(1)
	v_mfma_f32_16x16x32_f16 v[158:161], v[68:71], v[72:75], 0
	ds_read_b128 v[80:83], v133 offset:4096
	ds_read_b128 v[84:87], v136 offset:36864
	s_waitcnt lgkmcnt(2)
	v_mfma_f32_16x16x32_f16 v[142:145], v[76:79], v[64:67], 0
	ds_read_b128 v[88:91], v133 offset:6144
	ds_read_b128 v[92:95], v136 offset:38912
	v_mfma_f32_16x16x32_f16 v[162:165], v[76:79], v[72:75], 0
	ds_read_b128 v[202:205], v135 offset:32768
	ds_read_b128 v[206:209], v134 offset:2048
	s_waitcnt lgkmcnt(5)
	v_mfma_f32_16x16x32_f16 v[190:193], v[68:71], v[80:83], 0
	ds_read_b128 v[210:213], v135 offset:34816
	ds_read_b128 v[220:223], v134 offset:4096
	s_waitcnt lgkmcnt(5)
	v_mfma_f32_16x16x32_f16 v[68:71], v[68:71], v[88:91], 0
	ds_read_b128 v[224:227], v135 offset:36864
	v_mfma_f32_16x16x32_f16 v[194:197], v[76:79], v[80:83], 0
	ds_read_b128 v[228:231], v134 offset:6144
	v_mfma_f32_16x16x32_f16 v[76:79], v[76:79], v[88:91], 0
	ds_read_b128 v[232:235], v135 offset:38912
	v_mfma_f32_16x16x32_f16 v[154:157], v[84:87], v[64:67], 0
	v_mfma_f32_16x16x32_f16 v[166:169], v[84:87], v[72:75], 0
	s_waitcnt lgkmcnt(7)
	v_mfma_f32_16x16x32_f16 v[64:67], v[92:95], v[64:67], 0
	v_mfma_f32_16x16x32_f16 v[72:75], v[92:95], v[72:75], 0
	v_mfma_f32_16x16x32_f16 v[198:201], v[84:87], v[80:83], 0
	v_and_b32_e32 v62, 7, v148
	v_bfe_u32 v63, v148, 4, 3
	v_xor_b32_e32 v63, v63, v62
	v_sub_u32_e32 v63, v63, v62
	v_lshlrev_b32_e32 v62, 4, v63
	v_add_u32_e32 v62, 0x80, v62
	v_ashrrev_i32_e32 v63, 31, v62
	v_mfma_f32_16x16x32_f16 v[84:87], v[84:87], v[88:91], 0
	v_add_u32_e32 v32, 0x4000, v101
	v_and_b32_e32 v32, 0xffffff80, v32
	s_nop 0
	v_readfirstlane_b32 s101, v32
	v_lshl_add_u64 v[32:33], v[108:109], 0, v[62:63]
	s_mov_b32 m0, s101
	s_nop 0
	global_load_lds_dwordx4 v[32:33], off
	v_add_u32_e32 v36, 0x4000, v131
	v_and_b32_e32 v36, 0xffffff80, v36
	s_nop 0
	v_readfirstlane_b32 s101, v36
	v_lshl_add_u64 v[36:37], v[110:111], 0, v[62:63]
	s_mov_b32 m0, s101
	s_nop 0
	global_load_lds_dwordx4 v[36:37], off
	v_mfma_f32_16x16x32_f16 v[80:83], v[92:95], v[80:83], 0
	v_add_u32_e32 v40, 0x4000, v132
	v_and_b32_e32 v40, 0xffffff80, v40
	s_nop 0
	v_readfirstlane_b32 s101, v40
	v_lshl_add_u64 v[40:41], v[112:113], 0, v[62:63]
	s_mov_b32 m0, s101
	s_nop 0
	global_load_lds_dwordx4 v[40:41], off
	v_add_u32_e32 v44, 0x4000, v130
	v_and_b32_e32 v44, 0xffffff80, v44
	s_nop 0
	v_readfirstlane_b32 s101, v44
	v_lshl_add_u64 v[44:45], v[114:115], 0, v[62:63]
	s_mov_b32 m0, s101
	s_nop 0
	global_load_lds_dwordx4 v[44:45], off
	v_mfma_f32_16x16x32_f16 v[88:91], v[92:95], v[88:91], 0
	ds_read_b128 v[92:95], v134
	v_add_u32_e32 v48, 0xc000, v101
	v_and_b32_e32 v48, 0xffffff80, v48
	s_nop 0
	v_readfirstlane_b32 s101, v48
	v_lshl_add_u64 v[48:49], v[116:117], 0, v[62:63]
	s_mov_b32 m0, s101
	s_nop 0
	global_load_lds_dwordx4 v[48:49], off
	v_add_u32_e32 v52, 0xc000, v131
	v_and_b32_e32 v52, 0xffffff80, v52
	s_nop 0
	v_readfirstlane_b32 s101, v52
	v_lshl_add_u64 v[52:53], v[118:119], 0, v[62:63]
	s_mov_b32 m0, s101
	s_nop 0
	global_load_lds_dwordx4 v[52:53], off
	v_add_u32_e32 v56, 0xc000, v132
	v_and_b32_e32 v56, 0xffffff80, v56
	s_nop 0
	v_readfirstlane_b32 s101, v56
	v_lshl_add_u64 v[56:57], v[120:121], 0, v[62:63]
	s_mov_b32 m0, s101
	s_nop 0
	global_load_lds_dwordx4 v[56:57], off
	v_add_u32_e32 v60, 0xc000, v130
	v_and_b32_e32 v60, 0xffffff80, v60
	s_nop 0
	v_readfirstlane_b32 s101, v60
	v_lshl_add_u64 v[60:61], v[122:123], 0, v[62:63]
	s_mov_b32 m0, s101
	s_nop 0
	global_load_lds_dwordx4 v[60:61], off
	s_waitcnt vmcnt(0) lgkmcnt(0)
	s_barrier
	v_mfma_f32_16x16x32_f16 v[138:141], v[202:205], v[92:95], v[138:141]
	v_mfma_f32_16x16x32_f16 v[142:145], v[210:213], v[92:95], v[142:145]
	v_mfma_f32_16x16x32_f16 v[154:157], v[224:227], v[92:95], v[154:157]
	v_mfma_f32_16x16x32_f16 v[64:67], v[232:235], v[92:95], v[64:67]
	v_mfma_f32_16x16x32_f16 v[92:95], v[202:205], v[206:209], v[158:161]
	v_mfma_f32_16x16x32_f16 v[158:161], v[210:213], v[206:209], v[162:165]
	v_mfma_f32_16x16x32_f16 v[162:165], v[224:227], v[206:209], v[166:169]
	v_mfma_f32_16x16x32_f16 v[166:169], v[202:205], v[220:223], v[190:193]
	v_mfma_f32_16x16x32_f16 v[68:71], v[202:205], v[228:231], v[68:71]
	ds_read_b128 v[202:205], v136 offset:49152
	v_mfma_f32_16x16x32_f16 v[190:193], v[210:213], v[220:223], v[194:197]
	v_mfma_f32_16x16x32_f16 v[76:79], v[210:213], v[228:231], v[76:79]
	ds_read_b128 v[210:213], v136 offset:51200
	v_and_b32_e32 v30, 7, v148
	v_bfe_u32 v31, v148, 4, 3
	v_xor_b32_e32 v31, v31, v30
	v_sub_u32_e32 v31, v31, v30
	v_lshlrev_b32_e32 v30, 4, v31
	v_add_u32_e32 v30, 0x100, v30
	v_ashrrev_i32_e32 v31, 31, v30
	v_mfma_f32_16x16x32_f16 v[72:75], v[232:235], v[206:209], v[72:75]
	ds_read_b128 v[206:209], v133 offset:18432
	v_mfma_f32_16x16x32_f16 v[194:197], v[224:227], v[220:223], v[198:201]
	s_nop 2
	ds_read_b128 v[198:201], v133 offset:16384
	v_mfma_f32_16x16x32_f16 v[84:87], v[224:227], v[228:231], v[84:87]
	ds_read_b128 v[224:227], v136 offset:53248
	v_mfma_f32_16x16x32_f16 v[80:83], v[232:235], v[220:223], v[80:83]
	ds_read_b128 v[220:223], v133 offset:20480
	v_mfma_f32_16x16x32_f16 v[88:91], v[232:235], v[228:231], v[88:91]
	ds_read_b128 v[228:231], v133 offset:22528
	s_waitcnt lgkmcnt(3)
; #define GL_LOAD(s_, kt_) if (VAR != 1) { a##s_##0 = GL_A(0, kt_); a##s_##1 = GL_A(1, kt_); a##s_##2 = GL_A(2, kt_); a##s_##3 = GL_A(3, kt_); b##s_##0 = GL_B(0, kt_); b##s_##1 = GL_B(1, kt_); b##s_##2 = GL_B(2, kt_); b##s_##3 = GL_B(3, kt_); }
; #define LDS_STORE(s_, buf_) if (VAR != 2) { LDS_ST1(sA, 0, buf_, a##s_##0) LDS_ST1(sA, 1, buf_, a##s_##1) LDS_ST1(sA, 2, buf_, a##s_##2) LDS_ST1(sA, 3, buf_, a##s_##3) LDS_ST1(sB, 0, buf_, b##s_##0) LDS_ST1(sB, 1, buf_, b##s_##1) LDS_ST1(sB, 2, buf_, b##s_##2) LDS_ST1(sB, 3, buf_, b##s_##3) }
;     ...
;   GL_LOAD(0, 0)
;   GL_LOAD(1, 1)
;   LDS_STORE(0, 0)
;   if (VAR != 4) __syncthreads();
; #pragma unroll
;   for (int kt = 0; kt < nk; kt += 2) {
;     if (kt + 2 < nk) { GL_LOAD(0, kt + 2) }
;     MMA_TILE(0)
;     LDS_STORE(1, 1)
;     if (VAR != 4) __syncthreads();
;     if (kt + 3 < nk) { GL_LOAD(1, kt + 3) }
;     MMA_TILE(1)
;     if (kt + 2 < nk) { LDS_STORE(0, 0) }
;     if (VAR != 4) __syncthreads();
;   }
	v_mfma_f32_16x16x32_f16 v[138:141], v[202:205], v[198:201], v[138:141]
	ds_read_b128 v[232:235], v136 offset:55296
	v_mfma_f32_16x16x32_f16 v[92:95], v[202:205], v[206:209], v[92:95]
	v_mov_b32_e32 v0, v101
	v_and_b32_e32 v0, 0xffffff80, v0
	s_nop 0
	v_readfirstlane_b32 s101, v0
	v_lshl_add_u64 v[0:1], v[108:109], 0, v[30:31]
	s_mov_b32 m0, s101
	s_nop 0
	global_load_lds_dwordx4 v[0:1], off
	v_mfma_f32_16x16x32_f16 v[142:145], v[210:213], v[198:201], v[142:145]
	v_mov_b32_e32 v4, v131
	v_and_b32_e32 v4, 0xffffff80, v4
	s_nop 0
	v_readfirstlane_b32 s101, v4
	v_lshl_add_u64 v[4:5], v[110:111], 0, v[30:31]
	s_mov_b32 m0, s101
	s_nop 0
	global_load_lds_dwordx4 v[4:5], off
	v_mfma_f32_16x16x32_f16 v[158:161], v[210:213], v[206:209], v[158:161]
	v_mov_b32_e32 v8, v132
	v_and_b32_e32 v8, 0xffffff80, v8
	s_nop 0
	v_readfirstlane_b32 s101, v8
	v_lshl_add_u64 v[8:9], v[112:113], 0, v[30:31]
	s_mov_b32 m0, s101
	s_nop 0
	global_load_lds_dwordx4 v[8:9], off
	s_waitcnt lgkmcnt(2)
	v_mfma_f32_16x16x32_f16 v[166:169], v[202:205], v[220:223], v[166:169]
	v_mov_b32_e32 v12, v130
	v_and_b32_e32 v12, 0xffffff80, v12
	s_nop 0
	v_readfirstlane_b32 s101, v12
	v_lshl_add_u64 v[12:13], v[114:115], 0, v[30:31]
	s_mov_b32 m0, s101
	s_nop 0
	global_load_lds_dwordx4 v[12:13], off
	s_waitcnt lgkmcnt(1)
	v_mfma_f32_16x16x32_f16 v[68:71], v[202:205], v[228:231], v[68:71]
	ds_read_b128 v[202:205], v135 offset:49152
	v_mfma_f32_16x16x32_f16 v[190:193], v[210:213], v[220:223], v[190:193]
	v_add_u32_e32 v16, 0x8000, v101
	v_and_b32_e32 v16, 0xffffff80, v16
	s_nop 0
	v_readfirstlane_b32 s101, v16
	v_lshl_add_u64 v[16:17], v[116:117], 0, v[30:31]
	s_mov_b32 m0, s101
	s_nop 0
	global_load_lds_dwordx4 v[16:17], off
	v_mfma_f32_16x16x32_f16 v[76:79], v[210:213], v[228:231], v[76:79]
	ds_read_b128 v[210:213], v135 offset:51200
	v_mfma_f32_16x16x32_f16 v[154:157], v[224:227], v[198:201], v[154:157]
	v_add_u32_e32 v20, 0x8000, v131
	v_and_b32_e32 v20, 0xffffff80, v20
	s_nop 0
	v_readfirstlane_b32 s101, v20
	v_lshl_add_u64 v[20:21], v[118:119], 0, v[30:31]
	s_mov_b32 m0, s101
	s_nop 0
	global_load_lds_dwordx4 v[20:21], off
	v_mfma_f32_16x16x32_f16 v[162:165], v[224:227], v[206:209], v[162:165]
	v_add_u32_e32 v24, 0x8000, v132
	v_and_b32_e32 v24, 0xffffff80, v24
	s_nop 0
	v_readfirstlane_b32 s101, v24
	v_lshl_add_u64 v[24:25], v[120:121], 0, v[30:31]
	s_mov_b32 m0, s101
	s_nop 0
	global_load_lds_dwordx4 v[24:25], off
	s_waitcnt lgkmcnt(2)
	v_mfma_f32_16x16x32_f16 v[64:67], v[232:235], v[198:201], v[64:67]
	ds_read_b128 v[198:201], v134 offset:16384
	v_mfma_f32_16x16x32_f16 v[72:75], v[232:235], v[206:209], v[72:75]
	ds_read_b128 v[206:209], v134 offset:18432
	v_mfma_f32_16x16x32_f16 v[194:197], v[224:227], v[220:223], v[194:197]
	v_add_u32_e32 v28, 0x8000, v130
	v_and_b32_e32 v28, 0xffffff80, v28
	s_nop 0
	v_readfirstlane_b32 s101, v28
	v_lshl_add_u64 v[28:29], v[122:123], 0, v[30:31]
	s_mov_b32 m0, s101
	s_nop 0
	global_load_lds_dwordx4 v[28:29], off
	v_mfma_f32_16x16x32_f16 v[84:87], v[224:227], v[228:231], v[84:87]
	ds_read_b128 v[224:227], v135 offset:53248
	v_mfma_f32_16x16x32_f16 v[80:83], v[232:235], v[220:223], v[80:83]
	ds_read_b128 v[220:223], v134 offset:20480
	v_mfma_f32_16x16x32_f16 v[88:91], v[232:235], v[228:231], v[88:91]
	ds_read_b128 v[228:231], v134 offset:22528
	ds_read_b128 v[232:235], v135 offset:55296
	s_waitcnt vmcnt(0) lgkmcnt(0)
	s_barrier
	v_mfma_f32_16x16x32_f16 v[138:141], v[202:205], v[198:201], v[138:141]
	v_mfma_f32_16x16x32_f16 v[92:95], v[202:205], v[206:209], v[92:95]
	v_mfma_f32_16x16x32_f16 v[142:145], v[210:213], v[198:201], v[142:145]
	v_mfma_f32_16x16x32_f16 v[158:161], v[210:213], v[206:209], v[158:161]
	v_mfma_f32_16x16x32_f16 v[166:169], v[202:205], v[220:223], v[166:169]
	v_mfma_f32_16x16x32_f16 v[68:71], v[202:205], v[228:231], v[68:71]
	ds_read_b128 v[202:205], v136 offset:32768
	v_mfma_f32_16x16x32_f16 v[190:193], v[210:213], v[220:223], v[190:193]
	v_mfma_f32_16x16x32_f16 v[76:79], v[210:213], v[228:231], v[76:79]
	ds_read_b128 v[210:213], v136 offset:34816
	v_mfma_f32_16x16x32_f16 v[154:157], v[224:227], v[198:201], v[154:157]
	v_mfma_f32_16x16x32_f16 v[162:165], v[224:227], v[206:209], v[162:165]
	v_mfma_f32_16x16x32_f16 v[64:67], v[232:235], v[198:201], v[64:67]
	ds_read_b128 v[198:201], v133
	v_mfma_f32_16x16x32_f16 v[72:75], v[232:235], v[206:209], v[72:75]
	ds_read_b128 v[206:209], v133 offset:2048
	v_mfma_f32_16x16x32_f16 v[194:197], v[224:227], v[220:223], v[194:197]
	v_and_b32_e32 v62, 7, v148
	v_bfe_u32 v63, v148, 4, 3
	v_xor_b32_e32 v63, v63, v62
	v_sub_u32_e32 v63, v63, v62
	v_lshlrev_b32_e32 v62, 4, v63
	v_add_u32_e32 v62, 0x180, v62
	v_ashrrev_i32_e32 v63, 31, v62
	v_mfma_f32_16x16x32_f16 v[84:87], v[224:227], v[228:231], v[84:87]
	ds_read_b128 v[224:227], v136 offset:36864
	v_mfma_f32_16x16x32_f16 v[80:83], v[232:235], v[220:223], v[80:83]
	ds_read_b128 v[220:223], v133 offset:4096
	v_mfma_f32_16x16x32_f16 v[88:91], v[232:235], v[228:231], v[88:91]
	ds_read_b128 v[228:231], v133 offset:6144
	s_waitcnt lgkmcnt(4)
	v_mfma_f32_16x16x32_f16 v[138:141], v[202:205], v[198:201], v[138:141]
	ds_read_b128 v[232:235], v136 offset:38912
	s_waitcnt lgkmcnt(4)
	v_mfma_f32_16x16x32_f16 v[92:95], v[202:205], v[206:209], v[92:95]
	v_add_u32_e32 v32, 0x4000, v101
	v_and_b32_e32 v32, 0xffffff80, v32
	s_nop 0
	v_readfirstlane_b32 s101, v32
	v_lshl_add_u64 v[32:33], v[108:109], 0, v[62:63]
	s_mov_b32 m0, s101
	s_nop 0
	global_load_lds_dwordx4 v[32:33], off
	v_mfma_f32_16x16x32_f16 v[142:145], v[210:213], v[198:201], v[142:145]
	v_add_u32_e32 v36, 0x4000, v131
	v_and_b32_e32 v36, 0xffffff80, v36
	s_nop 0
	v_readfirstlane_b32 s101, v36
	v_lshl_add_u64 v[36:37], v[110:111], 0, v[62:63]
	s_mov_b32 m0, s101
	s_nop 0
	global_load_lds_dwordx4 v[36:37], off
	v_mfma_f32_16x16x32_f16 v[158:161], v[210:213], v[206:209], v[158:161]
	v_add_u32_e32 v40, 0x4000, v132
	v_and_b32_e32 v40, 0xffffff80, v40
	s_nop 0
	v_readfirstlane_b32 s101, v40
	v_lshl_add_u64 v[40:41], v[112:113], 0, v[62:63]
	s_mov_b32 m0, s101
	s_nop 0
	global_load_lds_dwordx4 v[40:41], off
	s_waitcnt lgkmcnt(2)
; #define GL_LOAD(s_, kt_) if (VAR != 1) { a##s_##0 = GL_A(0, kt_); a##s_##1 = GL_A(1, kt_); a##s_##2 = GL_A(2, kt_); a##s_##3 = GL_A(3, kt_); b##s_##0 = GL_B(0, kt_); b##s_##1 = GL_B(1, kt_); b##s_##2 = GL_B(2, kt_); b##s_##3 = GL_B(3, kt_); }
; #define LDS_STORE(s_, buf_) if (VAR != 2) { LDS_ST1(sA, 0, buf_, a##s_##0) LDS_ST1(sA, 1, buf_, a##s_##1) LDS_ST1(sA, 2, buf_, a##s_##2) LDS_ST1(sA, 3, buf_, a##s_##3) LDS_ST1(sB, 0, buf_, b##s_##0) LDS_ST1(sB, 1, buf_, b##s_##1) LDS_ST1(sB, 2, buf_, b##s_##2) LDS_ST1(sB, 3, buf_, b##s_##3) }
;     ...
;   GL_LOAD(0, 0)
;   GL_LOAD(1, 1)
;   LDS_STORE(0, 0)
;   if (VAR != 4) __syncthreads();
; #pragma unroll
;   for (int kt = 0; kt < nk; kt += 2) {
;     if (kt + 2 < nk) { GL_LOAD(0, kt + 2) }
;     MMA_TILE(0)
;     LDS_STORE(1, 1)
;     if (VAR != 4) __syncthreads();
;     if (kt + 3 < nk) { GL_LOAD(1, kt + 3) }
;     MMA_TILE(1)
;     if (kt + 2 < nk) { LDS_STORE(0, 0) }
;     if (VAR != 4) __syncthreads();
;   }
	v_mfma_f32_16x16x32_f16 v[166:169], v[202:205], v[220:223], v[166:169]
	v_add_u32_e32 v44, 0x4000, v130
	v_and_b32_e32 v44, 0xffffff80, v44
	s_nop 0
	v_readfirstlane_b32 s101, v44
	v_lshl_add_u64 v[44:45], v[114:115], 0, v[62:63]
	s_mov_b32 m0, s101
	s_nop 0
	global_load_lds_dwordx4 v[44:45], off
	s_waitcnt lgkmcnt(1)
	v_mfma_f32_16x16x32_f16 v[68:71], v[202:205], v[228:231], v[68:71]
	ds_read_b128 v[202:205], v135 offset:32768
	v_mfma_f32_16x16x32_f16 v[190:193], v[210:213], v[220:223], v[190:193]
	v_add_u32_e32 v48, 0xc000, v101
	v_and_b32_e32 v48, 0xffffff80, v48
	s_nop 0
	v_readfirstlane_b32 s101, v48
	v_lshl_add_u64 v[48:49], v[116:117], 0, v[62:63]
	s_mov_b32 m0, s101
	s_nop 0
	global_load_lds_dwordx4 v[48:49], off
	v_mfma_f32_16x16x32_f16 v[76:79], v[210:213], v[228:231], v[76:79]
	ds_read_b128 v[210:213], v135 offset:34816
	v_mfma_f32_16x16x32_f16 v[154:157], v[224:227], v[198:201], v[154:157]
	v_add_u32_e32 v52, 0xc000, v131
	v_and_b32_e32 v52, 0xffffff80, v52
	s_nop 0
	v_readfirstlane_b32 s101, v52
	v_lshl_add_u64 v[52:53], v[118:119], 0, v[62:63]
	s_mov_b32 m0, s101
	s_nop 0
	global_load_lds_dwordx4 v[52:53], off
	v_mfma_f32_16x16x32_f16 v[162:165], v[224:227], v[206:209], v[162:165]
	v_add_u32_e32 v56, 0xc000, v132
	v_and_b32_e32 v56, 0xffffff80, v56
	s_nop 0
	v_readfirstlane_b32 s101, v56
	v_lshl_add_u64 v[56:57], v[120:121], 0, v[62:63]
	s_mov_b32 m0, s101
	s_nop 0
	global_load_lds_dwordx4 v[56:57], off
	s_waitcnt lgkmcnt(2)
	v_mfma_f32_16x16x32_f16 v[64:67], v[232:235], v[198:201], v[64:67]
	ds_read_b128 v[198:201], v134
	v_mfma_f32_16x16x32_f16 v[72:75], v[232:235], v[206:209], v[72:75]
	ds_read_b128 v[206:209], v134 offset:2048
	v_mfma_f32_16x16x32_f16 v[194:197], v[224:227], v[220:223], v[194:197]
	v_add_u32_e32 v60, 0xc000, v130
	v_and_b32_e32 v60, 0xffffff80, v60
	s_nop 0
	v_readfirstlane_b32 s101, v60
	v_lshl_add_u64 v[60:61], v[122:123], 0, v[62:63]
	s_mov_b32 m0, s101
	s_nop 0
	global_load_lds_dwordx4 v[60:61], off
	v_mfma_f32_16x16x32_f16 v[84:87], v[224:227], v[228:231], v[84:87]
	ds_read_b128 v[224:227], v135 offset:36864
	v_mfma_f32_16x16x32_f16 v[80:83], v[232:235], v[220:223], v[80:83]
	ds_read_b128 v[220:223], v134 offset:4096
	v_mfma_f32_16x16x32_f16 v[88:91], v[232:235], v[228:231], v[88:91]
	ds_read_b128 v[228:231], v134 offset:6144
	ds_read_b128 v[232:235], v135 offset:38912
	s_waitcnt vmcnt(0) lgkmcnt(0)
	s_barrier
	v_mfma_f32_16x16x32_f16 v[138:141], v[202:205], v[198:201], v[138:141]
	v_mfma_f32_16x16x32_f16 v[92:95], v[202:205], v[206:209], v[92:95]
	v_mfma_f32_16x16x32_f16 v[142:145], v[210:213], v[198:201], v[142:145]
	v_mfma_f32_16x16x32_f16 v[158:161], v[210:213], v[206:209], v[158:161]
	v_mfma_f32_16x16x32_f16 v[166:169], v[202:205], v[220:223], v[166:169]
	v_mfma_f32_16x16x32_f16 v[68:71], v[202:205], v[228:231], v[68:71]
	ds_read_b128 v[202:205], v136 offset:49152
	v_mfma_f32_16x16x32_f16 v[190:193], v[210:213], v[220:223], v[190:193]
	v_mfma_f32_16x16x32_f16 v[76:79], v[210:213], v[228:231], v[76:79]
	ds_read_b128 v[210:213], v136 offset:51200
	v_mfma_f32_16x16x32_f16 v[154:157], v[224:227], v[198:201], v[154:157]
	v_mfma_f32_16x16x32_f16 v[162:165], v[224:227], v[206:209], v[162:165]
	v_mfma_f32_16x16x32_f16 v[64:67], v[232:235], v[198:201], v[64:67]
	ds_read_b128 v[198:201], v133 offset:16384
	v_mfma_f32_16x16x32_f16 v[72:75], v[232:235], v[206:209], v[72:75]
	ds_read_b128 v[206:209], v133 offset:18432
	v_mfma_f32_16x16x32_f16 v[194:197], v[224:227], v[220:223], v[194:197]
	v_and_b32_e32 v30, 7, v148
	v_bfe_u32 v31, v148, 4, 3
	v_xor_b32_e32 v31, v31, v30
	v_sub_u32_e32 v31, v31, v30
	v_lshlrev_b32_e32 v30, 4, v31
	v_add_u32_e32 v30, 0x200, v30
	v_ashrrev_i32_e32 v31, 31, v30
	v_mfma_f32_16x16x32_f16 v[84:87], v[224:227], v[228:231], v[84:87]
	ds_read_b128 v[224:227], v136 offset:53248
	v_mfma_f32_16x16x32_f16 v[80:83], v[232:235], v[220:223], v[80:83]
	ds_read_b128 v[220:223], v133 offset:20480
	v_mfma_f32_16x16x32_f16 v[88:91], v[232:235], v[228:231], v[88:91]
	ds_read_b128 v[228:231], v133 offset:22528
	s_waitcnt lgkmcnt(4)
	v_mfma_f32_16x16x32_f16 v[138:141], v[202:205], v[198:201], v[138:141]
	ds_read_b128 v[232:235], v136 offset:55296
	s_waitcnt lgkmcnt(4)
	v_mfma_f32_16x16x32_f16 v[92:95], v[202:205], v[206:209], v[92:95]
	v_mov_b32_e32 v0, v101
	v_and_b32_e32 v0, 0xffffff80, v0
	s_nop 0
	v_readfirstlane_b32 s101, v0
	v_lshl_add_u64 v[0:1], v[108:109], 0, v[30:31]
	s_mov_b32 m0, s101
	s_nop 0
	global_load_lds_dwordx4 v[0:1], off
	v_mfma_f32_16x16x32_f16 v[142:145], v[210:213], v[198:201], v[142:145]
	v_mov_b32_e32 v4, v131
	v_and_b32_e32 v4, 0xffffff80, v4
	s_nop 0
	v_readfirstlane_b32 s101, v4
	v_lshl_add_u64 v[4:5], v[110:111], 0, v[30:31]
	s_mov_b32 m0, s101
	s_nop 0
	global_load_lds_dwordx4 v[4:5], off
	v_mfma_f32_16x16x32_f16 v[158:161], v[210:213], v[206:209], v[158:161]
	v_mov_b32_e32 v8, v132
	v_and_b32_e32 v8, 0xffffff80, v8
	s_nop 0
	v_readfirstlane_b32 s101, v8
	v_lshl_add_u64 v[8:9], v[112:113], 0, v[30:31]
	s_mov_b32 m0, s101
	s_nop 0
	global_load_lds_dwordx4 v[8:9], off
	s_waitcnt lgkmcnt(2)
	v_mfma_f32_16x16x32_f16 v[166:169], v[202:205], v[220:223], v[166:169]
	v_mov_b32_e32 v12, v130
	v_and_b32_e32 v12, 0xffffff80, v12
	s_nop 0
	v_readfirstlane_b32 s101, v12
	v_lshl_add_u64 v[12:13], v[114:115], 0, v[30:31]
	s_mov_b32 m0, s101
	s_nop 0
	global_load_lds_dwordx4 v[12:13], off
	s_waitcnt lgkmcnt(1)
; #define GL_LOAD(s_, kt_) if (VAR != 1) { a##s_##0 = GL_A(0, kt_); a##s_##1 = GL_A(1, kt_); a##s_##2 = GL_A(2, kt_); a##s_##3 = GL_A(3, kt_); b##s_##0 = GL_B(0, kt_); b##s_##1 = GL_B(1, kt_); b##s_##2 = GL_B(2, kt_); b##s_##3 = GL_B(3, kt_); }
; #define LDS_STORE(s_, buf_) if (VAR != 2) { LDS_ST1(sA, 0, buf_, a##s_##0) LDS_ST1(sA, 1, buf_, a##s_##1) LDS_ST1(sA, 2, buf_, a##s_##2) LDS_ST1(sA, 3, buf_, a##s_##3) LDS_ST1(sB, 0, buf_, b##s_##0) LDS_ST1(sB, 1, buf_, b##s_##1) LDS_ST1(sB, 2, buf_, b##s_##2) LDS_ST1(sB, 3, buf_, b##s_##3) }
;     ...
;   GL_LOAD(0, 0)
;   GL_LOAD(1, 1)
;   LDS_STORE(0, 0)
;   if (VAR != 4) __syncthreads();
; #pragma unroll
;   for (int kt = 0; kt < nk; kt += 2) {
;     if (kt + 2 < nk) { GL_LOAD(0, kt + 2) }
;     MMA_TILE(0)
;     LDS_STORE(1, 1)
;     if (VAR != 4) __syncthreads();
;     if (kt + 3 < nk) { GL_LOAD(1, kt + 3) }
;     MMA_TILE(1)
;     if (kt + 2 < nk) { LDS_STORE(0, 0) }
;     if (VAR != 4) __syncthreads();
;   }
	v_mfma_f32_16x16x32_f16 v[68:71], v[202:205], v[228:231], v[68:71]
	ds_read_b128 v[202:205], v135 offset:49152
	v_mfma_f32_16x16x32_f16 v[190:193], v[210:213], v[220:223], v[190:193]
	v_add_u32_e32 v16, 0x8000, v101
	v_and_b32_e32 v16, 0xffffff80, v16
	s_nop 0
	v_readfirstlane_b32 s101, v16
	v_lshl_add_u64 v[16:17], v[116:117], 0, v[30:31]
	s_mov_b32 m0, s101
	s_nop 0
	global_load_lds_dwordx4 v[16:17], off
	v_mfma_f32_16x16x32_f16 v[76:79], v[210:213], v[228:231], v[76:79]
	ds_read_b128 v[210:213], v135 offset:51200
	v_mfma_f32_16x16x32_f16 v[154:157], v[224:227], v[198:201], v[154:157]
	v_add_u32_e32 v20, 0x8000, v131
	v_and_b32_e32 v20, 0xffffff80, v20
	s_nop 0
	v_readfirstlane_b32 s101, v20
	v_lshl_add_u64 v[20:21], v[118:119], 0, v[30:31]
	s_mov_b32 m0, s101
	s_nop 0
	global_load_lds_dwordx4 v[20:21], off
	v_mfma_f32_16x16x32_f16 v[162:165], v[224:227], v[206:209], v[162:165]
	v_add_u32_e32 v24, 0x8000, v132
	v_and_b32_e32 v24, 0xffffff80, v24
	s_nop 0
	v_readfirstlane_b32 s101, v24
	v_lshl_add_u64 v[24:25], v[120:121], 0, v[30:31]
	s_mov_b32 m0, s101
	s_nop 0
	global_load_lds_dwordx4 v[24:25], off
	s_waitcnt lgkmcnt(2)
	v_mfma_f32_16x16x32_f16 v[64:67], v[232:235], v[198:201], v[64:67]
	ds_read_b128 v[198:201], v134 offset:16384
	v_mfma_f32_16x16x32_f16 v[72:75], v[232:235], v[206:209], v[72:75]
	ds_read_b128 v[206:209], v134 offset:18432
	v_mfma_f32_16x16x32_f16 v[194:197], v[224:227], v[220:223], v[194:197]
	v_add_u32_e32 v28, 0x8000, v130
	v_and_b32_e32 v28, 0xffffff80, v28
	s_nop 0
	v_readfirstlane_b32 s101, v28
	v_lshl_add_u64 v[28:29], v[122:123], 0, v[30:31]
	s_mov_b32 m0, s101
	s_nop 0
	global_load_lds_dwordx4 v[28:29], off
	v_mfma_f32_16x16x32_f16 v[84:87], v[224:227], v[228:231], v[84:87]
	ds_read_b128 v[224:227], v135 offset:53248
	v_mfma_f32_16x16x32_f16 v[80:83], v[232:235], v[220:223], v[80:83]
	ds_read_b128 v[220:223], v134 offset:20480
	v_mfma_f32_16x16x32_f16 v[88:91], v[232:235], v[228:231], v[88:91]
	ds_read_b128 v[228:231], v134 offset:22528
	ds_read_b128 v[232:235], v135 offset:55296
	s_waitcnt vmcnt(0) lgkmcnt(0)
	s_barrier
	v_mfma_f32_16x16x32_f16 v[138:141], v[202:205], v[198:201], v[138:141]
	v_mfma_f32_16x16x32_f16 v[92:95], v[202:205], v[206:209], v[92:95]
	v_mfma_f32_16x16x32_f16 v[142:145], v[210:213], v[198:201], v[142:145]
	v_mfma_f32_16x16x32_f16 v[158:161], v[210:213], v[206:209], v[158:161]
	v_mfma_f32_16x16x32_f16 v[166:169], v[202:205], v[220:223], v[166:169]
	v_mfma_f32_16x16x32_f16 v[68:71], v[202:205], v[228:231], v[68:71]
	ds_read_b128 v[202:205], v136 offset:32768
	v_mfma_f32_16x16x32_f16 v[190:193], v[210:213], v[220:223], v[190:193]
	v_mfma_f32_16x16x32_f16 v[76:79], v[210:213], v[228:231], v[76:79]
	ds_read_b128 v[210:213], v136 offset:34816
	v_mfma_f32_16x16x32_f16 v[154:157], v[224:227], v[198:201], v[154:157]
	v_mfma_f32_16x16x32_f16 v[162:165], v[224:227], v[206:209], v[162:165]
	v_mfma_f32_16x16x32_f16 v[64:67], v[232:235], v[198:201], v[64:67]
	ds_read_b128 v[198:201], v133
	v_mfma_f32_16x16x32_f16 v[72:75], v[232:235], v[206:209], v[72:75]
	ds_read_b128 v[206:209], v133 offset:2048
	v_mfma_f32_16x16x32_f16 v[194:197], v[224:227], v[220:223], v[194:197]
	v_and_b32_e32 v62, 7, v148
	v_bfe_u32 v63, v148, 4, 3
	v_xor_b32_e32 v63, v63, v62
	v_sub_u32_e32 v63, v63, v62
	v_lshlrev_b32_e32 v62, 4, v63
	v_add_u32_e32 v62, 0x280, v62
	v_ashrrev_i32_e32 v63, 31, v62
	v_mfma_f32_16x16x32_f16 v[84:87], v[224:227], v[228:231], v[84:87]
	ds_read_b128 v[224:227], v136 offset:36864
	v_mfma_f32_16x16x32_f16 v[80:83], v[232:235], v[220:223], v[80:83]
	ds_read_b128 v[220:223], v133 offset:4096
	v_mfma_f32_16x16x32_f16 v[88:91], v[232:235], v[228:231], v[88:91]
	ds_read_b128 v[228:231], v133 offset:6144
	s_waitcnt lgkmcnt(4)
	v_mfma_f32_16x16x32_f16 v[138:141], v[202:205], v[198:201], v[138:141]
	ds_read_b128 v[232:235], v136 offset:38912
	s_waitcnt lgkmcnt(4)
	v_mfma_f32_16x16x32_f16 v[92:95], v[202:205], v[206:209], v[92:95]
	v_add_u32_e32 v32, 0x4000, v101
	v_and_b32_e32 v32, 0xffffff80, v32
	s_nop 0
	v_readfirstlane_b32 s101, v32
	v_lshl_add_u64 v[32:33], v[108:109], 0, v[62:63]
	s_mov_b32 m0, s101
	s_nop 0
	global_load_lds_dwordx4 v[32:33], off
	v_mfma_f32_16x16x32_f16 v[142:145], v[210:213], v[198:201], v[142:145]
	v_add_u32_e32 v36, 0x4000, v131
	v_and_b32_e32 v36, 0xffffff80, v36
	s_nop 0
	v_readfirstlane_b32 s101, v36
	v_lshl_add_u64 v[36:37], v[110:111], 0, v[62:63]
	s_mov_b32 m0, s101
	s_nop 0
	global_load_lds_dwordx4 v[36:37], off
	v_mfma_f32_16x16x32_f16 v[158:161], v[210:213], v[206:209], v[158:161]
	v_add_u32_e32 v40, 0x4000, v132
	v_and_b32_e32 v40, 0xffffff80, v40
	s_nop 0
	v_readfirstlane_b32 s101, v40
	v_lshl_add_u64 v[40:41], v[112:113], 0, v[62:63]
	s_mov_b32 m0, s101
	s_nop 0
	global_load_lds_dwordx4 v[40:41], off
	s_waitcnt lgkmcnt(2)
	v_mfma_f32_16x16x32_f16 v[166:169], v[202:205], v[220:223], v[166:169]
	v_add_u32_e32 v44, 0x4000, v130
	v_and_b32_e32 v44, 0xffffff80, v44
	s_nop 0
	v_readfirstlane_b32 s101, v44
	v_lshl_add_u64 v[44:45], v[114:115], 0, v[62:63]
	s_mov_b32 m0, s101
	s_nop 0
	global_load_lds_dwordx4 v[44:45], off
	s_waitcnt lgkmcnt(1)
; #define GL_LOAD(s_, kt_) if (VAR != 1) { a##s_##0 = GL_A(0, kt_); a##s_##1 = GL_A(1, kt_); a##s_##2 = GL_A(2, kt_); a##s_##3 = GL_A(3, kt_); b##s_##0 = GL_B(0, kt_); b##s_##1 = GL_B(1, kt_); b##s_##2 = GL_B(2, kt_); b##s_##3 = GL_B(3, kt_); }
; #define LDS_STORE(s_, buf_) if (VAR != 2) { LDS_ST1(sA, 0, buf_, a##s_##0) LDS_ST1(sA, 1, buf_, a##s_##1) LDS_ST1(sA, 2, buf_, a##s_##2) LDS_ST1(sA, 3, buf_, a##s_##3) LDS_ST1(sB, 0, buf_, b##s_##0) LDS_ST1(sB, 1, buf_, b##s_##1) LDS_ST1(sB, 2, buf_, b##s_##2) LDS_ST1(sB, 3, buf_, b##s_##3) }
;     ...
;   GL_LOAD(0, 0)
;   GL_LOAD(1, 1)
;   LDS_STORE(0, 0)
;   if (VAR != 4) __syncthreads();
; #pragma unroll
;   for (int kt = 0; kt < nk; kt += 2) {
;     if (kt + 2 < nk) { GL_LOAD(0, kt + 2) }
;     MMA_TILE(0)
;     LDS_STORE(1, 1)
;     if (VAR != 4) __syncthreads();
;     if (kt + 3 < nk) { GL_LOAD(1, kt + 3) }
;     MMA_TILE(1)
;     if (kt + 2 < nk) { LDS_STORE(0, 0) }
;     if (VAR != 4) __syncthreads();
;   }
	v_mfma_f32_16x16x32_f16 v[68:71], v[202:205], v[228:231], v[68:71]
	ds_read_b128 v[202:205], v135 offset:32768
	v_mfma_f32_16x16x32_f16 v[190:193], v[210:213], v[220:223], v[190:193]
	v_add_u32_e32 v48, 0xc000, v101
	v_and_b32_e32 v48, 0xffffff80, v48
	s_nop 0
	v_readfirstlane_b32 s101, v48
	v_lshl_add_u64 v[48:49], v[116:117], 0, v[62:63]
	s_mov_b32 m0, s101
	s_nop 0
	global_load_lds_dwordx4 v[48:49], off
	v_mfma_f32_16x16x32_f16 v[76:79], v[210:213], v[228:231], v[76:79]
	ds_read_b128 v[210:213], v135 offset:34816
	v_mfma_f32_16x16x32_f16 v[154:157], v[224:227], v[198:201], v[154:157]
	v_add_u32_e32 v52, 0xc000, v131
	v_and_b32_e32 v52, 0xffffff80, v52
	s_nop 0
	v_readfirstlane_b32 s101, v52
	v_lshl_add_u64 v[52:53], v[118:119], 0, v[62:63]
	s_mov_b32 m0, s101
	s_nop 0
	global_load_lds_dwordx4 v[52:53], off
	v_mfma_f32_16x16x32_f16 v[162:165], v[224:227], v[206:209], v[162:165]
	v_add_u32_e32 v56, 0xc000, v132
	v_and_b32_e32 v56, 0xffffff80, v56
	s_nop 0
	v_readfirstlane_b32 s101, v56
	v_lshl_add_u64 v[56:57], v[120:121], 0, v[62:63]
	s_mov_b32 m0, s101
	s_nop 0
	global_load_lds_dwordx4 v[56:57], off
	s_waitcnt lgkmcnt(2)
	v_mfma_f32_16x16x32_f16 v[64:67], v[232:235], v[198:201], v[64:67]
	ds_read_b128 v[198:201], v134
	v_mfma_f32_16x16x32_f16 v[72:75], v[232:235], v[206:209], v[72:75]
	ds_read_b128 v[206:209], v134 offset:2048
	v_mfma_f32_16x16x32_f16 v[194:197], v[224:227], v[220:223], v[194:197]
	v_add_u32_e32 v60, 0xc000, v130
	v_and_b32_e32 v60, 0xffffff80, v60
	s_nop 0
	v_readfirstlane_b32 s101, v60
	v_lshl_add_u64 v[60:61], v[122:123], 0, v[62:63]
	s_mov_b32 m0, s101
	s_nop 0
	global_load_lds_dwordx4 v[60:61], off
	v_mfma_f32_16x16x32_f16 v[84:87], v[224:227], v[228:231], v[84:87]
	ds_read_b128 v[224:227], v135 offset:36864
	v_mfma_f32_16x16x32_f16 v[80:83], v[232:235], v[220:223], v[80:83]
	ds_read_b128 v[220:223], v134 offset:4096
	v_mfma_f32_16x16x32_f16 v[88:91], v[232:235], v[228:231], v[88:91]
	ds_read_b128 v[228:231], v134 offset:6144
	ds_read_b128 v[232:235], v135 offset:38912
	s_waitcnt vmcnt(0) lgkmcnt(0)
	s_barrier
	v_mfma_f32_16x16x32_f16 v[138:141], v[202:205], v[198:201], v[138:141]
	v_mfma_f32_16x16x32_f16 v[92:95], v[202:205], v[206:209], v[92:95]
	v_mfma_f32_16x16x32_f16 v[142:145], v[210:213], v[198:201], v[142:145]
	v_mfma_f32_16x16x32_f16 v[158:161], v[210:213], v[206:209], v[158:161]
	v_mfma_f32_16x16x32_f16 v[166:169], v[202:205], v[220:223], v[166:169]
	v_mfma_f32_16x16x32_f16 v[68:71], v[202:205], v[228:231], v[68:71]
	ds_read_b128 v[202:205], v136 offset:49152
	v_mfma_f32_16x16x32_f16 v[190:193], v[210:213], v[220:223], v[190:193]
	v_mfma_f32_16x16x32_f16 v[76:79], v[210:213], v[228:231], v[76:79]
	ds_read_b128 v[210:213], v136 offset:51200
	v_mfma_f32_16x16x32_f16 v[154:157], v[224:227], v[198:201], v[154:157]
	v_mfma_f32_16x16x32_f16 v[162:165], v[224:227], v[206:209], v[162:165]
	v_mfma_f32_16x16x32_f16 v[64:67], v[232:235], v[198:201], v[64:67]
	ds_read_b128 v[198:201], v133 offset:16384
	v_mfma_f32_16x16x32_f16 v[72:75], v[232:235], v[206:209], v[72:75]
	ds_read_b128 v[206:209], v133 offset:18432
	v_mfma_f32_16x16x32_f16 v[194:197], v[224:227], v[220:223], v[194:197]
	v_and_b32_e32 v30, 7, v148
	v_bfe_u32 v31, v148, 4, 3
	v_xor_b32_e32 v31, v31, v30
	v_sub_u32_e32 v31, v31, v30
	v_lshlrev_b32_e32 v30, 4, v31
	v_add_u32_e32 v30, 0x300, v30
	v_ashrrev_i32_e32 v31, 31, v30
	v_mfma_f32_16x16x32_f16 v[84:87], v[224:227], v[228:231], v[84:87]
	ds_read_b128 v[224:227], v136 offset:53248
	v_mfma_f32_16x16x32_f16 v[80:83], v[232:235], v[220:223], v[80:83]
	ds_read_b128 v[220:223], v133 offset:20480
	v_mfma_f32_16x16x32_f16 v[88:91], v[232:235], v[228:231], v[88:91]
	ds_read_b128 v[228:231], v133 offset:22528
	s_waitcnt lgkmcnt(4)
	v_mfma_f32_16x16x32_f16 v[138:141], v[202:205], v[198:201], v[138:141]
	ds_read_b128 v[232:235], v136 offset:55296
	s_waitcnt lgkmcnt(4)
	v_mfma_f32_16x16x32_f16 v[92:95], v[202:205], v[206:209], v[92:95]
	v_mov_b32_e32 v0, v101
	v_and_b32_e32 v0, 0xffffff80, v0
	s_nop 0
	v_readfirstlane_b32 s101, v0
	v_lshl_add_u64 v[0:1], v[108:109], 0, v[30:31]
	s_mov_b32 m0, s101
	s_nop 0
	global_load_lds_dwordx4 v[0:1], off
	v_mfma_f32_16x16x32_f16 v[142:145], v[210:213], v[198:201], v[142:145]
	v_mov_b32_e32 v4, v131
	v_and_b32_e32 v4, 0xffffff80, v4
	s_nop 0
	v_readfirstlane_b32 s101, v4
	v_lshl_add_u64 v[4:5], v[110:111], 0, v[30:31]
	s_mov_b32 m0, s101
	s_nop 0
	global_load_lds_dwordx4 v[4:5], off
	v_mfma_f32_16x16x32_f16 v[158:161], v[210:213], v[206:209], v[158:161]
	v_mov_b32_e32 v8, v132
	v_and_b32_e32 v8, 0xffffff80, v8
	s_nop 0
	v_readfirstlane_b32 s101, v8
	v_lshl_add_u64 v[8:9], v[112:113], 0, v[30:31]
	s_mov_b32 m0, s101
	s_nop 0
	global_load_lds_dwordx4 v[8:9], off
	s_waitcnt lgkmcnt(2)
	v_mfma_f32_16x16x32_f16 v[166:169], v[202:205], v[220:223], v[166:169]
	v_mov_b32_e32 v12, v130
	v_and_b32_e32 v12, 0xffffff80, v12
	s_nop 0
	v_readfirstlane_b32 s101, v12
	v_lshl_add_u64 v[12:13], v[114:115], 0, v[30:31]
	s_mov_b32 m0, s101
	s_nop 0
	global_load_lds_dwordx4 v[12:13], off
	s_waitcnt lgkmcnt(1)
	v_mfma_f32_16x16x32_f16 v[68:71], v[202:205], v[228:231], v[68:71]
	ds_read_b128 v[202:205], v135 offset:49152
	v_mfma_f32_16x16x32_f16 v[190:193], v[210:213], v[220:223], v[190:193]
	v_add_u32_e32 v16, 0x8000, v101
	v_and_b32_e32 v16, 0xffffff80, v16
	s_nop 0
	v_readfirstlane_b32 s101, v16
	v_lshl_add_u64 v[16:17], v[116:117], 0, v[30:31]
	s_mov_b32 m0, s101
	s_nop 0
	global_load_lds_dwordx4 v[16:17], off
	v_mfma_f32_16x16x32_f16 v[76:79], v[210:213], v[228:231], v[76:79]
	ds_read_b128 v[210:213], v135 offset:51200
	v_mfma_f32_16x16x32_f16 v[154:157], v[224:227], v[198:201], v[154:157]
	v_add_u32_e32 v20, 0x8000, v131
	v_and_b32_e32 v20, 0xffffff80, v20
	s_nop 0
	v_readfirstlane_b32 s101, v20
	v_lshl_add_u64 v[20:21], v[118:119], 0, v[30:31]
	s_mov_b32 m0, s101
	s_nop 0
	global_load_lds_dwordx4 v[20:21], off
	v_mfma_f32_16x16x32_f16 v[162:165], v[224:227], v[206:209], v[162:165]
	v_add_u32_e32 v24, 0x8000, v132
	v_and_b32_e32 v24, 0xffffff80, v24
	s_nop 0
	v_readfirstlane_b32 s101, v24
	v_lshl_add_u64 v[24:25], v[120:121], 0, v[30:31]
	s_mov_b32 m0, s101
	s_nop 0
	global_load_lds_dwordx4 v[24:25], off
	s_waitcnt lgkmcnt(2)
; #define GL_LOAD(s_, kt_) if (VAR != 1) { a##s_##0 = GL_A(0, kt_); a##s_##1 = GL_A(1, kt_); a##s_##2 = GL_A(2, kt_); a##s_##3 = GL_A(3, kt_); b##s_##0 = GL_B(0, kt_); b##s_##1 = GL_B(1, kt_); b##s_##2 = GL_B(2, kt_); b##s_##3 = GL_B(3, kt_); }
; #define LDS_STORE(s_, buf_) if (VAR != 2) { LDS_ST1(sA, 0, buf_, a##s_##0) LDS_ST1(sA, 1, buf_, a##s_##1) LDS_ST1(sA, 2, buf_, a##s_##2) LDS_ST1(sA, 3, buf_, a##s_##3) LDS_ST1(sB, 0, buf_, b##s_##0) LDS_ST1(sB, 1, buf_, b##s_##1) LDS_ST1(sB, 2, buf_, b##s_##2) LDS_ST1(sB, 3, buf_, b##s_##3) }
;     ...
;   GL_LOAD(0, 0)
;   GL_LOAD(1, 1)
;   LDS_STORE(0, 0)
;   if (VAR != 4) __syncthreads();
; #pragma unroll
;   for (int kt = 0; kt < nk; kt += 2) {
;     if (kt + 2 < nk) { GL_LOAD(0, kt + 2) }
;     MMA_TILE(0)
;     LDS_STORE(1, 1)
;     if (VAR != 4) __syncthreads();
;     if (kt + 3 < nk) { GL_LOAD(1, kt + 3) }
;     MMA_TILE(1)
;     if (kt + 2 < nk) { LDS_STORE(0, 0) }
;     if (VAR != 4) __syncthreads();
;   }
	v_mfma_f32_16x16x32_f16 v[64:67], v[232:235], v[198:201], v[64:67]
	ds_read_b128 v[198:201], v134 offset:16384
	v_mfma_f32_16x16x32_f16 v[72:75], v[232:235], v[206:209], v[72:75]
	ds_read_b128 v[206:209], v134 offset:18432
	v_mfma_f32_16x16x32_f16 v[194:197], v[224:227], v[220:223], v[194:197]
	v_add_u32_e32 v28, 0x8000, v130
	v_and_b32_e32 v28, 0xffffff80, v28
	s_nop 0
	v_readfirstlane_b32 s101, v28
	v_lshl_add_u64 v[28:29], v[122:123], 0, v[30:31]
	s_mov_b32 m0, s101
	s_nop 0
	global_load_lds_dwordx4 v[28:29], off
	v_mfma_f32_16x16x32_f16 v[84:87], v[224:227], v[228:231], v[84:87]
	ds_read_b128 v[224:227], v135 offset:53248
	v_mfma_f32_16x16x32_f16 v[80:83], v[232:235], v[220:223], v[80:83]
	ds_read_b128 v[220:223], v134 offset:20480
	v_mfma_f32_16x16x32_f16 v[88:91], v[232:235], v[228:231], v[88:91]
	ds_read_b128 v[228:231], v134 offset:22528
	ds_read_b128 v[232:235], v135 offset:55296
	s_waitcnt vmcnt(0) lgkmcnt(0)
	s_barrier
	v_mfma_f32_16x16x32_f16 v[138:141], v[202:205], v[198:201], v[138:141]
	v_mfma_f32_16x16x32_f16 v[92:95], v[202:205], v[206:209], v[92:95]
	v_mfma_f32_16x16x32_f16 v[142:145], v[210:213], v[198:201], v[142:145]
	v_mfma_f32_16x16x32_f16 v[158:161], v[210:213], v[206:209], v[158:161]
	v_mfma_f32_16x16x32_f16 v[166:169], v[202:205], v[220:223], v[166:169]
	v_mfma_f32_16x16x32_f16 v[68:71], v[202:205], v[228:231], v[68:71]
	ds_read_b128 v[202:205], v136 offset:32768
	v_mfma_f32_16x16x32_f16 v[190:193], v[210:213], v[220:223], v[190:193]
	v_mfma_f32_16x16x32_f16 v[76:79], v[210:213], v[228:231], v[76:79]
	ds_read_b128 v[210:213], v136 offset:34816
	v_mfma_f32_16x16x32_f16 v[154:157], v[224:227], v[198:201], v[154:157]
	v_mfma_f32_16x16x32_f16 v[162:165], v[224:227], v[206:209], v[162:165]
	v_mfma_f32_16x16x32_f16 v[64:67], v[232:235], v[198:201], v[64:67]
	ds_read_b128 v[198:201], v133
	v_mfma_f32_16x16x32_f16 v[72:75], v[232:235], v[206:209], v[72:75]
	ds_read_b128 v[206:209], v133 offset:2048
	v_mfma_f32_16x16x32_f16 v[194:197], v[224:227], v[220:223], v[194:197]
	v_and_b32_e32 v62, 7, v148
	v_bfe_u32 v63, v148, 4, 3
	v_xor_b32_e32 v63, v63, v62
	v_sub_u32_e32 v63, v63, v62
	v_lshlrev_b32_e32 v62, 4, v63
	v_add_u32_e32 v62, 0x380, v62
	v_ashrrev_i32_e32 v63, 31, v62
	v_mfma_f32_16x16x32_f16 v[84:87], v[224:227], v[228:231], v[84:87]
	ds_read_b128 v[224:227], v136 offset:36864
	v_mfma_f32_16x16x32_f16 v[80:83], v[232:235], v[220:223], v[80:83]
	ds_read_b128 v[220:223], v133 offset:4096
	v_mfma_f32_16x16x32_f16 v[88:91], v[232:235], v[228:231], v[88:91]
	ds_read_b128 v[228:231], v133 offset:6144
	s_waitcnt lgkmcnt(4)
	v_mfma_f32_16x16x32_f16 v[138:141], v[202:205], v[198:201], v[138:141]
	ds_read_b128 v[232:235], v136 offset:38912
	s_waitcnt lgkmcnt(4)
	v_mfma_f32_16x16x32_f16 v[92:95], v[202:205], v[206:209], v[92:95]
	v_add_u32_e32 v32, 0x4000, v101
	v_and_b32_e32 v32, 0xffffff80, v32
	s_nop 0
	v_readfirstlane_b32 s101, v32
	v_lshl_add_u64 v[32:33], v[108:109], 0, v[62:63]
	s_mov_b32 m0, s101
	s_nop 0
	global_load_lds_dwordx4 v[32:33], off
	v_mfma_f32_16x16x32_f16 v[142:145], v[210:213], v[198:201], v[142:145]
	v_add_u32_e32 v36, 0x4000, v131
	v_and_b32_e32 v36, 0xffffff80, v36
	s_nop 0
	v_readfirstlane_b32 s101, v36
	v_lshl_add_u64 v[36:37], v[110:111], 0, v[62:63]
	s_mov_b32 m0, s101
	s_nop 0
	global_load_lds_dwordx4 v[36:37], off
	v_mfma_f32_16x16x32_f16 v[158:161], v[210:213], v[206:209], v[158:161]
	v_add_u32_e32 v40, 0x4000, v132
	v_and_b32_e32 v40, 0xffffff80, v40
	s_nop 0
	v_readfirstlane_b32 s101, v40
	v_lshl_add_u64 v[40:41], v[112:113], 0, v[62:63]
	s_mov_b32 m0, s101
	s_nop 0
	global_load_lds_dwordx4 v[40:41], off
	s_waitcnt lgkmcnt(2)
	v_mfma_f32_16x16x32_f16 v[166:169], v[202:205], v[220:223], v[166:169]
	v_add_u32_e32 v44, 0x4000, v130
	v_and_b32_e32 v44, 0xffffff80, v44
	s_nop 0
	v_readfirstlane_b32 s101, v44
	v_lshl_add_u64 v[44:45], v[114:115], 0, v[62:63]
	s_mov_b32 m0, s101
	s_nop 0
	global_load_lds_dwordx4 v[44:45], off
	s_waitcnt lgkmcnt(1)
	v_mfma_f32_16x16x32_f16 v[68:71], v[202:205], v[228:231], v[68:71]
	ds_read_b128 v[202:205], v135 offset:32768
	v_mfma_f32_16x16x32_f16 v[190:193], v[210:213], v[220:223], v[190:193]
	v_add_u32_e32 v48, 0xc000, v101
	v_and_b32_e32 v48, 0xffffff80, v48
	s_nop 0
	v_readfirstlane_b32 s101, v48
	v_lshl_add_u64 v[48:49], v[116:117], 0, v[62:63]
	s_mov_b32 m0, s101
	s_nop 0
	global_load_lds_dwordx4 v[48:49], off
	v_mfma_f32_16x16x32_f16 v[76:79], v[210:213], v[228:231], v[76:79]
	ds_read_b128 v[210:213], v135 offset:34816
	v_mfma_f32_16x16x32_f16 v[154:157], v[224:227], v[198:201], v[154:157]
	v_add_u32_e32 v52, 0xc000, v131
	v_and_b32_e32 v52, 0xffffff80, v52
	s_nop 0
	v_readfirstlane_b32 s101, v52
	v_lshl_add_u64 v[52:53], v[118:119], 0, v[62:63]
	s_mov_b32 m0, s101
	s_nop 0
	global_load_lds_dwordx4 v[52:53], off
	v_mfma_f32_16x16x32_f16 v[162:165], v[224:227], v[206:209], v[162:165]
	v_add_u32_e32 v56, 0xc000, v132
	v_and_b32_e32 v56, 0xffffff80, v56
	s_nop 0
	v_readfirstlane_b32 s101, v56
	v_lshl_add_u64 v[56:57], v[120:121], 0, v[62:63]
	s_mov_b32 m0, s101
	s_nop 0
	global_load_lds_dwordx4 v[56:57], off
	s_waitcnt lgkmcnt(2)
	v_mfma_f32_16x16x32_f16 v[64:67], v[232:235], v[198:201], v[64:67]
	ds_read_b128 v[198:201], v134
	v_mfma_f32_16x16x32_f16 v[72:75], v[232:235], v[206:209], v[72:75]
	ds_read_b128 v[206:209], v134 offset:2048
	v_mfma_f32_16x16x32_f16 v[194:197], v[224:227], v[220:223], v[194:197]
	v_add_u32_e32 v60, 0xc000, v130
	v_and_b32_e32 v60, 0xffffff80, v60
	s_nop 0
	v_readfirstlane_b32 s101, v60
	v_lshl_add_u64 v[60:61], v[122:123], 0, v[62:63]
	s_mov_b32 m0, s101
	s_nop 0
	global_load_lds_dwordx4 v[60:61], off
	v_mfma_f32_16x16x32_f16 v[84:87], v[224:227], v[228:231], v[84:87]
	ds_read_b128 v[224:227], v135 offset:36864
	v_mfma_f32_16x16x32_f16 v[80:83], v[232:235], v[220:223], v[80:83]
	ds_read_b128 v[220:223], v134 offset:4096
	v_mfma_f32_16x16x32_f16 v[88:91], v[232:235], v[228:231], v[88:91]
	ds_read_b128 v[228:231], v134 offset:6144
	ds_read_b128 v[232:235], v135 offset:38912
	s_waitcnt vmcnt(0) lgkmcnt(0)
	s_barrier
; #define GL_LOAD(s_, kt_) if (VAR != 1) { a##s_##0 = GL_A(0, kt_); a##s_##1 = GL_A(1, kt_); a##s_##2 = GL_A(2, kt_); a##s_##3 = GL_A(3, kt_); b##s_##0 = GL_B(0, kt_); b##s_##1 = GL_B(1, kt_); b##s_##2 = GL_B(2, kt_); b##s_##3 = GL_B(3, kt_); }
; #define LDS_STORE(s_, buf_) if (VAR != 2) { LDS_ST1(sA, 0, buf_, a##s_##0) LDS_ST1(sA, 1, buf_, a##s_##1) LDS_ST1(sA, 2, buf_, a##s_##2) LDS_ST1(sA, 3, buf_, a##s_##3) LDS_ST1(sB, 0, buf_, b##s_##0) LDS_ST1(sB, 1, buf_, b##s_##1) LDS_ST1(sB, 2, buf_, b##s_##2) LDS_ST1(sB, 3, buf_, b##s_##3) }
;     ...
;   GL_LOAD(0, 0)
;   GL_LOAD(1, 1)
;   LDS_STORE(0, 0)
;   if (VAR != 4) __syncthreads();
; #pragma unroll
;   for (int kt = 0; kt < nk; kt += 2) {
;     if (kt + 2 < nk) { GL_LOAD(0, kt + 2) }
;     MMA_TILE(0)
;     LDS_STORE(1, 1)
;     if (VAR != 4) __syncthreads();
;     if (kt + 3 < nk) { GL_LOAD(1, kt + 3) }
;     MMA_TILE(1)
;     if (kt + 2 < nk) { LDS_STORE(0, 0) }
;     if (VAR != 4) __syncthreads();
;   }
	v_mfma_f32_16x16x32_f16 v[138:141], v[202:205], v[198:201], v[138:141]
	v_mfma_f32_16x16x32_f16 v[92:95], v[202:205], v[206:209], v[92:95]
	v_mfma_f32_16x16x32_f16 v[142:145], v[210:213], v[198:201], v[142:145]
	v_mfma_f32_16x16x32_f16 v[158:161], v[210:213], v[206:209], v[158:161]
	v_mfma_f32_16x16x32_f16 v[166:169], v[202:205], v[220:223], v[166:169]
	v_mfma_f32_16x16x32_f16 v[68:71], v[202:205], v[228:231], v[68:71]
	ds_read_b128 v[202:205], v136 offset:49152
	v_mfma_f32_16x16x32_f16 v[190:193], v[210:213], v[220:223], v[190:193]
	v_mfma_f32_16x16x32_f16 v[76:79], v[210:213], v[228:231], v[76:79]
	ds_read_b128 v[210:213], v136 offset:51200
	v_mfma_f32_16x16x32_f16 v[154:157], v[224:227], v[198:201], v[154:157]
	v_mfma_f32_16x16x32_f16 v[162:165], v[224:227], v[206:209], v[162:165]
	v_mfma_f32_16x16x32_f16 v[64:67], v[232:235], v[198:201], v[64:67]
	ds_read_b128 v[198:201], v133 offset:16384
	v_mfma_f32_16x16x32_f16 v[72:75], v[232:235], v[206:209], v[72:75]
	ds_read_b128 v[206:209], v133 offset:18432
	v_mfma_f32_16x16x32_f16 v[194:197], v[224:227], v[220:223], v[194:197]
	v_and_b32_e32 v30, 7, v148
	v_bfe_u32 v31, v148, 4, 3
	v_xor_b32_e32 v31, v31, v30
	v_sub_u32_e32 v31, v31, v30
	v_lshlrev_b32_e32 v30, 4, v31
	v_add_u32_e32 v30, 0x400, v30
	v_ashrrev_i32_e32 v31, 31, v30
	v_mfma_f32_16x16x32_f16 v[84:87], v[224:227], v[228:231], v[84:87]
	ds_read_b128 v[224:227], v136 offset:53248
	v_mfma_f32_16x16x32_f16 v[80:83], v[232:235], v[220:223], v[80:83]
	ds_read_b128 v[220:223], v133 offset:20480
	v_mfma_f32_16x16x32_f16 v[88:91], v[232:235], v[228:231], v[88:91]
	ds_read_b128 v[228:231], v133 offset:22528
	s_waitcnt lgkmcnt(4)
	v_mfma_f32_16x16x32_f16 v[138:141], v[202:205], v[198:201], v[138:141]
	ds_read_b128 v[232:235], v136 offset:55296
	s_waitcnt lgkmcnt(4)
	v_mfma_f32_16x16x32_f16 v[92:95], v[202:205], v[206:209], v[92:95]
	v_mov_b32_e32 v0, v101
	v_and_b32_e32 v0, 0xffffff80, v0
	s_nop 0
	v_readfirstlane_b32 s101, v0
	v_lshl_add_u64 v[0:1], v[108:109], 0, v[30:31]
	s_mov_b32 m0, s101
	s_nop 0
	global_load_lds_dwordx4 v[0:1], off
	v_mfma_f32_16x16x32_f16 v[142:145], v[210:213], v[198:201], v[142:145]
	v_mov_b32_e32 v4, v131
	v_and_b32_e32 v4, 0xffffff80, v4
	s_nop 0
	v_readfirstlane_b32 s101, v4
	v_lshl_add_u64 v[4:5], v[110:111], 0, v[30:31]
	s_mov_b32 m0, s101
	s_nop 0
	global_load_lds_dwordx4 v[4:5], off
	v_mfma_f32_16x16x32_f16 v[158:161], v[210:213], v[206:209], v[158:161]
	v_mov_b32_e32 v8, v132
	v_and_b32_e32 v8, 0xffffff80, v8
	s_nop 0
	v_readfirstlane_b32 s101, v8
	v_lshl_add_u64 v[8:9], v[112:113], 0, v[30:31]
	s_mov_b32 m0, s101
	s_nop 0
	global_load_lds_dwordx4 v[8:9], off
	s_waitcnt lgkmcnt(2)
	v_mfma_f32_16x16x32_f16 v[166:169], v[202:205], v[220:223], v[166:169]
	v_mov_b32_e32 v12, v130
	v_and_b32_e32 v12, 0xffffff80, v12
	s_nop 0
	v_readfirstlane_b32 s101, v12
	v_lshl_add_u64 v[12:13], v[114:115], 0, v[30:31]
	s_mov_b32 m0, s101
	s_nop 0
	global_load_lds_dwordx4 v[12:13], off
	s_waitcnt lgkmcnt(1)
	v_mfma_f32_16x16x32_f16 v[68:71], v[202:205], v[228:231], v[68:71]
	ds_read_b128 v[202:205], v135 offset:49152
	v_mfma_f32_16x16x32_f16 v[190:193], v[210:213], v[220:223], v[190:193]
	v_add_u32_e32 v16, 0x8000, v101
	v_and_b32_e32 v16, 0xffffff80, v16
	s_nop 0
	v_readfirstlane_b32 s101, v16
	v_lshl_add_u64 v[16:17], v[116:117], 0, v[30:31]
	s_mov_b32 m0, s101
	s_nop 0
	global_load_lds_dwordx4 v[16:17], off
	v_mfma_f32_16x16x32_f16 v[76:79], v[210:213], v[228:231], v[76:79]
	ds_read_b128 v[210:213], v135 offset:51200
	v_mfma_f32_16x16x32_f16 v[154:157], v[224:227], v[198:201], v[154:157]
	v_add_u32_e32 v20, 0x8000, v131
	v_and_b32_e32 v20, 0xffffff80, v20
	s_nop 0
	v_readfirstlane_b32 s101, v20
	v_lshl_add_u64 v[20:21], v[118:119], 0, v[30:31]
	s_mov_b32 m0, s101
	s_nop 0
	global_load_lds_dwordx4 v[20:21], off
	v_mfma_f32_16x16x32_f16 v[162:165], v[224:227], v[206:209], v[162:165]
	v_add_u32_e32 v24, 0x8000, v132
	v_and_b32_e32 v24, 0xffffff80, v24
	s_nop 0
	v_readfirstlane_b32 s101, v24
	v_lshl_add_u64 v[24:25], v[120:121], 0, v[30:31]
	s_mov_b32 m0, s101
	s_nop 0
	global_load_lds_dwordx4 v[24:25], off
	s_waitcnt lgkmcnt(2)
	v_mfma_f32_16x16x32_f16 v[64:67], v[232:235], v[198:201], v[64:67]
	ds_read_b128 v[198:201], v134 offset:16384
	v_mfma_f32_16x16x32_f16 v[72:75], v[232:235], v[206:209], v[72:75]
	ds_read_b128 v[206:209], v134 offset:18432
	v_mfma_f32_16x16x32_f16 v[194:197], v[224:227], v[220:223], v[194:197]
	v_add_u32_e32 v28, 0x8000, v130
	v_and_b32_e32 v28, 0xffffff80, v28
	s_nop 0
	v_readfirstlane_b32 s101, v28
	v_lshl_add_u64 v[28:29], v[122:123], 0, v[30:31]
	s_mov_b32 m0, s101
	s_nop 0
	global_load_lds_dwordx4 v[28:29], off
	v_mfma_f32_16x16x32_f16 v[84:87], v[224:227], v[228:231], v[84:87]
	ds_read_b128 v[224:227], v135 offset:53248
	v_mfma_f32_16x16x32_f16 v[80:83], v[232:235], v[220:223], v[80:83]
	ds_read_b128 v[220:223], v134 offset:20480
	v_mfma_f32_16x16x32_f16 v[88:91], v[232:235], v[228:231], v[88:91]
	ds_read_b128 v[228:231], v134 offset:22528
	s_waitcnt lgkmcnt(4)
	v_mfma_f32_16x16x32_f16 v[138:141], v[202:205], v[198:201], v[138:141]
	ds_read_b128 v[232:235], v135 offset:55296
	s_waitcnt vmcnt(0) lgkmcnt(0)
	s_barrier
; #define GL_LOAD(s_, kt_) if (VAR != 1) { a##s_##0 = GL_A(0, kt_); a##s_##1 = GL_A(1, kt_); a##s_##2 = GL_A(2, kt_); a##s_##3 = GL_A(3, kt_); b##s_##0 = GL_B(0, kt_); b##s_##1 = GL_B(1, kt_); b##s_##2 = GL_B(2, kt_); b##s_##3 = GL_B(3, kt_); }
; #define LDS_STORE(s_, buf_) if (VAR != 2) { LDS_ST1(sA, 0, buf_, a##s_##0) LDS_ST1(sA, 1, buf_, a##s_##1) LDS_ST1(sA, 2, buf_, a##s_##2) LDS_ST1(sA, 3, buf_, a##s_##3) LDS_ST1(sB, 0, buf_, b##s_##0) LDS_ST1(sB, 1, buf_, b##s_##1) LDS_ST1(sB, 2, buf_, b##s_##2) LDS_ST1(sB, 3, buf_, b##s_##3) }
;     ...
;   GL_LOAD(0, 0)
;   GL_LOAD(1, 1)
;   LDS_STORE(0, 0)
;   if (VAR != 4) __syncthreads();
; #pragma unroll
;   for (int kt = 0; kt < nk; kt += 2) {
;     if (kt + 2 < nk) { GL_LOAD(0, kt + 2) }
;     MMA_TILE(0)
;     LDS_STORE(1, 1)
;     if (VAR != 4) __syncthreads();
;     if (kt + 3 < nk) { GL_LOAD(1, kt + 3) }
;     MMA_TILE(1)
;     if (kt + 2 < nk) { LDS_STORE(0, 0) }
;     if (VAR != 4) __syncthreads();
;   }
	v_mfma_f32_16x16x32_f16 v[142:145], v[210:213], v[198:201], v[142:145]
	ds_read_b128 v[0:3], v133
	v_mfma_f32_16x16x32_f16 v[158:161], v[210:213], v[206:209], v[158:161]
	ds_read_b128 v[4:7], v136 offset:32768
	v_mfma_f32_16x16x32_f16 v[154:157], v[224:227], v[198:201], v[154:157]
	ds_read_b128 v[8:11], v133 offset:2048
	v_mfma_f32_16x16x32_f16 v[162:165], v[224:227], v[206:209], v[162:165]
	ds_read_b128 v[12:15], v136 offset:34816
	v_mfma_f32_16x16x32_f16 v[190:193], v[210:213], v[220:223], v[190:193]
	ds_read_b128 v[16:19], v133 offset:4096
	v_mfma_f32_16x16x32_f16 v[210:213], v[210:213], v[228:231], v[76:79]
	ds_read_b128 v[20:23], v136 offset:36864
	v_mfma_f32_16x16x32_f16 v[194:197], v[224:227], v[220:223], v[194:197]
	ds_read_b128 v[24:27], v133 offset:6144
	v_mfma_f32_16x16x32_f16 v[224:227], v[224:227], v[228:231], v[84:87]
	ds_read_b128 v[28:31], v136 offset:38912
	v_mfma_f32_16x16x32_f16 v[198:201], v[232:235], v[198:201], v[64:67]
	s_nop 2
	v_mfma_f32_16x16x32_f16 v[236:239], v[202:205], v[206:209], v[92:95]
	v_mfma_f32_16x16x32_f16 v[206:209], v[232:235], v[206:209], v[72:75]
	v_mfma_f32_16x16x32_f16 v[166:169], v[202:205], v[220:223], v[166:169]
	v_mfma_f32_16x16x32_f16 v[220:223], v[232:235], v[220:223], v[80:83]
	v_mfma_f32_16x16x32_f16 v[202:205], v[202:205], v[228:231], v[68:71]
	v_mfma_f32_16x16x32_f16 v[228:231], v[232:235], v[228:231], v[88:91]
	ds_read_b128 v[232:235], v135 offset:38912
	s_nop 0
	s_waitcnt lgkmcnt(7)
	v_mfma_f32_16x16x32_f16 v[138:141], v[4:7], v[0:3], v[138:141]
	s_waitcnt lgkmcnt(5)
	v_mfma_f32_16x16x32_f16 v[142:145], v[12:15], v[0:3], v[142:145]
	s_waitcnt lgkmcnt(3)
	v_mfma_f32_16x16x32_f16 v[154:157], v[20:23], v[0:3], v[154:157]
	s_waitcnt lgkmcnt(1)
	v_mfma_f32_16x16x32_f16 v[0:3], v[28:31], v[0:3], v[198:201]
	v_mfma_f32_16x16x32_f16 v[198:201], v[4:7], v[8:11], v[236:239]
	v_mfma_f32_16x16x32_f16 v[158:161], v[12:15], v[8:11], v[158:161]
	v_and_b32_e32 v62, 7, v148
	v_bfe_u32 v63, v148, 4, 3
	v_xor_b32_e32 v63, v63, v62
	v_sub_u32_e32 v63, v63, v62
	v_lshlrev_b32_e32 v62, 4, v63
	v_add_u32_e32 v62, 0x480, v62
	v_ashrrev_i32_e32 v63, 31, v62
	v_add_u32_e32 v32, 0x4000, v101
	v_and_b32_e32 v32, 0xffffff80, v32
	s_nop 0
	v_readfirstlane_b32 s101, v32
	v_lshl_add_u64 v[32:33], v[108:109], 0, v[62:63]
	s_mov_b32 m0, s101
	s_nop 0
	global_load_lds_dwordx4 v[32:33], off
	v_mfma_f32_16x16x32_f16 v[166:169], v[4:7], v[16:19], v[166:169]
	v_add_u32_e32 v36, 0x4000, v131
	v_and_b32_e32 v36, 0xffffff80, v36
	s_nop 0
	v_readfirstlane_b32 s101, v36
	v_lshl_add_u64 v[36:37], v[110:111], 0, v[62:63]
	s_mov_b32 m0, s101
	s_nop 0
	global_load_lds_dwordx4 v[36:37], off
	v_add_u32_e32 v40, 0x4000, v132
	v_and_b32_e32 v40, 0xffffff80, v40
	s_nop 0
	v_readfirstlane_b32 s101, v40
	v_lshl_add_u64 v[40:41], v[112:113], 0, v[62:63]
	s_mov_b32 m0, s101
	s_nop 0
	global_load_lds_dwordx4 v[40:41], off
	v_mfma_f32_16x16x32_f16 v[4:7], v[4:7], v[24:27], v[202:205]
	s_nop 2
	ds_read_b128 v[202:205], v135 offset:32768
	v_add_u32_e32 v44, 0x4000, v130
	v_and_b32_e32 v44, 0xffffff80, v44
	s_nop 0
	v_readfirstlane_b32 s101, v44
	v_lshl_add_u64 v[44:45], v[114:115], 0, v[62:63]
	s_mov_b32 m0, s101
	s_nop 0
	global_load_lds_dwordx4 v[44:45], off
	v_mfma_f32_16x16x32_f16 v[190:193], v[12:15], v[16:19], v[190:193]
	v_add_u32_e32 v48, 0xc000, v101
	v_and_b32_e32 v48, 0xffffff80, v48
	s_nop 0
	v_readfirstlane_b32 s101, v48
	v_lshl_add_u64 v[48:49], v[116:117], 0, v[62:63]
	s_mov_b32 m0, s101
	s_nop 0
	global_load_lds_dwordx4 v[48:49], off
	v_mfma_f32_16x16x32_f16 v[12:15], v[12:15], v[24:27], v[210:213]
	s_nop 2
	ds_read_b128 v[210:213], v135 offset:34816
	v_add_u32_e32 v52, 0xc000, v131
	v_and_b32_e32 v52, 0xffffff80, v52
	s_nop 0
	v_readfirstlane_b32 s101, v52
	v_lshl_add_u64 v[52:53], v[118:119], 0, v[62:63]
	s_mov_b32 m0, s101
	s_nop 0
	global_load_lds_dwordx4 v[52:53], off
	v_mfma_f32_16x16x32_f16 v[162:165], v[20:23], v[8:11], v[162:165]
	v_add_u32_e32 v56, 0xc000, v132
	v_and_b32_e32 v56, 0xffffff80, v56
	s_nop 0
	v_readfirstlane_b32 s101, v56
	v_lshl_add_u64 v[56:57], v[120:121], 0, v[62:63]
	s_mov_b32 m0, s101
	s_nop 0
	global_load_lds_dwordx4 v[56:57], off
	v_add_u32_e32 v60, 0xc000, v130
	v_and_b32_e32 v60, 0xffffff80, v60
	s_nop 0
	v_readfirstlane_b32 s101, v60
	v_lshl_add_u64 v[60:61], v[122:123], 0, v[62:63]
	s_mov_b32 m0, s101
	s_nop 0
	global_load_lds_dwordx4 v[60:61], off
	v_mfma_f32_16x16x32_f16 v[8:11], v[28:31], v[8:11], v[206:209]
	s_nop 2
	ds_read_b128 v[206:209], v134 offset:2048
	v_mfma_f32_16x16x32_f16 v[194:197], v[20:23], v[16:19], v[194:197]
	v_mfma_f32_16x16x32_f16 v[20:23], v[20:23], v[24:27], v[224:227]
	s_nop 2
	ds_read_b128 v[224:227], v135 offset:36864
	v_mfma_f32_16x16x32_f16 v[16:19], v[28:31], v[16:19], v[220:223]
	s_nop 2
	ds_read_b128 v[220:223], v134 offset:4096
	v_mfma_f32_16x16x32_f16 v[24:27], v[28:31], v[24:27], v[228:231]
	ds_read_b128 v[28:31], v134
	s_waitcnt lgkmcnt(0)
	v_mfma_f32_16x16x32_f16 v[138:141], v[202:205], v[28:31], v[138:141]
	ds_read_b128 v[228:231], v134 offset:6144
	s_waitcnt vmcnt(0) lgkmcnt(0)
	s_barrier
; #define GL_LOAD(s_, kt_) if (VAR != 1) { a##s_##0 = GL_A(0, kt_); a##s_##1 = GL_A(1, kt_); a##s_##2 = GL_A(2, kt_); a##s_##3 = GL_A(3, kt_); b##s_##0 = GL_B(0, kt_); b##s_##1 = GL_B(1, kt_); b##s_##2 = GL_B(2, kt_); b##s_##3 = GL_B(3, kt_); }
; #define LDS_STORE(s_, buf_) if (VAR != 2) { LDS_ST1(sA, 0, buf_, a##s_##0) LDS_ST1(sA, 1, buf_, a##s_##1) LDS_ST1(sA, 2, buf_, a##s_##2) LDS_ST1(sA, 3, buf_, a##s_##3) LDS_ST1(sB, 0, buf_, b##s_##0) LDS_ST1(sB, 1, buf_, b##s_##1) LDS_ST1(sB, 2, buf_, b##s_##2) LDS_ST1(sB, 3, buf_, b##s_##3) }
;     ...
;   GL_LOAD(0, 0)
;   GL_LOAD(1, 1)
;   LDS_STORE(0, 0)
;   if (VAR != 4) __syncthreads();
; #pragma unroll
;   for (int kt = 0; kt < nk; kt += 2) {
;     if (kt + 2 < nk) { GL_LOAD(0, kt + 2) }
;     MMA_TILE(0)
;     LDS_STORE(1, 1)
;     if (VAR != 4) __syncthreads();
;     if (kt + 3 < nk) { GL_LOAD(1, kt + 3) }
;     MMA_TILE(1)
;     if (kt + 2 < nk) { LDS_STORE(0, 0) }
;     if (VAR != 4) __syncthreads();
;   }
	v_mfma_f32_16x16x32_f16 v[142:145], v[210:213], v[28:31], v[142:145]
	ds_read_b128 v[32:35], v133 offset:16384
	v_mfma_f32_16x16x32_f16 v[158:161], v[210:213], v[206:209], v[158:161]
	ds_read_b128 v[36:39], v136 offset:49152
	v_mfma_f32_16x16x32_f16 v[154:157], v[224:227], v[28:31], v[154:157]
	ds_read_b128 v[40:43], v133 offset:18432
	v_mfma_f32_16x16x32_f16 v[162:165], v[224:227], v[206:209], v[162:165]
	ds_read_b128 v[44:47], v136 offset:51200
	v_mfma_f32_16x16x32_f16 v[190:193], v[210:213], v[220:223], v[190:193]
	ds_read_b128 v[48:51], v133 offset:20480
	v_mfma_f32_16x16x32_f16 v[210:213], v[210:213], v[228:231], v[12:15]
	ds_read_b128 v[52:55], v136 offset:53248
	v_mfma_f32_16x16x32_f16 v[194:197], v[224:227], v[220:223], v[194:197]
	ds_read_b128 v[56:59], v133 offset:22528
	v_mfma_f32_16x16x32_f16 v[224:227], v[224:227], v[228:231], v[20:23]
	ds_read_b128 v[60:63], v136 offset:55296
	v_mfma_f32_16x16x32_f16 v[236:239], v[232:235], v[28:31], v[0:3]
	v_mfma_f32_16x16x32_f16 v[198:201], v[202:205], v[206:209], v[198:201]
	v_mfma_f32_16x16x32_f16 v[206:209], v[232:235], v[206:209], v[8:11]
	v_mfma_f32_16x16x32_f16 v[166:169], v[202:205], v[220:223], v[166:169]
	v_mfma_f32_16x16x32_f16 v[220:223], v[232:235], v[220:223], v[16:19]
	v_mfma_f32_16x16x32_f16 v[202:205], v[202:205], v[228:231], v[4:7]
	v_mfma_f32_16x16x32_f16 v[228:231], v[232:235], v[228:231], v[24:27]
	ds_read_b128 v[232:235], v135 offset:55296
	s_nop 1
	s_waitcnt lgkmcnt(7)
	v_mfma_f32_16x16x32_f16 v[138:141], v[36:39], v[32:35], v[138:141]
	s_waitcnt lgkmcnt(6)
	v_mfma_f32_16x16x32_f16 v[198:201], v[36:39], v[40:43], v[198:201]
	s_waitcnt lgkmcnt(5)
	v_mfma_f32_16x16x32_f16 v[142:145], v[44:47], v[32:35], v[142:145]
	v_mfma_f32_16x16x32_f16 v[158:161], v[44:47], v[40:43], v[158:161]
	s_waitcnt lgkmcnt(4)
	v_mfma_f32_16x16x32_f16 v[166:169], v[36:39], v[48:51], v[166:169]
	v_and_b32_e32 v94, 7, v148
	v_bfe_u32 v95, v148, 4, 3
	v_xor_b32_e32 v95, v95, v94
	v_sub_u32_e32 v95, v95, v94
	v_lshlrev_b32_e32 v94, 4, v95
	v_add_u32_e32 v94, 0x500, v94
	v_ashrrev_i32_e32 v95, 31, v94
	s_waitcnt lgkmcnt(2)
	v_mfma_f32_16x16x32_f16 v[36:39], v[36:39], v[56:59], v[202:205]
	s_nop 2
	ds_read_b128 v[202:205], v135 offset:49152
	v_mov_b32_e32 v64, v101
	v_and_b32_e32 v64, 0xffffff80, v64
	s_nop 0
	v_readfirstlane_b32 s101, v64
	v_lshl_add_u64 v[64:65], v[108:109], 0, v[94:95]
	s_mov_b32 m0, s101
	s_nop 0
	global_load_lds_dwordx4 v[64:65], off
	v_mfma_f32_16x16x32_f16 v[190:193], v[44:47], v[48:51], v[190:193]
	v_mov_b32_e32 v68, v131
	v_and_b32_e32 v68, 0xffffff80, v68
	s_nop 0
	v_readfirstlane_b32 s101, v68
	v_lshl_add_u64 v[68:69], v[110:111], 0, v[94:95]
	s_mov_b32 m0, s101
	s_nop 0
	global_load_lds_dwordx4 v[68:69], off
	v_mov_b32_e32 v72, v132
	v_and_b32_e32 v72, 0xffffff80, v72
	s_nop 0
	v_readfirstlane_b32 s101, v72
	v_lshl_add_u64 v[72:73], v[112:113], 0, v[94:95]
	s_mov_b32 m0, s101
	s_nop 0
	global_load_lds_dwordx4 v[72:73], off
	v_mfma_f32_16x16x32_f16 v[44:47], v[44:47], v[56:59], v[210:213]
	s_nop 2
	ds_read_b128 v[210:213], v135 offset:51200
	v_mfma_f32_16x16x32_f16 v[154:157], v[52:55], v[32:35], v[154:157]
	v_mov_b32_e32 v76, v130
	v_and_b32_e32 v76, 0xffffff80, v76
	s_nop 0
	v_readfirstlane_b32 s101, v76
	v_lshl_add_u64 v[76:77], v[114:115], 0, v[94:95]
	s_mov_b32 m0, s101
	s_nop 0
	global_load_lds_dwordx4 v[76:77], off
	v_mfma_f32_16x16x32_f16 v[162:165], v[52:55], v[40:43], v[162:165]
	v_add_u32_e32 v80, 0x8000, v101
	v_and_b32_e32 v80, 0xffffff80, v80
	s_nop 0
	v_readfirstlane_b32 s101, v80
	v_lshl_add_u64 v[80:81], v[116:117], 0, v[94:95]
	s_mov_b32 m0, s101
	s_nop 0
	global_load_lds_dwordx4 v[80:81], off
	s_waitcnt lgkmcnt(3)
	v_mfma_f32_16x16x32_f16 v[32:35], v[60:63], v[32:35], v[236:239]
	v_add_u32_e32 v84, 0x8000, v131
	v_and_b32_e32 v84, 0xffffff80, v84
	s_nop 0
	v_readfirstlane_b32 s101, v84
	v_lshl_add_u64 v[84:85], v[118:119], 0, v[94:95]
	s_mov_b32 m0, s101
	s_nop 0
	global_load_lds_dwordx4 v[84:85], off
	v_mfma_f32_16x16x32_f16 v[40:43], v[60:63], v[40:43], v[206:209]
	s_nop 2
	ds_read_b128 v[206:209], v134 offset:18432
	v_mfma_f32_16x16x32_f16 v[194:197], v[52:55], v[48:51], v[194:197]
	v_add_u32_e32 v88, 0x8000, v132
	v_and_b32_e32 v88, 0xffffff80, v88
	s_nop 0
	v_readfirstlane_b32 s101, v88
	v_lshl_add_u64 v[88:89], v[120:121], 0, v[94:95]
	s_mov_b32 m0, s101
	s_nop 0
	global_load_lds_dwordx4 v[88:89], off
	v_mfma_f32_16x16x32_f16 v[52:55], v[52:55], v[56:59], v[224:227]
	s_nop 2
	ds_read_b128 v[224:227], v135 offset:53248
	v_mfma_f32_16x16x32_f16 v[48:51], v[60:63], v[48:51], v[220:223]
	s_nop 2
	ds_read_b128 v[220:223], v134 offset:20480
	v_mfma_f32_16x16x32_f16 v[56:59], v[60:63], v[56:59], v[228:231]
	ds_read_b128 v[60:63], v134 offset:16384
	s_waitcnt lgkmcnt(0)
	v_mfma_f32_16x16x32_f16 v[138:141], v[202:205], v[60:63], v[138:141]
	ds_read_b128 v[228:231], v134 offset:22528
	v_add_u32_e32 v92, 0x8000, v130
	v_and_b32_e32 v92, 0xffffff80, v92
	s_nop 0
	v_readfirstlane_b32 s101, v92
	v_lshl_add_u64 v[92:93], v[122:123], 0, v[94:95]
	s_mov_b32 m0, s101
	s_nop 0
	global_load_lds_dwordx4 v[92:93], off
	s_waitcnt vmcnt(0) lgkmcnt(0)
	s_barrier
; #define GL_LOAD(s_, kt_) if (VAR != 1) { a##s_##0 = GL_A(0, kt_); a##s_##1 = GL_A(1, kt_); a##s_##2 = GL_A(2, kt_); a##s_##3 = GL_A(3, kt_); b##s_##0 = GL_B(0, kt_); b##s_##1 = GL_B(1, kt_); b##s_##2 = GL_B(2, kt_); b##s_##3 = GL_B(3, kt_); }
; #define LDS_STORE(s_, buf_) if (VAR != 2) { LDS_ST1(sA, 0, buf_, a##s_##0) LDS_ST1(sA, 1, buf_, a##s_##1) LDS_ST1(sA, 2, buf_, a##s_##2) LDS_ST1(sA, 3, buf_, a##s_##3) LDS_ST1(sB, 0, buf_, b##s_##0) LDS_ST1(sB, 1, buf_, b##s_##1) LDS_ST1(sB, 2, buf_, b##s_##2) LDS_ST1(sB, 3, buf_, b##s_##3) }
;     ...
;   GL_LOAD(0, 0)
;   GL_LOAD(1, 1)
;   LDS_STORE(0, 0)
;   if (VAR != 4) __syncthreads();
; #pragma unroll
;   for (int kt = 0; kt < nk; kt += 2) {
;     if (kt + 2 < nk) { GL_LOAD(0, kt + 2) }
;     MMA_TILE(0)
;     LDS_STORE(1, 1)
;     if (VAR != 4) __syncthreads();
;     if (kt + 3 < nk) { GL_LOAD(1, kt + 3) }
;     MMA_TILE(1)
;     if (kt + 2 < nk) { LDS_STORE(0, 0) }
;     if (VAR != 4) __syncthreads();
;   }
	v_mfma_f32_16x16x32_f16 v[142:145], v[210:213], v[60:63], v[142:145]
	ds_read_b128 v[64:67], v133
	v_mfma_f32_16x16x32_f16 v[158:161], v[210:213], v[206:209], v[158:161]
	ds_read_b128 v[68:71], v136 offset:32768
	v_mfma_f32_16x16x32_f16 v[154:157], v[224:227], v[60:63], v[154:157]
	ds_read_b128 v[72:75], v133 offset:2048
	v_mfma_f32_16x16x32_f16 v[162:165], v[224:227], v[206:209], v[162:165]
	ds_read_b128 v[76:79], v136 offset:34816
	v_mfma_f32_16x16x32_f16 v[190:193], v[210:213], v[220:223], v[190:193]
	ds_read_b128 v[80:83], v133 offset:4096
	v_mfma_f32_16x16x32_f16 v[210:213], v[210:213], v[228:231], v[44:47]
	ds_read_b128 v[84:87], v136 offset:36864
	v_mfma_f32_16x16x32_f16 v[194:197], v[224:227], v[220:223], v[194:197]
	ds_read_b128 v[88:91], v133 offset:6144
	v_mfma_f32_16x16x32_f16 v[224:227], v[224:227], v[228:231], v[52:55]
	ds_read_b128 v[92:95], v136 offset:38912
	v_mfma_f32_16x16x32_f16 v[236:239], v[232:235], v[60:63], v[32:35]
	s_nop 0
	v_mfma_f32_16x16x32_f16 v[198:201], v[202:205], v[206:209], v[198:201]
	v_mfma_f32_16x16x32_f16 v[206:209], v[232:235], v[206:209], v[40:43]
	v_mfma_f32_16x16x32_f16 v[166:169], v[202:205], v[220:223], v[166:169]
	v_mfma_f32_16x16x32_f16 v[220:223], v[232:235], v[220:223], v[48:51]
	v_mfma_f32_16x16x32_f16 v[202:205], v[202:205], v[228:231], v[36:39]
	v_mfma_f32_16x16x32_f16 v[228:231], v[232:235], v[228:231], v[56:59]
	ds_read_b128 v[232:235], v135 offset:38912
	s_nop 1
	s_waitcnt lgkmcnt(7)
	v_mfma_f32_16x16x32_f16 v[138:141], v[68:71], v[64:67], v[138:141]
	s_waitcnt lgkmcnt(6)
	v_mfma_f32_16x16x32_f16 v[198:201], v[68:71], v[72:75], v[198:201]
	s_waitcnt lgkmcnt(5)
	v_mfma_f32_16x16x32_f16 v[142:145], v[76:79], v[64:67], v[142:145]
	v_mfma_f32_16x16x32_f16 v[158:161], v[76:79], v[72:75], v[158:161]
	s_waitcnt lgkmcnt(4)
	v_mfma_f32_16x16x32_f16 v[166:169], v[68:71], v[80:83], v[166:169]
	v_and_b32_e32 v10, 7, v148
	v_bfe_u32 v11, v148, 4, 3
	v_xor_b32_e32 v11, v11, v10
	v_sub_u32_e32 v11, v11, v10
	v_lshlrev_b32_e32 v10, 4, v11
	v_add_u32_e32 v10, 0x580, v10
	v_ashrrev_i32_e32 v11, 31, v10
	v_add_u32_e32 v28, 0x4000, v101
	v_and_b32_e32 v28, 0xffffff80, v28
	s_nop 0
	v_readfirstlane_b32 s101, v28
	v_lshl_add_u64 v[28:29], v[108:109], 0, v[10:11]
	s_mov_b32 m0, s101
	s_nop 0
	global_load_lds_dwordx4 v[28:29], off
	s_waitcnt lgkmcnt(2)
	v_mfma_f32_16x16x32_f16 v[68:71], v[68:71], v[88:91], v[202:205]
	s_nop 2
	ds_read_b128 v[202:205], v135 offset:32768
	v_add_u32_e32 v24, 0x4000, v131
	v_and_b32_e32 v24, 0xffffff80, v24
	s_nop 0
	v_readfirstlane_b32 s101, v24
	v_lshl_add_u64 v[24:25], v[110:111], 0, v[10:11]
	s_mov_b32 m0, s101
	s_nop 0
	global_load_lds_dwordx4 v[24:25], off
	v_mfma_f32_16x16x32_f16 v[190:193], v[76:79], v[80:83], v[190:193]
	v_add_u32_e32 v12, 0x4000, v132
	v_and_b32_e32 v12, 0xffffff80, v12
	s_nop 0
	v_readfirstlane_b32 s101, v12
	v_lshl_add_u64 v[12:13], v[112:113], 0, v[10:11]
	s_mov_b32 m0, s101
	s_nop 0
	global_load_lds_dwordx4 v[12:13], off
	v_add_u32_e32 v16, 0x4000, v130
	v_and_b32_e32 v16, 0xffffff80, v16
	s_nop 0
	v_readfirstlane_b32 s101, v16
	v_lshl_add_u64 v[16:17], v[114:115], 0, v[10:11]
	s_mov_b32 m0, s101
	s_nop 0
	global_load_lds_dwordx4 v[16:17], off
	v_mfma_f32_16x16x32_f16 v[76:79], v[76:79], v[88:91], v[210:213]
	s_nop 2
	ds_read_b128 v[210:213], v135 offset:34816
	v_mfma_f32_16x16x32_f16 v[154:157], v[84:87], v[64:67], v[154:157]
	v_add_u32_e32 v20, 0xc000, v101
	v_and_b32_e32 v20, 0xffffff80, v20
	s_nop 0
	v_readfirstlane_b32 s101, v20
	v_lshl_add_u64 v[20:21], v[116:117], 0, v[10:11]
	s_mov_b32 m0, s101
	s_nop 0
	global_load_lds_dwordx4 v[20:21], off
	v_mfma_f32_16x16x32_f16 v[162:165], v[84:87], v[72:75], v[162:165]
	v_add_u32_e32 v0, 0xc000, v131
	v_and_b32_e32 v0, 0xffffff80, v0
	s_nop 0
	v_readfirstlane_b32 s101, v0
	v_lshl_add_u64 v[0:1], v[118:119], 0, v[10:11]
	s_mov_b32 m0, s101
	s_nop 0
	global_load_lds_dwordx4 v[0:1], off
	s_waitcnt lgkmcnt(3)
	v_mfma_f32_16x16x32_f16 v[64:67], v[92:95], v[64:67], v[236:239]
	v_add_u32_e32 v4, 0xc000, v132
	v_and_b32_e32 v4, 0xffffff80, v4
	s_nop 0
	v_readfirstlane_b32 s101, v4
	v_lshl_add_u64 v[4:5], v[120:121], 0, v[10:11]
	s_mov_b32 m0, s101
	s_nop 0
	global_load_lds_dwordx4 v[4:5], off
	v_mfma_f32_16x16x32_f16 v[72:75], v[92:95], v[72:75], v[206:209]
	s_nop 2
	ds_read_b128 v[206:209], v134 offset:2048
	v_mfma_f32_16x16x32_f16 v[194:197], v[84:87], v[80:83], v[194:197]
	v_add_u32_e32 v8, 0xc000, v130
	v_and_b32_e32 v8, 0xffffff80, v8
	s_nop 0
	v_readfirstlane_b32 s101, v8
	v_lshl_add_u64 v[8:9], v[122:123], 0, v[10:11]
	s_mov_b32 m0, s101
	s_nop 0
	global_load_lds_dwordx4 v[8:9], off
	v_mfma_f32_16x16x32_f16 v[84:87], v[84:87], v[88:91], v[224:227]
	s_nop 2
	ds_read_b128 v[224:227], v135 offset:36864
	v_mfma_f32_16x16x32_f16 v[80:83], v[92:95], v[80:83], v[220:223]
	s_nop 2
	ds_read_b128 v[220:223], v134 offset:4096
	v_mfma_f32_16x16x32_f16 v[88:91], v[92:95], v[88:91], v[228:231]
	ds_read_b128 v[92:95], v134
	s_nop 1
	ds_read_b128 v[228:231], v134 offset:6144
	s_waitcnt vmcnt(0) lgkmcnt(0)
	s_barrier
; #define GL_LOAD(s_, kt_) if (VAR != 1) { a##s_##0 = GL_A(0, kt_); a##s_##1 = GL_A(1, kt_); a##s_##2 = GL_A(2, kt_); a##s_##3 = GL_A(3, kt_); b##s_##0 = GL_B(0, kt_); b##s_##1 = GL_B(1, kt_); b##s_##2 = GL_B(2, kt_); b##s_##3 = GL_B(3, kt_); }
; #define LDS_STORE(s_, buf_) if (VAR != 2) { LDS_ST1(sA, 0, buf_, a##s_##0) LDS_ST1(sA, 1, buf_, a##s_##1) LDS_ST1(sA, 2, buf_, a##s_##2) LDS_ST1(sA, 3, buf_, a##s_##3) LDS_ST1(sB, 0, buf_, b##s_##0) LDS_ST1(sB, 1, buf_, b##s_##1) LDS_ST1(sB, 2, buf_, b##s_##2) LDS_ST1(sB, 3, buf_, b##s_##3) }
;     ...
;   GL_LOAD(0, 0)
;   GL_LOAD(1, 1)
;   LDS_STORE(0, 0)
;   if (VAR != 4) __syncthreads();
; #pragma unroll
;   for (int kt = 0; kt < nk; kt += 2) {
;     if (kt + 2 < nk) { GL_LOAD(0, kt + 2) }
;     MMA_TILE(0)
;     LDS_STORE(1, 1)
;     if (VAR != 4) __syncthreads();
;     if (kt + 3 < nk) { GL_LOAD(1, kt + 3) }
;     MMA_TILE(1)
;     if (kt + 2 < nk) { LDS_STORE(0, 0) }
;     if (VAR != 4) __syncthreads();
;   }
	v_mfma_f32_16x16x32_f16 v[138:141], v[202:205], v[92:95], v[138:141]
	v_mfma_f32_16x16x32_f16 v[142:145], v[210:213], v[92:95], v[142:145]
	v_mfma_f32_16x16x32_f16 v[154:157], v[224:227], v[92:95], v[154:157]
	v_mfma_f32_16x16x32_f16 v[64:67], v[232:235], v[92:95], v[64:67]
	v_mfma_f32_16x16x32_f16 v[92:95], v[202:205], v[206:209], v[198:201]
	s_nop 2
	ds_read_b128 v[198:201], v133 offset:16384
	v_mfma_f32_16x16x32_f16 v[158:161], v[210:213], v[206:209], v[158:161]
	v_mfma_f32_16x16x32_f16 v[166:169], v[202:205], v[220:223], v[166:169]
	v_mfma_f32_16x16x32_f16 v[68:71], v[202:205], v[228:231], v[68:71]
	ds_read_b128 v[202:205], v136 offset:49152
	v_mfma_f32_16x16x32_f16 v[190:193], v[210:213], v[220:223], v[190:193]
	v_mfma_f32_16x16x32_f16 v[76:79], v[210:213], v[228:231], v[76:79]
	ds_read_b128 v[210:213], v136 offset:51200
	v_mfma_f32_16x16x32_f16 v[162:165], v[224:227], v[206:209], v[162:165]
	v_mfma_f32_16x16x32_f16 v[72:75], v[232:235], v[206:209], v[72:75]
	ds_read_b128 v[206:209], v133 offset:18432
	v_mfma_f32_16x16x32_f16 v[194:197], v[224:227], v[220:223], v[194:197]
	v_and_b32_e32 v38, 7, v148
	v_bfe_u32 v39, v148, 4, 3
	v_xor_b32_e32 v39, v39, v38
	v_sub_u32_e32 v39, v39, v38
	v_lshlrev_b32_e32 v38, 4, v39
	v_add_u32_e32 v38, 0x600, v38
	v_ashrrev_i32_e32 v39, 31, v38
	v_mfma_f32_16x16x32_f16 v[84:87], v[224:227], v[228:231], v[84:87]
	ds_read_b128 v[224:227], v136 offset:53248
	v_mfma_f32_16x16x32_f16 v[80:83], v[232:235], v[220:223], v[80:83]
	ds_read_b128 v[220:223], v133 offset:20480
	v_mfma_f32_16x16x32_f16 v[88:91], v[232:235], v[228:231], v[88:91]
	ds_read_b128 v[228:231], v133 offset:22528
	s_waitcnt lgkmcnt(5)
	v_mfma_f32_16x16x32_f16 v[138:141], v[202:205], v[198:201], v[138:141]
	ds_read_b128 v[232:235], v136 offset:55296
	s_waitcnt lgkmcnt(4)
	v_mfma_f32_16x16x32_f16 v[92:95], v[202:205], v[206:209], v[92:95]
	v_mov_b32_e32 v52, v101
	v_and_b32_e32 v52, 0xffffff80, v52
	s_nop 0
	v_readfirstlane_b32 s101, v52
	v_lshl_add_u64 v[52:53], v[108:109], 0, v[38:39]
	s_mov_b32 m0, s101
	s_nop 0
	global_load_lds_dwordx4 v[52:53], off
	v_mfma_f32_16x16x32_f16 v[142:145], v[210:213], v[198:201], v[142:145]
	v_mov_b32_e32 v56, v131
	v_and_b32_e32 v56, 0xffffff80, v56
	s_nop 0
	v_readfirstlane_b32 s101, v56
	v_lshl_add_u64 v[56:57], v[110:111], 0, v[38:39]
	s_mov_b32 m0, s101
	s_nop 0
	global_load_lds_dwordx4 v[56:57], off
	v_mfma_f32_16x16x32_f16 v[158:161], v[210:213], v[206:209], v[158:161]
	v_mov_b32_e32 v60, v132
	v_and_b32_e32 v60, 0xffffff80, v60
	s_nop 0
	v_readfirstlane_b32 s101, v60
	v_lshl_add_u64 v[60:61], v[112:113], 0, v[38:39]
	s_mov_b32 m0, s101
	s_nop 0
	global_load_lds_dwordx4 v[60:61], off
	s_waitcnt lgkmcnt(2)
	v_mfma_f32_16x16x32_f16 v[166:169], v[202:205], v[220:223], v[166:169]
	v_mov_b32_e32 v40, v130
	v_and_b32_e32 v40, 0xffffff80, v40
	s_nop 0
	v_readfirstlane_b32 s101, v40
	v_lshl_add_u64 v[40:41], v[114:115], 0, v[38:39]
	s_mov_b32 m0, s101
	s_nop 0
	global_load_lds_dwordx4 v[40:41], off
	s_waitcnt lgkmcnt(1)
	v_mfma_f32_16x16x32_f16 v[68:71], v[202:205], v[228:231], v[68:71]
	ds_read_b128 v[202:205], v135 offset:49152
	v_mfma_f32_16x16x32_f16 v[190:193], v[210:213], v[220:223], v[190:193]
	v_add_u32_e32 v44, 0x8000, v101
	v_and_b32_e32 v44, 0xffffff80, v44
	s_nop 0
	v_readfirstlane_b32 s101, v44
	v_lshl_add_u64 v[44:45], v[116:117], 0, v[38:39]
	s_mov_b32 m0, s101
	s_nop 0
	global_load_lds_dwordx4 v[44:45], off
	v_mfma_f32_16x16x32_f16 v[76:79], v[210:213], v[228:231], v[76:79]
	ds_read_b128 v[210:213], v135 offset:51200
	v_mfma_f32_16x16x32_f16 v[154:157], v[224:227], v[198:201], v[154:157]
	v_add_u32_e32 v48, 0x8000, v131
	v_and_b32_e32 v48, 0xffffff80, v48
	s_nop 0
	v_readfirstlane_b32 s101, v48
	v_lshl_add_u64 v[48:49], v[118:119], 0, v[38:39]
	s_mov_b32 m0, s101
	s_nop 0
	global_load_lds_dwordx4 v[48:49], off
	v_mfma_f32_16x16x32_f16 v[162:165], v[224:227], v[206:209], v[162:165]
	v_add_u32_e32 v32, 0x8000, v132
	v_and_b32_e32 v32, 0xffffff80, v32
	s_nop 0
	v_readfirstlane_b32 s101, v32
	v_lshl_add_u64 v[32:33], v[120:121], 0, v[38:39]
	s_mov_b32 m0, s101
	s_nop 0
	global_load_lds_dwordx4 v[32:33], off
	s_waitcnt lgkmcnt(2)
	v_mfma_f32_16x16x32_f16 v[64:67], v[232:235], v[198:201], v[64:67]
	ds_read_b128 v[198:201], v134 offset:16384
	v_mfma_f32_16x16x32_f16 v[72:75], v[232:235], v[206:209], v[72:75]
	ds_read_b128 v[206:209], v134 offset:18432
	v_mfma_f32_16x16x32_f16 v[194:197], v[224:227], v[220:223], v[194:197]
	v_add_u32_e32 v36, 0x8000, v130
	v_and_b32_e32 v36, 0xffffff80, v36
	s_nop 0
	v_readfirstlane_b32 s101, v36
	v_lshl_add_u64 v[36:37], v[122:123], 0, v[38:39]
	s_mov_b32 m0, s101
	s_nop 0
	global_load_lds_dwordx4 v[36:37], off
	v_mfma_f32_16x16x32_f16 v[84:87], v[224:227], v[228:231], v[84:87]
	ds_read_b128 v[224:227], v135 offset:53248
	v_mfma_f32_16x16x32_f16 v[80:83], v[232:235], v[220:223], v[80:83]
	ds_read_b128 v[220:223], v134 offset:20480
	v_mfma_f32_16x16x32_f16 v[88:91], v[232:235], v[228:231], v[88:91]
	ds_read_b128 v[228:231], v134 offset:22528
	ds_read_b128 v[232:235], v135 offset:55296
	s_waitcnt vmcnt(0) lgkmcnt(0)
	s_barrier
; #define GL_LOAD(s_, kt_) if (VAR != 1) { a##s_##0 = GL_A(0, kt_); a##s_##1 = GL_A(1, kt_); a##s_##2 = GL_A(2, kt_); a##s_##3 = GL_A(3, kt_); b##s_##0 = GL_B(0, kt_); b##s_##1 = GL_B(1, kt_); b##s_##2 = GL_B(2, kt_); b##s_##3 = GL_B(3, kt_); }
; #define LDS_STORE(s_, buf_) if (VAR != 2) { LDS_ST1(sA, 0, buf_, a##s_##0) LDS_ST1(sA, 1, buf_, a##s_##1) LDS_ST1(sA, 2, buf_, a##s_##2) LDS_ST1(sA, 3, buf_, a##s_##3) LDS_ST1(sB, 0, buf_, b##s_##0) LDS_ST1(sB, 1, buf_, b##s_##1) LDS_ST1(sB, 2, buf_, b##s_##2) LDS_ST1(sB, 3, buf_, b##s_##3) }
;     ...
;   GL_LOAD(0, 0)
;   GL_LOAD(1, 1)
;   LDS_STORE(0, 0)
;   if (VAR != 4) __syncthreads();
; #pragma unroll
;   for (int kt = 0; kt < nk; kt += 2) {
;     if (kt + 2 < nk) { GL_LOAD(0, kt + 2) }
;     MMA_TILE(0)
;     LDS_STORE(1, 1)
;     if (VAR != 4) __syncthreads();
;     if (kt + 3 < nk) { GL_LOAD(1, kt + 3) }
;     MMA_TILE(1)
;     if (kt + 2 < nk) { LDS_STORE(0, 0) }
;     if (VAR != 4) __syncthreads();
;   }
	v_mfma_f32_16x16x32_f16 v[138:141], v[202:205], v[198:201], v[138:141]
	v_and_b32_e32 v6, 7, v148
	v_bfe_u32 v7, v148, 4, 3
	v_xor_b32_e32 v7, v7, v6
	v_sub_u32_e32 v7, v7, v6
	v_lshlrev_b32_e32 v6, 4, v7
	v_add_u32_e32 v6, 0x680, v6
	v_ashrrev_i32_e32 v7, 31, v6
	v_mfma_f32_16x16x32_f16 v[92:95], v[202:205], v[206:209], v[92:95]
	global_load_dwordx4 v[60:63], v[108:109], off offset:1792
	v_mfma_f32_16x16x32_f16 v[142:145], v[210:213], v[198:201], v[142:145]
	global_load_dwordx4 v[48:51], v[110:111], off offset:1792
	v_mfma_f32_16x16x32_f16 v[158:161], v[210:213], v[206:209], v[158:161]
	global_load_dwordx4 v[52:55], v[112:113], off offset:1792
	v_mfma_f32_16x16x32_f16 v[166:169], v[202:205], v[220:223], v[166:169]
	global_load_dwordx4 v[56:59], v[114:115], off offset:1792
	v_mfma_f32_16x16x32_f16 v[68:71], v[202:205], v[228:231], v[68:71]
	ds_read_b128 v[202:205], v136 offset:32768
	v_mfma_f32_16x16x32_f16 v[190:193], v[210:213], v[220:223], v[190:193]
	global_load_dwordx4 v[36:39], v[116:117], off offset:1792
	v_mfma_f32_16x16x32_f16 v[76:79], v[210:213], v[228:231], v[76:79]
	ds_read_b128 v[210:213], v136 offset:34816
	v_mfma_f32_16x16x32_f16 v[154:157], v[224:227], v[198:201], v[154:157]
	global_load_dwordx4 v[40:43], v[118:119], off offset:1792
	v_mfma_f32_16x16x32_f16 v[162:165], v[224:227], v[206:209], v[162:165]
	global_load_dwordx4 v[44:47], v[120:121], off offset:1792
	v_mfma_f32_16x16x32_f16 v[64:67], v[232:235], v[198:201], v[64:67]
	ds_read_b128 v[198:201], v133
	v_mfma_f32_16x16x32_f16 v[72:75], v[232:235], v[206:209], v[72:75]
	ds_read_b128 v[206:209], v133 offset:2048
	v_mfma_f32_16x16x32_f16 v[194:197], v[224:227], v[220:223], v[194:197]
	global_load_dwordx4 v[32:35], v[122:123], off offset:1792
	v_mfma_f32_16x16x32_f16 v[84:87], v[224:227], v[228:231], v[84:87]
	ds_read_b128 v[224:227], v136 offset:36864
	v_mfma_f32_16x16x32_f16 v[80:83], v[232:235], v[220:223], v[80:83]
	ds_read_b128 v[220:223], v133 offset:4096
	v_mfma_f32_16x16x32_f16 v[88:91], v[232:235], v[228:231], v[88:91]
	ds_read_b128 v[228:231], v133 offset:6144
	s_waitcnt lgkmcnt(4)
	v_mfma_f32_16x16x32_f16 v[138:141], v[202:205], v[198:201], v[138:141]
	ds_read_b128 v[232:235], v136 offset:38912
	s_waitcnt lgkmcnt(4)
	v_mfma_f32_16x16x32_f16 v[92:95], v[202:205], v[206:209], v[92:95]
	v_add_u32_e32 v20, 0x4000, v101
	v_and_b32_e32 v20, 0xffffff80, v20
	s_nop 0
	v_readfirstlane_b32 s101, v20
	v_lshl_add_u64 v[20:21], v[108:109], 0, v[6:7]
	s_mov_b32 m0, s101
	s_nop 0
	global_load_lds_dwordx4 v[20:21], off
	v_mfma_f32_16x16x32_f16 v[142:145], v[210:213], v[198:201], v[142:145]
	v_add_u32_e32 v24, 0x4000, v131
	v_and_b32_e32 v24, 0xffffff80, v24
	s_nop 0
	v_readfirstlane_b32 s101, v24
	v_lshl_add_u64 v[24:25], v[110:111], 0, v[6:7]
	s_mov_b32 m0, s101
	s_nop 0
	global_load_lds_dwordx4 v[24:25], off
	v_mfma_f32_16x16x32_f16 v[158:161], v[210:213], v[206:209], v[158:161]
	v_add_u32_e32 v28, 0x4000, v132
	v_and_b32_e32 v28, 0xffffff80, v28
	s_nop 0
	v_readfirstlane_b32 s101, v28
	v_lshl_add_u64 v[28:29], v[112:113], 0, v[6:7]
	s_mov_b32 m0, s101
	s_nop 0
	global_load_lds_dwordx4 v[28:29], off
	s_waitcnt lgkmcnt(2)
	v_mfma_f32_16x16x32_f16 v[166:169], v[202:205], v[220:223], v[166:169]
	v_add_u32_e32 v8, 0x4000, v130
	v_and_b32_e32 v8, 0xffffff80, v8
	s_nop 0
	v_readfirstlane_b32 s101, v8
	v_lshl_add_u64 v[8:9], v[114:115], 0, v[6:7]
	s_mov_b32 m0, s101
	s_nop 0
	global_load_lds_dwordx4 v[8:9], off
	s_waitcnt lgkmcnt(1)
	v_mfma_f32_16x16x32_f16 v[68:71], v[202:205], v[228:231], v[68:71]
	ds_read_b128 v[202:205], v135 offset:32768
	v_mfma_f32_16x16x32_f16 v[190:193], v[210:213], v[220:223], v[190:193]
	v_add_u32_e32 v12, 0xc000, v101
	v_and_b32_e32 v12, 0xffffff80, v12
	s_nop 0
	v_readfirstlane_b32 s101, v12
	v_lshl_add_u64 v[12:13], v[116:117], 0, v[6:7]
	s_mov_b32 m0, s101
	s_nop 0
	global_load_lds_dwordx4 v[12:13], off
	v_mfma_f32_16x16x32_f16 v[76:79], v[210:213], v[228:231], v[76:79]
	ds_read_b128 v[210:213], v135 offset:34816
	v_mfma_f32_16x16x32_f16 v[154:157], v[224:227], v[198:201], v[154:157]
	v_add_u32_e32 v16, 0xc000, v131
	v_and_b32_e32 v16, 0xffffff80, v16
	s_nop 0
	v_readfirstlane_b32 s101, v16
	v_lshl_add_u64 v[16:17], v[118:119], 0, v[6:7]
	s_mov_b32 m0, s101
	s_nop 0
	global_load_lds_dwordx4 v[16:17], off
	v_mfma_f32_16x16x32_f16 v[162:165], v[224:227], v[206:209], v[162:165]
	v_add_u32_e32 v0, 0xc000, v132
	v_and_b32_e32 v0, 0xffffff80, v0
	s_nop 0
	v_readfirstlane_b32 s101, v0
	v_lshl_add_u64 v[0:1], v[120:121], 0, v[6:7]
	s_mov_b32 m0, s101
	s_nop 0
	global_load_lds_dwordx4 v[0:1], off
	s_waitcnt lgkmcnt(2)
	v_mfma_f32_16x16x32_f16 v[64:67], v[232:235], v[198:201], v[64:67]
	ds_read_b128 v[198:201], v134
	v_mfma_f32_16x16x32_f16 v[72:75], v[232:235], v[206:209], v[72:75]
	ds_read_b128 v[206:209], v134 offset:2048
	v_mfma_f32_16x16x32_f16 v[194:197], v[224:227], v[220:223], v[194:197]
	v_add_u32_e32 v4, 0xc000, v130
	v_and_b32_e32 v4, 0xffffff80, v4
	s_nop 0
	v_readfirstlane_b32 s101, v4
	v_lshl_add_u64 v[4:5], v[122:123], 0, v[6:7]
	s_mov_b32 m0, s101
	s_nop 0
	global_load_lds_dwordx4 v[4:5], off
	v_mfma_f32_16x16x32_f16 v[84:87], v[224:227], v[228:231], v[84:87]
	ds_read_b128 v[224:227], v135 offset:36864
	v_mfma_f32_16x16x32_f16 v[80:83], v[232:235], v[220:223], v[80:83]
	ds_read_b128 v[220:223], v134 offset:4096
	v_mfma_f32_16x16x32_f16 v[88:91], v[232:235], v[228:231], v[88:91]
	ds_read_b128 v[228:231], v134 offset:6144
	ds_read_b128 v[232:235], v135 offset:38912
	s_waitcnt vmcnt(0) lgkmcnt(0)
	s_barrier
; #define GL_LOAD(s_, kt_) if (VAR != 1) { a##s_##0 = GL_A(0, kt_); a##s_##1 = GL_A(1, kt_); a##s_##2 = GL_A(2, kt_); a##s_##3 = GL_A(3, kt_); b##s_##0 = GL_B(0, kt_); b##s_##1 = GL_B(1, kt_); b##s_##2 = GL_B(2, kt_); b##s_##3 = GL_B(3, kt_); }
; #define LDS_STORE(s_, buf_) if (VAR != 2) { LDS_ST1(sA, 0, buf_, a##s_##0) LDS_ST1(sA, 1, buf_, a##s_##1) LDS_ST1(sA, 2, buf_, a##s_##2) LDS_ST1(sA, 3, buf_, a##s_##3) LDS_ST1(sB, 0, buf_, b##s_##0) LDS_ST1(sB, 1, buf_, b##s_##1) LDS_ST1(sB, 2, buf_, b##s_##2) LDS_ST1(sB, 3, buf_, b##s_##3) }
;     ...
;   for (int kt = 0; kt < nk; kt += 2) {
;     if (kt + 2 < nk) { GL_LOAD(0, kt + 2) }
;     MMA_TILE(0)
;     LDS_STORE(1, 1)
;     if (VAR != 4) __syncthreads();
;     if (kt + 3 < nk) { GL_LOAD(1, kt + 3) }
;     MMA_TILE(1)
;     if (kt + 2 < nk) { LDS_STORE(0, 0) }
;     if (VAR != 4) __syncthreads();
;   }
	v_mfma_f32_16x16x32_f16 v[138:141], v[202:205], v[198:201], v[138:141]
	global_load_dwordx4 v[28:31], v[108:109], off offset:1920
	v_mfma_f32_16x16x32_f16 v[92:95], v[202:205], v[206:209], v[92:95]
	global_load_dwordx4 v[16:19], v[110:111], off offset:1920
	v_mfma_f32_16x16x32_f16 v[142:145], v[210:213], v[198:201], v[142:145]
	ds_read_b128 v[108:111], v133 offset:16384
	v_mfma_f32_16x16x32_f16 v[158:161], v[210:213], v[206:209], v[158:161]
	global_load_dwordx4 v[20:23], v[112:113], off offset:1920
	v_mfma_f32_16x16x32_f16 v[166:169], v[202:205], v[220:223], v[166:169]
	global_load_dwordx4 v[24:27], v[114:115], off offset:1920
	v_mfma_f32_16x16x32_f16 v[68:71], v[202:205], v[228:231], v[68:71]
	ds_read_b128 v[112:115], v136 offset:49152
	v_mfma_f32_16x16x32_f16 v[190:193], v[210:213], v[220:223], v[190:193]
	ds_read_b128 v[202:205], v136 offset:53248
	v_mfma_f32_16x16x32_f16 v[76:79], v[210:213], v[228:231], v[76:79]
	ds_read_b128 v[210:213], v136 offset:55296
	v_mfma_f32_16x16x32_f16 v[154:157], v[224:227], v[198:201], v[154:157]
	global_load_dwordx4 v[4:7], v[116:117], off offset:1920
	v_mfma_f32_16x16x32_f16 v[162:165], v[224:227], v[206:209], v[162:165]
	global_load_dwordx4 v[8:11], v[118:119], off offset:1920
	v_mfma_f32_16x16x32_f16 v[64:67], v[232:235], v[198:201], v[64:67]
	ds_read_b128 v[116:119], v133 offset:18432
	v_mfma_f32_16x16x32_f16 v[72:75], v[232:235], v[206:209], v[72:75]
	ds_read_b128 v[198:201], v133 offset:20480
	v_mfma_f32_16x16x32_f16 v[194:197], v[224:227], v[220:223], v[194:197]
	ds_read_b128 v[206:209], v133 offset:22528
	v_mfma_f32_16x16x32_f16 v[84:87], v[224:227], v[228:231], v[84:87]
	global_load_dwordx4 v[12:15], v[120:121], off offset:1920
	v_mfma_f32_16x16x32_f16 v[80:83], v[232:235], v[220:223], v[80:83]
	global_load_dwordx4 v[0:3], v[122:123], off offset:1920
	v_mfma_f32_16x16x32_f16 v[88:91], v[232:235], v[228:231], v[88:91]
	ds_read_b128 v[120:123], v136 offset:51200
	s_waitcnt lgkmcnt(6)
	v_mfma_f32_16x16x32_f16 v[138:141], v[112:115], v[108:111], v[138:141]
	ds_write_b128 v101, v[60:63]
	s_waitcnt lgkmcnt(4)
	v_mfma_f32_16x16x32_f16 v[92:95], v[112:115], v[116:119], v[92:95]
	ds_write_b128 v131, v[48:51]
	s_waitcnt lgkmcnt(2)
	v_mfma_f32_16x16x32_f16 v[142:145], v[120:123], v[108:111], v[142:145]
	ds_write_b128 v132, v[52:55]
	v_mfma_f32_16x16x32_f16 v[154:157], v[202:205], v[108:111], v[154:157]
	v_mfma_f32_16x16x32_f16 v[64:67], v[210:213], v[108:111], v[64:67]
	v_mfma_f32_16x16x32_f16 v[108:111], v[120:123], v[116:119], v[158:161]
	ds_write_b128 v130, v[56:59]
	v_mfma_f32_16x16x32_f16 v[158:161], v[202:205], v[116:119], v[162:165]
	v_mfma_f32_16x16x32_f16 v[72:75], v[210:213], v[116:119], v[72:75]
	v_mfma_f32_16x16x32_f16 v[116:119], v[112:115], v[198:201], v[166:169]
	ds_write_b128 v101, v[36:39] offset:32768
	ds_write_b128 v131, v[40:43] offset:32768
	v_mfma_f32_16x16x32_f16 v[68:71], v[112:115], v[206:209], v[68:71]
	ds_read_b128 v[112:115], v134 offset:16384
	ds_write_b128 v132, v[44:47] offset:32768
	v_mfma_f32_16x16x32_f16 v[162:165], v[120:123], v[198:201], v[190:193]
	s_nop 2
	ds_read_b128 v[190:193], v134 offset:18432
	v_mfma_f32_16x16x32_f16 v[76:79], v[120:123], v[206:209], v[76:79]
	ds_read_b128 v[120:123], v135 offset:49152
	ds_write_b128 v130, v[32:35] offset:32768
	v_mfma_f32_16x16x32_f16 v[166:169], v[202:205], v[198:201], v[194:197]
	s_nop 2
	ds_read_b128 v[194:197], v135 offset:51200
	v_mfma_f32_16x16x32_f16 v[84:87], v[202:205], v[206:209], v[84:87]
	ds_read_b128 v[202:205], v135 offset:53248
	v_mfma_f32_16x16x32_f16 v[80:83], v[210:213], v[198:201], v[80:83]
	ds_read_b128 v[198:201], v134 offset:20480
	v_mfma_f32_16x16x32_f16 v[88:91], v[210:213], v[206:209], v[88:91]
	ds_read_b128 v[206:209], v134 offset:22528
	s_waitcnt lgkmcnt(5)
	v_mfma_f32_16x16x32_f16 v[138:141], v[120:123], v[112:115], v[138:141]
	ds_read_b128 v[210:213], v135 offset:55296
	s_waitcnt lgkmcnt(0)
	s_barrier
	v_mfma_f32_16x16x32_f16 v[142:145], v[194:197], v[112:115], v[142:145]
	ds_read_b128 v[32:35], v133
	v_mfma_f32_16x16x32_f16 v[108:111], v[194:197], v[190:193], v[108:111]
	ds_read_b128 v[36:39], v136 offset:32768
	v_mfma_f32_16x16x32_f16 v[154:157], v[202:205], v[112:115], v[154:157]
	ds_read_b128 v[40:43], v133 offset:2048
	v_mfma_f32_16x16x32_f16 v[64:67], v[210:213], v[112:115], v[64:67]
	v_mfma_f32_16x16x32_f16 v[112:115], v[202:205], v[190:193], v[158:161]
	ds_read_b128 v[44:47], v136 offset:34816
	v_mfma_f32_16x16x32_f16 v[158:161], v[194:197], v[198:201], v[162:165]
	ds_read_b128 v[48:51], v133 offset:4096
	v_mfma_f32_16x16x32_f16 v[76:79], v[194:197], v[206:209], v[76:79]
	ds_read_b128 v[52:55], v136 offset:36864
	v_mfma_f32_16x16x32_f16 v[162:165], v[202:205], v[198:201], v[166:169]
	ds_read_b128 v[56:59], v133 offset:6144
	v_mfma_f32_16x16x32_f16 v[84:87], v[202:205], v[206:209], v[84:87]
	ds_read_b128 v[60:63], v136 offset:38912
	s_waitcnt vmcnt(7)
	ds_write_b128 v101, v[28:31] offset:16384
	v_mfma_f32_16x16x32_f16 v[72:75], v[210:213], v[190:193], v[72:75]
	s_waitcnt vmcnt(6)
	ds_write_b128 v131, v[16:19] offset:16384
	v_mfma_f32_16x16x32_f16 v[92:95], v[120:123], v[190:193], v[92:95]
	s_waitcnt vmcnt(5)
	ds_write_b128 v132, v[20:23] offset:16384
	v_mfma_f32_16x16x32_f16 v[80:83], v[210:213], v[198:201], v[80:83]
	s_waitcnt vmcnt(4)
	ds_write_b128 v130, v[24:27] offset:16384
	v_mfma_f32_16x16x32_f16 v[88:91], v[210:213], v[206:209], v[88:91]
	s_waitcnt vmcnt(3)
	ds_write_b128 v101, v[4:7] offset:49152
	v_mfma_f32_16x16x32_f16 v[116:119], v[120:123], v[198:201], v[116:119]
	s_waitcnt vmcnt(2)
	ds_write_b128 v131, v[8:11] offset:49152
	v_mfma_f32_16x16x32_f16 v[68:71], v[120:123], v[206:209], v[68:71]
	s_waitcnt vmcnt(1)
; #define GL_LOAD(s_, kt_) if (VAR != 1) { a##s_##0 = GL_A(0, kt_); a##s_##1 = GL_A(1, kt_); a##s_##2 = GL_A(2, kt_); a##s_##3 = GL_A(3, kt_); b##s_##0 = GL_B(0, kt_); b##s_##1 = GL_B(1, kt_); b##s_##2 = GL_B(2, kt_); b##s_##3 = GL_B(3, kt_); }
; #define LDS_STORE(s_, buf_) if (VAR != 2) { LDS_ST1(sA, 0, buf_, a##s_##0) LDS_ST1(sA, 1, buf_, a##s_##1) LDS_ST1(sA, 2, buf_, a##s_##2) LDS_ST1(sA, 3, buf_, a##s_##3) LDS_ST1(sB, 0, buf_, b##s_##0) LDS_ST1(sB, 1, buf_, b##s_##1) LDS_ST1(sB, 2, buf_, b##s_##2) LDS_ST1(sB, 3, buf_, b##s_##3) }
;     ...
;   for (int kt = 0; kt < nk; kt += 2) {
;     if (kt + 2 < nk) { GL_LOAD(0, kt + 2) }
;     MMA_TILE(0)
;     LDS_STORE(1, 1)
;     if (VAR != 4) __syncthreads();
;     if (kt + 3 < nk) { GL_LOAD(1, kt + 3) }
;     MMA_TILE(1)
;     if (kt + 2 < nk) { LDS_STORE(0, 0) }
;     if (VAR != 4) __syncthreads();
;   }
	ds_write_b128 v132, v[12:15] offset:49152
	s_waitcnt lgkmcnt(13)
	v_mfma_f32_16x16x32_f16 v[120:123], v[36:39], v[32:35], v[138:141]
	s_waitcnt vmcnt(0)
	ds_write_b128 v130, v[0:3] offset:49152
	s_waitcnt lgkmcnt(12)
	v_mfma_f32_16x16x32_f16 v[138:141], v[44:47], v[32:35], v[142:145]
	s_waitcnt lgkmcnt(10)
	v_mfma_f32_16x16x32_f16 v[142:145], v[52:55], v[32:35], v[154:157]
	s_waitcnt lgkmcnt(8)
	v_mfma_f32_16x16x32_f16 v[32:35], v[60:63], v[32:35], v[64:67]
	v_mfma_f32_16x16x32_f16 v[64:67], v[36:39], v[40:43], v[92:95]
	ds_read_b128 v[154:157], v134 offset:6144
	v_mfma_f32_16x16x32_f16 v[92:95], v[44:47], v[40:43], v[108:111]
	v_mfma_f32_16x16x32_f16 v[108:111], v[52:55], v[40:43], v[112:115]
	v_mfma_f32_16x16x32_f16 v[40:43], v[60:63], v[40:43], v[72:75]
	v_mfma_f32_16x16x32_f16 v[72:75], v[36:39], v[48:51], v[116:119]
	v_mfma_f32_16x16x32_f16 v[36:39], v[36:39], v[56:59], v[68:71]
	s_nop 2
	ds_read_b128 v[68:71], v135 offset:32768
	v_mfma_f32_16x16x32_f16 v[112:115], v[44:47], v[48:51], v[158:161]
	s_nop 2
	ds_read_b128 v[158:161], v135 offset:38912
	v_mfma_f32_16x16x32_f16 v[44:47], v[44:47], v[56:59], v[76:79]
	s_nop 2
	ds_read_b128 v[76:79], v134 offset:2048
	v_mfma_f32_16x16x32_f16 v[116:119], v[52:55], v[48:51], v[162:165]
	v_mfma_f32_16x16x32_f16 v[52:55], v[52:55], v[56:59], v[84:87]
	s_nop 2
	ds_read_b128 v[84:87], v134 offset:4096
	v_mfma_f32_16x16x32_f16 v[48:51], v[60:63], v[48:51], v[80:83]
	s_nop 2
	ds_read_b128 v[80:83], v135 offset:34816
	v_mfma_f32_16x16x32_f16 v[56:59], v[60:63], v[56:59], v[88:91]
	ds_read_b128 v[60:63], v134
	s_waitcnt lgkmcnt(0)
	v_mfma_f32_16x16x32_f16 v[120:123], v[68:71], v[60:63], v[120:123]
	ds_read_b128 v[88:91], v135 offset:36864
	s_waitcnt lgkmcnt(0)
	s_barrier
	v_mfma_f32_16x16x32_f16 v[138:141], v[80:83], v[60:63], v[138:141]
	ds_read_b128 v[0:3], v133 offset:16384
	v_mfma_f32_16x16x32_f16 v[142:145], v[88:91], v[60:63], v[142:145]
	v_mfma_f32_16x16x32_f16 v[32:35], v[158:161], v[60:63], v[32:35]
	v_mfma_f32_16x16x32_f16 v[60:63], v[68:71], v[76:79], v[64:67]
	v_mfma_f32_16x16x32_f16 v[64:67], v[80:83], v[76:79], v[92:95]
	ds_read_b128 v[4:7], v136 offset:49152
	ds_read_b128 v[8:11], v133 offset:18432
	v_mfma_f32_16x16x32_f16 v[92:95], v[88:91], v[76:79], v[108:111]
	ds_read_b128 v[12:15], v136 offset:51200
	v_mfma_f32_16x16x32_f16 v[40:43], v[158:161], v[76:79], v[40:43]
	v_mfma_f32_16x16x32_f16 v[76:79], v[80:83], v[84:87], v[112:115]
	ds_read_b128 v[16:19], v133 offset:20480
	v_mfma_f32_16x16x32_f16 v[44:47], v[80:83], v[154:157], v[44:47]
	ds_read_b128 v[20:23], v136 offset:53248
	v_mfma_f32_16x16x32_f16 v[108:111], v[88:91], v[84:87], v[116:119]
	ds_read_b128 v[24:27], v133 offset:22528
	v_mfma_f32_16x16x32_f16 v[52:55], v[88:91], v[154:157], v[52:55]
	ds_read_b128 v[28:31], v136 offset:55296
	ds_read_b128 v[112:115], v135 offset:53248
	ds_read_b128 v[116:119], v134 offset:22528
	v_ashrrev_i32_e32 v101, 31, v100
	v_mfma_f32_16x16x32_f16 v[48:51], v[158:161], v[84:87], v[48:51]
	v_mfma_f32_16x16x32_f16 v[56:59], v[158:161], v[154:157], v[56:59]
	v_mfma_f32_16x16x32_f16 v[72:75], v[68:71], v[84:87], v[72:75]
	v_mfma_f32_16x16x32_f16 v[36:39], v[68:71], v[154:157], v[36:39]
	s_waitcnt lgkmcnt(8)
	v_mfma_f32_16x16x32_f16 v[68:71], v[4:7], v[0:3], v[120:123]
	s_nop 2
	ds_read_b128 v[120:123], v135 offset:55296
	s_waitcnt lgkmcnt(7)
	v_mfma_f32_16x16x32_f16 v[80:83], v[12:15], v[0:3], v[138:141]
	s_waitcnt lgkmcnt(5)
	v_mfma_f32_16x16x32_f16 v[84:87], v[20:23], v[0:3], v[142:145]
	s_waitcnt lgkmcnt(3)
	v_mfma_f32_16x16x32_f16 v[0:3], v[28:31], v[0:3], v[32:35]
	v_mfma_f32_16x16x32_f16 v[32:35], v[4:7], v[8:11], v[60:63]
	v_mfma_f32_16x16x32_f16 v[60:63], v[12:15], v[8:11], v[64:67]
	v_mfma_f32_16x16x32_f16 v[72:75], v[4:7], v[16:19], v[72:75]
	v_mfma_f32_16x16x32_f16 v[76:79], v[12:15], v[16:19], v[76:79]
	v_mfma_f32_16x16x32_f16 v[44:47], v[12:15], v[24:27], v[44:47]
	ds_read_b128 v[12:15], v134 offset:16384
	v_mfma_f32_16x16x32_f16 v[64:67], v[20:23], v[8:11], v[92:95]
	s_nop 2
	ds_read_b128 v[92:95], v135 offset:51200
	v_mfma_f32_16x16x32_f16 v[88:91], v[20:23], v[16:19], v[108:111]
	s_nop 2
	ds_read_b128 v[108:111], v134 offset:20480
	v_mfma_f32_16x16x32_f16 v[16:19], v[28:31], v[16:19], v[48:51]
	v_mfma_f32_16x16x32_f16 v[48:51], v[20:23], v[24:27], v[52:55]
	ds_read_b128 v[20:23], v134 offset:18432
	v_mfma_f32_16x16x32_f16 v[52:55], v[28:31], v[24:27], v[56:59]
	s_nop 2
	ds_read_b128 v[56:59], v135 offset:49152
	s_waitcnt lgkmcnt(0)
	s_barrier
; DI unsigned pack2(float lo, float hi) { f2_t v = {lo, hi}; h2_t b = __builtin_convertvector(v, h2_t); return __builtin_bit_cast(unsigned, b); }
; template <int VAR> DI void phase_up(const Params& P, int l, char* smem) {
;     ...
; #pragma unroll
;     for (int mt = 0; mt < 4; ++mt) {
;       const int row = row0 + mt * 16 + lr;
; #pragma unroll
;       for (int nt = 0; nt < 4; ++nt) {
;         float v[4];
; #pragma unroll
;         for (int j = 0; j < 4; ++j) { const float a = fmaxf(acc[mt][nt][j] * rs[mt], 0.f); v[j] = a * a; }
;         *(uint2*)(U + (size_t)row * DFF + col0 + nt * 16 + 4 * g) = make_uint2(pack2(v[0], v[1]), pack2(v[2], v[3]));
;       }
;     }
	s_setprio 0
	v_mfma_f32_16x16x32_f16 v[4:7], v[4:7], v[24:27], v[36:39]
	v_mfma_f32_16x16x32_f16 v[68:71], v[56:59], v[12:15], v[68:71]
	v_mfma_f32_16x16x32_f16 v[8:11], v[28:31], v[8:11], v[40:43]
	v_mfma_f32_16x16x32_f16 v[80:83], v[92:95], v[12:15], v[80:83]
	v_mfma_f32_16x16x32_f16 v[84:87], v[112:115], v[12:15], v[84:87]
	v_mfma_f32_16x16x32_f16 v[130:133], v[120:123], v[12:15], v[0:3]
	v_mfma_f32_16x16x32_f16 v[12:15], v[56:59], v[116:119], v[4:7]
	v_mfma_f32_16x16x32_f16 v[4:7], v[112:115], v[116:119], v[48:51]
	s_nop 2
	v_mul_f32_e32 v48, v128, v68
	v_mul_f32_e32 v49, v128, v69
	v_mul_f32_e32 v50, v128, v70
	v_mul_f32_e32 v51, v128, v71
	v_max_f32_e32 v48, 0, v48
	v_max_f32_e32 v49, 0, v49
	v_max_f32_e32 v50, 0, v50
	v_max_f32_e32 v51, 0, v51
	v_mfma_f32_16x16x32_f16 v[134:137], v[56:59], v[20:23], v[32:35]
	v_mul_f32_e64 v48, v48, v48
	v_mul_f32_e64 v49, v49, v49
	v_pk_mul_f32 v[50:51], v[50:51], v[50:51]
	v_cvt_pk_f16_f32 v48, v48, v49
	v_mfma_f32_16x16x32_f16 v[32:35], v[120:123], v[20:23], v[8:11]
	v_cvt_pk_f16_f32 v49, v50, v51
	v_mul_f32_e32 v50, v128, v82
	v_mul_f32_e32 v51, v128, v83
	v_mfma_f32_16x16x32_f16 v[8:11], v[92:95], v[116:119], v[44:47]
	v_max_f32_e32 v50, 0, v50
	v_max_f32_e32 v51, 0, v51
	v_pk_mul_f32 v[50:51], v[50:51], v[50:51]
	v_lshl_add_u64 v[44:45], v[100:101], 1, v[96:97]
	v_lshlrev_b64 v[46:47], 13, v[102:103]
	v_lshl_add_u64 v[46:47], v[44:45], 0, v[46:47]
	global_store_dwordx2 v[46:47], v[48:49], off
	v_mul_f32_e32 v48, v128, v80
	v_mul_f32_e32 v49, v128, v81
	v_max_f32_e32 v48, 0, v48
	v_max_f32_e32 v49, 0, v49
	v_pk_mul_f32 v[48:49], v[48:49], v[48:49]
	v_mfma_f32_16x16x32_f16 v[16:19], v[120:123], v[108:111], v[16:19]
	v_cvt_pk_f16_f32 v48, v48, v49
	v_cvt_pk_f16_f32 v49, v50, v51
	global_store_dwordx2 v[46:47], v[48:49], off offset:32
	v_mul_f32_e32 v48, v128, v84
	v_mul_f32_e32 v49, v128, v85
	v_mul_f32_e32 v50, v128, v86
	v_mul_f32_e32 v51, v128, v87
	v_max_f32_e32 v48, 0, v48
	v_max_f32_e32 v49, 0, v49
	v_max_f32_e32 v50, 0, v50
	v_max_f32_e32 v51, 0, v51
	v_pk_mul_f32 v[48:49], v[48:49], v[48:49]
	v_pk_mul_f32 v[50:51], v[50:51], v[50:51]
	v_cvt_pk_f16_f32 v48, v48, v49
	v_cvt_pk_f16_f32 v49, v50, v51
	global_store_dwordx2 v[46:47], v[48:49], off offset:64
	v_mul_f32_e32 v48, v128, v130
	v_mul_f32_e32 v49, v128, v131
	v_mul_f32_e32 v50, v128, v132
	v_mul_f32_e32 v51, v128, v133
	v_max_f32_e32 v48, 0, v48
	v_max_f32_e32 v49, 0, v49
	v_max_f32_e32 v50, 0, v50
	v_max_f32_e32 v51, 0, v51
	v_mfma_f32_16x16x32_f16 v[40:43], v[92:95], v[20:23], v[60:63]
	v_mul_f32_e64 v48, v48, v48
	v_mul_f32_e64 v49, v49, v49
	v_pk_mul_f32 v[50:51], v[50:51], v[50:51]
	v_mul_f32_e32 v32, v126, v32
	v_mfma_f32_16x16x32_f16 v[36:39], v[112:115], v[20:23], v[64:67]
	v_mul_f32_e32 v33, v126, v33
	v_mul_f32_e32 v34, v126, v34
	v_mul_f32_e32 v35, v126, v35
	v_mfma_f32_16x16x32_f16 v[28:31], v[56:59], v[108:111], v[72:75]
	v_cvt_pk_f16_f32 v48, v48, v49
	v_cvt_pk_f16_f32 v49, v50, v51
	v_max_f32_e32 v32, 0, v32
	v_mfma_f32_16x16x32_f16 v[24:27], v[92:95], v[108:111], v[76:79]
	v_max_f32_e32 v33, 0, v33
	v_max_f32_e32 v34, 0, v34
	v_max_f32_e32 v35, 0, v35
	v_mfma_f32_16x16x32_f16 v[20:23], v[112:115], v[108:111], v[88:91]
	global_store_dwordx2 v[46:47], v[48:49], off offset:96
	v_lshlrev_b64 v[46:47], 13, v[98:99]
	v_pk_mul_f32 v[32:33], v[32:33], v[32:33]
	v_mfma_f32_16x16x32_f16 v[0:3], v[120:123], v[116:119], v[52:55]
	v_mul_f32_e64 v34, v34, v34
	v_mul_f32_e64 v35, v35, v35
	v_mul_f32_e32 v16, v129, v16
	v_mul_f32_e32 v17, v129, v17
	v_mul_f32_e32 v18, v129, v18
	v_mul_f32_e32 v19, v129, v19
	v_lshl_add_u64 v[46:47], v[44:45], 0, v[46:47]
	v_cvt_pk_f16_f32 v32, v32, v33
	v_cvt_pk_f16_f32 v33, v34, v35
	v_max_f32_e32 v16, 0, v16
	v_max_f32_e32 v17, 0, v17
	v_max_f32_e32 v18, 0, v18
	v_max_f32_e32 v19, 0, v19
	v_mul_f32_e32 v48, v126, v134
	v_mul_f32_e32 v49, v126, v135
	v_mul_f32_e32 v50, v126, v136
	v_mul_f32_e32 v51, v126, v137
	v_mul_f32_e32 v40, v126, v40
	v_mul_f32_e32 v41, v126, v41
	v_mul_f32_e32 v42, v126, v42
	v_mul_f32_e32 v43, v126, v43
	v_mul_f32_e32 v36, v126, v36
	v_mul_f32_e32 v37, v126, v37
	v_mul_f32_e32 v38, v126, v38
	v_mul_f32_e32 v39, v126, v39
	global_store_dwordx2 v[46:47], v[32:33], off offset:96
	v_lshlrev_b64 v[32:33], 13, v[106:107]
; DI unsigned pack2(float lo, float hi) { f2_t v = {lo, hi}; h2_t b = __builtin_convertvector(v, h2_t); return __builtin_bit_cast(unsigned, b); }
; template <int VAR> DI void phase_up(const Params& P, int l, char* smem) {
;     ...
; #pragma unroll
;     for (int mt = 0; mt < 4; ++mt) {
;       const int row = row0 + mt * 16 + lr;
; #pragma unroll
;       for (int nt = 0; nt < 4; ++nt) {
;         float v[4];
; #pragma unroll
;         for (int j = 0; j < 4; ++j) { const float a = fmaxf(acc[mt][nt][j] * rs[mt], 0.f); v[j] = a * a; }
;         *(uint2*)(U + (size_t)row * DFF + col0 + nt * 16 + 4 * g) = make_uint2(pack2(v[0], v[1]), pack2(v[2], v[3]));
;       }
;     }
	v_mul_f32_e32 v28, v129, v28
	v_mul_f32_e32 v29, v129, v29
	v_mul_f32_e32 v30, v129, v30
	v_mul_f32_e32 v31, v129, v31
	v_mul_f32_e32 v24, v129, v24
	v_mul_f32_e32 v25, v129, v25
	v_mul_f32_e32 v26, v129, v26
	v_mul_f32_e32 v27, v129, v27
	v_mul_f32_e32 v20, v129, v20
	v_mul_f32_e32 v21, v129, v21
	v_mul_f32_e32 v22, v129, v22
	v_mul_f32_e32 v23, v129, v23
	v_pk_mul_f32 v[16:17], v[16:17], v[16:17]
	v_pk_mul_f32 v[18:19], v[18:19], v[18:19]
	v_mul_f32_e32 v12, v127, v12
	v_mul_f32_e32 v13, v127, v13
	v_mul_f32_e32 v14, v127, v14
	v_mul_f32_e32 v15, v127, v15
	v_mul_f32_e32 v8, v127, v8
	v_mul_f32_e32 v9, v127, v9
	v_mul_f32_e32 v10, v127, v10
	v_mul_f32_e32 v11, v127, v11
	v_mul_f32_e32 v4, v127, v4
	v_mul_f32_e32 v5, v127, v5
	v_mul_f32_e32 v6, v127, v6
	v_mul_f32_e32 v7, v127, v7
	v_mul_f32_e32 v0, v127, v0
	v_mul_f32_e32 v1, v127, v1
	v_mul_f32_e32 v2, v127, v2
	v_mul_f32_e32 v3, v127, v3
	v_max_f32_e32 v48, 0, v48
	v_max_f32_e32 v49, 0, v49
	v_max_f32_e32 v50, 0, v50
	v_max_f32_e32 v51, 0, v51
	v_max_f32_e32 v40, 0, v40
	v_max_f32_e32 v41, 0, v41
	v_max_f32_e32 v42, 0, v42
	v_max_f32_e32 v43, 0, v43
	v_max_f32_e32 v36, 0, v36
	v_max_f32_e32 v37, 0, v37
	v_max_f32_e32 v38, 0, v38
	v_max_f32_e32 v39, 0, v39
	v_lshl_add_u64 v[32:33], v[44:45], 0, v[32:33]
	v_max_f32_e32 v28, 0, v28
	v_max_f32_e32 v29, 0, v29
	v_max_f32_e32 v30, 0, v30
	v_max_f32_e32 v31, 0, v31
	v_max_f32_e32 v24, 0, v24
	v_max_f32_e32 v25, 0, v25
	v_max_f32_e32 v26, 0, v26
	v_max_f32_e32 v27, 0, v27
	v_max_f32_e32 v20, 0, v20
	v_max_f32_e32 v21, 0, v21
	v_max_f32_e32 v22, 0, v22
	v_max_f32_e32 v23, 0, v23
	v_cvt_pk_f16_f32 v16, v16, v17
	v_cvt_pk_f16_f32 v17, v18, v19
	v_max_f32_e32 v12, 0, v12
	v_max_f32_e32 v13, 0, v13
	v_max_f32_e32 v14, 0, v14
	v_max_f32_e32 v15, 0, v15
	v_max_f32_e32 v8, 0, v8
	v_max_f32_e32 v9, 0, v9
	v_max_f32_e32 v10, 0, v10
	v_max_f32_e32 v11, 0, v11
	v_max_f32_e32 v4, 0, v4
	v_max_f32_e32 v5, 0, v5
	v_max_f32_e32 v6, 0, v6
	v_max_f32_e32 v7, 0, v7
	v_max_f32_e32 v0, 0, v0
	v_max_f32_e32 v1, 0, v1
	v_max_f32_e32 v2, 0, v2
	v_max_f32_e32 v3, 0, v3
	v_pk_mul_f32 v[48:49], v[48:49], v[48:49]
	v_pk_mul_f32 v[50:51], v[50:51], v[50:51]
	v_pk_mul_f32 v[40:41], v[40:41], v[40:41]
	v_pk_mul_f32 v[42:43], v[42:43], v[42:43]
	v_pk_mul_f32 v[36:37], v[36:37], v[36:37]
	v_pk_mul_f32 v[38:39], v[38:39], v[38:39]
	v_pk_mul_f32 v[28:29], v[28:29], v[28:29]
	v_pk_mul_f32 v[30:31], v[30:31], v[30:31]
	v_pk_mul_f32 v[24:25], v[24:25], v[24:25]
	v_pk_mul_f32 v[26:27], v[26:27], v[26:27]
	v_pk_mul_f32 v[20:21], v[20:21], v[20:21]
	v_pk_mul_f32 v[22:23], v[22:23], v[22:23]
	global_store_dwordx2 v[32:33], v[16:17], off offset:96
	v_lshlrev_b64 v[16:17], 13, v[104:105]
	v_pk_mul_f32 v[12:13], v[12:13], v[12:13]
	v_pk_mul_f32 v[14:15], v[14:15], v[14:15]
	v_pk_mul_f32 v[8:9], v[8:9], v[8:9]
	v_pk_mul_f32 v[10:11], v[10:11], v[10:11]
	v_pk_mul_f32 v[4:5], v[4:5], v[4:5]
	v_pk_mul_f32 v[6:7], v[6:7], v[6:7]
	v_pk_mul_f32 v[0:1], v[0:1], v[0:1]
	v_pk_mul_f32 v[2:3], v[2:3], v[2:3]
	v_cvt_pk_f16_f32 v48, v48, v49
	v_cvt_pk_f16_f32 v49, v50, v51
	v_cvt_pk_f16_f32 v40, v40, v41
	v_cvt_pk_f16_f32 v41, v42, v43
	v_cvt_pk_f16_f32 v36, v36, v37
	v_cvt_pk_f16_f32 v37, v38, v39
	v_cvt_pk_f16_f32 v28, v28, v29
	v_cvt_pk_f16_f32 v29, v30, v31
	v_cvt_pk_f16_f32 v24, v24, v25
	v_cvt_pk_f16_f32 v25, v26, v27
	v_cvt_pk_f16_f32 v20, v20, v21
	v_cvt_pk_f16_f32 v21, v22, v23
	v_lshl_add_u64 v[16:17], v[44:45], 0, v[16:17]
	v_cvt_pk_f16_f32 v12, v12, v13
	v_cvt_pk_f16_f32 v13, v14, v15
	v_cvt_pk_f16_f32 v8, v8, v9
	v_cvt_pk_f16_f32 v9, v10, v11
	v_cvt_pk_f16_f32 v4, v4, v5
	v_cvt_pk_f16_f32 v5, v6, v7
	v_cvt_pk_f16_f32 v0, v0, v1
	v_cvt_pk_f16_f32 v1, v2, v3
	global_store_dwordx2 v[46:47], v[48:49], off
	global_store_dwordx2 v[46:47], v[40:41], off offset:32
	global_store_dwordx2 v[46:47], v[36:37], off offset:64
	global_store_dwordx2 v[32:33], v[28:29], off
	global_store_dwordx2 v[32:33], v[24:25], off offset:32
	global_store_dwordx2 v[32:33], v[20:21], off offset:64
	global_store_dwordx2 v[16:17], v[12:13], off
	global_store_dwordx2 v[16:17], v[8:9], off offset:32
	global_store_dwordx2 v[16:17], v[4:5], off offset:64
	global_store_dwordx2 v[16:17], v[0:1], off offset:96
	s_branch .LBB0_1312

; DI int TIDX() { int t = threadIdx.x; asm volatile("" : "+v"(t)); return t; }
; DI int BIDX() { int b = blockIdx.x; asm volatile("" : "+s"(b)); return b; }
; #define GL_LOAD(s_, kt_) if (VAR != 1) { a##s_##0 = GL_A(0, kt_); a##s_##1 = GL_A(1, kt_); a##s_##2 = GL_A(2, kt_); a##s_##3 = GL_A(3, kt_); b##s_##0 = GL_B(0, kt_); b##s_##1 = GL_B(1, kt_); b##s_##2 = GL_B(2, kt_); b##s_##3 = GL_B(3, kt_); }
; #define LDS_STORE(s_, buf_) if (VAR != 2) { LDS_ST1(sA, 0, buf_, a##s_##0) LDS_ST1(sA, 1, buf_, a##s_##1) LDS_ST1(sA, 2, buf_, a##s_##2) LDS_ST1(sA, 3, buf_, a##s_##3) LDS_ST1(sB, 0, buf_, b##s_##0) LDS_ST1(sB, 1, buf_, b##s_##1) LDS_ST1(sB, 2, buf_, b##s_##2) LDS_ST1(sB, 3, buf_, b##s_##3) }
; DI int tile_groups(int MT, int NT) { return (MT >> 6) * ((NT + 7) >> 3) * 512; }
;   const int tid = TIDX(), lane = tid & 63, wid = tid >> 6, wm = wid >> 1, wn = wid & 1, lr = lane & 15, g = lane >> 4;
;   char* sA = smem; char* sB = smem + 2 * LTILE;
;   uint4 a00 = {}, a01 = {}, a02 = {}, a03 = {}, b00 = {}, b01 = {}, b02 = {}, b03 = {}, a10 = {}, a11 = {}, a12 = {}, a13 = {}, b10 = {}, b11 = {}, b12 = {}, b13 = {};
;   constexpr int nk = NK;
;   const int sw0 = (g ^ ((lr >> 1) & 7)) << 4, sw1 = sw0 ^ 64;
;   const int r0 = tid >> 3, kc = tid & 7, kcs = kc ^ ((r0 >> 1) & 7);
;     ...
;   GL_LOAD(0, 0)
;   GL_LOAD(1, 1)
;   LDS_STORE(0, 0)
;   if (VAR != 4) __syncthreads();
; #pragma unroll
;   for (int kt = 0; kt < nk; kt += 2) {
;     if (kt + 2 < nk) { GL_LOAD(0, kt + 2) }
;     MMA_TILE(0)
;     LDS_STORE(1, 1)
;     if (VAR != 4) __syncthreads();
; DI void phase_resgemm(const Params& P, const bf16_t* A, int K, const bf16_t* Wt, float* ssq_out, const float* xsrc, char* smem) {
;     ...
;   for (int vb = BIDX(); vb < tile_groups(128, 8); vb += gridDim.x) {
;     int tm, tn; if (!tile_of(vb, 128, 8, tm, tn)) continue;
;     const int m0 = tm * 128, n0 = tn * 128;
;     f32x4 acc[4][4]; zero_acc(acc);
;     if (K == 1024) gemm_kloop<false, true, 16>(acc, A + (size_t)m0 * K, K, Wt + (size_t)n0 * K, K, smem);
;     else gemm_kloop<false, true, 64>(acc, A + (size_t)m0 * K, K, Wt + (size_t)n0 * K, K, smem);
.LBB0_1371:
	s_ashr_i32 s1, s2, 3
	s_andn2_b32 s1, s1, 63
	s_and_b32 s4, s9, 56
	s_or_b32 s1, s1, s4
	s_bfe_u32 s4, s2, 0x30003
	s_or_b32 s1, s1, s4
	s_cmpk_gt_i32 s1, 0x7f
	s_cbranch_scc1 .LBB0_1370
	s_lshl_b32 s4, s1, 7
	s_ashr_i32 s5, s4, 31
	v_mov_b32_e32 v58, v148
	s_and_b32 s10, s8, 0x380
	s_lshl_b64 s[12:13], s[4:5], 13
	s_add_u32 s12, s34, s12
	v_ashrrev_i32_e32 v16, 3, v58
	v_ashrrev_i32_e32 v17, 31, v16
	v_add_u32_e32 v18, 32, v16
	s_addc_u32 s13, s35, s13
	v_lshlrev_b64 v[6:7], 13, v[16:17]
	v_lshlrev_b32_e32 v17, 4, v58
	v_ashrrev_i32_e32 v19, 31, v18
	v_add_u32_e32 v20, 64, v16
	s_waitcnt lgkmcnt(0)
	v_lshl_add_u64 v[0:1], s[12:13], 0, v[6:7]
	v_and_b32_e32 v150, 0x70, v17
	v_lshlrev_b64 v[8:9], 13, v[18:19]
	v_ashrrev_i32_e32 v21, 31, v20
	v_add_u32_e32 v54, 0x60, v16
	s_lshl_b32 s1, s10, 13
	v_lshl_add_u64 v[0:1], v[0:1], 0, v[150:151]
	v_lshl_add_u64 v[2:3], s[12:13], 0, v[8:9]
	v_lshlrev_b64 v[46:47], 13, v[20:21]
	v_ashrrev_i32_e32 v55, 31, v54
	s_add_u32 s14, s6, s1
	global_load_dwordx4 v[22:25], v[0:1], off
	v_lshl_add_u64 v[2:3], v[2:3], 0, v[150:151]
	v_lshl_add_u64 v[4:5], s[12:13], 0, v[46:47]
	v_lshlrev_b64 v[50:51], 13, v[54:55]
	s_addc_u32 s15, s7, 0
	global_load_dwordx4 v[26:29], v[2:3], off
	v_lshl_add_u64 v[4:5], v[4:5], 0, v[150:151]
	v_lshl_add_u64 v[10:11], s[12:13], 0, v[50:51]
	global_load_dwordx4 v[30:33], v[4:5], off
	v_lshl_add_u64 v[14:15], v[10:11], 0, v[150:151]
	v_lshl_add_u64 v[6:7], s[14:15], 0, v[6:7]
	global_load_dwordx4 v[34:37], v[14:15], off
	v_lshl_add_u64 v[10:11], v[6:7], 0, v[150:151]
	v_lshl_add_u64 v[6:7], s[14:15], 0, v[8:9]
	global_load_dwordx4 v[38:41], v[10:11], off
	v_lshl_add_u64 v[12:13], v[6:7], 0, v[150:151]
	v_lshl_add_u64 v[6:7], s[14:15], 0, v[46:47]
	global_load_dwordx4 v[42:45], v[12:13], off
	v_lshl_add_u64 v[8:9], v[6:7], 0, v[150:151]
	v_lshl_add_u64 v[6:7], s[14:15], 0, v[50:51]
	global_load_dwordx4 v[46:49], v[8:9], off
	v_lshl_add_u64 v[6:7], v[6:7], 0, v[150:151]
	global_load_dwordx4 v[50:53], v[6:7], off
	v_and_b32_e32 v19, 15, v58
	v_lshlrev_b32_e32 v21, 3, v58
	v_and_b32_e32 v55, 48, v58
	v_lshrrev_b32_e32 v59, 1, v58
	s_waitcnt vmcnt(10)
	v_lshlrev_b32_e32 v60, 7, v58
	v_and_b32_e32 v90, 0x70, v21
	v_bitop3_b32 v134, v21, v55, s23 bitop3:0x6c
	v_bitop3_b32 v21, v17, s23, v58 bitop3:0x48
	v_and_or_b32 v91, v59, s24, v19
	v_and_b32_e32 v130, 0x2780, v60
	global_load_dwordx4 v[58:61], v[0:1], off offset:128
	global_load_dwordx4 v[62:65], v[2:3], off offset:128
	global_load_dwordx4 v[66:69], v[4:5], off offset:128
	global_load_dwordx4 v[70:73], v[14:15], off offset:128
	global_load_dwordx4 v[74:77], v[10:11], off offset:128
	global_load_dwordx4 v[78:81], v[12:13], off offset:128
	global_load_dwordx4 v[82:85], v[8:9], off offset:128
	global_load_dwordx4 v[86:89], v[6:7], off offset:128
	v_lshl_or_b32 v17, v16, 7, v21
	v_or_b32_e32 v16, v130, v134
	v_lshl_or_b32 v18, v18, 7, v21
	v_lshl_or_b32 v19, v20, 7, v21
	v_lshl_or_b32 v20, v54, 7, v21
	v_lshlrev_b32_e32 v54, 7, v91
	v_bitop3_b32 v21, v54, v90, v55 bitop3:0xf6
	s_movk_i32 s1, 0x1000
	v_readlane_b32 s12, v254, 55
	v_readlane_b32 s13, v254, 56
	v_readlane_b32 s14, v254, 57
	v_readlane_b32 s15, v254, 58
	s_waitcnt vmcnt(15)
	ds_write_b128 v17, v[22:25]
	s_waitcnt vmcnt(14)
	ds_write_b128 v18, v[26:29]
	s_waitcnt vmcnt(13)
	ds_write_b128 v19, v[30:33]
	s_waitcnt vmcnt(12)
	ds_write_b128 v20, v[34:37]
	s_waitcnt vmcnt(11)
	ds_write_b128 v17, v[38:41] offset:32768
	s_waitcnt vmcnt(10)
	ds_write_b128 v18, v[42:45] offset:32768
	s_waitcnt vmcnt(9)
	ds_write_b128 v19, v[46:49] offset:32768
	s_waitcnt vmcnt(8)
	ds_write_b128 v20, v[50:53] offset:32768
	s_waitcnt lgkmcnt(0)
	s_barrier
	s_setprio 1
	ds_read_b128 v[22:25], v16 offset:32768
	ds_read_b128 v[30:33], v21
	s_waitcnt lgkmcnt(0)
	v_mfma_f32_16x16x32_f16 v[38:41], v[22:25], v[30:33], 0
	ds_read_b128 v[26:29], v16 offset:34816
	ds_read_b128 v[34:37], v21 offset:2048
	s_waitcnt lgkmcnt(0)
	v_mfma_f32_16x16x32_f16 v[94:97], v[22:25], v[34:37], 0
	ds_read_b128 v[42:45], v16 offset:36864
	ds_read_b128 v[106:109], v21 offset:4096
	s_waitcnt lgkmcnt(0)
	v_mfma_f32_16x16x32_f16 v[114:117], v[22:25], v[106:109], 0
	ds_read_b128 v[50:53], v16 offset:38912
	ds_read_b128 v[110:113], v21 offset:6144
	s_waitcnt lgkmcnt(0)
	v_mfma_f32_16x16x32_f16 v[126:129], v[22:25], v[110:113], 0
	v_xor_b32_e32 v22, 64, v134
	v_mfma_f32_16x16x32_f16 v[46:49], v[26:29], v[30:33], 0
	v_or_b32_e32 v22, v130, v22
	v_mfma_f32_16x16x32_f16 v[90:93], v[42:45], v[30:33], 0
	ds_read_b128 v[130:133], v22 offset:32768
	v_mfma_f32_16x16x32_f16 v[30:33], v[50:53], v[30:33], 0
	ds_read_b128 v[142:145], v22 offset:36864
	v_mfma_f32_16x16x32_f16 v[98:101], v[26:29], v[34:37], 0
	ds_read_b128 v[154:157], v22 offset:38912
	v_mfma_f32_16x16x32_f16 v[102:105], v[42:45], v[34:37], 0
	v_bitop3_b32 v23, v54, v134, 64 bitop3:0xf6
	v_mfma_f32_16x16x32_f16 v[34:37], v[50:53], v[34:37], 0
	ds_read_b128 v[134:137], v23
	v_mfma_f32_16x16x32_f16 v[118:121], v[26:29], v[106:109], 0
	ds_read_b128 v[138:141], v23 offset:2048
	v_mfma_f32_16x16x32_f16 v[122:125], v[42:45], v[106:109], 0
	s_waitcnt vmcnt(7)
	ds_write_b128 v17, v[58:61] offset:16384
	v_mfma_f32_16x16x32_f16 v[106:109], v[50:53], v[106:109], 0
	s_waitcnt vmcnt(6)
	ds_write_b128 v18, v[62:65] offset:16384
	v_mfma_f32_16x16x32_f16 v[24:27], v[26:29], v[110:113], 0
	s_waitcnt vmcnt(5)
	ds_write_b128 v19, v[66:69] offset:16384
	v_mfma_f32_16x16x32_f16 v[42:45], v[42:45], v[110:113], 0
	s_waitcnt vmcnt(4)
	ds_write_b128 v20, v[70:73] offset:16384
	v_mfma_f32_16x16x32_f16 v[50:53], v[50:53], v[110:113], 0
	ds_read_b128 v[110:113], v22 offset:34816
	s_waitcnt lgkmcnt(6)
; #define GL_LOAD(s_, kt_) if (VAR != 1) { a##s_##0 = GL_A(0, kt_); a##s_##1 = GL_A(1, kt_); a##s_##2 = GL_A(2, kt_); a##s_##3 = GL_A(3, kt_); b##s_##0 = GL_B(0, kt_); b##s_##1 = GL_B(1, kt_); b##s_##2 = GL_B(2, kt_); b##s_##3 = GL_B(3, kt_); }
; #define LDS_STORE(s_, buf_) if (VAR != 2) { LDS_ST1(sA, 0, buf_, a##s_##0) LDS_ST1(sA, 1, buf_, a##s_##1) LDS_ST1(sA, 2, buf_, a##s_##2) LDS_ST1(sA, 3, buf_, a##s_##3) LDS_ST1(sB, 0, buf_, b##s_##0) LDS_ST1(sB, 1, buf_, b##s_##1) LDS_ST1(sB, 2, buf_, b##s_##2) LDS_ST1(sB, 3, buf_, b##s_##3) }
;     ...
;   GL_LOAD(0, 0)
;   GL_LOAD(1, 1)
;   LDS_STORE(0, 0)
;   if (VAR != 4) __syncthreads();
; #pragma unroll
;   for (int kt = 0; kt < nk; kt += 2) {
;     if (kt + 2 < nk) { GL_LOAD(0, kt + 2) }
;     MMA_TILE(0)
;     LDS_STORE(1, 1)
;     if (VAR != 4) __syncthreads();
;     if (kt + 3 < nk) { GL_LOAD(1, kt + 3) }
;     MMA_TILE(1)
;     if (kt + 2 < nk) { LDS_STORE(0, 0) }
;     if (VAR != 4) __syncthreads();
	v_mfma_f32_16x16x32_f16 v[38:41], v[130:133], v[134:137], v[38:41]
	s_waitcnt vmcnt(3)
	ds_write_b128 v17, v[74:77] offset:49152
	v_mfma_f32_16x16x32_f16 v[90:93], v[142:145], v[134:137], v[90:93]
	s_waitcnt vmcnt(2)
	ds_write_b128 v18, v[78:81] offset:49152
	v_mfma_f32_16x16x32_f16 v[28:31], v[154:157], v[134:137], v[30:33]
	s_waitcnt vmcnt(1)
	ds_write_b128 v19, v[82:85] offset:49152
	s_waitcnt lgkmcnt(8)
	v_mfma_f32_16x16x32_f16 v[94:97], v[130:133], v[138:141], v[94:97]
	s_waitcnt vmcnt(0)
	ds_write_b128 v20, v[86:89] offset:49152
	v_mfma_f32_16x16x32_f16 v[102:105], v[142:145], v[138:141], v[102:105]
	v_mfma_f32_16x16x32_f16 v[32:35], v[154:157], v[138:141], v[34:37]
	s_waitcnt lgkmcnt(4)
	v_mfma_f32_16x16x32_f16 v[46:49], v[110:113], v[134:137], v[46:49]
	ds_read_b128 v[134:137], v23 offset:4096
	v_mfma_f32_16x16x32_f16 v[98:101], v[110:113], v[138:141], v[98:101]
	ds_read_b128 v[138:141], v23 offset:6144
	s_waitcnt lgkmcnt(1)
	v_mfma_f32_16x16x32_f16 v[114:117], v[130:133], v[134:137], v[114:117]
	s_waitcnt lgkmcnt(0)
	v_mfma_f32_16x16x32_f16 v[126:129], v[130:133], v[138:141], v[126:129]
	global_load_dwordx4 v[130:133], v[0:1], off offset:256
	v_mfma_f32_16x16x32_f16 v[118:121], v[110:113], v[134:137], v[118:121]
	v_mfma_f32_16x16x32_f16 v[24:27], v[110:113], v[138:141], v[24:27]
	v_mfma_f32_16x16x32_f16 v[122:125], v[142:145], v[134:137], v[122:125]
	v_mfma_f32_16x16x32_f16 v[106:109], v[154:157], v[134:137], v[106:109]
	global_load_dwordx4 v[134:137], v[2:3], off offset:256
	global_load_dwordx4 v[158:161], v[4:5], off offset:256
	global_load_dwordx4 v[162:165], v[14:15], off offset:256
	global_load_dwordx4 v[110:113], v[10:11], off offset:256
	global_load_dwordx4 v[166:169], v[12:13], off offset:256
	global_load_dwordx4 v[190:193], v[8:9], off offset:256
	global_load_dwordx4 v[194:197], v[6:7], off offset:256
	s_waitcnt lgkmcnt(0)
	s_barrier
	v_mfma_f32_16x16x32_f16 v[42:45], v[142:145], v[138:141], v[42:45]
	ds_read_b128 v[58:61], v16 offset:49152
	v_mfma_f32_16x16x32_f16 v[50:53], v[154:157], v[138:141], v[50:53]
	ds_read_b128 v[62:65], v16 offset:51200
	ds_read_b128 v[66:69], v21 offset:16384
	s_waitcnt lgkmcnt(0)
	v_mfma_f32_16x16x32_f16 v[36:39], v[58:61], v[66:69], v[38:41]
	ds_read_b128 v[70:73], v21 offset:18432
	v_mfma_f32_16x16x32_f16 v[46:49], v[62:65], v[66:69], v[46:49]
	ds_read_b128 v[74:77], v16 offset:53248
	s_waitcnt lgkmcnt(0)
	v_mfma_f32_16x16x32_f16 v[82:85], v[74:77], v[66:69], v[90:93]
	ds_read_b128 v[78:81], v16 offset:55296
	s_waitcnt lgkmcnt(0)
	v_mfma_f32_16x16x32_f16 v[28:31], v[78:81], v[66:69], v[28:31]
	v_mfma_f32_16x16x32_f16 v[66:69], v[58:61], v[70:73], v[94:97]
	s_nop 2
	ds_read_b128 v[94:97], v21 offset:22528
	s_waitcnt vmcnt(7)
	ds_write_b128 v17, v[130:133]
	v_mfma_f32_16x16x32_f16 v[86:89], v[62:65], v[70:73], v[98:101]
	s_waitcnt vmcnt(6)
	ds_write_b128 v18, v[134:137]
	s_waitcnt vmcnt(5)
	ds_write_b128 v19, v[158:161]
	v_mfma_f32_16x16x32_f16 v[90:93], v[74:77], v[70:73], v[102:105]
	s_waitcnt vmcnt(4)
	ds_write_b128 v20, v[162:165]
	s_waitcnt vmcnt(3)
	ds_write_b128 v17, v[110:113] offset:32768
	v_mfma_f32_16x16x32_f16 v[32:35], v[78:81], v[70:73], v[32:35]
	ds_read_b128 v[70:73], v21 offset:20480
	s_waitcnt lgkmcnt(0)
	v_mfma_f32_16x16x32_f16 v[98:101], v[58:61], v[70:73], v[114:117]
	s_waitcnt vmcnt(2)
	ds_write_b128 v18, v[166:169] offset:32768
	v_mfma_f32_16x16x32_f16 v[58:61], v[58:61], v[94:97], v[126:129]
	s_waitcnt vmcnt(1)
	ds_write_b128 v19, v[190:193] offset:32768
	v_mfma_f32_16x16x32_f16 v[102:105], v[62:65], v[70:73], v[118:121]
	s_nop 2
	ds_read_b128 v[118:121], v22 offset:55296
	v_mfma_f32_16x16x32_f16 v[24:27], v[62:65], v[94:97], v[24:27]
	ds_read_b128 v[62:65], v22 offset:49152
	v_mfma_f32_16x16x32_f16 v[114:117], v[74:77], v[70:73], v[122:125]
	s_waitcnt vmcnt(0)
	ds_write_b128 v20, v[194:197] offset:32768
	v_mfma_f32_16x16x32_f16 v[40:43], v[74:77], v[94:97], v[42:45]
	ds_read_b128 v[74:77], v22 offset:51200
	v_mfma_f32_16x16x32_f16 v[70:73], v[78:81], v[70:73], v[106:109]
	s_nop 2
	ds_read_b128 v[106:109], v22 offset:53248
	v_mfma_f32_16x16x32_f16 v[50:53], v[78:81], v[94:97], v[50:53]
	ds_read_b128 v[78:81], v23 offset:16384
	s_waitcnt lgkmcnt(0)
	v_mfma_f32_16x16x32_f16 v[36:39], v[62:65], v[78:81], v[36:39]
	ds_read_b128 v[94:97], v23 offset:18432
	s_waitcnt lgkmcnt(0)
	v_mfma_f32_16x16x32_f16 v[66:69], v[62:65], v[94:97], v[66:69]
	v_mfma_f32_16x16x32_f16 v[44:47], v[74:77], v[78:81], v[46:49]
	v_mfma_f32_16x16x32_f16 v[82:85], v[106:109], v[78:81], v[82:85]
	v_mfma_f32_16x16x32_f16 v[28:31], v[118:121], v[78:81], v[28:31]
	v_mfma_f32_16x16x32_f16 v[78:81], v[74:77], v[94:97], v[86:89]
	v_mfma_f32_16x16x32_f16 v[86:89], v[106:109], v[94:97], v[90:93]
	s_nop 2
	ds_read_b128 v[90:93], v23 offset:20480
	v_mfma_f32_16x16x32_f16 v[32:35], v[118:121], v[94:97], v[32:35]
	ds_read_b128 v[94:97], v23 offset:22528
	s_waitcnt lgkmcnt(1)
	v_mfma_f32_16x16x32_f16 v[98:101], v[62:65], v[90:93], v[98:101]
	s_waitcnt lgkmcnt(0)
	v_mfma_f32_16x16x32_f16 v[58:61], v[62:65], v[94:97], v[58:61]
	global_load_dwordx4 v[62:65], v[0:1], off offset:384
	v_mfma_f32_16x16x32_f16 v[102:105], v[74:77], v[90:93], v[102:105]
	v_mfma_f32_16x16x32_f16 v[24:27], v[74:77], v[94:97], v[24:27]
	v_mfma_f32_16x16x32_f16 v[114:117], v[106:109], v[90:93], v[114:117]
	v_mfma_f32_16x16x32_f16 v[40:43], v[106:109], v[94:97], v[40:43]
	v_mfma_f32_16x16x32_f16 v[70:73], v[118:121], v[90:93], v[70:73]
	global_load_dwordx4 v[90:93], v[2:3], off offset:384
	global_load_dwordx4 v[122:125], v[4:5], off offset:384
	global_load_dwordx4 v[126:129], v[14:15], off offset:384
	global_load_dwordx4 v[74:77], v[10:11], off offset:384
	global_load_dwordx4 v[138:141], v[12:13], off offset:384
	global_load_dwordx4 v[142:145], v[8:9], off offset:384
	global_load_dwordx4 v[154:157], v[6:7], off offset:384
	s_waitcnt lgkmcnt(0)
	s_barrier
; #define GL_LOAD(s_, kt_) if (VAR != 1) { a##s_##0 = GL_A(0, kt_); a##s_##1 = GL_A(1, kt_); a##s_##2 = GL_A(2, kt_); a##s_##3 = GL_A(3, kt_); b##s_##0 = GL_B(0, kt_); b##s_##1 = GL_B(1, kt_); b##s_##2 = GL_B(2, kt_); b##s_##3 = GL_B(3, kt_); }
; #define LDS_STORE(s_, buf_) if (VAR != 2) { LDS_ST1(sA, 0, buf_, a##s_##0) LDS_ST1(sA, 1, buf_, a##s_##1) LDS_ST1(sA, 2, buf_, a##s_##2) LDS_ST1(sA, 3, buf_, a##s_##3) LDS_ST1(sB, 0, buf_, b##s_##0) LDS_ST1(sB, 1, buf_, b##s_##1) LDS_ST1(sB, 2, buf_, b##s_##2) LDS_ST1(sB, 3, buf_, b##s_##3) }
;     ...
;   GL_LOAD(0, 0)
;   GL_LOAD(1, 1)
;   LDS_STORE(0, 0)
;   if (VAR != 4) __syncthreads();
; #pragma unroll
;   for (int kt = 0; kt < nk; kt += 2) {
;     if (kt + 2 < nk) { GL_LOAD(0, kt + 2) }
;     MMA_TILE(0)
;     LDS_STORE(1, 1)
;     if (VAR != 4) __syncthreads();
;     if (kt + 3 < nk) { GL_LOAD(1, kt + 3) }
;     MMA_TILE(1)
;     if (kt + 2 < nk) { LDS_STORE(0, 0) }
;     if (VAR != 4) __syncthreads();
	v_mfma_f32_16x16x32_f16 v[48:51], v[118:121], v[94:97], v[50:53]
	ds_read_b128 v[106:109], v16 offset:32768
	ds_read_b128 v[94:97], v21
	s_waitcnt lgkmcnt(0)
	v_mfma_f32_16x16x32_f16 v[36:39], v[106:109], v[94:97], v[36:39]
	ds_read_b128 v[52:55], v16 offset:34816
	ds_read_b128 v[110:113], v21 offset:2048
	s_waitcnt lgkmcnt(0)
	v_mfma_f32_16x16x32_f16 v[66:69], v[106:109], v[110:113], v[66:69]
	ds_read_b128 v[118:121], v16 offset:36864
	v_mfma_f32_16x16x32_f16 v[44:47], v[52:55], v[94:97], v[44:47]
	ds_read_b128 v[130:133], v16 offset:38912
	v_mfma_f32_16x16x32_f16 v[78:81], v[52:55], v[110:113], v[78:81]
	s_waitcnt vmcnt(7)
	ds_write_b128 v17, v[62:65] offset:16384
	s_waitcnt lgkmcnt(2)
	v_mfma_f32_16x16x32_f16 v[82:85], v[118:121], v[94:97], v[82:85]
	s_waitcnt vmcnt(6)
	ds_write_b128 v18, v[90:93] offset:16384
	v_mfma_f32_16x16x32_f16 v[86:89], v[118:121], v[110:113], v[86:89]
	s_waitcnt vmcnt(5)
	ds_write_b128 v19, v[122:125] offset:16384
	s_waitcnt lgkmcnt(3)
	v_mfma_f32_16x16x32_f16 v[28:31], v[130:133], v[94:97], v[28:31]
	ds_read_b128 v[94:97], v21 offset:4096
	v_mfma_f32_16x16x32_f16 v[32:35], v[130:133], v[110:113], v[32:35]
	ds_read_b128 v[110:113], v21 offset:6144
	s_waitcnt lgkmcnt(1)
	v_mfma_f32_16x16x32_f16 v[98:101], v[106:109], v[94:97], v[98:101]
	s_waitcnt vmcnt(4)
	ds_write_b128 v20, v[126:129] offset:16384
	s_waitcnt lgkmcnt(1)
	v_mfma_f32_16x16x32_f16 v[58:61], v[106:109], v[110:113], v[58:61]
	ds_read_b128 v[106:109], v23
	v_mfma_f32_16x16x32_f16 v[102:105], v[52:55], v[94:97], v[102:105]
	s_waitcnt vmcnt(3)
	ds_write_b128 v17, v[74:77] offset:49152
	v_mfma_f32_16x16x32_f16 v[24:27], v[52:55], v[110:113], v[24:27]
	ds_read_b128 v[52:55], v22 offset:32768
	v_mfma_f32_16x16x32_f16 v[114:117], v[118:121], v[94:97], v[114:117]
	s_waitcnt vmcnt(2)
	ds_write_b128 v18, v[138:141] offset:49152
	v_mfma_f32_16x16x32_f16 v[40:43], v[118:121], v[110:113], v[40:43]
	ds_read_b128 v[118:121], v22 offset:36864
	v_mfma_f32_16x16x32_f16 v[70:73], v[130:133], v[94:97], v[70:73]
	ds_read_b128 v[94:97], v22 offset:34816
	v_mfma_f32_16x16x32_f16 v[48:51], v[130:133], v[110:113], v[48:51]
	ds_read_b128 v[110:113], v23 offset:2048
	s_waitcnt lgkmcnt(4)
	v_mfma_f32_16x16x32_f16 v[36:39], v[52:55], v[106:109], v[36:39]
	ds_read_b128 v[130:133], v22 offset:38912
	s_waitcnt lgkmcnt(1)
	v_mfma_f32_16x16x32_f16 v[66:69], v[52:55], v[110:113], v[66:69]
	s_waitcnt vmcnt(1)
	ds_write_b128 v19, v[142:145] offset:49152
	v_mfma_f32_16x16x32_f16 v[44:47], v[94:97], v[106:109], v[44:47]
	s_waitcnt vmcnt(0)
	ds_write_b128 v20, v[154:157] offset:49152
	v_mfma_f32_16x16x32_f16 v[78:81], v[94:97], v[110:113], v[78:81]
	v_mfma_f32_16x16x32_f16 v[82:85], v[118:121], v[106:109], v[82:85]
	v_mfma_f32_16x16x32_f16 v[86:89], v[118:121], v[110:113], v[86:89]
	s_waitcnt lgkmcnt(2)
	v_mfma_f32_16x16x32_f16 v[28:31], v[130:133], v[106:109], v[28:31]
	ds_read_b128 v[106:109], v23 offset:4096
	v_mfma_f32_16x16x32_f16 v[32:35], v[130:133], v[110:113], v[32:35]
	ds_read_b128 v[110:113], v23 offset:6144
	s_waitcnt lgkmcnt(1)
	v_mfma_f32_16x16x32_f16 v[98:101], v[52:55], v[106:109], v[98:101]
	s_waitcnt lgkmcnt(0)
	v_mfma_f32_16x16x32_f16 v[52:55], v[52:55], v[110:113], v[58:61]
	s_nop 2
	global_load_dwordx4 v[58:61], v[0:1], off offset:512
	v_mfma_f32_16x16x32_f16 v[102:105], v[94:97], v[106:109], v[102:105]
	v_mfma_f32_16x16x32_f16 v[24:27], v[94:97], v[110:113], v[24:27]
	v_mfma_f32_16x16x32_f16 v[114:117], v[118:121], v[106:109], v[114:117]
	v_mfma_f32_16x16x32_f16 v[40:43], v[118:121], v[110:113], v[40:43]
	v_mfma_f32_16x16x32_f16 v[70:73], v[130:133], v[106:109], v[70:73]
	global_load_dwordx4 v[106:109], v[2:3], off offset:512
	global_load_dwordx4 v[134:137], v[4:5], off offset:512
	global_load_dwordx4 v[158:161], v[14:15], off offset:512
	global_load_dwordx4 v[94:97], v[10:11], off offset:512
	global_load_dwordx4 v[162:165], v[12:13], off offset:512
	global_load_dwordx4 v[166:169], v[8:9], off offset:512
	global_load_dwordx4 v[190:193], v[6:7], off offset:512
	s_waitcnt lgkmcnt(0)
	s_barrier
	v_mfma_f32_16x16x32_f16 v[48:51], v[130:133], v[110:113], v[48:51]
	ds_read_b128 v[62:65], v16 offset:49152
	ds_read_b128 v[90:93], v21 offset:16384
	s_waitcnt lgkmcnt(0)
	v_mfma_f32_16x16x32_f16 v[36:39], v[62:65], v[90:93], v[36:39]
	ds_read_b128 v[74:77], v16 offset:51200
	ds_read_b128 v[110:113], v21 offset:18432
	s_waitcnt lgkmcnt(0)
	v_mfma_f32_16x16x32_f16 v[66:69], v[62:65], v[110:113], v[66:69]
	ds_read_b128 v[118:121], v16 offset:53248
	v_mfma_f32_16x16x32_f16 v[44:47], v[74:77], v[90:93], v[44:47]
	ds_read_b128 v[122:125], v16 offset:55296
	v_mfma_f32_16x16x32_f16 v[78:81], v[74:77], v[110:113], v[78:81]
	s_waitcnt vmcnt(7)
	ds_write_b128 v17, v[58:61]
	s_waitcnt lgkmcnt(2)
	v_mfma_f32_16x16x32_f16 v[82:85], v[118:121], v[90:93], v[82:85]
	s_waitcnt vmcnt(6)
	ds_write_b128 v18, v[106:109]
	v_mfma_f32_16x16x32_f16 v[86:89], v[118:121], v[110:113], v[86:89]
	s_waitcnt vmcnt(5)
	ds_write_b128 v19, v[134:137]
	s_waitcnt lgkmcnt(3)
	v_mfma_f32_16x16x32_f16 v[28:31], v[122:125], v[90:93], v[28:31]
	ds_read_b128 v[90:93], v21 offset:20480
	v_mfma_f32_16x16x32_f16 v[32:35], v[122:125], v[110:113], v[32:35]
	ds_read_b128 v[110:113], v21 offset:22528
	s_waitcnt lgkmcnt(1)
	v_mfma_f32_16x16x32_f16 v[98:101], v[62:65], v[90:93], v[98:101]
	s_waitcnt vmcnt(4)
	ds_write_b128 v20, v[158:161]
	s_waitcnt lgkmcnt(1)
	v_mfma_f32_16x16x32_f16 v[52:55], v[62:65], v[110:113], v[52:55]
	ds_read_b128 v[62:65], v22 offset:49152
	v_mfma_f32_16x16x32_f16 v[102:105], v[74:77], v[90:93], v[102:105]
	s_waitcnt vmcnt(3)
; #define GL_LOAD(s_, kt_) if (VAR != 1) { a##s_##0 = GL_A(0, kt_); a##s_##1 = GL_A(1, kt_); a##s_##2 = GL_A(2, kt_); a##s_##3 = GL_A(3, kt_); b##s_##0 = GL_B(0, kt_); b##s_##1 = GL_B(1, kt_); b##s_##2 = GL_B(2, kt_); b##s_##3 = GL_B(3, kt_); }
; #define LDS_STORE(s_, buf_) if (VAR != 2) { LDS_ST1(sA, 0, buf_, a##s_##0) LDS_ST1(sA, 1, buf_, a##s_##1) LDS_ST1(sA, 2, buf_, a##s_##2) LDS_ST1(sA, 3, buf_, a##s_##3) LDS_ST1(sB, 0, buf_, b##s_##0) LDS_ST1(sB, 1, buf_, b##s_##1) LDS_ST1(sB, 2, buf_, b##s_##2) LDS_ST1(sB, 3, buf_, b##s_##3) }
;     ...
;   GL_LOAD(0, 0)
;   GL_LOAD(1, 1)
;   LDS_STORE(0, 0)
;   if (VAR != 4) __syncthreads();
; #pragma unroll
;   for (int kt = 0; kt < nk; kt += 2) {
;     if (kt + 2 < nk) { GL_LOAD(0, kt + 2) }
;     MMA_TILE(0)
;     LDS_STORE(1, 1)
;     if (VAR != 4) __syncthreads();
;     if (kt + 3 < nk) { GL_LOAD(1, kt + 3) }
;     MMA_TILE(1)
;     if (kt + 2 < nk) { LDS_STORE(0, 0) }
;     if (VAR != 4) __syncthreads();
	ds_write_b128 v17, v[94:97] offset:32768
	v_mfma_f32_16x16x32_f16 v[24:27], v[74:77], v[110:113], v[24:27]
	ds_read_b128 v[74:77], v22 offset:51200
	v_mfma_f32_16x16x32_f16 v[114:117], v[118:121], v[90:93], v[114:117]
	s_waitcnt vmcnt(2)
	ds_write_b128 v18, v[162:165] offset:32768
	v_mfma_f32_16x16x32_f16 v[40:43], v[118:121], v[110:113], v[40:43]
	ds_read_b128 v[118:121], v22 offset:53248
	v_mfma_f32_16x16x32_f16 v[70:73], v[122:125], v[90:93], v[70:73]
	ds_read_b128 v[90:93], v23 offset:16384
	v_mfma_f32_16x16x32_f16 v[48:51], v[122:125], v[110:113], v[48:51]
	ds_read_b128 v[110:113], v23 offset:18432
	s_waitcnt lgkmcnt(1)
	v_mfma_f32_16x16x32_f16 v[36:39], v[62:65], v[90:93], v[36:39]
	ds_read_b128 v[122:125], v22 offset:55296
	s_waitcnt lgkmcnt(1)
	v_mfma_f32_16x16x32_f16 v[66:69], v[62:65], v[110:113], v[66:69]
	s_waitcnt vmcnt(1)
	ds_write_b128 v19, v[166:169] offset:32768
	v_mfma_f32_16x16x32_f16 v[44:47], v[74:77], v[90:93], v[44:47]
	s_waitcnt vmcnt(0)
	ds_write_b128 v20, v[190:193] offset:32768
	v_mfma_f32_16x16x32_f16 v[78:81], v[74:77], v[110:113], v[78:81]
	v_mfma_f32_16x16x32_f16 v[82:85], v[118:121], v[90:93], v[82:85]
	v_mfma_f32_16x16x32_f16 v[86:89], v[118:121], v[110:113], v[86:89]
	s_waitcnt lgkmcnt(2)
	v_mfma_f32_16x16x32_f16 v[28:31], v[122:125], v[90:93], v[28:31]
	ds_read_b128 v[90:93], v23 offset:20480
	v_mfma_f32_16x16x32_f16 v[32:35], v[122:125], v[110:113], v[32:35]
	ds_read_b128 v[110:113], v23 offset:22528
	s_waitcnt lgkmcnt(1)
	v_mfma_f32_16x16x32_f16 v[98:101], v[62:65], v[90:93], v[98:101]
	s_waitcnt lgkmcnt(0)
	v_mfma_f32_16x16x32_f16 v[52:55], v[62:65], v[110:113], v[52:55]
	global_load_dwordx4 v[62:65], v[0:1], off offset:640
	v_mfma_f32_16x16x32_f16 v[102:105], v[74:77], v[90:93], v[102:105]
	v_mfma_f32_16x16x32_f16 v[24:27], v[74:77], v[110:113], v[24:27]
	v_mfma_f32_16x16x32_f16 v[114:117], v[118:121], v[90:93], v[114:117]
	v_mfma_f32_16x16x32_f16 v[40:43], v[118:121], v[110:113], v[40:43]
	v_mfma_f32_16x16x32_f16 v[70:73], v[122:125], v[90:93], v[70:73]
	global_load_dwordx4 v[90:93], v[2:3], off offset:640
	global_load_dwordx4 v[126:129], v[4:5], off offset:640
	global_load_dwordx4 v[130:133], v[14:15], off offset:640
	global_load_dwordx4 v[74:77], v[10:11], off offset:640
	global_load_dwordx4 v[138:141], v[12:13], off offset:640
	global_load_dwordx4 v[142:145], v[8:9], off offset:640
	global_load_dwordx4 v[154:157], v[6:7], off offset:640
	s_waitcnt lgkmcnt(0)
	s_barrier
	v_mfma_f32_16x16x32_f16 v[48:51], v[122:125], v[110:113], v[48:51]
	ds_read_b128 v[58:61], v16 offset:32768
	ds_read_b128 v[106:109], v21
	s_waitcnt lgkmcnt(0)
	v_mfma_f32_16x16x32_f16 v[36:39], v[58:61], v[106:109], v[36:39]
	ds_read_b128 v[94:97], v16 offset:34816
	ds_read_b128 v[110:113], v21 offset:2048
	s_waitcnt lgkmcnt(0)
	v_mfma_f32_16x16x32_f16 v[66:69], v[58:61], v[110:113], v[66:69]
	ds_read_b128 v[118:121], v16 offset:36864
	v_mfma_f32_16x16x32_f16 v[44:47], v[94:97], v[106:109], v[44:47]
	ds_read_b128 v[122:125], v16 offset:38912
	v_mfma_f32_16x16x32_f16 v[78:81], v[94:97], v[110:113], v[78:81]
	s_waitcnt vmcnt(7)
	ds_write_b128 v17, v[62:65] offset:16384
	s_waitcnt lgkmcnt(2)
	v_mfma_f32_16x16x32_f16 v[82:85], v[118:121], v[106:109], v[82:85]
	s_waitcnt vmcnt(6)
	ds_write_b128 v18, v[90:93] offset:16384
	v_mfma_f32_16x16x32_f16 v[86:89], v[118:121], v[110:113], v[86:89]
	s_waitcnt vmcnt(5)
	ds_write_b128 v19, v[126:129] offset:16384
	s_waitcnt lgkmcnt(3)
	v_mfma_f32_16x16x32_f16 v[28:31], v[122:125], v[106:109], v[28:31]
	ds_read_b128 v[106:109], v21 offset:4096
	v_mfma_f32_16x16x32_f16 v[32:35], v[122:125], v[110:113], v[32:35]
	ds_read_b128 v[110:113], v21 offset:6144
	s_waitcnt lgkmcnt(1)
	v_mfma_f32_16x16x32_f16 v[98:101], v[58:61], v[106:109], v[98:101]
	s_waitcnt vmcnt(4)
	ds_write_b128 v20, v[130:133] offset:16384
	s_waitcnt lgkmcnt(1)
	v_mfma_f32_16x16x32_f16 v[52:55], v[58:61], v[110:113], v[52:55]
	ds_read_b128 v[58:61], v22 offset:32768
	v_mfma_f32_16x16x32_f16 v[102:105], v[94:97], v[106:109], v[102:105]
	s_waitcnt vmcnt(3)
	ds_write_b128 v17, v[74:77] offset:49152
	v_mfma_f32_16x16x32_f16 v[24:27], v[94:97], v[110:113], v[24:27]
	ds_read_b128 v[94:97], v22 offset:34816
	v_mfma_f32_16x16x32_f16 v[114:117], v[118:121], v[106:109], v[114:117]
	s_waitcnt vmcnt(2)
	ds_write_b128 v18, v[138:141] offset:49152
	v_mfma_f32_16x16x32_f16 v[40:43], v[118:121], v[110:113], v[40:43]
	ds_read_b128 v[118:121], v22 offset:36864
	v_mfma_f32_16x16x32_f16 v[70:73], v[122:125], v[106:109], v[70:73]
	ds_read_b128 v[106:109], v23
	v_mfma_f32_16x16x32_f16 v[48:51], v[122:125], v[110:113], v[48:51]
	ds_read_b128 v[110:113], v23 offset:2048
	s_waitcnt lgkmcnt(1)
	v_mfma_f32_16x16x32_f16 v[36:39], v[58:61], v[106:109], v[36:39]
	ds_read_b128 v[122:125], v22 offset:38912
	s_waitcnt lgkmcnt(1)
	v_mfma_f32_16x16x32_f16 v[66:69], v[58:61], v[110:113], v[66:69]
	s_waitcnt vmcnt(1)
	ds_write_b128 v19, v[142:145] offset:49152
	v_mfma_f32_16x16x32_f16 v[44:47], v[94:97], v[106:109], v[44:47]
	s_waitcnt vmcnt(0)
	ds_write_b128 v20, v[154:157] offset:49152
	v_mfma_f32_16x16x32_f16 v[78:81], v[94:97], v[110:113], v[78:81]
	v_mfma_f32_16x16x32_f16 v[82:85], v[118:121], v[106:109], v[82:85]
	v_mfma_f32_16x16x32_f16 v[86:89], v[118:121], v[110:113], v[86:89]
	s_waitcnt lgkmcnt(2)
	v_mfma_f32_16x16x32_f16 v[28:31], v[122:125], v[106:109], v[28:31]
	ds_read_b128 v[106:109], v23 offset:4096
	v_mfma_f32_16x16x32_f16 v[32:35], v[122:125], v[110:113], v[32:35]
	ds_read_b128 v[110:113], v23 offset:6144
	s_waitcnt lgkmcnt(1)
	v_mfma_f32_16x16x32_f16 v[98:101], v[58:61], v[106:109], v[98:101]
	s_waitcnt lgkmcnt(0)
	v_mfma_f32_16x16x32_f16 v[52:55], v[58:61], v[110:113], v[52:55]
	global_load_dwordx4 v[58:61], v[0:1], off offset:768
	v_mfma_f32_16x16x32_f16 v[102:105], v[94:97], v[106:109], v[102:105]
	v_mfma_f32_16x16x32_f16 v[24:27], v[94:97], v[110:113], v[24:27]
	v_mfma_f32_16x16x32_f16 v[114:117], v[118:121], v[106:109], v[114:117]
	v_mfma_f32_16x16x32_f16 v[40:43], v[118:121], v[110:113], v[40:43]
	v_mfma_f32_16x16x32_f16 v[70:73], v[122:125], v[106:109], v[70:73]
	global_load_dwordx4 v[106:109], v[2:3], off offset:768
	global_load_dwordx4 v[134:137], v[4:5], off offset:768
	global_load_dwordx4 v[158:161], v[14:15], off offset:768
	global_load_dwordx4 v[94:97], v[10:11], off offset:768
	global_load_dwordx4 v[162:165], v[12:13], off offset:768
	global_load_dwordx4 v[166:169], v[8:9], off offset:768
	global_load_dwordx4 v[190:193], v[6:7], off offset:768
	s_waitcnt lgkmcnt(0)
	s_barrier
; #define GL_LOAD(s_, kt_) if (VAR != 1) { a##s_##0 = GL_A(0, kt_); a##s_##1 = GL_A(1, kt_); a##s_##2 = GL_A(2, kt_); a##s_##3 = GL_A(3, kt_); b##s_##0 = GL_B(0, kt_); b##s_##1 = GL_B(1, kt_); b##s_##2 = GL_B(2, kt_); b##s_##3 = GL_B(3, kt_); }
; #define LDS_STORE(s_, buf_) if (VAR != 2) { LDS_ST1(sA, 0, buf_, a##s_##0) LDS_ST1(sA, 1, buf_, a##s_##1) LDS_ST1(sA, 2, buf_, a##s_##2) LDS_ST1(sA, 3, buf_, a##s_##3) LDS_ST1(sB, 0, buf_, b##s_##0) LDS_ST1(sB, 1, buf_, b##s_##1) LDS_ST1(sB, 2, buf_, b##s_##2) LDS_ST1(sB, 3, buf_, b##s_##3) }
;     ...
;   GL_LOAD(0, 0)
;   GL_LOAD(1, 1)
;   LDS_STORE(0, 0)
;   if (VAR != 4) __syncthreads();
; #pragma unroll
;   for (int kt = 0; kt < nk; kt += 2) {
;     if (kt + 2 < nk) { GL_LOAD(0, kt + 2) }
;     MMA_TILE(0)
;     LDS_STORE(1, 1)
;     if (VAR != 4) __syncthreads();
;     if (kt + 3 < nk) { GL_LOAD(1, kt + 3) }
;     MMA_TILE(1)
;     if (kt + 2 < nk) { LDS_STORE(0, 0) }
;     if (VAR != 4) __syncthreads();
	v_mfma_f32_16x16x32_f16 v[48:51], v[122:125], v[110:113], v[48:51]
	ds_read_b128 v[62:65], v16 offset:49152
	ds_read_b128 v[90:93], v21 offset:16384
	s_waitcnt lgkmcnt(0)
	v_mfma_f32_16x16x32_f16 v[36:39], v[62:65], v[90:93], v[36:39]
	ds_read_b128 v[74:77], v16 offset:51200
	ds_read_b128 v[110:113], v21 offset:18432
	s_waitcnt lgkmcnt(0)
	v_mfma_f32_16x16x32_f16 v[66:69], v[62:65], v[110:113], v[66:69]
	ds_read_b128 v[118:121], v16 offset:53248
	v_mfma_f32_16x16x32_f16 v[44:47], v[74:77], v[90:93], v[44:47]
	ds_read_b128 v[122:125], v16 offset:55296
	v_mfma_f32_16x16x32_f16 v[78:81], v[74:77], v[110:113], v[78:81]
	s_waitcnt vmcnt(7)
	ds_write_b128 v17, v[58:61]
	s_waitcnt lgkmcnt(2)
	v_mfma_f32_16x16x32_f16 v[82:85], v[118:121], v[90:93], v[82:85]
	s_waitcnt vmcnt(6)
	ds_write_b128 v18, v[106:109]
	v_mfma_f32_16x16x32_f16 v[86:89], v[118:121], v[110:113], v[86:89]
	s_waitcnt vmcnt(5)
	ds_write_b128 v19, v[134:137]
	s_waitcnt lgkmcnt(3)
	v_mfma_f32_16x16x32_f16 v[28:31], v[122:125], v[90:93], v[28:31]
	ds_read_b128 v[90:93], v21 offset:20480
	v_mfma_f32_16x16x32_f16 v[32:35], v[122:125], v[110:113], v[32:35]
	ds_read_b128 v[110:113], v21 offset:22528
	s_waitcnt lgkmcnt(1)
	v_mfma_f32_16x16x32_f16 v[98:101], v[62:65], v[90:93], v[98:101]
	s_waitcnt vmcnt(4)
	ds_write_b128 v20, v[158:161]
	s_waitcnt lgkmcnt(1)
	v_mfma_f32_16x16x32_f16 v[52:55], v[62:65], v[110:113], v[52:55]
	ds_read_b128 v[62:65], v22 offset:49152
	v_mfma_f32_16x16x32_f16 v[102:105], v[74:77], v[90:93], v[102:105]
	s_waitcnt vmcnt(3)
	ds_write_b128 v17, v[94:97] offset:32768
	v_mfma_f32_16x16x32_f16 v[24:27], v[74:77], v[110:113], v[24:27]
	ds_read_b128 v[74:77], v22 offset:51200
	v_mfma_f32_16x16x32_f16 v[114:117], v[118:121], v[90:93], v[114:117]
	s_waitcnt vmcnt(2)
	ds_write_b128 v18, v[162:165] offset:32768
	v_mfma_f32_16x16x32_f16 v[40:43], v[118:121], v[110:113], v[40:43]
	ds_read_b128 v[118:121], v22 offset:53248
	v_mfma_f32_16x16x32_f16 v[70:73], v[122:125], v[90:93], v[70:73]
	ds_read_b128 v[90:93], v23 offset:16384
	v_mfma_f32_16x16x32_f16 v[48:51], v[122:125], v[110:113], v[48:51]
	ds_read_b128 v[110:113], v23 offset:18432
	s_waitcnt lgkmcnt(1)
	v_mfma_f32_16x16x32_f16 v[36:39], v[62:65], v[90:93], v[36:39]
	ds_read_b128 v[122:125], v22 offset:55296
	s_waitcnt lgkmcnt(1)
	v_mfma_f32_16x16x32_f16 v[66:69], v[62:65], v[110:113], v[66:69]
	s_waitcnt vmcnt(1)
	ds_write_b128 v19, v[166:169] offset:32768
	v_mfma_f32_16x16x32_f16 v[44:47], v[74:77], v[90:93], v[44:47]
	s_waitcnt vmcnt(0)
	ds_write_b128 v20, v[190:193] offset:32768
	v_mfma_f32_16x16x32_f16 v[78:81], v[74:77], v[110:113], v[78:81]
	v_mfma_f32_16x16x32_f16 v[82:85], v[118:121], v[90:93], v[82:85]
	v_mfma_f32_16x16x32_f16 v[86:89], v[118:121], v[110:113], v[86:89]
	s_waitcnt lgkmcnt(2)
	v_mfma_f32_16x16x32_f16 v[28:31], v[122:125], v[90:93], v[28:31]
	ds_read_b128 v[90:93], v23 offset:20480
	v_mfma_f32_16x16x32_f16 v[32:35], v[122:125], v[110:113], v[32:35]
	ds_read_b128 v[110:113], v23 offset:22528
	s_waitcnt lgkmcnt(1)
	v_mfma_f32_16x16x32_f16 v[98:101], v[62:65], v[90:93], v[98:101]
	s_waitcnt lgkmcnt(0)
	v_mfma_f32_16x16x32_f16 v[52:55], v[62:65], v[110:113], v[52:55]
	global_load_dwordx4 v[62:65], v[0:1], off offset:896
	v_mfma_f32_16x16x32_f16 v[102:105], v[74:77], v[90:93], v[102:105]
	v_mfma_f32_16x16x32_f16 v[24:27], v[74:77], v[110:113], v[24:27]
	v_mfma_f32_16x16x32_f16 v[114:117], v[118:121], v[90:93], v[114:117]
	v_mfma_f32_16x16x32_f16 v[40:43], v[118:121], v[110:113], v[40:43]
	v_mfma_f32_16x16x32_f16 v[70:73], v[122:125], v[90:93], v[70:73]
	global_load_dwordx4 v[90:93], v[2:3], off offset:896
	global_load_dwordx4 v[126:129], v[4:5], off offset:896
	global_load_dwordx4 v[130:133], v[14:15], off offset:896
	global_load_dwordx4 v[74:77], v[10:11], off offset:896
	global_load_dwordx4 v[138:141], v[12:13], off offset:896
	global_load_dwordx4 v[142:145], v[8:9], off offset:896
	global_load_dwordx4 v[154:157], v[6:7], off offset:896
	s_waitcnt lgkmcnt(0)
	s_barrier
	v_mfma_f32_16x16x32_f16 v[48:51], v[122:125], v[110:113], v[48:51]
	ds_read_b128 v[58:61], v16 offset:32768
	ds_read_b128 v[106:109], v21
	s_waitcnt lgkmcnt(0)
	v_mfma_f32_16x16x32_f16 v[36:39], v[58:61], v[106:109], v[36:39]
	ds_read_b128 v[94:97], v16 offset:34816
	ds_read_b128 v[110:113], v21 offset:2048
	s_waitcnt lgkmcnt(0)
	v_mfma_f32_16x16x32_f16 v[66:69], v[58:61], v[110:113], v[66:69]
	ds_read_b128 v[118:121], v16 offset:36864
	v_mfma_f32_16x16x32_f16 v[44:47], v[94:97], v[106:109], v[44:47]
	ds_read_b128 v[122:125], v16 offset:38912
	v_mfma_f32_16x16x32_f16 v[78:81], v[94:97], v[110:113], v[78:81]
	s_waitcnt vmcnt(7)
	ds_write_b128 v17, v[62:65] offset:16384
	s_waitcnt lgkmcnt(2)
	v_mfma_f32_16x16x32_f16 v[82:85], v[118:121], v[106:109], v[82:85]
	s_waitcnt vmcnt(6)
	ds_write_b128 v18, v[90:93] offset:16384
	v_mfma_f32_16x16x32_f16 v[86:89], v[118:121], v[110:113], v[86:89]
	s_waitcnt vmcnt(5)
	ds_write_b128 v19, v[126:129] offset:16384
	s_waitcnt lgkmcnt(3)
	v_mfma_f32_16x16x32_f16 v[28:31], v[122:125], v[106:109], v[28:31]
	ds_read_b128 v[106:109], v21 offset:4096
	v_mfma_f32_16x16x32_f16 v[32:35], v[122:125], v[110:113], v[32:35]
	ds_read_b128 v[110:113], v21 offset:6144
	s_waitcnt lgkmcnt(1)
	v_mfma_f32_16x16x32_f16 v[98:101], v[58:61], v[106:109], v[98:101]
	s_waitcnt vmcnt(4)
	ds_write_b128 v20, v[130:133] offset:16384
	s_waitcnt lgkmcnt(1)
	v_mfma_f32_16x16x32_f16 v[52:55], v[58:61], v[110:113], v[52:55]
	ds_read_b128 v[58:61], v22 offset:32768
	v_mfma_f32_16x16x32_f16 v[102:105], v[94:97], v[106:109], v[102:105]
	s_waitcnt vmcnt(3)
; #define GL_LOAD(s_, kt_) if (VAR != 1) { a##s_##0 = GL_A(0, kt_); a##s_##1 = GL_A(1, kt_); a##s_##2 = GL_A(2, kt_); a##s_##3 = GL_A(3, kt_); b##s_##0 = GL_B(0, kt_); b##s_##1 = GL_B(1, kt_); b##s_##2 = GL_B(2, kt_); b##s_##3 = GL_B(3, kt_); }
; #define LDS_STORE(s_, buf_) if (VAR != 2) { LDS_ST1(sA, 0, buf_, a##s_##0) LDS_ST1(sA, 1, buf_, a##s_##1) LDS_ST1(sA, 2, buf_, a##s_##2) LDS_ST1(sA, 3, buf_, a##s_##3) LDS_ST1(sB, 0, buf_, b##s_##0) LDS_ST1(sB, 1, buf_, b##s_##1) LDS_ST1(sB, 2, buf_, b##s_##2) LDS_ST1(sB, 3, buf_, b##s_##3) }
;     ...
;   GL_LOAD(0, 0)
;   GL_LOAD(1, 1)
;   LDS_STORE(0, 0)
;   if (VAR != 4) __syncthreads();
; #pragma unroll
;   for (int kt = 0; kt < nk; kt += 2) {
;     if (kt + 2 < nk) { GL_LOAD(0, kt + 2) }
;     MMA_TILE(0)
;     LDS_STORE(1, 1)
;     if (VAR != 4) __syncthreads();
;     if (kt + 3 < nk) { GL_LOAD(1, kt + 3) }
;     MMA_TILE(1)
;     if (kt + 2 < nk) { LDS_STORE(0, 0) }
;     if (VAR != 4) __syncthreads();
	ds_write_b128 v17, v[74:77] offset:49152
	v_mfma_f32_16x16x32_f16 v[24:27], v[94:97], v[110:113], v[24:27]
	ds_read_b128 v[94:97], v22 offset:34816
	v_mfma_f32_16x16x32_f16 v[114:117], v[118:121], v[106:109], v[114:117]
	s_waitcnt vmcnt(2)
	ds_write_b128 v18, v[138:141] offset:49152
	v_mfma_f32_16x16x32_f16 v[40:43], v[118:121], v[110:113], v[40:43]
	ds_read_b128 v[118:121], v22 offset:36864
	v_mfma_f32_16x16x32_f16 v[70:73], v[122:125], v[106:109], v[70:73]
	ds_read_b128 v[106:109], v23
	v_mfma_f32_16x16x32_f16 v[48:51], v[122:125], v[110:113], v[48:51]
	ds_read_b128 v[110:113], v23 offset:2048
	s_waitcnt lgkmcnt(1)
	v_mfma_f32_16x16x32_f16 v[36:39], v[58:61], v[106:109], v[36:39]
	ds_read_b128 v[122:125], v22 offset:38912
	s_waitcnt lgkmcnt(1)
	v_mfma_f32_16x16x32_f16 v[66:69], v[58:61], v[110:113], v[66:69]
	s_waitcnt vmcnt(1)
	ds_write_b128 v19, v[142:145] offset:49152
	v_mfma_f32_16x16x32_f16 v[44:47], v[94:97], v[106:109], v[44:47]
	s_waitcnt vmcnt(0)
	ds_write_b128 v20, v[154:157] offset:49152
	v_mfma_f32_16x16x32_f16 v[78:81], v[94:97], v[110:113], v[78:81]
	v_mfma_f32_16x16x32_f16 v[82:85], v[118:121], v[106:109], v[82:85]
	v_mfma_f32_16x16x32_f16 v[86:89], v[118:121], v[110:113], v[86:89]
	s_waitcnt lgkmcnt(2)
	v_mfma_f32_16x16x32_f16 v[28:31], v[122:125], v[106:109], v[28:31]
	ds_read_b128 v[106:109], v23 offset:4096
	v_mfma_f32_16x16x32_f16 v[32:35], v[122:125], v[110:113], v[32:35]
	ds_read_b128 v[110:113], v23 offset:6144
	s_waitcnt lgkmcnt(1)
	v_mfma_f32_16x16x32_f16 v[98:101], v[58:61], v[106:109], v[98:101]
	s_waitcnt lgkmcnt(0)
	v_mfma_f32_16x16x32_f16 v[52:55], v[58:61], v[110:113], v[52:55]
	global_load_dwordx4 v[58:61], v[0:1], off offset:1024
	v_mfma_f32_16x16x32_f16 v[102:105], v[94:97], v[106:109], v[102:105]
	v_mfma_f32_16x16x32_f16 v[24:27], v[94:97], v[110:113], v[24:27]
	v_mfma_f32_16x16x32_f16 v[114:117], v[118:121], v[106:109], v[114:117]
	v_mfma_f32_16x16x32_f16 v[40:43], v[118:121], v[110:113], v[40:43]
	v_mfma_f32_16x16x32_f16 v[70:73], v[122:125], v[106:109], v[70:73]
	global_load_dwordx4 v[106:109], v[2:3], off offset:1024
	global_load_dwordx4 v[134:137], v[4:5], off offset:1024
	global_load_dwordx4 v[158:161], v[14:15], off offset:1024
	global_load_dwordx4 v[94:97], v[10:11], off offset:1024
	global_load_dwordx4 v[162:165], v[12:13], off offset:1024
	global_load_dwordx4 v[166:169], v[8:9], off offset:1024
	global_load_dwordx4 v[190:193], v[6:7], off offset:1024
	s_waitcnt lgkmcnt(0)
	s_barrier
	v_mfma_f32_16x16x32_f16 v[48:51], v[122:125], v[110:113], v[48:51]
	ds_read_b128 v[62:65], v16 offset:49152
	ds_read_b128 v[90:93], v21 offset:16384
	s_waitcnt lgkmcnt(0)
	v_mfma_f32_16x16x32_f16 v[36:39], v[62:65], v[90:93], v[36:39]
	ds_read_b128 v[74:77], v16 offset:51200
	ds_read_b128 v[110:113], v21 offset:18432
	s_waitcnt lgkmcnt(0)
	v_mfma_f32_16x16x32_f16 v[66:69], v[62:65], v[110:113], v[66:69]
	ds_read_b128 v[118:121], v16 offset:53248
	v_mfma_f32_16x16x32_f16 v[44:47], v[74:77], v[90:93], v[44:47]
	ds_read_b128 v[122:125], v16 offset:55296
	v_mfma_f32_16x16x32_f16 v[78:81], v[74:77], v[110:113], v[78:81]
	s_waitcnt vmcnt(7)
	ds_write_b128 v17, v[58:61]
	s_waitcnt lgkmcnt(2)
	v_mfma_f32_16x16x32_f16 v[82:85], v[118:121], v[90:93], v[82:85]
	s_waitcnt vmcnt(6)
	ds_write_b128 v18, v[106:109]
	v_mfma_f32_16x16x32_f16 v[86:89], v[118:121], v[110:113], v[86:89]
	s_waitcnt vmcnt(5)
	ds_write_b128 v19, v[134:137]
	s_waitcnt lgkmcnt(3)
	v_mfma_f32_16x16x32_f16 v[28:31], v[122:125], v[90:93], v[28:31]
	ds_read_b128 v[90:93], v21 offset:20480
	v_mfma_f32_16x16x32_f16 v[32:35], v[122:125], v[110:113], v[32:35]
	ds_read_b128 v[110:113], v21 offset:22528
	s_waitcnt lgkmcnt(1)
	v_mfma_f32_16x16x32_f16 v[98:101], v[62:65], v[90:93], v[98:101]
	s_waitcnt vmcnt(4)
	ds_write_b128 v20, v[158:161]
	s_waitcnt lgkmcnt(1)
	v_mfma_f32_16x16x32_f16 v[52:55], v[62:65], v[110:113], v[52:55]
	ds_read_b128 v[62:65], v22 offset:49152
	v_mfma_f32_16x16x32_f16 v[102:105], v[74:77], v[90:93], v[102:105]
	s_waitcnt vmcnt(3)
	ds_write_b128 v17, v[94:97] offset:32768
	v_mfma_f32_16x16x32_f16 v[24:27], v[74:77], v[110:113], v[24:27]
	ds_read_b128 v[74:77], v22 offset:51200
	v_mfma_f32_16x16x32_f16 v[114:117], v[118:121], v[90:93], v[114:117]
	s_waitcnt vmcnt(2)
	ds_write_b128 v18, v[162:165] offset:32768
	v_mfma_f32_16x16x32_f16 v[40:43], v[118:121], v[110:113], v[40:43]
	ds_read_b128 v[118:121], v22 offset:53248
	v_mfma_f32_16x16x32_f16 v[70:73], v[122:125], v[90:93], v[70:73]
	ds_read_b128 v[90:93], v23 offset:16384
	v_mfma_f32_16x16x32_f16 v[48:51], v[122:125], v[110:113], v[48:51]
	ds_read_b128 v[110:113], v23 offset:18432
	s_waitcnt lgkmcnt(1)
	v_mfma_f32_16x16x32_f16 v[36:39], v[62:65], v[90:93], v[36:39]
	ds_read_b128 v[122:125], v22 offset:55296
	s_waitcnt lgkmcnt(1)
	v_mfma_f32_16x16x32_f16 v[66:69], v[62:65], v[110:113], v[66:69]
	s_waitcnt vmcnt(1)
	ds_write_b128 v19, v[166:169] offset:32768
	v_mfma_f32_16x16x32_f16 v[44:47], v[74:77], v[90:93], v[44:47]
	s_waitcnt vmcnt(0)
	ds_write_b128 v20, v[190:193] offset:32768
	v_mfma_f32_16x16x32_f16 v[78:81], v[74:77], v[110:113], v[78:81]
	v_mfma_f32_16x16x32_f16 v[82:85], v[118:121], v[90:93], v[82:85]
	v_mfma_f32_16x16x32_f16 v[86:89], v[118:121], v[110:113], v[86:89]
	s_waitcnt lgkmcnt(2)
	v_mfma_f32_16x16x32_f16 v[28:31], v[122:125], v[90:93], v[28:31]
	ds_read_b128 v[90:93], v23 offset:20480
	v_mfma_f32_16x16x32_f16 v[32:35], v[122:125], v[110:113], v[32:35]
	ds_read_b128 v[110:113], v23 offset:22528
	s_waitcnt lgkmcnt(1)
	v_mfma_f32_16x16x32_f16 v[98:101], v[62:65], v[90:93], v[98:101]
	s_waitcnt lgkmcnt(0)
	v_mfma_f32_16x16x32_f16 v[52:55], v[62:65], v[110:113], v[52:55]
	global_load_dwordx4 v[62:65], v[0:1], off offset:1152
	v_mfma_f32_16x16x32_f16 v[102:105], v[74:77], v[90:93], v[102:105]
	v_mfma_f32_16x16x32_f16 v[24:27], v[74:77], v[110:113], v[24:27]
	v_mfma_f32_16x16x32_f16 v[114:117], v[118:121], v[90:93], v[114:117]
	v_mfma_f32_16x16x32_f16 v[40:43], v[118:121], v[110:113], v[40:43]
	v_mfma_f32_16x16x32_f16 v[70:73], v[122:125], v[90:93], v[70:73]
	global_load_dwordx4 v[90:93], v[2:3], off offset:1152
	global_load_dwordx4 v[126:129], v[4:5], off offset:1152
	global_load_dwordx4 v[130:133], v[14:15], off offset:1152
	global_load_dwordx4 v[74:77], v[10:11], off offset:1152
	global_load_dwordx4 v[138:141], v[12:13], off offset:1152
	global_load_dwordx4 v[142:145], v[8:9], off offset:1152
	global_load_dwordx4 v[154:157], v[6:7], off offset:1152
	s_waitcnt lgkmcnt(0)
	s_barrier
; #define GL_LOAD(s_, kt_) if (VAR != 1) { a##s_##0 = GL_A(0, kt_); a##s_##1 = GL_A(1, kt_); a##s_##2 = GL_A(2, kt_); a##s_##3 = GL_A(3, kt_); b##s_##0 = GL_B(0, kt_); b##s_##1 = GL_B(1, kt_); b##s_##2 = GL_B(2, kt_); b##s_##3 = GL_B(3, kt_); }
; #define LDS_STORE(s_, buf_) if (VAR != 2) { LDS_ST1(sA, 0, buf_, a##s_##0) LDS_ST1(sA, 1, buf_, a##s_##1) LDS_ST1(sA, 2, buf_, a##s_##2) LDS_ST1(sA, 3, buf_, a##s_##3) LDS_ST1(sB, 0, buf_, b##s_##0) LDS_ST1(sB, 1, buf_, b##s_##1) LDS_ST1(sB, 2, buf_, b##s_##2) LDS_ST1(sB, 3, buf_, b##s_##3) }
;     ...
;   GL_LOAD(0, 0)
;   GL_LOAD(1, 1)
;   LDS_STORE(0, 0)
;   if (VAR != 4) __syncthreads();
; #pragma unroll
;   for (int kt = 0; kt < nk; kt += 2) {
;     if (kt + 2 < nk) { GL_LOAD(0, kt + 2) }
;     MMA_TILE(0)
;     LDS_STORE(1, 1)
;     if (VAR != 4) __syncthreads();
;     if (kt + 3 < nk) { GL_LOAD(1, kt + 3) }
;     MMA_TILE(1)
;     if (kt + 2 < nk) { LDS_STORE(0, 0) }
;     if (VAR != 4) __syncthreads();
	v_mfma_f32_16x16x32_f16 v[48:51], v[122:125], v[110:113], v[48:51]
	ds_read_b128 v[58:61], v16 offset:32768
	ds_read_b128 v[106:109], v21
	s_waitcnt lgkmcnt(0)
	v_mfma_f32_16x16x32_f16 v[36:39], v[58:61], v[106:109], v[36:39]
	ds_read_b128 v[94:97], v16 offset:34816
	ds_read_b128 v[110:113], v21 offset:2048
	s_waitcnt lgkmcnt(0)
	v_mfma_f32_16x16x32_f16 v[66:69], v[58:61], v[110:113], v[66:69]
	ds_read_b128 v[118:121], v16 offset:36864
	v_mfma_f32_16x16x32_f16 v[44:47], v[94:97], v[106:109], v[44:47]
	ds_read_b128 v[122:125], v16 offset:38912
	v_mfma_f32_16x16x32_f16 v[78:81], v[94:97], v[110:113], v[78:81]
	s_waitcnt vmcnt(7)
	ds_write_b128 v17, v[62:65] offset:16384
	s_waitcnt lgkmcnt(2)
	v_mfma_f32_16x16x32_f16 v[82:85], v[118:121], v[106:109], v[82:85]
	s_waitcnt vmcnt(6)
	ds_write_b128 v18, v[90:93] offset:16384
	v_mfma_f32_16x16x32_f16 v[86:89], v[118:121], v[110:113], v[86:89]
	s_waitcnt vmcnt(5)
	ds_write_b128 v19, v[126:129] offset:16384
	s_waitcnt lgkmcnt(3)
	v_mfma_f32_16x16x32_f16 v[28:31], v[122:125], v[106:109], v[28:31]
	ds_read_b128 v[106:109], v21 offset:4096
	v_mfma_f32_16x16x32_f16 v[32:35], v[122:125], v[110:113], v[32:35]
	ds_read_b128 v[110:113], v21 offset:6144
	s_waitcnt lgkmcnt(1)
	v_mfma_f32_16x16x32_f16 v[98:101], v[58:61], v[106:109], v[98:101]
	s_waitcnt vmcnt(4)
	ds_write_b128 v20, v[130:133] offset:16384
	s_waitcnt lgkmcnt(1)
	v_mfma_f32_16x16x32_f16 v[52:55], v[58:61], v[110:113], v[52:55]
	ds_read_b128 v[58:61], v22 offset:32768
	v_mfma_f32_16x16x32_f16 v[102:105], v[94:97], v[106:109], v[102:105]
	s_waitcnt vmcnt(3)
	ds_write_b128 v17, v[74:77] offset:49152
	v_mfma_f32_16x16x32_f16 v[24:27], v[94:97], v[110:113], v[24:27]
	ds_read_b128 v[94:97], v22 offset:34816
	v_mfma_f32_16x16x32_f16 v[114:117], v[118:121], v[106:109], v[114:117]
	s_waitcnt vmcnt(2)
	ds_write_b128 v18, v[138:141] offset:49152
	v_mfma_f32_16x16x32_f16 v[40:43], v[118:121], v[110:113], v[40:43]
	ds_read_b128 v[118:121], v22 offset:36864
	v_mfma_f32_16x16x32_f16 v[70:73], v[122:125], v[106:109], v[70:73]
	ds_read_b128 v[106:109], v23
	v_mfma_f32_16x16x32_f16 v[48:51], v[122:125], v[110:113], v[48:51]
	ds_read_b128 v[110:113], v23 offset:2048
	s_waitcnt lgkmcnt(1)
	v_mfma_f32_16x16x32_f16 v[36:39], v[58:61], v[106:109], v[36:39]
	ds_read_b128 v[122:125], v22 offset:38912
	s_waitcnt lgkmcnt(1)
	v_mfma_f32_16x16x32_f16 v[66:69], v[58:61], v[110:113], v[66:69]
	s_waitcnt vmcnt(1)
	ds_write_b128 v19, v[142:145] offset:49152
	v_mfma_f32_16x16x32_f16 v[44:47], v[94:97], v[106:109], v[44:47]
	s_waitcnt vmcnt(0)
	ds_write_b128 v20, v[154:157] offset:49152
	v_mfma_f32_16x16x32_f16 v[78:81], v[94:97], v[110:113], v[78:81]
	v_mfma_f32_16x16x32_f16 v[82:85], v[118:121], v[106:109], v[82:85]
	v_mfma_f32_16x16x32_f16 v[86:89], v[118:121], v[110:113], v[86:89]
	s_waitcnt lgkmcnt(2)
	v_mfma_f32_16x16x32_f16 v[28:31], v[122:125], v[106:109], v[28:31]
	ds_read_b128 v[106:109], v23 offset:4096
	v_mfma_f32_16x16x32_f16 v[32:35], v[122:125], v[110:113], v[32:35]
	ds_read_b128 v[110:113], v23 offset:6144
	s_waitcnt lgkmcnt(1)
	v_mfma_f32_16x16x32_f16 v[98:101], v[58:61], v[106:109], v[98:101]
	s_waitcnt lgkmcnt(0)
	v_mfma_f32_16x16x32_f16 v[52:55], v[58:61], v[110:113], v[52:55]
	global_load_dwordx4 v[58:61], v[0:1], off offset:1280
	v_mfma_f32_16x16x32_f16 v[102:105], v[94:97], v[106:109], v[102:105]
	v_mfma_f32_16x16x32_f16 v[24:27], v[94:97], v[110:113], v[24:27]
	v_mfma_f32_16x16x32_f16 v[114:117], v[118:121], v[106:109], v[114:117]
	v_mfma_f32_16x16x32_f16 v[40:43], v[118:121], v[110:113], v[40:43]
	v_mfma_f32_16x16x32_f16 v[70:73], v[122:125], v[106:109], v[70:73]
	global_load_dwordx4 v[106:109], v[2:3], off offset:1280
	global_load_dwordx4 v[134:137], v[4:5], off offset:1280
	global_load_dwordx4 v[158:161], v[14:15], off offset:1280
	global_load_dwordx4 v[94:97], v[10:11], off offset:1280
	global_load_dwordx4 v[162:165], v[12:13], off offset:1280
	global_load_dwordx4 v[166:169], v[8:9], off offset:1280
	global_load_dwordx4 v[190:193], v[6:7], off offset:1280
	s_waitcnt lgkmcnt(0)
	s_barrier
	v_mfma_f32_16x16x32_f16 v[48:51], v[122:125], v[110:113], v[48:51]
	ds_read_b128 v[62:65], v16 offset:49152
	ds_read_b128 v[90:93], v21 offset:16384
	s_waitcnt lgkmcnt(0)
	v_mfma_f32_16x16x32_f16 v[36:39], v[62:65], v[90:93], v[36:39]
	ds_read_b128 v[74:77], v16 offset:51200
	ds_read_b128 v[110:113], v21 offset:18432
	s_waitcnt lgkmcnt(0)
	v_mfma_f32_16x16x32_f16 v[66:69], v[62:65], v[110:113], v[66:69]
	ds_read_b128 v[118:121], v16 offset:53248
	v_mfma_f32_16x16x32_f16 v[44:47], v[74:77], v[90:93], v[44:47]
	ds_read_b128 v[122:125], v16 offset:55296
	v_mfma_f32_16x16x32_f16 v[78:81], v[74:77], v[110:113], v[78:81]
	s_waitcnt vmcnt(7)
	ds_write_b128 v17, v[58:61]
	s_waitcnt lgkmcnt(2)
	v_mfma_f32_16x16x32_f16 v[82:85], v[118:121], v[90:93], v[82:85]
	s_waitcnt vmcnt(6)
	ds_write_b128 v18, v[106:109]
	v_mfma_f32_16x16x32_f16 v[86:89], v[118:121], v[110:113], v[86:89]
	s_waitcnt vmcnt(5)
	ds_write_b128 v19, v[134:137]
	s_waitcnt lgkmcnt(3)
	v_mfma_f32_16x16x32_f16 v[28:31], v[122:125], v[90:93], v[28:31]
	ds_read_b128 v[90:93], v21 offset:20480
	v_mfma_f32_16x16x32_f16 v[32:35], v[122:125], v[110:113], v[32:35]
	ds_read_b128 v[110:113], v21 offset:22528
	s_waitcnt lgkmcnt(1)
	v_mfma_f32_16x16x32_f16 v[98:101], v[62:65], v[90:93], v[98:101]
	s_waitcnt vmcnt(4)
	ds_write_b128 v20, v[158:161]
	s_waitcnt lgkmcnt(1)
	v_mfma_f32_16x16x32_f16 v[52:55], v[62:65], v[110:113], v[52:55]
	ds_read_b128 v[62:65], v22 offset:49152
	v_mfma_f32_16x16x32_f16 v[102:105], v[74:77], v[90:93], v[102:105]
	s_waitcnt vmcnt(3)
; #define GL_LOAD(s_, kt_) if (VAR != 1) { a##s_##0 = GL_A(0, kt_); a##s_##1 = GL_A(1, kt_); a##s_##2 = GL_A(2, kt_); a##s_##3 = GL_A(3, kt_); b##s_##0 = GL_B(0, kt_); b##s_##1 = GL_B(1, kt_); b##s_##2 = GL_B(2, kt_); b##s_##3 = GL_B(3, kt_); }
; #define LDS_STORE(s_, buf_) if (VAR != 2) { LDS_ST1(sA, 0, buf_, a##s_##0) LDS_ST1(sA, 1, buf_, a##s_##1) LDS_ST1(sA, 2, buf_, a##s_##2) LDS_ST1(sA, 3, buf_, a##s_##3) LDS_ST1(sB, 0, buf_, b##s_##0) LDS_ST1(sB, 1, buf_, b##s_##1) LDS_ST1(sB, 2, buf_, b##s_##2) LDS_ST1(sB, 3, buf_, b##s_##3) }
;     ...
;   GL_LOAD(0, 0)
;   GL_LOAD(1, 1)
;   LDS_STORE(0, 0)
;   if (VAR != 4) __syncthreads();
; #pragma unroll
;   for (int kt = 0; kt < nk; kt += 2) {
;     if (kt + 2 < nk) { GL_LOAD(0, kt + 2) }
;     MMA_TILE(0)
;     LDS_STORE(1, 1)
;     if (VAR != 4) __syncthreads();
;     if (kt + 3 < nk) { GL_LOAD(1, kt + 3) }
;     MMA_TILE(1)
;     if (kt + 2 < nk) { LDS_STORE(0, 0) }
;     if (VAR != 4) __syncthreads();
	ds_write_b128 v17, v[94:97] offset:32768
	v_mfma_f32_16x16x32_f16 v[24:27], v[74:77], v[110:113], v[24:27]
	ds_read_b128 v[74:77], v22 offset:51200
	v_mfma_f32_16x16x32_f16 v[114:117], v[118:121], v[90:93], v[114:117]
	s_waitcnt vmcnt(2)
	ds_write_b128 v18, v[162:165] offset:32768
	v_mfma_f32_16x16x32_f16 v[40:43], v[118:121], v[110:113], v[40:43]
	ds_read_b128 v[118:121], v22 offset:53248
	v_mfma_f32_16x16x32_f16 v[70:73], v[122:125], v[90:93], v[70:73]
	ds_read_b128 v[90:93], v23 offset:16384
	v_mfma_f32_16x16x32_f16 v[48:51], v[122:125], v[110:113], v[48:51]
	ds_read_b128 v[110:113], v23 offset:18432
	s_waitcnt lgkmcnt(1)
	v_mfma_f32_16x16x32_f16 v[36:39], v[62:65], v[90:93], v[36:39]
	ds_read_b128 v[122:125], v22 offset:55296
	s_waitcnt lgkmcnt(1)
	v_mfma_f32_16x16x32_f16 v[66:69], v[62:65], v[110:113], v[66:69]
	s_waitcnt vmcnt(1)
	ds_write_b128 v19, v[166:169] offset:32768
	v_mfma_f32_16x16x32_f16 v[44:47], v[74:77], v[90:93], v[44:47]
	s_waitcnt vmcnt(0)
	ds_write_b128 v20, v[190:193] offset:32768
	v_mfma_f32_16x16x32_f16 v[78:81], v[74:77], v[110:113], v[78:81]
	v_mfma_f32_16x16x32_f16 v[82:85], v[118:121], v[90:93], v[82:85]
	v_mfma_f32_16x16x32_f16 v[86:89], v[118:121], v[110:113], v[86:89]
	s_waitcnt lgkmcnt(2)
	v_mfma_f32_16x16x32_f16 v[28:31], v[122:125], v[90:93], v[28:31]
	ds_read_b128 v[90:93], v23 offset:20480
	v_mfma_f32_16x16x32_f16 v[32:35], v[122:125], v[110:113], v[32:35]
	ds_read_b128 v[110:113], v23 offset:22528
	s_waitcnt lgkmcnt(1)
	v_mfma_f32_16x16x32_f16 v[98:101], v[62:65], v[90:93], v[98:101]
	s_waitcnt lgkmcnt(0)
	v_mfma_f32_16x16x32_f16 v[52:55], v[62:65], v[110:113], v[52:55]
	global_load_dwordx4 v[62:65], v[0:1], off offset:1408
	v_mfma_f32_16x16x32_f16 v[102:105], v[74:77], v[90:93], v[102:105]
	v_mfma_f32_16x16x32_f16 v[24:27], v[74:77], v[110:113], v[24:27]
	v_mfma_f32_16x16x32_f16 v[114:117], v[118:121], v[90:93], v[114:117]
	v_mfma_f32_16x16x32_f16 v[40:43], v[118:121], v[110:113], v[40:43]
	v_mfma_f32_16x16x32_f16 v[70:73], v[122:125], v[90:93], v[70:73]
	global_load_dwordx4 v[90:93], v[2:3], off offset:1408
	global_load_dwordx4 v[126:129], v[4:5], off offset:1408
	global_load_dwordx4 v[130:133], v[14:15], off offset:1408
	global_load_dwordx4 v[74:77], v[10:11], off offset:1408
	global_load_dwordx4 v[138:141], v[12:13], off offset:1408
	global_load_dwordx4 v[142:145], v[8:9], off offset:1408
	global_load_dwordx4 v[154:157], v[6:7], off offset:1408
	s_waitcnt lgkmcnt(0)
	s_barrier
	v_mfma_f32_16x16x32_f16 v[48:51], v[122:125], v[110:113], v[48:51]
	ds_read_b128 v[58:61], v16 offset:32768
	ds_read_b128 v[106:109], v21
	s_waitcnt lgkmcnt(0)
	v_mfma_f32_16x16x32_f16 v[36:39], v[58:61], v[106:109], v[36:39]
	ds_read_b128 v[94:97], v16 offset:34816
	ds_read_b128 v[110:113], v21 offset:2048
	s_waitcnt lgkmcnt(0)
	v_mfma_f32_16x16x32_f16 v[66:69], v[58:61], v[110:113], v[66:69]
	ds_read_b128 v[118:121], v16 offset:36864
	v_mfma_f32_16x16x32_f16 v[44:47], v[94:97], v[106:109], v[44:47]
	ds_read_b128 v[122:125], v16 offset:38912
	v_mfma_f32_16x16x32_f16 v[78:81], v[94:97], v[110:113], v[78:81]
	s_waitcnt vmcnt(7)
	ds_write_b128 v17, v[62:65] offset:16384
	s_waitcnt lgkmcnt(2)
	v_mfma_f32_16x16x32_f16 v[82:85], v[118:121], v[106:109], v[82:85]
	s_waitcnt vmcnt(6)
	ds_write_b128 v18, v[90:93] offset:16384
	v_mfma_f32_16x16x32_f16 v[86:89], v[118:121], v[110:113], v[86:89]
	s_waitcnt vmcnt(5)
	ds_write_b128 v19, v[126:129] offset:16384
	s_waitcnt lgkmcnt(3)
	v_mfma_f32_16x16x32_f16 v[28:31], v[122:125], v[106:109], v[28:31]
	ds_read_b128 v[106:109], v21 offset:4096
	v_mfma_f32_16x16x32_f16 v[32:35], v[122:125], v[110:113], v[32:35]
	ds_read_b128 v[110:113], v21 offset:6144
	s_waitcnt lgkmcnt(1)
	v_mfma_f32_16x16x32_f16 v[98:101], v[58:61], v[106:109], v[98:101]
	s_waitcnt vmcnt(4)
	ds_write_b128 v20, v[130:133] offset:16384
	s_waitcnt lgkmcnt(1)
	v_mfma_f32_16x16x32_f16 v[52:55], v[58:61], v[110:113], v[52:55]
	ds_read_b128 v[58:61], v22 offset:32768
	v_mfma_f32_16x16x32_f16 v[102:105], v[94:97], v[106:109], v[102:105]
	s_waitcnt vmcnt(3)
	ds_write_b128 v17, v[74:77] offset:49152
	v_mfma_f32_16x16x32_f16 v[24:27], v[94:97], v[110:113], v[24:27]
	ds_read_b128 v[94:97], v22 offset:34816
	v_mfma_f32_16x16x32_f16 v[114:117], v[118:121], v[106:109], v[114:117]
	s_waitcnt vmcnt(2)
	ds_write_b128 v18, v[138:141] offset:49152
	v_mfma_f32_16x16x32_f16 v[40:43], v[118:121], v[110:113], v[40:43]
	ds_read_b128 v[118:121], v22 offset:36864
	v_mfma_f32_16x16x32_f16 v[70:73], v[122:125], v[106:109], v[70:73]
	ds_read_b128 v[106:109], v23
	v_mfma_f32_16x16x32_f16 v[48:51], v[122:125], v[110:113], v[48:51]
	ds_read_b128 v[110:113], v23 offset:2048
	s_waitcnt lgkmcnt(1)
	v_mfma_f32_16x16x32_f16 v[36:39], v[58:61], v[106:109], v[36:39]
	ds_read_b128 v[122:125], v22 offset:38912
	s_waitcnt lgkmcnt(1)
	v_mfma_f32_16x16x32_f16 v[66:69], v[58:61], v[110:113], v[66:69]
	s_waitcnt vmcnt(1)
	ds_write_b128 v19, v[142:145] offset:49152
	v_mfma_f32_16x16x32_f16 v[44:47], v[94:97], v[106:109], v[44:47]
	s_waitcnt vmcnt(0)
	ds_write_b128 v20, v[154:157] offset:49152
	v_mfma_f32_16x16x32_f16 v[78:81], v[94:97], v[110:113], v[78:81]
	v_mfma_f32_16x16x32_f16 v[82:85], v[118:121], v[106:109], v[82:85]
	v_mfma_f32_16x16x32_f16 v[86:89], v[118:121], v[110:113], v[86:89]
	s_waitcnt lgkmcnt(2)
	v_mfma_f32_16x16x32_f16 v[28:31], v[122:125], v[106:109], v[28:31]
	ds_read_b128 v[106:109], v23 offset:4096
	v_mfma_f32_16x16x32_f16 v[32:35], v[122:125], v[110:113], v[32:35]
	ds_read_b128 v[110:113], v23 offset:6144
	s_waitcnt lgkmcnt(1)
	v_mfma_f32_16x16x32_f16 v[98:101], v[58:61], v[106:109], v[98:101]
	s_waitcnt lgkmcnt(0)
	v_mfma_f32_16x16x32_f16 v[52:55], v[58:61], v[110:113], v[52:55]
	global_load_dwordx4 v[58:61], v[0:1], off offset:1536
	v_mfma_f32_16x16x32_f16 v[102:105], v[94:97], v[106:109], v[102:105]
	v_mfma_f32_16x16x32_f16 v[24:27], v[94:97], v[110:113], v[24:27]
	v_mfma_f32_16x16x32_f16 v[114:117], v[118:121], v[106:109], v[114:117]
	v_mfma_f32_16x16x32_f16 v[40:43], v[118:121], v[110:113], v[40:43]
	v_mfma_f32_16x16x32_f16 v[70:73], v[122:125], v[106:109], v[70:73]
	global_load_dwordx4 v[106:109], v[2:3], off offset:1536
	global_load_dwordx4 v[134:137], v[4:5], off offset:1536
	global_load_dwordx4 v[158:161], v[14:15], off offset:1536
	global_load_dwordx4 v[94:97], v[10:11], off offset:1536
	global_load_dwordx4 v[162:165], v[12:13], off offset:1536
	global_load_dwordx4 v[166:169], v[8:9], off offset:1536
	global_load_dwordx4 v[190:193], v[6:7], off offset:1536
	s_waitcnt lgkmcnt(0)
	s_barrier
; #define GL_LOAD(s_, kt_) if (VAR != 1) { a##s_##0 = GL_A(0, kt_); a##s_##1 = GL_A(1, kt_); a##s_##2 = GL_A(2, kt_); a##s_##3 = GL_A(3, kt_); b##s_##0 = GL_B(0, kt_); b##s_##1 = GL_B(1, kt_); b##s_##2 = GL_B(2, kt_); b##s_##3 = GL_B(3, kt_); }
; #define LDS_STORE(s_, buf_) if (VAR != 2) { LDS_ST1(sA, 0, buf_, a##s_##0) LDS_ST1(sA, 1, buf_, a##s_##1) LDS_ST1(sA, 2, buf_, a##s_##2) LDS_ST1(sA, 3, buf_, a##s_##3) LDS_ST1(sB, 0, buf_, b##s_##0) LDS_ST1(sB, 1, buf_, b##s_##1) LDS_ST1(sB, 2, buf_, b##s_##2) LDS_ST1(sB, 3, buf_, b##s_##3) }
;     ...
;   GL_LOAD(0, 0)
;   GL_LOAD(1, 1)
;   LDS_STORE(0, 0)
;   if (VAR != 4) __syncthreads();
; #pragma unroll
;   for (int kt = 0; kt < nk; kt += 2) {
;     if (kt + 2 < nk) { GL_LOAD(0, kt + 2) }
;     MMA_TILE(0)
;     LDS_STORE(1, 1)
;     if (VAR != 4) __syncthreads();
;     if (kt + 3 < nk) { GL_LOAD(1, kt + 3) }
;     MMA_TILE(1)
;     if (kt + 2 < nk) { LDS_STORE(0, 0) }
;     if (VAR != 4) __syncthreads();
	v_mfma_f32_16x16x32_f16 v[48:51], v[122:125], v[110:113], v[48:51]
	ds_read_b128 v[62:65], v16 offset:49152
	ds_read_b128 v[90:93], v21 offset:16384
	s_waitcnt lgkmcnt(0)
	v_mfma_f32_16x16x32_f16 v[36:39], v[62:65], v[90:93], v[36:39]
	ds_read_b128 v[74:77], v16 offset:51200
	ds_read_b128 v[110:113], v21 offset:18432
	s_waitcnt lgkmcnt(0)
	v_mfma_f32_16x16x32_f16 v[66:69], v[62:65], v[110:113], v[66:69]
	ds_read_b128 v[118:121], v16 offset:53248
	v_mfma_f32_16x16x32_f16 v[44:47], v[74:77], v[90:93], v[44:47]
	ds_read_b128 v[122:125], v16 offset:55296
	v_mfma_f32_16x16x32_f16 v[78:81], v[74:77], v[110:113], v[78:81]
	s_waitcnt vmcnt(7)
	ds_write_b128 v17, v[58:61]
	s_waitcnt lgkmcnt(2)
	v_mfma_f32_16x16x32_f16 v[82:85], v[118:121], v[90:93], v[82:85]
	s_waitcnt vmcnt(6)
	ds_write_b128 v18, v[106:109]
	v_mfma_f32_16x16x32_f16 v[86:89], v[118:121], v[110:113], v[86:89]
	s_waitcnt vmcnt(5)
	ds_write_b128 v19, v[134:137]
	s_waitcnt lgkmcnt(3)
	v_mfma_f32_16x16x32_f16 v[28:31], v[122:125], v[90:93], v[28:31]
	ds_read_b128 v[90:93], v21 offset:20480
	v_mfma_f32_16x16x32_f16 v[32:35], v[122:125], v[110:113], v[32:35]
	ds_read_b128 v[110:113], v21 offset:22528
	s_waitcnt lgkmcnt(1)
	v_mfma_f32_16x16x32_f16 v[98:101], v[62:65], v[90:93], v[98:101]
	s_waitcnt vmcnt(4)
	ds_write_b128 v20, v[158:161]
	s_waitcnt lgkmcnt(1)
	v_mfma_f32_16x16x32_f16 v[52:55], v[62:65], v[110:113], v[52:55]
	ds_read_b128 v[62:65], v22 offset:49152
	v_mfma_f32_16x16x32_f16 v[102:105], v[74:77], v[90:93], v[102:105]
	s_waitcnt vmcnt(3)
	ds_write_b128 v17, v[94:97] offset:32768
	v_mfma_f32_16x16x32_f16 v[24:27], v[74:77], v[110:113], v[24:27]
	ds_read_b128 v[74:77], v22 offset:51200
	v_mfma_f32_16x16x32_f16 v[114:117], v[118:121], v[90:93], v[114:117]
	s_waitcnt vmcnt(2)
	ds_write_b128 v18, v[162:165] offset:32768
	v_mfma_f32_16x16x32_f16 v[40:43], v[118:121], v[110:113], v[40:43]
	ds_read_b128 v[118:121], v22 offset:53248
	v_mfma_f32_16x16x32_f16 v[70:73], v[122:125], v[90:93], v[70:73]
	ds_read_b128 v[90:93], v23 offset:16384
	v_mfma_f32_16x16x32_f16 v[48:51], v[122:125], v[110:113], v[48:51]
	ds_read_b128 v[110:113], v23 offset:18432
	s_waitcnt lgkmcnt(1)
	v_mfma_f32_16x16x32_f16 v[36:39], v[62:65], v[90:93], v[36:39]
	ds_read_b128 v[122:125], v22 offset:55296
	s_waitcnt lgkmcnt(1)
	v_mfma_f32_16x16x32_f16 v[66:69], v[62:65], v[110:113], v[66:69]
	s_waitcnt vmcnt(1)
	ds_write_b128 v19, v[166:169] offset:32768
	v_mfma_f32_16x16x32_f16 v[44:47], v[74:77], v[90:93], v[44:47]
	s_waitcnt vmcnt(0)
	ds_write_b128 v20, v[190:193] offset:32768
	v_mfma_f32_16x16x32_f16 v[78:81], v[74:77], v[110:113], v[78:81]
	v_mfma_f32_16x16x32_f16 v[82:85], v[118:121], v[90:93], v[82:85]
	v_mfma_f32_16x16x32_f16 v[86:89], v[118:121], v[110:113], v[86:89]
	s_waitcnt lgkmcnt(2)
	v_mfma_f32_16x16x32_f16 v[28:31], v[122:125], v[90:93], v[28:31]
	ds_read_b128 v[90:93], v23 offset:20480
	v_mfma_f32_16x16x32_f16 v[32:35], v[122:125], v[110:113], v[32:35]
	ds_read_b128 v[110:113], v23 offset:22528
	s_waitcnt lgkmcnt(1)
	v_mfma_f32_16x16x32_f16 v[98:101], v[62:65], v[90:93], v[98:101]
	s_waitcnt lgkmcnt(0)
	v_mfma_f32_16x16x32_f16 v[52:55], v[62:65], v[110:113], v[52:55]
	global_load_dwordx4 v[62:65], v[0:1], off offset:1664
	v_mfma_f32_16x16x32_f16 v[102:105], v[74:77], v[90:93], v[102:105]
	v_mfma_f32_16x16x32_f16 v[24:27], v[74:77], v[110:113], v[24:27]
	v_mfma_f32_16x16x32_f16 v[114:117], v[118:121], v[90:93], v[114:117]
	v_mfma_f32_16x16x32_f16 v[40:43], v[118:121], v[110:113], v[40:43]
	v_mfma_f32_16x16x32_f16 v[70:73], v[122:125], v[90:93], v[70:73]
	global_load_dwordx4 v[90:93], v[2:3], off offset:1664
	global_load_dwordx4 v[126:129], v[4:5], off offset:1664
	global_load_dwordx4 v[130:133], v[14:15], off offset:1664
	global_load_dwordx4 v[74:77], v[10:11], off offset:1664
	global_load_dwordx4 v[138:141], v[12:13], off offset:1664
	global_load_dwordx4 v[142:145], v[8:9], off offset:1664
	global_load_dwordx4 v[154:157], v[6:7], off offset:1664
	s_waitcnt lgkmcnt(0)
	s_barrier
	v_mfma_f32_16x16x32_f16 v[48:51], v[122:125], v[110:113], v[48:51]
	ds_read_b128 v[58:61], v16 offset:32768
	ds_read_b128 v[106:109], v21
	s_waitcnt lgkmcnt(0)
	v_mfma_f32_16x16x32_f16 v[36:39], v[58:61], v[106:109], v[36:39]
	ds_read_b128 v[94:97], v16 offset:34816
	ds_read_b128 v[110:113], v21 offset:2048
	s_waitcnt lgkmcnt(0)
	v_mfma_f32_16x16x32_f16 v[66:69], v[58:61], v[110:113], v[66:69]
	ds_read_b128 v[118:121], v16 offset:36864
	v_mfma_f32_16x16x32_f16 v[44:47], v[94:97], v[106:109], v[44:47]
	ds_read_b128 v[122:125], v16 offset:38912
	v_mfma_f32_16x16x32_f16 v[78:81], v[94:97], v[110:113], v[78:81]
	s_waitcnt vmcnt(7)
	ds_write_b128 v17, v[62:65] offset:16384
	s_waitcnt lgkmcnt(2)
	v_mfma_f32_16x16x32_f16 v[82:85], v[118:121], v[106:109], v[82:85]
	s_waitcnt vmcnt(6)
	ds_write_b128 v18, v[90:93] offset:16384
	v_mfma_f32_16x16x32_f16 v[86:89], v[118:121], v[110:113], v[86:89]
	s_waitcnt vmcnt(5)
	ds_write_b128 v19, v[126:129] offset:16384
	s_waitcnt lgkmcnt(3)
	v_mfma_f32_16x16x32_f16 v[28:31], v[122:125], v[106:109], v[28:31]
	ds_read_b128 v[106:109], v21 offset:4096
	v_mfma_f32_16x16x32_f16 v[32:35], v[122:125], v[110:113], v[32:35]
	ds_read_b128 v[110:113], v21 offset:6144
	s_waitcnt lgkmcnt(1)
	v_mfma_f32_16x16x32_f16 v[98:101], v[58:61], v[106:109], v[98:101]
	s_waitcnt vmcnt(4)
	ds_write_b128 v20, v[130:133] offset:16384
	s_waitcnt lgkmcnt(1)
	v_mfma_f32_16x16x32_f16 v[52:55], v[58:61], v[110:113], v[52:55]
	ds_read_b128 v[58:61], v22 offset:32768
	v_mfma_f32_16x16x32_f16 v[102:105], v[94:97], v[106:109], v[102:105]
	s_waitcnt vmcnt(3)
; #define GL_LOAD(s_, kt_) if (VAR != 1) { a##s_##0 = GL_A(0, kt_); a##s_##1 = GL_A(1, kt_); a##s_##2 = GL_A(2, kt_); a##s_##3 = GL_A(3, kt_); b##s_##0 = GL_B(0, kt_); b##s_##1 = GL_B(1, kt_); b##s_##2 = GL_B(2, kt_); b##s_##3 = GL_B(3, kt_); }
; #define LDS_STORE(s_, buf_) if (VAR != 2) { LDS_ST1(sA, 0, buf_, a##s_##0) LDS_ST1(sA, 1, buf_, a##s_##1) LDS_ST1(sA, 2, buf_, a##s_##2) LDS_ST1(sA, 3, buf_, a##s_##3) LDS_ST1(sB, 0, buf_, b##s_##0) LDS_ST1(sB, 1, buf_, b##s_##1) LDS_ST1(sB, 2, buf_, b##s_##2) LDS_ST1(sB, 3, buf_, b##s_##3) }
;     ...
;   GL_LOAD(0, 0)
;   GL_LOAD(1, 1)
;   LDS_STORE(0, 0)
;   if (VAR != 4) __syncthreads();
; #pragma unroll
;   for (int kt = 0; kt < nk; kt += 2) {
;     if (kt + 2 < nk) { GL_LOAD(0, kt + 2) }
;     MMA_TILE(0)
;     LDS_STORE(1, 1)
;     if (VAR != 4) __syncthreads();
;     if (kt + 3 < nk) { GL_LOAD(1, kt + 3) }
;     MMA_TILE(1)
;     if (kt + 2 < nk) { LDS_STORE(0, 0) }
;     if (VAR != 4) __syncthreads();
	ds_write_b128 v17, v[74:77] offset:49152
	v_mfma_f32_16x16x32_f16 v[24:27], v[94:97], v[110:113], v[24:27]
	ds_read_b128 v[94:97], v22 offset:34816
	v_mfma_f32_16x16x32_f16 v[114:117], v[118:121], v[106:109], v[114:117]
	s_waitcnt vmcnt(2)
	ds_write_b128 v18, v[138:141] offset:49152
	v_mfma_f32_16x16x32_f16 v[40:43], v[118:121], v[110:113], v[40:43]
	ds_read_b128 v[118:121], v22 offset:36864
	v_mfma_f32_16x16x32_f16 v[70:73], v[122:125], v[106:109], v[70:73]
	ds_read_b128 v[106:109], v23
	v_mfma_f32_16x16x32_f16 v[48:51], v[122:125], v[110:113], v[48:51]
	ds_read_b128 v[110:113], v23 offset:2048
	s_waitcnt lgkmcnt(1)
	v_mfma_f32_16x16x32_f16 v[36:39], v[58:61], v[106:109], v[36:39]
	ds_read_b128 v[122:125], v22 offset:38912
	s_waitcnt lgkmcnt(1)
	v_mfma_f32_16x16x32_f16 v[66:69], v[58:61], v[110:113], v[66:69]
	s_waitcnt vmcnt(1)
	ds_write_b128 v19, v[142:145] offset:49152
	v_mfma_f32_16x16x32_f16 v[44:47], v[94:97], v[106:109], v[44:47]
	s_waitcnt vmcnt(0)
	ds_write_b128 v20, v[154:157] offset:49152
	v_mfma_f32_16x16x32_f16 v[78:81], v[94:97], v[110:113], v[78:81]
	v_mfma_f32_16x16x32_f16 v[82:85], v[118:121], v[106:109], v[82:85]
	v_mfma_f32_16x16x32_f16 v[86:89], v[118:121], v[110:113], v[86:89]
	s_waitcnt lgkmcnt(2)
	v_mfma_f32_16x16x32_f16 v[28:31], v[122:125], v[106:109], v[28:31]
	ds_read_b128 v[106:109], v23 offset:4096
	v_mfma_f32_16x16x32_f16 v[32:35], v[122:125], v[110:113], v[32:35]
	ds_read_b128 v[110:113], v23 offset:6144
	s_waitcnt lgkmcnt(1)
	v_mfma_f32_16x16x32_f16 v[98:101], v[58:61], v[106:109], v[98:101]
	s_waitcnt lgkmcnt(0)
	v_mfma_f32_16x16x32_f16 v[52:55], v[58:61], v[110:113], v[52:55]
	global_load_dwordx4 v[58:61], v[0:1], off offset:1792
	v_mfma_f32_16x16x32_f16 v[102:105], v[94:97], v[106:109], v[102:105]
	v_mfma_f32_16x16x32_f16 v[24:27], v[94:97], v[110:113], v[24:27]
	v_mfma_f32_16x16x32_f16 v[114:117], v[118:121], v[106:109], v[114:117]
	v_mfma_f32_16x16x32_f16 v[40:43], v[118:121], v[110:113], v[40:43]
	v_mfma_f32_16x16x32_f16 v[70:73], v[122:125], v[106:109], v[70:73]
	global_load_dwordx4 v[106:109], v[2:3], off offset:1792
	global_load_dwordx4 v[134:137], v[4:5], off offset:1792
	global_load_dwordx4 v[158:161], v[14:15], off offset:1792
	global_load_dwordx4 v[94:97], v[10:11], off offset:1792
	global_load_dwordx4 v[162:165], v[12:13], off offset:1792
	global_load_dwordx4 v[166:169], v[8:9], off offset:1792
	global_load_dwordx4 v[190:193], v[6:7], off offset:1792
	s_waitcnt lgkmcnt(0)
	s_barrier
	v_mfma_f32_16x16x32_f16 v[48:51], v[122:125], v[110:113], v[48:51]
	ds_read_b128 v[62:65], v16 offset:49152
	ds_read_b128 v[90:93], v21 offset:16384
	s_waitcnt lgkmcnt(0)
	v_mfma_f32_16x16x32_f16 v[36:39], v[62:65], v[90:93], v[36:39]
	ds_read_b128 v[74:77], v16 offset:51200
	ds_read_b128 v[110:113], v21 offset:18432
	s_waitcnt lgkmcnt(0)
	v_mfma_f32_16x16x32_f16 v[66:69], v[62:65], v[110:113], v[66:69]
	ds_read_b128 v[118:121], v16 offset:53248
	v_mfma_f32_16x16x32_f16 v[44:47], v[74:77], v[90:93], v[44:47]
	ds_read_b128 v[122:125], v16 offset:55296
	v_mfma_f32_16x16x32_f16 v[78:81], v[74:77], v[110:113], v[78:81]
	s_waitcnt vmcnt(7)
	ds_write_b128 v17, v[58:61]
	s_waitcnt lgkmcnt(2)
	v_mfma_f32_16x16x32_f16 v[82:85], v[118:121], v[90:93], v[82:85]
	s_waitcnt vmcnt(6)
	ds_write_b128 v18, v[106:109]
	v_mfma_f32_16x16x32_f16 v[86:89], v[118:121], v[110:113], v[86:89]
	s_waitcnt vmcnt(5)
	ds_write_b128 v19, v[134:137]
	s_waitcnt lgkmcnt(3)
	v_mfma_f32_16x16x32_f16 v[28:31], v[122:125], v[90:93], v[28:31]
	ds_read_b128 v[90:93], v21 offset:20480
	v_mfma_f32_16x16x32_f16 v[32:35], v[122:125], v[110:113], v[32:35]
	ds_read_b128 v[110:113], v21 offset:22528
	s_waitcnt lgkmcnt(1)
	v_mfma_f32_16x16x32_f16 v[98:101], v[62:65], v[90:93], v[98:101]
	s_waitcnt vmcnt(4)
	ds_write_b128 v20, v[158:161]
	s_waitcnt lgkmcnt(1)
	v_mfma_f32_16x16x32_f16 v[52:55], v[62:65], v[110:113], v[52:55]
	ds_read_b128 v[62:65], v22 offset:49152
	v_mfma_f32_16x16x32_f16 v[102:105], v[74:77], v[90:93], v[102:105]
	s_waitcnt vmcnt(3)
	ds_write_b128 v17, v[94:97] offset:32768
	v_mfma_f32_16x16x32_f16 v[24:27], v[74:77], v[110:113], v[24:27]
	ds_read_b128 v[74:77], v22 offset:51200
	v_mfma_f32_16x16x32_f16 v[114:117], v[118:121], v[90:93], v[114:117]
	s_waitcnt vmcnt(2)
	ds_write_b128 v18, v[162:165] offset:32768
	v_mfma_f32_16x16x32_f16 v[40:43], v[118:121], v[110:113], v[40:43]
	ds_read_b128 v[118:121], v22 offset:53248
	v_mfma_f32_16x16x32_f16 v[70:73], v[122:125], v[90:93], v[70:73]
	ds_read_b128 v[90:93], v23 offset:16384
	v_mfma_f32_16x16x32_f16 v[48:51], v[122:125], v[110:113], v[48:51]
	ds_read_b128 v[110:113], v23 offset:18432
	s_waitcnt lgkmcnt(1)
	v_mfma_f32_16x16x32_f16 v[36:39], v[62:65], v[90:93], v[36:39]
	ds_read_b128 v[122:125], v22 offset:55296
	s_waitcnt lgkmcnt(1)
	v_mfma_f32_16x16x32_f16 v[66:69], v[62:65], v[110:113], v[66:69]
	s_waitcnt vmcnt(1)
	ds_write_b128 v19, v[166:169] offset:32768
	v_mfma_f32_16x16x32_f16 v[44:47], v[74:77], v[90:93], v[44:47]
	s_waitcnt vmcnt(0)
	ds_write_b128 v20, v[190:193] offset:32768
	v_mfma_f32_16x16x32_f16 v[78:81], v[74:77], v[110:113], v[78:81]
	v_mfma_f32_16x16x32_f16 v[82:85], v[118:121], v[90:93], v[82:85]
	v_mfma_f32_16x16x32_f16 v[86:89], v[118:121], v[110:113], v[86:89]
	s_waitcnt lgkmcnt(2)
	v_mfma_f32_16x16x32_f16 v[28:31], v[122:125], v[90:93], v[28:31]
	ds_read_b128 v[90:93], v23 offset:20480
	v_mfma_f32_16x16x32_f16 v[32:35], v[122:125], v[110:113], v[32:35]
	ds_read_b128 v[110:113], v23 offset:22528
	s_waitcnt lgkmcnt(1)
	v_mfma_f32_16x16x32_f16 v[98:101], v[62:65], v[90:93], v[98:101]
	s_waitcnt lgkmcnt(0)
	v_mfma_f32_16x16x32_f16 v[52:55], v[62:65], v[110:113], v[52:55]
	global_load_dwordx4 v[62:65], v[0:1], off offset:1920
	v_mfma_f32_16x16x32_f16 v[102:105], v[74:77], v[90:93], v[102:105]
	v_mfma_f32_16x16x32_f16 v[24:27], v[74:77], v[110:113], v[24:27]
	v_mfma_f32_16x16x32_f16 v[114:117], v[118:121], v[90:93], v[114:117]
	v_mfma_f32_16x16x32_f16 v[40:43], v[118:121], v[110:113], v[40:43]
	v_mfma_f32_16x16x32_f16 v[70:73], v[122:125], v[90:93], v[70:73]
	global_load_dwordx4 v[90:93], v[2:3], off offset:1920
	global_load_dwordx4 v[126:129], v[4:5], off offset:1920
	global_load_dwordx4 v[130:133], v[14:15], off offset:1920
	global_load_dwordx4 v[74:77], v[10:11], off offset:1920
	global_load_dwordx4 v[138:141], v[12:13], off offset:1920
	global_load_dwordx4 v[142:145], v[8:9], off offset:1920
	global_load_dwordx4 v[154:157], v[6:7], off offset:1920
	s_waitcnt lgkmcnt(0)
	s_barrier
; #define GL_LOAD(s_, kt_) if (VAR != 1) { a##s_##0 = GL_A(0, kt_); a##s_##1 = GL_A(1, kt_); a##s_##2 = GL_A(2, kt_); a##s_##3 = GL_A(3, kt_); b##s_##0 = GL_B(0, kt_); b##s_##1 = GL_B(1, kt_); b##s_##2 = GL_B(2, kt_); b##s_##3 = GL_B(3, kt_); }
; #define LDS_STORE(s_, buf_) if (VAR != 2) { LDS_ST1(sA, 0, buf_, a##s_##0) LDS_ST1(sA, 1, buf_, a##s_##1) LDS_ST1(sA, 2, buf_, a##s_##2) LDS_ST1(sA, 3, buf_, a##s_##3) LDS_ST1(sB, 0, buf_, b##s_##0) LDS_ST1(sB, 1, buf_, b##s_##1) LDS_ST1(sB, 2, buf_, b##s_##2) LDS_ST1(sB, 3, buf_, b##s_##3) }
;     ...
;   GL_LOAD(0, 0)
;   GL_LOAD(1, 1)
;   LDS_STORE(0, 0)
;   if (VAR != 4) __syncthreads();
; #pragma unroll
;   for (int kt = 0; kt < nk; kt += 2) {
;     if (kt + 2 < nk) { GL_LOAD(0, kt + 2) }
;     MMA_TILE(0)
;     LDS_STORE(1, 1)
;     if (VAR != 4) __syncthreads();
;     if (kt + 3 < nk) { GL_LOAD(1, kt + 3) }
;     MMA_TILE(1)
;     if (kt + 2 < nk) { LDS_STORE(0, 0) }
;     if (VAR != 4) __syncthreads();
	v_mfma_f32_16x16x32_f16 v[48:51], v[122:125], v[110:113], v[48:51]
	ds_read_b128 v[58:61], v16 offset:32768
	ds_read_b128 v[106:109], v21
	s_waitcnt lgkmcnt(0)
	v_mfma_f32_16x16x32_f16 v[36:39], v[58:61], v[106:109], v[36:39]
	ds_read_b128 v[94:97], v16 offset:34816
	ds_read_b128 v[110:113], v21 offset:2048
	s_waitcnt lgkmcnt(0)
	v_mfma_f32_16x16x32_f16 v[66:69], v[58:61], v[110:113], v[66:69]
	ds_read_b128 v[118:121], v16 offset:36864
	v_mfma_f32_16x16x32_f16 v[44:47], v[94:97], v[106:109], v[44:47]
	ds_read_b128 v[122:125], v16 offset:38912
	v_mfma_f32_16x16x32_f16 v[78:81], v[94:97], v[110:113], v[78:81]
	s_waitcnt vmcnt(7)
	ds_write_b128 v17, v[62:65] offset:16384
	s_waitcnt lgkmcnt(2)
	v_mfma_f32_16x16x32_f16 v[82:85], v[118:121], v[106:109], v[82:85]
	s_waitcnt vmcnt(6)
	ds_write_b128 v18, v[90:93] offset:16384
	v_mfma_f32_16x16x32_f16 v[86:89], v[118:121], v[110:113], v[86:89]
	s_waitcnt vmcnt(5)
	ds_write_b128 v19, v[126:129] offset:16384
	s_waitcnt lgkmcnt(3)
	v_mfma_f32_16x16x32_f16 v[28:31], v[122:125], v[106:109], v[28:31]
	ds_read_b128 v[106:109], v21 offset:4096
	v_mfma_f32_16x16x32_f16 v[32:35], v[122:125], v[110:113], v[32:35]
	ds_read_b128 v[110:113], v21 offset:6144
	s_waitcnt lgkmcnt(1)
	v_mfma_f32_16x16x32_f16 v[98:101], v[58:61], v[106:109], v[98:101]
	s_waitcnt vmcnt(4)
	ds_write_b128 v20, v[130:133] offset:16384
	s_waitcnt lgkmcnt(1)
	v_mfma_f32_16x16x32_f16 v[52:55], v[58:61], v[110:113], v[52:55]
	ds_read_b128 v[58:61], v22 offset:32768
	v_mfma_f32_16x16x32_f16 v[102:105], v[94:97], v[106:109], v[102:105]
	s_waitcnt vmcnt(3)
	ds_write_b128 v17, v[74:77] offset:49152
	v_mfma_f32_16x16x32_f16 v[24:27], v[94:97], v[110:113], v[24:27]
	ds_read_b128 v[94:97], v22 offset:34816
	v_mfma_f32_16x16x32_f16 v[114:117], v[118:121], v[106:109], v[114:117]
	s_waitcnt vmcnt(2)
	ds_write_b128 v18, v[138:141] offset:49152
	v_mfma_f32_16x16x32_f16 v[40:43], v[118:121], v[110:113], v[40:43]
	ds_read_b128 v[118:121], v22 offset:36864
	v_mfma_f32_16x16x32_f16 v[70:73], v[122:125], v[106:109], v[70:73]
	ds_read_b128 v[106:109], v23
	v_mfma_f32_16x16x32_f16 v[48:51], v[122:125], v[110:113], v[48:51]
	ds_read_b128 v[110:113], v23 offset:2048
	s_waitcnt lgkmcnt(1)
	v_mfma_f32_16x16x32_f16 v[36:39], v[58:61], v[106:109], v[36:39]
	ds_read_b128 v[122:125], v22 offset:38912
	s_waitcnt lgkmcnt(1)
	v_mfma_f32_16x16x32_f16 v[66:69], v[58:61], v[110:113], v[66:69]
	s_waitcnt vmcnt(1)
	ds_write_b128 v19, v[142:145] offset:49152
	v_mfma_f32_16x16x32_f16 v[44:47], v[94:97], v[106:109], v[44:47]
	s_waitcnt vmcnt(0)
	ds_write_b128 v20, v[154:157] offset:49152
	v_mfma_f32_16x16x32_f16 v[78:81], v[94:97], v[110:113], v[78:81]
	v_mfma_f32_16x16x32_f16 v[82:85], v[118:121], v[106:109], v[82:85]
	v_mfma_f32_16x16x32_f16 v[86:89], v[118:121], v[110:113], v[86:89]
	s_waitcnt lgkmcnt(2)
	v_mfma_f32_16x16x32_f16 v[28:31], v[122:125], v[106:109], v[28:31]
	ds_read_b128 v[106:109], v23 offset:4096
	v_mfma_f32_16x16x32_f16 v[32:35], v[122:125], v[110:113], v[32:35]
	ds_read_b128 v[110:113], v23 offset:6144
	s_waitcnt lgkmcnt(1)
	v_mfma_f32_16x16x32_f16 v[98:101], v[58:61], v[106:109], v[98:101]
	s_waitcnt lgkmcnt(0)
	v_mfma_f32_16x16x32_f16 v[52:55], v[58:61], v[110:113], v[52:55]
	global_load_dwordx4 v[58:61], v[0:1], off offset:2048
	v_mfma_f32_16x16x32_f16 v[102:105], v[94:97], v[106:109], v[102:105]
	v_mfma_f32_16x16x32_f16 v[24:27], v[94:97], v[110:113], v[24:27]
	v_mfma_f32_16x16x32_f16 v[114:117], v[118:121], v[106:109], v[114:117]
	v_mfma_f32_16x16x32_f16 v[40:43], v[118:121], v[110:113], v[40:43]
	v_mfma_f32_16x16x32_f16 v[70:73], v[122:125], v[106:109], v[70:73]
	global_load_dwordx4 v[106:109], v[2:3], off offset:2048
	global_load_dwordx4 v[134:137], v[4:5], off offset:2048
	global_load_dwordx4 v[158:161], v[14:15], off offset:2048
	global_load_dwordx4 v[94:97], v[10:11], off offset:2048
	global_load_dwordx4 v[162:165], v[12:13], off offset:2048
	global_load_dwordx4 v[166:169], v[8:9], off offset:2048
	global_load_dwordx4 v[190:193], v[6:7], off offset:2048
	s_waitcnt lgkmcnt(0)
	s_barrier
	v_mfma_f32_16x16x32_f16 v[48:51], v[122:125], v[110:113], v[48:51]
	ds_read_b128 v[62:65], v16 offset:49152
	ds_read_b128 v[90:93], v21 offset:16384
	s_waitcnt lgkmcnt(0)
	v_mfma_f32_16x16x32_f16 v[36:39], v[62:65], v[90:93], v[36:39]
	ds_read_b128 v[74:77], v16 offset:51200
	ds_read_b128 v[110:113], v21 offset:18432
	s_waitcnt lgkmcnt(0)
	v_mfma_f32_16x16x32_f16 v[66:69], v[62:65], v[110:113], v[66:69]
	ds_read_b128 v[118:121], v16 offset:53248
	v_mfma_f32_16x16x32_f16 v[44:47], v[74:77], v[90:93], v[44:47]
	ds_read_b128 v[122:125], v16 offset:55296
	v_mfma_f32_16x16x32_f16 v[78:81], v[74:77], v[110:113], v[78:81]
	s_waitcnt vmcnt(7)
	ds_write_b128 v17, v[58:61]
	s_waitcnt lgkmcnt(2)
	v_mfma_f32_16x16x32_f16 v[82:85], v[118:121], v[90:93], v[82:85]
	s_waitcnt vmcnt(6)
	ds_write_b128 v18, v[106:109]
	v_mfma_f32_16x16x32_f16 v[86:89], v[118:121], v[110:113], v[86:89]
	s_waitcnt vmcnt(5)
	ds_write_b128 v19, v[134:137]
	s_waitcnt lgkmcnt(3)
	v_mfma_f32_16x16x32_f16 v[28:31], v[122:125], v[90:93], v[28:31]
	ds_read_b128 v[90:93], v21 offset:20480
	v_mfma_f32_16x16x32_f16 v[32:35], v[122:125], v[110:113], v[32:35]
	ds_read_b128 v[110:113], v21 offset:22528
	s_waitcnt lgkmcnt(1)
	v_mfma_f32_16x16x32_f16 v[98:101], v[62:65], v[90:93], v[98:101]
	s_waitcnt vmcnt(4)
	ds_write_b128 v20, v[158:161]
	s_waitcnt lgkmcnt(1)
	v_mfma_f32_16x16x32_f16 v[52:55], v[62:65], v[110:113], v[52:55]
	ds_read_b128 v[62:65], v22 offset:49152
	v_mfma_f32_16x16x32_f16 v[102:105], v[74:77], v[90:93], v[102:105]
	s_waitcnt vmcnt(3)
; #define GL_LOAD(s_, kt_) if (VAR != 1) { a##s_##0 = GL_A(0, kt_); a##s_##1 = GL_A(1, kt_); a##s_##2 = GL_A(2, kt_); a##s_##3 = GL_A(3, kt_); b##s_##0 = GL_B(0, kt_); b##s_##1 = GL_B(1, kt_); b##s_##2 = GL_B(2, kt_); b##s_##3 = GL_B(3, kt_); }
; #define LDS_STORE(s_, buf_) if (VAR != 2) { LDS_ST1(sA, 0, buf_, a##s_##0) LDS_ST1(sA, 1, buf_, a##s_##1) LDS_ST1(sA, 2, buf_, a##s_##2) LDS_ST1(sA, 3, buf_, a##s_##3) LDS_ST1(sB, 0, buf_, b##s_##0) LDS_ST1(sB, 1, buf_, b##s_##1) LDS_ST1(sB, 2, buf_, b##s_##2) LDS_ST1(sB, 3, buf_, b##s_##3) }
;     ...
;   GL_LOAD(0, 0)
;   GL_LOAD(1, 1)
;   LDS_STORE(0, 0)
;   if (VAR != 4) __syncthreads();
; #pragma unroll
;   for (int kt = 0; kt < nk; kt += 2) {
;     if (kt + 2 < nk) { GL_LOAD(0, kt + 2) }
;     MMA_TILE(0)
;     LDS_STORE(1, 1)
;     if (VAR != 4) __syncthreads();
;     if (kt + 3 < nk) { GL_LOAD(1, kt + 3) }
;     MMA_TILE(1)
;     if (kt + 2 < nk) { LDS_STORE(0, 0) }
;     if (VAR != 4) __syncthreads();
	ds_write_b128 v17, v[94:97] offset:32768
	v_mfma_f32_16x16x32_f16 v[24:27], v[74:77], v[110:113], v[24:27]
	ds_read_b128 v[74:77], v22 offset:51200
	v_mfma_f32_16x16x32_f16 v[114:117], v[118:121], v[90:93], v[114:117]
	s_waitcnt vmcnt(2)
	ds_write_b128 v18, v[162:165] offset:32768
	v_mfma_f32_16x16x32_f16 v[40:43], v[118:121], v[110:113], v[40:43]
	ds_read_b128 v[118:121], v22 offset:53248
	v_mfma_f32_16x16x32_f16 v[70:73], v[122:125], v[90:93], v[70:73]
	ds_read_b128 v[90:93], v23 offset:16384
	v_mfma_f32_16x16x32_f16 v[48:51], v[122:125], v[110:113], v[48:51]
	ds_read_b128 v[110:113], v23 offset:18432
	s_waitcnt lgkmcnt(1)
	v_mfma_f32_16x16x32_f16 v[36:39], v[62:65], v[90:93], v[36:39]
	ds_read_b128 v[122:125], v22 offset:55296
	s_waitcnt lgkmcnt(1)
	v_mfma_f32_16x16x32_f16 v[66:69], v[62:65], v[110:113], v[66:69]
	s_waitcnt vmcnt(1)
	ds_write_b128 v19, v[166:169] offset:32768
	v_mfma_f32_16x16x32_f16 v[44:47], v[74:77], v[90:93], v[44:47]
	s_waitcnt vmcnt(0)
	ds_write_b128 v20, v[190:193] offset:32768
	v_mfma_f32_16x16x32_f16 v[78:81], v[74:77], v[110:113], v[78:81]
	v_mfma_f32_16x16x32_f16 v[82:85], v[118:121], v[90:93], v[82:85]
	v_mfma_f32_16x16x32_f16 v[86:89], v[118:121], v[110:113], v[86:89]
	s_waitcnt lgkmcnt(2)
	v_mfma_f32_16x16x32_f16 v[28:31], v[122:125], v[90:93], v[28:31]
	ds_read_b128 v[90:93], v23 offset:20480
	v_mfma_f32_16x16x32_f16 v[32:35], v[122:125], v[110:113], v[32:35]
	ds_read_b128 v[110:113], v23 offset:22528
	s_waitcnt lgkmcnt(1)
	v_mfma_f32_16x16x32_f16 v[98:101], v[62:65], v[90:93], v[98:101]
	s_waitcnt lgkmcnt(0)
	v_mfma_f32_16x16x32_f16 v[52:55], v[62:65], v[110:113], v[52:55]
	global_load_dwordx4 v[62:65], v[0:1], off offset:2176
	v_mfma_f32_16x16x32_f16 v[102:105], v[74:77], v[90:93], v[102:105]
	v_mfma_f32_16x16x32_f16 v[24:27], v[74:77], v[110:113], v[24:27]
	v_mfma_f32_16x16x32_f16 v[114:117], v[118:121], v[90:93], v[114:117]
	v_mfma_f32_16x16x32_f16 v[40:43], v[118:121], v[110:113], v[40:43]
	v_mfma_f32_16x16x32_f16 v[70:73], v[122:125], v[90:93], v[70:73]
	global_load_dwordx4 v[90:93], v[2:3], off offset:2176
	global_load_dwordx4 v[126:129], v[4:5], off offset:2176
	global_load_dwordx4 v[130:133], v[14:15], off offset:2176
	global_load_dwordx4 v[74:77], v[10:11], off offset:2176
	global_load_dwordx4 v[138:141], v[12:13], off offset:2176
	global_load_dwordx4 v[142:145], v[8:9], off offset:2176
	global_load_dwordx4 v[154:157], v[6:7], off offset:2176
	s_waitcnt lgkmcnt(0)
	s_barrier
	v_mfma_f32_16x16x32_f16 v[48:51], v[122:125], v[110:113], v[48:51]
	ds_read_b128 v[58:61], v16 offset:32768
	ds_read_b128 v[106:109], v21
	s_waitcnt lgkmcnt(0)
	v_mfma_f32_16x16x32_f16 v[36:39], v[58:61], v[106:109], v[36:39]
	ds_read_b128 v[94:97], v16 offset:34816
	ds_read_b128 v[110:113], v21 offset:2048
	s_waitcnt lgkmcnt(0)
	v_mfma_f32_16x16x32_f16 v[66:69], v[58:61], v[110:113], v[66:69]
	ds_read_b128 v[118:121], v16 offset:36864
	v_mfma_f32_16x16x32_f16 v[44:47], v[94:97], v[106:109], v[44:47]
	ds_read_b128 v[122:125], v16 offset:38912
	v_mfma_f32_16x16x32_f16 v[78:81], v[94:97], v[110:113], v[78:81]
	s_waitcnt vmcnt(7)
	ds_write_b128 v17, v[62:65] offset:16384
	s_waitcnt lgkmcnt(2)
	v_mfma_f32_16x16x32_f16 v[82:85], v[118:121], v[106:109], v[82:85]
	s_waitcnt vmcnt(6)
	ds_write_b128 v18, v[90:93] offset:16384
	v_mfma_f32_16x16x32_f16 v[86:89], v[118:121], v[110:113], v[86:89]
	s_waitcnt vmcnt(5)
	ds_write_b128 v19, v[126:129] offset:16384
	s_waitcnt lgkmcnt(3)
	v_mfma_f32_16x16x32_f16 v[28:31], v[122:125], v[106:109], v[28:31]
	ds_read_b128 v[106:109], v21 offset:4096
	v_mfma_f32_16x16x32_f16 v[32:35], v[122:125], v[110:113], v[32:35]
	ds_read_b128 v[110:113], v21 offset:6144
	s_waitcnt lgkmcnt(1)
	v_mfma_f32_16x16x32_f16 v[98:101], v[58:61], v[106:109], v[98:101]
	s_waitcnt vmcnt(4)
	ds_write_b128 v20, v[130:133] offset:16384
	s_waitcnt lgkmcnt(1)
	v_mfma_f32_16x16x32_f16 v[52:55], v[58:61], v[110:113], v[52:55]
	ds_read_b128 v[58:61], v22 offset:32768
	v_mfma_f32_16x16x32_f16 v[102:105], v[94:97], v[106:109], v[102:105]
	s_waitcnt vmcnt(3)
	ds_write_b128 v17, v[74:77] offset:49152
	v_mfma_f32_16x16x32_f16 v[24:27], v[94:97], v[110:113], v[24:27]
	ds_read_b128 v[94:97], v22 offset:34816
	v_mfma_f32_16x16x32_f16 v[114:117], v[118:121], v[106:109], v[114:117]
	s_waitcnt vmcnt(2)
	ds_write_b128 v18, v[138:141] offset:49152
	v_mfma_f32_16x16x32_f16 v[40:43], v[118:121], v[110:113], v[40:43]
	ds_read_b128 v[118:121], v22 offset:36864
	v_mfma_f32_16x16x32_f16 v[70:73], v[122:125], v[106:109], v[70:73]
	ds_read_b128 v[106:109], v23
	v_mfma_f32_16x16x32_f16 v[48:51], v[122:125], v[110:113], v[48:51]
	ds_read_b128 v[110:113], v23 offset:2048
	s_waitcnt lgkmcnt(1)
	v_mfma_f32_16x16x32_f16 v[36:39], v[58:61], v[106:109], v[36:39]
	ds_read_b128 v[122:125], v22 offset:38912
	s_waitcnt lgkmcnt(1)
	v_mfma_f32_16x16x32_f16 v[66:69], v[58:61], v[110:113], v[66:69]
	s_waitcnt vmcnt(1)
	ds_write_b128 v19, v[142:145] offset:49152
	v_mfma_f32_16x16x32_f16 v[44:47], v[94:97], v[106:109], v[44:47]
	s_waitcnt vmcnt(0)
	ds_write_b128 v20, v[154:157] offset:49152
	v_mfma_f32_16x16x32_f16 v[78:81], v[94:97], v[110:113], v[78:81]
	v_mfma_f32_16x16x32_f16 v[82:85], v[118:121], v[106:109], v[82:85]
	v_mfma_f32_16x16x32_f16 v[86:89], v[118:121], v[110:113], v[86:89]
	s_waitcnt lgkmcnt(2)
	v_mfma_f32_16x16x32_f16 v[28:31], v[122:125], v[106:109], v[28:31]
	ds_read_b128 v[106:109], v23 offset:4096
	v_mfma_f32_16x16x32_f16 v[32:35], v[122:125], v[110:113], v[32:35]
	ds_read_b128 v[110:113], v23 offset:6144
	s_waitcnt lgkmcnt(1)
	v_mfma_f32_16x16x32_f16 v[98:101], v[58:61], v[106:109], v[98:101]
	s_waitcnt lgkmcnt(0)
	v_mfma_f32_16x16x32_f16 v[52:55], v[58:61], v[110:113], v[52:55]
	global_load_dwordx4 v[58:61], v[0:1], off offset:2304
	v_mfma_f32_16x16x32_f16 v[102:105], v[94:97], v[106:109], v[102:105]
	v_mfma_f32_16x16x32_f16 v[24:27], v[94:97], v[110:113], v[24:27]
	v_mfma_f32_16x16x32_f16 v[114:117], v[118:121], v[106:109], v[114:117]
	v_mfma_f32_16x16x32_f16 v[40:43], v[118:121], v[110:113], v[40:43]
	v_mfma_f32_16x16x32_f16 v[70:73], v[122:125], v[106:109], v[70:73]
	global_load_dwordx4 v[106:109], v[2:3], off offset:2304
	global_load_dwordx4 v[134:137], v[4:5], off offset:2304
	global_load_dwordx4 v[158:161], v[14:15], off offset:2304
	global_load_dwordx4 v[94:97], v[10:11], off offset:2304
	global_load_dwordx4 v[162:165], v[12:13], off offset:2304
	global_load_dwordx4 v[166:169], v[8:9], off offset:2304
	global_load_dwordx4 v[190:193], v[6:7], off offset:2304
	s_waitcnt lgkmcnt(0)
	s_barrier
; #define GL_LOAD(s_, kt_) if (VAR != 1) { a##s_##0 = GL_A(0, kt_); a##s_##1 = GL_A(1, kt_); a##s_##2 = GL_A(2, kt_); a##s_##3 = GL_A(3, kt_); b##s_##0 = GL_B(0, kt_); b##s_##1 = GL_B(1, kt_); b##s_##2 = GL_B(2, kt_); b##s_##3 = GL_B(3, kt_); }
; #define LDS_STORE(s_, buf_) if (VAR != 2) { LDS_ST1(sA, 0, buf_, a##s_##0) LDS_ST1(sA, 1, buf_, a##s_##1) LDS_ST1(sA, 2, buf_, a##s_##2) LDS_ST1(sA, 3, buf_, a##s_##3) LDS_ST1(sB, 0, buf_, b##s_##0) LDS_ST1(sB, 1, buf_, b##s_##1) LDS_ST1(sB, 2, buf_, b##s_##2) LDS_ST1(sB, 3, buf_, b##s_##3) }
;     ...
;   GL_LOAD(0, 0)
;   GL_LOAD(1, 1)
;   LDS_STORE(0, 0)
;   if (VAR != 4) __syncthreads();
; #pragma unroll
;   for (int kt = 0; kt < nk; kt += 2) {
;     if (kt + 2 < nk) { GL_LOAD(0, kt + 2) }
;     MMA_TILE(0)
;     LDS_STORE(1, 1)
;     if (VAR != 4) __syncthreads();
;     if (kt + 3 < nk) { GL_LOAD(1, kt + 3) }
;     MMA_TILE(1)
;     if (kt + 2 < nk) { LDS_STORE(0, 0) }
;     if (VAR != 4) __syncthreads();
	v_mfma_f32_16x16x32_f16 v[48:51], v[122:125], v[110:113], v[48:51]
	ds_read_b128 v[62:65], v16 offset:49152
	ds_read_b128 v[90:93], v21 offset:16384
	s_waitcnt lgkmcnt(0)
	v_mfma_f32_16x16x32_f16 v[36:39], v[62:65], v[90:93], v[36:39]
	ds_read_b128 v[74:77], v16 offset:51200
	ds_read_b128 v[110:113], v21 offset:18432
	s_waitcnt lgkmcnt(0)
	v_mfma_f32_16x16x32_f16 v[66:69], v[62:65], v[110:113], v[66:69]
	ds_read_b128 v[118:121], v16 offset:53248
	v_mfma_f32_16x16x32_f16 v[44:47], v[74:77], v[90:93], v[44:47]
	ds_read_b128 v[122:125], v16 offset:55296
	v_mfma_f32_16x16x32_f16 v[78:81], v[74:77], v[110:113], v[78:81]
	s_waitcnt vmcnt(7)
	ds_write_b128 v17, v[58:61]
	s_waitcnt lgkmcnt(2)
	v_mfma_f32_16x16x32_f16 v[82:85], v[118:121], v[90:93], v[82:85]
	s_waitcnt vmcnt(6)
	ds_write_b128 v18, v[106:109]
	v_mfma_f32_16x16x32_f16 v[86:89], v[118:121], v[110:113], v[86:89]
	s_waitcnt vmcnt(5)
	ds_write_b128 v19, v[134:137]
	s_waitcnt lgkmcnt(3)
	v_mfma_f32_16x16x32_f16 v[28:31], v[122:125], v[90:93], v[28:31]
	ds_read_b128 v[90:93], v21 offset:20480
	v_mfma_f32_16x16x32_f16 v[32:35], v[122:125], v[110:113], v[32:35]
	ds_read_b128 v[110:113], v21 offset:22528
	s_waitcnt lgkmcnt(1)
	v_mfma_f32_16x16x32_f16 v[98:101], v[62:65], v[90:93], v[98:101]
	s_waitcnt vmcnt(4)
	ds_write_b128 v20, v[158:161]
	s_waitcnt lgkmcnt(1)
	v_mfma_f32_16x16x32_f16 v[52:55], v[62:65], v[110:113], v[52:55]
	ds_read_b128 v[62:65], v22 offset:49152
	v_mfma_f32_16x16x32_f16 v[102:105], v[74:77], v[90:93], v[102:105]
	s_waitcnt vmcnt(3)
	ds_write_b128 v17, v[94:97] offset:32768
	v_mfma_f32_16x16x32_f16 v[24:27], v[74:77], v[110:113], v[24:27]
	ds_read_b128 v[74:77], v22 offset:51200
	v_mfma_f32_16x16x32_f16 v[114:117], v[118:121], v[90:93], v[114:117]
	s_waitcnt vmcnt(2)
	ds_write_b128 v18, v[162:165] offset:32768
	v_mfma_f32_16x16x32_f16 v[40:43], v[118:121], v[110:113], v[40:43]
	ds_read_b128 v[118:121], v22 offset:53248
	v_mfma_f32_16x16x32_f16 v[70:73], v[122:125], v[90:93], v[70:73]
	ds_read_b128 v[90:93], v23 offset:16384
	v_mfma_f32_16x16x32_f16 v[48:51], v[122:125], v[110:113], v[48:51]
	ds_read_b128 v[110:113], v23 offset:18432
	s_waitcnt lgkmcnt(1)
	v_mfma_f32_16x16x32_f16 v[36:39], v[62:65], v[90:93], v[36:39]
	ds_read_b128 v[122:125], v22 offset:55296
	s_waitcnt lgkmcnt(1)
	v_mfma_f32_16x16x32_f16 v[66:69], v[62:65], v[110:113], v[66:69]
	s_waitcnt vmcnt(1)
	ds_write_b128 v19, v[166:169] offset:32768
	v_mfma_f32_16x16x32_f16 v[44:47], v[74:77], v[90:93], v[44:47]
	s_waitcnt vmcnt(0)
	ds_write_b128 v20, v[190:193] offset:32768
	v_mfma_f32_16x16x32_f16 v[78:81], v[74:77], v[110:113], v[78:81]
	v_mfma_f32_16x16x32_f16 v[82:85], v[118:121], v[90:93], v[82:85]
	v_mfma_f32_16x16x32_f16 v[86:89], v[118:121], v[110:113], v[86:89]
	s_waitcnt lgkmcnt(2)
	v_mfma_f32_16x16x32_f16 v[28:31], v[122:125], v[90:93], v[28:31]
	ds_read_b128 v[90:93], v23 offset:20480
	v_mfma_f32_16x16x32_f16 v[32:35], v[122:125], v[110:113], v[32:35]
	ds_read_b128 v[110:113], v23 offset:22528
	s_waitcnt lgkmcnt(1)
	v_mfma_f32_16x16x32_f16 v[98:101], v[62:65], v[90:93], v[98:101]
	s_waitcnt lgkmcnt(0)
	v_mfma_f32_16x16x32_f16 v[52:55], v[62:65], v[110:113], v[52:55]
	global_load_dwordx4 v[62:65], v[0:1], off offset:2432
	v_mfma_f32_16x16x32_f16 v[102:105], v[74:77], v[90:93], v[102:105]
	v_mfma_f32_16x16x32_f16 v[24:27], v[74:77], v[110:113], v[24:27]
	v_mfma_f32_16x16x32_f16 v[114:117], v[118:121], v[90:93], v[114:117]
	v_mfma_f32_16x16x32_f16 v[40:43], v[118:121], v[110:113], v[40:43]
	v_mfma_f32_16x16x32_f16 v[70:73], v[122:125], v[90:93], v[70:73]
	global_load_dwordx4 v[90:93], v[2:3], off offset:2432
	global_load_dwordx4 v[126:129], v[4:5], off offset:2432
	global_load_dwordx4 v[130:133], v[14:15], off offset:2432
	global_load_dwordx4 v[74:77], v[10:11], off offset:2432
	global_load_dwordx4 v[138:141], v[12:13], off offset:2432
	global_load_dwordx4 v[142:145], v[8:9], off offset:2432
	global_load_dwordx4 v[154:157], v[6:7], off offset:2432
	s_waitcnt lgkmcnt(0)
	s_barrier
	v_mfma_f32_16x16x32_f16 v[48:51], v[122:125], v[110:113], v[48:51]
	ds_read_b128 v[58:61], v16 offset:32768
	ds_read_b128 v[106:109], v21
	s_waitcnt lgkmcnt(0)
	v_mfma_f32_16x16x32_f16 v[36:39], v[58:61], v[106:109], v[36:39]
	ds_read_b128 v[94:97], v16 offset:34816
	ds_read_b128 v[110:113], v21 offset:2048
	s_waitcnt lgkmcnt(0)
	v_mfma_f32_16x16x32_f16 v[66:69], v[58:61], v[110:113], v[66:69]
	ds_read_b128 v[118:121], v16 offset:36864
	v_mfma_f32_16x16x32_f16 v[44:47], v[94:97], v[106:109], v[44:47]
	ds_read_b128 v[122:125], v16 offset:38912
	v_mfma_f32_16x16x32_f16 v[78:81], v[94:97], v[110:113], v[78:81]
	s_waitcnt vmcnt(7)
	ds_write_b128 v17, v[62:65] offset:16384
	s_waitcnt lgkmcnt(2)
	v_mfma_f32_16x16x32_f16 v[82:85], v[118:121], v[106:109], v[82:85]
	s_waitcnt vmcnt(6)
	ds_write_b128 v18, v[90:93] offset:16384
	v_mfma_f32_16x16x32_f16 v[86:89], v[118:121], v[110:113], v[86:89]
	s_waitcnt vmcnt(5)
	ds_write_b128 v19, v[126:129] offset:16384
	s_waitcnt lgkmcnt(3)
	v_mfma_f32_16x16x32_f16 v[28:31], v[122:125], v[106:109], v[28:31]
	ds_read_b128 v[106:109], v21 offset:4096
	v_mfma_f32_16x16x32_f16 v[32:35], v[122:125], v[110:113], v[32:35]
	ds_read_b128 v[110:113], v21 offset:6144
	s_waitcnt lgkmcnt(1)
	v_mfma_f32_16x16x32_f16 v[98:101], v[58:61], v[106:109], v[98:101]
	s_waitcnt vmcnt(4)
	ds_write_b128 v20, v[130:133] offset:16384
	s_waitcnt lgkmcnt(1)
	v_mfma_f32_16x16x32_f16 v[52:55], v[58:61], v[110:113], v[52:55]
	ds_read_b128 v[58:61], v22 offset:32768
	v_mfma_f32_16x16x32_f16 v[102:105], v[94:97], v[106:109], v[102:105]
	s_waitcnt vmcnt(3)
; #define GL_LOAD(s_, kt_) if (VAR != 1) { a##s_##0 = GL_A(0, kt_); a##s_##1 = GL_A(1, kt_); a##s_##2 = GL_A(2, kt_); a##s_##3 = GL_A(3, kt_); b##s_##0 = GL_B(0, kt_); b##s_##1 = GL_B(1, kt_); b##s_##2 = GL_B(2, kt_); b##s_##3 = GL_B(3, kt_); }
; #define LDS_STORE(s_, buf_) if (VAR != 2) { LDS_ST1(sA, 0, buf_, a##s_##0) LDS_ST1(sA, 1, buf_, a##s_##1) LDS_ST1(sA, 2, buf_, a##s_##2) LDS_ST1(sA, 3, buf_, a##s_##3) LDS_ST1(sB, 0, buf_, b##s_##0) LDS_ST1(sB, 1, buf_, b##s_##1) LDS_ST1(sB, 2, buf_, b##s_##2) LDS_ST1(sB, 3, buf_, b##s_##3) }
;     ...
;   GL_LOAD(0, 0)
;   GL_LOAD(1, 1)
;   LDS_STORE(0, 0)
;   if (VAR != 4) __syncthreads();
; #pragma unroll
;   for (int kt = 0; kt < nk; kt += 2) {
;     if (kt + 2 < nk) { GL_LOAD(0, kt + 2) }
;     MMA_TILE(0)
;     LDS_STORE(1, 1)
;     if (VAR != 4) __syncthreads();
;     if (kt + 3 < nk) { GL_LOAD(1, kt + 3) }
;     MMA_TILE(1)
;     if (kt + 2 < nk) { LDS_STORE(0, 0) }
;     if (VAR != 4) __syncthreads();
	ds_write_b128 v17, v[74:77] offset:49152
	v_mfma_f32_16x16x32_f16 v[24:27], v[94:97], v[110:113], v[24:27]
	ds_read_b128 v[94:97], v22 offset:34816
	v_mfma_f32_16x16x32_f16 v[114:117], v[118:121], v[106:109], v[114:117]
	s_waitcnt vmcnt(2)
	ds_write_b128 v18, v[138:141] offset:49152
	v_mfma_f32_16x16x32_f16 v[40:43], v[118:121], v[110:113], v[40:43]
	ds_read_b128 v[118:121], v22 offset:36864
	v_mfma_f32_16x16x32_f16 v[70:73], v[122:125], v[106:109], v[70:73]
	ds_read_b128 v[106:109], v23
	v_mfma_f32_16x16x32_f16 v[48:51], v[122:125], v[110:113], v[48:51]
	ds_read_b128 v[110:113], v23 offset:2048
	s_waitcnt lgkmcnt(1)
	v_mfma_f32_16x16x32_f16 v[36:39], v[58:61], v[106:109], v[36:39]
	ds_read_b128 v[122:125], v22 offset:38912
	s_waitcnt lgkmcnt(1)
	v_mfma_f32_16x16x32_f16 v[66:69], v[58:61], v[110:113], v[66:69]
	s_waitcnt vmcnt(1)
	ds_write_b128 v19, v[142:145] offset:49152
	v_mfma_f32_16x16x32_f16 v[44:47], v[94:97], v[106:109], v[44:47]
	s_waitcnt vmcnt(0)
	ds_write_b128 v20, v[154:157] offset:49152
	v_mfma_f32_16x16x32_f16 v[78:81], v[94:97], v[110:113], v[78:81]
	v_mfma_f32_16x16x32_f16 v[82:85], v[118:121], v[106:109], v[82:85]
	v_mfma_f32_16x16x32_f16 v[86:89], v[118:121], v[110:113], v[86:89]
	s_waitcnt lgkmcnt(2)
	v_mfma_f32_16x16x32_f16 v[28:31], v[122:125], v[106:109], v[28:31]
	ds_read_b128 v[106:109], v23 offset:4096
	v_mfma_f32_16x16x32_f16 v[32:35], v[122:125], v[110:113], v[32:35]
	ds_read_b128 v[110:113], v23 offset:6144
	s_waitcnt lgkmcnt(1)
	v_mfma_f32_16x16x32_f16 v[98:101], v[58:61], v[106:109], v[98:101]
	s_waitcnt lgkmcnt(0)
	v_mfma_f32_16x16x32_f16 v[52:55], v[58:61], v[110:113], v[52:55]
	global_load_dwordx4 v[58:61], v[0:1], off offset:2560
	v_mfma_f32_16x16x32_f16 v[102:105], v[94:97], v[106:109], v[102:105]
	v_mfma_f32_16x16x32_f16 v[24:27], v[94:97], v[110:113], v[24:27]
	v_mfma_f32_16x16x32_f16 v[114:117], v[118:121], v[106:109], v[114:117]
	v_mfma_f32_16x16x32_f16 v[40:43], v[118:121], v[110:113], v[40:43]
	v_mfma_f32_16x16x32_f16 v[70:73], v[122:125], v[106:109], v[70:73]
	global_load_dwordx4 v[106:109], v[2:3], off offset:2560
	global_load_dwordx4 v[134:137], v[4:5], off offset:2560
	global_load_dwordx4 v[158:161], v[14:15], off offset:2560
	global_load_dwordx4 v[94:97], v[10:11], off offset:2560
	global_load_dwordx4 v[162:165], v[12:13], off offset:2560
	global_load_dwordx4 v[166:169], v[8:9], off offset:2560
	global_load_dwordx4 v[190:193], v[6:7], off offset:2560
	s_waitcnt lgkmcnt(0)
	s_barrier
	v_mfma_f32_16x16x32_f16 v[48:51], v[122:125], v[110:113], v[48:51]
	ds_read_b128 v[62:65], v16 offset:49152
	ds_read_b128 v[90:93], v21 offset:16384
	s_waitcnt lgkmcnt(0)
	v_mfma_f32_16x16x32_f16 v[36:39], v[62:65], v[90:93], v[36:39]
	ds_read_b128 v[74:77], v16 offset:51200
	ds_read_b128 v[110:113], v21 offset:18432
	s_waitcnt lgkmcnt(0)
	v_mfma_f32_16x16x32_f16 v[66:69], v[62:65], v[110:113], v[66:69]
	ds_read_b128 v[118:121], v16 offset:53248
	v_mfma_f32_16x16x32_f16 v[44:47], v[74:77], v[90:93], v[44:47]
	ds_read_b128 v[122:125], v16 offset:55296
	v_mfma_f32_16x16x32_f16 v[78:81], v[74:77], v[110:113], v[78:81]
	s_waitcnt vmcnt(7)
	ds_write_b128 v17, v[58:61]
	s_waitcnt lgkmcnt(2)
	v_mfma_f32_16x16x32_f16 v[82:85], v[118:121], v[90:93], v[82:85]
	s_waitcnt vmcnt(6)
	ds_write_b128 v18, v[106:109]
	v_mfma_f32_16x16x32_f16 v[86:89], v[118:121], v[110:113], v[86:89]
	s_waitcnt vmcnt(5)
	ds_write_b128 v19, v[134:137]
	s_waitcnt lgkmcnt(3)
	v_mfma_f32_16x16x32_f16 v[28:31], v[122:125], v[90:93], v[28:31]
	ds_read_b128 v[90:93], v21 offset:20480
	v_mfma_f32_16x16x32_f16 v[32:35], v[122:125], v[110:113], v[32:35]
	ds_read_b128 v[110:113], v21 offset:22528
	s_waitcnt lgkmcnt(1)
	v_mfma_f32_16x16x32_f16 v[98:101], v[62:65], v[90:93], v[98:101]
	s_waitcnt vmcnt(4)
	ds_write_b128 v20, v[158:161]
	s_waitcnt lgkmcnt(1)
	v_mfma_f32_16x16x32_f16 v[52:55], v[62:65], v[110:113], v[52:55]
	ds_read_b128 v[62:65], v22 offset:49152
	v_mfma_f32_16x16x32_f16 v[102:105], v[74:77], v[90:93], v[102:105]
	s_waitcnt vmcnt(3)
	ds_write_b128 v17, v[94:97] offset:32768
	v_mfma_f32_16x16x32_f16 v[24:27], v[74:77], v[110:113], v[24:27]
	ds_read_b128 v[74:77], v22 offset:51200
	v_mfma_f32_16x16x32_f16 v[114:117], v[118:121], v[90:93], v[114:117]
	s_waitcnt vmcnt(2)
	ds_write_b128 v18, v[162:165] offset:32768
	v_mfma_f32_16x16x32_f16 v[40:43], v[118:121], v[110:113], v[40:43]
	ds_read_b128 v[118:121], v22 offset:53248
	v_mfma_f32_16x16x32_f16 v[70:73], v[122:125], v[90:93], v[70:73]
	ds_read_b128 v[90:93], v23 offset:16384
	v_mfma_f32_16x16x32_f16 v[48:51], v[122:125], v[110:113], v[48:51]
	ds_read_b128 v[110:113], v23 offset:18432
	s_waitcnt lgkmcnt(1)
	v_mfma_f32_16x16x32_f16 v[36:39], v[62:65], v[90:93], v[36:39]
	ds_read_b128 v[122:125], v22 offset:55296
	s_waitcnt lgkmcnt(1)
	v_mfma_f32_16x16x32_f16 v[66:69], v[62:65], v[110:113], v[66:69]
	s_waitcnt vmcnt(1)
	ds_write_b128 v19, v[166:169] offset:32768
	v_mfma_f32_16x16x32_f16 v[44:47], v[74:77], v[90:93], v[44:47]
	s_waitcnt vmcnt(0)
	ds_write_b128 v20, v[190:193] offset:32768
	v_mfma_f32_16x16x32_f16 v[78:81], v[74:77], v[110:113], v[78:81]
	v_mfma_f32_16x16x32_f16 v[82:85], v[118:121], v[90:93], v[82:85]
	v_mfma_f32_16x16x32_f16 v[86:89], v[118:121], v[110:113], v[86:89]
	s_waitcnt lgkmcnt(2)
	v_mfma_f32_16x16x32_f16 v[28:31], v[122:125], v[90:93], v[28:31]
	ds_read_b128 v[90:93], v23 offset:20480
	v_mfma_f32_16x16x32_f16 v[32:35], v[122:125], v[110:113], v[32:35]
	ds_read_b128 v[110:113], v23 offset:22528
	s_waitcnt lgkmcnt(1)
	v_mfma_f32_16x16x32_f16 v[98:101], v[62:65], v[90:93], v[98:101]
	s_waitcnt lgkmcnt(0)
	v_mfma_f32_16x16x32_f16 v[52:55], v[62:65], v[110:113], v[52:55]
	global_load_dwordx4 v[62:65], v[0:1], off offset:2688
	v_mfma_f32_16x16x32_f16 v[102:105], v[74:77], v[90:93], v[102:105]
	v_mfma_f32_16x16x32_f16 v[24:27], v[74:77], v[110:113], v[24:27]
	v_mfma_f32_16x16x32_f16 v[114:117], v[118:121], v[90:93], v[114:117]
	v_mfma_f32_16x16x32_f16 v[40:43], v[118:121], v[110:113], v[40:43]
	v_mfma_f32_16x16x32_f16 v[70:73], v[122:125], v[90:93], v[70:73]
	global_load_dwordx4 v[90:93], v[2:3], off offset:2688
	global_load_dwordx4 v[126:129], v[4:5], off offset:2688
	global_load_dwordx4 v[130:133], v[14:15], off offset:2688
	global_load_dwordx4 v[74:77], v[10:11], off offset:2688
	global_load_dwordx4 v[138:141], v[12:13], off offset:2688
	global_load_dwordx4 v[142:145], v[8:9], off offset:2688
	global_load_dwordx4 v[154:157], v[6:7], off offset:2688
	s_waitcnt lgkmcnt(0)
	s_barrier
; #define GL_LOAD(s_, kt_) if (VAR != 1) { a##s_##0 = GL_A(0, kt_); a##s_##1 = GL_A(1, kt_); a##s_##2 = GL_A(2, kt_); a##s_##3 = GL_A(3, kt_); b##s_##0 = GL_B(0, kt_); b##s_##1 = GL_B(1, kt_); b##s_##2 = GL_B(2, kt_); b##s_##3 = GL_B(3, kt_); }
; #define LDS_STORE(s_, buf_) if (VAR != 2) { LDS_ST1(sA, 0, buf_, a##s_##0) LDS_ST1(sA, 1, buf_, a##s_##1) LDS_ST1(sA, 2, buf_, a##s_##2) LDS_ST1(sA, 3, buf_, a##s_##3) LDS_ST1(sB, 0, buf_, b##s_##0) LDS_ST1(sB, 1, buf_, b##s_##1) LDS_ST1(sB, 2, buf_, b##s_##2) LDS_ST1(sB, 3, buf_, b##s_##3) }
;     ...
;   GL_LOAD(0, 0)
;   GL_LOAD(1, 1)
;   LDS_STORE(0, 0)
;   if (VAR != 4) __syncthreads();
; #pragma unroll
;   for (int kt = 0; kt < nk; kt += 2) {
;     if (kt + 2 < nk) { GL_LOAD(0, kt + 2) }
;     MMA_TILE(0)
;     LDS_STORE(1, 1)
;     if (VAR != 4) __syncthreads();
;     if (kt + 3 < nk) { GL_LOAD(1, kt + 3) }
;     MMA_TILE(1)
;     if (kt + 2 < nk) { LDS_STORE(0, 0) }
;     if (VAR != 4) __syncthreads();
	v_mfma_f32_16x16x32_f16 v[48:51], v[122:125], v[110:113], v[48:51]
	ds_read_b128 v[58:61], v16 offset:32768
	ds_read_b128 v[106:109], v21
	s_waitcnt lgkmcnt(0)
	v_mfma_f32_16x16x32_f16 v[36:39], v[58:61], v[106:109], v[36:39]
	ds_read_b128 v[94:97], v16 offset:34816
	ds_read_b128 v[110:113], v21 offset:2048
	s_waitcnt lgkmcnt(0)
	v_mfma_f32_16x16x32_f16 v[66:69], v[58:61], v[110:113], v[66:69]
	ds_read_b128 v[118:121], v16 offset:36864
	v_mfma_f32_16x16x32_f16 v[44:47], v[94:97], v[106:109], v[44:47]
	ds_read_b128 v[122:125], v16 offset:38912
	v_mfma_f32_16x16x32_f16 v[78:81], v[94:97], v[110:113], v[78:81]
	s_waitcnt vmcnt(7)
	ds_write_b128 v17, v[62:65] offset:16384
	s_waitcnt lgkmcnt(2)
	v_mfma_f32_16x16x32_f16 v[82:85], v[118:121], v[106:109], v[82:85]
	s_waitcnt vmcnt(6)
	ds_write_b128 v18, v[90:93] offset:16384
	v_mfma_f32_16x16x32_f16 v[86:89], v[118:121], v[110:113], v[86:89]
	s_waitcnt vmcnt(5)
	ds_write_b128 v19, v[126:129] offset:16384
	s_waitcnt lgkmcnt(3)
	v_mfma_f32_16x16x32_f16 v[28:31], v[122:125], v[106:109], v[28:31]
	ds_read_b128 v[106:109], v21 offset:4096
	v_mfma_f32_16x16x32_f16 v[32:35], v[122:125], v[110:113], v[32:35]
	ds_read_b128 v[110:113], v21 offset:6144
	s_waitcnt lgkmcnt(1)
	v_mfma_f32_16x16x32_f16 v[98:101], v[58:61], v[106:109], v[98:101]
	s_waitcnt vmcnt(4)
	ds_write_b128 v20, v[130:133] offset:16384
	s_waitcnt lgkmcnt(1)
	v_mfma_f32_16x16x32_f16 v[52:55], v[58:61], v[110:113], v[52:55]
	ds_read_b128 v[58:61], v22 offset:32768
	v_mfma_f32_16x16x32_f16 v[102:105], v[94:97], v[106:109], v[102:105]
	s_waitcnt vmcnt(3)
	ds_write_b128 v17, v[74:77] offset:49152
	v_mfma_f32_16x16x32_f16 v[24:27], v[94:97], v[110:113], v[24:27]
	ds_read_b128 v[94:97], v22 offset:34816
	v_mfma_f32_16x16x32_f16 v[114:117], v[118:121], v[106:109], v[114:117]
	s_waitcnt vmcnt(2)
	ds_write_b128 v18, v[138:141] offset:49152
	v_mfma_f32_16x16x32_f16 v[40:43], v[118:121], v[110:113], v[40:43]
	ds_read_b128 v[118:121], v22 offset:36864
	v_mfma_f32_16x16x32_f16 v[70:73], v[122:125], v[106:109], v[70:73]
	ds_read_b128 v[106:109], v23
	v_mfma_f32_16x16x32_f16 v[48:51], v[122:125], v[110:113], v[48:51]
	ds_read_b128 v[110:113], v23 offset:2048
	s_waitcnt lgkmcnt(1)
	v_mfma_f32_16x16x32_f16 v[36:39], v[58:61], v[106:109], v[36:39]
	ds_read_b128 v[122:125], v22 offset:38912
	s_waitcnt lgkmcnt(1)
	v_mfma_f32_16x16x32_f16 v[66:69], v[58:61], v[110:113], v[66:69]
	s_waitcnt vmcnt(1)
	ds_write_b128 v19, v[142:145] offset:49152
	v_mfma_f32_16x16x32_f16 v[44:47], v[94:97], v[106:109], v[44:47]
	s_waitcnt vmcnt(0)
	ds_write_b128 v20, v[154:157] offset:49152
	v_mfma_f32_16x16x32_f16 v[78:81], v[94:97], v[110:113], v[78:81]
	v_mfma_f32_16x16x32_f16 v[82:85], v[118:121], v[106:109], v[82:85]
	v_mfma_f32_16x16x32_f16 v[86:89], v[118:121], v[110:113], v[86:89]
	s_waitcnt lgkmcnt(2)
	v_mfma_f32_16x16x32_f16 v[28:31], v[122:125], v[106:109], v[28:31]
	ds_read_b128 v[106:109], v23 offset:4096
	v_mfma_f32_16x16x32_f16 v[32:35], v[122:125], v[110:113], v[32:35]
	ds_read_b128 v[110:113], v23 offset:6144
	s_waitcnt lgkmcnt(1)
	v_mfma_f32_16x16x32_f16 v[98:101], v[58:61], v[106:109], v[98:101]
	s_waitcnt lgkmcnt(0)
	v_mfma_f32_16x16x32_f16 v[52:55], v[58:61], v[110:113], v[52:55]
	global_load_dwordx4 v[58:61], v[0:1], off offset:2816
	v_mfma_f32_16x16x32_f16 v[102:105], v[94:97], v[106:109], v[102:105]
	v_mfma_f32_16x16x32_f16 v[24:27], v[94:97], v[110:113], v[24:27]
	v_mfma_f32_16x16x32_f16 v[114:117], v[118:121], v[106:109], v[114:117]
	v_mfma_f32_16x16x32_f16 v[40:43], v[118:121], v[110:113], v[40:43]
	v_mfma_f32_16x16x32_f16 v[70:73], v[122:125], v[106:109], v[70:73]
	global_load_dwordx4 v[106:109], v[2:3], off offset:2816
	global_load_dwordx4 v[134:137], v[4:5], off offset:2816
	global_load_dwordx4 v[158:161], v[14:15], off offset:2816
	global_load_dwordx4 v[94:97], v[10:11], off offset:2816
	global_load_dwordx4 v[162:165], v[12:13], off offset:2816
	global_load_dwordx4 v[166:169], v[8:9], off offset:2816
	global_load_dwordx4 v[190:193], v[6:7], off offset:2816
	s_waitcnt lgkmcnt(0)
	s_barrier
	v_mfma_f32_16x16x32_f16 v[48:51], v[122:125], v[110:113], v[48:51]
	ds_read_b128 v[62:65], v16 offset:49152
	ds_read_b128 v[90:93], v21 offset:16384
	s_waitcnt lgkmcnt(0)
	v_mfma_f32_16x16x32_f16 v[36:39], v[62:65], v[90:93], v[36:39]
	ds_read_b128 v[74:77], v16 offset:51200
	ds_read_b128 v[110:113], v21 offset:18432
	s_waitcnt lgkmcnt(0)
	v_mfma_f32_16x16x32_f16 v[66:69], v[62:65], v[110:113], v[66:69]
	ds_read_b128 v[118:121], v16 offset:53248
	v_mfma_f32_16x16x32_f16 v[44:47], v[74:77], v[90:93], v[44:47]
	ds_read_b128 v[122:125], v16 offset:55296
	v_mfma_f32_16x16x32_f16 v[78:81], v[74:77], v[110:113], v[78:81]
	s_waitcnt vmcnt(7)
	ds_write_b128 v17, v[58:61]
	s_waitcnt lgkmcnt(2)
	v_mfma_f32_16x16x32_f16 v[82:85], v[118:121], v[90:93], v[82:85]
	s_waitcnt vmcnt(6)
	ds_write_b128 v18, v[106:109]
	v_mfma_f32_16x16x32_f16 v[86:89], v[118:121], v[110:113], v[86:89]
	s_waitcnt vmcnt(5)
	ds_write_b128 v19, v[134:137]
	s_waitcnt lgkmcnt(3)
	v_mfma_f32_16x16x32_f16 v[28:31], v[122:125], v[90:93], v[28:31]
	ds_read_b128 v[90:93], v21 offset:20480
	v_mfma_f32_16x16x32_f16 v[32:35], v[122:125], v[110:113], v[32:35]
	ds_read_b128 v[110:113], v21 offset:22528
	s_waitcnt lgkmcnt(1)
	v_mfma_f32_16x16x32_f16 v[98:101], v[62:65], v[90:93], v[98:101]
	s_waitcnt vmcnt(4)
	ds_write_b128 v20, v[158:161]
	s_waitcnt lgkmcnt(1)
	v_mfma_f32_16x16x32_f16 v[52:55], v[62:65], v[110:113], v[52:55]
	ds_read_b128 v[62:65], v22 offset:49152
	v_mfma_f32_16x16x32_f16 v[102:105], v[74:77], v[90:93], v[102:105]
	s_waitcnt vmcnt(3)
; #define GL_LOAD(s_, kt_) if (VAR != 1) { a##s_##0 = GL_A(0, kt_); a##s_##1 = GL_A(1, kt_); a##s_##2 = GL_A(2, kt_); a##s_##3 = GL_A(3, kt_); b##s_##0 = GL_B(0, kt_); b##s_##1 = GL_B(1, kt_); b##s_##2 = GL_B(2, kt_); b##s_##3 = GL_B(3, kt_); }
; #define LDS_STORE(s_, buf_) if (VAR != 2) { LDS_ST1(sA, 0, buf_, a##s_##0) LDS_ST1(sA, 1, buf_, a##s_##1) LDS_ST1(sA, 2, buf_, a##s_##2) LDS_ST1(sA, 3, buf_, a##s_##3) LDS_ST1(sB, 0, buf_, b##s_##0) LDS_ST1(sB, 1, buf_, b##s_##1) LDS_ST1(sB, 2, buf_, b##s_##2) LDS_ST1(sB, 3, buf_, b##s_##3) }
;     ...
;   GL_LOAD(0, 0)
;   GL_LOAD(1, 1)
;   LDS_STORE(0, 0)
;   if (VAR != 4) __syncthreads();
; #pragma unroll
;   for (int kt = 0; kt < nk; kt += 2) {
;     if (kt + 2 < nk) { GL_LOAD(0, kt + 2) }
;     MMA_TILE(0)
;     LDS_STORE(1, 1)
;     if (VAR != 4) __syncthreads();
;     if (kt + 3 < nk) { GL_LOAD(1, kt + 3) }
;     MMA_TILE(1)
;     if (kt + 2 < nk) { LDS_STORE(0, 0) }
;     if (VAR != 4) __syncthreads();
	ds_write_b128 v17, v[94:97] offset:32768
	v_mfma_f32_16x16x32_f16 v[24:27], v[74:77], v[110:113], v[24:27]
	ds_read_b128 v[74:77], v22 offset:51200
	v_mfma_f32_16x16x32_f16 v[114:117], v[118:121], v[90:93], v[114:117]
	s_waitcnt vmcnt(2)
	ds_write_b128 v18, v[162:165] offset:32768
	v_mfma_f32_16x16x32_f16 v[40:43], v[118:121], v[110:113], v[40:43]
	ds_read_b128 v[118:121], v22 offset:53248
	v_mfma_f32_16x16x32_f16 v[70:73], v[122:125], v[90:93], v[70:73]
	ds_read_b128 v[90:93], v23 offset:16384
	v_mfma_f32_16x16x32_f16 v[48:51], v[122:125], v[110:113], v[48:51]
	ds_read_b128 v[110:113], v23 offset:18432
	s_waitcnt lgkmcnt(1)
	v_mfma_f32_16x16x32_f16 v[36:39], v[62:65], v[90:93], v[36:39]
	ds_read_b128 v[122:125], v22 offset:55296
	s_waitcnt lgkmcnt(1)
	v_mfma_f32_16x16x32_f16 v[66:69], v[62:65], v[110:113], v[66:69]
	s_waitcnt vmcnt(1)
	ds_write_b128 v19, v[166:169] offset:32768
	v_mfma_f32_16x16x32_f16 v[44:47], v[74:77], v[90:93], v[44:47]
	s_waitcnt vmcnt(0)
	ds_write_b128 v20, v[190:193] offset:32768
	v_mfma_f32_16x16x32_f16 v[78:81], v[74:77], v[110:113], v[78:81]
	v_mfma_f32_16x16x32_f16 v[82:85], v[118:121], v[90:93], v[82:85]
	v_mfma_f32_16x16x32_f16 v[86:89], v[118:121], v[110:113], v[86:89]
	s_waitcnt lgkmcnt(2)
	v_mfma_f32_16x16x32_f16 v[28:31], v[122:125], v[90:93], v[28:31]
	ds_read_b128 v[90:93], v23 offset:20480
	v_mfma_f32_16x16x32_f16 v[32:35], v[122:125], v[110:113], v[32:35]
	ds_read_b128 v[110:113], v23 offset:22528
	s_waitcnt lgkmcnt(1)
	v_mfma_f32_16x16x32_f16 v[98:101], v[62:65], v[90:93], v[98:101]
	s_waitcnt lgkmcnt(0)
	v_mfma_f32_16x16x32_f16 v[52:55], v[62:65], v[110:113], v[52:55]
	global_load_dwordx4 v[62:65], v[0:1], off offset:2944
	v_mfma_f32_16x16x32_f16 v[102:105], v[74:77], v[90:93], v[102:105]
	v_mfma_f32_16x16x32_f16 v[24:27], v[74:77], v[110:113], v[24:27]
	v_mfma_f32_16x16x32_f16 v[114:117], v[118:121], v[90:93], v[114:117]
	v_mfma_f32_16x16x32_f16 v[40:43], v[118:121], v[110:113], v[40:43]
	v_mfma_f32_16x16x32_f16 v[70:73], v[122:125], v[90:93], v[70:73]
	global_load_dwordx4 v[90:93], v[2:3], off offset:2944
	global_load_dwordx4 v[126:129], v[4:5], off offset:2944
	global_load_dwordx4 v[130:133], v[14:15], off offset:2944
	global_load_dwordx4 v[74:77], v[10:11], off offset:2944
	global_load_dwordx4 v[138:141], v[12:13], off offset:2944
	global_load_dwordx4 v[142:145], v[8:9], off offset:2944
	global_load_dwordx4 v[154:157], v[6:7], off offset:2944
	s_waitcnt lgkmcnt(0)
	s_barrier
	v_mfma_f32_16x16x32_f16 v[48:51], v[122:125], v[110:113], v[48:51]
	ds_read_b128 v[58:61], v16 offset:32768
	ds_read_b128 v[106:109], v21
	s_waitcnt lgkmcnt(0)
	v_mfma_f32_16x16x32_f16 v[36:39], v[58:61], v[106:109], v[36:39]
	ds_read_b128 v[94:97], v16 offset:34816
	ds_read_b128 v[110:113], v21 offset:2048
	s_waitcnt lgkmcnt(0)
	v_mfma_f32_16x16x32_f16 v[66:69], v[58:61], v[110:113], v[66:69]
	ds_read_b128 v[118:121], v16 offset:36864
	v_mfma_f32_16x16x32_f16 v[44:47], v[94:97], v[106:109], v[44:47]
	ds_read_b128 v[122:125], v16 offset:38912
	v_mfma_f32_16x16x32_f16 v[78:81], v[94:97], v[110:113], v[78:81]
	s_waitcnt vmcnt(7)
	ds_write_b128 v17, v[62:65] offset:16384
	s_waitcnt lgkmcnt(2)
	v_mfma_f32_16x16x32_f16 v[82:85], v[118:121], v[106:109], v[82:85]
	s_waitcnt vmcnt(6)
	ds_write_b128 v18, v[90:93] offset:16384
	v_mfma_f32_16x16x32_f16 v[86:89], v[118:121], v[110:113], v[86:89]
	s_waitcnt vmcnt(5)
	ds_write_b128 v19, v[126:129] offset:16384
	s_waitcnt lgkmcnt(3)
	v_mfma_f32_16x16x32_f16 v[28:31], v[122:125], v[106:109], v[28:31]
	ds_read_b128 v[106:109], v21 offset:4096
	v_mfma_f32_16x16x32_f16 v[32:35], v[122:125], v[110:113], v[32:35]
	ds_read_b128 v[110:113], v21 offset:6144
	s_waitcnt lgkmcnt(1)
	v_mfma_f32_16x16x32_f16 v[98:101], v[58:61], v[106:109], v[98:101]
	s_waitcnt vmcnt(4)
	ds_write_b128 v20, v[130:133] offset:16384
	s_waitcnt lgkmcnt(1)
	v_mfma_f32_16x16x32_f16 v[52:55], v[58:61], v[110:113], v[52:55]
	ds_read_b128 v[58:61], v22 offset:32768
	v_mfma_f32_16x16x32_f16 v[102:105], v[94:97], v[106:109], v[102:105]
	s_waitcnt vmcnt(3)
	ds_write_b128 v17, v[74:77] offset:49152
	v_mfma_f32_16x16x32_f16 v[24:27], v[94:97], v[110:113], v[24:27]
	ds_read_b128 v[94:97], v22 offset:34816
	v_mfma_f32_16x16x32_f16 v[114:117], v[118:121], v[106:109], v[114:117]
	s_waitcnt vmcnt(2)
	ds_write_b128 v18, v[138:141] offset:49152
	v_mfma_f32_16x16x32_f16 v[40:43], v[118:121], v[110:113], v[40:43]
	ds_read_b128 v[118:121], v22 offset:36864
	v_mfma_f32_16x16x32_f16 v[70:73], v[122:125], v[106:109], v[70:73]
	ds_read_b128 v[106:109], v23
	v_mfma_f32_16x16x32_f16 v[48:51], v[122:125], v[110:113], v[48:51]
	ds_read_b128 v[110:113], v23 offset:2048
	s_waitcnt lgkmcnt(1)
	v_mfma_f32_16x16x32_f16 v[36:39], v[58:61], v[106:109], v[36:39]
	ds_read_b128 v[122:125], v22 offset:38912
	s_waitcnt lgkmcnt(1)
	v_mfma_f32_16x16x32_f16 v[66:69], v[58:61], v[110:113], v[66:69]
	s_waitcnt vmcnt(1)
	ds_write_b128 v19, v[142:145] offset:49152
	v_mfma_f32_16x16x32_f16 v[44:47], v[94:97], v[106:109], v[44:47]
	s_waitcnt vmcnt(0)
	ds_write_b128 v20, v[154:157] offset:49152
	v_mfma_f32_16x16x32_f16 v[78:81], v[94:97], v[110:113], v[78:81]
	v_mfma_f32_16x16x32_f16 v[82:85], v[118:121], v[106:109], v[82:85]
	v_mfma_f32_16x16x32_f16 v[86:89], v[118:121], v[110:113], v[86:89]
	s_waitcnt lgkmcnt(2)
	v_mfma_f32_16x16x32_f16 v[28:31], v[122:125], v[106:109], v[28:31]
	ds_read_b128 v[106:109], v23 offset:4096
	v_mfma_f32_16x16x32_f16 v[32:35], v[122:125], v[110:113], v[32:35]
	ds_read_b128 v[110:113], v23 offset:6144
	s_waitcnt lgkmcnt(1)
	v_mfma_f32_16x16x32_f16 v[98:101], v[58:61], v[106:109], v[98:101]
	s_waitcnt lgkmcnt(0)
	v_mfma_f32_16x16x32_f16 v[52:55], v[58:61], v[110:113], v[52:55]
	global_load_dwordx4 v[58:61], v[0:1], off offset:3072
	v_mfma_f32_16x16x32_f16 v[102:105], v[94:97], v[106:109], v[102:105]
	v_mfma_f32_16x16x32_f16 v[24:27], v[94:97], v[110:113], v[24:27]
	v_mfma_f32_16x16x32_f16 v[114:117], v[118:121], v[106:109], v[114:117]
	v_mfma_f32_16x16x32_f16 v[40:43], v[118:121], v[110:113], v[40:43]
	v_mfma_f32_16x16x32_f16 v[70:73], v[122:125], v[106:109], v[70:73]
	global_load_dwordx4 v[106:109], v[2:3], off offset:3072
	global_load_dwordx4 v[134:137], v[4:5], off offset:3072
	global_load_dwordx4 v[158:161], v[14:15], off offset:3072
	global_load_dwordx4 v[94:97], v[10:11], off offset:3072
	global_load_dwordx4 v[162:165], v[12:13], off offset:3072
	global_load_dwordx4 v[166:169], v[8:9], off offset:3072
	global_load_dwordx4 v[190:193], v[6:7], off offset:3072
	s_waitcnt lgkmcnt(0)
	s_barrier
; #define GL_LOAD(s_, kt_) if (VAR != 1) { a##s_##0 = GL_A(0, kt_); a##s_##1 = GL_A(1, kt_); a##s_##2 = GL_A(2, kt_); a##s_##3 = GL_A(3, kt_); b##s_##0 = GL_B(0, kt_); b##s_##1 = GL_B(1, kt_); b##s_##2 = GL_B(2, kt_); b##s_##3 = GL_B(3, kt_); }
; #define LDS_STORE(s_, buf_) if (VAR != 2) { LDS_ST1(sA, 0, buf_, a##s_##0) LDS_ST1(sA, 1, buf_, a##s_##1) LDS_ST1(sA, 2, buf_, a##s_##2) LDS_ST1(sA, 3, buf_, a##s_##3) LDS_ST1(sB, 0, buf_, b##s_##0) LDS_ST1(sB, 1, buf_, b##s_##1) LDS_ST1(sB, 2, buf_, b##s_##2) LDS_ST1(sB, 3, buf_, b##s_##3) }
;     ...
;   GL_LOAD(0, 0)
;   GL_LOAD(1, 1)
;   LDS_STORE(0, 0)
;   if (VAR != 4) __syncthreads();
; #pragma unroll
;   for (int kt = 0; kt < nk; kt += 2) {
;     if (kt + 2 < nk) { GL_LOAD(0, kt + 2) }
;     MMA_TILE(0)
;     LDS_STORE(1, 1)
;     if (VAR != 4) __syncthreads();
;     if (kt + 3 < nk) { GL_LOAD(1, kt + 3) }
;     MMA_TILE(1)
;     if (kt + 2 < nk) { LDS_STORE(0, 0) }
;     if (VAR != 4) __syncthreads();
	v_mfma_f32_16x16x32_f16 v[48:51], v[122:125], v[110:113], v[48:51]
	ds_read_b128 v[62:65], v16 offset:49152
	ds_read_b128 v[90:93], v21 offset:16384
	s_waitcnt lgkmcnt(0)
	v_mfma_f32_16x16x32_f16 v[36:39], v[62:65], v[90:93], v[36:39]
	ds_read_b128 v[74:77], v16 offset:51200
	ds_read_b128 v[110:113], v21 offset:18432
	s_waitcnt lgkmcnt(0)
	v_mfma_f32_16x16x32_f16 v[66:69], v[62:65], v[110:113], v[66:69]
	ds_read_b128 v[118:121], v16 offset:53248
	v_mfma_f32_16x16x32_f16 v[44:47], v[74:77], v[90:93], v[44:47]
	ds_read_b128 v[122:125], v16 offset:55296
	v_mfma_f32_16x16x32_f16 v[78:81], v[74:77], v[110:113], v[78:81]
	s_waitcnt vmcnt(7)
	ds_write_b128 v17, v[58:61]
	s_waitcnt lgkmcnt(2)
	v_mfma_f32_16x16x32_f16 v[82:85], v[118:121], v[90:93], v[82:85]
	s_waitcnt vmcnt(6)
	ds_write_b128 v18, v[106:109]
	v_mfma_f32_16x16x32_f16 v[86:89], v[118:121], v[110:113], v[86:89]
	s_waitcnt vmcnt(5)
	ds_write_b128 v19, v[134:137]
	s_waitcnt lgkmcnt(3)
	v_mfma_f32_16x16x32_f16 v[28:31], v[122:125], v[90:93], v[28:31]
	ds_read_b128 v[90:93], v21 offset:20480
	v_mfma_f32_16x16x32_f16 v[32:35], v[122:125], v[110:113], v[32:35]
	ds_read_b128 v[110:113], v21 offset:22528
	s_waitcnt lgkmcnt(1)
	v_mfma_f32_16x16x32_f16 v[98:101], v[62:65], v[90:93], v[98:101]
	s_waitcnt vmcnt(4)
	ds_write_b128 v20, v[158:161]
	s_waitcnt lgkmcnt(1)
	v_mfma_f32_16x16x32_f16 v[52:55], v[62:65], v[110:113], v[52:55]
	ds_read_b128 v[62:65], v22 offset:49152
	v_mfma_f32_16x16x32_f16 v[102:105], v[74:77], v[90:93], v[102:105]
	s_waitcnt vmcnt(3)
	ds_write_b128 v17, v[94:97] offset:32768
	v_mfma_f32_16x16x32_f16 v[24:27], v[74:77], v[110:113], v[24:27]
	ds_read_b128 v[74:77], v22 offset:51200
	v_mfma_f32_16x16x32_f16 v[114:117], v[118:121], v[90:93], v[114:117]
	s_waitcnt vmcnt(2)
	ds_write_b128 v18, v[162:165] offset:32768
	v_mfma_f32_16x16x32_f16 v[40:43], v[118:121], v[110:113], v[40:43]
	ds_read_b128 v[118:121], v22 offset:53248
	v_mfma_f32_16x16x32_f16 v[70:73], v[122:125], v[90:93], v[70:73]
	ds_read_b128 v[90:93], v23 offset:16384
	v_mfma_f32_16x16x32_f16 v[48:51], v[122:125], v[110:113], v[48:51]
	ds_read_b128 v[110:113], v23 offset:18432
	s_waitcnt lgkmcnt(1)
	v_mfma_f32_16x16x32_f16 v[36:39], v[62:65], v[90:93], v[36:39]
	ds_read_b128 v[122:125], v22 offset:55296
	s_waitcnt lgkmcnt(1)
	v_mfma_f32_16x16x32_f16 v[66:69], v[62:65], v[110:113], v[66:69]
	s_waitcnt vmcnt(1)
	ds_write_b128 v19, v[166:169] offset:32768
	v_mfma_f32_16x16x32_f16 v[44:47], v[74:77], v[90:93], v[44:47]
	s_waitcnt vmcnt(0)
	ds_write_b128 v20, v[190:193] offset:32768
	v_mfma_f32_16x16x32_f16 v[78:81], v[74:77], v[110:113], v[78:81]
	v_mfma_f32_16x16x32_f16 v[82:85], v[118:121], v[90:93], v[82:85]
	v_mfma_f32_16x16x32_f16 v[86:89], v[118:121], v[110:113], v[86:89]
	s_waitcnt lgkmcnt(2)
	v_mfma_f32_16x16x32_f16 v[28:31], v[122:125], v[90:93], v[28:31]
	ds_read_b128 v[90:93], v23 offset:20480
	v_mfma_f32_16x16x32_f16 v[32:35], v[122:125], v[110:113], v[32:35]
	ds_read_b128 v[110:113], v23 offset:22528
	s_waitcnt lgkmcnt(1)
	v_mfma_f32_16x16x32_f16 v[98:101], v[62:65], v[90:93], v[98:101]
	s_waitcnt lgkmcnt(0)
	v_mfma_f32_16x16x32_f16 v[52:55], v[62:65], v[110:113], v[52:55]
	global_load_dwordx4 v[62:65], v[0:1], off offset:3200
	v_mfma_f32_16x16x32_f16 v[102:105], v[74:77], v[90:93], v[102:105]
	v_mfma_f32_16x16x32_f16 v[24:27], v[74:77], v[110:113], v[24:27]
	v_mfma_f32_16x16x32_f16 v[114:117], v[118:121], v[90:93], v[114:117]
	v_mfma_f32_16x16x32_f16 v[40:43], v[118:121], v[110:113], v[40:43]
	v_mfma_f32_16x16x32_f16 v[70:73], v[122:125], v[90:93], v[70:73]
	global_load_dwordx4 v[90:93], v[2:3], off offset:3200
	global_load_dwordx4 v[126:129], v[4:5], off offset:3200
	global_load_dwordx4 v[130:133], v[14:15], off offset:3200
	global_load_dwordx4 v[74:77], v[10:11], off offset:3200
	global_load_dwordx4 v[138:141], v[12:13], off offset:3200
	global_load_dwordx4 v[142:145], v[8:9], off offset:3200
	global_load_dwordx4 v[154:157], v[6:7], off offset:3200
	s_waitcnt lgkmcnt(0)
	s_barrier
	v_mfma_f32_16x16x32_f16 v[48:51], v[122:125], v[110:113], v[48:51]
	ds_read_b128 v[58:61], v16 offset:32768
	ds_read_b128 v[106:109], v21
	s_waitcnt lgkmcnt(0)
	v_mfma_f32_16x16x32_f16 v[36:39], v[58:61], v[106:109], v[36:39]
	ds_read_b128 v[94:97], v16 offset:34816
	ds_read_b128 v[110:113], v21 offset:2048
	s_waitcnt lgkmcnt(0)
	v_mfma_f32_16x16x32_f16 v[66:69], v[58:61], v[110:113], v[66:69]
	ds_read_b128 v[118:121], v16 offset:36864
	v_mfma_f32_16x16x32_f16 v[44:47], v[94:97], v[106:109], v[44:47]
	ds_read_b128 v[122:125], v16 offset:38912
	v_mfma_f32_16x16x32_f16 v[78:81], v[94:97], v[110:113], v[78:81]
	s_waitcnt vmcnt(7)
	ds_write_b128 v17, v[62:65] offset:16384
	s_waitcnt lgkmcnt(2)
	v_mfma_f32_16x16x32_f16 v[82:85], v[118:121], v[106:109], v[82:85]
	s_waitcnt vmcnt(6)
	ds_write_b128 v18, v[90:93] offset:16384
	v_mfma_f32_16x16x32_f16 v[86:89], v[118:121], v[110:113], v[86:89]
	s_waitcnt vmcnt(5)
	ds_write_b128 v19, v[126:129] offset:16384
	s_waitcnt lgkmcnt(3)
	v_mfma_f32_16x16x32_f16 v[28:31], v[122:125], v[106:109], v[28:31]
	ds_read_b128 v[106:109], v21 offset:4096
	v_mfma_f32_16x16x32_f16 v[32:35], v[122:125], v[110:113], v[32:35]
	ds_read_b128 v[110:113], v21 offset:6144
	s_waitcnt lgkmcnt(1)
	v_mfma_f32_16x16x32_f16 v[98:101], v[58:61], v[106:109], v[98:101]
	s_waitcnt vmcnt(4)
	ds_write_b128 v20, v[130:133] offset:16384
	s_waitcnt lgkmcnt(1)
	v_mfma_f32_16x16x32_f16 v[52:55], v[58:61], v[110:113], v[52:55]
	ds_read_b128 v[58:61], v22 offset:32768
	v_mfma_f32_16x16x32_f16 v[102:105], v[94:97], v[106:109], v[102:105]
	s_waitcnt vmcnt(3)
; #define GL_LOAD(s_, kt_) if (VAR != 1) { a##s_##0 = GL_A(0, kt_); a##s_##1 = GL_A(1, kt_); a##s_##2 = GL_A(2, kt_); a##s_##3 = GL_A(3, kt_); b##s_##0 = GL_B(0, kt_); b##s_##1 = GL_B(1, kt_); b##s_##2 = GL_B(2, kt_); b##s_##3 = GL_B(3, kt_); }
; #define LDS_STORE(s_, buf_) if (VAR != 2) { LDS_ST1(sA, 0, buf_, a##s_##0) LDS_ST1(sA, 1, buf_, a##s_##1) LDS_ST1(sA, 2, buf_, a##s_##2) LDS_ST1(sA, 3, buf_, a##s_##3) LDS_ST1(sB, 0, buf_, b##s_##0) LDS_ST1(sB, 1, buf_, b##s_##1) LDS_ST1(sB, 2, buf_, b##s_##2) LDS_ST1(sB, 3, buf_, b##s_##3) }
;     ...
;   GL_LOAD(0, 0)
;   GL_LOAD(1, 1)
;   LDS_STORE(0, 0)
;   if (VAR != 4) __syncthreads();
; #pragma unroll
;   for (int kt = 0; kt < nk; kt += 2) {
;     if (kt + 2 < nk) { GL_LOAD(0, kt + 2) }
;     MMA_TILE(0)
;     LDS_STORE(1, 1)
;     if (VAR != 4) __syncthreads();
;     if (kt + 3 < nk) { GL_LOAD(1, kt + 3) }
;     MMA_TILE(1)
;     if (kt + 2 < nk) { LDS_STORE(0, 0) }
;     if (VAR != 4) __syncthreads();
	ds_write_b128 v17, v[74:77] offset:49152
	v_mfma_f32_16x16x32_f16 v[24:27], v[94:97], v[110:113], v[24:27]
	ds_read_b128 v[94:97], v22 offset:34816
	v_mfma_f32_16x16x32_f16 v[114:117], v[118:121], v[106:109], v[114:117]
	s_waitcnt vmcnt(2)
	ds_write_b128 v18, v[138:141] offset:49152
	v_mfma_f32_16x16x32_f16 v[40:43], v[118:121], v[110:113], v[40:43]
	ds_read_b128 v[118:121], v22 offset:36864
	v_mfma_f32_16x16x32_f16 v[70:73], v[122:125], v[106:109], v[70:73]
	ds_read_b128 v[106:109], v23
	v_mfma_f32_16x16x32_f16 v[48:51], v[122:125], v[110:113], v[48:51]
	ds_read_b128 v[110:113], v23 offset:2048
	s_waitcnt lgkmcnt(1)
	v_mfma_f32_16x16x32_f16 v[36:39], v[58:61], v[106:109], v[36:39]
	ds_read_b128 v[122:125], v22 offset:38912
	s_waitcnt lgkmcnt(1)
	v_mfma_f32_16x16x32_f16 v[66:69], v[58:61], v[110:113], v[66:69]
	s_waitcnt vmcnt(1)
	ds_write_b128 v19, v[142:145] offset:49152
	v_mfma_f32_16x16x32_f16 v[44:47], v[94:97], v[106:109], v[44:47]
	s_waitcnt vmcnt(0)
	ds_write_b128 v20, v[154:157] offset:49152
	v_mfma_f32_16x16x32_f16 v[78:81], v[94:97], v[110:113], v[78:81]
	v_mfma_f32_16x16x32_f16 v[82:85], v[118:121], v[106:109], v[82:85]
	v_mfma_f32_16x16x32_f16 v[86:89], v[118:121], v[110:113], v[86:89]
	s_waitcnt lgkmcnt(2)
	v_mfma_f32_16x16x32_f16 v[28:31], v[122:125], v[106:109], v[28:31]
	ds_read_b128 v[106:109], v23 offset:4096
	v_mfma_f32_16x16x32_f16 v[32:35], v[122:125], v[110:113], v[32:35]
	ds_read_b128 v[110:113], v23 offset:6144
	s_waitcnt lgkmcnt(1)
	v_mfma_f32_16x16x32_f16 v[98:101], v[58:61], v[106:109], v[98:101]
	s_waitcnt lgkmcnt(0)
	v_mfma_f32_16x16x32_f16 v[52:55], v[58:61], v[110:113], v[52:55]
	global_load_dwordx4 v[58:61], v[0:1], off offset:3328
	v_mfma_f32_16x16x32_f16 v[102:105], v[94:97], v[106:109], v[102:105]
	v_mfma_f32_16x16x32_f16 v[24:27], v[94:97], v[110:113], v[24:27]
	v_mfma_f32_16x16x32_f16 v[114:117], v[118:121], v[106:109], v[114:117]
	v_mfma_f32_16x16x32_f16 v[40:43], v[118:121], v[110:113], v[40:43]
	v_mfma_f32_16x16x32_f16 v[70:73], v[122:125], v[106:109], v[70:73]
	global_load_dwordx4 v[106:109], v[2:3], off offset:3328
	global_load_dwordx4 v[134:137], v[4:5], off offset:3328
	global_load_dwordx4 v[158:161], v[14:15], off offset:3328
	global_load_dwordx4 v[94:97], v[10:11], off offset:3328
	global_load_dwordx4 v[162:165], v[12:13], off offset:3328
	global_load_dwordx4 v[166:169], v[8:9], off offset:3328
	global_load_dwordx4 v[190:193], v[6:7], off offset:3328
	s_waitcnt lgkmcnt(0)
	s_barrier
	v_mfma_f32_16x16x32_f16 v[48:51], v[122:125], v[110:113], v[48:51]
	ds_read_b128 v[62:65], v16 offset:49152
	ds_read_b128 v[90:93], v21 offset:16384
	s_waitcnt lgkmcnt(0)
	v_mfma_f32_16x16x32_f16 v[36:39], v[62:65], v[90:93], v[36:39]
	ds_read_b128 v[74:77], v16 offset:51200
	ds_read_b128 v[110:113], v21 offset:18432
	s_waitcnt lgkmcnt(0)
	v_mfma_f32_16x16x32_f16 v[66:69], v[62:65], v[110:113], v[66:69]
	ds_read_b128 v[118:121], v16 offset:53248
	v_mfma_f32_16x16x32_f16 v[44:47], v[74:77], v[90:93], v[44:47]
	ds_read_b128 v[122:125], v16 offset:55296
	v_mfma_f32_16x16x32_f16 v[78:81], v[74:77], v[110:113], v[78:81]
	s_waitcnt vmcnt(7)
	ds_write_b128 v17, v[58:61]
	s_waitcnt lgkmcnt(2)
	v_mfma_f32_16x16x32_f16 v[82:85], v[118:121], v[90:93], v[82:85]
	s_waitcnt vmcnt(6)
	ds_write_b128 v18, v[106:109]
	v_mfma_f32_16x16x32_f16 v[86:89], v[118:121], v[110:113], v[86:89]
	s_waitcnt vmcnt(5)
	ds_write_b128 v19, v[134:137]
	s_waitcnt lgkmcnt(3)
	v_mfma_f32_16x16x32_f16 v[28:31], v[122:125], v[90:93], v[28:31]
	ds_read_b128 v[90:93], v21 offset:20480
	v_mfma_f32_16x16x32_f16 v[32:35], v[122:125], v[110:113], v[32:35]
	ds_read_b128 v[110:113], v21 offset:22528
	s_waitcnt lgkmcnt(1)
	v_mfma_f32_16x16x32_f16 v[98:101], v[62:65], v[90:93], v[98:101]
	s_waitcnt vmcnt(4)
	ds_write_b128 v20, v[158:161]
	s_waitcnt lgkmcnt(1)
	v_mfma_f32_16x16x32_f16 v[52:55], v[62:65], v[110:113], v[52:55]
	ds_read_b128 v[62:65], v22 offset:49152
	v_mfma_f32_16x16x32_f16 v[102:105], v[74:77], v[90:93], v[102:105]
	s_waitcnt vmcnt(3)
	ds_write_b128 v17, v[94:97] offset:32768
	v_mfma_f32_16x16x32_f16 v[24:27], v[74:77], v[110:113], v[24:27]
	ds_read_b128 v[74:77], v22 offset:51200
	v_mfma_f32_16x16x32_f16 v[114:117], v[118:121], v[90:93], v[114:117]
	s_waitcnt vmcnt(2)
	ds_write_b128 v18, v[162:165] offset:32768
	v_mfma_f32_16x16x32_f16 v[40:43], v[118:121], v[110:113], v[40:43]
	ds_read_b128 v[118:121], v22 offset:53248
	v_mfma_f32_16x16x32_f16 v[70:73], v[122:125], v[90:93], v[70:73]
	ds_read_b128 v[90:93], v23 offset:16384
	v_mfma_f32_16x16x32_f16 v[48:51], v[122:125], v[110:113], v[48:51]
	ds_read_b128 v[110:113], v23 offset:18432
	s_waitcnt lgkmcnt(1)
	v_mfma_f32_16x16x32_f16 v[36:39], v[62:65], v[90:93], v[36:39]
	ds_read_b128 v[122:125], v22 offset:55296
	s_waitcnt lgkmcnt(1)
	v_mfma_f32_16x16x32_f16 v[66:69], v[62:65], v[110:113], v[66:69]
	s_waitcnt vmcnt(1)
	ds_write_b128 v19, v[166:169] offset:32768
	v_mfma_f32_16x16x32_f16 v[44:47], v[74:77], v[90:93], v[44:47]
	s_waitcnt vmcnt(0)
	ds_write_b128 v20, v[190:193] offset:32768
	v_mfma_f32_16x16x32_f16 v[78:81], v[74:77], v[110:113], v[78:81]
	v_mfma_f32_16x16x32_f16 v[82:85], v[118:121], v[90:93], v[82:85]
	v_mfma_f32_16x16x32_f16 v[86:89], v[118:121], v[110:113], v[86:89]
	s_waitcnt lgkmcnt(2)
	v_mfma_f32_16x16x32_f16 v[28:31], v[122:125], v[90:93], v[28:31]
	ds_read_b128 v[90:93], v23 offset:20480
	v_mfma_f32_16x16x32_f16 v[32:35], v[122:125], v[110:113], v[32:35]
	ds_read_b128 v[110:113], v23 offset:22528
	s_waitcnt lgkmcnt(1)
	v_mfma_f32_16x16x32_f16 v[98:101], v[62:65], v[90:93], v[98:101]
	s_waitcnt lgkmcnt(0)
	v_mfma_f32_16x16x32_f16 v[52:55], v[62:65], v[110:113], v[52:55]
	global_load_dwordx4 v[62:65], v[0:1], off offset:3456
	v_mfma_f32_16x16x32_f16 v[102:105], v[74:77], v[90:93], v[102:105]
	v_mfma_f32_16x16x32_f16 v[24:27], v[74:77], v[110:113], v[24:27]
	v_mfma_f32_16x16x32_f16 v[114:117], v[118:121], v[90:93], v[114:117]
	v_mfma_f32_16x16x32_f16 v[40:43], v[118:121], v[110:113], v[40:43]
	v_mfma_f32_16x16x32_f16 v[70:73], v[122:125], v[90:93], v[70:73]
	global_load_dwordx4 v[90:93], v[2:3], off offset:3456
	global_load_dwordx4 v[126:129], v[4:5], off offset:3456
	global_load_dwordx4 v[130:133], v[14:15], off offset:3456
	global_load_dwordx4 v[74:77], v[10:11], off offset:3456
	global_load_dwordx4 v[138:141], v[12:13], off offset:3456
	global_load_dwordx4 v[142:145], v[8:9], off offset:3456
	global_load_dwordx4 v[154:157], v[6:7], off offset:3456
	s_waitcnt lgkmcnt(0)
	s_barrier
; #define GL_LOAD(s_, kt_) if (VAR != 1) { a##s_##0 = GL_A(0, kt_); a##s_##1 = GL_A(1, kt_); a##s_##2 = GL_A(2, kt_); a##s_##3 = GL_A(3, kt_); b##s_##0 = GL_B(0, kt_); b##s_##1 = GL_B(1, kt_); b##s_##2 = GL_B(2, kt_); b##s_##3 = GL_B(3, kt_); }
; #define LDS_STORE(s_, buf_) if (VAR != 2) { LDS_ST1(sA, 0, buf_, a##s_##0) LDS_ST1(sA, 1, buf_, a##s_##1) LDS_ST1(sA, 2, buf_, a##s_##2) LDS_ST1(sA, 3, buf_, a##s_##3) LDS_ST1(sB, 0, buf_, b##s_##0) LDS_ST1(sB, 1, buf_, b##s_##1) LDS_ST1(sB, 2, buf_, b##s_##2) LDS_ST1(sB, 3, buf_, b##s_##3) }
;     ...
;   GL_LOAD(0, 0)
;   GL_LOAD(1, 1)
;   LDS_STORE(0, 0)
;   if (VAR != 4) __syncthreads();
; #pragma unroll
;   for (int kt = 0; kt < nk; kt += 2) {
;     if (kt + 2 < nk) { GL_LOAD(0, kt + 2) }
;     MMA_TILE(0)
;     LDS_STORE(1, 1)
;     if (VAR != 4) __syncthreads();
;     if (kt + 3 < nk) { GL_LOAD(1, kt + 3) }
;     MMA_TILE(1)
;     if (kt + 2 < nk) { LDS_STORE(0, 0) }
;     if (VAR != 4) __syncthreads();
	v_mfma_f32_16x16x32_f16 v[48:51], v[122:125], v[110:113], v[48:51]
	ds_read_b128 v[58:61], v16 offset:32768
	ds_read_b128 v[106:109], v21
	s_waitcnt lgkmcnt(0)
	v_mfma_f32_16x16x32_f16 v[36:39], v[58:61], v[106:109], v[36:39]
	ds_read_b128 v[94:97], v16 offset:34816
	ds_read_b128 v[110:113], v21 offset:2048
	s_waitcnt lgkmcnt(0)
	v_mfma_f32_16x16x32_f16 v[66:69], v[58:61], v[110:113], v[66:69]
	ds_read_b128 v[118:121], v16 offset:36864
	v_mfma_f32_16x16x32_f16 v[44:47], v[94:97], v[106:109], v[44:47]
	ds_read_b128 v[122:125], v16 offset:38912
	v_mfma_f32_16x16x32_f16 v[78:81], v[94:97], v[110:113], v[78:81]
	s_waitcnt vmcnt(7)
	ds_write_b128 v17, v[62:65] offset:16384
	s_waitcnt lgkmcnt(2)
	v_mfma_f32_16x16x32_f16 v[82:85], v[118:121], v[106:109], v[82:85]
	s_waitcnt vmcnt(6)
	ds_write_b128 v18, v[90:93] offset:16384
	v_mfma_f32_16x16x32_f16 v[86:89], v[118:121], v[110:113], v[86:89]
	s_waitcnt vmcnt(5)
	ds_write_b128 v19, v[126:129] offset:16384
	s_waitcnt lgkmcnt(3)
	v_mfma_f32_16x16x32_f16 v[28:31], v[122:125], v[106:109], v[28:31]
	ds_read_b128 v[106:109], v21 offset:4096
	v_mfma_f32_16x16x32_f16 v[32:35], v[122:125], v[110:113], v[32:35]
	ds_read_b128 v[110:113], v21 offset:6144
	s_waitcnt lgkmcnt(1)
	v_mfma_f32_16x16x32_f16 v[98:101], v[58:61], v[106:109], v[98:101]
	s_waitcnt vmcnt(4)
	ds_write_b128 v20, v[130:133] offset:16384
	s_waitcnt lgkmcnt(1)
	v_mfma_f32_16x16x32_f16 v[52:55], v[58:61], v[110:113], v[52:55]
	ds_read_b128 v[58:61], v22 offset:32768
	v_mfma_f32_16x16x32_f16 v[102:105], v[94:97], v[106:109], v[102:105]
	s_waitcnt vmcnt(3)
	ds_write_b128 v17, v[74:77] offset:49152
	v_mfma_f32_16x16x32_f16 v[24:27], v[94:97], v[110:113], v[24:27]
	ds_read_b128 v[94:97], v22 offset:34816
	v_mfma_f32_16x16x32_f16 v[114:117], v[118:121], v[106:109], v[114:117]
	s_waitcnt vmcnt(2)
	ds_write_b128 v18, v[138:141] offset:49152
	v_mfma_f32_16x16x32_f16 v[40:43], v[118:121], v[110:113], v[40:43]
	ds_read_b128 v[118:121], v22 offset:36864
	v_mfma_f32_16x16x32_f16 v[70:73], v[122:125], v[106:109], v[70:73]
	ds_read_b128 v[106:109], v23
	v_mfma_f32_16x16x32_f16 v[48:51], v[122:125], v[110:113], v[48:51]
	ds_read_b128 v[110:113], v23 offset:2048
	s_waitcnt lgkmcnt(1)
	v_mfma_f32_16x16x32_f16 v[36:39], v[58:61], v[106:109], v[36:39]
	ds_read_b128 v[122:125], v22 offset:38912
	s_waitcnt lgkmcnt(1)
	v_mfma_f32_16x16x32_f16 v[66:69], v[58:61], v[110:113], v[66:69]
	s_waitcnt vmcnt(1)
	ds_write_b128 v19, v[142:145] offset:49152
	v_mfma_f32_16x16x32_f16 v[44:47], v[94:97], v[106:109], v[44:47]
	s_waitcnt vmcnt(0)
	ds_write_b128 v20, v[154:157] offset:49152
	v_mfma_f32_16x16x32_f16 v[78:81], v[94:97], v[110:113], v[78:81]
	v_mfma_f32_16x16x32_f16 v[82:85], v[118:121], v[106:109], v[82:85]
	v_mfma_f32_16x16x32_f16 v[86:89], v[118:121], v[110:113], v[86:89]
	s_waitcnt lgkmcnt(2)
	v_mfma_f32_16x16x32_f16 v[28:31], v[122:125], v[106:109], v[28:31]
	ds_read_b128 v[106:109], v23 offset:4096
	v_mfma_f32_16x16x32_f16 v[32:35], v[122:125], v[110:113], v[32:35]
	ds_read_b128 v[110:113], v23 offset:6144
	s_waitcnt lgkmcnt(1)
	v_mfma_f32_16x16x32_f16 v[98:101], v[58:61], v[106:109], v[98:101]
	s_waitcnt lgkmcnt(0)
	v_mfma_f32_16x16x32_f16 v[52:55], v[58:61], v[110:113], v[52:55]
	global_load_dwordx4 v[58:61], v[0:1], off offset:3584
	v_mfma_f32_16x16x32_f16 v[102:105], v[94:97], v[106:109], v[102:105]
	v_mfma_f32_16x16x32_f16 v[24:27], v[94:97], v[110:113], v[24:27]
	v_mfma_f32_16x16x32_f16 v[114:117], v[118:121], v[106:109], v[114:117]
	v_mfma_f32_16x16x32_f16 v[40:43], v[118:121], v[110:113], v[40:43]
	v_mfma_f32_16x16x32_f16 v[70:73], v[122:125], v[106:109], v[70:73]
	global_load_dwordx4 v[106:109], v[2:3], off offset:3584
	global_load_dwordx4 v[134:137], v[4:5], off offset:3584
	global_load_dwordx4 v[158:161], v[14:15], off offset:3584
	global_load_dwordx4 v[94:97], v[10:11], off offset:3584
	global_load_dwordx4 v[162:165], v[12:13], off offset:3584
	global_load_dwordx4 v[166:169], v[8:9], off offset:3584
	global_load_dwordx4 v[190:193], v[6:7], off offset:3584
	s_waitcnt lgkmcnt(0)
	s_barrier
	v_mfma_f32_16x16x32_f16 v[48:51], v[122:125], v[110:113], v[48:51]
	ds_read_b128 v[62:65], v16 offset:49152
	ds_read_b128 v[90:93], v21 offset:16384
	s_waitcnt lgkmcnt(0)
	v_mfma_f32_16x16x32_f16 v[36:39], v[62:65], v[90:93], v[36:39]
	ds_read_b128 v[74:77], v16 offset:51200
	ds_read_b128 v[110:113], v21 offset:18432
	s_waitcnt lgkmcnt(0)
	v_mfma_f32_16x16x32_f16 v[66:69], v[62:65], v[110:113], v[66:69]
	ds_read_b128 v[118:121], v16 offset:53248
	v_mfma_f32_16x16x32_f16 v[44:47], v[74:77], v[90:93], v[44:47]
	ds_read_b128 v[122:125], v16 offset:55296
	v_mfma_f32_16x16x32_f16 v[78:81], v[74:77], v[110:113], v[78:81]
	s_waitcnt vmcnt(7)
	ds_write_b128 v17, v[58:61]
	s_waitcnt lgkmcnt(2)
	v_mfma_f32_16x16x32_f16 v[82:85], v[118:121], v[90:93], v[82:85]
	s_waitcnt vmcnt(6)
	ds_write_b128 v18, v[106:109]
	v_mfma_f32_16x16x32_f16 v[86:89], v[118:121], v[110:113], v[86:89]
	s_waitcnt vmcnt(5)
	ds_write_b128 v19, v[134:137]
	s_waitcnt lgkmcnt(3)
	v_mfma_f32_16x16x32_f16 v[28:31], v[122:125], v[90:93], v[28:31]
	ds_read_b128 v[90:93], v21 offset:20480
	v_mfma_f32_16x16x32_f16 v[32:35], v[122:125], v[110:113], v[32:35]
	ds_read_b128 v[110:113], v21 offset:22528
	s_waitcnt lgkmcnt(1)
	v_mfma_f32_16x16x32_f16 v[98:101], v[62:65], v[90:93], v[98:101]
	s_waitcnt vmcnt(4)
	ds_write_b128 v20, v[158:161]
	s_waitcnt lgkmcnt(1)
	v_mfma_f32_16x16x32_f16 v[52:55], v[62:65], v[110:113], v[52:55]
	ds_read_b128 v[62:65], v22 offset:49152
	v_mfma_f32_16x16x32_f16 v[102:105], v[74:77], v[90:93], v[102:105]
	s_waitcnt vmcnt(3)
; #define GL_LOAD(s_, kt_) if (VAR != 1) { a##s_##0 = GL_A(0, kt_); a##s_##1 = GL_A(1, kt_); a##s_##2 = GL_A(2, kt_); a##s_##3 = GL_A(3, kt_); b##s_##0 = GL_B(0, kt_); b##s_##1 = GL_B(1, kt_); b##s_##2 = GL_B(2, kt_); b##s_##3 = GL_B(3, kt_); }
; #define LDS_STORE(s_, buf_) if (VAR != 2) { LDS_ST1(sA, 0, buf_, a##s_##0) LDS_ST1(sA, 1, buf_, a##s_##1) LDS_ST1(sA, 2, buf_, a##s_##2) LDS_ST1(sA, 3, buf_, a##s_##3) LDS_ST1(sB, 0, buf_, b##s_##0) LDS_ST1(sB, 1, buf_, b##s_##1) LDS_ST1(sB, 2, buf_, b##s_##2) LDS_ST1(sB, 3, buf_, b##s_##3) }
;     ...
;   GL_LOAD(0, 0)
;   GL_LOAD(1, 1)
;   LDS_STORE(0, 0)
;   if (VAR != 4) __syncthreads();
; #pragma unroll
;   for (int kt = 0; kt < nk; kt += 2) {
;     if (kt + 2 < nk) { GL_LOAD(0, kt + 2) }
;     MMA_TILE(0)
;     LDS_STORE(1, 1)
;     if (VAR != 4) __syncthreads();
;     if (kt + 3 < nk) { GL_LOAD(1, kt + 3) }
;     MMA_TILE(1)
;     if (kt + 2 < nk) { LDS_STORE(0, 0) }
;     if (VAR != 4) __syncthreads();
	ds_write_b128 v17, v[94:97] offset:32768
	v_mfma_f32_16x16x32_f16 v[24:27], v[74:77], v[110:113], v[24:27]
	ds_read_b128 v[74:77], v22 offset:51200
	v_mfma_f32_16x16x32_f16 v[114:117], v[118:121], v[90:93], v[114:117]
	s_waitcnt vmcnt(2)
	ds_write_b128 v18, v[162:165] offset:32768
	v_mfma_f32_16x16x32_f16 v[40:43], v[118:121], v[110:113], v[40:43]
	ds_read_b128 v[118:121], v22 offset:53248
	v_mfma_f32_16x16x32_f16 v[70:73], v[122:125], v[90:93], v[70:73]
	ds_read_b128 v[90:93], v23 offset:16384
	v_mfma_f32_16x16x32_f16 v[48:51], v[122:125], v[110:113], v[48:51]
	ds_read_b128 v[110:113], v23 offset:18432
	s_waitcnt lgkmcnt(1)
	v_mfma_f32_16x16x32_f16 v[36:39], v[62:65], v[90:93], v[36:39]
	ds_read_b128 v[122:125], v22 offset:55296
	s_waitcnt lgkmcnt(1)
	v_mfma_f32_16x16x32_f16 v[66:69], v[62:65], v[110:113], v[66:69]
	s_waitcnt vmcnt(1)
	ds_write_b128 v19, v[166:169] offset:32768
	v_mfma_f32_16x16x32_f16 v[44:47], v[74:77], v[90:93], v[44:47]
	s_waitcnt vmcnt(0)
	ds_write_b128 v20, v[190:193] offset:32768
	v_mfma_f32_16x16x32_f16 v[78:81], v[74:77], v[110:113], v[78:81]
	v_mfma_f32_16x16x32_f16 v[82:85], v[118:121], v[90:93], v[82:85]
	v_mfma_f32_16x16x32_f16 v[86:89], v[118:121], v[110:113], v[86:89]
	s_waitcnt lgkmcnt(2)
	v_mfma_f32_16x16x32_f16 v[28:31], v[122:125], v[90:93], v[28:31]
	ds_read_b128 v[90:93], v23 offset:20480
	v_mfma_f32_16x16x32_f16 v[32:35], v[122:125], v[110:113], v[32:35]
	ds_read_b128 v[110:113], v23 offset:22528
	s_waitcnt lgkmcnt(1)
	v_mfma_f32_16x16x32_f16 v[98:101], v[62:65], v[90:93], v[98:101]
	s_waitcnt lgkmcnt(0)
	v_mfma_f32_16x16x32_f16 v[52:55], v[62:65], v[110:113], v[52:55]
	global_load_dwordx4 v[62:65], v[0:1], off offset:3712
	v_mfma_f32_16x16x32_f16 v[102:105], v[74:77], v[90:93], v[102:105]
	v_mfma_f32_16x16x32_f16 v[24:27], v[74:77], v[110:113], v[24:27]
	v_mfma_f32_16x16x32_f16 v[114:117], v[118:121], v[90:93], v[114:117]
	v_mfma_f32_16x16x32_f16 v[40:43], v[118:121], v[110:113], v[40:43]
	v_mfma_f32_16x16x32_f16 v[70:73], v[122:125], v[90:93], v[70:73]
	global_load_dwordx4 v[90:93], v[2:3], off offset:3712
	global_load_dwordx4 v[126:129], v[4:5], off offset:3712
	global_load_dwordx4 v[130:133], v[14:15], off offset:3712
	global_load_dwordx4 v[74:77], v[10:11], off offset:3712
	global_load_dwordx4 v[138:141], v[12:13], off offset:3712
	global_load_dwordx4 v[142:145], v[8:9], off offset:3712
	global_load_dwordx4 v[154:157], v[6:7], off offset:3712
	s_waitcnt lgkmcnt(0)
	s_barrier
	v_mfma_f32_16x16x32_f16 v[48:51], v[122:125], v[110:113], v[48:51]
	ds_read_b128 v[58:61], v16 offset:32768
	ds_read_b128 v[106:109], v21
	s_waitcnt lgkmcnt(0)
	v_mfma_f32_16x16x32_f16 v[36:39], v[58:61], v[106:109], v[36:39]
	ds_read_b128 v[94:97], v16 offset:34816
	ds_read_b128 v[110:113], v21 offset:2048
	s_waitcnt lgkmcnt(0)
	v_mfma_f32_16x16x32_f16 v[66:69], v[58:61], v[110:113], v[66:69]
	ds_read_b128 v[118:121], v16 offset:36864
	v_mfma_f32_16x16x32_f16 v[44:47], v[94:97], v[106:109], v[44:47]
	ds_read_b128 v[122:125], v16 offset:38912
	v_mfma_f32_16x16x32_f16 v[78:81], v[94:97], v[110:113], v[78:81]
	s_waitcnt vmcnt(7)
	ds_write_b128 v17, v[62:65] offset:16384
	s_waitcnt lgkmcnt(2)
	v_mfma_f32_16x16x32_f16 v[82:85], v[118:121], v[106:109], v[82:85]
	s_waitcnt vmcnt(6)
	ds_write_b128 v18, v[90:93] offset:16384
	v_mfma_f32_16x16x32_f16 v[86:89], v[118:121], v[110:113], v[86:89]
	s_waitcnt vmcnt(5)
	ds_write_b128 v19, v[126:129] offset:16384
	s_waitcnt lgkmcnt(3)
	v_mfma_f32_16x16x32_f16 v[28:31], v[122:125], v[106:109], v[28:31]
	ds_read_b128 v[106:109], v21 offset:4096
	v_mfma_f32_16x16x32_f16 v[32:35], v[122:125], v[110:113], v[32:35]
	ds_read_b128 v[110:113], v21 offset:6144
	s_waitcnt lgkmcnt(1)
	v_mfma_f32_16x16x32_f16 v[98:101], v[58:61], v[106:109], v[98:101]
	s_waitcnt vmcnt(4)
	ds_write_b128 v20, v[130:133] offset:16384
	s_waitcnt lgkmcnt(1)
	v_mfma_f32_16x16x32_f16 v[52:55], v[58:61], v[110:113], v[52:55]
	ds_read_b128 v[58:61], v22 offset:32768
	v_mfma_f32_16x16x32_f16 v[102:105], v[94:97], v[106:109], v[102:105]
	s_waitcnt vmcnt(3)
	ds_write_b128 v17, v[74:77] offset:49152
	v_mfma_f32_16x16x32_f16 v[24:27], v[94:97], v[110:113], v[24:27]
	ds_read_b128 v[94:97], v22 offset:34816
	v_mfma_f32_16x16x32_f16 v[114:117], v[118:121], v[106:109], v[114:117]
	s_waitcnt vmcnt(2)
	ds_write_b128 v18, v[138:141] offset:49152
	v_mfma_f32_16x16x32_f16 v[40:43], v[118:121], v[110:113], v[40:43]
	ds_read_b128 v[118:121], v22 offset:36864
	v_mfma_f32_16x16x32_f16 v[70:73], v[122:125], v[106:109], v[70:73]
	ds_read_b128 v[106:109], v23
	v_mfma_f32_16x16x32_f16 v[48:51], v[122:125], v[110:113], v[48:51]
	ds_read_b128 v[110:113], v23 offset:2048
	s_waitcnt lgkmcnt(1)
	v_mfma_f32_16x16x32_f16 v[36:39], v[58:61], v[106:109], v[36:39]
	ds_read_b128 v[122:125], v22 offset:38912
	s_waitcnt lgkmcnt(1)
	v_mfma_f32_16x16x32_f16 v[66:69], v[58:61], v[110:113], v[66:69]
	s_waitcnt vmcnt(1)
	ds_write_b128 v19, v[142:145] offset:49152
	v_mfma_f32_16x16x32_f16 v[44:47], v[94:97], v[106:109], v[44:47]
	s_waitcnt vmcnt(0)
	ds_write_b128 v20, v[154:157] offset:49152
	v_mfma_f32_16x16x32_f16 v[78:81], v[94:97], v[110:113], v[78:81]
	v_mfma_f32_16x16x32_f16 v[82:85], v[118:121], v[106:109], v[82:85]
	v_mfma_f32_16x16x32_f16 v[86:89], v[118:121], v[110:113], v[86:89]
	s_waitcnt lgkmcnt(2)
	v_mfma_f32_16x16x32_f16 v[28:31], v[122:125], v[106:109], v[28:31]
	ds_read_b128 v[106:109], v23 offset:4096
	v_mfma_f32_16x16x32_f16 v[32:35], v[122:125], v[110:113], v[32:35]
	ds_read_b128 v[110:113], v23 offset:6144
	s_waitcnt lgkmcnt(1)
	v_mfma_f32_16x16x32_f16 v[98:101], v[58:61], v[106:109], v[98:101]
	s_waitcnt lgkmcnt(0)
	v_mfma_f32_16x16x32_f16 v[52:55], v[58:61], v[110:113], v[52:55]
	global_load_dwordx4 v[58:61], v[0:1], off offset:3840
	v_mfma_f32_16x16x32_f16 v[102:105], v[94:97], v[106:109], v[102:105]
	v_mfma_f32_16x16x32_f16 v[24:27], v[94:97], v[110:113], v[24:27]
	v_mfma_f32_16x16x32_f16 v[114:117], v[118:121], v[106:109], v[114:117]
	v_mfma_f32_16x16x32_f16 v[40:43], v[118:121], v[110:113], v[40:43]
	v_mfma_f32_16x16x32_f16 v[70:73], v[122:125], v[106:109], v[70:73]
	global_load_dwordx4 v[106:109], v[2:3], off offset:3840
	global_load_dwordx4 v[134:137], v[4:5], off offset:3840
	global_load_dwordx4 v[158:161], v[14:15], off offset:3840
	global_load_dwordx4 v[94:97], v[10:11], off offset:3840
	global_load_dwordx4 v[162:165], v[12:13], off offset:3840
	global_load_dwordx4 v[166:169], v[8:9], off offset:3840
	global_load_dwordx4 v[190:193], v[6:7], off offset:3840
	s_waitcnt lgkmcnt(0)
	s_barrier
; #define GL_LOAD(s_, kt_) if (VAR != 1) { a##s_##0 = GL_A(0, kt_); a##s_##1 = GL_A(1, kt_); a##s_##2 = GL_A(2, kt_); a##s_##3 = GL_A(3, kt_); b##s_##0 = GL_B(0, kt_); b##s_##1 = GL_B(1, kt_); b##s_##2 = GL_B(2, kt_); b##s_##3 = GL_B(3, kt_); }
; #define LDS_STORE(s_, buf_) if (VAR != 2) { LDS_ST1(sA, 0, buf_, a##s_##0) LDS_ST1(sA, 1, buf_, a##s_##1) LDS_ST1(sA, 2, buf_, a##s_##2) LDS_ST1(sA, 3, buf_, a##s_##3) LDS_ST1(sB, 0, buf_, b##s_##0) LDS_ST1(sB, 1, buf_, b##s_##1) LDS_ST1(sB, 2, buf_, b##s_##2) LDS_ST1(sB, 3, buf_, b##s_##3) }
;     ...
;   GL_LOAD(0, 0)
;   GL_LOAD(1, 1)
;   LDS_STORE(0, 0)
;   if (VAR != 4) __syncthreads();
; #pragma unroll
;   for (int kt = 0; kt < nk; kt += 2) {
;     if (kt + 2 < nk) { GL_LOAD(0, kt + 2) }
;     MMA_TILE(0)
;     LDS_STORE(1, 1)
;     if (VAR != 4) __syncthreads();
;     if (kt + 3 < nk) { GL_LOAD(1, kt + 3) }
;     MMA_TILE(1)
;     if (kt + 2 < nk) { LDS_STORE(0, 0) }
;     if (VAR != 4) __syncthreads();
	v_mfma_f32_16x16x32_f16 v[48:51], v[122:125], v[110:113], v[48:51]
	ds_read_b128 v[62:65], v16 offset:49152
	ds_read_b128 v[90:93], v21 offset:16384
	s_waitcnt lgkmcnt(0)
	v_mfma_f32_16x16x32_f16 v[36:39], v[62:65], v[90:93], v[36:39]
	ds_read_b128 v[74:77], v16 offset:51200
	ds_read_b128 v[110:113], v21 offset:18432
	s_waitcnt lgkmcnt(0)
	v_mfma_f32_16x16x32_f16 v[66:69], v[62:65], v[110:113], v[66:69]
	ds_read_b128 v[118:121], v16 offset:53248
	v_mfma_f32_16x16x32_f16 v[44:47], v[74:77], v[90:93], v[44:47]
	ds_read_b128 v[122:125], v16 offset:55296
	v_mfma_f32_16x16x32_f16 v[78:81], v[74:77], v[110:113], v[78:81]
	s_waitcnt vmcnt(7)
	ds_write_b128 v17, v[58:61]
	s_waitcnt lgkmcnt(2)
	v_mfma_f32_16x16x32_f16 v[82:85], v[118:121], v[90:93], v[82:85]
	s_waitcnt vmcnt(6)
	ds_write_b128 v18, v[106:109]
	v_mfma_f32_16x16x32_f16 v[86:89], v[118:121], v[110:113], v[86:89]
	s_waitcnt vmcnt(5)
	ds_write_b128 v19, v[134:137]
	s_waitcnt lgkmcnt(3)
	v_mfma_f32_16x16x32_f16 v[28:31], v[122:125], v[90:93], v[28:31]
	ds_read_b128 v[90:93], v21 offset:20480
	v_mfma_f32_16x16x32_f16 v[32:35], v[122:125], v[110:113], v[32:35]
	ds_read_b128 v[110:113], v21 offset:22528
	s_waitcnt lgkmcnt(1)
	v_mfma_f32_16x16x32_f16 v[98:101], v[62:65], v[90:93], v[98:101]
	s_waitcnt vmcnt(4)
	ds_write_b128 v20, v[158:161]
	s_waitcnt lgkmcnt(1)
	v_mfma_f32_16x16x32_f16 v[52:55], v[62:65], v[110:113], v[52:55]
	ds_read_b128 v[62:65], v22 offset:49152
	v_mfma_f32_16x16x32_f16 v[102:105], v[74:77], v[90:93], v[102:105]
	s_waitcnt vmcnt(3)
	ds_write_b128 v17, v[94:97] offset:32768
	v_mfma_f32_16x16x32_f16 v[24:27], v[74:77], v[110:113], v[24:27]
	ds_read_b128 v[74:77], v22 offset:51200
	v_mfma_f32_16x16x32_f16 v[114:117], v[118:121], v[90:93], v[114:117]
	s_waitcnt vmcnt(2)
	ds_write_b128 v18, v[162:165] offset:32768
	v_mfma_f32_16x16x32_f16 v[40:43], v[118:121], v[110:113], v[40:43]
	ds_read_b128 v[118:121], v22 offset:53248
	v_mfma_f32_16x16x32_f16 v[70:73], v[122:125], v[90:93], v[70:73]
	ds_read_b128 v[90:93], v23 offset:16384
	v_mfma_f32_16x16x32_f16 v[48:51], v[122:125], v[110:113], v[48:51]
	ds_read_b128 v[110:113], v23 offset:18432
	s_waitcnt lgkmcnt(1)
	v_mfma_f32_16x16x32_f16 v[36:39], v[62:65], v[90:93], v[36:39]
	ds_read_b128 v[122:125], v22 offset:55296
	s_waitcnt lgkmcnt(1)
	v_mfma_f32_16x16x32_f16 v[66:69], v[62:65], v[110:113], v[66:69]
	s_waitcnt vmcnt(1)
	ds_write_b128 v19, v[166:169] offset:32768
	v_mfma_f32_16x16x32_f16 v[44:47], v[74:77], v[90:93], v[44:47]
	s_waitcnt vmcnt(0)
	ds_write_b128 v20, v[190:193] offset:32768
	v_mfma_f32_16x16x32_f16 v[78:81], v[74:77], v[110:113], v[78:81]
	v_mfma_f32_16x16x32_f16 v[82:85], v[118:121], v[90:93], v[82:85]
	v_mfma_f32_16x16x32_f16 v[86:89], v[118:121], v[110:113], v[86:89]
	s_waitcnt lgkmcnt(2)
	v_mfma_f32_16x16x32_f16 v[28:31], v[122:125], v[90:93], v[28:31]
	ds_read_b128 v[90:93], v23 offset:20480
	v_mfma_f32_16x16x32_f16 v[32:35], v[122:125], v[110:113], v[32:35]
	ds_read_b128 v[110:113], v23 offset:22528
	s_waitcnt lgkmcnt(1)
	v_mfma_f32_16x16x32_f16 v[98:101], v[62:65], v[90:93], v[98:101]
	s_waitcnt lgkmcnt(0)
	v_mfma_f32_16x16x32_f16 v[52:55], v[62:65], v[110:113], v[52:55]
	global_load_dwordx4 v[62:65], v[0:1], off offset:3968
	v_add_co_u32_e32 v0, vcc, s1, v0
	v_mfma_f32_16x16x32_f16 v[102:105], v[74:77], v[90:93], v[102:105]
	v_mfma_f32_16x16x32_f16 v[24:27], v[74:77], v[110:113], v[24:27]
	v_mfma_f32_16x16x32_f16 v[114:117], v[118:121], v[90:93], v[114:117]
	v_mfma_f32_16x16x32_f16 v[40:43], v[118:121], v[110:113], v[40:43]
	v_mfma_f32_16x16x32_f16 v[70:73], v[122:125], v[90:93], v[70:73]
	global_load_dwordx4 v[90:93], v[2:3], off offset:3968
	global_load_dwordx4 v[126:129], v[4:5], off offset:3968
	global_load_dwordx4 v[130:133], v[14:15], off offset:3968
	global_load_dwordx4 v[74:77], v[10:11], off offset:3968
	global_load_dwordx4 v[138:141], v[12:13], off offset:3968
	global_load_dwordx4 v[142:145], v[8:9], off offset:3968
	global_load_dwordx4 v[154:157], v[6:7], off offset:3968
	s_waitcnt lgkmcnt(0)
	s_barrier
	v_mfma_f32_16x16x32_f16 v[48:51], v[122:125], v[110:113], v[48:51]
	ds_read_b128 v[58:61], v16 offset:32768
	ds_read_b128 v[106:109], v21
	s_waitcnt lgkmcnt(0)
	v_mfma_f32_16x16x32_f16 v[36:39], v[58:61], v[106:109], v[36:39]
	ds_read_b128 v[94:97], v16 offset:34816
	ds_read_b128 v[110:113], v21 offset:2048
	s_waitcnt lgkmcnt(0)
	v_mfma_f32_16x16x32_f16 v[66:69], v[58:61], v[110:113], v[66:69]
	ds_read_b128 v[118:121], v16 offset:36864
	v_mfma_f32_16x16x32_f16 v[44:47], v[94:97], v[106:109], v[44:47]
	ds_read_b128 v[122:125], v16 offset:38912
	v_mfma_f32_16x16x32_f16 v[78:81], v[94:97], v[110:113], v[78:81]
	ds_read_b128 v[158:161], v23 offset:6144
	s_waitcnt lgkmcnt(2)
	v_mfma_f32_16x16x32_f16 v[82:85], v[118:121], v[106:109], v[82:85]
	v_addc_co_u32_e32 v1, vcc, 0, v1, vcc
	v_mfma_f32_16x16x32_f16 v[86:89], v[118:121], v[110:113], v[86:89]
	v_add_co_u32_e32 v2, vcc, s1, v2
	s_waitcnt lgkmcnt(1)
	v_mfma_f32_16x16x32_f16 v[28:31], v[122:125], v[106:109], v[28:31]
	ds_read_b128 v[106:109], v21 offset:4096
	v_mfma_f32_16x16x32_f16 v[32:35], v[122:125], v[110:113], v[32:35]
	ds_read_b128 v[110:113], v21 offset:6144
	s_waitcnt lgkmcnt(1)
	v_mfma_f32_16x16x32_f16 v[98:101], v[58:61], v[106:109], v[98:101]
	v_addc_co_u32_e32 v3, vcc, 0, v3, vcc
	s_waitcnt lgkmcnt(0)
; #define GL_LOAD(s_, kt_) if (VAR != 1) { a##s_##0 = GL_A(0, kt_); a##s_##1 = GL_A(1, kt_); a##s_##2 = GL_A(2, kt_); a##s_##3 = GL_A(3, kt_); b##s_##0 = GL_B(0, kt_); b##s_##1 = GL_B(1, kt_); b##s_##2 = GL_B(2, kt_); b##s_##3 = GL_B(3, kt_); }
; #define LDS_STORE(s_, buf_) if (VAR != 2) { LDS_ST1(sA, 0, buf_, a##s_##0) LDS_ST1(sA, 1, buf_, a##s_##1) LDS_ST1(sA, 2, buf_, a##s_##2) LDS_ST1(sA, 3, buf_, a##s_##3) LDS_ST1(sB, 0, buf_, b##s_##0) LDS_ST1(sB, 1, buf_, b##s_##1) LDS_ST1(sB, 2, buf_, b##s_##2) LDS_ST1(sB, 3, buf_, b##s_##3) }
;     ...
;   GL_LOAD(0, 0)
;   GL_LOAD(1, 1)
;   LDS_STORE(0, 0)
;   if (VAR != 4) __syncthreads();
; #pragma unroll
;   for (int kt = 0; kt < nk; kt += 2) {
;     if (kt + 2 < nk) { GL_LOAD(0, kt + 2) }
;     MMA_TILE(0)
;     LDS_STORE(1, 1)
;     if (VAR != 4) __syncthreads();
;     if (kt + 3 < nk) { GL_LOAD(1, kt + 3) }
;     MMA_TILE(1)
;     if (kt + 2 < nk) { LDS_STORE(0, 0) }
;     if (VAR != 4) __syncthreads();
	v_mfma_f32_16x16x32_f16 v[52:55], v[58:61], v[110:113], v[52:55]
	ds_read_b128 v[58:61], v22 offset:32768
	v_mfma_f32_16x16x32_f16 v[102:105], v[94:97], v[106:109], v[102:105]
	v_add_co_u32_e32 v4, vcc, s1, v4
	v_mfma_f32_16x16x32_f16 v[24:27], v[94:97], v[110:113], v[24:27]
	ds_read_b128 v[94:97], v22 offset:34816
	v_addc_co_u32_e32 v5, vcc, 0, v5, vcc
	v_mfma_f32_16x16x32_f16 v[114:117], v[118:121], v[106:109], v[114:117]
	v_add_co_u32_e32 v14, vcc, s1, v14
	v_addc_co_u32_e32 v15, vcc, 0, v15, vcc
	v_mfma_f32_16x16x32_f16 v[40:43], v[118:121], v[110:113], v[40:43]
	ds_read_b128 v[118:121], v22 offset:36864
	v_add_co_u32_e32 v10, vcc, s1, v10
	v_mfma_f32_16x16x32_f16 v[70:73], v[122:125], v[106:109], v[70:73]
	ds_read_b128 v[106:109], v23
	v_addc_co_u32_e32 v11, vcc, 0, v11, vcc
	v_mfma_f32_16x16x32_f16 v[48:51], v[122:125], v[110:113], v[48:51]
	ds_read_b128 v[110:113], v23 offset:2048
	ds_read_b128 v[122:125], v22 offset:38912
	s_waitcnt lgkmcnt(2)
	v_mfma_f32_16x16x32_f16 v[36:39], v[58:61], v[106:109], v[36:39]
	v_add_co_u32_e32 v12, vcc, s1, v12
	v_addc_co_u32_e32 v13, vcc, 0, v13, vcc
	s_waitcnt lgkmcnt(1)
	v_mfma_f32_16x16x32_f16 v[66:69], v[58:61], v[110:113], v[66:69]
	v_add_co_u32_e32 v8, vcc, s1, v8
	v_addc_co_u32_e32 v9, vcc, 0, v9, vcc
	v_mfma_f32_16x16x32_f16 v[44:47], v[94:97], v[106:109], v[44:47]
	v_add_co_u32_e32 v6, vcc, s1, v6
	v_addc_co_u32_e32 v7, vcc, 0, v7, vcc
	v_mfma_f32_16x16x32_f16 v[78:81], v[94:97], v[110:113], v[78:81]
	s_waitcnt vmcnt(7)
	ds_write_b128 v17, v[62:65] offset:16384
	s_waitcnt vmcnt(6)
	ds_write_b128 v18, v[90:93] offset:16384
	v_mfma_f32_16x16x32_f16 v[52:55], v[58:61], v[158:161], v[52:55]
	s_waitcnt vmcnt(5)
	ds_write_b128 v19, v[126:129] offset:16384
	s_waitcnt vmcnt(4)
	ds_write_b128 v20, v[130:133] offset:16384
	v_mfma_f32_16x16x32_f16 v[24:27], v[94:97], v[158:161], v[24:27]
	s_waitcnt vmcnt(3)
	ds_write_b128 v17, v[74:77] offset:49152
	s_waitcnt vmcnt(2)
	ds_write_b128 v18, v[138:141] offset:49152
	v_mfma_f32_16x16x32_f16 v[82:85], v[118:121], v[106:109], v[82:85]
	s_waitcnt vmcnt(1)
	ds_write_b128 v19, v[142:145] offset:49152
	s_waitcnt vmcnt(0)
	ds_write_b128 v20, v[154:157] offset:49152
	v_mfma_f32_16x16x32_f16 v[86:89], v[118:121], v[110:113], v[86:89]
	s_waitcnt lgkmcnt(8)
	v_mfma_f32_16x16x32_f16 v[28:31], v[122:125], v[106:109], v[28:31]
	ds_read_b128 v[106:109], v23 offset:4096
	v_mfma_f32_16x16x32_f16 v[32:35], v[122:125], v[110:113], v[32:35]
	global_load_dwordx4 v[110:113], v[0:1], off
	global_load_dwordx4 v[134:137], v[2:3], off
	v_mfma_f32_16x16x32_f16 v[40:43], v[118:121], v[158:161], v[40:43]
	global_load_dwordx4 v[162:165], v[4:5], off
	s_waitcnt lgkmcnt(0)
	v_mfma_f32_16x16x32_f16 v[98:101], v[58:61], v[106:109], v[98:101]
	global_load_dwordx4 v[166:169], v[14:15], off
	v_mfma_f32_16x16x32_f16 v[102:105], v[94:97], v[106:109], v[102:105]
	v_mfma_f32_16x16x32_f16 v[114:117], v[118:121], v[106:109], v[114:117]
	v_mfma_f32_16x16x32_f16 v[70:73], v[122:125], v[106:109], v[70:73]
	global_load_dwordx4 v[106:109], v[10:11], off
	global_load_dwordx4 v[190:193], v[12:13], off
	global_load_dwordx4 v[58:61], v[8:9], off
	global_load_dwordx4 v[94:97], v[6:7], off
	s_waitcnt lgkmcnt(0)
	s_barrier
	v_mfma_f32_16x16x32_f16 v[48:51], v[122:125], v[158:161], v[48:51]
	ds_read_b128 v[62:65], v16 offset:49152
	ds_read_b128 v[90:93], v21 offset:16384
	s_waitcnt lgkmcnt(0)
	v_mfma_f32_16x16x32_f16 v[36:39], v[62:65], v[90:93], v[36:39]
	ds_read_b128 v[74:77], v16 offset:51200
	ds_read_b128 v[118:121], v21 offset:18432
	s_waitcnt lgkmcnt(0)
	v_mfma_f32_16x16x32_f16 v[66:69], v[62:65], v[118:121], v[66:69]
	ds_read_b128 v[122:125], v16 offset:53248
	v_mfma_f32_16x16x32_f16 v[44:47], v[74:77], v[90:93], v[44:47]
	ds_read_b128 v[126:129], v16 offset:55296
	v_mfma_f32_16x16x32_f16 v[78:81], v[74:77], v[118:121], v[78:81]
	s_waitcnt vmcnt(7)
	ds_write_b128 v17, v[110:113]
	s_waitcnt lgkmcnt(2)
	v_mfma_f32_16x16x32_f16 v[82:85], v[122:125], v[90:93], v[82:85]
	s_waitcnt vmcnt(6)
	ds_write_b128 v18, v[134:137]
	v_mfma_f32_16x16x32_f16 v[86:89], v[122:125], v[118:121], v[86:89]
	s_waitcnt vmcnt(5)
	ds_write_b128 v19, v[162:165]
	s_waitcnt lgkmcnt(3)
	v_mfma_f32_16x16x32_f16 v[28:31], v[126:129], v[90:93], v[28:31]
	ds_read_b128 v[90:93], v21 offset:20480
	v_mfma_f32_16x16x32_f16 v[32:35], v[126:129], v[118:121], v[32:35]
	ds_read_b128 v[118:121], v21 offset:22528
	s_waitcnt lgkmcnt(1)
	v_mfma_f32_16x16x32_f16 v[98:101], v[62:65], v[90:93], v[98:101]
	s_waitcnt vmcnt(4)
	ds_write_b128 v20, v[166:169]
	s_waitcnt lgkmcnt(1)
	v_mfma_f32_16x16x32_f16 v[52:55], v[62:65], v[118:121], v[52:55]
	ds_read_b128 v[62:65], v22 offset:49152
	v_mfma_f32_16x16x32_f16 v[102:105], v[74:77], v[90:93], v[102:105]
	s_waitcnt vmcnt(3)
	ds_write_b128 v17, v[106:109] offset:32768
	v_mfma_f32_16x16x32_f16 v[24:27], v[74:77], v[118:121], v[24:27]
	ds_read_b128 v[74:77], v22 offset:51200
	v_mfma_f32_16x16x32_f16 v[114:117], v[122:125], v[90:93], v[114:117]
	s_waitcnt vmcnt(2)
	ds_write_b128 v18, v[190:193] offset:32768
	v_mfma_f32_16x16x32_f16 v[40:43], v[122:125], v[118:121], v[40:43]
	ds_read_b128 v[122:125], v22 offset:53248
	v_mfma_f32_16x16x32_f16 v[70:73], v[126:129], v[90:93], v[70:73]
	ds_read_b128 v[90:93], v23 offset:16384
	v_mfma_f32_16x16x32_f16 v[48:51], v[126:129], v[118:121], v[48:51]
	ds_read_b128 v[118:121], v23 offset:18432
	s_waitcnt lgkmcnt(1)
	v_mfma_f32_16x16x32_f16 v[36:39], v[62:65], v[90:93], v[36:39]
	ds_read_b128 v[126:129], v22 offset:55296
	s_waitcnt lgkmcnt(1)
	v_mfma_f32_16x16x32_f16 v[66:69], v[62:65], v[118:121], v[66:69]
	s_waitcnt vmcnt(1)
; #define GL_LOAD(s_, kt_) if (VAR != 1) { a##s_##0 = GL_A(0, kt_); a##s_##1 = GL_A(1, kt_); a##s_##2 = GL_A(2, kt_); a##s_##3 = GL_A(3, kt_); b##s_##0 = GL_B(0, kt_); b##s_##1 = GL_B(1, kt_); b##s_##2 = GL_B(2, kt_); b##s_##3 = GL_B(3, kt_); }
; #define LDS_STORE(s_, buf_) if (VAR != 2) { LDS_ST1(sA, 0, buf_, a##s_##0) LDS_ST1(sA, 1, buf_, a##s_##1) LDS_ST1(sA, 2, buf_, a##s_##2) LDS_ST1(sA, 3, buf_, a##s_##3) LDS_ST1(sB, 0, buf_, b##s_##0) LDS_ST1(sB, 1, buf_, b##s_##1) LDS_ST1(sB, 2, buf_, b##s_##2) LDS_ST1(sB, 3, buf_, b##s_##3) }
;     ...
;   GL_LOAD(0, 0)
;   GL_LOAD(1, 1)
;   LDS_STORE(0, 0)
;   if (VAR != 4) __syncthreads();
; #pragma unroll
;   for (int kt = 0; kt < nk; kt += 2) {
;     if (kt + 2 < nk) { GL_LOAD(0, kt + 2) }
;     MMA_TILE(0)
;     LDS_STORE(1, 1)
;     if (VAR != 4) __syncthreads();
;     if (kt + 3 < nk) { GL_LOAD(1, kt + 3) }
;     MMA_TILE(1)
;     if (kt + 2 < nk) { LDS_STORE(0, 0) }
;     if (VAR != 4) __syncthreads();
	ds_write_b128 v19, v[58:61] offset:32768
	v_mfma_f32_16x16x32_f16 v[44:47], v[74:77], v[90:93], v[44:47]
	s_waitcnt vmcnt(0)
	ds_write_b128 v20, v[94:97] offset:32768
	v_mfma_f32_16x16x32_f16 v[78:81], v[74:77], v[118:121], v[78:81]
	v_mfma_f32_16x16x32_f16 v[82:85], v[122:125], v[90:93], v[82:85]
	v_mfma_f32_16x16x32_f16 v[86:89], v[122:125], v[118:121], v[86:89]
	s_waitcnt lgkmcnt(2)
	v_mfma_f32_16x16x32_f16 v[28:31], v[126:129], v[90:93], v[28:31]
	ds_read_b128 v[90:93], v23 offset:20480
	v_mfma_f32_16x16x32_f16 v[32:35], v[126:129], v[118:121], v[32:35]
	ds_read_b128 v[118:121], v23 offset:22528
	s_waitcnt lgkmcnt(1)
	v_mfma_f32_16x16x32_f16 v[98:101], v[62:65], v[90:93], v[98:101]
	s_waitcnt lgkmcnt(0)
	v_mfma_f32_16x16x32_f16 v[52:55], v[62:65], v[118:121], v[52:55]
	global_load_dwordx4 v[62:65], v[0:1], off offset:128
	v_mfma_f32_16x16x32_f16 v[102:105], v[74:77], v[90:93], v[102:105]
	v_mfma_f32_16x16x32_f16 v[24:27], v[74:77], v[118:121], v[24:27]
	v_mfma_f32_16x16x32_f16 v[114:117], v[122:125], v[90:93], v[114:117]
	v_mfma_f32_16x16x32_f16 v[40:43], v[122:125], v[118:121], v[40:43]
	v_mfma_f32_16x16x32_f16 v[70:73], v[126:129], v[90:93], v[70:73]
	global_load_dwordx4 v[90:93], v[2:3], off offset:128
	global_load_dwordx4 v[130:133], v[4:5], off offset:128
	global_load_dwordx4 v[138:141], v[14:15], off offset:128
	global_load_dwordx4 v[74:77], v[10:11], off offset:128
	global_load_dwordx4 v[142:145], v[12:13], off offset:128
	global_load_dwordx4 v[154:157], v[8:9], off offset:128
	global_load_dwordx4 v[158:161], v[6:7], off offset:128
	s_waitcnt lgkmcnt(0)
	s_barrier
	v_mfma_f32_16x16x32_f16 v[48:51], v[126:129], v[118:121], v[48:51]
	ds_read_b128 v[58:61], v16 offset:32768
	ds_read_b128 v[106:109], v21
	s_waitcnt lgkmcnt(0)
	v_mfma_f32_16x16x32_f16 v[36:39], v[58:61], v[106:109], v[36:39]
	ds_read_b128 v[94:97], v16 offset:34816
	ds_read_b128 v[110:113], v21 offset:2048
	s_waitcnt lgkmcnt(0)
	v_mfma_f32_16x16x32_f16 v[66:69], v[58:61], v[110:113], v[66:69]
	ds_read_b128 v[118:121], v16 offset:36864
	v_mfma_f32_16x16x32_f16 v[44:47], v[94:97], v[106:109], v[44:47]
	ds_read_b128 v[122:125], v16 offset:38912
	v_mfma_f32_16x16x32_f16 v[78:81], v[94:97], v[110:113], v[78:81]
	s_waitcnt vmcnt(7)
	ds_write_b128 v17, v[62:65] offset:16384
	s_waitcnt lgkmcnt(2)
	v_mfma_f32_16x16x32_f16 v[82:85], v[118:121], v[106:109], v[82:85]
	s_waitcnt vmcnt(6)
	ds_write_b128 v18, v[90:93] offset:16384
	v_mfma_f32_16x16x32_f16 v[86:89], v[118:121], v[110:113], v[86:89]
	s_waitcnt vmcnt(5)
	ds_write_b128 v19, v[130:133] offset:16384
	s_waitcnt lgkmcnt(3)
	v_mfma_f32_16x16x32_f16 v[28:31], v[122:125], v[106:109], v[28:31]
	ds_read_b128 v[106:109], v21 offset:4096
	v_mfma_f32_16x16x32_f16 v[32:35], v[122:125], v[110:113], v[32:35]
	ds_read_b128 v[110:113], v21 offset:6144
	s_waitcnt lgkmcnt(1)
	v_mfma_f32_16x16x32_f16 v[98:101], v[58:61], v[106:109], v[98:101]
	s_waitcnt vmcnt(4)
	ds_write_b128 v20, v[138:141] offset:16384
	s_waitcnt lgkmcnt(1)
	v_mfma_f32_16x16x32_f16 v[52:55], v[58:61], v[110:113], v[52:55]
	ds_read_b128 v[58:61], v22 offset:32768
	v_mfma_f32_16x16x32_f16 v[102:105], v[94:97], v[106:109], v[102:105]
	s_waitcnt vmcnt(3)
	ds_write_b128 v17, v[74:77] offset:49152
	v_mfma_f32_16x16x32_f16 v[24:27], v[94:97], v[110:113], v[24:27]
	ds_read_b128 v[94:97], v22 offset:34816
	v_mfma_f32_16x16x32_f16 v[114:117], v[118:121], v[106:109], v[114:117]
	s_waitcnt vmcnt(2)
	ds_write_b128 v18, v[142:145] offset:49152
	v_mfma_f32_16x16x32_f16 v[40:43], v[118:121], v[110:113], v[40:43]
	ds_read_b128 v[118:121], v22 offset:36864
	v_mfma_f32_16x16x32_f16 v[70:73], v[122:125], v[106:109], v[70:73]
	ds_read_b128 v[106:109], v23
	v_mfma_f32_16x16x32_f16 v[48:51], v[122:125], v[110:113], v[48:51]
	ds_read_b128 v[110:113], v23 offset:2048
	s_waitcnt lgkmcnt(1)
	v_mfma_f32_16x16x32_f16 v[36:39], v[58:61], v[106:109], v[36:39]
	ds_read_b128 v[122:125], v22 offset:38912
	s_waitcnt lgkmcnt(1)
	v_mfma_f32_16x16x32_f16 v[66:69], v[58:61], v[110:113], v[66:69]
	s_waitcnt vmcnt(1)
	ds_write_b128 v19, v[154:157] offset:49152
	v_mfma_f32_16x16x32_f16 v[44:47], v[94:97], v[106:109], v[44:47]
	s_waitcnt vmcnt(0)
	ds_write_b128 v20, v[158:161] offset:49152
	v_mfma_f32_16x16x32_f16 v[78:81], v[94:97], v[110:113], v[78:81]
	v_mfma_f32_16x16x32_f16 v[82:85], v[118:121], v[106:109], v[82:85]
	v_mfma_f32_16x16x32_f16 v[86:89], v[118:121], v[110:113], v[86:89]
	s_waitcnt lgkmcnt(2)
	v_mfma_f32_16x16x32_f16 v[28:31], v[122:125], v[106:109], v[28:31]
	ds_read_b128 v[106:109], v23 offset:4096
	v_mfma_f32_16x16x32_f16 v[32:35], v[122:125], v[110:113], v[32:35]
	ds_read_b128 v[110:113], v23 offset:6144
	s_waitcnt lgkmcnt(1)
	v_mfma_f32_16x16x32_f16 v[98:101], v[58:61], v[106:109], v[98:101]
	s_waitcnt lgkmcnt(0)
	v_mfma_f32_16x16x32_f16 v[52:55], v[58:61], v[110:113], v[52:55]
	global_load_dwordx4 v[58:61], v[0:1], off offset:256
	v_mfma_f32_16x16x32_f16 v[102:105], v[94:97], v[106:109], v[102:105]
	v_mfma_f32_16x16x32_f16 v[24:27], v[94:97], v[110:113], v[24:27]
	v_mfma_f32_16x16x32_f16 v[114:117], v[118:121], v[106:109], v[114:117]
	v_mfma_f32_16x16x32_f16 v[40:43], v[118:121], v[110:113], v[40:43]
	v_mfma_f32_16x16x32_f16 v[70:73], v[122:125], v[106:109], v[70:73]
	global_load_dwordx4 v[106:109], v[2:3], off offset:256
	global_load_dwordx4 v[126:129], v[4:5], off offset:256
	global_load_dwordx4 v[134:137], v[14:15], off offset:256
	global_load_dwordx4 v[94:97], v[10:11], off offset:256
	global_load_dwordx4 v[162:165], v[12:13], off offset:256
	global_load_dwordx4 v[166:169], v[8:9], off offset:256
	global_load_dwordx4 v[190:193], v[6:7], off offset:256
	s_waitcnt lgkmcnt(0)
	s_barrier
; #define GL_LOAD(s_, kt_) if (VAR != 1) { a##s_##0 = GL_A(0, kt_); a##s_##1 = GL_A(1, kt_); a##s_##2 = GL_A(2, kt_); a##s_##3 = GL_A(3, kt_); b##s_##0 = GL_B(0, kt_); b##s_##1 = GL_B(1, kt_); b##s_##2 = GL_B(2, kt_); b##s_##3 = GL_B(3, kt_); }
; #define LDS_STORE(s_, buf_) if (VAR != 2) { LDS_ST1(sA, 0, buf_, a##s_##0) LDS_ST1(sA, 1, buf_, a##s_##1) LDS_ST1(sA, 2, buf_, a##s_##2) LDS_ST1(sA, 3, buf_, a##s_##3) LDS_ST1(sB, 0, buf_, b##s_##0) LDS_ST1(sB, 1, buf_, b##s_##1) LDS_ST1(sB, 2, buf_, b##s_##2) LDS_ST1(sB, 3, buf_, b##s_##3) }
;     ...
;   GL_LOAD(0, 0)
;   GL_LOAD(1, 1)
;   LDS_STORE(0, 0)
;   if (VAR != 4) __syncthreads();
; #pragma unroll
;   for (int kt = 0; kt < nk; kt += 2) {
;     if (kt + 2 < nk) { GL_LOAD(0, kt + 2) }
;     MMA_TILE(0)
;     LDS_STORE(1, 1)
;     if (VAR != 4) __syncthreads();
;     if (kt + 3 < nk) { GL_LOAD(1, kt + 3) }
;     MMA_TILE(1)
;     if (kt + 2 < nk) { LDS_STORE(0, 0) }
;     if (VAR != 4) __syncthreads();
	v_mfma_f32_16x16x32_f16 v[48:51], v[122:125], v[110:113], v[48:51]
	ds_read_b128 v[62:65], v16 offset:49152
	ds_read_b128 v[90:93], v21 offset:16384
	s_waitcnt lgkmcnt(0)
	v_mfma_f32_16x16x32_f16 v[36:39], v[62:65], v[90:93], v[36:39]
	ds_read_b128 v[74:77], v16 offset:51200
	ds_read_b128 v[110:113], v21 offset:18432
	s_waitcnt lgkmcnt(0)
	v_mfma_f32_16x16x32_f16 v[66:69], v[62:65], v[110:113], v[66:69]
	ds_read_b128 v[118:121], v16 offset:53248
	v_mfma_f32_16x16x32_f16 v[44:47], v[74:77], v[90:93], v[44:47]
	ds_read_b128 v[122:125], v16 offset:55296
	v_mfma_f32_16x16x32_f16 v[78:81], v[74:77], v[110:113], v[78:81]
	s_waitcnt vmcnt(7)
	ds_write_b128 v17, v[58:61]
	s_waitcnt lgkmcnt(2)
	v_mfma_f32_16x16x32_f16 v[82:85], v[118:121], v[90:93], v[82:85]
	s_waitcnt vmcnt(6)
	ds_write_b128 v18, v[106:109]
	v_mfma_f32_16x16x32_f16 v[86:89], v[118:121], v[110:113], v[86:89]
	s_waitcnt vmcnt(5)
	ds_write_b128 v19, v[126:129]
	s_waitcnt lgkmcnt(3)
	v_mfma_f32_16x16x32_f16 v[28:31], v[122:125], v[90:93], v[28:31]
	ds_read_b128 v[90:93], v21 offset:20480
	v_mfma_f32_16x16x32_f16 v[32:35], v[122:125], v[110:113], v[32:35]
	ds_read_b128 v[110:113], v21 offset:22528
	s_waitcnt lgkmcnt(1)
	v_mfma_f32_16x16x32_f16 v[98:101], v[62:65], v[90:93], v[98:101]
	s_waitcnt vmcnt(4)
	ds_write_b128 v20, v[134:137]
	s_waitcnt lgkmcnt(1)
	v_mfma_f32_16x16x32_f16 v[52:55], v[62:65], v[110:113], v[52:55]
	ds_read_b128 v[62:65], v22 offset:49152
	v_mfma_f32_16x16x32_f16 v[102:105], v[74:77], v[90:93], v[102:105]
	s_waitcnt vmcnt(3)
	ds_write_b128 v17, v[94:97] offset:32768
	v_mfma_f32_16x16x32_f16 v[24:27], v[74:77], v[110:113], v[24:27]
	ds_read_b128 v[74:77], v22 offset:51200
	v_mfma_f32_16x16x32_f16 v[114:117], v[118:121], v[90:93], v[114:117]
	s_waitcnt vmcnt(2)
	ds_write_b128 v18, v[162:165] offset:32768
	v_mfma_f32_16x16x32_f16 v[40:43], v[118:121], v[110:113], v[40:43]
	ds_read_b128 v[118:121], v22 offset:53248
	v_mfma_f32_16x16x32_f16 v[70:73], v[122:125], v[90:93], v[70:73]
	ds_read_b128 v[90:93], v23 offset:16384
	v_mfma_f32_16x16x32_f16 v[48:51], v[122:125], v[110:113], v[48:51]
	ds_read_b128 v[110:113], v23 offset:18432
	s_waitcnt lgkmcnt(1)
	v_mfma_f32_16x16x32_f16 v[36:39], v[62:65], v[90:93], v[36:39]
	ds_read_b128 v[122:125], v22 offset:55296
	s_waitcnt lgkmcnt(1)
	v_mfma_f32_16x16x32_f16 v[66:69], v[62:65], v[110:113], v[66:69]
	s_waitcnt vmcnt(1)
	ds_write_b128 v19, v[166:169] offset:32768
	v_mfma_f32_16x16x32_f16 v[44:47], v[74:77], v[90:93], v[44:47]
	s_waitcnt vmcnt(0)
	ds_write_b128 v20, v[190:193] offset:32768
	v_mfma_f32_16x16x32_f16 v[78:81], v[74:77], v[110:113], v[78:81]
	v_mfma_f32_16x16x32_f16 v[82:85], v[118:121], v[90:93], v[82:85]
	v_mfma_f32_16x16x32_f16 v[86:89], v[118:121], v[110:113], v[86:89]
	s_waitcnt lgkmcnt(2)
	v_mfma_f32_16x16x32_f16 v[28:31], v[122:125], v[90:93], v[28:31]
	ds_read_b128 v[90:93], v23 offset:20480
	v_mfma_f32_16x16x32_f16 v[32:35], v[122:125], v[110:113], v[32:35]
	ds_read_b128 v[110:113], v23 offset:22528
	s_waitcnt lgkmcnt(1)
	v_mfma_f32_16x16x32_f16 v[98:101], v[62:65], v[90:93], v[98:101]
	s_waitcnt lgkmcnt(0)
	v_mfma_f32_16x16x32_f16 v[52:55], v[62:65], v[110:113], v[52:55]
	global_load_dwordx4 v[62:65], v[0:1], off offset:384
	v_mfma_f32_16x16x32_f16 v[102:105], v[74:77], v[90:93], v[102:105]
	v_mfma_f32_16x16x32_f16 v[24:27], v[74:77], v[110:113], v[24:27]
	v_mfma_f32_16x16x32_f16 v[114:117], v[118:121], v[90:93], v[114:117]
	v_mfma_f32_16x16x32_f16 v[40:43], v[118:121], v[110:113], v[40:43]
	v_mfma_f32_16x16x32_f16 v[70:73], v[122:125], v[90:93], v[70:73]
	global_load_dwordx4 v[90:93], v[2:3], off offset:384
	global_load_dwordx4 v[130:133], v[4:5], off offset:384
	global_load_dwordx4 v[138:141], v[14:15], off offset:384
	global_load_dwordx4 v[74:77], v[10:11], off offset:384
	global_load_dwordx4 v[142:145], v[12:13], off offset:384
	global_load_dwordx4 v[154:157], v[8:9], off offset:384
	global_load_dwordx4 v[158:161], v[6:7], off offset:384
	s_waitcnt lgkmcnt(0)
	s_barrier
	v_mfma_f32_16x16x32_f16 v[48:51], v[122:125], v[110:113], v[48:51]
	ds_read_b128 v[58:61], v16 offset:32768
	ds_read_b128 v[106:109], v21
	s_waitcnt lgkmcnt(0)
	v_mfma_f32_16x16x32_f16 v[36:39], v[58:61], v[106:109], v[36:39]
	ds_read_b128 v[94:97], v16 offset:34816
	ds_read_b128 v[110:113], v21 offset:2048
	s_waitcnt lgkmcnt(0)
	v_mfma_f32_16x16x32_f16 v[66:69], v[58:61], v[110:113], v[66:69]
	ds_read_b128 v[118:121], v16 offset:36864
	v_mfma_f32_16x16x32_f16 v[44:47], v[94:97], v[106:109], v[44:47]
	ds_read_b128 v[122:125], v16 offset:38912
	v_mfma_f32_16x16x32_f16 v[78:81], v[94:97], v[110:113], v[78:81]
	s_waitcnt vmcnt(7)
	ds_write_b128 v17, v[62:65] offset:16384
	s_waitcnt lgkmcnt(2)
	v_mfma_f32_16x16x32_f16 v[82:85], v[118:121], v[106:109], v[82:85]
	s_waitcnt vmcnt(6)
	ds_write_b128 v18, v[90:93] offset:16384
	v_mfma_f32_16x16x32_f16 v[86:89], v[118:121], v[110:113], v[86:89]
	s_waitcnt vmcnt(5)
	ds_write_b128 v19, v[130:133] offset:16384
	s_waitcnt lgkmcnt(3)
	v_mfma_f32_16x16x32_f16 v[28:31], v[122:125], v[106:109], v[28:31]
	ds_read_b128 v[106:109], v21 offset:4096
	v_mfma_f32_16x16x32_f16 v[32:35], v[122:125], v[110:113], v[32:35]
	ds_read_b128 v[110:113], v21 offset:6144
	s_waitcnt lgkmcnt(1)
	v_mfma_f32_16x16x32_f16 v[98:101], v[58:61], v[106:109], v[98:101]
	s_waitcnt vmcnt(4)
	ds_write_b128 v20, v[138:141] offset:16384
	s_waitcnt lgkmcnt(1)
	v_mfma_f32_16x16x32_f16 v[52:55], v[58:61], v[110:113], v[52:55]
	ds_read_b128 v[58:61], v22 offset:32768
	v_mfma_f32_16x16x32_f16 v[102:105], v[94:97], v[106:109], v[102:105]
	s_waitcnt vmcnt(3)
; #define GL_LOAD(s_, kt_) if (VAR != 1) { a##s_##0 = GL_A(0, kt_); a##s_##1 = GL_A(1, kt_); a##s_##2 = GL_A(2, kt_); a##s_##3 = GL_A(3, kt_); b##s_##0 = GL_B(0, kt_); b##s_##1 = GL_B(1, kt_); b##s_##2 = GL_B(2, kt_); b##s_##3 = GL_B(3, kt_); }
; #define LDS_STORE(s_, buf_) if (VAR != 2) { LDS_ST1(sA, 0, buf_, a##s_##0) LDS_ST1(sA, 1, buf_, a##s_##1) LDS_ST1(sA, 2, buf_, a##s_##2) LDS_ST1(sA, 3, buf_, a##s_##3) LDS_ST1(sB, 0, buf_, b##s_##0) LDS_ST1(sB, 1, buf_, b##s_##1) LDS_ST1(sB, 2, buf_, b##s_##2) LDS_ST1(sB, 3, buf_, b##s_##3) }
;     ...
;   GL_LOAD(0, 0)
;   GL_LOAD(1, 1)
;   LDS_STORE(0, 0)
;   if (VAR != 4) __syncthreads();
; #pragma unroll
;   for (int kt = 0; kt < nk; kt += 2) {
;     if (kt + 2 < nk) { GL_LOAD(0, kt + 2) }
;     MMA_TILE(0)
;     LDS_STORE(1, 1)
;     if (VAR != 4) __syncthreads();
;     if (kt + 3 < nk) { GL_LOAD(1, kt + 3) }
;     MMA_TILE(1)
;     if (kt + 2 < nk) { LDS_STORE(0, 0) }
;     if (VAR != 4) __syncthreads();
	ds_write_b128 v17, v[74:77] offset:49152
	v_mfma_f32_16x16x32_f16 v[24:27], v[94:97], v[110:113], v[24:27]
	ds_read_b128 v[94:97], v22 offset:34816
	v_mfma_f32_16x16x32_f16 v[114:117], v[118:121], v[106:109], v[114:117]
	s_waitcnt vmcnt(2)
	ds_write_b128 v18, v[142:145] offset:49152
	v_mfma_f32_16x16x32_f16 v[40:43], v[118:121], v[110:113], v[40:43]
	ds_read_b128 v[118:121], v22 offset:36864
	v_mfma_f32_16x16x32_f16 v[70:73], v[122:125], v[106:109], v[70:73]
	ds_read_b128 v[106:109], v23
	v_mfma_f32_16x16x32_f16 v[48:51], v[122:125], v[110:113], v[48:51]
	ds_read_b128 v[110:113], v23 offset:2048
	s_waitcnt lgkmcnt(1)
	v_mfma_f32_16x16x32_f16 v[36:39], v[58:61], v[106:109], v[36:39]
	ds_read_b128 v[122:125], v22 offset:38912
	s_waitcnt lgkmcnt(1)
	v_mfma_f32_16x16x32_f16 v[66:69], v[58:61], v[110:113], v[66:69]
	s_waitcnt vmcnt(1)
	ds_write_b128 v19, v[154:157] offset:49152
	v_mfma_f32_16x16x32_f16 v[44:47], v[94:97], v[106:109], v[44:47]
	s_waitcnt vmcnt(0)
	ds_write_b128 v20, v[158:161] offset:49152
	v_mfma_f32_16x16x32_f16 v[78:81], v[94:97], v[110:113], v[78:81]
	v_mfma_f32_16x16x32_f16 v[82:85], v[118:121], v[106:109], v[82:85]
	v_mfma_f32_16x16x32_f16 v[86:89], v[118:121], v[110:113], v[86:89]
	s_waitcnt lgkmcnt(2)
	v_mfma_f32_16x16x32_f16 v[28:31], v[122:125], v[106:109], v[28:31]
	ds_read_b128 v[106:109], v23 offset:4096
	v_mfma_f32_16x16x32_f16 v[32:35], v[122:125], v[110:113], v[32:35]
	ds_read_b128 v[110:113], v23 offset:6144
	s_waitcnt lgkmcnt(1)
	v_mfma_f32_16x16x32_f16 v[98:101], v[58:61], v[106:109], v[98:101]
	s_waitcnt lgkmcnt(0)
	v_mfma_f32_16x16x32_f16 v[52:55], v[58:61], v[110:113], v[52:55]
	global_load_dwordx4 v[58:61], v[0:1], off offset:512
	v_mfma_f32_16x16x32_f16 v[102:105], v[94:97], v[106:109], v[102:105]
	v_mfma_f32_16x16x32_f16 v[24:27], v[94:97], v[110:113], v[24:27]
	v_mfma_f32_16x16x32_f16 v[114:117], v[118:121], v[106:109], v[114:117]
	v_mfma_f32_16x16x32_f16 v[40:43], v[118:121], v[110:113], v[40:43]
	v_mfma_f32_16x16x32_f16 v[70:73], v[122:125], v[106:109], v[70:73]
	global_load_dwordx4 v[106:109], v[2:3], off offset:512
	global_load_dwordx4 v[126:129], v[4:5], off offset:512
	global_load_dwordx4 v[134:137], v[14:15], off offset:512
	global_load_dwordx4 v[94:97], v[10:11], off offset:512
	global_load_dwordx4 v[162:165], v[12:13], off offset:512
	global_load_dwordx4 v[166:169], v[8:9], off offset:512
	global_load_dwordx4 v[190:193], v[6:7], off offset:512
	s_waitcnt lgkmcnt(0)
	s_barrier
	v_mfma_f32_16x16x32_f16 v[48:51], v[122:125], v[110:113], v[48:51]
	ds_read_b128 v[62:65], v16 offset:49152
	ds_read_b128 v[90:93], v21 offset:16384
	s_waitcnt lgkmcnt(0)
	v_mfma_f32_16x16x32_f16 v[36:39], v[62:65], v[90:93], v[36:39]
	ds_read_b128 v[74:77], v16 offset:51200
	ds_read_b128 v[110:113], v21 offset:18432
	s_waitcnt lgkmcnt(0)
	v_mfma_f32_16x16x32_f16 v[66:69], v[62:65], v[110:113], v[66:69]
	ds_read_b128 v[118:121], v16 offset:53248
	v_mfma_f32_16x16x32_f16 v[44:47], v[74:77], v[90:93], v[44:47]
	ds_read_b128 v[122:125], v16 offset:55296
	v_mfma_f32_16x16x32_f16 v[78:81], v[74:77], v[110:113], v[78:81]
	s_waitcnt vmcnt(7)
	ds_write_b128 v17, v[58:61]
	s_waitcnt lgkmcnt(2)
	v_mfma_f32_16x16x32_f16 v[82:85], v[118:121], v[90:93], v[82:85]
	s_waitcnt vmcnt(6)
	ds_write_b128 v18, v[106:109]
	v_mfma_f32_16x16x32_f16 v[86:89], v[118:121], v[110:113], v[86:89]
	s_waitcnt vmcnt(5)
	ds_write_b128 v19, v[126:129]
	s_waitcnt lgkmcnt(3)
	v_mfma_f32_16x16x32_f16 v[28:31], v[122:125], v[90:93], v[28:31]
	ds_read_b128 v[90:93], v21 offset:20480
	v_mfma_f32_16x16x32_f16 v[32:35], v[122:125], v[110:113], v[32:35]
	ds_read_b128 v[110:113], v21 offset:22528
	s_waitcnt lgkmcnt(1)
	v_mfma_f32_16x16x32_f16 v[98:101], v[62:65], v[90:93], v[98:101]
	s_waitcnt vmcnt(4)
	ds_write_b128 v20, v[134:137]
	s_waitcnt lgkmcnt(1)
	v_mfma_f32_16x16x32_f16 v[52:55], v[62:65], v[110:113], v[52:55]
	ds_read_b128 v[62:65], v22 offset:49152
	v_mfma_f32_16x16x32_f16 v[102:105], v[74:77], v[90:93], v[102:105]
	s_waitcnt vmcnt(3)
	ds_write_b128 v17, v[94:97] offset:32768
	v_mfma_f32_16x16x32_f16 v[24:27], v[74:77], v[110:113], v[24:27]
	ds_read_b128 v[74:77], v22 offset:51200
	v_mfma_f32_16x16x32_f16 v[114:117], v[118:121], v[90:93], v[114:117]
	s_waitcnt vmcnt(2)
	ds_write_b128 v18, v[162:165] offset:32768
	v_mfma_f32_16x16x32_f16 v[40:43], v[118:121], v[110:113], v[40:43]
	ds_read_b128 v[118:121], v22 offset:53248
	v_mfma_f32_16x16x32_f16 v[70:73], v[122:125], v[90:93], v[70:73]
	ds_read_b128 v[90:93], v23 offset:16384
	v_mfma_f32_16x16x32_f16 v[48:51], v[122:125], v[110:113], v[48:51]
	ds_read_b128 v[110:113], v23 offset:18432
	s_waitcnt lgkmcnt(1)
	v_mfma_f32_16x16x32_f16 v[36:39], v[62:65], v[90:93], v[36:39]
	ds_read_b128 v[122:125], v22 offset:55296
	s_waitcnt lgkmcnt(1)
	v_mfma_f32_16x16x32_f16 v[66:69], v[62:65], v[110:113], v[66:69]
	s_waitcnt vmcnt(1)
	ds_write_b128 v19, v[166:169] offset:32768
	v_mfma_f32_16x16x32_f16 v[44:47], v[74:77], v[90:93], v[44:47]
	s_waitcnt vmcnt(0)
	ds_write_b128 v20, v[190:193] offset:32768
	v_mfma_f32_16x16x32_f16 v[78:81], v[74:77], v[110:113], v[78:81]
	v_mfma_f32_16x16x32_f16 v[82:85], v[118:121], v[90:93], v[82:85]
	v_mfma_f32_16x16x32_f16 v[86:89], v[118:121], v[110:113], v[86:89]
	s_waitcnt lgkmcnt(2)
	v_mfma_f32_16x16x32_f16 v[28:31], v[122:125], v[90:93], v[28:31]
	ds_read_b128 v[90:93], v23 offset:20480
	v_mfma_f32_16x16x32_f16 v[32:35], v[122:125], v[110:113], v[32:35]
	ds_read_b128 v[110:113], v23 offset:22528
	s_waitcnt lgkmcnt(1)
	v_mfma_f32_16x16x32_f16 v[98:101], v[62:65], v[90:93], v[98:101]
	s_waitcnt lgkmcnt(0)
	v_mfma_f32_16x16x32_f16 v[52:55], v[62:65], v[110:113], v[52:55]
	global_load_dwordx4 v[62:65], v[0:1], off offset:640
	v_mfma_f32_16x16x32_f16 v[102:105], v[74:77], v[90:93], v[102:105]
	v_mfma_f32_16x16x32_f16 v[24:27], v[74:77], v[110:113], v[24:27]
	v_mfma_f32_16x16x32_f16 v[114:117], v[118:121], v[90:93], v[114:117]
	v_mfma_f32_16x16x32_f16 v[40:43], v[118:121], v[110:113], v[40:43]
	v_mfma_f32_16x16x32_f16 v[70:73], v[122:125], v[90:93], v[70:73]
	global_load_dwordx4 v[90:93], v[2:3], off offset:640
	global_load_dwordx4 v[130:133], v[4:5], off offset:640
	global_load_dwordx4 v[138:141], v[14:15], off offset:640
	global_load_dwordx4 v[74:77], v[10:11], off offset:640
	global_load_dwordx4 v[142:145], v[12:13], off offset:640
	global_load_dwordx4 v[154:157], v[8:9], off offset:640
	global_load_dwordx4 v[158:161], v[6:7], off offset:640
	s_waitcnt lgkmcnt(0)
	s_barrier
; #define GL_LOAD(s_, kt_) if (VAR != 1) { a##s_##0 = GL_A(0, kt_); a##s_##1 = GL_A(1, kt_); a##s_##2 = GL_A(2, kt_); a##s_##3 = GL_A(3, kt_); b##s_##0 = GL_B(0, kt_); b##s_##1 = GL_B(1, kt_); b##s_##2 = GL_B(2, kt_); b##s_##3 = GL_B(3, kt_); }
; #define LDS_STORE(s_, buf_) if (VAR != 2) { LDS_ST1(sA, 0, buf_, a##s_##0) LDS_ST1(sA, 1, buf_, a##s_##1) LDS_ST1(sA, 2, buf_, a##s_##2) LDS_ST1(sA, 3, buf_, a##s_##3) LDS_ST1(sB, 0, buf_, b##s_##0) LDS_ST1(sB, 1, buf_, b##s_##1) LDS_ST1(sB, 2, buf_, b##s_##2) LDS_ST1(sB, 3, buf_, b##s_##3) }
;     ...
;   GL_LOAD(0, 0)
;   GL_LOAD(1, 1)
;   LDS_STORE(0, 0)
;   if (VAR != 4) __syncthreads();
; #pragma unroll
;   for (int kt = 0; kt < nk; kt += 2) {
;     if (kt + 2 < nk) { GL_LOAD(0, kt + 2) }
;     MMA_TILE(0)
;     LDS_STORE(1, 1)
;     if (VAR != 4) __syncthreads();
;     if (kt + 3 < nk) { GL_LOAD(1, kt + 3) }
;     MMA_TILE(1)
;     if (kt + 2 < nk) { LDS_STORE(0, 0) }
;     if (VAR != 4) __syncthreads();
	v_mfma_f32_16x16x32_f16 v[48:51], v[122:125], v[110:113], v[48:51]
	ds_read_b128 v[58:61], v16 offset:32768
	ds_read_b128 v[106:109], v21
	s_waitcnt lgkmcnt(0)
	v_mfma_f32_16x16x32_f16 v[36:39], v[58:61], v[106:109], v[36:39]
	ds_read_b128 v[94:97], v16 offset:34816
	ds_read_b128 v[110:113], v21 offset:2048
	s_waitcnt lgkmcnt(0)
	v_mfma_f32_16x16x32_f16 v[66:69], v[58:61], v[110:113], v[66:69]
	ds_read_b128 v[118:121], v16 offset:36864
	v_mfma_f32_16x16x32_f16 v[44:47], v[94:97], v[106:109], v[44:47]
	ds_read_b128 v[122:125], v16 offset:38912
	v_mfma_f32_16x16x32_f16 v[78:81], v[94:97], v[110:113], v[78:81]
	s_waitcnt vmcnt(7)
	ds_write_b128 v17, v[62:65] offset:16384
	s_waitcnt lgkmcnt(2)
	v_mfma_f32_16x16x32_f16 v[82:85], v[118:121], v[106:109], v[82:85]
	s_waitcnt vmcnt(6)
	ds_write_b128 v18, v[90:93] offset:16384
	v_mfma_f32_16x16x32_f16 v[86:89], v[118:121], v[110:113], v[86:89]
	s_waitcnt vmcnt(5)
	ds_write_b128 v19, v[130:133] offset:16384
	s_waitcnt lgkmcnt(3)
	v_mfma_f32_16x16x32_f16 v[28:31], v[122:125], v[106:109], v[28:31]
	ds_read_b128 v[106:109], v21 offset:4096
	v_mfma_f32_16x16x32_f16 v[32:35], v[122:125], v[110:113], v[32:35]
	ds_read_b128 v[110:113], v21 offset:6144
	s_waitcnt lgkmcnt(1)
	v_mfma_f32_16x16x32_f16 v[98:101], v[58:61], v[106:109], v[98:101]
	s_waitcnt vmcnt(4)
	ds_write_b128 v20, v[138:141] offset:16384
	s_waitcnt lgkmcnt(1)
	v_mfma_f32_16x16x32_f16 v[52:55], v[58:61], v[110:113], v[52:55]
	ds_read_b128 v[58:61], v22 offset:32768
	v_mfma_f32_16x16x32_f16 v[102:105], v[94:97], v[106:109], v[102:105]
	s_waitcnt vmcnt(3)
	ds_write_b128 v17, v[74:77] offset:49152
	v_mfma_f32_16x16x32_f16 v[24:27], v[94:97], v[110:113], v[24:27]
	ds_read_b128 v[94:97], v22 offset:34816
	v_mfma_f32_16x16x32_f16 v[114:117], v[118:121], v[106:109], v[114:117]
	s_waitcnt vmcnt(2)
	ds_write_b128 v18, v[142:145] offset:49152
	v_mfma_f32_16x16x32_f16 v[40:43], v[118:121], v[110:113], v[40:43]
	ds_read_b128 v[118:121], v22 offset:36864
	v_mfma_f32_16x16x32_f16 v[70:73], v[122:125], v[106:109], v[70:73]
	ds_read_b128 v[106:109], v23
	v_mfma_f32_16x16x32_f16 v[48:51], v[122:125], v[110:113], v[48:51]
	ds_read_b128 v[110:113], v23 offset:2048
	s_waitcnt lgkmcnt(1)
	v_mfma_f32_16x16x32_f16 v[36:39], v[58:61], v[106:109], v[36:39]
	ds_read_b128 v[122:125], v22 offset:38912
	s_waitcnt lgkmcnt(1)
	v_mfma_f32_16x16x32_f16 v[66:69], v[58:61], v[110:113], v[66:69]
	s_waitcnt vmcnt(1)
	ds_write_b128 v19, v[154:157] offset:49152
	v_mfma_f32_16x16x32_f16 v[44:47], v[94:97], v[106:109], v[44:47]
	s_waitcnt vmcnt(0)
	ds_write_b128 v20, v[158:161] offset:49152
	v_mfma_f32_16x16x32_f16 v[78:81], v[94:97], v[110:113], v[78:81]
	v_mfma_f32_16x16x32_f16 v[82:85], v[118:121], v[106:109], v[82:85]
	v_mfma_f32_16x16x32_f16 v[86:89], v[118:121], v[110:113], v[86:89]
	s_waitcnt lgkmcnt(2)
	v_mfma_f32_16x16x32_f16 v[28:31], v[122:125], v[106:109], v[28:31]
	ds_read_b128 v[106:109], v23 offset:4096
	v_mfma_f32_16x16x32_f16 v[32:35], v[122:125], v[110:113], v[32:35]
	ds_read_b128 v[110:113], v23 offset:6144
	s_waitcnt lgkmcnt(1)
	v_mfma_f32_16x16x32_f16 v[98:101], v[58:61], v[106:109], v[98:101]
	s_waitcnt lgkmcnt(0)
	v_mfma_f32_16x16x32_f16 v[52:55], v[58:61], v[110:113], v[52:55]
	global_load_dwordx4 v[58:61], v[0:1], off offset:768
	v_mfma_f32_16x16x32_f16 v[102:105], v[94:97], v[106:109], v[102:105]
	v_mfma_f32_16x16x32_f16 v[24:27], v[94:97], v[110:113], v[24:27]
	v_mfma_f32_16x16x32_f16 v[114:117], v[118:121], v[106:109], v[114:117]
	v_mfma_f32_16x16x32_f16 v[40:43], v[118:121], v[110:113], v[40:43]
	v_mfma_f32_16x16x32_f16 v[70:73], v[122:125], v[106:109], v[70:73]
	global_load_dwordx4 v[106:109], v[2:3], off offset:768
	global_load_dwordx4 v[126:129], v[4:5], off offset:768
	global_load_dwordx4 v[134:137], v[14:15], off offset:768
	global_load_dwordx4 v[94:97], v[10:11], off offset:768
	global_load_dwordx4 v[162:165], v[12:13], off offset:768
	global_load_dwordx4 v[166:169], v[8:9], off offset:768
	global_load_dwordx4 v[190:193], v[6:7], off offset:768
	s_waitcnt lgkmcnt(0)
	s_barrier
	v_mfma_f32_16x16x32_f16 v[48:51], v[122:125], v[110:113], v[48:51]
	ds_read_b128 v[62:65], v16 offset:49152
	ds_read_b128 v[90:93], v21 offset:16384
	s_waitcnt lgkmcnt(0)
	v_mfma_f32_16x16x32_f16 v[36:39], v[62:65], v[90:93], v[36:39]
	ds_read_b128 v[74:77], v16 offset:51200
	ds_read_b128 v[110:113], v21 offset:18432
	s_waitcnt lgkmcnt(0)
	v_mfma_f32_16x16x32_f16 v[66:69], v[62:65], v[110:113], v[66:69]
	ds_read_b128 v[118:121], v16 offset:53248
	v_mfma_f32_16x16x32_f16 v[44:47], v[74:77], v[90:93], v[44:47]
	ds_read_b128 v[122:125], v16 offset:55296
	v_mfma_f32_16x16x32_f16 v[78:81], v[74:77], v[110:113], v[78:81]
	s_waitcnt vmcnt(7)
	ds_write_b128 v17, v[58:61]
	s_waitcnt lgkmcnt(2)
	v_mfma_f32_16x16x32_f16 v[82:85], v[118:121], v[90:93], v[82:85]
	s_waitcnt vmcnt(6)
	ds_write_b128 v18, v[106:109]
	v_mfma_f32_16x16x32_f16 v[86:89], v[118:121], v[110:113], v[86:89]
	s_waitcnt vmcnt(5)
	ds_write_b128 v19, v[126:129]
	s_waitcnt lgkmcnt(3)
	v_mfma_f32_16x16x32_f16 v[28:31], v[122:125], v[90:93], v[28:31]
	ds_read_b128 v[90:93], v21 offset:20480
	v_mfma_f32_16x16x32_f16 v[32:35], v[122:125], v[110:113], v[32:35]
	ds_read_b128 v[110:113], v21 offset:22528
	s_waitcnt lgkmcnt(1)
	v_mfma_f32_16x16x32_f16 v[98:101], v[62:65], v[90:93], v[98:101]
	s_waitcnt vmcnt(4)
	ds_write_b128 v20, v[134:137]
	s_waitcnt lgkmcnt(1)
	v_mfma_f32_16x16x32_f16 v[52:55], v[62:65], v[110:113], v[52:55]
	ds_read_b128 v[62:65], v22 offset:49152
	v_mfma_f32_16x16x32_f16 v[102:105], v[74:77], v[90:93], v[102:105]
	s_waitcnt vmcnt(3)
; #define GL_LOAD(s_, kt_) if (VAR != 1) { a##s_##0 = GL_A(0, kt_); a##s_##1 = GL_A(1, kt_); a##s_##2 = GL_A(2, kt_); a##s_##3 = GL_A(3, kt_); b##s_##0 = GL_B(0, kt_); b##s_##1 = GL_B(1, kt_); b##s_##2 = GL_B(2, kt_); b##s_##3 = GL_B(3, kt_); }
; #define LDS_STORE(s_, buf_) if (VAR != 2) { LDS_ST1(sA, 0, buf_, a##s_##0) LDS_ST1(sA, 1, buf_, a##s_##1) LDS_ST1(sA, 2, buf_, a##s_##2) LDS_ST1(sA, 3, buf_, a##s_##3) LDS_ST1(sB, 0, buf_, b##s_##0) LDS_ST1(sB, 1, buf_, b##s_##1) LDS_ST1(sB, 2, buf_, b##s_##2) LDS_ST1(sB, 3, buf_, b##s_##3) }
;     ...
;   GL_LOAD(0, 0)
;   GL_LOAD(1, 1)
;   LDS_STORE(0, 0)
;   if (VAR != 4) __syncthreads();
; #pragma unroll
;   for (int kt = 0; kt < nk; kt += 2) {
;     if (kt + 2 < nk) { GL_LOAD(0, kt + 2) }
;     MMA_TILE(0)
;     LDS_STORE(1, 1)
;     if (VAR != 4) __syncthreads();
;     if (kt + 3 < nk) { GL_LOAD(1, kt + 3) }
;     MMA_TILE(1)
;     if (kt + 2 < nk) { LDS_STORE(0, 0) }
;     if (VAR != 4) __syncthreads();
	ds_write_b128 v17, v[94:97] offset:32768
	v_mfma_f32_16x16x32_f16 v[24:27], v[74:77], v[110:113], v[24:27]
	ds_read_b128 v[74:77], v22 offset:51200
	v_mfma_f32_16x16x32_f16 v[114:117], v[118:121], v[90:93], v[114:117]
	s_waitcnt vmcnt(2)
	ds_write_b128 v18, v[162:165] offset:32768
	v_mfma_f32_16x16x32_f16 v[40:43], v[118:121], v[110:113], v[40:43]
	ds_read_b128 v[118:121], v22 offset:53248
	v_mfma_f32_16x16x32_f16 v[70:73], v[122:125], v[90:93], v[70:73]
	ds_read_b128 v[90:93], v23 offset:16384
	v_mfma_f32_16x16x32_f16 v[48:51], v[122:125], v[110:113], v[48:51]
	ds_read_b128 v[110:113], v23 offset:18432
	s_waitcnt lgkmcnt(1)
	v_mfma_f32_16x16x32_f16 v[36:39], v[62:65], v[90:93], v[36:39]
	ds_read_b128 v[122:125], v22 offset:55296
	s_waitcnt lgkmcnt(1)
	v_mfma_f32_16x16x32_f16 v[66:69], v[62:65], v[110:113], v[66:69]
	s_waitcnt vmcnt(1)
	ds_write_b128 v19, v[166:169] offset:32768
	v_mfma_f32_16x16x32_f16 v[44:47], v[74:77], v[90:93], v[44:47]
	s_waitcnt vmcnt(0)
	ds_write_b128 v20, v[190:193] offset:32768
	v_mfma_f32_16x16x32_f16 v[78:81], v[74:77], v[110:113], v[78:81]
	v_mfma_f32_16x16x32_f16 v[82:85], v[118:121], v[90:93], v[82:85]
	v_mfma_f32_16x16x32_f16 v[86:89], v[118:121], v[110:113], v[86:89]
	s_waitcnt lgkmcnt(2)
	v_mfma_f32_16x16x32_f16 v[28:31], v[122:125], v[90:93], v[28:31]
	ds_read_b128 v[90:93], v23 offset:20480
	v_mfma_f32_16x16x32_f16 v[32:35], v[122:125], v[110:113], v[32:35]
	ds_read_b128 v[110:113], v23 offset:22528
	s_waitcnt lgkmcnt(1)
	v_mfma_f32_16x16x32_f16 v[98:101], v[62:65], v[90:93], v[98:101]
	s_waitcnt lgkmcnt(0)
	v_mfma_f32_16x16x32_f16 v[52:55], v[62:65], v[110:113], v[52:55]
	global_load_dwordx4 v[62:65], v[0:1], off offset:896
	v_mfma_f32_16x16x32_f16 v[102:105], v[74:77], v[90:93], v[102:105]
	v_mfma_f32_16x16x32_f16 v[24:27], v[74:77], v[110:113], v[24:27]
	v_mfma_f32_16x16x32_f16 v[114:117], v[118:121], v[90:93], v[114:117]
	v_mfma_f32_16x16x32_f16 v[40:43], v[118:121], v[110:113], v[40:43]
	v_mfma_f32_16x16x32_f16 v[70:73], v[122:125], v[90:93], v[70:73]
	global_load_dwordx4 v[90:93], v[2:3], off offset:896
	global_load_dwordx4 v[130:133], v[4:5], off offset:896
	global_load_dwordx4 v[138:141], v[14:15], off offset:896
	global_load_dwordx4 v[74:77], v[10:11], off offset:896
	global_load_dwordx4 v[142:145], v[12:13], off offset:896
	global_load_dwordx4 v[154:157], v[8:9], off offset:896
	global_load_dwordx4 v[158:161], v[6:7], off offset:896
	s_waitcnt lgkmcnt(0)
	s_barrier
	v_mfma_f32_16x16x32_f16 v[48:51], v[122:125], v[110:113], v[48:51]
	ds_read_b128 v[58:61], v16 offset:32768
	ds_read_b128 v[106:109], v21
	s_waitcnt lgkmcnt(0)
	v_mfma_f32_16x16x32_f16 v[36:39], v[58:61], v[106:109], v[36:39]
	ds_read_b128 v[94:97], v16 offset:34816
	ds_read_b128 v[110:113], v21 offset:2048
	s_waitcnt lgkmcnt(0)
	v_mfma_f32_16x16x32_f16 v[66:69], v[58:61], v[110:113], v[66:69]
	ds_read_b128 v[118:121], v16 offset:36864
	v_mfma_f32_16x16x32_f16 v[44:47], v[94:97], v[106:109], v[44:47]
	ds_read_b128 v[122:125], v16 offset:38912
	v_mfma_f32_16x16x32_f16 v[78:81], v[94:97], v[110:113], v[78:81]
	s_waitcnt vmcnt(7)
	ds_write_b128 v17, v[62:65] offset:16384
	s_waitcnt lgkmcnt(2)
	v_mfma_f32_16x16x32_f16 v[82:85], v[118:121], v[106:109], v[82:85]
	s_waitcnt vmcnt(6)
	ds_write_b128 v18, v[90:93] offset:16384
	v_mfma_f32_16x16x32_f16 v[86:89], v[118:121], v[110:113], v[86:89]
	s_waitcnt vmcnt(5)
	ds_write_b128 v19, v[130:133] offset:16384
	s_waitcnt lgkmcnt(3)
	v_mfma_f32_16x16x32_f16 v[28:31], v[122:125], v[106:109], v[28:31]
	ds_read_b128 v[106:109], v21 offset:4096
	v_mfma_f32_16x16x32_f16 v[32:35], v[122:125], v[110:113], v[32:35]
	ds_read_b128 v[110:113], v21 offset:6144
	s_waitcnt lgkmcnt(1)
	v_mfma_f32_16x16x32_f16 v[98:101], v[58:61], v[106:109], v[98:101]
	s_waitcnt vmcnt(4)
	ds_write_b128 v20, v[138:141] offset:16384
	s_waitcnt lgkmcnt(1)
	v_mfma_f32_16x16x32_f16 v[52:55], v[58:61], v[110:113], v[52:55]
	ds_read_b128 v[58:61], v22 offset:32768
	v_mfma_f32_16x16x32_f16 v[102:105], v[94:97], v[106:109], v[102:105]
	s_waitcnt vmcnt(3)
	ds_write_b128 v17, v[74:77] offset:49152
	v_mfma_f32_16x16x32_f16 v[24:27], v[94:97], v[110:113], v[24:27]
	ds_read_b128 v[94:97], v22 offset:34816
	v_mfma_f32_16x16x32_f16 v[114:117], v[118:121], v[106:109], v[114:117]
	s_waitcnt vmcnt(2)
	ds_write_b128 v18, v[142:145] offset:49152
	v_mfma_f32_16x16x32_f16 v[40:43], v[118:121], v[110:113], v[40:43]
	ds_read_b128 v[118:121], v22 offset:36864
	v_mfma_f32_16x16x32_f16 v[70:73], v[122:125], v[106:109], v[70:73]
	ds_read_b128 v[106:109], v23
	v_mfma_f32_16x16x32_f16 v[48:51], v[122:125], v[110:113], v[48:51]
	ds_read_b128 v[110:113], v23 offset:2048
	s_waitcnt lgkmcnt(1)
	v_mfma_f32_16x16x32_f16 v[36:39], v[58:61], v[106:109], v[36:39]
	ds_read_b128 v[122:125], v22 offset:38912
	s_waitcnt lgkmcnt(1)
	v_mfma_f32_16x16x32_f16 v[66:69], v[58:61], v[110:113], v[66:69]
	s_waitcnt vmcnt(1)
	ds_write_b128 v19, v[154:157] offset:49152
	v_mfma_f32_16x16x32_f16 v[44:47], v[94:97], v[106:109], v[44:47]
	s_waitcnt vmcnt(0)
	ds_write_b128 v20, v[158:161] offset:49152
	v_mfma_f32_16x16x32_f16 v[78:81], v[94:97], v[110:113], v[78:81]
	v_mfma_f32_16x16x32_f16 v[82:85], v[118:121], v[106:109], v[82:85]
	v_mfma_f32_16x16x32_f16 v[86:89], v[118:121], v[110:113], v[86:89]
	s_waitcnt lgkmcnt(2)
	v_mfma_f32_16x16x32_f16 v[28:31], v[122:125], v[106:109], v[28:31]
	ds_read_b128 v[106:109], v23 offset:4096
	v_mfma_f32_16x16x32_f16 v[32:35], v[122:125], v[110:113], v[32:35]
	ds_read_b128 v[110:113], v23 offset:6144
	s_waitcnt lgkmcnt(1)
	v_mfma_f32_16x16x32_f16 v[98:101], v[58:61], v[106:109], v[98:101]
	s_waitcnt lgkmcnt(0)
	v_mfma_f32_16x16x32_f16 v[52:55], v[58:61], v[110:113], v[52:55]
	global_load_dwordx4 v[58:61], v[0:1], off offset:1024
	v_mfma_f32_16x16x32_f16 v[102:105], v[94:97], v[106:109], v[102:105]
	v_mfma_f32_16x16x32_f16 v[24:27], v[94:97], v[110:113], v[24:27]
	v_mfma_f32_16x16x32_f16 v[114:117], v[118:121], v[106:109], v[114:117]
	v_mfma_f32_16x16x32_f16 v[40:43], v[118:121], v[110:113], v[40:43]
	v_mfma_f32_16x16x32_f16 v[70:73], v[122:125], v[106:109], v[70:73]
	global_load_dwordx4 v[106:109], v[2:3], off offset:1024
	global_load_dwordx4 v[126:129], v[4:5], off offset:1024
	global_load_dwordx4 v[134:137], v[14:15], off offset:1024
	global_load_dwordx4 v[94:97], v[10:11], off offset:1024
	global_load_dwordx4 v[162:165], v[12:13], off offset:1024
	global_load_dwordx4 v[166:169], v[8:9], off offset:1024
	global_load_dwordx4 v[190:193], v[6:7], off offset:1024
	s_waitcnt lgkmcnt(0)
	s_barrier
; #define GL_LOAD(s_, kt_) if (VAR != 1) { a##s_##0 = GL_A(0, kt_); a##s_##1 = GL_A(1, kt_); a##s_##2 = GL_A(2, kt_); a##s_##3 = GL_A(3, kt_); b##s_##0 = GL_B(0, kt_); b##s_##1 = GL_B(1, kt_); b##s_##2 = GL_B(2, kt_); b##s_##3 = GL_B(3, kt_); }
; #define LDS_STORE(s_, buf_) if (VAR != 2) { LDS_ST1(sA, 0, buf_, a##s_##0) LDS_ST1(sA, 1, buf_, a##s_##1) LDS_ST1(sA, 2, buf_, a##s_##2) LDS_ST1(sA, 3, buf_, a##s_##3) LDS_ST1(sB, 0, buf_, b##s_##0) LDS_ST1(sB, 1, buf_, b##s_##1) LDS_ST1(sB, 2, buf_, b##s_##2) LDS_ST1(sB, 3, buf_, b##s_##3) }
;     ...
;   GL_LOAD(0, 0)
;   GL_LOAD(1, 1)
;   LDS_STORE(0, 0)
;   if (VAR != 4) __syncthreads();
; #pragma unroll
;   for (int kt = 0; kt < nk; kt += 2) {
;     if (kt + 2 < nk) { GL_LOAD(0, kt + 2) }
;     MMA_TILE(0)
;     LDS_STORE(1, 1)
;     if (VAR != 4) __syncthreads();
;     if (kt + 3 < nk) { GL_LOAD(1, kt + 3) }
;     MMA_TILE(1)
;     if (kt + 2 < nk) { LDS_STORE(0, 0) }
;     if (VAR != 4) __syncthreads();
	v_mfma_f32_16x16x32_f16 v[48:51], v[122:125], v[110:113], v[48:51]
	ds_read_b128 v[62:65], v16 offset:49152
	ds_read_b128 v[90:93], v21 offset:16384
	s_waitcnt lgkmcnt(0)
	v_mfma_f32_16x16x32_f16 v[36:39], v[62:65], v[90:93], v[36:39]
	ds_read_b128 v[74:77], v16 offset:51200
	ds_read_b128 v[110:113], v21 offset:18432
	s_waitcnt lgkmcnt(0)
	v_mfma_f32_16x16x32_f16 v[66:69], v[62:65], v[110:113], v[66:69]
	ds_read_b128 v[118:121], v16 offset:53248
	v_mfma_f32_16x16x32_f16 v[44:47], v[74:77], v[90:93], v[44:47]
	ds_read_b128 v[122:125], v16 offset:55296
	v_mfma_f32_16x16x32_f16 v[78:81], v[74:77], v[110:113], v[78:81]
	s_waitcnt vmcnt(7)
	ds_write_b128 v17, v[58:61]
	s_waitcnt lgkmcnt(2)
	v_mfma_f32_16x16x32_f16 v[82:85], v[118:121], v[90:93], v[82:85]
	s_waitcnt vmcnt(6)
	ds_write_b128 v18, v[106:109]
	v_mfma_f32_16x16x32_f16 v[86:89], v[118:121], v[110:113], v[86:89]
	s_waitcnt vmcnt(5)
	ds_write_b128 v19, v[126:129]
	s_waitcnt lgkmcnt(3)
	v_mfma_f32_16x16x32_f16 v[28:31], v[122:125], v[90:93], v[28:31]
	ds_read_b128 v[90:93], v21 offset:20480
	v_mfma_f32_16x16x32_f16 v[32:35], v[122:125], v[110:113], v[32:35]
	ds_read_b128 v[110:113], v21 offset:22528
	s_waitcnt lgkmcnt(1)
	v_mfma_f32_16x16x32_f16 v[98:101], v[62:65], v[90:93], v[98:101]
	s_waitcnt vmcnt(4)
	ds_write_b128 v20, v[134:137]
	s_waitcnt lgkmcnt(1)
	v_mfma_f32_16x16x32_f16 v[52:55], v[62:65], v[110:113], v[52:55]
	ds_read_b128 v[62:65], v22 offset:49152
	v_mfma_f32_16x16x32_f16 v[102:105], v[74:77], v[90:93], v[102:105]
	s_waitcnt vmcnt(3)
	ds_write_b128 v17, v[94:97] offset:32768
	v_mfma_f32_16x16x32_f16 v[24:27], v[74:77], v[110:113], v[24:27]
	ds_read_b128 v[74:77], v22 offset:51200
	v_mfma_f32_16x16x32_f16 v[114:117], v[118:121], v[90:93], v[114:117]
	s_waitcnt vmcnt(2)
	ds_write_b128 v18, v[162:165] offset:32768
	v_mfma_f32_16x16x32_f16 v[40:43], v[118:121], v[110:113], v[40:43]
	ds_read_b128 v[118:121], v22 offset:53248
	v_mfma_f32_16x16x32_f16 v[70:73], v[122:125], v[90:93], v[70:73]
	ds_read_b128 v[90:93], v23 offset:16384
	v_mfma_f32_16x16x32_f16 v[48:51], v[122:125], v[110:113], v[48:51]
	ds_read_b128 v[110:113], v23 offset:18432
	s_waitcnt lgkmcnt(1)
	v_mfma_f32_16x16x32_f16 v[36:39], v[62:65], v[90:93], v[36:39]
	ds_read_b128 v[122:125], v22 offset:55296
	s_waitcnt lgkmcnt(1)
	v_mfma_f32_16x16x32_f16 v[66:69], v[62:65], v[110:113], v[66:69]
	s_waitcnt vmcnt(1)
	ds_write_b128 v19, v[166:169] offset:32768
	v_mfma_f32_16x16x32_f16 v[44:47], v[74:77], v[90:93], v[44:47]
	s_waitcnt vmcnt(0)
	ds_write_b128 v20, v[190:193] offset:32768
	v_mfma_f32_16x16x32_f16 v[78:81], v[74:77], v[110:113], v[78:81]
	v_mfma_f32_16x16x32_f16 v[82:85], v[118:121], v[90:93], v[82:85]
	v_mfma_f32_16x16x32_f16 v[86:89], v[118:121], v[110:113], v[86:89]
	s_waitcnt lgkmcnt(2)
	v_mfma_f32_16x16x32_f16 v[28:31], v[122:125], v[90:93], v[28:31]
	ds_read_b128 v[90:93], v23 offset:20480
	v_mfma_f32_16x16x32_f16 v[32:35], v[122:125], v[110:113], v[32:35]
	ds_read_b128 v[110:113], v23 offset:22528
	s_waitcnt lgkmcnt(1)
	v_mfma_f32_16x16x32_f16 v[98:101], v[62:65], v[90:93], v[98:101]
	s_waitcnt lgkmcnt(0)
	v_mfma_f32_16x16x32_f16 v[52:55], v[62:65], v[110:113], v[52:55]
	global_load_dwordx4 v[62:65], v[0:1], off offset:1152
	v_mfma_f32_16x16x32_f16 v[102:105], v[74:77], v[90:93], v[102:105]
	v_mfma_f32_16x16x32_f16 v[24:27], v[74:77], v[110:113], v[24:27]
	v_mfma_f32_16x16x32_f16 v[114:117], v[118:121], v[90:93], v[114:117]
	v_mfma_f32_16x16x32_f16 v[40:43], v[118:121], v[110:113], v[40:43]
	v_mfma_f32_16x16x32_f16 v[70:73], v[122:125], v[90:93], v[70:73]
	global_load_dwordx4 v[90:93], v[2:3], off offset:1152
	global_load_dwordx4 v[130:133], v[4:5], off offset:1152
	global_load_dwordx4 v[138:141], v[14:15], off offset:1152
	global_load_dwordx4 v[74:77], v[10:11], off offset:1152
	global_load_dwordx4 v[142:145], v[12:13], off offset:1152
	global_load_dwordx4 v[154:157], v[8:9], off offset:1152
	global_load_dwordx4 v[158:161], v[6:7], off offset:1152
	s_waitcnt lgkmcnt(0)
	s_barrier
	v_mfma_f32_16x16x32_f16 v[48:51], v[122:125], v[110:113], v[48:51]
	ds_read_b128 v[58:61], v16 offset:32768
	ds_read_b128 v[106:109], v21
	s_waitcnt lgkmcnt(0)
	v_mfma_f32_16x16x32_f16 v[36:39], v[58:61], v[106:109], v[36:39]
	ds_read_b128 v[94:97], v16 offset:34816
	ds_read_b128 v[110:113], v21 offset:2048
	s_waitcnt lgkmcnt(0)
	v_mfma_f32_16x16x32_f16 v[66:69], v[58:61], v[110:113], v[66:69]
	ds_read_b128 v[118:121], v16 offset:36864
	v_mfma_f32_16x16x32_f16 v[44:47], v[94:97], v[106:109], v[44:47]
	ds_read_b128 v[122:125], v16 offset:38912
	v_mfma_f32_16x16x32_f16 v[78:81], v[94:97], v[110:113], v[78:81]
	s_waitcnt vmcnt(7)
	ds_write_b128 v17, v[62:65] offset:16384
	s_waitcnt lgkmcnt(2)
	v_mfma_f32_16x16x32_f16 v[82:85], v[118:121], v[106:109], v[82:85]
	s_waitcnt vmcnt(6)
	ds_write_b128 v18, v[90:93] offset:16384
	v_mfma_f32_16x16x32_f16 v[86:89], v[118:121], v[110:113], v[86:89]
	s_waitcnt vmcnt(5)
	ds_write_b128 v19, v[130:133] offset:16384
	s_waitcnt lgkmcnt(3)
	v_mfma_f32_16x16x32_f16 v[28:31], v[122:125], v[106:109], v[28:31]
	ds_read_b128 v[106:109], v21 offset:4096
	v_mfma_f32_16x16x32_f16 v[32:35], v[122:125], v[110:113], v[32:35]
	ds_read_b128 v[110:113], v21 offset:6144
	s_waitcnt lgkmcnt(1)
	v_mfma_f32_16x16x32_f16 v[98:101], v[58:61], v[106:109], v[98:101]
	s_waitcnt vmcnt(4)
	ds_write_b128 v20, v[138:141] offset:16384
	s_waitcnt lgkmcnt(1)
	v_mfma_f32_16x16x32_f16 v[52:55], v[58:61], v[110:113], v[52:55]
	ds_read_b128 v[58:61], v22 offset:32768
	v_mfma_f32_16x16x32_f16 v[102:105], v[94:97], v[106:109], v[102:105]
	s_waitcnt vmcnt(3)
; #define GL_LOAD(s_, kt_) if (VAR != 1) { a##s_##0 = GL_A(0, kt_); a##s_##1 = GL_A(1, kt_); a##s_##2 = GL_A(2, kt_); a##s_##3 = GL_A(3, kt_); b##s_##0 = GL_B(0, kt_); b##s_##1 = GL_B(1, kt_); b##s_##2 = GL_B(2, kt_); b##s_##3 = GL_B(3, kt_); }
; #define LDS_STORE(s_, buf_) if (VAR != 2) { LDS_ST1(sA, 0, buf_, a##s_##0) LDS_ST1(sA, 1, buf_, a##s_##1) LDS_ST1(sA, 2, buf_, a##s_##2) LDS_ST1(sA, 3, buf_, a##s_##3) LDS_ST1(sB, 0, buf_, b##s_##0) LDS_ST1(sB, 1, buf_, b##s_##1) LDS_ST1(sB, 2, buf_, b##s_##2) LDS_ST1(sB, 3, buf_, b##s_##3) }
;     ...
;   GL_LOAD(0, 0)
;   GL_LOAD(1, 1)
;   LDS_STORE(0, 0)
;   if (VAR != 4) __syncthreads();
; #pragma unroll
;   for (int kt = 0; kt < nk; kt += 2) {
;     if (kt + 2 < nk) { GL_LOAD(0, kt + 2) }
;     MMA_TILE(0)
;     LDS_STORE(1, 1)
;     if (VAR != 4) __syncthreads();
;     if (kt + 3 < nk) { GL_LOAD(1, kt + 3) }
;     MMA_TILE(1)
;     if (kt + 2 < nk) { LDS_STORE(0, 0) }
;     if (VAR != 4) __syncthreads();
	ds_write_b128 v17, v[74:77] offset:49152
	v_mfma_f32_16x16x32_f16 v[24:27], v[94:97], v[110:113], v[24:27]
	ds_read_b128 v[94:97], v22 offset:34816
	v_mfma_f32_16x16x32_f16 v[114:117], v[118:121], v[106:109], v[114:117]
	s_waitcnt vmcnt(2)
	ds_write_b128 v18, v[142:145] offset:49152
	v_mfma_f32_16x16x32_f16 v[40:43], v[118:121], v[110:113], v[40:43]
	ds_read_b128 v[118:121], v22 offset:36864
	v_mfma_f32_16x16x32_f16 v[70:73], v[122:125], v[106:109], v[70:73]
	ds_read_b128 v[106:109], v23
	v_mfma_f32_16x16x32_f16 v[48:51], v[122:125], v[110:113], v[48:51]
	ds_read_b128 v[110:113], v23 offset:2048
	s_waitcnt lgkmcnt(1)
	v_mfma_f32_16x16x32_f16 v[36:39], v[58:61], v[106:109], v[36:39]
	ds_read_b128 v[122:125], v22 offset:38912
	s_waitcnt lgkmcnt(1)
	v_mfma_f32_16x16x32_f16 v[66:69], v[58:61], v[110:113], v[66:69]
	s_waitcnt vmcnt(1)
	ds_write_b128 v19, v[154:157] offset:49152
	v_mfma_f32_16x16x32_f16 v[44:47], v[94:97], v[106:109], v[44:47]
	s_waitcnt vmcnt(0)
	ds_write_b128 v20, v[158:161] offset:49152
	v_mfma_f32_16x16x32_f16 v[78:81], v[94:97], v[110:113], v[78:81]
	v_mfma_f32_16x16x32_f16 v[82:85], v[118:121], v[106:109], v[82:85]
	v_mfma_f32_16x16x32_f16 v[86:89], v[118:121], v[110:113], v[86:89]
	s_waitcnt lgkmcnt(2)
	v_mfma_f32_16x16x32_f16 v[28:31], v[122:125], v[106:109], v[28:31]
	ds_read_b128 v[106:109], v23 offset:4096
	v_mfma_f32_16x16x32_f16 v[32:35], v[122:125], v[110:113], v[32:35]
	ds_read_b128 v[110:113], v23 offset:6144
	s_waitcnt lgkmcnt(1)
	v_mfma_f32_16x16x32_f16 v[98:101], v[58:61], v[106:109], v[98:101]
	s_waitcnt lgkmcnt(0)
	v_mfma_f32_16x16x32_f16 v[52:55], v[58:61], v[110:113], v[52:55]
	global_load_dwordx4 v[58:61], v[0:1], off offset:1280
	v_mfma_f32_16x16x32_f16 v[102:105], v[94:97], v[106:109], v[102:105]
	v_mfma_f32_16x16x32_f16 v[24:27], v[94:97], v[110:113], v[24:27]
	v_mfma_f32_16x16x32_f16 v[114:117], v[118:121], v[106:109], v[114:117]
	v_mfma_f32_16x16x32_f16 v[40:43], v[118:121], v[110:113], v[40:43]
	v_mfma_f32_16x16x32_f16 v[70:73], v[122:125], v[106:109], v[70:73]
	global_load_dwordx4 v[106:109], v[2:3], off offset:1280
	global_load_dwordx4 v[126:129], v[4:5], off offset:1280
	global_load_dwordx4 v[134:137], v[14:15], off offset:1280
	global_load_dwordx4 v[94:97], v[10:11], off offset:1280
	global_load_dwordx4 v[162:165], v[12:13], off offset:1280
	global_load_dwordx4 v[166:169], v[8:9], off offset:1280
	global_load_dwordx4 v[190:193], v[6:7], off offset:1280
	s_waitcnt lgkmcnt(0)
	s_barrier
	v_mfma_f32_16x16x32_f16 v[48:51], v[122:125], v[110:113], v[48:51]
	ds_read_b128 v[62:65], v16 offset:49152
	ds_read_b128 v[90:93], v21 offset:16384
	s_waitcnt lgkmcnt(0)
	v_mfma_f32_16x16x32_f16 v[36:39], v[62:65], v[90:93], v[36:39]
	ds_read_b128 v[74:77], v16 offset:51200
	ds_read_b128 v[110:113], v21 offset:18432
	s_waitcnt lgkmcnt(0)
	v_mfma_f32_16x16x32_f16 v[66:69], v[62:65], v[110:113], v[66:69]
	ds_read_b128 v[118:121], v16 offset:53248
	v_mfma_f32_16x16x32_f16 v[44:47], v[74:77], v[90:93], v[44:47]
	ds_read_b128 v[122:125], v16 offset:55296
	v_mfma_f32_16x16x32_f16 v[78:81], v[74:77], v[110:113], v[78:81]
	s_waitcnt vmcnt(7)
	ds_write_b128 v17, v[58:61]
	s_waitcnt lgkmcnt(2)
	v_mfma_f32_16x16x32_f16 v[82:85], v[118:121], v[90:93], v[82:85]
	s_waitcnt vmcnt(6)
	ds_write_b128 v18, v[106:109]
	v_mfma_f32_16x16x32_f16 v[86:89], v[118:121], v[110:113], v[86:89]
	s_waitcnt vmcnt(5)
	ds_write_b128 v19, v[126:129]
	s_waitcnt lgkmcnt(3)
	v_mfma_f32_16x16x32_f16 v[28:31], v[122:125], v[90:93], v[28:31]
	ds_read_b128 v[90:93], v21 offset:20480
	v_mfma_f32_16x16x32_f16 v[32:35], v[122:125], v[110:113], v[32:35]
	ds_read_b128 v[110:113], v21 offset:22528
	s_waitcnt lgkmcnt(1)
	v_mfma_f32_16x16x32_f16 v[98:101], v[62:65], v[90:93], v[98:101]
	s_waitcnt vmcnt(4)
	ds_write_b128 v20, v[134:137]
	s_waitcnt lgkmcnt(1)
	v_mfma_f32_16x16x32_f16 v[52:55], v[62:65], v[110:113], v[52:55]
	ds_read_b128 v[62:65], v22 offset:49152
	v_mfma_f32_16x16x32_f16 v[102:105], v[74:77], v[90:93], v[102:105]
	s_waitcnt vmcnt(3)
	ds_write_b128 v17, v[94:97] offset:32768
	v_mfma_f32_16x16x32_f16 v[24:27], v[74:77], v[110:113], v[24:27]
	ds_read_b128 v[74:77], v22 offset:51200
	v_mfma_f32_16x16x32_f16 v[114:117], v[118:121], v[90:93], v[114:117]
	s_waitcnt vmcnt(2)
	ds_write_b128 v18, v[162:165] offset:32768
	v_mfma_f32_16x16x32_f16 v[40:43], v[118:121], v[110:113], v[40:43]
	ds_read_b128 v[118:121], v22 offset:53248
	v_mfma_f32_16x16x32_f16 v[70:73], v[122:125], v[90:93], v[70:73]
	ds_read_b128 v[90:93], v23 offset:16384
	v_mfma_f32_16x16x32_f16 v[48:51], v[122:125], v[110:113], v[48:51]
	ds_read_b128 v[110:113], v23 offset:18432
	s_waitcnt lgkmcnt(1)
	v_mfma_f32_16x16x32_f16 v[36:39], v[62:65], v[90:93], v[36:39]
	ds_read_b128 v[122:125], v22 offset:55296
	s_waitcnt lgkmcnt(1)
	v_mfma_f32_16x16x32_f16 v[66:69], v[62:65], v[110:113], v[66:69]
	s_waitcnt vmcnt(1)
	ds_write_b128 v19, v[166:169] offset:32768
	v_mfma_f32_16x16x32_f16 v[44:47], v[74:77], v[90:93], v[44:47]
	s_waitcnt vmcnt(0)
	ds_write_b128 v20, v[190:193] offset:32768
	v_mfma_f32_16x16x32_f16 v[78:81], v[74:77], v[110:113], v[78:81]
	v_mfma_f32_16x16x32_f16 v[82:85], v[118:121], v[90:93], v[82:85]
	v_mfma_f32_16x16x32_f16 v[86:89], v[118:121], v[110:113], v[86:89]
	s_waitcnt lgkmcnt(2)
	v_mfma_f32_16x16x32_f16 v[28:31], v[122:125], v[90:93], v[28:31]
	ds_read_b128 v[90:93], v23 offset:20480
	v_mfma_f32_16x16x32_f16 v[32:35], v[122:125], v[110:113], v[32:35]
	ds_read_b128 v[110:113], v23 offset:22528
	s_waitcnt lgkmcnt(1)
	v_mfma_f32_16x16x32_f16 v[98:101], v[62:65], v[90:93], v[98:101]
	s_waitcnt lgkmcnt(0)
	v_mfma_f32_16x16x32_f16 v[52:55], v[62:65], v[110:113], v[52:55]
	global_load_dwordx4 v[62:65], v[0:1], off offset:1408
	v_mfma_f32_16x16x32_f16 v[102:105], v[74:77], v[90:93], v[102:105]
	v_mfma_f32_16x16x32_f16 v[24:27], v[74:77], v[110:113], v[24:27]
	v_mfma_f32_16x16x32_f16 v[114:117], v[118:121], v[90:93], v[114:117]
	v_mfma_f32_16x16x32_f16 v[40:43], v[118:121], v[110:113], v[40:43]
	v_mfma_f32_16x16x32_f16 v[70:73], v[122:125], v[90:93], v[70:73]
	global_load_dwordx4 v[90:93], v[2:3], off offset:1408
	global_load_dwordx4 v[130:133], v[4:5], off offset:1408
	global_load_dwordx4 v[138:141], v[14:15], off offset:1408
	global_load_dwordx4 v[74:77], v[10:11], off offset:1408
	global_load_dwordx4 v[142:145], v[12:13], off offset:1408
	global_load_dwordx4 v[154:157], v[8:9], off offset:1408
	global_load_dwordx4 v[158:161], v[6:7], off offset:1408
	s_waitcnt lgkmcnt(0)
	s_barrier
; #define GL_LOAD(s_, kt_) if (VAR != 1) { a##s_##0 = GL_A(0, kt_); a##s_##1 = GL_A(1, kt_); a##s_##2 = GL_A(2, kt_); a##s_##3 = GL_A(3, kt_); b##s_##0 = GL_B(0, kt_); b##s_##1 = GL_B(1, kt_); b##s_##2 = GL_B(2, kt_); b##s_##3 = GL_B(3, kt_); }
; #define LDS_STORE(s_, buf_) if (VAR != 2) { LDS_ST1(sA, 0, buf_, a##s_##0) LDS_ST1(sA, 1, buf_, a##s_##1) LDS_ST1(sA, 2, buf_, a##s_##2) LDS_ST1(sA, 3, buf_, a##s_##3) LDS_ST1(sB, 0, buf_, b##s_##0) LDS_ST1(sB, 1, buf_, b##s_##1) LDS_ST1(sB, 2, buf_, b##s_##2) LDS_ST1(sB, 3, buf_, b##s_##3) }
;     ...
;   GL_LOAD(0, 0)
;   GL_LOAD(1, 1)
;   LDS_STORE(0, 0)
;   if (VAR != 4) __syncthreads();
; #pragma unroll
;   for (int kt = 0; kt < nk; kt += 2) {
;     if (kt + 2 < nk) { GL_LOAD(0, kt + 2) }
;     MMA_TILE(0)
;     LDS_STORE(1, 1)
;     if (VAR != 4) __syncthreads();
;     if (kt + 3 < nk) { GL_LOAD(1, kt + 3) }
;     MMA_TILE(1)
;     if (kt + 2 < nk) { LDS_STORE(0, 0) }
;     if (VAR != 4) __syncthreads();
	v_mfma_f32_16x16x32_f16 v[48:51], v[122:125], v[110:113], v[48:51]
	ds_read_b128 v[58:61], v16 offset:32768
	ds_read_b128 v[106:109], v21
	s_waitcnt lgkmcnt(0)
	v_mfma_f32_16x16x32_f16 v[36:39], v[58:61], v[106:109], v[36:39]
	ds_read_b128 v[94:97], v16 offset:34816
	ds_read_b128 v[110:113], v21 offset:2048
	s_waitcnt lgkmcnt(0)
	v_mfma_f32_16x16x32_f16 v[66:69], v[58:61], v[110:113], v[66:69]
	ds_read_b128 v[118:121], v16 offset:36864
	v_mfma_f32_16x16x32_f16 v[44:47], v[94:97], v[106:109], v[44:47]
	ds_read_b128 v[122:125], v16 offset:38912
	v_mfma_f32_16x16x32_f16 v[78:81], v[94:97], v[110:113], v[78:81]
	s_waitcnt vmcnt(7)
	ds_write_b128 v17, v[62:65] offset:16384
	s_waitcnt lgkmcnt(2)
	v_mfma_f32_16x16x32_f16 v[82:85], v[118:121], v[106:109], v[82:85]
	s_waitcnt vmcnt(6)
	ds_write_b128 v18, v[90:93] offset:16384
	v_mfma_f32_16x16x32_f16 v[86:89], v[118:121], v[110:113], v[86:89]
	s_waitcnt vmcnt(5)
	ds_write_b128 v19, v[130:133] offset:16384
	s_waitcnt lgkmcnt(3)
	v_mfma_f32_16x16x32_f16 v[28:31], v[122:125], v[106:109], v[28:31]
	ds_read_b128 v[106:109], v21 offset:4096
	v_mfma_f32_16x16x32_f16 v[32:35], v[122:125], v[110:113], v[32:35]
	ds_read_b128 v[110:113], v21 offset:6144
	s_waitcnt lgkmcnt(1)
	v_mfma_f32_16x16x32_f16 v[98:101], v[58:61], v[106:109], v[98:101]
	s_waitcnt vmcnt(4)
	ds_write_b128 v20, v[138:141] offset:16384
	s_waitcnt lgkmcnt(1)
	v_mfma_f32_16x16x32_f16 v[52:55], v[58:61], v[110:113], v[52:55]
	ds_read_b128 v[58:61], v22 offset:32768
	v_mfma_f32_16x16x32_f16 v[102:105], v[94:97], v[106:109], v[102:105]
	s_waitcnt vmcnt(3)
	ds_write_b128 v17, v[74:77] offset:49152
	v_mfma_f32_16x16x32_f16 v[24:27], v[94:97], v[110:113], v[24:27]
	ds_read_b128 v[94:97], v22 offset:34816
	v_mfma_f32_16x16x32_f16 v[114:117], v[118:121], v[106:109], v[114:117]
	s_waitcnt vmcnt(2)
	ds_write_b128 v18, v[142:145] offset:49152
	v_mfma_f32_16x16x32_f16 v[40:43], v[118:121], v[110:113], v[40:43]
	ds_read_b128 v[118:121], v22 offset:36864
	v_mfma_f32_16x16x32_f16 v[70:73], v[122:125], v[106:109], v[70:73]
	ds_read_b128 v[106:109], v23
	v_mfma_f32_16x16x32_f16 v[48:51], v[122:125], v[110:113], v[48:51]
	ds_read_b128 v[110:113], v23 offset:2048
	s_waitcnt lgkmcnt(1)
	v_mfma_f32_16x16x32_f16 v[36:39], v[58:61], v[106:109], v[36:39]
	ds_read_b128 v[122:125], v22 offset:38912
	s_waitcnt lgkmcnt(1)
	v_mfma_f32_16x16x32_f16 v[66:69], v[58:61], v[110:113], v[66:69]
	s_waitcnt vmcnt(1)
	ds_write_b128 v19, v[154:157] offset:49152
	v_mfma_f32_16x16x32_f16 v[44:47], v[94:97], v[106:109], v[44:47]
	s_waitcnt vmcnt(0)
	ds_write_b128 v20, v[158:161] offset:49152
	v_mfma_f32_16x16x32_f16 v[78:81], v[94:97], v[110:113], v[78:81]
	v_mfma_f32_16x16x32_f16 v[82:85], v[118:121], v[106:109], v[82:85]
	v_mfma_f32_16x16x32_f16 v[86:89], v[118:121], v[110:113], v[86:89]
	s_waitcnt lgkmcnt(2)
	v_mfma_f32_16x16x32_f16 v[28:31], v[122:125], v[106:109], v[28:31]
	ds_read_b128 v[106:109], v23 offset:4096
	v_mfma_f32_16x16x32_f16 v[32:35], v[122:125], v[110:113], v[32:35]
	ds_read_b128 v[110:113], v23 offset:6144
	s_waitcnt lgkmcnt(1)
	v_mfma_f32_16x16x32_f16 v[98:101], v[58:61], v[106:109], v[98:101]
	s_waitcnt lgkmcnt(0)
	v_mfma_f32_16x16x32_f16 v[52:55], v[58:61], v[110:113], v[52:55]
	global_load_dwordx4 v[58:61], v[0:1], off offset:1536
	v_mfma_f32_16x16x32_f16 v[102:105], v[94:97], v[106:109], v[102:105]
	v_mfma_f32_16x16x32_f16 v[24:27], v[94:97], v[110:113], v[24:27]
	v_mfma_f32_16x16x32_f16 v[114:117], v[118:121], v[106:109], v[114:117]
	v_mfma_f32_16x16x32_f16 v[40:43], v[118:121], v[110:113], v[40:43]
	v_mfma_f32_16x16x32_f16 v[70:73], v[122:125], v[106:109], v[70:73]
	global_load_dwordx4 v[106:109], v[2:3], off offset:1536
	global_load_dwordx4 v[126:129], v[4:5], off offset:1536
	global_load_dwordx4 v[134:137], v[14:15], off offset:1536
	global_load_dwordx4 v[94:97], v[10:11], off offset:1536
	global_load_dwordx4 v[162:165], v[12:13], off offset:1536
	global_load_dwordx4 v[166:169], v[8:9], off offset:1536
	global_load_dwordx4 v[190:193], v[6:7], off offset:1536
	s_waitcnt lgkmcnt(0)
	s_barrier
	v_mfma_f32_16x16x32_f16 v[48:51], v[122:125], v[110:113], v[48:51]
	ds_read_b128 v[62:65], v16 offset:49152
	ds_read_b128 v[90:93], v21 offset:16384
	s_waitcnt lgkmcnt(0)
	v_mfma_f32_16x16x32_f16 v[36:39], v[62:65], v[90:93], v[36:39]
	ds_read_b128 v[74:77], v16 offset:51200
	ds_read_b128 v[110:113], v21 offset:18432
	s_waitcnt lgkmcnt(0)
	v_mfma_f32_16x16x32_f16 v[66:69], v[62:65], v[110:113], v[66:69]
	ds_read_b128 v[118:121], v16 offset:53248
	v_mfma_f32_16x16x32_f16 v[44:47], v[74:77], v[90:93], v[44:47]
	ds_read_b128 v[122:125], v16 offset:55296
	v_mfma_f32_16x16x32_f16 v[78:81], v[74:77], v[110:113], v[78:81]
	s_waitcnt vmcnt(7)
	ds_write_b128 v17, v[58:61]
	s_waitcnt lgkmcnt(2)
	v_mfma_f32_16x16x32_f16 v[82:85], v[118:121], v[90:93], v[82:85]
	s_waitcnt vmcnt(6)
	ds_write_b128 v18, v[106:109]
	v_mfma_f32_16x16x32_f16 v[86:89], v[118:121], v[110:113], v[86:89]
	s_waitcnt vmcnt(5)
	ds_write_b128 v19, v[126:129]
	s_waitcnt lgkmcnt(3)
	v_mfma_f32_16x16x32_f16 v[28:31], v[122:125], v[90:93], v[28:31]
	ds_read_b128 v[90:93], v21 offset:20480
	v_mfma_f32_16x16x32_f16 v[32:35], v[122:125], v[110:113], v[32:35]
	ds_read_b128 v[110:113], v21 offset:22528
	s_waitcnt lgkmcnt(1)
	v_mfma_f32_16x16x32_f16 v[98:101], v[62:65], v[90:93], v[98:101]
	s_waitcnt vmcnt(4)
	ds_write_b128 v20, v[134:137]
	s_waitcnt lgkmcnt(1)
	v_mfma_f32_16x16x32_f16 v[52:55], v[62:65], v[110:113], v[52:55]
	ds_read_b128 v[62:65], v22 offset:49152
	v_mfma_f32_16x16x32_f16 v[102:105], v[74:77], v[90:93], v[102:105]
	s_waitcnt vmcnt(3)
; #define GL_LOAD(s_, kt_) if (VAR != 1) { a##s_##0 = GL_A(0, kt_); a##s_##1 = GL_A(1, kt_); a##s_##2 = GL_A(2, kt_); a##s_##3 = GL_A(3, kt_); b##s_##0 = GL_B(0, kt_); b##s_##1 = GL_B(1, kt_); b##s_##2 = GL_B(2, kt_); b##s_##3 = GL_B(3, kt_); }
; #define LDS_STORE(s_, buf_) if (VAR != 2) { LDS_ST1(sA, 0, buf_, a##s_##0) LDS_ST1(sA, 1, buf_, a##s_##1) LDS_ST1(sA, 2, buf_, a##s_##2) LDS_ST1(sA, 3, buf_, a##s_##3) LDS_ST1(sB, 0, buf_, b##s_##0) LDS_ST1(sB, 1, buf_, b##s_##1) LDS_ST1(sB, 2, buf_, b##s_##2) LDS_ST1(sB, 3, buf_, b##s_##3) }
;     ...
;   GL_LOAD(0, 0)
;   GL_LOAD(1, 1)
;   LDS_STORE(0, 0)
;   if (VAR != 4) __syncthreads();
; #pragma unroll
;   for (int kt = 0; kt < nk; kt += 2) {
;     if (kt + 2 < nk) { GL_LOAD(0, kt + 2) }
;     MMA_TILE(0)
;     LDS_STORE(1, 1)
;     if (VAR != 4) __syncthreads();
;     if (kt + 3 < nk) { GL_LOAD(1, kt + 3) }
;     MMA_TILE(1)
;     if (kt + 2 < nk) { LDS_STORE(0, 0) }
;     if (VAR != 4) __syncthreads();
	ds_write_b128 v17, v[94:97] offset:32768
	v_mfma_f32_16x16x32_f16 v[24:27], v[74:77], v[110:113], v[24:27]
	ds_read_b128 v[74:77], v22 offset:51200
	v_mfma_f32_16x16x32_f16 v[114:117], v[118:121], v[90:93], v[114:117]
	s_waitcnt vmcnt(2)
	ds_write_b128 v18, v[162:165] offset:32768
	v_mfma_f32_16x16x32_f16 v[40:43], v[118:121], v[110:113], v[40:43]
	ds_read_b128 v[118:121], v22 offset:53248
	v_mfma_f32_16x16x32_f16 v[70:73], v[122:125], v[90:93], v[70:73]
	ds_read_b128 v[90:93], v23 offset:16384
	v_mfma_f32_16x16x32_f16 v[48:51], v[122:125], v[110:113], v[48:51]
	ds_read_b128 v[110:113], v23 offset:18432
	s_waitcnt lgkmcnt(1)
	v_mfma_f32_16x16x32_f16 v[36:39], v[62:65], v[90:93], v[36:39]
	ds_read_b128 v[122:125], v22 offset:55296
	s_waitcnt lgkmcnt(1)
	v_mfma_f32_16x16x32_f16 v[66:69], v[62:65], v[110:113], v[66:69]
	s_waitcnt vmcnt(1)
	ds_write_b128 v19, v[166:169] offset:32768
	v_mfma_f32_16x16x32_f16 v[44:47], v[74:77], v[90:93], v[44:47]
	s_waitcnt vmcnt(0)
	ds_write_b128 v20, v[190:193] offset:32768
	v_mfma_f32_16x16x32_f16 v[78:81], v[74:77], v[110:113], v[78:81]
	v_mfma_f32_16x16x32_f16 v[82:85], v[118:121], v[90:93], v[82:85]
	v_mfma_f32_16x16x32_f16 v[86:89], v[118:121], v[110:113], v[86:89]
	s_waitcnt lgkmcnt(2)
	v_mfma_f32_16x16x32_f16 v[28:31], v[122:125], v[90:93], v[28:31]
	ds_read_b128 v[90:93], v23 offset:20480
	v_mfma_f32_16x16x32_f16 v[32:35], v[122:125], v[110:113], v[32:35]
	ds_read_b128 v[110:113], v23 offset:22528
	s_waitcnt lgkmcnt(1)
	v_mfma_f32_16x16x32_f16 v[98:101], v[62:65], v[90:93], v[98:101]
	s_waitcnt lgkmcnt(0)
	v_mfma_f32_16x16x32_f16 v[52:55], v[62:65], v[110:113], v[52:55]
	global_load_dwordx4 v[62:65], v[0:1], off offset:1664
	v_mfma_f32_16x16x32_f16 v[102:105], v[74:77], v[90:93], v[102:105]
	v_mfma_f32_16x16x32_f16 v[24:27], v[74:77], v[110:113], v[24:27]
	v_mfma_f32_16x16x32_f16 v[114:117], v[118:121], v[90:93], v[114:117]
	v_mfma_f32_16x16x32_f16 v[40:43], v[118:121], v[110:113], v[40:43]
	v_mfma_f32_16x16x32_f16 v[70:73], v[122:125], v[90:93], v[70:73]
	global_load_dwordx4 v[90:93], v[2:3], off offset:1664
	global_load_dwordx4 v[130:133], v[4:5], off offset:1664
	global_load_dwordx4 v[138:141], v[14:15], off offset:1664
	global_load_dwordx4 v[74:77], v[10:11], off offset:1664
	global_load_dwordx4 v[142:145], v[12:13], off offset:1664
	global_load_dwordx4 v[154:157], v[8:9], off offset:1664
	global_load_dwordx4 v[158:161], v[6:7], off offset:1664
	s_waitcnt lgkmcnt(0)
	s_barrier
	v_mfma_f32_16x16x32_f16 v[48:51], v[122:125], v[110:113], v[48:51]
	ds_read_b128 v[58:61], v16 offset:32768
	ds_read_b128 v[106:109], v21
	s_waitcnt lgkmcnt(0)
	v_mfma_f32_16x16x32_f16 v[36:39], v[58:61], v[106:109], v[36:39]
	ds_read_b128 v[94:97], v16 offset:34816
	ds_read_b128 v[110:113], v21 offset:2048
	s_waitcnt lgkmcnt(0)
	v_mfma_f32_16x16x32_f16 v[66:69], v[58:61], v[110:113], v[66:69]
	ds_read_b128 v[118:121], v16 offset:36864
	v_mfma_f32_16x16x32_f16 v[44:47], v[94:97], v[106:109], v[44:47]
	ds_read_b128 v[122:125], v16 offset:38912
	v_mfma_f32_16x16x32_f16 v[78:81], v[94:97], v[110:113], v[78:81]
	s_waitcnt vmcnt(7)
	ds_write_b128 v17, v[62:65] offset:16384
	s_waitcnt lgkmcnt(2)
	v_mfma_f32_16x16x32_f16 v[82:85], v[118:121], v[106:109], v[82:85]
	s_waitcnt vmcnt(6)
	ds_write_b128 v18, v[90:93] offset:16384
	v_mfma_f32_16x16x32_f16 v[86:89], v[118:121], v[110:113], v[86:89]
	s_waitcnt vmcnt(5)
	ds_write_b128 v19, v[130:133] offset:16384
	s_waitcnt lgkmcnt(3)
	v_mfma_f32_16x16x32_f16 v[28:31], v[122:125], v[106:109], v[28:31]
	ds_read_b128 v[106:109], v21 offset:4096
	v_mfma_f32_16x16x32_f16 v[32:35], v[122:125], v[110:113], v[32:35]
	ds_read_b128 v[110:113], v21 offset:6144
	s_waitcnt lgkmcnt(1)
	v_mfma_f32_16x16x32_f16 v[98:101], v[58:61], v[106:109], v[98:101]
	s_waitcnt vmcnt(4)
	ds_write_b128 v20, v[138:141] offset:16384
	s_waitcnt lgkmcnt(1)
	v_mfma_f32_16x16x32_f16 v[52:55], v[58:61], v[110:113], v[52:55]
	ds_read_b128 v[58:61], v22 offset:32768
	v_mfma_f32_16x16x32_f16 v[102:105], v[94:97], v[106:109], v[102:105]
	s_waitcnt vmcnt(3)
	ds_write_b128 v17, v[74:77] offset:49152
	v_mfma_f32_16x16x32_f16 v[24:27], v[94:97], v[110:113], v[24:27]
	ds_read_b128 v[94:97], v22 offset:34816
	v_mfma_f32_16x16x32_f16 v[114:117], v[118:121], v[106:109], v[114:117]
	s_waitcnt vmcnt(2)
	ds_write_b128 v18, v[142:145] offset:49152
	v_mfma_f32_16x16x32_f16 v[40:43], v[118:121], v[110:113], v[40:43]
	ds_read_b128 v[118:121], v22 offset:36864
	v_mfma_f32_16x16x32_f16 v[70:73], v[122:125], v[106:109], v[70:73]
	ds_read_b128 v[106:109], v23
	v_mfma_f32_16x16x32_f16 v[48:51], v[122:125], v[110:113], v[48:51]
	ds_read_b128 v[110:113], v23 offset:2048
	s_waitcnt lgkmcnt(1)
	v_mfma_f32_16x16x32_f16 v[36:39], v[58:61], v[106:109], v[36:39]
	ds_read_b128 v[122:125], v22 offset:38912
	s_waitcnt lgkmcnt(1)
	v_mfma_f32_16x16x32_f16 v[66:69], v[58:61], v[110:113], v[66:69]
	s_waitcnt vmcnt(1)
	ds_write_b128 v19, v[154:157] offset:49152
	v_mfma_f32_16x16x32_f16 v[44:47], v[94:97], v[106:109], v[44:47]
	s_waitcnt vmcnt(0)
	ds_write_b128 v20, v[158:161] offset:49152
	v_mfma_f32_16x16x32_f16 v[78:81], v[94:97], v[110:113], v[78:81]
	v_mfma_f32_16x16x32_f16 v[82:85], v[118:121], v[106:109], v[82:85]
	v_mfma_f32_16x16x32_f16 v[86:89], v[118:121], v[110:113], v[86:89]
	s_waitcnt lgkmcnt(2)
	v_mfma_f32_16x16x32_f16 v[28:31], v[122:125], v[106:109], v[28:31]
	ds_read_b128 v[106:109], v23 offset:4096
	v_mfma_f32_16x16x32_f16 v[32:35], v[122:125], v[110:113], v[32:35]
	ds_read_b128 v[110:113], v23 offset:6144
	s_waitcnt lgkmcnt(1)
	v_mfma_f32_16x16x32_f16 v[98:101], v[58:61], v[106:109], v[98:101]
	s_waitcnt lgkmcnt(0)
	v_mfma_f32_16x16x32_f16 v[52:55], v[58:61], v[110:113], v[52:55]
	global_load_dwordx4 v[58:61], v[0:1], off offset:1792
	v_mfma_f32_16x16x32_f16 v[102:105], v[94:97], v[106:109], v[102:105]
	v_mfma_f32_16x16x32_f16 v[24:27], v[94:97], v[110:113], v[24:27]
	v_mfma_f32_16x16x32_f16 v[114:117], v[118:121], v[106:109], v[114:117]
	v_mfma_f32_16x16x32_f16 v[40:43], v[118:121], v[110:113], v[40:43]
	v_mfma_f32_16x16x32_f16 v[70:73], v[122:125], v[106:109], v[70:73]
	global_load_dwordx4 v[106:109], v[2:3], off offset:1792
	global_load_dwordx4 v[126:129], v[4:5], off offset:1792
	global_load_dwordx4 v[134:137], v[14:15], off offset:1792
	global_load_dwordx4 v[94:97], v[10:11], off offset:1792
	global_load_dwordx4 v[162:165], v[12:13], off offset:1792
	global_load_dwordx4 v[166:169], v[8:9], off offset:1792
	global_load_dwordx4 v[190:193], v[6:7], off offset:1792
	s_waitcnt lgkmcnt(0)
	s_barrier
; #define GL_LOAD(s_, kt_) if (VAR != 1) { a##s_##0 = GL_A(0, kt_); a##s_##1 = GL_A(1, kt_); a##s_##2 = GL_A(2, kt_); a##s_##3 = GL_A(3, kt_); b##s_##0 = GL_B(0, kt_); b##s_##1 = GL_B(1, kt_); b##s_##2 = GL_B(2, kt_); b##s_##3 = GL_B(3, kt_); }
; #define LDS_STORE(s_, buf_) if (VAR != 2) { LDS_ST1(sA, 0, buf_, a##s_##0) LDS_ST1(sA, 1, buf_, a##s_##1) LDS_ST1(sA, 2, buf_, a##s_##2) LDS_ST1(sA, 3, buf_, a##s_##3) LDS_ST1(sB, 0, buf_, b##s_##0) LDS_ST1(sB, 1, buf_, b##s_##1) LDS_ST1(sB, 2, buf_, b##s_##2) LDS_ST1(sB, 3, buf_, b##s_##3) }
;     ...
;   GL_LOAD(0, 0)
;   GL_LOAD(1, 1)
;   LDS_STORE(0, 0)
;   if (VAR != 4) __syncthreads();
; #pragma unroll
;   for (int kt = 0; kt < nk; kt += 2) {
;     if (kt + 2 < nk) { GL_LOAD(0, kt + 2) }
;     MMA_TILE(0)
;     LDS_STORE(1, 1)
;     if (VAR != 4) __syncthreads();
;     if (kt + 3 < nk) { GL_LOAD(1, kt + 3) }
;     MMA_TILE(1)
;     if (kt + 2 < nk) { LDS_STORE(0, 0) }
;     if (VAR != 4) __syncthreads();
	v_mfma_f32_16x16x32_f16 v[48:51], v[122:125], v[110:113], v[48:51]
	ds_read_b128 v[62:65], v16 offset:49152
	ds_read_b128 v[90:93], v21 offset:16384
	s_waitcnt lgkmcnt(0)
	v_mfma_f32_16x16x32_f16 v[36:39], v[62:65], v[90:93], v[36:39]
	ds_read_b128 v[74:77], v16 offset:51200
	ds_read_b128 v[110:113], v21 offset:18432
	s_waitcnt lgkmcnt(0)
	v_mfma_f32_16x16x32_f16 v[66:69], v[62:65], v[110:113], v[66:69]
	ds_read_b128 v[118:121], v16 offset:53248
	v_mfma_f32_16x16x32_f16 v[44:47], v[74:77], v[90:93], v[44:47]
	ds_read_b128 v[122:125], v16 offset:55296
	v_mfma_f32_16x16x32_f16 v[78:81], v[74:77], v[110:113], v[78:81]
	s_waitcnt vmcnt(7)
	ds_write_b128 v17, v[58:61]
	s_waitcnt lgkmcnt(2)
	v_mfma_f32_16x16x32_f16 v[82:85], v[118:121], v[90:93], v[82:85]
	s_waitcnt vmcnt(6)
	ds_write_b128 v18, v[106:109]
	v_mfma_f32_16x16x32_f16 v[86:89], v[118:121], v[110:113], v[86:89]
	s_waitcnt vmcnt(5)
	ds_write_b128 v19, v[126:129]
	s_waitcnt lgkmcnt(3)
	v_mfma_f32_16x16x32_f16 v[28:31], v[122:125], v[90:93], v[28:31]
	ds_read_b128 v[90:93], v21 offset:20480
	v_mfma_f32_16x16x32_f16 v[32:35], v[122:125], v[110:113], v[32:35]
	ds_read_b128 v[110:113], v21 offset:22528
	s_waitcnt lgkmcnt(1)
	v_mfma_f32_16x16x32_f16 v[98:101], v[62:65], v[90:93], v[98:101]
	s_waitcnt vmcnt(4)
	ds_write_b128 v20, v[134:137]
	s_waitcnt lgkmcnt(1)
	v_mfma_f32_16x16x32_f16 v[52:55], v[62:65], v[110:113], v[52:55]
	ds_read_b128 v[62:65], v22 offset:49152
	v_mfma_f32_16x16x32_f16 v[102:105], v[74:77], v[90:93], v[102:105]
	s_waitcnt vmcnt(3)
	ds_write_b128 v17, v[94:97] offset:32768
	v_mfma_f32_16x16x32_f16 v[24:27], v[74:77], v[110:113], v[24:27]
	ds_read_b128 v[74:77], v22 offset:51200
	v_mfma_f32_16x16x32_f16 v[114:117], v[118:121], v[90:93], v[114:117]
	s_waitcnt vmcnt(2)
	ds_write_b128 v18, v[162:165] offset:32768
	v_mfma_f32_16x16x32_f16 v[40:43], v[118:121], v[110:113], v[40:43]
	ds_read_b128 v[118:121], v22 offset:53248
	v_mfma_f32_16x16x32_f16 v[70:73], v[122:125], v[90:93], v[70:73]
	ds_read_b128 v[90:93], v23 offset:16384
	v_mfma_f32_16x16x32_f16 v[48:51], v[122:125], v[110:113], v[48:51]
	ds_read_b128 v[110:113], v23 offset:18432
	s_waitcnt lgkmcnt(1)
	v_mfma_f32_16x16x32_f16 v[36:39], v[62:65], v[90:93], v[36:39]
	ds_read_b128 v[122:125], v22 offset:55296
	s_waitcnt lgkmcnt(1)
	v_mfma_f32_16x16x32_f16 v[66:69], v[62:65], v[110:113], v[66:69]
	s_waitcnt vmcnt(1)
	ds_write_b128 v19, v[166:169] offset:32768
	v_mfma_f32_16x16x32_f16 v[44:47], v[74:77], v[90:93], v[44:47]
	s_waitcnt vmcnt(0)
	ds_write_b128 v20, v[190:193] offset:32768
	v_mfma_f32_16x16x32_f16 v[78:81], v[74:77], v[110:113], v[78:81]
	v_mfma_f32_16x16x32_f16 v[82:85], v[118:121], v[90:93], v[82:85]
	v_mfma_f32_16x16x32_f16 v[86:89], v[118:121], v[110:113], v[86:89]
	s_waitcnt lgkmcnt(2)
	v_mfma_f32_16x16x32_f16 v[28:31], v[122:125], v[90:93], v[28:31]
	ds_read_b128 v[90:93], v23 offset:20480
	v_mfma_f32_16x16x32_f16 v[32:35], v[122:125], v[110:113], v[32:35]
	ds_read_b128 v[110:113], v23 offset:22528
	s_waitcnt lgkmcnt(1)
	v_mfma_f32_16x16x32_f16 v[98:101], v[62:65], v[90:93], v[98:101]
	s_waitcnt lgkmcnt(0)
	v_mfma_f32_16x16x32_f16 v[52:55], v[62:65], v[110:113], v[52:55]
	global_load_dwordx4 v[62:65], v[0:1], off offset:1920
	v_mfma_f32_16x16x32_f16 v[102:105], v[74:77], v[90:93], v[102:105]
	v_mfma_f32_16x16x32_f16 v[24:27], v[74:77], v[110:113], v[24:27]
	v_mfma_f32_16x16x32_f16 v[114:117], v[118:121], v[90:93], v[114:117]
	v_mfma_f32_16x16x32_f16 v[40:43], v[118:121], v[110:113], v[40:43]
	v_mfma_f32_16x16x32_f16 v[70:73], v[122:125], v[90:93], v[70:73]
	global_load_dwordx4 v[90:93], v[2:3], off offset:1920
	global_load_dwordx4 v[130:133], v[4:5], off offset:1920
	global_load_dwordx4 v[138:141], v[14:15], off offset:1920
	global_load_dwordx4 v[74:77], v[10:11], off offset:1920
	global_load_dwordx4 v[142:145], v[12:13], off offset:1920
	global_load_dwordx4 v[154:157], v[8:9], off offset:1920
	global_load_dwordx4 v[158:161], v[6:7], off offset:1920
	s_waitcnt lgkmcnt(0)
	s_barrier
	v_mfma_f32_16x16x32_f16 v[48:51], v[122:125], v[110:113], v[48:51]
	ds_read_b128 v[58:61], v16 offset:32768
	ds_read_b128 v[106:109], v21
	s_waitcnt lgkmcnt(0)
	v_mfma_f32_16x16x32_f16 v[36:39], v[58:61], v[106:109], v[36:39]
	ds_read_b128 v[94:97], v16 offset:34816
	ds_read_b128 v[110:113], v21 offset:2048
	s_waitcnt lgkmcnt(0)
	v_mfma_f32_16x16x32_f16 v[66:69], v[58:61], v[110:113], v[66:69]
	ds_read_b128 v[118:121], v16 offset:36864
	v_mfma_f32_16x16x32_f16 v[44:47], v[94:97], v[106:109], v[44:47]
	ds_read_b128 v[122:125], v16 offset:38912
	v_mfma_f32_16x16x32_f16 v[78:81], v[94:97], v[110:113], v[78:81]
	s_waitcnt vmcnt(7)
	ds_write_b128 v17, v[62:65] offset:16384
	s_waitcnt lgkmcnt(2)
	v_mfma_f32_16x16x32_f16 v[82:85], v[118:121], v[106:109], v[82:85]
	s_waitcnt vmcnt(6)
	ds_write_b128 v18, v[90:93] offset:16384
	v_mfma_f32_16x16x32_f16 v[86:89], v[118:121], v[110:113], v[86:89]
	s_waitcnt vmcnt(5)
	ds_write_b128 v19, v[130:133] offset:16384
	s_waitcnt lgkmcnt(3)
	v_mfma_f32_16x16x32_f16 v[28:31], v[122:125], v[106:109], v[28:31]
	ds_read_b128 v[106:109], v21 offset:4096
	v_mfma_f32_16x16x32_f16 v[32:35], v[122:125], v[110:113], v[32:35]
	ds_read_b128 v[110:113], v21 offset:6144
	s_waitcnt lgkmcnt(1)
	v_mfma_f32_16x16x32_f16 v[98:101], v[58:61], v[106:109], v[98:101]
	s_waitcnt vmcnt(4)
	ds_write_b128 v20, v[138:141] offset:16384
	s_waitcnt lgkmcnt(1)
	v_mfma_f32_16x16x32_f16 v[52:55], v[58:61], v[110:113], v[52:55]
	ds_read_b128 v[58:61], v22 offset:32768
	v_mfma_f32_16x16x32_f16 v[102:105], v[94:97], v[106:109], v[102:105]
	s_waitcnt vmcnt(3)
; #define GL_LOAD(s_, kt_) if (VAR != 1) { a##s_##0 = GL_A(0, kt_); a##s_##1 = GL_A(1, kt_); a##s_##2 = GL_A(2, kt_); a##s_##3 = GL_A(3, kt_); b##s_##0 = GL_B(0, kt_); b##s_##1 = GL_B(1, kt_); b##s_##2 = GL_B(2, kt_); b##s_##3 = GL_B(3, kt_); }
; #define LDS_STORE(s_, buf_) if (VAR != 2) { LDS_ST1(sA, 0, buf_, a##s_##0) LDS_ST1(sA, 1, buf_, a##s_##1) LDS_ST1(sA, 2, buf_, a##s_##2) LDS_ST1(sA, 3, buf_, a##s_##3) LDS_ST1(sB, 0, buf_, b##s_##0) LDS_ST1(sB, 1, buf_, b##s_##1) LDS_ST1(sB, 2, buf_, b##s_##2) LDS_ST1(sB, 3, buf_, b##s_##3) }
;     ...
;   GL_LOAD(0, 0)
;   GL_LOAD(1, 1)
;   LDS_STORE(0, 0)
;   if (VAR != 4) __syncthreads();
; #pragma unroll
;   for (int kt = 0; kt < nk; kt += 2) {
;     if (kt + 2 < nk) { GL_LOAD(0, kt + 2) }
;     MMA_TILE(0)
;     LDS_STORE(1, 1)
;     if (VAR != 4) __syncthreads();
;     if (kt + 3 < nk) { GL_LOAD(1, kt + 3) }
;     MMA_TILE(1)
;     if (kt + 2 < nk) { LDS_STORE(0, 0) }
;     if (VAR != 4) __syncthreads();
	ds_write_b128 v17, v[74:77] offset:49152
	v_mfma_f32_16x16x32_f16 v[24:27], v[94:97], v[110:113], v[24:27]
	ds_read_b128 v[94:97], v22 offset:34816
	v_mfma_f32_16x16x32_f16 v[114:117], v[118:121], v[106:109], v[114:117]
	s_waitcnt vmcnt(2)
	ds_write_b128 v18, v[142:145] offset:49152
	v_mfma_f32_16x16x32_f16 v[40:43], v[118:121], v[110:113], v[40:43]
	ds_read_b128 v[118:121], v22 offset:36864
	v_mfma_f32_16x16x32_f16 v[70:73], v[122:125], v[106:109], v[70:73]
	ds_read_b128 v[106:109], v23
	v_mfma_f32_16x16x32_f16 v[48:51], v[122:125], v[110:113], v[48:51]
	ds_read_b128 v[110:113], v23 offset:2048
	s_waitcnt lgkmcnt(1)
	v_mfma_f32_16x16x32_f16 v[36:39], v[58:61], v[106:109], v[36:39]
	ds_read_b128 v[122:125], v22 offset:38912
	s_waitcnt lgkmcnt(1)
	v_mfma_f32_16x16x32_f16 v[66:69], v[58:61], v[110:113], v[66:69]
	s_waitcnt vmcnt(1)
	ds_write_b128 v19, v[154:157] offset:49152
	v_mfma_f32_16x16x32_f16 v[44:47], v[94:97], v[106:109], v[44:47]
	s_waitcnt vmcnt(0)
	ds_write_b128 v20, v[158:161] offset:49152
	v_mfma_f32_16x16x32_f16 v[78:81], v[94:97], v[110:113], v[78:81]
	v_mfma_f32_16x16x32_f16 v[82:85], v[118:121], v[106:109], v[82:85]
	v_mfma_f32_16x16x32_f16 v[86:89], v[118:121], v[110:113], v[86:89]
	s_waitcnt lgkmcnt(2)
	v_mfma_f32_16x16x32_f16 v[28:31], v[122:125], v[106:109], v[28:31]
	ds_read_b128 v[106:109], v23 offset:4096
	v_mfma_f32_16x16x32_f16 v[32:35], v[122:125], v[110:113], v[32:35]
	ds_read_b128 v[110:113], v23 offset:6144
	s_waitcnt lgkmcnt(1)
	v_mfma_f32_16x16x32_f16 v[98:101], v[58:61], v[106:109], v[98:101]
	s_waitcnt lgkmcnt(0)
	v_mfma_f32_16x16x32_f16 v[52:55], v[58:61], v[110:113], v[52:55]
	global_load_dwordx4 v[58:61], v[0:1], off offset:2048
	v_mfma_f32_16x16x32_f16 v[102:105], v[94:97], v[106:109], v[102:105]
	v_mfma_f32_16x16x32_f16 v[24:27], v[94:97], v[110:113], v[24:27]
	v_mfma_f32_16x16x32_f16 v[114:117], v[118:121], v[106:109], v[114:117]
	v_mfma_f32_16x16x32_f16 v[40:43], v[118:121], v[110:113], v[40:43]
	v_mfma_f32_16x16x32_f16 v[70:73], v[122:125], v[106:109], v[70:73]
	global_load_dwordx4 v[106:109], v[2:3], off offset:2048
	global_load_dwordx4 v[126:129], v[4:5], off offset:2048
	global_load_dwordx4 v[134:137], v[14:15], off offset:2048
	global_load_dwordx4 v[94:97], v[10:11], off offset:2048
	global_load_dwordx4 v[162:165], v[12:13], off offset:2048
	global_load_dwordx4 v[166:169], v[8:9], off offset:2048
	global_load_dwordx4 v[190:193], v[6:7], off offset:2048
	s_waitcnt lgkmcnt(0)
	s_barrier
	v_mfma_f32_16x16x32_f16 v[48:51], v[122:125], v[110:113], v[48:51]
	ds_read_b128 v[62:65], v16 offset:49152
	ds_read_b128 v[90:93], v21 offset:16384
	s_waitcnt lgkmcnt(0)
	v_mfma_f32_16x16x32_f16 v[36:39], v[62:65], v[90:93], v[36:39]
	ds_read_b128 v[74:77], v16 offset:51200
	ds_read_b128 v[110:113], v21 offset:18432
	s_waitcnt lgkmcnt(0)
	v_mfma_f32_16x16x32_f16 v[66:69], v[62:65], v[110:113], v[66:69]
	ds_read_b128 v[118:121], v16 offset:53248
	v_mfma_f32_16x16x32_f16 v[44:47], v[74:77], v[90:93], v[44:47]
	ds_read_b128 v[122:125], v16 offset:55296
	v_mfma_f32_16x16x32_f16 v[78:81], v[74:77], v[110:113], v[78:81]
	s_waitcnt vmcnt(7)
	ds_write_b128 v17, v[58:61]
	s_waitcnt lgkmcnt(2)
	v_mfma_f32_16x16x32_f16 v[82:85], v[118:121], v[90:93], v[82:85]
	s_waitcnt vmcnt(6)
	ds_write_b128 v18, v[106:109]
	v_mfma_f32_16x16x32_f16 v[86:89], v[118:121], v[110:113], v[86:89]
	s_waitcnt vmcnt(5)
	ds_write_b128 v19, v[126:129]
	s_waitcnt lgkmcnt(3)
	v_mfma_f32_16x16x32_f16 v[28:31], v[122:125], v[90:93], v[28:31]
	ds_read_b128 v[90:93], v21 offset:20480
	v_mfma_f32_16x16x32_f16 v[32:35], v[122:125], v[110:113], v[32:35]
	ds_read_b128 v[110:113], v21 offset:22528
	s_waitcnt lgkmcnt(1)
	v_mfma_f32_16x16x32_f16 v[98:101], v[62:65], v[90:93], v[98:101]
	s_waitcnt vmcnt(4)
	ds_write_b128 v20, v[134:137]
	s_waitcnt lgkmcnt(1)
	v_mfma_f32_16x16x32_f16 v[52:55], v[62:65], v[110:113], v[52:55]
	ds_read_b128 v[62:65], v22 offset:49152
	v_mfma_f32_16x16x32_f16 v[102:105], v[74:77], v[90:93], v[102:105]
	s_waitcnt vmcnt(3)
	ds_write_b128 v17, v[94:97] offset:32768
	v_mfma_f32_16x16x32_f16 v[24:27], v[74:77], v[110:113], v[24:27]
	ds_read_b128 v[74:77], v22 offset:51200
	v_mfma_f32_16x16x32_f16 v[114:117], v[118:121], v[90:93], v[114:117]
	s_waitcnt vmcnt(2)
	ds_write_b128 v18, v[162:165] offset:32768
	v_mfma_f32_16x16x32_f16 v[40:43], v[118:121], v[110:113], v[40:43]
	ds_read_b128 v[118:121], v22 offset:53248
	v_mfma_f32_16x16x32_f16 v[70:73], v[122:125], v[90:93], v[70:73]
	ds_read_b128 v[90:93], v23 offset:16384
	v_mfma_f32_16x16x32_f16 v[48:51], v[122:125], v[110:113], v[48:51]
	ds_read_b128 v[110:113], v23 offset:18432
	s_waitcnt lgkmcnt(1)
	v_mfma_f32_16x16x32_f16 v[36:39], v[62:65], v[90:93], v[36:39]
	ds_read_b128 v[122:125], v22 offset:55296
	s_waitcnt lgkmcnt(1)
	v_mfma_f32_16x16x32_f16 v[66:69], v[62:65], v[110:113], v[66:69]
	s_waitcnt vmcnt(1)
	ds_write_b128 v19, v[166:169] offset:32768
	v_mfma_f32_16x16x32_f16 v[44:47], v[74:77], v[90:93], v[44:47]
	s_waitcnt vmcnt(0)
	ds_write_b128 v20, v[190:193] offset:32768
	v_mfma_f32_16x16x32_f16 v[78:81], v[74:77], v[110:113], v[78:81]
	v_mfma_f32_16x16x32_f16 v[82:85], v[118:121], v[90:93], v[82:85]
	v_mfma_f32_16x16x32_f16 v[86:89], v[118:121], v[110:113], v[86:89]
	s_waitcnt lgkmcnt(2)
	v_mfma_f32_16x16x32_f16 v[28:31], v[122:125], v[90:93], v[28:31]
	ds_read_b128 v[90:93], v23 offset:20480
	v_mfma_f32_16x16x32_f16 v[32:35], v[122:125], v[110:113], v[32:35]
	ds_read_b128 v[110:113], v23 offset:22528
	s_waitcnt lgkmcnt(1)
	v_mfma_f32_16x16x32_f16 v[98:101], v[62:65], v[90:93], v[98:101]
	s_waitcnt lgkmcnt(0)
	v_mfma_f32_16x16x32_f16 v[52:55], v[62:65], v[110:113], v[52:55]
	global_load_dwordx4 v[62:65], v[0:1], off offset:2176
	v_mfma_f32_16x16x32_f16 v[102:105], v[74:77], v[90:93], v[102:105]
	v_mfma_f32_16x16x32_f16 v[24:27], v[74:77], v[110:113], v[24:27]
	v_mfma_f32_16x16x32_f16 v[114:117], v[118:121], v[90:93], v[114:117]
	v_mfma_f32_16x16x32_f16 v[40:43], v[118:121], v[110:113], v[40:43]
	v_mfma_f32_16x16x32_f16 v[70:73], v[122:125], v[90:93], v[70:73]
	global_load_dwordx4 v[90:93], v[2:3], off offset:2176
	global_load_dwordx4 v[130:133], v[4:5], off offset:2176
	global_load_dwordx4 v[138:141], v[14:15], off offset:2176
	global_load_dwordx4 v[74:77], v[10:11], off offset:2176
	global_load_dwordx4 v[142:145], v[12:13], off offset:2176
	global_load_dwordx4 v[154:157], v[8:9], off offset:2176
	global_load_dwordx4 v[158:161], v[6:7], off offset:2176
	s_waitcnt lgkmcnt(0)
	s_barrier
; #define GL_LOAD(s_, kt_) if (VAR != 1) { a##s_##0 = GL_A(0, kt_); a##s_##1 = GL_A(1, kt_); a##s_##2 = GL_A(2, kt_); a##s_##3 = GL_A(3, kt_); b##s_##0 = GL_B(0, kt_); b##s_##1 = GL_B(1, kt_); b##s_##2 = GL_B(2, kt_); b##s_##3 = GL_B(3, kt_); }
; #define LDS_STORE(s_, buf_) if (VAR != 2) { LDS_ST1(sA, 0, buf_, a##s_##0) LDS_ST1(sA, 1, buf_, a##s_##1) LDS_ST1(sA, 2, buf_, a##s_##2) LDS_ST1(sA, 3, buf_, a##s_##3) LDS_ST1(sB, 0, buf_, b##s_##0) LDS_ST1(sB, 1, buf_, b##s_##1) LDS_ST1(sB, 2, buf_, b##s_##2) LDS_ST1(sB, 3, buf_, b##s_##3) }
;     ...
;   GL_LOAD(0, 0)
;   GL_LOAD(1, 1)
;   LDS_STORE(0, 0)
;   if (VAR != 4) __syncthreads();
; #pragma unroll
;   for (int kt = 0; kt < nk; kt += 2) {
;     if (kt + 2 < nk) { GL_LOAD(0, kt + 2) }
;     MMA_TILE(0)
;     LDS_STORE(1, 1)
;     if (VAR != 4) __syncthreads();
;     if (kt + 3 < nk) { GL_LOAD(1, kt + 3) }
;     MMA_TILE(1)
;     if (kt + 2 < nk) { LDS_STORE(0, 0) }
;     if (VAR != 4) __syncthreads();
	v_mfma_f32_16x16x32_f16 v[48:51], v[122:125], v[110:113], v[48:51]
	ds_read_b128 v[58:61], v16 offset:32768
	ds_read_b128 v[106:109], v21
	s_waitcnt lgkmcnt(0)
	v_mfma_f32_16x16x32_f16 v[36:39], v[58:61], v[106:109], v[36:39]
	ds_read_b128 v[94:97], v16 offset:34816
	ds_read_b128 v[110:113], v21 offset:2048
	s_waitcnt lgkmcnt(0)
	v_mfma_f32_16x16x32_f16 v[66:69], v[58:61], v[110:113], v[66:69]
	ds_read_b128 v[118:121], v16 offset:36864
	v_mfma_f32_16x16x32_f16 v[44:47], v[94:97], v[106:109], v[44:47]
	ds_read_b128 v[122:125], v16 offset:38912
	v_mfma_f32_16x16x32_f16 v[78:81], v[94:97], v[110:113], v[78:81]
	s_waitcnt vmcnt(7)
	ds_write_b128 v17, v[62:65] offset:16384
	s_waitcnt lgkmcnt(2)
	v_mfma_f32_16x16x32_f16 v[82:85], v[118:121], v[106:109], v[82:85]
	s_waitcnt vmcnt(6)
	ds_write_b128 v18, v[90:93] offset:16384
	v_mfma_f32_16x16x32_f16 v[86:89], v[118:121], v[110:113], v[86:89]
	s_waitcnt vmcnt(5)
	ds_write_b128 v19, v[130:133] offset:16384
	s_waitcnt lgkmcnt(3)
	v_mfma_f32_16x16x32_f16 v[28:31], v[122:125], v[106:109], v[28:31]
	ds_read_b128 v[106:109], v21 offset:4096
	v_mfma_f32_16x16x32_f16 v[32:35], v[122:125], v[110:113], v[32:35]
	ds_read_b128 v[110:113], v21 offset:6144
	s_waitcnt lgkmcnt(1)
	v_mfma_f32_16x16x32_f16 v[98:101], v[58:61], v[106:109], v[98:101]
	s_waitcnt vmcnt(4)
	ds_write_b128 v20, v[138:141] offset:16384
	s_waitcnt lgkmcnt(1)
	v_mfma_f32_16x16x32_f16 v[52:55], v[58:61], v[110:113], v[52:55]
	ds_read_b128 v[58:61], v22 offset:32768
	v_mfma_f32_16x16x32_f16 v[102:105], v[94:97], v[106:109], v[102:105]
	s_waitcnt vmcnt(3)
	ds_write_b128 v17, v[74:77] offset:49152
	v_mfma_f32_16x16x32_f16 v[24:27], v[94:97], v[110:113], v[24:27]
	ds_read_b128 v[94:97], v22 offset:34816
	v_mfma_f32_16x16x32_f16 v[114:117], v[118:121], v[106:109], v[114:117]
	s_waitcnt vmcnt(2)
	ds_write_b128 v18, v[142:145] offset:49152
	v_mfma_f32_16x16x32_f16 v[40:43], v[118:121], v[110:113], v[40:43]
	ds_read_b128 v[118:121], v22 offset:36864
	v_mfma_f32_16x16x32_f16 v[70:73], v[122:125], v[106:109], v[70:73]
	ds_read_b128 v[106:109], v23
	v_mfma_f32_16x16x32_f16 v[48:51], v[122:125], v[110:113], v[48:51]
	ds_read_b128 v[110:113], v23 offset:2048
	s_waitcnt lgkmcnt(1)
	v_mfma_f32_16x16x32_f16 v[36:39], v[58:61], v[106:109], v[36:39]
	ds_read_b128 v[122:125], v22 offset:38912
	s_waitcnt lgkmcnt(1)
	v_mfma_f32_16x16x32_f16 v[66:69], v[58:61], v[110:113], v[66:69]
	s_waitcnt vmcnt(1)
	ds_write_b128 v19, v[154:157] offset:49152
	v_mfma_f32_16x16x32_f16 v[44:47], v[94:97], v[106:109], v[44:47]
	s_waitcnt vmcnt(0)
	ds_write_b128 v20, v[158:161] offset:49152
	v_mfma_f32_16x16x32_f16 v[78:81], v[94:97], v[110:113], v[78:81]
	v_mfma_f32_16x16x32_f16 v[82:85], v[118:121], v[106:109], v[82:85]
	v_mfma_f32_16x16x32_f16 v[86:89], v[118:121], v[110:113], v[86:89]
	s_waitcnt lgkmcnt(2)
	v_mfma_f32_16x16x32_f16 v[28:31], v[122:125], v[106:109], v[28:31]
	ds_read_b128 v[106:109], v23 offset:4096
	v_mfma_f32_16x16x32_f16 v[32:35], v[122:125], v[110:113], v[32:35]
	ds_read_b128 v[110:113], v23 offset:6144
	s_waitcnt lgkmcnt(1)
	v_mfma_f32_16x16x32_f16 v[98:101], v[58:61], v[106:109], v[98:101]
	s_waitcnt lgkmcnt(0)
	v_mfma_f32_16x16x32_f16 v[52:55], v[58:61], v[110:113], v[52:55]
	global_load_dwordx4 v[58:61], v[0:1], off offset:2304
	v_mfma_f32_16x16x32_f16 v[102:105], v[94:97], v[106:109], v[102:105]
	v_mfma_f32_16x16x32_f16 v[24:27], v[94:97], v[110:113], v[24:27]
	v_mfma_f32_16x16x32_f16 v[114:117], v[118:121], v[106:109], v[114:117]
	v_mfma_f32_16x16x32_f16 v[40:43], v[118:121], v[110:113], v[40:43]
	v_mfma_f32_16x16x32_f16 v[70:73], v[122:125], v[106:109], v[70:73]
	global_load_dwordx4 v[106:109], v[2:3], off offset:2304
	global_load_dwordx4 v[126:129], v[4:5], off offset:2304
	global_load_dwordx4 v[134:137], v[14:15], off offset:2304
	global_load_dwordx4 v[94:97], v[10:11], off offset:2304
	global_load_dwordx4 v[162:165], v[12:13], off offset:2304
	global_load_dwordx4 v[166:169], v[8:9], off offset:2304
	global_load_dwordx4 v[190:193], v[6:7], off offset:2304
	s_waitcnt lgkmcnt(0)
	s_barrier
	v_mfma_f32_16x16x32_f16 v[48:51], v[122:125], v[110:113], v[48:51]
	ds_read_b128 v[62:65], v16 offset:49152
	ds_read_b128 v[90:93], v21 offset:16384
	s_waitcnt lgkmcnt(0)
	v_mfma_f32_16x16x32_f16 v[36:39], v[62:65], v[90:93], v[36:39]
	ds_read_b128 v[74:77], v16 offset:51200
	ds_read_b128 v[110:113], v21 offset:18432
	s_waitcnt lgkmcnt(0)
	v_mfma_f32_16x16x32_f16 v[66:69], v[62:65], v[110:113], v[66:69]
	ds_read_b128 v[118:121], v16 offset:53248
	v_mfma_f32_16x16x32_f16 v[44:47], v[74:77], v[90:93], v[44:47]
	ds_read_b128 v[122:125], v16 offset:55296
	v_mfma_f32_16x16x32_f16 v[78:81], v[74:77], v[110:113], v[78:81]
	s_waitcnt vmcnt(7)
	ds_write_b128 v17, v[58:61]
	s_waitcnt lgkmcnt(2)
	v_mfma_f32_16x16x32_f16 v[82:85], v[118:121], v[90:93], v[82:85]
	s_waitcnt vmcnt(6)
	ds_write_b128 v18, v[106:109]
	v_mfma_f32_16x16x32_f16 v[86:89], v[118:121], v[110:113], v[86:89]
	s_waitcnt vmcnt(5)
	ds_write_b128 v19, v[126:129]
	s_waitcnt lgkmcnt(3)
	v_mfma_f32_16x16x32_f16 v[28:31], v[122:125], v[90:93], v[28:31]
	ds_read_b128 v[90:93], v21 offset:20480
	v_mfma_f32_16x16x32_f16 v[32:35], v[122:125], v[110:113], v[32:35]
	ds_read_b128 v[110:113], v21 offset:22528
	s_waitcnt lgkmcnt(1)
	v_mfma_f32_16x16x32_f16 v[98:101], v[62:65], v[90:93], v[98:101]
	s_waitcnt vmcnt(4)
	ds_write_b128 v20, v[134:137]
	s_waitcnt lgkmcnt(1)
	v_mfma_f32_16x16x32_f16 v[52:55], v[62:65], v[110:113], v[52:55]
	ds_read_b128 v[62:65], v22 offset:49152
	v_mfma_f32_16x16x32_f16 v[102:105], v[74:77], v[90:93], v[102:105]
	s_waitcnt vmcnt(3)
; #define GL_LOAD(s_, kt_) if (VAR != 1) { a##s_##0 = GL_A(0, kt_); a##s_##1 = GL_A(1, kt_); a##s_##2 = GL_A(2, kt_); a##s_##3 = GL_A(3, kt_); b##s_##0 = GL_B(0, kt_); b##s_##1 = GL_B(1, kt_); b##s_##2 = GL_B(2, kt_); b##s_##3 = GL_B(3, kt_); }
; #define LDS_STORE(s_, buf_) if (VAR != 2) { LDS_ST1(sA, 0, buf_, a##s_##0) LDS_ST1(sA, 1, buf_, a##s_##1) LDS_ST1(sA, 2, buf_, a##s_##2) LDS_ST1(sA, 3, buf_, a##s_##3) LDS_ST1(sB, 0, buf_, b##s_##0) LDS_ST1(sB, 1, buf_, b##s_##1) LDS_ST1(sB, 2, buf_, b##s_##2) LDS_ST1(sB, 3, buf_, b##s_##3) }
;     ...
;   GL_LOAD(0, 0)
;   GL_LOAD(1, 1)
;   LDS_STORE(0, 0)
;   if (VAR != 4) __syncthreads();
; #pragma unroll
;   for (int kt = 0; kt < nk; kt += 2) {
;     if (kt + 2 < nk) { GL_LOAD(0, kt + 2) }
;     MMA_TILE(0)
;     LDS_STORE(1, 1)
;     if (VAR != 4) __syncthreads();
;     if (kt + 3 < nk) { GL_LOAD(1, kt + 3) }
;     MMA_TILE(1)
;     if (kt + 2 < nk) { LDS_STORE(0, 0) }
;     if (VAR != 4) __syncthreads();
	ds_write_b128 v17, v[94:97] offset:32768
	v_mfma_f32_16x16x32_f16 v[24:27], v[74:77], v[110:113], v[24:27]
	ds_read_b128 v[74:77], v22 offset:51200
	v_mfma_f32_16x16x32_f16 v[114:117], v[118:121], v[90:93], v[114:117]
	s_waitcnt vmcnt(2)
	ds_write_b128 v18, v[162:165] offset:32768
	v_mfma_f32_16x16x32_f16 v[40:43], v[118:121], v[110:113], v[40:43]
	ds_read_b128 v[118:121], v22 offset:53248
	v_mfma_f32_16x16x32_f16 v[70:73], v[122:125], v[90:93], v[70:73]
	ds_read_b128 v[90:93], v23 offset:16384
	v_mfma_f32_16x16x32_f16 v[48:51], v[122:125], v[110:113], v[48:51]
	ds_read_b128 v[110:113], v23 offset:18432
	s_waitcnt lgkmcnt(1)
	v_mfma_f32_16x16x32_f16 v[36:39], v[62:65], v[90:93], v[36:39]
	ds_read_b128 v[122:125], v22 offset:55296
	s_waitcnt lgkmcnt(1)
	v_mfma_f32_16x16x32_f16 v[66:69], v[62:65], v[110:113], v[66:69]
	s_waitcnt vmcnt(1)
	ds_write_b128 v19, v[166:169] offset:32768
	v_mfma_f32_16x16x32_f16 v[44:47], v[74:77], v[90:93], v[44:47]
	s_waitcnt vmcnt(0)
	ds_write_b128 v20, v[190:193] offset:32768
	v_mfma_f32_16x16x32_f16 v[78:81], v[74:77], v[110:113], v[78:81]
	v_mfma_f32_16x16x32_f16 v[82:85], v[118:121], v[90:93], v[82:85]
	v_mfma_f32_16x16x32_f16 v[86:89], v[118:121], v[110:113], v[86:89]
	s_waitcnt lgkmcnt(2)
	v_mfma_f32_16x16x32_f16 v[28:31], v[122:125], v[90:93], v[28:31]
	ds_read_b128 v[90:93], v23 offset:20480
	v_mfma_f32_16x16x32_f16 v[32:35], v[122:125], v[110:113], v[32:35]
	ds_read_b128 v[110:113], v23 offset:22528
	s_waitcnt lgkmcnt(1)
	v_mfma_f32_16x16x32_f16 v[98:101], v[62:65], v[90:93], v[98:101]
	s_waitcnt lgkmcnt(0)
	v_mfma_f32_16x16x32_f16 v[52:55], v[62:65], v[110:113], v[52:55]
	global_load_dwordx4 v[62:65], v[0:1], off offset:2432
	v_mfma_f32_16x16x32_f16 v[102:105], v[74:77], v[90:93], v[102:105]
	v_mfma_f32_16x16x32_f16 v[24:27], v[74:77], v[110:113], v[24:27]
	v_mfma_f32_16x16x32_f16 v[114:117], v[118:121], v[90:93], v[114:117]
	v_mfma_f32_16x16x32_f16 v[40:43], v[118:121], v[110:113], v[40:43]
	v_mfma_f32_16x16x32_f16 v[70:73], v[122:125], v[90:93], v[70:73]
	global_load_dwordx4 v[90:93], v[2:3], off offset:2432
	global_load_dwordx4 v[130:133], v[4:5], off offset:2432
	global_load_dwordx4 v[138:141], v[14:15], off offset:2432
	global_load_dwordx4 v[74:77], v[10:11], off offset:2432
	global_load_dwordx4 v[142:145], v[12:13], off offset:2432
	global_load_dwordx4 v[154:157], v[8:9], off offset:2432
	global_load_dwordx4 v[158:161], v[6:7], off offset:2432
	s_waitcnt lgkmcnt(0)
	s_barrier
	v_mfma_f32_16x16x32_f16 v[48:51], v[122:125], v[110:113], v[48:51]
	ds_read_b128 v[58:61], v16 offset:32768
	ds_read_b128 v[106:109], v21
	s_waitcnt lgkmcnt(0)
	v_mfma_f32_16x16x32_f16 v[36:39], v[58:61], v[106:109], v[36:39]
	ds_read_b128 v[94:97], v16 offset:34816
	ds_read_b128 v[110:113], v21 offset:2048
	s_waitcnt lgkmcnt(0)
	v_mfma_f32_16x16x32_f16 v[66:69], v[58:61], v[110:113], v[66:69]
	ds_read_b128 v[118:121], v16 offset:36864
	v_mfma_f32_16x16x32_f16 v[44:47], v[94:97], v[106:109], v[44:47]
	ds_read_b128 v[122:125], v16 offset:38912
	v_mfma_f32_16x16x32_f16 v[78:81], v[94:97], v[110:113], v[78:81]
	s_waitcnt vmcnt(7)
	ds_write_b128 v17, v[62:65] offset:16384
	s_waitcnt lgkmcnt(2)
	v_mfma_f32_16x16x32_f16 v[82:85], v[118:121], v[106:109], v[82:85]
	s_waitcnt vmcnt(6)
	ds_write_b128 v18, v[90:93] offset:16384
	v_mfma_f32_16x16x32_f16 v[86:89], v[118:121], v[110:113], v[86:89]
	s_waitcnt vmcnt(5)
	ds_write_b128 v19, v[130:133] offset:16384
	s_waitcnt lgkmcnt(3)
	v_mfma_f32_16x16x32_f16 v[28:31], v[122:125], v[106:109], v[28:31]
	ds_read_b128 v[106:109], v21 offset:4096
	v_mfma_f32_16x16x32_f16 v[32:35], v[122:125], v[110:113], v[32:35]
	ds_read_b128 v[110:113], v21 offset:6144
	s_waitcnt lgkmcnt(1)
	v_mfma_f32_16x16x32_f16 v[98:101], v[58:61], v[106:109], v[98:101]
	s_waitcnt vmcnt(4)
	ds_write_b128 v20, v[138:141] offset:16384
	s_waitcnt lgkmcnt(1)
	v_mfma_f32_16x16x32_f16 v[52:55], v[58:61], v[110:113], v[52:55]
	ds_read_b128 v[58:61], v22 offset:32768
	v_mfma_f32_16x16x32_f16 v[102:105], v[94:97], v[106:109], v[102:105]
	s_waitcnt vmcnt(3)
	ds_write_b128 v17, v[74:77] offset:49152
	v_mfma_f32_16x16x32_f16 v[24:27], v[94:97], v[110:113], v[24:27]
	ds_read_b128 v[94:97], v22 offset:34816
	v_mfma_f32_16x16x32_f16 v[114:117], v[118:121], v[106:109], v[114:117]
	s_waitcnt vmcnt(2)
	ds_write_b128 v18, v[142:145] offset:49152
	v_mfma_f32_16x16x32_f16 v[40:43], v[118:121], v[110:113], v[40:43]
	ds_read_b128 v[118:121], v22 offset:36864
	v_mfma_f32_16x16x32_f16 v[70:73], v[122:125], v[106:109], v[70:73]
	ds_read_b128 v[106:109], v23
	v_mfma_f32_16x16x32_f16 v[48:51], v[122:125], v[110:113], v[48:51]
	ds_read_b128 v[110:113], v23 offset:2048
	s_waitcnt lgkmcnt(1)
	v_mfma_f32_16x16x32_f16 v[36:39], v[58:61], v[106:109], v[36:39]
	ds_read_b128 v[122:125], v22 offset:38912
	s_waitcnt lgkmcnt(1)
	v_mfma_f32_16x16x32_f16 v[66:69], v[58:61], v[110:113], v[66:69]
	s_waitcnt vmcnt(1)
	ds_write_b128 v19, v[154:157] offset:49152
	v_mfma_f32_16x16x32_f16 v[44:47], v[94:97], v[106:109], v[44:47]
	s_waitcnt vmcnt(0)
	ds_write_b128 v20, v[158:161] offset:49152
	v_mfma_f32_16x16x32_f16 v[78:81], v[94:97], v[110:113], v[78:81]
	v_mfma_f32_16x16x32_f16 v[82:85], v[118:121], v[106:109], v[82:85]
	v_mfma_f32_16x16x32_f16 v[86:89], v[118:121], v[110:113], v[86:89]
	s_waitcnt lgkmcnt(2)
	v_mfma_f32_16x16x32_f16 v[28:31], v[122:125], v[106:109], v[28:31]
	ds_read_b128 v[106:109], v23 offset:4096
	v_mfma_f32_16x16x32_f16 v[32:35], v[122:125], v[110:113], v[32:35]
	ds_read_b128 v[110:113], v23 offset:6144
	s_waitcnt lgkmcnt(1)
	v_mfma_f32_16x16x32_f16 v[98:101], v[58:61], v[106:109], v[98:101]
	s_waitcnt lgkmcnt(0)
	v_mfma_f32_16x16x32_f16 v[52:55], v[58:61], v[110:113], v[52:55]
	global_load_dwordx4 v[58:61], v[0:1], off offset:2560
	v_mfma_f32_16x16x32_f16 v[102:105], v[94:97], v[106:109], v[102:105]
	v_mfma_f32_16x16x32_f16 v[24:27], v[94:97], v[110:113], v[24:27]
	v_mfma_f32_16x16x32_f16 v[114:117], v[118:121], v[106:109], v[114:117]
	v_mfma_f32_16x16x32_f16 v[40:43], v[118:121], v[110:113], v[40:43]
	v_mfma_f32_16x16x32_f16 v[70:73], v[122:125], v[106:109], v[70:73]
	global_load_dwordx4 v[106:109], v[2:3], off offset:2560
	global_load_dwordx4 v[126:129], v[4:5], off offset:2560
	global_load_dwordx4 v[134:137], v[14:15], off offset:2560
	global_load_dwordx4 v[94:97], v[10:11], off offset:2560
	global_load_dwordx4 v[162:165], v[12:13], off offset:2560
	global_load_dwordx4 v[166:169], v[8:9], off offset:2560
	global_load_dwordx4 v[190:193], v[6:7], off offset:2560
	s_waitcnt lgkmcnt(0)
	s_barrier
; #define GL_LOAD(s_, kt_) if (VAR != 1) { a##s_##0 = GL_A(0, kt_); a##s_##1 = GL_A(1, kt_); a##s_##2 = GL_A(2, kt_); a##s_##3 = GL_A(3, kt_); b##s_##0 = GL_B(0, kt_); b##s_##1 = GL_B(1, kt_); b##s_##2 = GL_B(2, kt_); b##s_##3 = GL_B(3, kt_); }
; #define LDS_STORE(s_, buf_) if (VAR != 2) { LDS_ST1(sA, 0, buf_, a##s_##0) LDS_ST1(sA, 1, buf_, a##s_##1) LDS_ST1(sA, 2, buf_, a##s_##2) LDS_ST1(sA, 3, buf_, a##s_##3) LDS_ST1(sB, 0, buf_, b##s_##0) LDS_ST1(sB, 1, buf_, b##s_##1) LDS_ST1(sB, 2, buf_, b##s_##2) LDS_ST1(sB, 3, buf_, b##s_##3) }
;     ...
;   GL_LOAD(0, 0)
;   GL_LOAD(1, 1)
;   LDS_STORE(0, 0)
;   if (VAR != 4) __syncthreads();
; #pragma unroll
;   for (int kt = 0; kt < nk; kt += 2) {
;     if (kt + 2 < nk) { GL_LOAD(0, kt + 2) }
;     MMA_TILE(0)
;     LDS_STORE(1, 1)
;     if (VAR != 4) __syncthreads();
;     if (kt + 3 < nk) { GL_LOAD(1, kt + 3) }
;     MMA_TILE(1)
;     if (kt + 2 < nk) { LDS_STORE(0, 0) }
;     if (VAR != 4) __syncthreads();
	v_mfma_f32_16x16x32_f16 v[48:51], v[122:125], v[110:113], v[48:51]
	ds_read_b128 v[62:65], v16 offset:49152
	ds_read_b128 v[90:93], v21 offset:16384
	s_waitcnt lgkmcnt(0)
	v_mfma_f32_16x16x32_f16 v[36:39], v[62:65], v[90:93], v[36:39]
	ds_read_b128 v[74:77], v16 offset:51200
	ds_read_b128 v[110:113], v21 offset:18432
	s_waitcnt lgkmcnt(0)
	v_mfma_f32_16x16x32_f16 v[66:69], v[62:65], v[110:113], v[66:69]
	ds_read_b128 v[118:121], v16 offset:53248
	v_mfma_f32_16x16x32_f16 v[44:47], v[74:77], v[90:93], v[44:47]
	ds_read_b128 v[122:125], v16 offset:55296
	v_mfma_f32_16x16x32_f16 v[78:81], v[74:77], v[110:113], v[78:81]
	s_waitcnt vmcnt(7)
	ds_write_b128 v17, v[58:61]
	s_waitcnt lgkmcnt(2)
	v_mfma_f32_16x16x32_f16 v[82:85], v[118:121], v[90:93], v[82:85]
	s_waitcnt vmcnt(6)
	ds_write_b128 v18, v[106:109]
	v_mfma_f32_16x16x32_f16 v[86:89], v[118:121], v[110:113], v[86:89]
	s_waitcnt vmcnt(5)
	ds_write_b128 v19, v[126:129]
	s_waitcnt lgkmcnt(3)
	v_mfma_f32_16x16x32_f16 v[28:31], v[122:125], v[90:93], v[28:31]
	ds_read_b128 v[90:93], v21 offset:20480
	v_mfma_f32_16x16x32_f16 v[32:35], v[122:125], v[110:113], v[32:35]
	ds_read_b128 v[110:113], v21 offset:22528
	s_waitcnt lgkmcnt(1)
	v_mfma_f32_16x16x32_f16 v[98:101], v[62:65], v[90:93], v[98:101]
	s_waitcnt vmcnt(4)
	ds_write_b128 v20, v[134:137]
	s_waitcnt lgkmcnt(1)
	v_mfma_f32_16x16x32_f16 v[52:55], v[62:65], v[110:113], v[52:55]
	ds_read_b128 v[62:65], v22 offset:49152
	v_mfma_f32_16x16x32_f16 v[102:105], v[74:77], v[90:93], v[102:105]
	s_waitcnt vmcnt(3)
	ds_write_b128 v17, v[94:97] offset:32768
	v_mfma_f32_16x16x32_f16 v[24:27], v[74:77], v[110:113], v[24:27]
	ds_read_b128 v[74:77], v22 offset:51200
	v_mfma_f32_16x16x32_f16 v[114:117], v[118:121], v[90:93], v[114:117]
	s_waitcnt vmcnt(2)
	ds_write_b128 v18, v[162:165] offset:32768
	v_mfma_f32_16x16x32_f16 v[40:43], v[118:121], v[110:113], v[40:43]
	ds_read_b128 v[118:121], v22 offset:53248
	v_mfma_f32_16x16x32_f16 v[70:73], v[122:125], v[90:93], v[70:73]
	ds_read_b128 v[90:93], v23 offset:16384
	v_mfma_f32_16x16x32_f16 v[48:51], v[122:125], v[110:113], v[48:51]
	ds_read_b128 v[110:113], v23 offset:18432
	s_waitcnt lgkmcnt(1)
	v_mfma_f32_16x16x32_f16 v[36:39], v[62:65], v[90:93], v[36:39]
	ds_read_b128 v[122:125], v22 offset:55296
	s_waitcnt lgkmcnt(1)
	v_mfma_f32_16x16x32_f16 v[66:69], v[62:65], v[110:113], v[66:69]
	s_waitcnt vmcnt(1)
	ds_write_b128 v19, v[166:169] offset:32768
	v_mfma_f32_16x16x32_f16 v[44:47], v[74:77], v[90:93], v[44:47]
	s_waitcnt vmcnt(0)
	ds_write_b128 v20, v[190:193] offset:32768
	v_mfma_f32_16x16x32_f16 v[78:81], v[74:77], v[110:113], v[78:81]
	v_mfma_f32_16x16x32_f16 v[82:85], v[118:121], v[90:93], v[82:85]
	v_mfma_f32_16x16x32_f16 v[86:89], v[118:121], v[110:113], v[86:89]
	s_waitcnt lgkmcnt(2)
	v_mfma_f32_16x16x32_f16 v[28:31], v[122:125], v[90:93], v[28:31]
	ds_read_b128 v[90:93], v23 offset:20480
	v_mfma_f32_16x16x32_f16 v[32:35], v[122:125], v[110:113], v[32:35]
	ds_read_b128 v[110:113], v23 offset:22528
	s_waitcnt lgkmcnt(1)
	v_mfma_f32_16x16x32_f16 v[98:101], v[62:65], v[90:93], v[98:101]
	s_waitcnt lgkmcnt(0)
	v_mfma_f32_16x16x32_f16 v[52:55], v[62:65], v[110:113], v[52:55]
	global_load_dwordx4 v[62:65], v[0:1], off offset:2688
	v_mfma_f32_16x16x32_f16 v[102:105], v[74:77], v[90:93], v[102:105]
	v_mfma_f32_16x16x32_f16 v[24:27], v[74:77], v[110:113], v[24:27]
	v_mfma_f32_16x16x32_f16 v[114:117], v[118:121], v[90:93], v[114:117]
	v_mfma_f32_16x16x32_f16 v[40:43], v[118:121], v[110:113], v[40:43]
	v_mfma_f32_16x16x32_f16 v[70:73], v[122:125], v[90:93], v[70:73]
	global_load_dwordx4 v[90:93], v[2:3], off offset:2688
	global_load_dwordx4 v[130:133], v[4:5], off offset:2688
	global_load_dwordx4 v[138:141], v[14:15], off offset:2688
	global_load_dwordx4 v[74:77], v[10:11], off offset:2688
	global_load_dwordx4 v[142:145], v[12:13], off offset:2688
	global_load_dwordx4 v[154:157], v[8:9], off offset:2688
	global_load_dwordx4 v[158:161], v[6:7], off offset:2688
	s_waitcnt lgkmcnt(0)
	s_barrier
	v_mfma_f32_16x16x32_f16 v[48:51], v[122:125], v[110:113], v[48:51]
	ds_read_b128 v[58:61], v16 offset:32768
	ds_read_b128 v[106:109], v21
	s_waitcnt lgkmcnt(0)
	v_mfma_f32_16x16x32_f16 v[36:39], v[58:61], v[106:109], v[36:39]
	ds_read_b128 v[94:97], v16 offset:34816
	ds_read_b128 v[110:113], v21 offset:2048
	s_waitcnt lgkmcnt(0)
	v_mfma_f32_16x16x32_f16 v[66:69], v[58:61], v[110:113], v[66:69]
	ds_read_b128 v[118:121], v16 offset:36864
	v_mfma_f32_16x16x32_f16 v[44:47], v[94:97], v[106:109], v[44:47]
	ds_read_b128 v[122:125], v16 offset:38912
	v_mfma_f32_16x16x32_f16 v[78:81], v[94:97], v[110:113], v[78:81]
	s_waitcnt vmcnt(7)
	ds_write_b128 v17, v[62:65] offset:16384
	s_waitcnt lgkmcnt(2)
	v_mfma_f32_16x16x32_f16 v[82:85], v[118:121], v[106:109], v[82:85]
	s_waitcnt vmcnt(6)
	ds_write_b128 v18, v[90:93] offset:16384
	v_mfma_f32_16x16x32_f16 v[86:89], v[118:121], v[110:113], v[86:89]
	s_waitcnt vmcnt(5)
	ds_write_b128 v19, v[130:133] offset:16384
	s_waitcnt lgkmcnt(3)
	v_mfma_f32_16x16x32_f16 v[28:31], v[122:125], v[106:109], v[28:31]
	ds_read_b128 v[106:109], v21 offset:4096
	v_mfma_f32_16x16x32_f16 v[32:35], v[122:125], v[110:113], v[32:35]
	ds_read_b128 v[110:113], v21 offset:6144
	s_waitcnt lgkmcnt(1)
	v_mfma_f32_16x16x32_f16 v[98:101], v[58:61], v[106:109], v[98:101]
	s_waitcnt vmcnt(4)
	ds_write_b128 v20, v[138:141] offset:16384
	s_waitcnt lgkmcnt(1)
	v_mfma_f32_16x16x32_f16 v[52:55], v[58:61], v[110:113], v[52:55]
	ds_read_b128 v[58:61], v22 offset:32768
	v_mfma_f32_16x16x32_f16 v[102:105], v[94:97], v[106:109], v[102:105]
	s_waitcnt vmcnt(3)
; #define GL_LOAD(s_, kt_) if (VAR != 1) { a##s_##0 = GL_A(0, kt_); a##s_##1 = GL_A(1, kt_); a##s_##2 = GL_A(2, kt_); a##s_##3 = GL_A(3, kt_); b##s_##0 = GL_B(0, kt_); b##s_##1 = GL_B(1, kt_); b##s_##2 = GL_B(2, kt_); b##s_##3 = GL_B(3, kt_); }
; #define LDS_STORE(s_, buf_) if (VAR != 2) { LDS_ST1(sA, 0, buf_, a##s_##0) LDS_ST1(sA, 1, buf_, a##s_##1) LDS_ST1(sA, 2, buf_, a##s_##2) LDS_ST1(sA, 3, buf_, a##s_##3) LDS_ST1(sB, 0, buf_, b##s_##0) LDS_ST1(sB, 1, buf_, b##s_##1) LDS_ST1(sB, 2, buf_, b##s_##2) LDS_ST1(sB, 3, buf_, b##s_##3) }
;     ...
;   GL_LOAD(0, 0)
;   GL_LOAD(1, 1)
;   LDS_STORE(0, 0)
;   if (VAR != 4) __syncthreads();
; #pragma unroll
;   for (int kt = 0; kt < nk; kt += 2) {
;     if (kt + 2 < nk) { GL_LOAD(0, kt + 2) }
;     MMA_TILE(0)
;     LDS_STORE(1, 1)
;     if (VAR != 4) __syncthreads();
;     if (kt + 3 < nk) { GL_LOAD(1, kt + 3) }
;     MMA_TILE(1)
;     if (kt + 2 < nk) { LDS_STORE(0, 0) }
;     if (VAR != 4) __syncthreads();
	ds_write_b128 v17, v[74:77] offset:49152
	v_mfma_f32_16x16x32_f16 v[24:27], v[94:97], v[110:113], v[24:27]
	ds_read_b128 v[94:97], v22 offset:34816
	v_mfma_f32_16x16x32_f16 v[114:117], v[118:121], v[106:109], v[114:117]
	s_waitcnt vmcnt(2)
	ds_write_b128 v18, v[142:145] offset:49152
	v_mfma_f32_16x16x32_f16 v[40:43], v[118:121], v[110:113], v[40:43]
	ds_read_b128 v[118:121], v22 offset:36864
	v_mfma_f32_16x16x32_f16 v[70:73], v[122:125], v[106:109], v[70:73]
	ds_read_b128 v[106:109], v23
	v_mfma_f32_16x16x32_f16 v[48:51], v[122:125], v[110:113], v[48:51]
	ds_read_b128 v[110:113], v23 offset:2048
	s_waitcnt lgkmcnt(1)
	v_mfma_f32_16x16x32_f16 v[36:39], v[58:61], v[106:109], v[36:39]
	ds_read_b128 v[122:125], v22 offset:38912
	s_waitcnt lgkmcnt(1)
	v_mfma_f32_16x16x32_f16 v[66:69], v[58:61], v[110:113], v[66:69]
	s_waitcnt vmcnt(1)
	ds_write_b128 v19, v[154:157] offset:49152
	v_mfma_f32_16x16x32_f16 v[44:47], v[94:97], v[106:109], v[44:47]
	s_waitcnt vmcnt(0)
	ds_write_b128 v20, v[158:161] offset:49152
	v_mfma_f32_16x16x32_f16 v[78:81], v[94:97], v[110:113], v[78:81]
	v_mfma_f32_16x16x32_f16 v[82:85], v[118:121], v[106:109], v[82:85]
	v_mfma_f32_16x16x32_f16 v[86:89], v[118:121], v[110:113], v[86:89]
	s_waitcnt lgkmcnt(2)
	v_mfma_f32_16x16x32_f16 v[28:31], v[122:125], v[106:109], v[28:31]
	ds_read_b128 v[106:109], v23 offset:4096
	v_mfma_f32_16x16x32_f16 v[32:35], v[122:125], v[110:113], v[32:35]
	ds_read_b128 v[110:113], v23 offset:6144
	s_waitcnt lgkmcnt(1)
	v_mfma_f32_16x16x32_f16 v[98:101], v[58:61], v[106:109], v[98:101]
	s_waitcnt lgkmcnt(0)
	v_mfma_f32_16x16x32_f16 v[52:55], v[58:61], v[110:113], v[52:55]
	global_load_dwordx4 v[58:61], v[0:1], off offset:2816
	v_mfma_f32_16x16x32_f16 v[102:105], v[94:97], v[106:109], v[102:105]
	v_mfma_f32_16x16x32_f16 v[24:27], v[94:97], v[110:113], v[24:27]
	v_mfma_f32_16x16x32_f16 v[114:117], v[118:121], v[106:109], v[114:117]
	v_mfma_f32_16x16x32_f16 v[40:43], v[118:121], v[110:113], v[40:43]
	v_mfma_f32_16x16x32_f16 v[70:73], v[122:125], v[106:109], v[70:73]
	global_load_dwordx4 v[106:109], v[2:3], off offset:2816
	global_load_dwordx4 v[126:129], v[4:5], off offset:2816
	global_load_dwordx4 v[134:137], v[14:15], off offset:2816
	global_load_dwordx4 v[94:97], v[10:11], off offset:2816
	global_load_dwordx4 v[162:165], v[12:13], off offset:2816
	global_load_dwordx4 v[166:169], v[8:9], off offset:2816
	global_load_dwordx4 v[190:193], v[6:7], off offset:2816
	s_waitcnt lgkmcnt(0)
	s_barrier
	v_mfma_f32_16x16x32_f16 v[48:51], v[122:125], v[110:113], v[48:51]
	ds_read_b128 v[62:65], v16 offset:49152
	ds_read_b128 v[90:93], v21 offset:16384
	s_waitcnt lgkmcnt(0)
	v_mfma_f32_16x16x32_f16 v[36:39], v[62:65], v[90:93], v[36:39]
	ds_read_b128 v[74:77], v16 offset:51200
	ds_read_b128 v[110:113], v21 offset:18432
	s_waitcnt lgkmcnt(0)
	v_mfma_f32_16x16x32_f16 v[66:69], v[62:65], v[110:113], v[66:69]
	ds_read_b128 v[118:121], v16 offset:53248
	v_mfma_f32_16x16x32_f16 v[44:47], v[74:77], v[90:93], v[44:47]
	ds_read_b128 v[122:125], v16 offset:55296
	v_mfma_f32_16x16x32_f16 v[78:81], v[74:77], v[110:113], v[78:81]
	s_waitcnt vmcnt(7)
	ds_write_b128 v17, v[58:61]
	s_waitcnt lgkmcnt(2)
	v_mfma_f32_16x16x32_f16 v[82:85], v[118:121], v[90:93], v[82:85]
	s_waitcnt vmcnt(6)
	ds_write_b128 v18, v[106:109]
	v_mfma_f32_16x16x32_f16 v[86:89], v[118:121], v[110:113], v[86:89]
	s_waitcnt vmcnt(5)
	ds_write_b128 v19, v[126:129]
	s_waitcnt lgkmcnt(3)
	v_mfma_f32_16x16x32_f16 v[28:31], v[122:125], v[90:93], v[28:31]
	ds_read_b128 v[90:93], v21 offset:20480
	v_mfma_f32_16x16x32_f16 v[32:35], v[122:125], v[110:113], v[32:35]
	ds_read_b128 v[110:113], v21 offset:22528
	s_waitcnt lgkmcnt(1)
	v_mfma_f32_16x16x32_f16 v[98:101], v[62:65], v[90:93], v[98:101]
	s_waitcnt vmcnt(4)
	ds_write_b128 v20, v[134:137]
	s_waitcnt lgkmcnt(1)
	v_mfma_f32_16x16x32_f16 v[52:55], v[62:65], v[110:113], v[52:55]
	ds_read_b128 v[62:65], v22 offset:49152
	v_mfma_f32_16x16x32_f16 v[102:105], v[74:77], v[90:93], v[102:105]
	s_waitcnt vmcnt(3)
	ds_write_b128 v17, v[94:97] offset:32768
	v_mfma_f32_16x16x32_f16 v[24:27], v[74:77], v[110:113], v[24:27]
	ds_read_b128 v[74:77], v22 offset:51200
	v_mfma_f32_16x16x32_f16 v[114:117], v[118:121], v[90:93], v[114:117]
	s_waitcnt vmcnt(2)
	ds_write_b128 v18, v[162:165] offset:32768
	v_mfma_f32_16x16x32_f16 v[40:43], v[118:121], v[110:113], v[40:43]
	ds_read_b128 v[118:121], v22 offset:53248
	v_mfma_f32_16x16x32_f16 v[70:73], v[122:125], v[90:93], v[70:73]
	ds_read_b128 v[90:93], v23 offset:16384
	v_mfma_f32_16x16x32_f16 v[48:51], v[122:125], v[110:113], v[48:51]
	ds_read_b128 v[110:113], v23 offset:18432
	s_waitcnt lgkmcnt(1)
	v_mfma_f32_16x16x32_f16 v[36:39], v[62:65], v[90:93], v[36:39]
	ds_read_b128 v[122:125], v22 offset:55296
	s_waitcnt lgkmcnt(1)
	v_mfma_f32_16x16x32_f16 v[66:69], v[62:65], v[110:113], v[66:69]
	s_waitcnt vmcnt(1)
	ds_write_b128 v19, v[166:169] offset:32768
	v_mfma_f32_16x16x32_f16 v[44:47], v[74:77], v[90:93], v[44:47]
	s_waitcnt vmcnt(0)
	ds_write_b128 v20, v[190:193] offset:32768
	v_mfma_f32_16x16x32_f16 v[78:81], v[74:77], v[110:113], v[78:81]
	v_mfma_f32_16x16x32_f16 v[82:85], v[118:121], v[90:93], v[82:85]
	v_mfma_f32_16x16x32_f16 v[86:89], v[118:121], v[110:113], v[86:89]
	s_waitcnt lgkmcnt(2)
	v_mfma_f32_16x16x32_f16 v[28:31], v[122:125], v[90:93], v[28:31]
	ds_read_b128 v[90:93], v23 offset:20480
	v_mfma_f32_16x16x32_f16 v[32:35], v[122:125], v[110:113], v[32:35]
	ds_read_b128 v[110:113], v23 offset:22528
	s_waitcnt lgkmcnt(1)
	v_mfma_f32_16x16x32_f16 v[98:101], v[62:65], v[90:93], v[98:101]
	s_waitcnt lgkmcnt(0)
	v_mfma_f32_16x16x32_f16 v[52:55], v[62:65], v[110:113], v[52:55]
	global_load_dwordx4 v[62:65], v[0:1], off offset:2944
	v_mfma_f32_16x16x32_f16 v[102:105], v[74:77], v[90:93], v[102:105]
	v_mfma_f32_16x16x32_f16 v[24:27], v[74:77], v[110:113], v[24:27]
	v_mfma_f32_16x16x32_f16 v[114:117], v[118:121], v[90:93], v[114:117]
	v_mfma_f32_16x16x32_f16 v[40:43], v[118:121], v[110:113], v[40:43]
	v_mfma_f32_16x16x32_f16 v[70:73], v[122:125], v[90:93], v[70:73]
	global_load_dwordx4 v[90:93], v[2:3], off offset:2944
	global_load_dwordx4 v[130:133], v[4:5], off offset:2944
	global_load_dwordx4 v[138:141], v[14:15], off offset:2944
	global_load_dwordx4 v[74:77], v[10:11], off offset:2944
	global_load_dwordx4 v[142:145], v[12:13], off offset:2944
	global_load_dwordx4 v[154:157], v[8:9], off offset:2944
	global_load_dwordx4 v[158:161], v[6:7], off offset:2944
	s_waitcnt lgkmcnt(0)
	s_barrier
; #define GL_LOAD(s_, kt_) if (VAR != 1) { a##s_##0 = GL_A(0, kt_); a##s_##1 = GL_A(1, kt_); a##s_##2 = GL_A(2, kt_); a##s_##3 = GL_A(3, kt_); b##s_##0 = GL_B(0, kt_); b##s_##1 = GL_B(1, kt_); b##s_##2 = GL_B(2, kt_); b##s_##3 = GL_B(3, kt_); }
; #define LDS_STORE(s_, buf_) if (VAR != 2) { LDS_ST1(sA, 0, buf_, a##s_##0) LDS_ST1(sA, 1, buf_, a##s_##1) LDS_ST1(sA, 2, buf_, a##s_##2) LDS_ST1(sA, 3, buf_, a##s_##3) LDS_ST1(sB, 0, buf_, b##s_##0) LDS_ST1(sB, 1, buf_, b##s_##1) LDS_ST1(sB, 2, buf_, b##s_##2) LDS_ST1(sB, 3, buf_, b##s_##3) }
;     ...
;   GL_LOAD(0, 0)
;   GL_LOAD(1, 1)
;   LDS_STORE(0, 0)
;   if (VAR != 4) __syncthreads();
; #pragma unroll
;   for (int kt = 0; kt < nk; kt += 2) {
;     if (kt + 2 < nk) { GL_LOAD(0, kt + 2) }
;     MMA_TILE(0)
;     LDS_STORE(1, 1)
;     if (VAR != 4) __syncthreads();
;     if (kt + 3 < nk) { GL_LOAD(1, kt + 3) }
;     MMA_TILE(1)
;     if (kt + 2 < nk) { LDS_STORE(0, 0) }
;     if (VAR != 4) __syncthreads();
	v_mfma_f32_16x16x32_f16 v[48:51], v[122:125], v[110:113], v[48:51]
	ds_read_b128 v[58:61], v16 offset:32768
	ds_read_b128 v[106:109], v21
	s_waitcnt lgkmcnt(0)
	v_mfma_f32_16x16x32_f16 v[36:39], v[58:61], v[106:109], v[36:39]
	ds_read_b128 v[94:97], v16 offset:34816
	ds_read_b128 v[110:113], v21 offset:2048
	s_waitcnt lgkmcnt(0)
	v_mfma_f32_16x16x32_f16 v[66:69], v[58:61], v[110:113], v[66:69]
	ds_read_b128 v[118:121], v16 offset:36864
	v_mfma_f32_16x16x32_f16 v[44:47], v[94:97], v[106:109], v[44:47]
	ds_read_b128 v[122:125], v16 offset:38912
	v_mfma_f32_16x16x32_f16 v[78:81], v[94:97], v[110:113], v[78:81]
	s_waitcnt vmcnt(7)
	ds_write_b128 v17, v[62:65] offset:16384
	s_waitcnt lgkmcnt(2)
	v_mfma_f32_16x16x32_f16 v[82:85], v[118:121], v[106:109], v[82:85]
	s_waitcnt vmcnt(6)
	ds_write_b128 v18, v[90:93] offset:16384
	v_mfma_f32_16x16x32_f16 v[86:89], v[118:121], v[110:113], v[86:89]
	s_waitcnt vmcnt(5)
	ds_write_b128 v19, v[130:133] offset:16384
	s_waitcnt lgkmcnt(3)
	v_mfma_f32_16x16x32_f16 v[28:31], v[122:125], v[106:109], v[28:31]
	ds_read_b128 v[106:109], v21 offset:4096
	v_mfma_f32_16x16x32_f16 v[32:35], v[122:125], v[110:113], v[32:35]
	ds_read_b128 v[110:113], v21 offset:6144
	s_waitcnt lgkmcnt(1)
	v_mfma_f32_16x16x32_f16 v[98:101], v[58:61], v[106:109], v[98:101]
	s_waitcnt vmcnt(4)
	ds_write_b128 v20, v[138:141] offset:16384
	s_waitcnt lgkmcnt(1)
	v_mfma_f32_16x16x32_f16 v[52:55], v[58:61], v[110:113], v[52:55]
	ds_read_b128 v[58:61], v22 offset:32768
	v_mfma_f32_16x16x32_f16 v[102:105], v[94:97], v[106:109], v[102:105]
	s_waitcnt vmcnt(3)
	ds_write_b128 v17, v[74:77] offset:49152
	v_mfma_f32_16x16x32_f16 v[24:27], v[94:97], v[110:113], v[24:27]
	ds_read_b128 v[94:97], v22 offset:34816
	v_mfma_f32_16x16x32_f16 v[114:117], v[118:121], v[106:109], v[114:117]
	s_waitcnt vmcnt(2)
	ds_write_b128 v18, v[142:145] offset:49152
	v_mfma_f32_16x16x32_f16 v[40:43], v[118:121], v[110:113], v[40:43]
	ds_read_b128 v[118:121], v22 offset:36864
	v_mfma_f32_16x16x32_f16 v[70:73], v[122:125], v[106:109], v[70:73]
	ds_read_b128 v[106:109], v23
	v_mfma_f32_16x16x32_f16 v[48:51], v[122:125], v[110:113], v[48:51]
	ds_read_b128 v[110:113], v23 offset:2048
	s_waitcnt lgkmcnt(1)
	v_mfma_f32_16x16x32_f16 v[36:39], v[58:61], v[106:109], v[36:39]
	ds_read_b128 v[122:125], v22 offset:38912
	s_waitcnt lgkmcnt(1)
	v_mfma_f32_16x16x32_f16 v[66:69], v[58:61], v[110:113], v[66:69]
	s_waitcnt vmcnt(1)
	ds_write_b128 v19, v[154:157] offset:49152
	v_mfma_f32_16x16x32_f16 v[44:47], v[94:97], v[106:109], v[44:47]
	s_waitcnt vmcnt(0)
	ds_write_b128 v20, v[158:161] offset:49152
	v_mfma_f32_16x16x32_f16 v[78:81], v[94:97], v[110:113], v[78:81]
	v_mfma_f32_16x16x32_f16 v[82:85], v[118:121], v[106:109], v[82:85]
	v_mfma_f32_16x16x32_f16 v[86:89], v[118:121], v[110:113], v[86:89]
	s_waitcnt lgkmcnt(2)
	v_mfma_f32_16x16x32_f16 v[28:31], v[122:125], v[106:109], v[28:31]
	ds_read_b128 v[106:109], v23 offset:4096
	v_mfma_f32_16x16x32_f16 v[32:35], v[122:125], v[110:113], v[32:35]
	ds_read_b128 v[110:113], v23 offset:6144
	s_waitcnt lgkmcnt(1)
	v_mfma_f32_16x16x32_f16 v[98:101], v[58:61], v[106:109], v[98:101]
	s_waitcnt lgkmcnt(0)
	v_mfma_f32_16x16x32_f16 v[52:55], v[58:61], v[110:113], v[52:55]
	global_load_dwordx4 v[58:61], v[0:1], off offset:3072
	v_mfma_f32_16x16x32_f16 v[102:105], v[94:97], v[106:109], v[102:105]
	v_mfma_f32_16x16x32_f16 v[24:27], v[94:97], v[110:113], v[24:27]
	v_mfma_f32_16x16x32_f16 v[114:117], v[118:121], v[106:109], v[114:117]
	v_mfma_f32_16x16x32_f16 v[40:43], v[118:121], v[110:113], v[40:43]
	v_mfma_f32_16x16x32_f16 v[70:73], v[122:125], v[106:109], v[70:73]
	global_load_dwordx4 v[106:109], v[2:3], off offset:3072
	global_load_dwordx4 v[126:129], v[4:5], off offset:3072
	global_load_dwordx4 v[134:137], v[14:15], off offset:3072
	global_load_dwordx4 v[94:97], v[10:11], off offset:3072
	global_load_dwordx4 v[162:165], v[12:13], off offset:3072
	global_load_dwordx4 v[166:169], v[8:9], off offset:3072
	global_load_dwordx4 v[190:193], v[6:7], off offset:3072
	s_waitcnt lgkmcnt(0)
	s_barrier
	v_mfma_f32_16x16x32_f16 v[48:51], v[122:125], v[110:113], v[48:51]
	ds_read_b128 v[62:65], v16 offset:49152
	ds_read_b128 v[90:93], v21 offset:16384
	s_waitcnt lgkmcnt(0)
	v_mfma_f32_16x16x32_f16 v[36:39], v[62:65], v[90:93], v[36:39]
	ds_read_b128 v[74:77], v16 offset:51200
	ds_read_b128 v[110:113], v21 offset:18432
	s_waitcnt lgkmcnt(0)
	v_mfma_f32_16x16x32_f16 v[66:69], v[62:65], v[110:113], v[66:69]
	ds_read_b128 v[118:121], v16 offset:53248
	v_mfma_f32_16x16x32_f16 v[44:47], v[74:77], v[90:93], v[44:47]
	ds_read_b128 v[122:125], v16 offset:55296
	v_mfma_f32_16x16x32_f16 v[78:81], v[74:77], v[110:113], v[78:81]
	s_waitcnt vmcnt(7)
	ds_write_b128 v17, v[58:61]
	s_waitcnt lgkmcnt(2)
	v_mfma_f32_16x16x32_f16 v[82:85], v[118:121], v[90:93], v[82:85]
	s_waitcnt vmcnt(6)
	ds_write_b128 v18, v[106:109]
	v_mfma_f32_16x16x32_f16 v[86:89], v[118:121], v[110:113], v[86:89]
	s_waitcnt vmcnt(5)
	ds_write_b128 v19, v[126:129]
	s_waitcnt lgkmcnt(3)
	v_mfma_f32_16x16x32_f16 v[28:31], v[122:125], v[90:93], v[28:31]
	ds_read_b128 v[90:93], v21 offset:20480
	v_mfma_f32_16x16x32_f16 v[32:35], v[122:125], v[110:113], v[32:35]
	ds_read_b128 v[110:113], v21 offset:22528
	s_waitcnt lgkmcnt(1)
	v_mfma_f32_16x16x32_f16 v[98:101], v[62:65], v[90:93], v[98:101]
	s_waitcnt vmcnt(4)
	ds_write_b128 v20, v[134:137]
	s_waitcnt lgkmcnt(1)
	v_mfma_f32_16x16x32_f16 v[52:55], v[62:65], v[110:113], v[52:55]
	ds_read_b128 v[62:65], v22 offset:49152
	v_mfma_f32_16x16x32_f16 v[102:105], v[74:77], v[90:93], v[102:105]
	s_waitcnt vmcnt(3)
; #define GL_LOAD(s_, kt_) if (VAR != 1) { a##s_##0 = GL_A(0, kt_); a##s_##1 = GL_A(1, kt_); a##s_##2 = GL_A(2, kt_); a##s_##3 = GL_A(3, kt_); b##s_##0 = GL_B(0, kt_); b##s_##1 = GL_B(1, kt_); b##s_##2 = GL_B(2, kt_); b##s_##3 = GL_B(3, kt_); }
; #define LDS_STORE(s_, buf_) if (VAR != 2) { LDS_ST1(sA, 0, buf_, a##s_##0) LDS_ST1(sA, 1, buf_, a##s_##1) LDS_ST1(sA, 2, buf_, a##s_##2) LDS_ST1(sA, 3, buf_, a##s_##3) LDS_ST1(sB, 0, buf_, b##s_##0) LDS_ST1(sB, 1, buf_, b##s_##1) LDS_ST1(sB, 2, buf_, b##s_##2) LDS_ST1(sB, 3, buf_, b##s_##3) }
;     ...
;   GL_LOAD(0, 0)
;   GL_LOAD(1, 1)
;   LDS_STORE(0, 0)
;   if (VAR != 4) __syncthreads();
; #pragma unroll
;   for (int kt = 0; kt < nk; kt += 2) {
;     if (kt + 2 < nk) { GL_LOAD(0, kt + 2) }
;     MMA_TILE(0)
;     LDS_STORE(1, 1)
;     if (VAR != 4) __syncthreads();
;     if (kt + 3 < nk) { GL_LOAD(1, kt + 3) }
;     MMA_TILE(1)
;     if (kt + 2 < nk) { LDS_STORE(0, 0) }
;     if (VAR != 4) __syncthreads();
	ds_write_b128 v17, v[94:97] offset:32768
	v_mfma_f32_16x16x32_f16 v[24:27], v[74:77], v[110:113], v[24:27]
	ds_read_b128 v[74:77], v22 offset:51200
	v_mfma_f32_16x16x32_f16 v[114:117], v[118:121], v[90:93], v[114:117]
	s_waitcnt vmcnt(2)
	ds_write_b128 v18, v[162:165] offset:32768
	v_mfma_f32_16x16x32_f16 v[40:43], v[118:121], v[110:113], v[40:43]
	ds_read_b128 v[118:121], v22 offset:53248
	v_mfma_f32_16x16x32_f16 v[70:73], v[122:125], v[90:93], v[70:73]
	ds_read_b128 v[90:93], v23 offset:16384
	v_mfma_f32_16x16x32_f16 v[48:51], v[122:125], v[110:113], v[48:51]
	ds_read_b128 v[110:113], v23 offset:18432
	s_waitcnt lgkmcnt(1)
	v_mfma_f32_16x16x32_f16 v[36:39], v[62:65], v[90:93], v[36:39]
	ds_read_b128 v[122:125], v22 offset:55296
	s_waitcnt lgkmcnt(1)
	v_mfma_f32_16x16x32_f16 v[66:69], v[62:65], v[110:113], v[66:69]
	s_waitcnt vmcnt(1)
	ds_write_b128 v19, v[166:169] offset:32768
	v_mfma_f32_16x16x32_f16 v[44:47], v[74:77], v[90:93], v[44:47]
	s_waitcnt vmcnt(0)
	ds_write_b128 v20, v[190:193] offset:32768
	v_mfma_f32_16x16x32_f16 v[78:81], v[74:77], v[110:113], v[78:81]
	v_mfma_f32_16x16x32_f16 v[82:85], v[118:121], v[90:93], v[82:85]
	v_mfma_f32_16x16x32_f16 v[86:89], v[118:121], v[110:113], v[86:89]
	s_waitcnt lgkmcnt(2)
	v_mfma_f32_16x16x32_f16 v[28:31], v[122:125], v[90:93], v[28:31]
	ds_read_b128 v[90:93], v23 offset:20480
	v_mfma_f32_16x16x32_f16 v[32:35], v[122:125], v[110:113], v[32:35]
	ds_read_b128 v[110:113], v23 offset:22528
	s_waitcnt lgkmcnt(1)
	v_mfma_f32_16x16x32_f16 v[98:101], v[62:65], v[90:93], v[98:101]
	s_waitcnt lgkmcnt(0)
	v_mfma_f32_16x16x32_f16 v[52:55], v[62:65], v[110:113], v[52:55]
	global_load_dwordx4 v[62:65], v[0:1], off offset:3200
	v_mfma_f32_16x16x32_f16 v[102:105], v[74:77], v[90:93], v[102:105]
	v_mfma_f32_16x16x32_f16 v[24:27], v[74:77], v[110:113], v[24:27]
	v_mfma_f32_16x16x32_f16 v[114:117], v[118:121], v[90:93], v[114:117]
	v_mfma_f32_16x16x32_f16 v[40:43], v[118:121], v[110:113], v[40:43]
	v_mfma_f32_16x16x32_f16 v[70:73], v[122:125], v[90:93], v[70:73]
	global_load_dwordx4 v[90:93], v[2:3], off offset:3200
	global_load_dwordx4 v[130:133], v[4:5], off offset:3200
	global_load_dwordx4 v[138:141], v[14:15], off offset:3200
	global_load_dwordx4 v[74:77], v[10:11], off offset:3200
	global_load_dwordx4 v[142:145], v[12:13], off offset:3200
	global_load_dwordx4 v[154:157], v[8:9], off offset:3200
	global_load_dwordx4 v[158:161], v[6:7], off offset:3200
	s_waitcnt lgkmcnt(0)
	s_barrier
	v_mfma_f32_16x16x32_f16 v[48:51], v[122:125], v[110:113], v[48:51]
	ds_read_b128 v[58:61], v16 offset:32768
	ds_read_b128 v[106:109], v21
	s_waitcnt lgkmcnt(0)
	v_mfma_f32_16x16x32_f16 v[36:39], v[58:61], v[106:109], v[36:39]
	ds_read_b128 v[94:97], v16 offset:34816
	ds_read_b128 v[110:113], v21 offset:2048
	s_waitcnt lgkmcnt(0)
	v_mfma_f32_16x16x32_f16 v[66:69], v[58:61], v[110:113], v[66:69]
	ds_read_b128 v[118:121], v16 offset:36864
	v_mfma_f32_16x16x32_f16 v[44:47], v[94:97], v[106:109], v[44:47]
	ds_read_b128 v[122:125], v16 offset:38912
	v_mfma_f32_16x16x32_f16 v[78:81], v[94:97], v[110:113], v[78:81]
	s_waitcnt vmcnt(7)
	ds_write_b128 v17, v[62:65] offset:16384
	s_waitcnt lgkmcnt(2)
	v_mfma_f32_16x16x32_f16 v[82:85], v[118:121], v[106:109], v[82:85]
	s_waitcnt vmcnt(6)
	ds_write_b128 v18, v[90:93] offset:16384
	v_mfma_f32_16x16x32_f16 v[86:89], v[118:121], v[110:113], v[86:89]
	s_waitcnt vmcnt(5)
	ds_write_b128 v19, v[130:133] offset:16384
	s_waitcnt lgkmcnt(3)
	v_mfma_f32_16x16x32_f16 v[28:31], v[122:125], v[106:109], v[28:31]
	ds_read_b128 v[106:109], v21 offset:4096
	v_mfma_f32_16x16x32_f16 v[32:35], v[122:125], v[110:113], v[32:35]
	ds_read_b128 v[110:113], v21 offset:6144
	s_waitcnt lgkmcnt(1)
	v_mfma_f32_16x16x32_f16 v[98:101], v[58:61], v[106:109], v[98:101]
	s_waitcnt vmcnt(4)
	ds_write_b128 v20, v[138:141] offset:16384
	s_waitcnt lgkmcnt(1)
	v_mfma_f32_16x16x32_f16 v[52:55], v[58:61], v[110:113], v[52:55]
	ds_read_b128 v[58:61], v22 offset:32768
	v_mfma_f32_16x16x32_f16 v[102:105], v[94:97], v[106:109], v[102:105]
	s_waitcnt vmcnt(3)
	ds_write_b128 v17, v[74:77] offset:49152
	v_mfma_f32_16x16x32_f16 v[24:27], v[94:97], v[110:113], v[24:27]
	ds_read_b128 v[94:97], v22 offset:34816
	v_mfma_f32_16x16x32_f16 v[114:117], v[118:121], v[106:109], v[114:117]
	s_waitcnt vmcnt(2)
	ds_write_b128 v18, v[142:145] offset:49152
	v_mfma_f32_16x16x32_f16 v[40:43], v[118:121], v[110:113], v[40:43]
	ds_read_b128 v[118:121], v22 offset:36864
	v_mfma_f32_16x16x32_f16 v[70:73], v[122:125], v[106:109], v[70:73]
	ds_read_b128 v[106:109], v23
	v_mfma_f32_16x16x32_f16 v[48:51], v[122:125], v[110:113], v[48:51]
	ds_read_b128 v[110:113], v23 offset:2048
	s_waitcnt lgkmcnt(1)
	v_mfma_f32_16x16x32_f16 v[36:39], v[58:61], v[106:109], v[36:39]
	ds_read_b128 v[122:125], v22 offset:38912
	s_waitcnt lgkmcnt(1)
	v_mfma_f32_16x16x32_f16 v[66:69], v[58:61], v[110:113], v[66:69]
	s_waitcnt vmcnt(1)
	ds_write_b128 v19, v[154:157] offset:49152
	v_mfma_f32_16x16x32_f16 v[44:47], v[94:97], v[106:109], v[44:47]
	s_waitcnt vmcnt(0)
	ds_write_b128 v20, v[158:161] offset:49152
	v_mfma_f32_16x16x32_f16 v[78:81], v[94:97], v[110:113], v[78:81]
	v_mfma_f32_16x16x32_f16 v[82:85], v[118:121], v[106:109], v[82:85]
	v_mfma_f32_16x16x32_f16 v[86:89], v[118:121], v[110:113], v[86:89]
	s_waitcnt lgkmcnt(2)
	v_mfma_f32_16x16x32_f16 v[28:31], v[122:125], v[106:109], v[28:31]
	ds_read_b128 v[106:109], v23 offset:4096
	v_mfma_f32_16x16x32_f16 v[32:35], v[122:125], v[110:113], v[32:35]
	ds_read_b128 v[110:113], v23 offset:6144
	s_waitcnt lgkmcnt(1)
	v_mfma_f32_16x16x32_f16 v[98:101], v[58:61], v[106:109], v[98:101]
	s_waitcnt lgkmcnt(0)
	v_mfma_f32_16x16x32_f16 v[52:55], v[58:61], v[110:113], v[52:55]
	global_load_dwordx4 v[58:61], v[0:1], off offset:3328
	v_mfma_f32_16x16x32_f16 v[102:105], v[94:97], v[106:109], v[102:105]
	v_mfma_f32_16x16x32_f16 v[24:27], v[94:97], v[110:113], v[24:27]
	v_mfma_f32_16x16x32_f16 v[114:117], v[118:121], v[106:109], v[114:117]
	v_mfma_f32_16x16x32_f16 v[40:43], v[118:121], v[110:113], v[40:43]
	v_mfma_f32_16x16x32_f16 v[70:73], v[122:125], v[106:109], v[70:73]
	global_load_dwordx4 v[106:109], v[2:3], off offset:3328
	global_load_dwordx4 v[126:129], v[4:5], off offset:3328
	global_load_dwordx4 v[134:137], v[14:15], off offset:3328
	global_load_dwordx4 v[94:97], v[10:11], off offset:3328
	global_load_dwordx4 v[162:165], v[12:13], off offset:3328
	global_load_dwordx4 v[166:169], v[8:9], off offset:3328
	global_load_dwordx4 v[190:193], v[6:7], off offset:3328
	s_waitcnt lgkmcnt(0)
	s_barrier
; #define GL_LOAD(s_, kt_) if (VAR != 1) { a##s_##0 = GL_A(0, kt_); a##s_##1 = GL_A(1, kt_); a##s_##2 = GL_A(2, kt_); a##s_##3 = GL_A(3, kt_); b##s_##0 = GL_B(0, kt_); b##s_##1 = GL_B(1, kt_); b##s_##2 = GL_B(2, kt_); b##s_##3 = GL_B(3, kt_); }
; #define LDS_STORE(s_, buf_) if (VAR != 2) { LDS_ST1(sA, 0, buf_, a##s_##0) LDS_ST1(sA, 1, buf_, a##s_##1) LDS_ST1(sA, 2, buf_, a##s_##2) LDS_ST1(sA, 3, buf_, a##s_##3) LDS_ST1(sB, 0, buf_, b##s_##0) LDS_ST1(sB, 1, buf_, b##s_##1) LDS_ST1(sB, 2, buf_, b##s_##2) LDS_ST1(sB, 3, buf_, b##s_##3) }
;     ...
;   GL_LOAD(0, 0)
;   GL_LOAD(1, 1)
;   LDS_STORE(0, 0)
;   if (VAR != 4) __syncthreads();
; #pragma unroll
;   for (int kt = 0; kt < nk; kt += 2) {
;     if (kt + 2 < nk) { GL_LOAD(0, kt + 2) }
;     MMA_TILE(0)
;     LDS_STORE(1, 1)
;     if (VAR != 4) __syncthreads();
;     if (kt + 3 < nk) { GL_LOAD(1, kt + 3) }
;     MMA_TILE(1)
;     if (kt + 2 < nk) { LDS_STORE(0, 0) }
;     if (VAR != 4) __syncthreads();
	v_mfma_f32_16x16x32_f16 v[48:51], v[122:125], v[110:113], v[48:51]
	ds_read_b128 v[62:65], v16 offset:49152
	ds_read_b128 v[90:93], v21 offset:16384
	s_waitcnt lgkmcnt(0)
	v_mfma_f32_16x16x32_f16 v[36:39], v[62:65], v[90:93], v[36:39]
	ds_read_b128 v[74:77], v16 offset:51200
	ds_read_b128 v[110:113], v21 offset:18432
	s_waitcnt lgkmcnt(0)
	v_mfma_f32_16x16x32_f16 v[66:69], v[62:65], v[110:113], v[66:69]
	ds_read_b128 v[118:121], v16 offset:53248
	v_mfma_f32_16x16x32_f16 v[44:47], v[74:77], v[90:93], v[44:47]
	ds_read_b128 v[122:125], v16 offset:55296
	v_mfma_f32_16x16x32_f16 v[78:81], v[74:77], v[110:113], v[78:81]
	s_waitcnt vmcnt(7)
	ds_write_b128 v17, v[58:61]
	s_waitcnt lgkmcnt(2)
	v_mfma_f32_16x16x32_f16 v[82:85], v[118:121], v[90:93], v[82:85]
	s_waitcnt vmcnt(6)
	ds_write_b128 v18, v[106:109]
	v_mfma_f32_16x16x32_f16 v[86:89], v[118:121], v[110:113], v[86:89]
	s_waitcnt vmcnt(5)
	ds_write_b128 v19, v[126:129]
	s_waitcnt lgkmcnt(3)
	v_mfma_f32_16x16x32_f16 v[28:31], v[122:125], v[90:93], v[28:31]
	ds_read_b128 v[90:93], v21 offset:20480
	v_mfma_f32_16x16x32_f16 v[32:35], v[122:125], v[110:113], v[32:35]
	ds_read_b128 v[110:113], v21 offset:22528
	s_waitcnt lgkmcnt(1)
	v_mfma_f32_16x16x32_f16 v[98:101], v[62:65], v[90:93], v[98:101]
	s_waitcnt vmcnt(4)
	ds_write_b128 v20, v[134:137]
	s_waitcnt lgkmcnt(1)
	v_mfma_f32_16x16x32_f16 v[52:55], v[62:65], v[110:113], v[52:55]
	ds_read_b128 v[62:65], v22 offset:49152
	v_mfma_f32_16x16x32_f16 v[102:105], v[74:77], v[90:93], v[102:105]
	s_waitcnt vmcnt(3)
	ds_write_b128 v17, v[94:97] offset:32768
	v_mfma_f32_16x16x32_f16 v[24:27], v[74:77], v[110:113], v[24:27]
	ds_read_b128 v[74:77], v22 offset:51200
	v_mfma_f32_16x16x32_f16 v[114:117], v[118:121], v[90:93], v[114:117]
	s_waitcnt vmcnt(2)
	ds_write_b128 v18, v[162:165] offset:32768
	v_mfma_f32_16x16x32_f16 v[40:43], v[118:121], v[110:113], v[40:43]
	ds_read_b128 v[118:121], v22 offset:53248
	v_mfma_f32_16x16x32_f16 v[70:73], v[122:125], v[90:93], v[70:73]
	ds_read_b128 v[90:93], v23 offset:16384
	v_mfma_f32_16x16x32_f16 v[48:51], v[122:125], v[110:113], v[48:51]
	ds_read_b128 v[110:113], v23 offset:18432
	s_waitcnt lgkmcnt(1)
	v_mfma_f32_16x16x32_f16 v[36:39], v[62:65], v[90:93], v[36:39]
	ds_read_b128 v[122:125], v22 offset:55296
	s_waitcnt lgkmcnt(1)
	v_mfma_f32_16x16x32_f16 v[66:69], v[62:65], v[110:113], v[66:69]
	s_waitcnt vmcnt(1)
	ds_write_b128 v19, v[166:169] offset:32768
	v_mfma_f32_16x16x32_f16 v[44:47], v[74:77], v[90:93], v[44:47]
	s_waitcnt vmcnt(0)
	ds_write_b128 v20, v[190:193] offset:32768
	v_mfma_f32_16x16x32_f16 v[78:81], v[74:77], v[110:113], v[78:81]
	v_mfma_f32_16x16x32_f16 v[82:85], v[118:121], v[90:93], v[82:85]
	v_mfma_f32_16x16x32_f16 v[86:89], v[118:121], v[110:113], v[86:89]
	s_waitcnt lgkmcnt(2)
	v_mfma_f32_16x16x32_f16 v[28:31], v[122:125], v[90:93], v[28:31]
	ds_read_b128 v[90:93], v23 offset:20480
	v_mfma_f32_16x16x32_f16 v[32:35], v[122:125], v[110:113], v[32:35]
	ds_read_b128 v[110:113], v23 offset:22528
	s_waitcnt lgkmcnt(1)
	v_mfma_f32_16x16x32_f16 v[98:101], v[62:65], v[90:93], v[98:101]
	s_waitcnt lgkmcnt(0)
	v_mfma_f32_16x16x32_f16 v[52:55], v[62:65], v[110:113], v[52:55]
	global_load_dwordx4 v[62:65], v[0:1], off offset:3456
	v_mfma_f32_16x16x32_f16 v[102:105], v[74:77], v[90:93], v[102:105]
	v_mfma_f32_16x16x32_f16 v[24:27], v[74:77], v[110:113], v[24:27]
	v_mfma_f32_16x16x32_f16 v[114:117], v[118:121], v[90:93], v[114:117]
	v_mfma_f32_16x16x32_f16 v[40:43], v[118:121], v[110:113], v[40:43]
	v_mfma_f32_16x16x32_f16 v[70:73], v[122:125], v[90:93], v[70:73]
	global_load_dwordx4 v[90:93], v[2:3], off offset:3456
	global_load_dwordx4 v[130:133], v[4:5], off offset:3456
	global_load_dwordx4 v[138:141], v[14:15], off offset:3456
	global_load_dwordx4 v[74:77], v[10:11], off offset:3456
	global_load_dwordx4 v[142:145], v[12:13], off offset:3456
	global_load_dwordx4 v[154:157], v[8:9], off offset:3456
	global_load_dwordx4 v[158:161], v[6:7], off offset:3456
	s_waitcnt lgkmcnt(0)
	s_barrier
	v_mfma_f32_16x16x32_f16 v[48:51], v[122:125], v[110:113], v[48:51]
	ds_read_b128 v[58:61], v16 offset:32768
	ds_read_b128 v[106:109], v21
	s_waitcnt lgkmcnt(0)
	v_mfma_f32_16x16x32_f16 v[36:39], v[58:61], v[106:109], v[36:39]
	ds_read_b128 v[94:97], v16 offset:34816
	ds_read_b128 v[110:113], v21 offset:2048
	s_waitcnt lgkmcnt(0)
	v_mfma_f32_16x16x32_f16 v[66:69], v[58:61], v[110:113], v[66:69]
	ds_read_b128 v[118:121], v16 offset:36864
	v_mfma_f32_16x16x32_f16 v[44:47], v[94:97], v[106:109], v[44:47]
	ds_read_b128 v[122:125], v16 offset:38912
	v_mfma_f32_16x16x32_f16 v[78:81], v[94:97], v[110:113], v[78:81]
	s_waitcnt vmcnt(7)
	ds_write_b128 v17, v[62:65] offset:16384
	s_waitcnt lgkmcnt(2)
	v_mfma_f32_16x16x32_f16 v[82:85], v[118:121], v[106:109], v[82:85]
	s_waitcnt vmcnt(6)
	ds_write_b128 v18, v[90:93] offset:16384
	v_mfma_f32_16x16x32_f16 v[86:89], v[118:121], v[110:113], v[86:89]
	s_waitcnt vmcnt(5)
	ds_write_b128 v19, v[130:133] offset:16384
	s_waitcnt lgkmcnt(3)
	v_mfma_f32_16x16x32_f16 v[28:31], v[122:125], v[106:109], v[28:31]
	ds_read_b128 v[106:109], v21 offset:4096
	v_mfma_f32_16x16x32_f16 v[32:35], v[122:125], v[110:113], v[32:35]
	ds_read_b128 v[110:113], v21 offset:6144
	s_waitcnt lgkmcnt(1)
	v_mfma_f32_16x16x32_f16 v[98:101], v[58:61], v[106:109], v[98:101]
	s_waitcnt vmcnt(4)
	ds_write_b128 v20, v[138:141] offset:16384
	s_waitcnt lgkmcnt(1)
	v_mfma_f32_16x16x32_f16 v[52:55], v[58:61], v[110:113], v[52:55]
	ds_read_b128 v[58:61], v22 offset:32768
	v_mfma_f32_16x16x32_f16 v[102:105], v[94:97], v[106:109], v[102:105]
	s_waitcnt vmcnt(3)
; #define GL_LOAD(s_, kt_) if (VAR != 1) { a##s_##0 = GL_A(0, kt_); a##s_##1 = GL_A(1, kt_); a##s_##2 = GL_A(2, kt_); a##s_##3 = GL_A(3, kt_); b##s_##0 = GL_B(0, kt_); b##s_##1 = GL_B(1, kt_); b##s_##2 = GL_B(2, kt_); b##s_##3 = GL_B(3, kt_); }
; #define LDS_STORE(s_, buf_) if (VAR != 2) { LDS_ST1(sA, 0, buf_, a##s_##0) LDS_ST1(sA, 1, buf_, a##s_##1) LDS_ST1(sA, 2, buf_, a##s_##2) LDS_ST1(sA, 3, buf_, a##s_##3) LDS_ST1(sB, 0, buf_, b##s_##0) LDS_ST1(sB, 1, buf_, b##s_##1) LDS_ST1(sB, 2, buf_, b##s_##2) LDS_ST1(sB, 3, buf_, b##s_##3) }
;     ...
;   GL_LOAD(0, 0)
;   GL_LOAD(1, 1)
;   LDS_STORE(0, 0)
;   if (VAR != 4) __syncthreads();
; #pragma unroll
;   for (int kt = 0; kt < nk; kt += 2) {
;     if (kt + 2 < nk) { GL_LOAD(0, kt + 2) }
;     MMA_TILE(0)
;     LDS_STORE(1, 1)
;     if (VAR != 4) __syncthreads();
;     if (kt + 3 < nk) { GL_LOAD(1, kt + 3) }
;     MMA_TILE(1)
;     if (kt + 2 < nk) { LDS_STORE(0, 0) }
;     if (VAR != 4) __syncthreads();
	ds_write_b128 v17, v[74:77] offset:49152
	v_mfma_f32_16x16x32_f16 v[24:27], v[94:97], v[110:113], v[24:27]
	ds_read_b128 v[94:97], v22 offset:34816
	v_mfma_f32_16x16x32_f16 v[114:117], v[118:121], v[106:109], v[114:117]
	s_waitcnt vmcnt(2)
	ds_write_b128 v18, v[142:145] offset:49152
	v_mfma_f32_16x16x32_f16 v[40:43], v[118:121], v[110:113], v[40:43]
	ds_read_b128 v[118:121], v22 offset:36864
	v_mfma_f32_16x16x32_f16 v[70:73], v[122:125], v[106:109], v[70:73]
	ds_read_b128 v[106:109], v23
	v_mfma_f32_16x16x32_f16 v[48:51], v[122:125], v[110:113], v[48:51]
	ds_read_b128 v[110:113], v23 offset:2048
	s_waitcnt lgkmcnt(1)
	v_mfma_f32_16x16x32_f16 v[36:39], v[58:61], v[106:109], v[36:39]
	ds_read_b128 v[122:125], v22 offset:38912
	s_waitcnt lgkmcnt(1)
	v_mfma_f32_16x16x32_f16 v[66:69], v[58:61], v[110:113], v[66:69]
	s_waitcnt vmcnt(1)
	ds_write_b128 v19, v[154:157] offset:49152
	v_mfma_f32_16x16x32_f16 v[44:47], v[94:97], v[106:109], v[44:47]
	s_waitcnt vmcnt(0)
	ds_write_b128 v20, v[158:161] offset:49152
	v_mfma_f32_16x16x32_f16 v[78:81], v[94:97], v[110:113], v[78:81]
	v_mfma_f32_16x16x32_f16 v[82:85], v[118:121], v[106:109], v[82:85]
	v_mfma_f32_16x16x32_f16 v[86:89], v[118:121], v[110:113], v[86:89]
	s_waitcnt lgkmcnt(2)
	v_mfma_f32_16x16x32_f16 v[28:31], v[122:125], v[106:109], v[28:31]
	ds_read_b128 v[106:109], v23 offset:4096
	v_mfma_f32_16x16x32_f16 v[32:35], v[122:125], v[110:113], v[32:35]
	ds_read_b128 v[110:113], v23 offset:6144
	s_waitcnt lgkmcnt(1)
	v_mfma_f32_16x16x32_f16 v[98:101], v[58:61], v[106:109], v[98:101]
	s_waitcnt lgkmcnt(0)
	v_mfma_f32_16x16x32_f16 v[52:55], v[58:61], v[110:113], v[52:55]
	global_load_dwordx4 v[58:61], v[0:1], off offset:3584
	v_mfma_f32_16x16x32_f16 v[102:105], v[94:97], v[106:109], v[102:105]
	v_mfma_f32_16x16x32_f16 v[24:27], v[94:97], v[110:113], v[24:27]
	v_mfma_f32_16x16x32_f16 v[114:117], v[118:121], v[106:109], v[114:117]
	v_mfma_f32_16x16x32_f16 v[40:43], v[118:121], v[110:113], v[40:43]
	v_mfma_f32_16x16x32_f16 v[70:73], v[122:125], v[106:109], v[70:73]
	global_load_dwordx4 v[106:109], v[2:3], off offset:3584
	global_load_dwordx4 v[126:129], v[4:5], off offset:3584
	global_load_dwordx4 v[134:137], v[14:15], off offset:3584
	global_load_dwordx4 v[94:97], v[10:11], off offset:3584
	global_load_dwordx4 v[162:165], v[12:13], off offset:3584
	global_load_dwordx4 v[166:169], v[8:9], off offset:3584
	global_load_dwordx4 v[190:193], v[6:7], off offset:3584
	s_waitcnt lgkmcnt(0)
	s_barrier
	v_mfma_f32_16x16x32_f16 v[48:51], v[122:125], v[110:113], v[48:51]
	ds_read_b128 v[62:65], v16 offset:49152
	ds_read_b128 v[90:93], v21 offset:16384
	s_waitcnt lgkmcnt(0)
	v_mfma_f32_16x16x32_f16 v[36:39], v[62:65], v[90:93], v[36:39]
	ds_read_b128 v[74:77], v16 offset:51200
	ds_read_b128 v[110:113], v21 offset:18432
	s_waitcnt lgkmcnt(0)
	v_mfma_f32_16x16x32_f16 v[66:69], v[62:65], v[110:113], v[66:69]
	ds_read_b128 v[118:121], v16 offset:53248
	v_mfma_f32_16x16x32_f16 v[44:47], v[74:77], v[90:93], v[44:47]
	ds_read_b128 v[122:125], v16 offset:55296
	v_mfma_f32_16x16x32_f16 v[78:81], v[74:77], v[110:113], v[78:81]
	s_waitcnt vmcnt(7)
	ds_write_b128 v17, v[58:61]
	s_waitcnt lgkmcnt(2)
	v_mfma_f32_16x16x32_f16 v[82:85], v[118:121], v[90:93], v[82:85]
	s_waitcnt vmcnt(6)
	ds_write_b128 v18, v[106:109]
	v_mfma_f32_16x16x32_f16 v[86:89], v[118:121], v[110:113], v[86:89]
	s_waitcnt vmcnt(5)
	ds_write_b128 v19, v[126:129]
	s_waitcnt lgkmcnt(3)
	v_mfma_f32_16x16x32_f16 v[28:31], v[122:125], v[90:93], v[28:31]
	ds_read_b128 v[90:93], v21 offset:20480
	v_mfma_f32_16x16x32_f16 v[32:35], v[122:125], v[110:113], v[32:35]
	ds_read_b128 v[110:113], v21 offset:22528
	s_waitcnt lgkmcnt(1)
	v_mfma_f32_16x16x32_f16 v[98:101], v[62:65], v[90:93], v[98:101]
	s_waitcnt vmcnt(4)
	ds_write_b128 v20, v[134:137]
	s_waitcnt lgkmcnt(1)
	v_mfma_f32_16x16x32_f16 v[52:55], v[62:65], v[110:113], v[52:55]
	ds_read_b128 v[62:65], v22 offset:49152
	v_mfma_f32_16x16x32_f16 v[102:105], v[74:77], v[90:93], v[102:105]
	s_waitcnt vmcnt(3)
	ds_write_b128 v17, v[94:97] offset:32768
	v_mfma_f32_16x16x32_f16 v[24:27], v[74:77], v[110:113], v[24:27]
	ds_read_b128 v[74:77], v22 offset:51200
	v_mfma_f32_16x16x32_f16 v[114:117], v[118:121], v[90:93], v[114:117]
	s_waitcnt vmcnt(2)
	ds_write_b128 v18, v[162:165] offset:32768
	v_mfma_f32_16x16x32_f16 v[40:43], v[118:121], v[110:113], v[40:43]
	ds_read_b128 v[118:121], v22 offset:53248
	v_mfma_f32_16x16x32_f16 v[70:73], v[122:125], v[90:93], v[70:73]
	ds_read_b128 v[90:93], v23 offset:16384
	v_mfma_f32_16x16x32_f16 v[48:51], v[122:125], v[110:113], v[48:51]
	ds_read_b128 v[110:113], v23 offset:18432
	s_waitcnt lgkmcnt(1)
	v_mfma_f32_16x16x32_f16 v[36:39], v[62:65], v[90:93], v[36:39]
	ds_read_b128 v[122:125], v22 offset:55296
	s_waitcnt lgkmcnt(1)
	v_mfma_f32_16x16x32_f16 v[66:69], v[62:65], v[110:113], v[66:69]
	s_waitcnt vmcnt(1)
	ds_write_b128 v19, v[166:169] offset:32768
	v_mfma_f32_16x16x32_f16 v[44:47], v[74:77], v[90:93], v[44:47]
	s_waitcnt vmcnt(0)
	ds_write_b128 v20, v[190:193] offset:32768
	v_mfma_f32_16x16x32_f16 v[78:81], v[74:77], v[110:113], v[78:81]
	v_mfma_f32_16x16x32_f16 v[82:85], v[118:121], v[90:93], v[82:85]
	v_mfma_f32_16x16x32_f16 v[86:89], v[118:121], v[110:113], v[86:89]
	s_waitcnt lgkmcnt(2)
	v_mfma_f32_16x16x32_f16 v[28:31], v[122:125], v[90:93], v[28:31]
	ds_read_b128 v[90:93], v23 offset:20480
	v_mfma_f32_16x16x32_f16 v[32:35], v[122:125], v[110:113], v[32:35]
	ds_read_b128 v[110:113], v23 offset:22528
	s_waitcnt lgkmcnt(1)
	v_mfma_f32_16x16x32_f16 v[98:101], v[62:65], v[90:93], v[98:101]
	s_waitcnt lgkmcnt(0)
	v_mfma_f32_16x16x32_f16 v[52:55], v[62:65], v[110:113], v[52:55]
	global_load_dwordx4 v[62:65], v[0:1], off offset:3712
	v_mfma_f32_16x16x32_f16 v[102:105], v[74:77], v[90:93], v[102:105]
	v_mfma_f32_16x16x32_f16 v[24:27], v[74:77], v[110:113], v[24:27]
	v_mfma_f32_16x16x32_f16 v[114:117], v[118:121], v[90:93], v[114:117]
	v_mfma_f32_16x16x32_f16 v[40:43], v[118:121], v[110:113], v[40:43]
	v_mfma_f32_16x16x32_f16 v[70:73], v[122:125], v[90:93], v[70:73]
	global_load_dwordx4 v[90:93], v[2:3], off offset:3712
	global_load_dwordx4 v[130:133], v[4:5], off offset:3712
	global_load_dwordx4 v[138:141], v[14:15], off offset:3712
	global_load_dwordx4 v[74:77], v[10:11], off offset:3712
	global_load_dwordx4 v[142:145], v[12:13], off offset:3712
	global_load_dwordx4 v[154:157], v[8:9], off offset:3712
	global_load_dwordx4 v[158:161], v[6:7], off offset:3712
	s_waitcnt lgkmcnt(0)
	s_barrier
; #define GL_LOAD(s_, kt_) if (VAR != 1) { a##s_##0 = GL_A(0, kt_); a##s_##1 = GL_A(1, kt_); a##s_##2 = GL_A(2, kt_); a##s_##3 = GL_A(3, kt_); b##s_##0 = GL_B(0, kt_); b##s_##1 = GL_B(1, kt_); b##s_##2 = GL_B(2, kt_); b##s_##3 = GL_B(3, kt_); }
; #define LDS_STORE(s_, buf_) if (VAR != 2) { LDS_ST1(sA, 0, buf_, a##s_##0) LDS_ST1(sA, 1, buf_, a##s_##1) LDS_ST1(sA, 2, buf_, a##s_##2) LDS_ST1(sA, 3, buf_, a##s_##3) LDS_ST1(sB, 0, buf_, b##s_##0) LDS_ST1(sB, 1, buf_, b##s_##1) LDS_ST1(sB, 2, buf_, b##s_##2) LDS_ST1(sB, 3, buf_, b##s_##3) }
;     ...
;   GL_LOAD(0, 0)
;   GL_LOAD(1, 1)
;   LDS_STORE(0, 0)
;   if (VAR != 4) __syncthreads();
; #pragma unroll
;   for (int kt = 0; kt < nk; kt += 2) {
;     if (kt + 2 < nk) { GL_LOAD(0, kt + 2) }
;     MMA_TILE(0)
;     LDS_STORE(1, 1)
;     if (VAR != 4) __syncthreads();
;     if (kt + 3 < nk) { GL_LOAD(1, kt + 3) }
;     MMA_TILE(1)
;     if (kt + 2 < nk) { LDS_STORE(0, 0) }
;     if (VAR != 4) __syncthreads();
	v_mfma_f32_16x16x32_f16 v[48:51], v[122:125], v[110:113], v[48:51]
	ds_read_b128 v[58:61], v16 offset:32768
	ds_read_b128 v[106:109], v21
	s_waitcnt lgkmcnt(0)
	v_mfma_f32_16x16x32_f16 v[36:39], v[58:61], v[106:109], v[36:39]
	ds_read_b128 v[94:97], v16 offset:34816
	ds_read_b128 v[110:113], v21 offset:2048
	s_waitcnt lgkmcnt(0)
	v_mfma_f32_16x16x32_f16 v[66:69], v[58:61], v[110:113], v[66:69]
	ds_read_b128 v[118:121], v16 offset:36864
	v_mfma_f32_16x16x32_f16 v[44:47], v[94:97], v[106:109], v[44:47]
	ds_read_b128 v[122:125], v16 offset:38912
	v_mfma_f32_16x16x32_f16 v[78:81], v[94:97], v[110:113], v[78:81]
	s_waitcnt vmcnt(7)
	ds_write_b128 v17, v[62:65] offset:16384
	s_waitcnt lgkmcnt(2)
	v_mfma_f32_16x16x32_f16 v[82:85], v[118:121], v[106:109], v[82:85]
	s_waitcnt vmcnt(6)
	ds_write_b128 v18, v[90:93] offset:16384
	v_mfma_f32_16x16x32_f16 v[86:89], v[118:121], v[110:113], v[86:89]
	s_waitcnt vmcnt(5)
	ds_write_b128 v19, v[130:133] offset:16384
	s_waitcnt lgkmcnt(3)
	v_mfma_f32_16x16x32_f16 v[28:31], v[122:125], v[106:109], v[28:31]
	ds_read_b128 v[106:109], v21 offset:4096
	v_mfma_f32_16x16x32_f16 v[32:35], v[122:125], v[110:113], v[32:35]
	ds_read_b128 v[110:113], v21 offset:6144
	s_waitcnt lgkmcnt(1)
	v_mfma_f32_16x16x32_f16 v[98:101], v[58:61], v[106:109], v[98:101]
	s_waitcnt vmcnt(4)
	ds_write_b128 v20, v[138:141] offset:16384
	s_waitcnt lgkmcnt(1)
	v_mfma_f32_16x16x32_f16 v[52:55], v[58:61], v[110:113], v[52:55]
	ds_read_b128 v[58:61], v22 offset:32768
	v_mfma_f32_16x16x32_f16 v[102:105], v[94:97], v[106:109], v[102:105]
	s_waitcnt vmcnt(3)
	ds_write_b128 v17, v[74:77] offset:49152
	v_mfma_f32_16x16x32_f16 v[24:27], v[94:97], v[110:113], v[24:27]
	ds_read_b128 v[94:97], v22 offset:34816
	v_mfma_f32_16x16x32_f16 v[114:117], v[118:121], v[106:109], v[114:117]
	s_waitcnt vmcnt(2)
	ds_write_b128 v18, v[142:145] offset:49152
	v_mfma_f32_16x16x32_f16 v[40:43], v[118:121], v[110:113], v[40:43]
	ds_read_b128 v[118:121], v22 offset:36864
	v_mfma_f32_16x16x32_f16 v[70:73], v[122:125], v[106:109], v[70:73]
	ds_read_b128 v[106:109], v23
	v_mfma_f32_16x16x32_f16 v[48:51], v[122:125], v[110:113], v[48:51]
	ds_read_b128 v[110:113], v23 offset:2048
	s_waitcnt lgkmcnt(1)
	v_mfma_f32_16x16x32_f16 v[36:39], v[58:61], v[106:109], v[36:39]
	ds_read_b128 v[122:125], v22 offset:38912
	s_waitcnt lgkmcnt(1)
	v_mfma_f32_16x16x32_f16 v[66:69], v[58:61], v[110:113], v[66:69]
	s_waitcnt vmcnt(1)
	ds_write_b128 v19, v[154:157] offset:49152
	v_mfma_f32_16x16x32_f16 v[44:47], v[94:97], v[106:109], v[44:47]
	s_waitcnt vmcnt(0)
	ds_write_b128 v20, v[158:161] offset:49152
	v_mfma_f32_16x16x32_f16 v[78:81], v[94:97], v[110:113], v[78:81]
	v_mfma_f32_16x16x32_f16 v[82:85], v[118:121], v[106:109], v[82:85]
	v_mfma_f32_16x16x32_f16 v[86:89], v[118:121], v[110:113], v[86:89]
	s_waitcnt lgkmcnt(2)
	v_mfma_f32_16x16x32_f16 v[28:31], v[122:125], v[106:109], v[28:31]
	ds_read_b128 v[106:109], v23 offset:4096
	v_mfma_f32_16x16x32_f16 v[32:35], v[122:125], v[110:113], v[32:35]
	ds_read_b128 v[110:113], v23 offset:6144
	s_waitcnt lgkmcnt(1)
	v_mfma_f32_16x16x32_f16 v[98:101], v[58:61], v[106:109], v[98:101]
	s_waitcnt lgkmcnt(0)
	v_mfma_f32_16x16x32_f16 v[52:55], v[58:61], v[110:113], v[52:55]
	global_load_dwordx4 v[58:61], v[0:1], off offset:3840
	v_mfma_f32_16x16x32_f16 v[102:105], v[94:97], v[106:109], v[102:105]
	v_mfma_f32_16x16x32_f16 v[24:27], v[94:97], v[110:113], v[24:27]
	v_mfma_f32_16x16x32_f16 v[114:117], v[118:121], v[106:109], v[114:117]
	v_mfma_f32_16x16x32_f16 v[40:43], v[118:121], v[110:113], v[40:43]
	v_mfma_f32_16x16x32_f16 v[70:73], v[122:125], v[106:109], v[70:73]
	global_load_dwordx4 v[106:109], v[2:3], off offset:3840
	global_load_dwordx4 v[126:129], v[4:5], off offset:3840
	global_load_dwordx4 v[134:137], v[14:15], off offset:3840
	global_load_dwordx4 v[94:97], v[10:11], off offset:3840
	global_load_dwordx4 v[162:165], v[12:13], off offset:3840
	global_load_dwordx4 v[166:169], v[8:9], off offset:3840
	global_load_dwordx4 v[190:193], v[6:7], off offset:3840
	s_waitcnt lgkmcnt(0)
	s_barrier
	v_mfma_f32_16x16x32_f16 v[48:51], v[122:125], v[110:113], v[48:51]
	ds_read_b128 v[62:65], v16 offset:49152
	ds_read_b128 v[90:93], v21 offset:16384
	s_waitcnt lgkmcnt(0)
	v_mfma_f32_16x16x32_f16 v[36:39], v[62:65], v[90:93], v[36:39]
	ds_read_b128 v[74:77], v16 offset:51200
	ds_read_b128 v[110:113], v21 offset:18432
	s_waitcnt lgkmcnt(0)
	v_mfma_f32_16x16x32_f16 v[66:69], v[62:65], v[110:113], v[66:69]
	ds_read_b128 v[118:121], v16 offset:53248
	v_mfma_f32_16x16x32_f16 v[44:47], v[74:77], v[90:93], v[44:47]
	ds_read_b128 v[122:125], v16 offset:55296
	v_mfma_f32_16x16x32_f16 v[78:81], v[74:77], v[110:113], v[78:81]
	s_waitcnt vmcnt(7)
	ds_write_b128 v17, v[58:61]
	s_waitcnt lgkmcnt(2)
	v_mfma_f32_16x16x32_f16 v[82:85], v[118:121], v[90:93], v[82:85]
	s_waitcnt vmcnt(6)
	ds_write_b128 v18, v[106:109]
	v_mfma_f32_16x16x32_f16 v[86:89], v[118:121], v[110:113], v[86:89]
	s_waitcnt vmcnt(5)
	ds_write_b128 v19, v[126:129]
	s_waitcnt lgkmcnt(3)
	v_mfma_f32_16x16x32_f16 v[28:31], v[122:125], v[90:93], v[28:31]
	ds_read_b128 v[90:93], v21 offset:20480
	v_mfma_f32_16x16x32_f16 v[32:35], v[122:125], v[110:113], v[32:35]
	ds_read_b128 v[110:113], v21 offset:22528
	s_waitcnt lgkmcnt(1)
	v_mfma_f32_16x16x32_f16 v[98:101], v[62:65], v[90:93], v[98:101]
	s_waitcnt vmcnt(4)
	ds_write_b128 v20, v[134:137]
	s_waitcnt lgkmcnt(1)
	v_mfma_f32_16x16x32_f16 v[52:55], v[62:65], v[110:113], v[52:55]
	ds_read_b128 v[62:65], v22 offset:49152
	v_mfma_f32_16x16x32_f16 v[102:105], v[74:77], v[90:93], v[102:105]
	s_waitcnt vmcnt(3)
; #define GL_LOAD(s_, kt_) if (VAR != 1) { a##s_##0 = GL_A(0, kt_); a##s_##1 = GL_A(1, kt_); a##s_##2 = GL_A(2, kt_); a##s_##3 = GL_A(3, kt_); b##s_##0 = GL_B(0, kt_); b##s_##1 = GL_B(1, kt_); b##s_##2 = GL_B(2, kt_); b##s_##3 = GL_B(3, kt_); }
; #define LDS_STORE(s_, buf_) if (VAR != 2) { LDS_ST1(sA, 0, buf_, a##s_##0) LDS_ST1(sA, 1, buf_, a##s_##1) LDS_ST1(sA, 2, buf_, a##s_##2) LDS_ST1(sA, 3, buf_, a##s_##3) LDS_ST1(sB, 0, buf_, b##s_##0) LDS_ST1(sB, 1, buf_, b##s_##1) LDS_ST1(sB, 2, buf_, b##s_##2) LDS_ST1(sB, 3, buf_, b##s_##3) }
;     ...
;   GL_LOAD(0, 0)
;   GL_LOAD(1, 1)
;   LDS_STORE(0, 0)
;   if (VAR != 4) __syncthreads();
; #pragma unroll
;   for (int kt = 0; kt < nk; kt += 2) {
;     if (kt + 2 < nk) { GL_LOAD(0, kt + 2) }
;     MMA_TILE(0)
;     LDS_STORE(1, 1)
;     if (VAR != 4) __syncthreads();
;     if (kt + 3 < nk) { GL_LOAD(1, kt + 3) }
;     MMA_TILE(1)
;     if (kt + 2 < nk) { LDS_STORE(0, 0) }
;     if (VAR != 4) __syncthreads();
	ds_write_b128 v17, v[94:97] offset:32768
	v_mfma_f32_16x16x32_f16 v[24:27], v[74:77], v[110:113], v[24:27]
	ds_read_b128 v[74:77], v22 offset:51200
	v_mfma_f32_16x16x32_f16 v[114:117], v[118:121], v[90:93], v[114:117]
	s_waitcnt vmcnt(2)
	ds_write_b128 v18, v[162:165] offset:32768
	v_mfma_f32_16x16x32_f16 v[40:43], v[118:121], v[110:113], v[40:43]
	ds_read_b128 v[118:121], v22 offset:53248
	v_mfma_f32_16x16x32_f16 v[70:73], v[122:125], v[90:93], v[70:73]
	ds_read_b128 v[90:93], v23 offset:16384
	v_mfma_f32_16x16x32_f16 v[48:51], v[122:125], v[110:113], v[48:51]
	ds_read_b128 v[110:113], v23 offset:18432
	s_waitcnt lgkmcnt(1)
	v_mfma_f32_16x16x32_f16 v[36:39], v[62:65], v[90:93], v[36:39]
	ds_read_b128 v[122:125], v22 offset:55296
	s_waitcnt lgkmcnt(1)
	v_mfma_f32_16x16x32_f16 v[66:69], v[62:65], v[110:113], v[66:69]
	s_waitcnt vmcnt(1)
	ds_write_b128 v19, v[166:169] offset:32768
	v_mfma_f32_16x16x32_f16 v[44:47], v[74:77], v[90:93], v[44:47]
	s_waitcnt vmcnt(0)
	ds_write_b128 v20, v[190:193] offset:32768
	v_mfma_f32_16x16x32_f16 v[78:81], v[74:77], v[110:113], v[78:81]
	v_mfma_f32_16x16x32_f16 v[82:85], v[118:121], v[90:93], v[82:85]
	v_mfma_f32_16x16x32_f16 v[86:89], v[118:121], v[110:113], v[86:89]
	s_waitcnt lgkmcnt(2)
	v_mfma_f32_16x16x32_f16 v[28:31], v[122:125], v[90:93], v[28:31]
	ds_read_b128 v[90:93], v23 offset:20480
	v_mfma_f32_16x16x32_f16 v[32:35], v[122:125], v[110:113], v[32:35]
	ds_read_b128 v[110:113], v23 offset:22528
	s_waitcnt lgkmcnt(1)
	v_mfma_f32_16x16x32_f16 v[98:101], v[62:65], v[90:93], v[98:101]
	s_waitcnt lgkmcnt(0)
	v_mfma_f32_16x16x32_f16 v[52:55], v[62:65], v[110:113], v[52:55]
	global_load_dwordx4 v[62:65], v[0:1], off offset:3968
	global_load_dwordx4 v[0:3], v[2:3], off offset:3968
	v_mfma_f32_16x16x32_f16 v[102:105], v[74:77], v[90:93], v[102:105]
	v_mfma_f32_16x16x32_f16 v[24:27], v[74:77], v[110:113], v[24:27]
	v_mfma_f32_16x16x32_f16 v[114:117], v[118:121], v[90:93], v[114:117]
	v_mfma_f32_16x16x32_f16 v[40:43], v[118:121], v[110:113], v[40:43]
	v_mfma_f32_16x16x32_f16 v[70:73], v[122:125], v[90:93], v[70:73]
	global_load_dwordx4 v[90:93], v[4:5], off offset:3968
	global_load_dwordx4 v[130:133], v[14:15], off offset:3968
	global_load_dwordx4 v[74:77], v[10:11], off offset:3968
	global_load_dwordx4 v[10:13], v[12:13], off offset:3968
	global_load_dwordx4 v[138:141], v[8:9], off offset:3968
	global_load_dwordx4 v[4:7], v[6:7], off offset:3968
	s_waitcnt lgkmcnt(0)
	s_barrier
	ds_read_b128 v[58:61], v16 offset:32768
	v_mfma_f32_16x16x32_f16 v[48:51], v[122:125], v[110:113], v[48:51]
	ds_read_b128 v[94:97], v16 offset:34816
	ds_read_b128 v[106:109], v21
	ds_read_b128 v[110:113], v21 offset:2048
	ds_read_b128 v[118:121], v16 offset:36864
	ds_read_b128 v[122:125], v16 offset:38912
	s_waitcnt lgkmcnt(3)
	v_mfma_f32_16x16x32_f16 v[36:39], v[58:61], v[106:109], v[36:39]
	v_mfma_f32_16x16x32_f16 v[44:47], v[94:97], v[106:109], v[44:47]
	s_waitcnt lgkmcnt(1)
	v_mfma_f32_16x16x32_f16 v[82:85], v[118:121], v[106:109], v[82:85]
	s_waitcnt lgkmcnt(0)
	v_mfma_f32_16x16x32_f16 v[28:31], v[122:125], v[106:109], v[28:31]
	v_mfma_f32_16x16x32_f16 v[66:69], v[58:61], v[110:113], v[66:69]
	v_mfma_f32_16x16x32_f16 v[78:81], v[94:97], v[110:113], v[78:81]
	v_mfma_f32_16x16x32_f16 v[86:89], v[118:121], v[110:113], v[86:89]
	v_mfma_f32_16x16x32_f16 v[32:35], v[122:125], v[110:113], v[32:35]
	ds_read_b128 v[106:109], v21 offset:4096
	ds_read_b128 v[110:113], v21 offset:6144
	s_waitcnt lgkmcnt(1)
	v_mfma_f32_16x16x32_f16 v[98:101], v[58:61], v[106:109], v[98:101]
	v_mfma_f32_16x16x32_f16 v[102:105], v[94:97], v[106:109], v[102:105]
	v_mfma_f32_16x16x32_f16 v[114:117], v[118:121], v[106:109], v[114:117]
	v_mfma_f32_16x16x32_f16 v[70:73], v[122:125], v[106:109], v[70:73]
	s_waitcnt lgkmcnt(0)
	v_mfma_f32_16x16x32_f16 v[52:55], v[58:61], v[110:113], v[52:55]
	ds_read_b128 v[58:61], v22 offset:32768
	v_mfma_f32_16x16x32_f16 v[24:27], v[94:97], v[110:113], v[24:27]
	v_mfma_f32_16x16x32_f16 v[40:43], v[118:121], v[110:113], v[40:43]
	v_mfma_f32_16x16x32_f16 v[48:51], v[122:125], v[110:113], v[48:51]
	ds_read_b128 v[94:97], v22 offset:34816
	ds_read_b128 v[106:109], v23
	ds_read_b128 v[110:113], v23 offset:2048
	ds_read_b128 v[118:121], v22 offset:36864
	ds_read_b128 v[122:125], v22 offset:38912
	s_waitcnt lgkmcnt(3)
	v_mfma_f32_16x16x32_f16 v[36:39], v[58:61], v[106:109], v[36:39]
	v_mfma_f32_16x16x32_f16 v[44:47], v[94:97], v[106:109], v[44:47]
	s_waitcnt lgkmcnt(1)
	v_mfma_f32_16x16x32_f16 v[82:85], v[118:121], v[106:109], v[82:85]
	s_waitcnt lgkmcnt(0)
	v_mfma_f32_16x16x32_f16 v[28:31], v[122:125], v[106:109], v[28:31]
	v_mfma_f32_16x16x32_f16 v[66:69], v[58:61], v[110:113], v[66:69]
	v_mfma_f32_16x16x32_f16 v[78:81], v[94:97], v[110:113], v[78:81]
	v_mfma_f32_16x16x32_f16 v[86:89], v[118:121], v[110:113], v[86:89]
	v_mfma_f32_16x16x32_f16 v[32:35], v[122:125], v[110:113], v[32:35]
	ds_read_b128 v[106:109], v23 offset:4096
	ds_read_b128 v[110:113], v23 offset:6144
	s_waitcnt vmcnt(7)
	ds_write_b128 v17, v[62:65] offset:16384
	s_waitcnt vmcnt(6)
	ds_write_b128 v18, v[0:3] offset:16384
	s_waitcnt vmcnt(5)
	ds_write_b128 v19, v[90:93] offset:16384
	s_waitcnt vmcnt(4)
	ds_write_b128 v20, v[130:133] offset:16384
	s_waitcnt lgkmcnt(5)
	v_mfma_f32_16x16x32_f16 v[98:101], v[58:61], v[106:109], v[98:101]
	s_waitcnt vmcnt(3)
	ds_write_b128 v17, v[74:77] offset:49152
	s_waitcnt vmcnt(2)
	ds_write_b128 v18, v[10:13] offset:49152
	s_waitcnt vmcnt(1)
	ds_write_b128 v19, v[138:141] offset:49152
	s_waitcnt vmcnt(0)
	ds_write_b128 v20, v[4:7] offset:49152
	s_waitcnt lgkmcnt(0)
	s_barrier
; DI int TIDX() { int t = threadIdx.x; asm volatile("" : "+v"(t)); return t; }
; DI unsigned pack2(float lo, float hi) { f2_t v = {lo, hi}; h2_t b = __builtin_convertvector(v, h2_t); return __builtin_bit_cast(unsigned, b); }
; #define GL_LOAD(s_, kt_) if (VAR != 1) { a##s_##0 = GL_A(0, kt_); a##s_##1 = GL_A(1, kt_); a##s_##2 = GL_A(2, kt_); a##s_##3 = GL_A(3, kt_); b##s_##0 = GL_B(0, kt_); b##s_##1 = GL_B(1, kt_); b##s_##2 = GL_B(2, kt_); b##s_##3 = GL_B(3, kt_); }
; #define LDS_STORE(s_, buf_) if (VAR != 2) { LDS_ST1(sA, 0, buf_, a##s_##0) LDS_ST1(sA, 1, buf_, a##s_##1) LDS_ST1(sA, 2, buf_, a##s_##2) LDS_ST1(sA, 3, buf_, a##s_##3) LDS_ST1(sB, 0, buf_, b##s_##0) LDS_ST1(sB, 1, buf_, b##s_##1) LDS_ST1(sB, 2, buf_, b##s_##2) LDS_ST1(sB, 3, buf_, b##s_##3) }
;     ...
;   for (int kt = 0; kt < nk; kt += 2) {
;     if (kt + 2 < nk) { GL_LOAD(0, kt + 2) }
;     MMA_TILE(0)
;     LDS_STORE(1, 1)
;     if (VAR != 4) __syncthreads();
;     if (kt + 3 < nk) { GL_LOAD(1, kt + 3) }
;     MMA_TILE(1)
;     if (kt + 2 < nk) { LDS_STORE(0, 0) }
;     if (VAR != 4) __syncthreads();
; DI void epi_residual(const f32x4 (&v)[4][4], int row0, int col0, const float* xsrc, float* x, bf16_t* xb, float* ssq_out, bool write_xb, bool write_ssq) {
;   const int lane = TIDX() & 63, lr = lane & 15, g = lane >> 4;
; #pragma unroll
;   for (int mt = 0; mt < 4; ++mt) {
;     const int row = row0 + mt * 16 + lr;
;     float ss = 0.f;
; #pragma unroll
;     for (int nt = 0; nt < 4; ++nt) {
;       const int col = col0 + nt * 16 + 4 * g;
;       float4* px = (float4*)(x + (size_t)row * DM + col);
;       float4 o = *(const float4*)(xsrc + (size_t)row * DM + col);
;       o.x += v[mt][nt][0]; o.y += v[mt][nt][1]; o.z += v[mt][nt][2]; o.w += v[mt][nt][3];
;       *px = o;
;       ss += (o.x * o.x + o.y * o.y) + (o.z * o.z + o.w * o.w);
;       if (write_xb) *(uint2*)(xb + (size_t)row * DM + col) = make_uint2(pack2(o.x, o.y), pack2(o.z, o.w));
;     }
;     if (write_ssq) {
;       ss += __shfl_xor(ss, 16); ss += __shfl_xor(ss, 32);
;       if (g == 0) ssq_out[(size_t)row * 16 + (col0 >> 6)] = ss;
;     }
;   }
	v_mfma_f32_16x16x32_f16 v[52:55], v[58:61], v[110:113], v[52:55]
	ds_read_b128 v[4:7], v16 offset:49152
	v_add_u32_e32 v130, s4, v57
	v_mfma_f32_16x16x32_f16 v[0:3], v[118:121], v[110:113], v[40:43]
	v_readlane_b32 s4, v254, 45
	v_readlane_b32 s5, v254, 46
	v_mfma_f32_16x16x32_f16 v[8:11], v[122:125], v[110:113], v[48:51]
	ds_read_b128 v[12:15], v16 offset:51200
	ds_read_b128 v[40:43], v21 offset:16384
	s_nop 0
	ds_read_b128 v[48:51], v21 offset:18432
	ds_read_b128 v[58:61], v16 offset:53248
	ds_read_b128 v[16:19], v16 offset:55296
	v_mfma_f32_16x16x32_f16 v[102:105], v[94:97], v[106:109], v[102:105]
	v_mfma_f32_16x16x32_f16 v[114:117], v[118:121], v[106:109], v[114:117]
	v_mfma_f32_16x16x32_f16 v[70:73], v[122:125], v[106:109], v[70:73]
	v_mfma_f32_16x16x32_f16 v[24:27], v[94:97], v[110:113], v[24:27]
	s_waitcnt lgkmcnt(3)
	v_mfma_f32_16x16x32_f16 v[36:39], v[4:7], v[40:43], v[36:39]
	v_mfma_f32_16x16x32_f16 v[44:47], v[12:15], v[40:43], v[44:47]
	s_waitcnt lgkmcnt(1)
	v_mfma_f32_16x16x32_f16 v[62:65], v[58:61], v[40:43], v[82:85]
	s_waitcnt lgkmcnt(0)
	v_mfma_f32_16x16x32_f16 v[28:31], v[16:19], v[40:43], v[28:31]
	ds_read_b128 v[40:43], v21 offset:20480
	ds_read_b128 v[74:77], v21 offset:22528
	ds_read_b128 v[82:85], v23 offset:16384
	ds_read_b128 v[90:93], v23 offset:18432
	ds_read_b128 v[94:97], v22 offset:49152
	ds_read_b128 v[106:109], v22 offset:51200
	ds_read_b128 v[110:113], v23 offset:20480
	ds_read_b128 v[118:121], v23 offset:22528
	ds_read_b128 v[122:125], v22 offset:53248
	ds_read_b128 v[126:129], v22 offset:55296
	v_mfma_f32_16x16x32_f16 v[66:69], v[4:7], v[48:51], v[66:69]
	s_waitcnt lgkmcnt(0)
	s_barrier
	s_setprio 0
	v_mfma_f32_16x16x32_f16 v[78:81], v[12:15], v[48:51], v[78:81]
	v_mfma_f32_16x16x32_f16 v[20:23], v[58:61], v[48:51], v[86:89]
	v_mfma_f32_16x16x32_f16 v[32:35], v[16:19], v[48:51], v[32:35]
	v_mov_b32_e32 v49, v148
	v_or_b32_e32 v48, s10, v56
	v_and_or_b32 v50, v49, 15, v130
	v_bfe_u32 v134, v49, 4, 2
	v_ashrrev_i32_e32 v51, 31, v50
	v_mfma_f32_16x16x32_f16 v[86:89], v[4:7], v[40:43], v[98:101]
	v_lshl_or_b32 v135, v134, 2, v48
	v_lshrrev_b32_e32 v150, 4, v48
	v_lshl_add_u64 v[48:49], s[4:5], 0, v[150:151]
	v_mfma_f32_16x16x32_f16 v[98:101], v[12:15], v[40:43], v[102:105]
	v_lshlrev_b32_e32 v150, 2, v135
	v_readlane_b32 s4, v254, 43
	v_readlane_b32 s5, v254, 44
	v_mfma_f32_16x16x32_f16 v[102:105], v[58:61], v[40:43], v[114:117]
	v_cmp_eq_u32_e32 vcc, 0, v134
	s_nop 1
	v_lshlrev_b64 v[114:115], 12, v[50:51]
	v_lshl_add_u64 v[114:115], s[12:13], 0, v[114:115]
	v_lshl_add_u64 v[130:131], v[114:115], 0, v[150:151]
	v_mfma_f32_16x16x32_f16 v[70:73], v[16:19], v[40:43], v[70:73]
	global_load_dwordx4 v[40:43], v[130:131], off
	v_lshlrev_b64 v[114:115], 11, v[50:51]
	v_lshl_add_u64 v[132:133], s[4:5], 0, v[114:115]
	v_mfma_f32_16x16x32_f16 v[36:39], v[94:97], v[82:85], v[36:39]
	v_mfma_f32_16x16x32_f16 v[4:7], v[4:7], v[74:77], v[52:55]
	s_nop 2
	v_lshlrev_b32_e32 v52, 1, v135
	v_mov_b32_e32 v53, v151
	v_lshl_add_u64 v[54:55], v[132:133], 0, v[52:53]
	v_mfma_f32_16x16x32_f16 v[114:117], v[12:15], v[74:77], v[24:27]
	s_waitcnt vmcnt(0)
	v_pk_add_f32 v[36:37], v[36:37], v[40:41]
	v_pk_add_f32 v[38:39], v[38:39], v[42:43]
	v_cvt_pk_f16_f32 v40, v36, v37
	v_cvt_pk_f16_f32 v41, v38, v39
	global_store_dwordx4 v[130:131], v[36:39], off
	global_store_dwordx2 v[54:55], v[40:41], off
	global_load_dwordx4 v[24:27], v[130:131], off offset:64
	v_mfma_f32_16x16x32_f16 v[12:15], v[106:109], v[82:85], v[44:47]
	v_mfma_f32_16x16x32_f16 v[0:3], v[58:61], v[74:77], v[0:3]
	v_mfma_f32_16x16x32_f16 v[58:61], v[16:19], v[74:77], v[8:11]
	s_waitcnt vmcnt(0)
	s_nop 4
	v_pk_add_f32 v[12:13], v[12:13], v[24:25]
	v_pk_add_f32 v[14:15], v[14:15], v[26:27]
	v_cvt_pk_f16_f32 v24, v12, v13
	v_cvt_pk_f16_f32 v25, v14, v15
	global_store_dwordx4 v[130:131], v[12:15], off offset:64
	global_store_dwordx2 v[54:55], v[24:25], off offset:32
	global_load_dwordx4 v[8:11], v[130:131], off offset:128
	v_mfma_f32_16x16x32_f16 v[16:19], v[122:125], v[82:85], v[62:65]
	v_mul_f32_e64 v12, v12, v12
	v_mul_f32_e64 v13, v13, v13
	v_pk_mul_f32 v[14:15], v[14:15], v[14:15]
	v_add_f32_e32 v12, v12, v13
	v_mfma_f32_16x16x32_f16 v[44:47], v[94:97], v[90:93], v[66:69]
	v_add_f32_e32 v14, v14, v15
	v_add_f32_e32 v12, v12, v14
	s_waitcnt vmcnt(0)
	v_pk_add_f32 v[8:9], v[16:17], v[8:9]
	v_pk_add_f32 v[10:11], v[18:19], v[10:11]
	v_cvt_pk_f16_f32 v24, v8, v9
	v_cvt_pk_f16_f32 v25, v10, v11
	global_store_dwordx4 v[130:131], v[8:11], off offset:128
	global_store_dwordx2 v[54:55], v[24:25], off offset:64
	global_load_dwordx4 v[24:27], v[130:131], off offset:192
	v_mfma_f32_16x16x32_f16 v[16:19], v[126:129], v[82:85], v[28:31]
	v_mul_f32_e64 v66, v36, v36
	v_mul_f32_e64 v67, v37, v37
	v_pk_mul_f32 v[68:69], v[38:39], v[38:39]
	v_pk_mul_f32 v[8:9], v[8:9], v[8:9]
	v_pk_mul_f32 v[10:11], v[10:11], v[10:11]
	v_add_f32_e32 v8, v8, v9
	v_add_f32_e32 v10, v10, v11
	v_add_f32_e32 v8, v8, v10
	v_mfma_f32_16x16x32_f16 v[40:43], v[106:109], v[90:93], v[78:81]
	s_waitcnt vmcnt(0)
	v_pk_add_f32 v[62:63], v[16:17], v[24:25]
	v_add_f32_e32 v16, v68, v69
	v_add_f32_e32 v17, v66, v67
	v_pk_add_f32 v[64:65], v[18:19], v[26:27]
	v_add_f32_e32 v16, v17, v16
	v_pk_mul_f32 v[74:75], v[62:63], v[62:63]
	v_pk_mul_f32 v[76:77], v[64:65], v[64:65]
	v_add_f32_e32 v12, v16, v12
	v_add_f32_e32 v66, v12, v8
	v_mfma_f32_16x16x32_f16 v[12:15], v[94:97], v[118:121], v[4:7]
	global_store_dwordx4 v[130:131], v[62:65], off offset:192
	s_nop 1
	v_add_f32_e32 v4, v76, v77
	v_add_f32_e32 v5, v74, v75
	v_add_f32_e32 v4, v5, v4
	v_add_f32_e32 v66, v66, v4
	ds_bpermute_b32 v67, v189, v66
	v_cvt_pk_f16_f32 v62, v62, v63
	v_cvt_pk_f16_f32 v63, v64, v65
	global_store_dwordx2 v[54:55], v[62:63], off offset:96
	v_mfma_f32_16x16x32_f16 v[36:39], v[122:125], v[90:93], v[20:23]
	s_waitcnt lgkmcnt(0)
	v_add_f32_e32 v54, v66, v67
	ds_bpermute_b32 v55, v188, v54
	v_mfma_f32_16x16x32_f16 v[32:35], v[126:129], v[90:93], v[32:35]
	v_mfma_f32_16x16x32_f16 v[28:31], v[94:97], v[110:113], v[86:89]
	v_mfma_f32_16x16x32_f16 v[24:27], v[106:109], v[110:113], v[98:101]
	v_mfma_f32_16x16x32_f16 v[20:23], v[122:125], v[110:113], v[102:105]
	v_mfma_f32_16x16x32_f16 v[16:19], v[126:129], v[110:113], v[70:73]
	v_mfma_f32_16x16x32_f16 v[8:11], v[106:109], v[118:121], v[114:117]
	v_mfma_f32_16x16x32_f16 v[4:7], v[122:125], v[118:121], v[0:3]
	v_mfma_f32_16x16x32_f16 v[0:3], v[126:129], v[118:121], v[58:61]
	s_and_saveexec_b64 s[4:5], vcc
	s_cbranch_execz .LBB0_1374
	s_waitcnt lgkmcnt(0)
	v_add_f32_e32 v58, v54, v55
	v_lshlrev_b64 v[54:55], 6, v[50:51]
	v_lshl_add_u64 v[54:55], v[48:49], 0, v[54:55]
	global_store_dword v[54:55], v58, off

; DI int BIDX() { int b = blockIdx.x; asm volatile("" : "+s"(b)); return b; }
; #define GL_LOAD(s_, kt_) if (VAR != 1) { a##s_##0 = GL_A(0, kt_); a##s_##1 = GL_A(1, kt_); a##s_##2 = GL_A(2, kt_); a##s_##3 = GL_A(3, kt_); b##s_##0 = GL_B(0, kt_); b##s_##1 = GL_B(1, kt_); b##s_##2 = GL_B(2, kt_); b##s_##3 = GL_B(3, kt_); }
; #define LDS_STORE(s_, buf_) if (VAR != 2) { LDS_ST1(sA, 0, buf_, a##s_##0) LDS_ST1(sA, 1, buf_, a##s_##1) LDS_ST1(sA, 2, buf_, a##s_##2) LDS_ST1(sA, 3, buf_, a##s_##3) LDS_ST1(sB, 0, buf_, b##s_##0) LDS_ST1(sB, 1, buf_, b##s_##1) LDS_ST1(sB, 2, buf_, b##s_##2) LDS_ST1(sB, 3, buf_, b##s_##3) }
; DI int tile_groups(int MT, int NT) { return (MT >> 6) * ((NT + 7) >> 3) * 512; }
;     ...
;   GL_LOAD(0, 0)
;   GL_LOAD(1, 1)
;   LDS_STORE(0, 0)
;   if (VAR != 4) __syncthreads();
; #pragma unroll
;   for (int kt = 0; kt < nk; kt += 2) {
;     if (kt + 2 < nk) { GL_LOAD(0, kt + 2) }
;     MMA_TILE(0)
;     LDS_STORE(1, 1)
;     if (VAR != 4) __syncthreads();
;     if (kt + 3 < nk) { GL_LOAD(1, kt + 3) }
;     MMA_TILE(1)
; DI void phase_ple(const Params& P, int l, char* smem) {
;     ...
;   for (int vb = BIDX(); vb < tile_groups(128, 8); vb += gridDim.x) {
;     int tm, tn; if (!tile_of(vb, 128, 8, tm, tn)) continue;
;     const int m0 = tm * 128, n0 = tn * 128;
;     const int row0 = m0 + wm * 64, col0 = n0 + wn * 64;
;     uint4* park = (uint4*)(ws + OFF_VT) + ((size_t)BIDX() * 256 + tid) * 8;
;     {
;       f32x4 pp[4][4]; zero_acc(pp);
;       gemm_kloop<false, true, 4>(pp, pl + (size_t)m0 * PLE, PLE, W + WO_PP + (size_t)n0 * PLE, PLE, smem);
.LBB0_1435:
	s_ashr_i32 s1, s8, 3
	s_andn2_b32 s1, s1, 63
	s_and_b32 s2, s14, 56
	s_or_b32 s1, s1, s2
	s_bfe_u32 s2, s8, 0x30003
	s_or_b32 s1, s1, s2
	s_cmpk_gt_i32 s1, 0x7f
	s_cbranch_scc1 .LBB0_1434
	s_lshl_b32 s6, s1, 7
	v_readlane_b32 s1, v253, 0
	s_mov_b32 s16, s1
	s_ashr_i32 s17, s16, 31
	s_lshl_b64 s[16:17], s[16:17], 15
	s_ashr_i32 s7, s6, 31
	v_mov_b32_e32 v88, v148
	s_and_b32 s2, s13, 0x380
	v_lshl_add_u64 v[102:103], v[96:97], 0, s[16:17]
	s_lshl_b64 s[16:17], s[6:7], 9
	v_readlane_b32 s18, v254, 39
	v_readlane_b32 s19, v254, 40
	s_waitcnt vmcnt(5)
	v_ashrrev_i32_e32 v80, 3, v88
	s_add_u32 s16, s18, s16
	v_ashrrev_i32_e32 v81, 31, v80
	s_addc_u32 s17, s19, s17
	v_lshlrev_b32_e32 v0, 3, v88
	v_and_b32_e32 v91, 48, v88
	v_lshlrev_b64 v[16:17], 9, v[80:81]
	v_lshlrev_b32_e32 v81, 4, v88
	v_and_b32_e32 v90, 0x70, v0
	v_bitop3_b32 v170, v0, v91, s23 bitop3:0x6c
	s_waitcnt lgkmcnt(0)
	v_lshl_add_u64 v[0:1], s[16:17], 0, v[16:17]
	v_and_b32_e32 v150, 0x70, v81
	v_add_u32_e32 v82, 32, v80
	s_waitcnt vmcnt(4)
	v_add_u32_e32 v84, 64, v80
	v_add_u32_e32 v86, 0x60, v80
	s_lshl_b32 s1, s2, 9
	s_waitcnt vmcnt(1)
	v_lshl_add_u64 v[64:65], v[0:1], 0, v[150:151]
	v_ashrrev_i32_e32 v83, 31, v82
	v_ashrrev_i32_e32 v85, 31, v84
	v_ashrrev_i32_e32 v87, 31, v86
	s_add_u32 s18, s9, s1
	global_load_dwordx4 v[0:3], v[64:65], off
	v_lshlrev_b64 v[20:21], 9, v[82:83]
	v_lshlrev_b64 v[24:25], 9, v[84:85]
	v_lshlrev_b64 v[28:29], 9, v[86:87]
	s_addc_u32 s19, s10, 0
	v_lshl_add_u64 v[4:5], s[16:17], 0, v[20:21]
	v_lshl_add_u64 v[8:9], s[16:17], 0, v[24:25]
	v_lshl_add_u64 v[12:13], s[16:17], 0, v[28:29]
	v_lshl_add_u64 v[66:67], v[4:5], 0, v[150:151]
	s_waitcnt vmcnt(1)
	v_lshl_add_u64 v[68:69], v[8:9], 0, v[150:151]
	v_lshl_add_u64 v[70:71], v[12:13], 0, v[150:151]
	v_lshl_add_u64 v[16:17], s[18:19], 0, v[16:17]
	global_load_dwordx4 v[4:7], v[66:67], off
	global_load_dwordx4 v[8:11], v[68:69], off
	global_load_dwordx4 v[12:15], v[70:71], off
	v_lshl_add_u64 v[72:73], v[16:17], 0, v[150:151]
	v_lshl_add_u64 v[20:21], s[18:19], 0, v[20:21]
	global_load_dwordx4 v[16:19], v[72:73], off
	v_lshl_add_u64 v[74:75], v[20:21], 0, v[150:151]
	v_lshl_add_u64 v[24:25], s[18:19], 0, v[24:25]
	global_load_dwordx4 v[20:23], v[74:75], off
	v_lshl_add_u64 v[76:77], v[24:25], 0, v[150:151]
	global_load_dwordx4 v[24:27], v[76:77], off
	v_lshl_add_u64 v[28:29], s[18:19], 0, v[28:29]
	v_lshl_add_u64 v[78:79], v[28:29], 0, v[150:151]
	global_load_dwordx4 v[28:31], v[78:79], off
	global_load_dwordx4 v[32:35], v[64:65], off offset:128
	global_load_dwordx4 v[36:39], v[66:67], off offset:128
	global_load_dwordx4 v[40:43], v[68:69], off offset:128
	global_load_dwordx4 v[44:47], v[70:71], off offset:128
	global_load_dwordx4 v[48:51], v[72:73], off offset:128
	global_load_dwordx4 v[52:55], v[74:75], off offset:128
	global_load_dwordx4 v[56:59], v[76:77], off offset:128
	global_load_dwordx4 v[60:63], v[78:79], off offset:128
	v_bitop3_b32 v83, v81, s23, v88 bitop3:0x48
	v_lshl_or_b32 v80, v80, 7, v83
	v_and_b32_e32 v89, 15, v88
	v_lshl_or_b32 v81, v82, 7, v83
	v_lshl_or_b32 v82, v84, 7, v83
	v_lshl_or_b32 v83, v86, 7, v83
	v_xor_b32_e32 v171, 64, v170
	v_add_u32_e32 v123, s6, v122
	v_readlane_b32 s16, v254, 45
	v_readlane_b32 s17, v254, 46
	s_mov_b32 s18, 0x358637bd
	s_mov_b32 s1, 0x800000
	s_lshl_b64 s[6:7], s[6:7], 11
	s_waitcnt vmcnt(15)
	ds_write_b128 v80, v[0:3]
	v_lshrrev_b32_e32 v0, 1, v88
	v_and_or_b32 v0, v0, s24, v89
	v_lshlrev_b32_e32 v150, 7, v0
	v_lshlrev_b32_e32 v0, 7, v88
	v_and_b32_e32 v194, 0x2780, v0
	v_bitop3_b32 v84, v150, v90, v91 bitop3:0xf6
	v_or_b32_e32 v85, v194, v170
	s_waitcnt vmcnt(14)
	ds_write_b128 v81, v[4:7]
	s_waitcnt vmcnt(13)
	ds_write_b128 v82, v[8:11]
	s_waitcnt vmcnt(12)
	ds_write_b128 v83, v[12:15]
	s_waitcnt vmcnt(11)
	ds_write_b128 v80, v[16:19] offset:32768
	s_waitcnt vmcnt(10)
	ds_write_b128 v81, v[20:23] offset:32768
	s_waitcnt vmcnt(9)
	ds_write_b128 v82, v[24:27] offset:32768
	s_waitcnt vmcnt(8)
	ds_write_b128 v83, v[28:31] offset:32768
	s_waitcnt lgkmcnt(0)
	s_barrier
	s_setprio 1
	global_load_dwordx4 v[0:3], v[64:65], off offset:256
	global_load_dwordx4 v[4:7], v[66:67], off offset:256
	global_load_dwordx4 v[8:11], v[68:69], off offset:256
	global_load_dwordx4 v[12:15], v[70:71], off offset:256
	global_load_dwordx4 v[16:19], v[72:73], off offset:256
	global_load_dwordx4 v[20:23], v[74:75], off offset:256
	global_load_dwordx4 v[24:27], v[76:77], off offset:256
	global_load_dwordx4 v[28:31], v[78:79], off offset:256
	ds_read_b128 v[86:89], v84
	ds_read_b128 v[90:93], v85 offset:32768
	ds_read_b128 v[98:101], v84 offset:2048
	ds_read_b128 v[104:107], v85 offset:34816
	ds_read_b128 v[108:111], v84 offset:4096
	ds_read_b128 v[112:115], v85 offset:36864
	ds_read_b128 v[116:119], v84 offset:6144
	ds_read_b128 v[124:127], v85 offset:38912
	s_waitcnt lgkmcnt(6)
	v_mfma_f32_16x16x32_f16 v[128:131], v[90:93], v[86:89], 0
	s_waitcnt lgkmcnt(4)
	v_mfma_f32_16x16x32_f16 v[132:135], v[104:107], v[86:89], 0
	s_waitcnt lgkmcnt(2)
	v_mfma_f32_16x16x32_f16 v[136:139], v[112:115], v[86:89], 0
	s_waitcnt lgkmcnt(0)
	v_mfma_f32_16x16x32_f16 v[140:143], v[124:127], v[86:89], 0
	v_bitop3_b32 v86, v150, v170, 64 bitop3:0xf6
	v_or_b32_e32 v87, v194, v171
	v_mfma_f32_16x16x32_f16 v[144:147], v[90:93], v[98:101], 0
	v_mfma_f32_16x16x32_f16 v[154:157], v[104:107], v[98:101], 0
	v_mfma_f32_16x16x32_f16 v[158:161], v[112:115], v[98:101], 0
	v_mfma_f32_16x16x32_f16 v[98:101], v[124:127], v[98:101], 0
	v_mfma_f32_16x16x32_f16 v[162:165], v[90:93], v[108:111], 0
	v_mfma_f32_16x16x32_f16 v[166:169], v[104:107], v[108:111], 0
	v_mfma_f32_16x16x32_f16 v[190:193], v[112:115], v[108:111], 0
	v_mfma_f32_16x16x32_f16 v[108:111], v[124:127], v[108:111], 0
	v_mfma_f32_16x16x32_f16 v[88:91], v[90:93], v[116:119], 0
	v_mfma_f32_16x16x32_f16 v[92:95], v[104:107], v[116:119], 0
	v_mfma_f32_16x16x32_f16 v[104:107], v[112:115], v[116:119], 0
	v_mfma_f32_16x16x32_f16 v[112:115], v[124:127], v[116:119], 0
	ds_read_b128 v[116:119], v86
	ds_read_b128 v[124:127], v87 offset:32768
	ds_read_b128 v[194:197], v86 offset:2048
	ds_read_b128 v[198:201], v87 offset:34816
	ds_read_b128 v[202:205], v86 offset:4096
	ds_read_b128 v[206:209], v87 offset:36864
	ds_read_b128 v[210:213], v86 offset:6144
	ds_read_b128 v[220:223], v87 offset:38912
	s_waitcnt vmcnt(15)
	ds_write_b128 v80, v[32:35] offset:16384
	s_waitcnt vmcnt(14)
	ds_write_b128 v81, v[36:39] offset:16384
	s_waitcnt vmcnt(13)
	ds_write_b128 v82, v[40:43] offset:16384
	s_waitcnt vmcnt(12)
	ds_write_b128 v83, v[44:47] offset:16384
	s_waitcnt vmcnt(11)
	ds_write_b128 v80, v[48:51] offset:49152
	s_waitcnt vmcnt(10)
	ds_write_b128 v81, v[52:55] offset:49152
	s_waitcnt vmcnt(9)
	ds_write_b128 v82, v[56:59] offset:49152
	s_waitcnt vmcnt(8)
	ds_write_b128 v83, v[60:63] offset:49152
	s_waitcnt lgkmcnt(0)
	s_barrier
; #define GL_LOAD(s_, kt_) if (VAR != 1) { a##s_##0 = GL_A(0, kt_); a##s_##1 = GL_A(1, kt_); a##s_##2 = GL_A(2, kt_); a##s_##3 = GL_A(3, kt_); b##s_##0 = GL_B(0, kt_); b##s_##1 = GL_B(1, kt_); b##s_##2 = GL_B(2, kt_); b##s_##3 = GL_B(3, kt_); }
; #define LDS_STORE(s_, buf_) if (VAR != 2) { LDS_ST1(sA, 0, buf_, a##s_##0) LDS_ST1(sA, 1, buf_, a##s_##1) LDS_ST1(sA, 2, buf_, a##s_##2) LDS_ST1(sA, 3, buf_, a##s_##3) LDS_ST1(sB, 0, buf_, b##s_##0) LDS_ST1(sB, 1, buf_, b##s_##1) LDS_ST1(sB, 2, buf_, b##s_##2) LDS_ST1(sB, 3, buf_, b##s_##3) }
;     ...
;   for (int kt = 0; kt < nk; kt += 2) {
;     if (kt + 2 < nk) { GL_LOAD(0, kt + 2) }
;     MMA_TILE(0)
;     LDS_STORE(1, 1)
;     if (VAR != 4) __syncthreads();
;     if (kt + 3 < nk) { GL_LOAD(1, kt + 3) }
;     MMA_TILE(1)
;     if (kt + 2 < nk) { LDS_STORE(0, 0) }
;     if (VAR != 4) __syncthreads();
;   }
	v_mfma_f32_16x16x32_f16 v[128:131], v[124:127], v[116:119], v[128:131]
	global_load_dwordx4 v[32:35], v[64:65], off offset:384
	v_mfma_f32_16x16x32_f16 v[132:135], v[198:201], v[116:119], v[132:135]
	v_mfma_f32_16x16x32_f16 v[136:139], v[206:209], v[116:119], v[136:139]
	v_mfma_f32_16x16x32_f16 v[116:119], v[220:223], v[116:119], v[140:143]
	v_mfma_f32_16x16x32_f16 v[140:143], v[124:127], v[194:197], v[144:147]
	global_load_dwordx4 v[36:39], v[66:67], off offset:384
	ds_read_b128 v[64:67], v84 offset:16384
	global_load_dwordx4 v[40:43], v[68:69], off offset:384
	v_mfma_f32_16x16x32_f16 v[144:147], v[198:201], v[194:197], v[154:157]
	global_load_dwordx4 v[44:47], v[70:71], off offset:384
	v_mfma_f32_16x16x32_f16 v[154:157], v[206:209], v[194:197], v[158:161]
	v_mfma_f32_16x16x32_f16 v[158:161], v[124:127], v[202:205], v[162:165]
	ds_read_b128 v[68:71], v85 offset:49152
	global_load_dwordx4 v[48:51], v[72:73], off offset:384
	v_mfma_f32_16x16x32_f16 v[88:91], v[124:127], v[210:213], v[88:91]
	ds_read_b128 v[124:127], v84 offset:20480
	v_mfma_f32_16x16x32_f16 v[162:165], v[198:201], v[202:205], v[166:169]
	global_load_dwordx4 v[52:55], v[74:75], off offset:384
	v_mfma_f32_16x16x32_f16 v[92:95], v[198:201], v[210:213], v[92:95]
	ds_read_b128 v[72:75], v84 offset:18432
	ds_read_b128 v[198:201], v85 offset:55296
	global_load_dwordx4 v[56:59], v[76:77], off offset:384
	global_load_dwordx4 v[60:63], v[78:79], off offset:384
	v_mfma_f32_16x16x32_f16 v[98:101], v[220:223], v[194:197], v[98:101]
	ds_read_b128 v[76:79], v85 offset:51200
	v_mfma_f32_16x16x32_f16 v[166:169], v[206:209], v[202:205], v[190:193]
	s_nop 2
	ds_read_b128 v[190:193], v85 offset:53248
	v_mfma_f32_16x16x32_f16 v[104:107], v[206:209], v[210:213], v[104:107]
	ds_read_b128 v[194:197], v84 offset:22528
	v_mfma_f32_16x16x32_f16 v[108:111], v[220:223], v[202:205], v[108:111]
	s_waitcnt vmcnt(15)
	ds_write_b128 v80, v[0:3]
	v_mfma_f32_16x16x32_f16 v[112:115], v[220:223], v[210:213], v[112:115]
	s_waitcnt vmcnt(14)
	ds_write_b128 v81, v[4:7]
	s_waitcnt lgkmcnt(8)
	v_mfma_f32_16x16x32_f16 v[128:131], v[68:71], v[64:67], v[128:131]
	s_waitcnt vmcnt(13)
	ds_write_b128 v82, v[8:11]
	s_waitcnt lgkmcnt(5)
	v_mfma_f32_16x16x32_f16 v[132:135], v[76:79], v[64:67], v[132:135]
	s_waitcnt lgkmcnt(4)
	v_mfma_f32_16x16x32_f16 v[136:139], v[190:193], v[64:67], v[136:139]
	v_mfma_f32_16x16x32_f16 v[64:67], v[198:201], v[64:67], v[116:119]
	v_mfma_f32_16x16x32_f16 v[116:119], v[68:71], v[72:75], v[140:143]
	s_waitcnt vmcnt(12)
	ds_write_b128 v83, v[12:15]
	s_waitcnt vmcnt(11)
	ds_write_b128 v80, v[16:19] offset:32768
	v_mfma_f32_16x16x32_f16 v[140:143], v[76:79], v[72:75], v[144:147]
	s_waitcnt vmcnt(10)
	ds_write_b128 v81, v[20:23] offset:32768
	v_mfma_f32_16x16x32_f16 v[144:147], v[190:193], v[72:75], v[154:157]
	v_mfma_f32_16x16x32_f16 v[72:75], v[198:201], v[72:75], v[98:101]
	v_mfma_f32_16x16x32_f16 v[98:101], v[68:71], v[124:127], v[158:161]
	s_waitcnt vmcnt(9)
	ds_write_b128 v82, v[24:27] offset:32768
	s_waitcnt vmcnt(8)
	ds_write_b128 v83, v[28:31] offset:32768
	s_waitcnt lgkmcnt(8)
	v_mfma_f32_16x16x32_f16 v[68:71], v[68:71], v[194:197], v[88:91]
	v_mfma_f32_16x16x32_f16 v[154:157], v[76:79], v[124:127], v[162:165]
	s_nop 2
	ds_read_b128 v[162:165], v87 offset:51200
	v_mfma_f32_16x16x32_f16 v[76:79], v[76:79], v[194:197], v[92:95]
	v_mfma_f32_16x16x32_f16 v[158:161], v[190:193], v[124:127], v[166:169]
	s_nop 2
	ds_read_b128 v[166:169], v86 offset:20480
	v_mfma_f32_16x16x32_f16 v[88:91], v[190:193], v[194:197], v[104:107]
	s_nop 2
	ds_read_b128 v[104:107], v86 offset:16384
	ds_read_b128 v[190:193], v87 offset:53248
	v_mfma_f32_16x16x32_f16 v[108:111], v[198:201], v[124:127], v[108:111]
	ds_read_b128 v[124:127], v86 offset:18432
	v_mfma_f32_16x16x32_f16 v[92:95], v[198:201], v[194:197], v[112:115]
	s_nop 2
	ds_read_b128 v[112:115], v87 offset:49152
	ds_read_b128 v[194:197], v86 offset:22528
	ds_read_b128 v[198:201], v87 offset:55296
	s_waitcnt lgkmcnt(0)
	s_barrier
	ds_read_b128 v[0:3], v84
	ds_read_b128 v[4:7], v85 offset:32768
	ds_read_b128 v[8:11], v84 offset:2048
	ds_read_b128 v[12:15], v85 offset:34816
	ds_read_b128 v[16:19], v84 offset:4096
	ds_read_b128 v[20:23], v85 offset:36864
	ds_read_b128 v[24:27], v84 offset:6144
	ds_read_b128 v[28:31], v85 offset:38912
	v_mfma_f32_16x16x32_f16 v[128:131], v[112:115], v[104:107], v[128:131]
	v_mfma_f32_16x16x32_f16 v[132:135], v[162:165], v[104:107], v[132:135]
	v_mfma_f32_16x16x32_f16 v[136:139], v[190:193], v[104:107], v[136:139]
	v_mfma_f32_16x16x32_f16 v[64:67], v[198:201], v[104:107], v[64:67]
	v_mfma_f32_16x16x32_f16 v[104:107], v[112:115], v[124:127], v[116:119]
	v_mfma_f32_16x16x32_f16 v[116:119], v[162:165], v[124:127], v[140:143]
	v_mfma_f32_16x16x32_f16 v[140:143], v[190:193], v[124:127], v[144:147]
	v_mfma_f32_16x16x32_f16 v[72:75], v[198:201], v[124:127], v[72:75]
	v_mfma_f32_16x16x32_f16 v[98:101], v[112:115], v[166:169], v[98:101]
	v_mfma_f32_16x16x32_f16 v[124:127], v[162:165], v[166:169], v[154:157]
	v_mfma_f32_16x16x32_f16 v[144:147], v[190:193], v[166:169], v[158:161]
	v_mfma_f32_16x16x32_f16 v[108:111], v[198:201], v[166:169], v[108:111]
	v_mfma_f32_16x16x32_f16 v[68:71], v[112:115], v[194:197], v[68:71]
	v_mfma_f32_16x16x32_f16 v[76:79], v[162:165], v[194:197], v[76:79]
	v_mfma_f32_16x16x32_f16 v[88:91], v[190:193], v[194:197], v[88:91]
	v_mfma_f32_16x16x32_f16 v[92:95], v[198:201], v[194:197], v[92:95]
	s_waitcnt lgkmcnt(6)
	v_mfma_f32_16x16x32_f16 v[112:115], v[4:7], v[0:3], v[128:131]
	s_waitcnt lgkmcnt(4)
	v_mfma_f32_16x16x32_f16 v[128:131], v[12:15], v[0:3], v[132:135]
	s_waitcnt lgkmcnt(2)
; #define GL_LOAD(s_, kt_) if (VAR != 1) { a##s_##0 = GL_A(0, kt_); a##s_##1 = GL_A(1, kt_); a##s_##2 = GL_A(2, kt_); a##s_##3 = GL_A(3, kt_); b##s_##0 = GL_B(0, kt_); b##s_##1 = GL_B(1, kt_); b##s_##2 = GL_B(2, kt_); b##s_##3 = GL_B(3, kt_); }
; #define LDS_STORE(s_, buf_) if (VAR != 2) { LDS_ST1(sA, 0, buf_, a##s_##0) LDS_ST1(sA, 1, buf_, a##s_##1) LDS_ST1(sA, 2, buf_, a##s_##2) LDS_ST1(sA, 3, buf_, a##s_##3) LDS_ST1(sB, 0, buf_, b##s_##0) LDS_ST1(sB, 1, buf_, b##s_##1) LDS_ST1(sB, 2, buf_, b##s_##2) LDS_ST1(sB, 3, buf_, b##s_##3) }
;     ...
;   for (int kt = 0; kt < nk; kt += 2) {
;     if (kt + 2 < nk) { GL_LOAD(0, kt + 2) }
;     MMA_TILE(0)
;     LDS_STORE(1, 1)
;     if (VAR != 4) __syncthreads();
;     if (kt + 3 < nk) { GL_LOAD(1, kt + 3) }
;     MMA_TILE(1)
;     if (kt + 2 < nk) { LDS_STORE(0, 0) }
;     if (VAR != 4) __syncthreads();
;   }
	v_mfma_f32_16x16x32_f16 v[132:135], v[20:23], v[0:3], v[136:139]
	s_waitcnt lgkmcnt(0)
	v_mfma_f32_16x16x32_f16 v[0:3], v[28:31], v[0:3], v[64:67]
	v_mfma_f32_16x16x32_f16 v[64:67], v[4:7], v[8:11], v[104:107]
	v_mfma_f32_16x16x32_f16 v[104:107], v[12:15], v[8:11], v[116:119]
	v_mfma_f32_16x16x32_f16 v[116:119], v[20:23], v[8:11], v[140:143]
	v_mfma_f32_16x16x32_f16 v[8:11], v[28:31], v[8:11], v[72:75]
	v_mfma_f32_16x16x32_f16 v[72:75], v[4:7], v[16:19], v[98:101]
	v_mfma_f32_16x16x32_f16 v[98:101], v[12:15], v[16:19], v[124:127]
	v_mfma_f32_16x16x32_f16 v[124:127], v[20:23], v[16:19], v[144:147]
	v_mfma_f32_16x16x32_f16 v[16:19], v[28:31], v[16:19], v[108:111]
	v_mfma_f32_16x16x32_f16 v[4:7], v[4:7], v[24:27], v[68:71]
	v_mfma_f32_16x16x32_f16 v[12:15], v[12:15], v[24:27], v[76:79]
	v_mfma_f32_16x16x32_f16 v[20:23], v[20:23], v[24:27], v[88:91]
	v_mfma_f32_16x16x32_f16 v[24:27], v[28:31], v[24:27], v[92:95]
	ds_read_b128 v[28:31], v86
	ds_read_b128 v[68:71], v87 offset:32768
	ds_read_b128 v[76:79], v86 offset:2048
	ds_read_b128 v[88:91], v87 offset:34816
	ds_read_b128 v[92:95], v86 offset:4096
	ds_read_b128 v[108:111], v87 offset:36864
	ds_read_b128 v[136:139], v86 offset:6144
	ds_read_b128 v[140:143], v87 offset:38912
	s_waitcnt vmcnt(7)
	ds_write_b128 v80, v[32:35] offset:16384
	s_waitcnt vmcnt(6)
	ds_write_b128 v81, v[36:39] offset:16384
	s_waitcnt vmcnt(5)
	ds_write_b128 v82, v[40:43] offset:16384
	s_waitcnt vmcnt(4)
	ds_write_b128 v83, v[44:47] offset:16384
	s_waitcnt vmcnt(3)
	ds_write_b128 v80, v[48:51] offset:49152
	s_waitcnt vmcnt(2)
	ds_write_b128 v81, v[52:55] offset:49152
	s_waitcnt vmcnt(1)
	ds_write_b128 v82, v[56:59] offset:49152
	s_waitcnt vmcnt(0)
	ds_write_b128 v83, v[60:63] offset:49152
	s_waitcnt lgkmcnt(0)
	s_barrier
	ds_read_b128 v[32:35], v84 offset:16384
	ds_read_b128 v[36:39], v85 offset:49152
	ds_read_b128 v[40:43], v84 offset:18432
	ds_read_b128 v[44:47], v85 offset:51200
	ds_read_b128 v[48:51], v84 offset:20480
	ds_read_b128 v[52:55], v85 offset:53248
	ds_read_b128 v[56:59], v84 offset:22528
	ds_read_b128 v[60:63], v85 offset:55296
	v_mfma_f32_16x16x32_f16 v[112:115], v[68:71], v[28:31], v[112:115]
	v_mfma_f32_16x16x32_f16 v[128:131], v[88:91], v[28:31], v[128:131]
	v_mfma_f32_16x16x32_f16 v[132:135], v[108:111], v[28:31], v[132:135]
	v_mfma_f32_16x16x32_f16 v[0:3], v[140:143], v[28:31], v[0:3]
	v_mfma_f32_16x16x32_f16 v[28:31], v[68:71], v[76:79], v[64:67]
	v_mfma_f32_16x16x32_f16 v[64:67], v[88:91], v[76:79], v[104:107]
	v_mfma_f32_16x16x32_f16 v[104:107], v[108:111], v[76:79], v[116:119]
	v_mfma_f32_16x16x32_f16 v[8:11], v[140:143], v[76:79], v[8:11]
	v_mfma_f32_16x16x32_f16 v[72:75], v[68:71], v[92:95], v[72:75]
	v_mfma_f32_16x16x32_f16 v[76:79], v[88:91], v[92:95], v[98:101]
	v_mfma_f32_16x16x32_f16 v[98:101], v[108:111], v[92:95], v[124:127]
	v_mfma_f32_16x16x32_f16 v[16:19], v[140:143], v[92:95], v[16:19]
	v_mfma_f32_16x16x32_f16 v[4:7], v[68:71], v[136:139], v[4:7]
	v_mfma_f32_16x16x32_f16 v[12:15], v[88:91], v[136:139], v[12:15]
	v_mfma_f32_16x16x32_f16 v[20:23], v[108:111], v[136:139], v[20:23]
	v_mfma_f32_16x16x32_f16 v[24:27], v[140:143], v[136:139], v[24:27]
	s_waitcnt lgkmcnt(6)
	v_mfma_f32_16x16x32_f16 v[68:71], v[36:39], v[32:35], v[112:115]
	s_waitcnt lgkmcnt(4)
	v_mfma_f32_16x16x32_f16 v[80:83], v[44:47], v[32:35], v[128:131]
	s_waitcnt lgkmcnt(2)
	v_mfma_f32_16x16x32_f16 v[88:91], v[52:55], v[32:35], v[132:135]
	s_waitcnt lgkmcnt(0)
	v_mfma_f32_16x16x32_f16 v[0:3], v[60:63], v[32:35], v[0:3]
	v_mfma_f32_16x16x32_f16 v[28:31], v[36:39], v[40:43], v[28:31]
	v_mfma_f32_16x16x32_f16 v[32:35], v[44:47], v[40:43], v[64:67]
	v_mfma_f32_16x16x32_f16 v[64:67], v[52:55], v[40:43], v[104:107]
	v_mfma_f32_16x16x32_f16 v[8:11], v[60:63], v[40:43], v[8:11]
	v_mfma_f32_16x16x32_f16 v[40:43], v[36:39], v[48:51], v[72:75]
	v_mfma_f32_16x16x32_f16 v[72:75], v[44:47], v[48:51], v[76:79]
	v_mfma_f32_16x16x32_f16 v[76:79], v[52:55], v[48:51], v[98:101]
	v_mfma_f32_16x16x32_f16 v[16:19], v[60:63], v[48:51], v[16:19]
	v_mfma_f32_16x16x32_f16 v[4:7], v[36:39], v[56:59], v[4:7]
	v_mfma_f32_16x16x32_f16 v[12:15], v[44:47], v[56:59], v[12:15]
	v_mfma_f32_16x16x32_f16 v[20:23], v[52:55], v[56:59], v[20:23]
	v_mfma_f32_16x16x32_f16 v[24:27], v[60:63], v[56:59], v[24:27]
	ds_read_b128 v[36:39], v86 offset:16384
	ds_read_b128 v[44:47], v87 offset:49152
	ds_read_b128 v[48:51], v86 offset:18432
	ds_read_b128 v[52:55], v87 offset:51200
	ds_read_b128 v[56:59], v86 offset:20480
	ds_read_b128 v[60:63], v87 offset:53248
	ds_read_b128 v[92:95], v86 offset:22528
	ds_read_b128 v[84:87], v87 offset:55296
	s_waitcnt lgkmcnt(0)
	s_barrier
; DI unsigned pack2(float lo, float hi) { f2_t v = {lo, hi}; h2_t b = __builtin_convertvector(v, h2_t); return __builtin_bit_cast(unsigned, b); }
; DI void load_rstd(float (&rs)[4], const float* ssq, int row0, int lr) {
; #pragma unroll
;   for (int mt = 0; mt < 4; ++mt) {
;     const float4* q = (const float4*)(ssq + (size_t)(row0 + mt * 16 + lr) * 16);
;     const float4 a = q[0], b = q[1], c = q[2], d = q[3];
;     const float s = ((a.x + a.y) + (a.z + a.w)) + ((b.x + b.y) + (b.z + b.w)) + ((c.x + c.y) + (c.z + c.w)) + ((d.x + d.y) + (d.z + d.w));
;     rs[mt] = rsqrtf(s * (1.0f / 1024.0f) + EPS);
;   }
; DI void phase_ple(const Params& P, int l, char* smem) {
;     ...
;       gemm_kloop<false, true, 4>(pp, pl + (size_t)m0 * PLE, PLE, W + WO_PP + (size_t)n0 * PLE, PLE, smem);
; #pragma unroll
;       for (int mt = 0; mt < 4; ++mt)
; #pragma unroll
;         for (int h = 0; h < 2; ++h)
;           park[mt * 2 + h] = make_uint4(pack2(pp[mt][2 * h][0], pp[mt][2 * h][1]), pack2(pp[mt][2 * h][2], pp[mt][2 * h][3]), pack2(pp[mt][2 * h + 1][0], pp[mt][2 * h + 1][1]), pack2(pp[mt][2 * h + 1][2], pp[mt][2 * h + 1][3]));
;     }
;     f32x4 acc[4][4]; zero_acc(acc);
;     float rs[4]; load_rstd(rs, ssq, row0, lr);
;     gemm_kloop<false, true, 16>(acc, xb + (size_t)m0 * DM, DM, W + WO_GATE + (size_t)n0 * DM, DM, smem);
	v_mfma_f32_16x16x32_f16 v[68:71], v[44:47], v[36:39], v[68:71]
	v_mfma_f32_16x16x32_f16 v[80:83], v[52:55], v[36:39], v[80:83]
	v_mfma_f32_16x16x32_f16 v[0:3], v[84:87], v[36:39], v[0:3]
	v_mfma_f32_16x16x32_f16 v[28:31], v[44:47], v[48:51], v[28:31]
	v_mfma_f32_16x16x32_f16 v[32:35], v[52:55], v[48:51], v[32:35]
	v_mfma_f32_16x16x32_f16 v[88:91], v[60:63], v[36:39], v[88:91]
	v_mfma_f32_16x16x32_f16 v[36:39], v[60:63], v[48:51], v[64:67]
	v_mfma_f32_16x16x32_f16 v[8:11], v[84:87], v[48:51], v[8:11]
	v_mfma_f32_16x16x32_f16 v[40:43], v[44:47], v[56:59], v[40:43]
	v_mfma_f32_16x16x32_f16 v[48:51], v[52:55], v[56:59], v[72:75]
	v_mfma_f32_16x16x32_f16 v[64:67], v[60:63], v[56:59], v[76:79]
	s_nop 1
	v_mov_b32_e32 v72, v148
	v_mfma_f32_16x16x32_f16 v[16:19], v[84:87], v[56:59], v[16:19]
	v_mfma_f32_16x16x32_f16 v[4:7], v[44:47], v[92:95], v[4:7]
	v_cvt_pk_f16_f32 v44, v68, v69
	v_cvt_pk_f16_f32 v45, v70, v71
	v_cvt_pk_f16_f32 v46, v80, v81
	v_cvt_pk_f16_f32 v47, v82, v83
	v_mfma_f32_16x16x32_f16 v[12:15], v[52:55], v[92:95], v[12:15]
	global_store_dwordx4 v[102:103], v[44:47], off
	s_nop 1
	v_cvt_pk_f16_f32 v46, v0, v1
	v_cvt_pk_f16_f32 v47, v2, v3
	v_cvt_pk_f16_f32 v0, v28, v29
	v_cvt_pk_f16_f32 v1, v30, v31
	v_cvt_pk_f16_f32 v2, v32, v33
	v_cvt_pk_f16_f32 v3, v34, v35
	v_mfma_f32_16x16x32_f16 v[20:23], v[60:63], v[92:95], v[20:23]
	global_store_dwordx4 v[102:103], v[0:3], off offset:32
	v_cvt_pk_f16_f32 v44, v88, v89
	v_cvt_pk_f16_f32 v45, v90, v91
	v_mfma_f32_16x16x32_f16 v[24:27], v[84:87], v[92:95], v[24:27]
	v_cvt_pk_f16_f32 v0, v36, v37
	v_cvt_pk_f16_f32 v1, v38, v39
	v_cvt_pk_f16_f32 v2, v8, v9
	v_cvt_pk_f16_f32 v3, v10, v11
	global_store_dwordx4 v[102:103], v[0:3], off offset:48
	global_store_dwordx4 v[102:103], v[44:47], off offset:16
	s_nop 0
	v_cvt_pk_f16_f32 v0, v40, v41
	v_cvt_pk_f16_f32 v1, v42, v43
	v_cvt_pk_f16_f32 v2, v48, v49
	v_cvt_pk_f16_f32 v3, v50, v51
	global_store_dwordx4 v[102:103], v[0:3], off offset:64
	s_nop 1
	v_cvt_pk_f16_f32 v0, v64, v65
	v_cvt_pk_f16_f32 v1, v66, v67
	v_cvt_pk_f16_f32 v2, v16, v17
	v_cvt_pk_f16_f32 v3, v18, v19
	global_store_dwordx4 v[102:103], v[0:3], off offset:80
	s_nop 1
	v_cvt_pk_f16_f32 v0, v4, v5
	v_cvt_pk_f16_f32 v1, v6, v7
	v_cvt_pk_f16_f32 v2, v12, v13
	v_cvt_pk_f16_f32 v3, v14, v15
	global_store_dwordx4 v[102:103], v[0:3], off offset:96
	s_nop 1
	v_cvt_pk_f16_f32 v0, v20, v21
	v_cvt_pk_f16_f32 v1, v22, v23
	v_cvt_pk_f16_f32 v2, v24, v25
	v_cvt_pk_f16_f32 v3, v26, v27
	global_store_dwordx4 v[102:103], v[0:3], off offset:112
	s_nop 1
	v_or_b32_e32 v0, v123, v121
	v_ashrrev_i32_e32 v1, 31, v0
	v_lshlrev_b64 v[2:3], 6, v[0:1]
	v_lshl_add_u64 v[14:15], s[16:17], 0, v[2:3]
	global_load_dwordx4 v[2:5], v[14:15], off offset:32
	global_load_dwordx4 v[6:9], v[14:15], off offset:16
	global_load_dwordx4 v[10:13], v[14:15], off
	s_nop 0
	global_load_dwordx4 v[14:17], v[14:15], off offset:48
	s_waitcnt vmcnt(2)
	v_mov_b32_e32 v20, v7
	s_waitcnt vmcnt(1)
	v_mov_b32_e32 v18, v11
	v_mov_b32_e32 v19, v12
	v_mov_b32_e32 v21, v8
	v_mov_b32_e32 v11, v13
	v_mov_b32_e32 v7, v9
	v_mov_b32_e32 v8, v3
	v_pk_add_f32 v[10:11], v[18:19], v[10:11]
	v_pk_add_f32 v[6:7], v[20:21], v[6:7]
	v_pk_add_f32 v[2:3], v[2:3], v[8:9]
	v_mov_b32_e32 v8, v5
	v_pk_add_f32 v[10:11], v[10:11], v[10:11] op_sel:[0,1] op_sel_hi:[1,0]
	v_pk_add_f32 v[6:7], v[6:7], v[6:7] op_sel:[0,1] op_sel_hi:[1,0]
	v_pk_add_f32 v[4:5], v[4:5], v[8:9]
	s_waitcnt vmcnt(0)
	v_mov_b32_e32 v11, v14
	v_mov_b32_e32 v7, v15
	v_mov_b32_e32 v3, v16
	v_mov_b32_e32 v5, v17
	v_pk_add_f32 v[6:7], v[10:11], v[6:7]
	v_pk_add_f32 v[2:3], v[2:3], v[4:5]
	s_nop 0
	v_pk_add_f32 v[18:19], v[6:7], v[2:3]
	v_or_b32_e32 v2, 16, v0
	v_ashrrev_i32_e32 v3, 31, v2
	v_lshlrev_b64 v[2:3], 6, v[2:3]
	v_lshl_add_u64 v[14:15], s[16:17], 0, v[2:3]
	global_load_dwordx4 v[2:5], v[14:15], off offset:32
	global_load_dwordx4 v[6:9], v[14:15], off offset:16
	global_load_dwordx4 v[10:13], v[14:15], off
	s_nop 0
	global_load_dwordx4 v[14:17], v[14:15], off offset:48
	s_waitcnt vmcnt(2)
	v_mov_b32_e32 v22, v7
	s_waitcnt vmcnt(1)
	v_mov_b32_e32 v20, v11
	v_mov_b32_e32 v21, v12
	v_mov_b32_e32 v23, v8
	v_mov_b32_e32 v11, v13
	v_mov_b32_e32 v7, v9
	v_mov_b32_e32 v8, v3
	v_pk_add_f32 v[10:11], v[20:21], v[10:11]
	v_pk_add_f32 v[6:7], v[22:23], v[6:7]
	v_pk_add_f32 v[2:3], v[2:3], v[8:9]
	v_mov_b32_e32 v8, v5
	v_pk_add_f32 v[10:11], v[10:11], v[10:11] op_sel:[0,1] op_sel_hi:[1,0]
	v_pk_add_f32 v[6:7], v[6:7], v[6:7] op_sel:[0,1] op_sel_hi:[1,0]
	v_pk_add_f32 v[4:5], v[4:5], v[8:9]
	s_waitcnt vmcnt(0)
	v_mov_b32_e32 v11, v14
	v_mov_b32_e32 v7, v15
	v_mov_b32_e32 v3, v16
	v_mov_b32_e32 v5, v17
	v_pk_add_f32 v[6:7], v[10:11], v[6:7]
	v_pk_add_f32 v[2:3], v[2:3], v[4:5]
	v_mov_b32_e32 v5, v18
	v_pk_add_f32 v[2:3], v[6:7], v[2:3]
	s_nop 0
	v_mov_b32_e32 v4, v2
	v_mov_b32_e32 v18, v3
	v_pk_add_f32 v[4:5], v[4:5], v[18:19]
	v_mov_b64_e32 v[2:3], s[18:19]
	s_mov_b32 s18, 0x3a800000
	v_pk_fma_f32 v[100:101], v[4:5], s[18:19], v[2:3] op_sel_hi:[1,0,0]
	s_nop 0
	v_mul_f32_e32 v1, 0x4b800000, v101
	v_cmp_gt_f32_e32 vcc, s1, v101
	v_cmp_gt_f32_e64 s[44:45], s1, v100
	s_nop 0
	v_cndmask_b32_e32 v1, v101, v1, vcc
	v_rsq_f32_e32 v1, v1
	s_nop 0
	v_mul_f32_e32 v4, 0x45800000, v1
	v_cndmask_b32_e32 v101, v1, v4, vcc
	v_or_b32_e32 v4, 32, v0
	v_ashrrev_i32_e32 v5, 31, v4
	v_lshlrev_b64 v[4:5], 6, v[4:5]
	v_lshl_add_u64 v[16:17], s[16:17], 0, v[4:5]
	global_load_dwordx4 v[4:7], v[16:17], off offset:32
	global_load_dwordx4 v[8:11], v[16:17], off offset:16
	global_load_dwordx4 v[12:15], v[16:17], off
	s_nop 0
	global_load_dwordx4 v[16:19], v[16:17], off offset:48
	v_or_b32_e32 v0, 48, v0
	v_ashrrev_i32_e32 v1, 31, v0
	v_lshlrev_b64 v[0:1], 6, v[0:1]
	v_lshl_add_u64 v[0:1], s[16:17], 0, v[0:1]
	v_readlane_b32 s16, v254, 43
	v_readlane_b32 s17, v254, 44
	s_add_u32 s6, s16, s6
	s_addc_u32 s7, s17, s7
	s_waitcnt vmcnt(2)
; #define GL_LOAD(s_, kt_) if (VAR != 1) { a##s_##0 = GL_A(0, kt_); a##s_##1 = GL_A(1, kt_); a##s_##2 = GL_A(2, kt_); a##s_##3 = GL_A(3, kt_); b##s_##0 = GL_B(0, kt_); b##s_##1 = GL_B(1, kt_); b##s_##2 = GL_B(2, kt_); b##s_##3 = GL_B(3, kt_); }
; #define LDS_STORE(s_, buf_) if (VAR != 2) { LDS_ST1(sA, 0, buf_, a##s_##0) LDS_ST1(sA, 1, buf_, a##s_##1) LDS_ST1(sA, 2, buf_, a##s_##2) LDS_ST1(sA, 3, buf_, a##s_##3) LDS_ST1(sB, 0, buf_, b##s_##0) LDS_ST1(sB, 1, buf_, b##s_##1) LDS_ST1(sB, 2, buf_, b##s_##2) LDS_ST1(sB, 3, buf_, b##s_##3) }
;     ...
;   GL_LOAD(0, 0)
;   GL_LOAD(1, 1)
;   LDS_STORE(0, 0)
;   if (VAR != 4) __syncthreads();
; DI void load_rstd(float (&rs)[4], const float* ssq, int row0, int lr) {
; #pragma unroll
;   for (int mt = 0; mt < 4; ++mt) {
;     const float4* q = (const float4*)(ssq + (size_t)(row0 + mt * 16 + lr) * 16);
;     const float4 a = q[0], b = q[1], c = q[2], d = q[3];
;     const float s = ((a.x + a.y) + (a.z + a.w)) + ((b.x + b.y) + (b.z + b.w)) + ((c.x + c.y) + (c.z + c.w)) + ((d.x + d.y) + (d.z + d.w));
;     rs[mt] = rsqrtf(s * (1.0f / 1024.0f) + EPS);
;   }
	v_mov_b32_e32 v22, v9
	s_waitcnt vmcnt(1)
	v_mov_b32_e32 v20, v13
	v_mov_b32_e32 v21, v14
	v_mov_b32_e32 v23, v10
	v_mov_b32_e32 v13, v15
	v_mov_b32_e32 v9, v11
	v_mov_b32_e32 v10, v5
	v_pk_add_f32 v[12:13], v[20:21], v[12:13]
	v_pk_add_f32 v[8:9], v[22:23], v[8:9]
	v_pk_add_f32 v[4:5], v[4:5], v[10:11]
	v_mov_b32_e32 v10, v7
	v_pk_add_f32 v[12:13], v[12:13], v[12:13] op_sel:[0,1] op_sel_hi:[1,0]
	v_pk_add_f32 v[8:9], v[8:9], v[8:9] op_sel:[0,1] op_sel_hi:[1,0]
	v_pk_add_f32 v[6:7], v[6:7], v[10:11]
	s_waitcnt vmcnt(0)
	v_mov_b32_e32 v13, v16
	v_mov_b32_e32 v9, v17
	v_mov_b32_e32 v5, v18
	v_mov_b32_e32 v7, v19
	v_pk_add_f32 v[8:9], v[12:13], v[8:9]
	v_pk_add_f32 v[4:5], v[4:5], v[6:7]
	s_nop 0
	v_pk_add_f32 v[20:21], v[8:9], v[4:5]
	global_load_dwordx4 v[4:7], v[0:1], off offset:32
	global_load_dwordx4 v[8:11], v[0:1], off offset:16
	global_load_dwordx4 v[12:15], v[0:1], off
	global_load_dwordx4 v[16:19], v[0:1], off offset:48
	s_waitcnt vmcnt(2)
	v_mov_b32_e32 v22, v9
	s_waitcnt vmcnt(1)
	v_mov_b32_e32 v0, v13
	v_mov_b32_e32 v1, v14
	v_mov_b32_e32 v23, v10
	v_mov_b32_e32 v13, v15
	v_mov_b32_e32 v9, v11
	v_mov_b32_e32 v10, v5
	v_pk_add_f32 v[0:1], v[0:1], v[12:13]
	v_pk_add_f32 v[8:9], v[22:23], v[8:9]
	v_pk_add_f32 v[4:5], v[4:5], v[10:11]
	v_mov_b32_e32 v10, v7
	v_pk_add_f32 v[0:1], v[0:1], v[0:1] op_sel:[0,1] op_sel_hi:[1,0]
	v_pk_add_f32 v[8:9], v[8:9], v[8:9] op_sel:[0,1] op_sel_hi:[1,0]
	v_pk_add_f32 v[6:7], v[6:7], v[10:11]
	s_waitcnt vmcnt(0)
	v_mov_b32_e32 v1, v16
	v_mov_b32_e32 v9, v17
	v_mov_b32_e32 v5, v18
	v_mov_b32_e32 v7, v19
	v_pk_add_f32 v[0:1], v[0:1], v[8:9]
	v_pk_add_f32 v[4:5], v[4:5], v[6:7]
	v_ashrrev_i32_e32 v64, 3, v72
	v_pk_add_f32 v[0:1], v[0:1], v[4:5]
	v_mov_b32_e32 v5, v20
	v_mov_b32_e32 v4, v0
	v_mov_b32_e32 v20, v1
	v_pk_add_f32 v[0:1], v[4:5], v[20:21]
	v_ashrrev_i32_e32 v65, 31, v64
	v_pk_fma_f32 v[98:99], v[0:1], s[18:19], v[2:3] op_sel_hi:[1,0,0]
	v_lshlrev_b32_e32 v0, 3, v72
	v_and_b32_e32 v75, 48, v72
	v_lshlrev_b64 v[16:17], 11, v[64:65]
	v_lshlrev_b32_e32 v65, 4, v72
	v_and_b32_e32 v74, 0x70, v0
	v_bitop3_b32 v129, v0, v75, s23 bitop3:0x6c
	v_lshl_add_u64 v[0:1], s[6:7], 0, v[16:17]
	v_and_b32_e32 v150, 0x70, v65
	v_add_u32_e32 v66, 32, v64
	v_add_u32_e32 v68, 64, v64
	v_add_u32_e32 v70, 0x60, v64
	v_cmp_gt_f32_e64 s[38:39], s1, v98
	v_cmp_gt_f32_e64 s[40:41], s1, v99
	s_lshl_b32 s1, s2, 11
	v_lshl_add_u64 v[104:105], v[0:1], 0, v[150:151]
	v_ashrrev_i32_e32 v67, 31, v66
	v_ashrrev_i32_e32 v69, 31, v68
	v_ashrrev_i32_e32 v71, 31, v70
	s_add_u32 s16, s11, s1
	global_load_dwordx4 v[0:3], v[104:105], off
	v_lshlrev_b64 v[20:21], 11, v[66:67]
	v_lshlrev_b64 v[24:25], 11, v[68:69]
	v_lshlrev_b64 v[28:29], 11, v[70:71]
	s_addc_u32 s17, s12, 0
	v_lshl_add_u64 v[4:5], s[6:7], 0, v[20:21]
	v_lshl_add_u64 v[8:9], s[6:7], 0, v[24:25]
	v_lshl_add_u64 v[12:13], s[6:7], 0, v[28:29]
	v_lshl_add_u64 v[106:107], v[4:5], 0, v[150:151]
	v_lshl_add_u64 v[108:109], v[8:9], 0, v[150:151]
	v_lshl_add_u64 v[110:111], v[12:13], 0, v[150:151]
	v_lshl_add_u64 v[16:17], s[16:17], 0, v[16:17]
	global_load_dwordx4 v[4:7], v[106:107], off
	global_load_dwordx4 v[8:11], v[108:109], off
	global_load_dwordx4 v[12:15], v[110:111], off
	v_lshl_add_u64 v[112:113], v[16:17], 0, v[150:151]
	v_lshl_add_u64 v[20:21], s[16:17], 0, v[20:21]
	global_load_dwordx4 v[16:19], v[112:113], off
	v_lshl_add_u64 v[114:115], v[20:21], 0, v[150:151]
	v_lshl_add_u64 v[24:25], s[16:17], 0, v[24:25]
	global_load_dwordx4 v[20:23], v[114:115], off
	v_lshl_add_u64 v[116:117], v[24:25], 0, v[150:151]
	global_load_dwordx4 v[24:27], v[116:117], off
	v_lshl_add_u64 v[28:29], s[16:17], 0, v[28:29]
	v_lshl_add_u64 v[118:119], v[28:29], 0, v[150:151]
	global_load_dwordx4 v[28:31], v[118:119], off
	global_load_dwordx4 v[32:35], v[104:105], off offset:128
	global_load_dwordx4 v[36:39], v[106:107], off offset:128
	global_load_dwordx4 v[40:43], v[108:109], off offset:128
	global_load_dwordx4 v[44:47], v[110:111], off offset:128
	global_load_dwordx4 v[48:51], v[112:113], off offset:128
	global_load_dwordx4 v[52:55], v[114:115], off offset:128
	global_load_dwordx4 v[56:59], v[116:117], off offset:128
	global_load_dwordx4 v[60:63], v[118:119], off offset:128
	v_bitop3_b32 v65, v65, s23, v72 bitop3:0x48
	v_lshl_or_b32 v126, v64, 7, v65
	v_and_b32_e32 v73, 15, v72
	v_lshl_or_b32 v124, v66, 7, v65
	v_lshl_or_b32 v125, v68, 7, v65
	v_lshl_or_b32 v127, v70, 7, v65
	v_xor_b32_e32 v130, 64, v129
	v_readlane_b32 s16, v254, 55
	v_readlane_b32 s6, v253, 11
	v_readlane_b32 s17, v254, 56
	v_readlane_b32 s7, v253, 12
	v_readlane_b32 s18, v254, 57
	v_readlane_b32 s19, v254, 58
	s_waitcnt vmcnt(15)
	ds_write_b128 v126, v[0:3]
	v_lshrrev_b32_e32 v0, 1, v72
	v_and_or_b32 v0, v0, s24, v73
	v_lshlrev_b32_e32 v150, 7, v0
	v_lshlrev_b32_e32 v0, 7, v72
	v_and_b32_e32 v170, 0x2780, v0
	v_bitop3_b32 v128, v150, v74, v75 bitop3:0xf6
	v_or_b32_e32 v131, v170, v129
	v_bitop3_b32 v129, v150, v129, 64 bitop3:0xf6
	v_or_b32_e32 v130, v170, v130
	s_waitcnt vmcnt(14)
	ds_write_b128 v124, v[4:7]
	s_waitcnt vmcnt(13)
	ds_write_b128 v125, v[8:11]
	s_waitcnt vmcnt(12)
	ds_write_b128 v127, v[12:15]
	s_waitcnt vmcnt(11)
	ds_write_b128 v126, v[16:19] offset:32768
	s_waitcnt vmcnt(10)
	ds_write_b128 v124, v[20:23] offset:32768
	s_waitcnt vmcnt(9)
	ds_write_b128 v125, v[24:27] offset:32768
	s_waitcnt vmcnt(8)
	ds_write_b128 v127, v[28:31] offset:32768
	s_waitcnt lgkmcnt(0)
	s_barrier
; #define GL_LOAD(s_, kt_) if (VAR != 1) { a##s_##0 = GL_A(0, kt_); a##s_##1 = GL_A(1, kt_); a##s_##2 = GL_A(2, kt_); a##s_##3 = GL_A(3, kt_); b##s_##0 = GL_B(0, kt_); b##s_##1 = GL_B(1, kt_); b##s_##2 = GL_B(2, kt_); b##s_##3 = GL_B(3, kt_); }
; #define LDS_STORE(s_, buf_) if (VAR != 2) { LDS_ST1(sA, 0, buf_, a##s_##0) LDS_ST1(sA, 1, buf_, a##s_##1) LDS_ST1(sA, 2, buf_, a##s_##2) LDS_ST1(sA, 3, buf_, a##s_##3) LDS_ST1(sB, 0, buf_, b##s_##0) LDS_ST1(sB, 1, buf_, b##s_##1) LDS_ST1(sB, 2, buf_, b##s_##2) LDS_ST1(sB, 3, buf_, b##s_##3) }
;     ...
;   GL_LOAD(0, 0)
;   GL_LOAD(1, 1)
;   LDS_STORE(0, 0)
;   if (VAR != 4) __syncthreads();
; #pragma unroll
;   for (int kt = 0; kt < nk; kt += 2) {
;     if (kt + 2 < nk) { GL_LOAD(0, kt + 2) }
;     MMA_TILE(0)
;     LDS_STORE(1, 1)
;     if (VAR != 4) __syncthreads();
;     if (kt + 3 < nk) { GL_LOAD(1, kt + 3) }
;     MMA_TILE(1)
;     if (kt + 2 < nk) { LDS_STORE(0, 0) }
;     if (VAR != 4) __syncthreads();
	global_load_dwordx4 v[0:3], v[104:105], off offset:256
	global_load_dwordx4 v[4:7], v[106:107], off offset:256
	global_load_dwordx4 v[8:11], v[108:109], off offset:256
	global_load_dwordx4 v[12:15], v[110:111], off offset:256
	global_load_dwordx4 v[16:19], v[112:113], off offset:256
	global_load_dwordx4 v[20:23], v[114:115], off offset:256
	global_load_dwordx4 v[24:27], v[116:117], off offset:256
	global_load_dwordx4 v[28:31], v[118:119], off offset:256
	ds_read_b128 v[64:67], v128
	ds_read_b128 v[68:71], v131 offset:32768
	ds_read_b128 v[72:75], v128 offset:2048
	ds_read_b128 v[76:79], v131 offset:34816
	ds_read_b128 v[80:83], v128 offset:4096
	ds_read_b128 v[84:87], v131 offset:36864
	ds_read_b128 v[88:91], v128 offset:6144
	ds_read_b128 v[92:95], v131 offset:38912
	s_waitcnt lgkmcnt(6)
	v_mfma_f32_16x16x32_f16 v[132:135], v[68:71], v[64:67], 0
	s_waitcnt lgkmcnt(4)
	v_mfma_f32_16x16x32_f16 v[136:139], v[76:79], v[64:67], 0
	s_waitcnt lgkmcnt(2)
	v_mfma_f32_16x16x32_f16 v[140:143], v[84:87], v[64:67], 0
	s_waitcnt lgkmcnt(0)
	v_mfma_f32_16x16x32_f16 v[64:67], v[92:95], v[64:67], 0
	v_mfma_f32_16x16x32_f16 v[144:147], v[68:71], v[72:75], 0
	v_mfma_f32_16x16x32_f16 v[154:157], v[76:79], v[72:75], 0
	v_mfma_f32_16x16x32_f16 v[158:161], v[84:87], v[72:75], 0
	v_mfma_f32_16x16x32_f16 v[72:75], v[92:95], v[72:75], 0
	v_mfma_f32_16x16x32_f16 v[162:165], v[68:71], v[80:83], 0
	v_mfma_f32_16x16x32_f16 v[166:169], v[76:79], v[80:83], 0
	v_mfma_f32_16x16x32_f16 v[190:193], v[84:87], v[80:83], 0
	v_mfma_f32_16x16x32_f16 v[80:83], v[92:95], v[80:83], 0
	v_mfma_f32_16x16x32_f16 v[68:71], v[68:71], v[88:91], 0
	v_mfma_f32_16x16x32_f16 v[76:79], v[76:79], v[88:91], 0
	v_mfma_f32_16x16x32_f16 v[84:87], v[84:87], v[88:91], 0
	v_mfma_f32_16x16x32_f16 v[88:91], v[92:95], v[88:91], 0
	ds_read_b128 v[92:95], v129
	ds_read_b128 v[194:197], v130 offset:32768
	ds_read_b128 v[198:201], v129 offset:2048
	ds_read_b128 v[202:205], v130 offset:34816
	ds_read_b128 v[206:209], v129 offset:4096
	ds_read_b128 v[210:213], v130 offset:36864
	ds_read_b128 v[220:223], v129 offset:6144
	ds_read_b128 v[224:227], v130 offset:38912
	s_waitcnt vmcnt(15)
	ds_write_b128 v126, v[32:35] offset:16384
	s_waitcnt vmcnt(14)
	ds_write_b128 v124, v[36:39] offset:16384
	s_waitcnt vmcnt(13)
	ds_write_b128 v125, v[40:43] offset:16384
	s_waitcnt vmcnt(12)
	ds_write_b128 v127, v[44:47] offset:16384
	s_waitcnt vmcnt(11)
	ds_write_b128 v126, v[48:51] offset:49152
	s_waitcnt vmcnt(10)
	ds_write_b128 v124, v[52:55] offset:49152
	s_waitcnt vmcnt(9)
	ds_write_b128 v125, v[56:59] offset:49152
	s_waitcnt vmcnt(8)
	ds_write_b128 v127, v[60:63] offset:49152
	s_waitcnt lgkmcnt(0)
	s_barrier
	v_mfma_f32_16x16x32_f16 v[132:135], v[194:197], v[92:95], v[132:135]
	global_load_dwordx4 v[32:35], v[104:105], off offset:384
	v_mfma_f32_16x16x32_f16 v[136:139], v[202:205], v[92:95], v[136:139]
	v_mfma_f32_16x16x32_f16 v[140:143], v[210:213], v[92:95], v[140:143]
	v_mfma_f32_16x16x32_f16 v[64:67], v[224:227], v[92:95], v[64:67]
	v_mfma_f32_16x16x32_f16 v[92:95], v[194:197], v[198:201], v[144:147]
	global_load_dwordx4 v[36:39], v[106:107], off offset:384
	global_load_dwordx4 v[40:43], v[108:109], off offset:384
	global_load_dwordx4 v[44:47], v[110:111], off offset:384
	v_mfma_f32_16x16x32_f16 v[144:147], v[202:205], v[198:201], v[154:157]
	global_load_dwordx4 v[48:51], v[112:113], off offset:384
	v_mfma_f32_16x16x32_f16 v[154:157], v[210:213], v[198:201], v[158:161]
	v_mfma_f32_16x16x32_f16 v[158:161], v[194:197], v[206:209], v[162:165]
	global_load_dwordx4 v[52:55], v[114:115], off offset:384
	global_load_dwordx4 v[56:59], v[116:117], off offset:384
	v_mfma_f32_16x16x32_f16 v[68:71], v[194:197], v[220:223], v[68:71]
	ds_read_b128 v[194:197], v131 offset:49152
	v_mfma_f32_16x16x32_f16 v[162:165], v[202:205], v[206:209], v[166:169]
	global_load_dwordx4 v[60:63], v[118:119], off offset:384
	v_mfma_f32_16x16x32_f16 v[76:79], v[202:205], v[220:223], v[76:79]
	ds_read_b128 v[202:205], v131 offset:51200
	s_waitcnt vmcnt(15)
	ds_write_b128 v126, v[0:3]
	s_waitcnt vmcnt(14)
	ds_write_b128 v124, v[4:7]
	s_waitcnt vmcnt(13)
	ds_write_b128 v125, v[8:11]
	v_mfma_f32_16x16x32_f16 v[72:75], v[224:227], v[198:201], v[72:75]
	ds_read_b128 v[198:201], v128 offset:18432
	v_mfma_f32_16x16x32_f16 v[166:169], v[210:213], v[206:209], v[190:193]
	s_nop 2
	ds_read_b128 v[190:193], v128 offset:16384
	v_mfma_f32_16x16x32_f16 v[84:87], v[210:213], v[220:223], v[84:87]
	ds_read_b128 v[210:213], v131 offset:53248
	v_mfma_f32_16x16x32_f16 v[80:83], v[224:227], v[206:209], v[80:83]
	ds_read_b128 v[206:209], v128 offset:20480
	v_mfma_f32_16x16x32_f16 v[88:91], v[224:227], v[220:223], v[88:91]
	ds_read_b128 v[220:223], v128 offset:22528
	s_waitcnt lgkmcnt(3)
	v_mfma_f32_16x16x32_f16 v[132:135], v[194:197], v[190:193], v[132:135]
	ds_read_b128 v[224:227], v131 offset:55296
	v_mfma_f32_16x16x32_f16 v[92:95], v[194:197], v[198:201], v[92:95]
	s_waitcnt vmcnt(12)
	ds_write_b128 v127, v[12:15]
	v_mfma_f32_16x16x32_f16 v[136:139], v[202:205], v[190:193], v[136:139]
	s_waitcnt vmcnt(11)
	ds_write_b128 v126, v[16:19] offset:32768
	v_mfma_f32_16x16x32_f16 v[144:147], v[202:205], v[198:201], v[144:147]
	s_waitcnt vmcnt(10)
	ds_write_b128 v124, v[20:23] offset:32768
	s_waitcnt lgkmcnt(5)
	v_mfma_f32_16x16x32_f16 v[158:161], v[194:197], v[206:209], v[158:161]
	s_waitcnt vmcnt(9)
	ds_write_b128 v125, v[24:27] offset:32768
	s_waitcnt lgkmcnt(5)
	v_mfma_f32_16x16x32_f16 v[68:71], v[194:197], v[220:223], v[68:71]
	ds_read_b128 v[194:197], v130 offset:49152
	v_mfma_f32_16x16x32_f16 v[162:165], v[202:205], v[206:209], v[162:165]
	s_waitcnt vmcnt(8)
	ds_write_b128 v127, v[28:31] offset:32768
	v_mfma_f32_16x16x32_f16 v[76:79], v[202:205], v[220:223], v[76:79]
	ds_read_b128 v[202:205], v130 offset:51200
	v_mfma_f32_16x16x32_f16 v[140:143], v[210:213], v[190:193], v[140:143]
	v_mfma_f32_16x16x32_f16 v[154:157], v[210:213], v[198:201], v[154:157]
	s_waitcnt lgkmcnt(7)
	v_mfma_f32_16x16x32_f16 v[64:67], v[224:227], v[190:193], v[64:67]
	ds_read_b128 v[190:193], v129 offset:16384
	v_mfma_f32_16x16x32_f16 v[72:75], v[224:227], v[198:201], v[72:75]
	ds_read_b128 v[198:201], v129 offset:18432
	v_mfma_f32_16x16x32_f16 v[166:169], v[210:213], v[206:209], v[166:169]
	v_mfma_f32_16x16x32_f16 v[84:87], v[210:213], v[220:223], v[84:87]
	ds_read_b128 v[210:213], v130 offset:53248
	v_mfma_f32_16x16x32_f16 v[80:83], v[224:227], v[206:209], v[80:83]
	ds_read_b128 v[206:209], v129 offset:20480
	v_mfma_f32_16x16x32_f16 v[88:91], v[224:227], v[220:223], v[88:91]
	ds_read_b128 v[220:223], v129 offset:22528
	ds_read_b128 v[224:227], v130 offset:55296
	s_waitcnt lgkmcnt(0)
	s_barrier
; #define GL_LOAD(s_, kt_) if (VAR != 1) { a##s_##0 = GL_A(0, kt_); a##s_##1 = GL_A(1, kt_); a##s_##2 = GL_A(2, kt_); a##s_##3 = GL_A(3, kt_); b##s_##0 = GL_B(0, kt_); b##s_##1 = GL_B(1, kt_); b##s_##2 = GL_B(2, kt_); b##s_##3 = GL_B(3, kt_); }
; #define LDS_STORE(s_, buf_) if (VAR != 2) { LDS_ST1(sA, 0, buf_, a##s_##0) LDS_ST1(sA, 1, buf_, a##s_##1) LDS_ST1(sA, 2, buf_, a##s_##2) LDS_ST1(sA, 3, buf_, a##s_##3) LDS_ST1(sB, 0, buf_, b##s_##0) LDS_ST1(sB, 1, buf_, b##s_##1) LDS_ST1(sB, 2, buf_, b##s_##2) LDS_ST1(sB, 3, buf_, b##s_##3) }
;     ...
;   GL_LOAD(0, 0)
;   GL_LOAD(1, 1)
;   LDS_STORE(0, 0)
;   if (VAR != 4) __syncthreads();
; #pragma unroll
;   for (int kt = 0; kt < nk; kt += 2) {
;     if (kt + 2 < nk) { GL_LOAD(0, kt + 2) }
;     MMA_TILE(0)
;     LDS_STORE(1, 1)
;     if (VAR != 4) __syncthreads();
;     if (kt + 3 < nk) { GL_LOAD(1, kt + 3) }
;     MMA_TILE(1)
;     if (kt + 2 < nk) { LDS_STORE(0, 0) }
;     if (VAR != 4) __syncthreads();
	v_mfma_f32_16x16x32_f16 v[132:135], v[194:197], v[190:193], v[132:135]
	global_load_dwordx4 v[0:3], v[104:105], off offset:512
	v_mfma_f32_16x16x32_f16 v[92:95], v[194:197], v[198:201], v[92:95]
	global_load_dwordx4 v[4:7], v[106:107], off offset:512
	v_mfma_f32_16x16x32_f16 v[136:139], v[202:205], v[190:193], v[136:139]
	global_load_dwordx4 v[8:11], v[108:109], off offset:512
	v_mfma_f32_16x16x32_f16 v[144:147], v[202:205], v[198:201], v[144:147]
	global_load_dwordx4 v[12:15], v[110:111], off offset:512
	v_mfma_f32_16x16x32_f16 v[158:161], v[194:197], v[206:209], v[158:161]
	global_load_dwordx4 v[16:19], v[112:113], off offset:512
	v_mfma_f32_16x16x32_f16 v[68:71], v[194:197], v[220:223], v[68:71]
	ds_read_b128 v[194:197], v131 offset:32768
	v_mfma_f32_16x16x32_f16 v[162:165], v[202:205], v[206:209], v[162:165]
	global_load_dwordx4 v[20:23], v[114:115], off offset:512
	v_mfma_f32_16x16x32_f16 v[76:79], v[202:205], v[220:223], v[76:79]
	ds_read_b128 v[202:205], v131 offset:34816
	v_mfma_f32_16x16x32_f16 v[140:143], v[210:213], v[190:193], v[140:143]
	global_load_dwordx4 v[24:27], v[116:117], off offset:512
	v_mfma_f32_16x16x32_f16 v[154:157], v[210:213], v[198:201], v[154:157]
	global_load_dwordx4 v[28:31], v[118:119], off offset:512
	v_mfma_f32_16x16x32_f16 v[64:67], v[224:227], v[190:193], v[64:67]
	ds_read_b128 v[190:193], v128
	v_mfma_f32_16x16x32_f16 v[72:75], v[224:227], v[198:201], v[72:75]
	ds_read_b128 v[198:201], v128 offset:2048
	v_mfma_f32_16x16x32_f16 v[166:169], v[210:213], v[206:209], v[166:169]
	s_waitcnt vmcnt(15)
	ds_write_b128 v126, v[32:35] offset:16384
	v_mfma_f32_16x16x32_f16 v[84:87], v[210:213], v[220:223], v[84:87]
	ds_read_b128 v[210:213], v131 offset:36864
	v_mfma_f32_16x16x32_f16 v[80:83], v[224:227], v[206:209], v[80:83]
	ds_read_b128 v[206:209], v128 offset:4096
	v_mfma_f32_16x16x32_f16 v[88:91], v[224:227], v[220:223], v[88:91]
	ds_read_b128 v[220:223], v128 offset:6144
	s_waitcnt lgkmcnt(5)
	v_mfma_f32_16x16x32_f16 v[132:135], v[194:197], v[190:193], v[132:135]
	ds_read_b128 v[224:227], v131 offset:38912
	s_waitcnt lgkmcnt(5)
	v_mfma_f32_16x16x32_f16 v[92:95], v[194:197], v[198:201], v[92:95]
	s_waitcnt vmcnt(14)
	ds_write_b128 v124, v[36:39] offset:16384
	v_mfma_f32_16x16x32_f16 v[136:139], v[202:205], v[190:193], v[136:139]
	s_waitcnt vmcnt(13)
	ds_write_b128 v125, v[40:43] offset:16384
	v_mfma_f32_16x16x32_f16 v[144:147], v[202:205], v[198:201], v[144:147]
	s_waitcnt vmcnt(12)
	ds_write_b128 v127, v[44:47] offset:16384
	s_waitcnt lgkmcnt(5)
	v_mfma_f32_16x16x32_f16 v[158:161], v[194:197], v[206:209], v[158:161]
	s_waitcnt vmcnt(11)
	ds_write_b128 v126, v[48:51] offset:49152
	s_waitcnt lgkmcnt(5)
	v_mfma_f32_16x16x32_f16 v[68:71], v[194:197], v[220:223], v[68:71]
	ds_read_b128 v[194:197], v130 offset:32768
	v_mfma_f32_16x16x32_f16 v[162:165], v[202:205], v[206:209], v[162:165]
	s_waitcnt vmcnt(10)
	ds_write_b128 v124, v[52:55] offset:49152
	v_mfma_f32_16x16x32_f16 v[76:79], v[202:205], v[220:223], v[76:79]
	ds_read_b128 v[202:205], v130 offset:34816
	v_mfma_f32_16x16x32_f16 v[140:143], v[210:213], v[190:193], v[140:143]
	s_waitcnt vmcnt(9)
	ds_write_b128 v125, v[56:59] offset:49152
	v_mfma_f32_16x16x32_f16 v[154:157], v[210:213], v[198:201], v[154:157]
	s_waitcnt vmcnt(8)
	ds_write_b128 v127, v[60:63] offset:49152
	s_waitcnt lgkmcnt(9)
	v_mfma_f32_16x16x32_f16 v[64:67], v[224:227], v[190:193], v[64:67]
	ds_read_b128 v[190:193], v129
	v_mfma_f32_16x16x32_f16 v[72:75], v[224:227], v[198:201], v[72:75]
	ds_read_b128 v[198:201], v129 offset:2048
	v_mfma_f32_16x16x32_f16 v[166:169], v[210:213], v[206:209], v[166:169]
	v_mfma_f32_16x16x32_f16 v[84:87], v[210:213], v[220:223], v[84:87]
	ds_read_b128 v[210:213], v130 offset:36864
	v_mfma_f32_16x16x32_f16 v[80:83], v[224:227], v[206:209], v[80:83]
	ds_read_b128 v[206:209], v129 offset:4096
	v_mfma_f32_16x16x32_f16 v[88:91], v[224:227], v[220:223], v[88:91]
	ds_read_b128 v[220:223], v129 offset:6144
	ds_read_b128 v[224:227], v130 offset:38912
	s_waitcnt lgkmcnt(0)
	s_barrier
	v_mfma_f32_16x16x32_f16 v[132:135], v[194:197], v[190:193], v[132:135]
	global_load_dwordx4 v[32:35], v[104:105], off offset:640
	v_mfma_f32_16x16x32_f16 v[92:95], v[194:197], v[198:201], v[92:95]
	global_load_dwordx4 v[36:39], v[106:107], off offset:640
	v_mfma_f32_16x16x32_f16 v[136:139], v[202:205], v[190:193], v[136:139]
	global_load_dwordx4 v[40:43], v[108:109], off offset:640
	v_mfma_f32_16x16x32_f16 v[144:147], v[202:205], v[198:201], v[144:147]
	global_load_dwordx4 v[44:47], v[110:111], off offset:640
	v_mfma_f32_16x16x32_f16 v[158:161], v[194:197], v[206:209], v[158:161]
	global_load_dwordx4 v[48:51], v[112:113], off offset:640
	v_mfma_f32_16x16x32_f16 v[68:71], v[194:197], v[220:223], v[68:71]
	ds_read_b128 v[194:197], v131 offset:49152
	v_mfma_f32_16x16x32_f16 v[162:165], v[202:205], v[206:209], v[162:165]
	global_load_dwordx4 v[52:55], v[114:115], off offset:640
	v_mfma_f32_16x16x32_f16 v[76:79], v[202:205], v[220:223], v[76:79]
	ds_read_b128 v[202:205], v131 offset:51200
	v_mfma_f32_16x16x32_f16 v[140:143], v[210:213], v[190:193], v[140:143]
	global_load_dwordx4 v[56:59], v[116:117], off offset:640
	v_mfma_f32_16x16x32_f16 v[154:157], v[210:213], v[198:201], v[154:157]
	global_load_dwordx4 v[60:63], v[118:119], off offset:640
	v_mfma_f32_16x16x32_f16 v[64:67], v[224:227], v[190:193], v[64:67]
	ds_read_b128 v[190:193], v128 offset:16384
	v_mfma_f32_16x16x32_f16 v[72:75], v[224:227], v[198:201], v[72:75]
	ds_read_b128 v[198:201], v128 offset:18432
	v_mfma_f32_16x16x32_f16 v[166:169], v[210:213], v[206:209], v[166:169]
	s_waitcnt vmcnt(15)
; #define GL_LOAD(s_, kt_) if (VAR != 1) { a##s_##0 = GL_A(0, kt_); a##s_##1 = GL_A(1, kt_); a##s_##2 = GL_A(2, kt_); a##s_##3 = GL_A(3, kt_); b##s_##0 = GL_B(0, kt_); b##s_##1 = GL_B(1, kt_); b##s_##2 = GL_B(2, kt_); b##s_##3 = GL_B(3, kt_); }
; #define LDS_STORE(s_, buf_) if (VAR != 2) { LDS_ST1(sA, 0, buf_, a##s_##0) LDS_ST1(sA, 1, buf_, a##s_##1) LDS_ST1(sA, 2, buf_, a##s_##2) LDS_ST1(sA, 3, buf_, a##s_##3) LDS_ST1(sB, 0, buf_, b##s_##0) LDS_ST1(sB, 1, buf_, b##s_##1) LDS_ST1(sB, 2, buf_, b##s_##2) LDS_ST1(sB, 3, buf_, b##s_##3) }
;     ...
;   GL_LOAD(0, 0)
;   GL_LOAD(1, 1)
;   LDS_STORE(0, 0)
;   if (VAR != 4) __syncthreads();
; #pragma unroll
;   for (int kt = 0; kt < nk; kt += 2) {
;     if (kt + 2 < nk) { GL_LOAD(0, kt + 2) }
;     MMA_TILE(0)
;     LDS_STORE(1, 1)
;     if (VAR != 4) __syncthreads();
;     if (kt + 3 < nk) { GL_LOAD(1, kt + 3) }
;     MMA_TILE(1)
;     if (kt + 2 < nk) { LDS_STORE(0, 0) }
;     if (VAR != 4) __syncthreads();
	ds_write_b128 v126, v[0:3]
	v_mfma_f32_16x16x32_f16 v[84:87], v[210:213], v[220:223], v[84:87]
	ds_read_b128 v[210:213], v131 offset:53248
	v_mfma_f32_16x16x32_f16 v[80:83], v[224:227], v[206:209], v[80:83]
	ds_read_b128 v[206:209], v128 offset:20480
	v_mfma_f32_16x16x32_f16 v[88:91], v[224:227], v[220:223], v[88:91]
	ds_read_b128 v[220:223], v128 offset:22528
	s_waitcnt lgkmcnt(5)
	v_mfma_f32_16x16x32_f16 v[132:135], v[194:197], v[190:193], v[132:135]
	ds_read_b128 v[224:227], v131 offset:55296
	s_waitcnt lgkmcnt(5)
	v_mfma_f32_16x16x32_f16 v[92:95], v[194:197], v[198:201], v[92:95]
	s_waitcnt vmcnt(14)
	ds_write_b128 v124, v[4:7]
	v_mfma_f32_16x16x32_f16 v[136:139], v[202:205], v[190:193], v[136:139]
	s_waitcnt vmcnt(13)
	ds_write_b128 v125, v[8:11]
	v_mfma_f32_16x16x32_f16 v[144:147], v[202:205], v[198:201], v[144:147]
	s_waitcnt vmcnt(12)
	ds_write_b128 v127, v[12:15]
	s_waitcnt lgkmcnt(5)
	v_mfma_f32_16x16x32_f16 v[158:161], v[194:197], v[206:209], v[158:161]
	s_waitcnt vmcnt(11)
	ds_write_b128 v126, v[16:19] offset:32768
	s_waitcnt lgkmcnt(5)
	v_mfma_f32_16x16x32_f16 v[68:71], v[194:197], v[220:223], v[68:71]
	ds_read_b128 v[194:197], v130 offset:49152
	v_mfma_f32_16x16x32_f16 v[162:165], v[202:205], v[206:209], v[162:165]
	s_waitcnt vmcnt(10)
	ds_write_b128 v124, v[20:23] offset:32768
	v_mfma_f32_16x16x32_f16 v[76:79], v[202:205], v[220:223], v[76:79]
	ds_read_b128 v[202:205], v130 offset:51200
	v_mfma_f32_16x16x32_f16 v[140:143], v[210:213], v[190:193], v[140:143]
	s_waitcnt vmcnt(9)
	ds_write_b128 v125, v[24:27] offset:32768
	v_mfma_f32_16x16x32_f16 v[154:157], v[210:213], v[198:201], v[154:157]
	s_waitcnt vmcnt(8)
	ds_write_b128 v127, v[28:31] offset:32768
	s_waitcnt lgkmcnt(9)
	v_mfma_f32_16x16x32_f16 v[64:67], v[224:227], v[190:193], v[64:67]
	ds_read_b128 v[190:193], v129 offset:16384
	v_mfma_f32_16x16x32_f16 v[72:75], v[224:227], v[198:201], v[72:75]
	ds_read_b128 v[198:201], v129 offset:18432
	v_mfma_f32_16x16x32_f16 v[166:169], v[210:213], v[206:209], v[166:169]
	v_mfma_f32_16x16x32_f16 v[84:87], v[210:213], v[220:223], v[84:87]
	ds_read_b128 v[210:213], v130 offset:53248
	v_mfma_f32_16x16x32_f16 v[80:83], v[224:227], v[206:209], v[80:83]
	ds_read_b128 v[206:209], v129 offset:20480
	v_mfma_f32_16x16x32_f16 v[88:91], v[224:227], v[220:223], v[88:91]
	ds_read_b128 v[220:223], v129 offset:22528
	ds_read_b128 v[224:227], v130 offset:55296
	s_waitcnt lgkmcnt(0)
	s_barrier
	v_mfma_f32_16x16x32_f16 v[132:135], v[194:197], v[190:193], v[132:135]
	global_load_dwordx4 v[0:3], v[104:105], off offset:768
	v_mfma_f32_16x16x32_f16 v[92:95], v[194:197], v[198:201], v[92:95]
	global_load_dwordx4 v[4:7], v[106:107], off offset:768
	v_mfma_f32_16x16x32_f16 v[136:139], v[202:205], v[190:193], v[136:139]
	global_load_dwordx4 v[8:11], v[108:109], off offset:768
	v_mfma_f32_16x16x32_f16 v[144:147], v[202:205], v[198:201], v[144:147]
	global_load_dwordx4 v[12:15], v[110:111], off offset:768
	v_mfma_f32_16x16x32_f16 v[158:161], v[194:197], v[206:209], v[158:161]
	global_load_dwordx4 v[16:19], v[112:113], off offset:768
	v_mfma_f32_16x16x32_f16 v[68:71], v[194:197], v[220:223], v[68:71]
	ds_read_b128 v[194:197], v131 offset:32768
	v_mfma_f32_16x16x32_f16 v[162:165], v[202:205], v[206:209], v[162:165]
	global_load_dwordx4 v[20:23], v[114:115], off offset:768
	v_mfma_f32_16x16x32_f16 v[76:79], v[202:205], v[220:223], v[76:79]
	ds_read_b128 v[202:205], v131 offset:34816
	v_mfma_f32_16x16x32_f16 v[140:143], v[210:213], v[190:193], v[140:143]
	global_load_dwordx4 v[24:27], v[116:117], off offset:768
	v_mfma_f32_16x16x32_f16 v[154:157], v[210:213], v[198:201], v[154:157]
	global_load_dwordx4 v[28:31], v[118:119], off offset:768
	v_mfma_f32_16x16x32_f16 v[64:67], v[224:227], v[190:193], v[64:67]
	ds_read_b128 v[190:193], v128
	v_mfma_f32_16x16x32_f16 v[72:75], v[224:227], v[198:201], v[72:75]
	ds_read_b128 v[198:201], v128 offset:2048
	v_mfma_f32_16x16x32_f16 v[166:169], v[210:213], v[206:209], v[166:169]
	s_waitcnt vmcnt(15)
	ds_write_b128 v126, v[32:35] offset:16384
	v_mfma_f32_16x16x32_f16 v[84:87], v[210:213], v[220:223], v[84:87]
	ds_read_b128 v[210:213], v131 offset:36864
	v_mfma_f32_16x16x32_f16 v[80:83], v[224:227], v[206:209], v[80:83]
	ds_read_b128 v[206:209], v128 offset:4096
	v_mfma_f32_16x16x32_f16 v[88:91], v[224:227], v[220:223], v[88:91]
	ds_read_b128 v[220:223], v128 offset:6144
	s_waitcnt lgkmcnt(5)
	v_mfma_f32_16x16x32_f16 v[132:135], v[194:197], v[190:193], v[132:135]
	ds_read_b128 v[224:227], v131 offset:38912
	s_waitcnt lgkmcnt(5)
	v_mfma_f32_16x16x32_f16 v[92:95], v[194:197], v[198:201], v[92:95]
	s_waitcnt vmcnt(14)
	ds_write_b128 v124, v[36:39] offset:16384
	v_mfma_f32_16x16x32_f16 v[136:139], v[202:205], v[190:193], v[136:139]
	s_waitcnt vmcnt(13)
	ds_write_b128 v125, v[40:43] offset:16384
	v_mfma_f32_16x16x32_f16 v[144:147], v[202:205], v[198:201], v[144:147]
	s_waitcnt vmcnt(12)
	ds_write_b128 v127, v[44:47] offset:16384
	s_waitcnt lgkmcnt(5)
	v_mfma_f32_16x16x32_f16 v[158:161], v[194:197], v[206:209], v[158:161]
	s_waitcnt vmcnt(11)
	ds_write_b128 v126, v[48:51] offset:49152
	s_waitcnt lgkmcnt(5)
	v_mfma_f32_16x16x32_f16 v[68:71], v[194:197], v[220:223], v[68:71]
	ds_read_b128 v[194:197], v130 offset:32768
	v_mfma_f32_16x16x32_f16 v[162:165], v[202:205], v[206:209], v[162:165]
	s_waitcnt vmcnt(10)
	ds_write_b128 v124, v[52:55] offset:49152
	v_mfma_f32_16x16x32_f16 v[76:79], v[202:205], v[220:223], v[76:79]
	ds_read_b128 v[202:205], v130 offset:34816
	v_mfma_f32_16x16x32_f16 v[140:143], v[210:213], v[190:193], v[140:143]
	s_waitcnt vmcnt(9)
	ds_write_b128 v125, v[56:59] offset:49152
	v_mfma_f32_16x16x32_f16 v[154:157], v[210:213], v[198:201], v[154:157]
	s_waitcnt vmcnt(8)
	ds_write_b128 v127, v[60:63] offset:49152
	s_waitcnt lgkmcnt(9)
	v_mfma_f32_16x16x32_f16 v[64:67], v[224:227], v[190:193], v[64:67]
	ds_read_b128 v[190:193], v129
	v_mfma_f32_16x16x32_f16 v[72:75], v[224:227], v[198:201], v[72:75]
	ds_read_b128 v[198:201], v129 offset:2048
	v_mfma_f32_16x16x32_f16 v[166:169], v[210:213], v[206:209], v[166:169]
	v_mfma_f32_16x16x32_f16 v[84:87], v[210:213], v[220:223], v[84:87]
	ds_read_b128 v[210:213], v130 offset:36864
	v_mfma_f32_16x16x32_f16 v[80:83], v[224:227], v[206:209], v[80:83]
	ds_read_b128 v[206:209], v129 offset:4096
	v_mfma_f32_16x16x32_f16 v[88:91], v[224:227], v[220:223], v[88:91]
	ds_read_b128 v[220:223], v129 offset:6144
	ds_read_b128 v[224:227], v130 offset:38912
	s_waitcnt lgkmcnt(0)
	s_barrier
; #define GL_LOAD(s_, kt_) if (VAR != 1) { a##s_##0 = GL_A(0, kt_); a##s_##1 = GL_A(1, kt_); a##s_##2 = GL_A(2, kt_); a##s_##3 = GL_A(3, kt_); b##s_##0 = GL_B(0, kt_); b##s_##1 = GL_B(1, kt_); b##s_##2 = GL_B(2, kt_); b##s_##3 = GL_B(3, kt_); }
; #define LDS_STORE(s_, buf_) if (VAR != 2) { LDS_ST1(sA, 0, buf_, a##s_##0) LDS_ST1(sA, 1, buf_, a##s_##1) LDS_ST1(sA, 2, buf_, a##s_##2) LDS_ST1(sA, 3, buf_, a##s_##3) LDS_ST1(sB, 0, buf_, b##s_##0) LDS_ST1(sB, 1, buf_, b##s_##1) LDS_ST1(sB, 2, buf_, b##s_##2) LDS_ST1(sB, 3, buf_, b##s_##3) }
;     ...
;   GL_LOAD(0, 0)
;   GL_LOAD(1, 1)
;   LDS_STORE(0, 0)
;   if (VAR != 4) __syncthreads();
; #pragma unroll
;   for (int kt = 0; kt < nk; kt += 2) {
;     if (kt + 2 < nk) { GL_LOAD(0, kt + 2) }
;     MMA_TILE(0)
;     LDS_STORE(1, 1)
;     if (VAR != 4) __syncthreads();
;     if (kt + 3 < nk) { GL_LOAD(1, kt + 3) }
;     MMA_TILE(1)
;     if (kt + 2 < nk) { LDS_STORE(0, 0) }
;     if (VAR != 4) __syncthreads();
	v_mfma_f32_16x16x32_f16 v[132:135], v[194:197], v[190:193], v[132:135]
	global_load_dwordx4 v[32:35], v[104:105], off offset:896
	v_mfma_f32_16x16x32_f16 v[92:95], v[194:197], v[198:201], v[92:95]
	global_load_dwordx4 v[36:39], v[106:107], off offset:896
	v_mfma_f32_16x16x32_f16 v[136:139], v[202:205], v[190:193], v[136:139]
	global_load_dwordx4 v[40:43], v[108:109], off offset:896
	v_mfma_f32_16x16x32_f16 v[144:147], v[202:205], v[198:201], v[144:147]
	global_load_dwordx4 v[44:47], v[110:111], off offset:896
	v_mfma_f32_16x16x32_f16 v[158:161], v[194:197], v[206:209], v[158:161]
	global_load_dwordx4 v[48:51], v[112:113], off offset:896
	v_mfma_f32_16x16x32_f16 v[68:71], v[194:197], v[220:223], v[68:71]
	ds_read_b128 v[194:197], v131 offset:49152
	v_mfma_f32_16x16x32_f16 v[162:165], v[202:205], v[206:209], v[162:165]
	global_load_dwordx4 v[52:55], v[114:115], off offset:896
	v_mfma_f32_16x16x32_f16 v[76:79], v[202:205], v[220:223], v[76:79]
	ds_read_b128 v[202:205], v131 offset:51200
	v_mfma_f32_16x16x32_f16 v[140:143], v[210:213], v[190:193], v[140:143]
	global_load_dwordx4 v[56:59], v[116:117], off offset:896
	v_mfma_f32_16x16x32_f16 v[154:157], v[210:213], v[198:201], v[154:157]
	global_load_dwordx4 v[60:63], v[118:119], off offset:896
	v_mfma_f32_16x16x32_f16 v[64:67], v[224:227], v[190:193], v[64:67]
	ds_read_b128 v[190:193], v128 offset:16384
	v_mfma_f32_16x16x32_f16 v[72:75], v[224:227], v[198:201], v[72:75]
	ds_read_b128 v[198:201], v128 offset:18432
	v_mfma_f32_16x16x32_f16 v[166:169], v[210:213], v[206:209], v[166:169]
	s_waitcnt vmcnt(15)
	ds_write_b128 v126, v[0:3]
	v_mfma_f32_16x16x32_f16 v[84:87], v[210:213], v[220:223], v[84:87]
	ds_read_b128 v[210:213], v131 offset:53248
	v_mfma_f32_16x16x32_f16 v[80:83], v[224:227], v[206:209], v[80:83]
	ds_read_b128 v[206:209], v128 offset:20480
	v_mfma_f32_16x16x32_f16 v[88:91], v[224:227], v[220:223], v[88:91]
	ds_read_b128 v[220:223], v128 offset:22528
	s_waitcnt lgkmcnt(5)
	v_mfma_f32_16x16x32_f16 v[132:135], v[194:197], v[190:193], v[132:135]
	ds_read_b128 v[224:227], v131 offset:55296
	s_waitcnt lgkmcnt(5)
	v_mfma_f32_16x16x32_f16 v[92:95], v[194:197], v[198:201], v[92:95]
	s_waitcnt vmcnt(14)
	ds_write_b128 v124, v[4:7]
	v_mfma_f32_16x16x32_f16 v[136:139], v[202:205], v[190:193], v[136:139]
	s_waitcnt vmcnt(13)
	ds_write_b128 v125, v[8:11]
	v_mfma_f32_16x16x32_f16 v[144:147], v[202:205], v[198:201], v[144:147]
	s_waitcnt vmcnt(12)
	ds_write_b128 v127, v[12:15]
	s_waitcnt lgkmcnt(5)
	v_mfma_f32_16x16x32_f16 v[158:161], v[194:197], v[206:209], v[158:161]
	s_waitcnt vmcnt(11)
	ds_write_b128 v126, v[16:19] offset:32768
	s_waitcnt lgkmcnt(5)
	v_mfma_f32_16x16x32_f16 v[68:71], v[194:197], v[220:223], v[68:71]
	ds_read_b128 v[194:197], v130 offset:49152
	v_mfma_f32_16x16x32_f16 v[162:165], v[202:205], v[206:209], v[162:165]
	s_waitcnt vmcnt(10)
	ds_write_b128 v124, v[20:23] offset:32768
	v_mfma_f32_16x16x32_f16 v[76:79], v[202:205], v[220:223], v[76:79]
	ds_read_b128 v[202:205], v130 offset:51200
	v_mfma_f32_16x16x32_f16 v[140:143], v[210:213], v[190:193], v[140:143]
	s_waitcnt vmcnt(9)
	ds_write_b128 v125, v[24:27] offset:32768
	v_mfma_f32_16x16x32_f16 v[154:157], v[210:213], v[198:201], v[154:157]
	s_waitcnt vmcnt(8)
	ds_write_b128 v127, v[28:31] offset:32768
	s_waitcnt lgkmcnt(9)
	v_mfma_f32_16x16x32_f16 v[64:67], v[224:227], v[190:193], v[64:67]
	ds_read_b128 v[190:193], v129 offset:16384
	v_mfma_f32_16x16x32_f16 v[72:75], v[224:227], v[198:201], v[72:75]
	ds_read_b128 v[198:201], v129 offset:18432
	v_mfma_f32_16x16x32_f16 v[166:169], v[210:213], v[206:209], v[166:169]
	v_mfma_f32_16x16x32_f16 v[84:87], v[210:213], v[220:223], v[84:87]
	ds_read_b128 v[210:213], v130 offset:53248
	v_mfma_f32_16x16x32_f16 v[80:83], v[224:227], v[206:209], v[80:83]
	ds_read_b128 v[206:209], v129 offset:20480
	v_mfma_f32_16x16x32_f16 v[88:91], v[224:227], v[220:223], v[88:91]
	ds_read_b128 v[220:223], v129 offset:22528
	ds_read_b128 v[224:227], v130 offset:55296
	s_waitcnt lgkmcnt(0)
	s_barrier
	v_mfma_f32_16x16x32_f16 v[132:135], v[194:197], v[190:193], v[132:135]
	global_load_dwordx4 v[0:3], v[104:105], off offset:1024
	v_mfma_f32_16x16x32_f16 v[92:95], v[194:197], v[198:201], v[92:95]
	global_load_dwordx4 v[4:7], v[106:107], off offset:1024
	v_mfma_f32_16x16x32_f16 v[136:139], v[202:205], v[190:193], v[136:139]
	global_load_dwordx4 v[8:11], v[108:109], off offset:1024
	v_mfma_f32_16x16x32_f16 v[144:147], v[202:205], v[198:201], v[144:147]
	global_load_dwordx4 v[12:15], v[110:111], off offset:1024
	v_mfma_f32_16x16x32_f16 v[158:161], v[194:197], v[206:209], v[158:161]
	global_load_dwordx4 v[16:19], v[112:113], off offset:1024
	v_mfma_f32_16x16x32_f16 v[68:71], v[194:197], v[220:223], v[68:71]
	ds_read_b128 v[194:197], v131 offset:32768
	v_mfma_f32_16x16x32_f16 v[162:165], v[202:205], v[206:209], v[162:165]
	global_load_dwordx4 v[20:23], v[114:115], off offset:1024
	v_mfma_f32_16x16x32_f16 v[76:79], v[202:205], v[220:223], v[76:79]
	ds_read_b128 v[202:205], v131 offset:34816
	v_mfma_f32_16x16x32_f16 v[140:143], v[210:213], v[190:193], v[140:143]
	global_load_dwordx4 v[24:27], v[116:117], off offset:1024
	v_mfma_f32_16x16x32_f16 v[154:157], v[210:213], v[198:201], v[154:157]
	global_load_dwordx4 v[28:31], v[118:119], off offset:1024
	v_mfma_f32_16x16x32_f16 v[64:67], v[224:227], v[190:193], v[64:67]
	ds_read_b128 v[190:193], v128
	v_mfma_f32_16x16x32_f16 v[72:75], v[224:227], v[198:201], v[72:75]
	ds_read_b128 v[198:201], v128 offset:2048
	v_mfma_f32_16x16x32_f16 v[166:169], v[210:213], v[206:209], v[166:169]
	s_waitcnt vmcnt(15)
; #define GL_LOAD(s_, kt_) if (VAR != 1) { a##s_##0 = GL_A(0, kt_); a##s_##1 = GL_A(1, kt_); a##s_##2 = GL_A(2, kt_); a##s_##3 = GL_A(3, kt_); b##s_##0 = GL_B(0, kt_); b##s_##1 = GL_B(1, kt_); b##s_##2 = GL_B(2, kt_); b##s_##3 = GL_B(3, kt_); }
; #define LDS_STORE(s_, buf_) if (VAR != 2) { LDS_ST1(sA, 0, buf_, a##s_##0) LDS_ST1(sA, 1, buf_, a##s_##1) LDS_ST1(sA, 2, buf_, a##s_##2) LDS_ST1(sA, 3, buf_, a##s_##3) LDS_ST1(sB, 0, buf_, b##s_##0) LDS_ST1(sB, 1, buf_, b##s_##1) LDS_ST1(sB, 2, buf_, b##s_##2) LDS_ST1(sB, 3, buf_, b##s_##3) }
;     ...
;   GL_LOAD(0, 0)
;   GL_LOAD(1, 1)
;   LDS_STORE(0, 0)
;   if (VAR != 4) __syncthreads();
; #pragma unroll
;   for (int kt = 0; kt < nk; kt += 2) {
;     if (kt + 2 < nk) { GL_LOAD(0, kt + 2) }
;     MMA_TILE(0)
;     LDS_STORE(1, 1)
;     if (VAR != 4) __syncthreads();
;     if (kt + 3 < nk) { GL_LOAD(1, kt + 3) }
;     MMA_TILE(1)
;     if (kt + 2 < nk) { LDS_STORE(0, 0) }
;     if (VAR != 4) __syncthreads();
	ds_write_b128 v126, v[32:35] offset:16384
	v_mfma_f32_16x16x32_f16 v[84:87], v[210:213], v[220:223], v[84:87]
	ds_read_b128 v[210:213], v131 offset:36864
	v_mfma_f32_16x16x32_f16 v[80:83], v[224:227], v[206:209], v[80:83]
	ds_read_b128 v[206:209], v128 offset:4096
	v_mfma_f32_16x16x32_f16 v[88:91], v[224:227], v[220:223], v[88:91]
	ds_read_b128 v[220:223], v128 offset:6144
	s_waitcnt lgkmcnt(5)
	v_mfma_f32_16x16x32_f16 v[132:135], v[194:197], v[190:193], v[132:135]
	ds_read_b128 v[224:227], v131 offset:38912
	s_waitcnt lgkmcnt(5)
	v_mfma_f32_16x16x32_f16 v[92:95], v[194:197], v[198:201], v[92:95]
	s_waitcnt vmcnt(14)
	ds_write_b128 v124, v[36:39] offset:16384
	v_mfma_f32_16x16x32_f16 v[136:139], v[202:205], v[190:193], v[136:139]
	s_waitcnt vmcnt(13)
	ds_write_b128 v125, v[40:43] offset:16384
	v_mfma_f32_16x16x32_f16 v[144:147], v[202:205], v[198:201], v[144:147]
	s_waitcnt vmcnt(12)
	ds_write_b128 v127, v[44:47] offset:16384
	s_waitcnt lgkmcnt(5)
	v_mfma_f32_16x16x32_f16 v[158:161], v[194:197], v[206:209], v[158:161]
	s_waitcnt vmcnt(11)
	ds_write_b128 v126, v[48:51] offset:49152
	s_waitcnt lgkmcnt(5)
	v_mfma_f32_16x16x32_f16 v[68:71], v[194:197], v[220:223], v[68:71]
	ds_read_b128 v[194:197], v130 offset:32768
	v_mfma_f32_16x16x32_f16 v[162:165], v[202:205], v[206:209], v[162:165]
	s_waitcnt vmcnt(10)
	ds_write_b128 v124, v[52:55] offset:49152
	v_mfma_f32_16x16x32_f16 v[76:79], v[202:205], v[220:223], v[76:79]
	ds_read_b128 v[202:205], v130 offset:34816
	v_mfma_f32_16x16x32_f16 v[140:143], v[210:213], v[190:193], v[140:143]
	s_waitcnt vmcnt(9)
	ds_write_b128 v125, v[56:59] offset:49152
	v_mfma_f32_16x16x32_f16 v[154:157], v[210:213], v[198:201], v[154:157]
	s_waitcnt vmcnt(8)
	ds_write_b128 v127, v[60:63] offset:49152
	s_waitcnt lgkmcnt(9)
	v_mfma_f32_16x16x32_f16 v[64:67], v[224:227], v[190:193], v[64:67]
	ds_read_b128 v[190:193], v129
	v_mfma_f32_16x16x32_f16 v[72:75], v[224:227], v[198:201], v[72:75]
	ds_read_b128 v[198:201], v129 offset:2048
	v_mfma_f32_16x16x32_f16 v[166:169], v[210:213], v[206:209], v[166:169]
	v_mfma_f32_16x16x32_f16 v[84:87], v[210:213], v[220:223], v[84:87]
	ds_read_b128 v[210:213], v130 offset:36864
	v_mfma_f32_16x16x32_f16 v[80:83], v[224:227], v[206:209], v[80:83]
	ds_read_b128 v[206:209], v129 offset:4096
	v_mfma_f32_16x16x32_f16 v[88:91], v[224:227], v[220:223], v[88:91]
	ds_read_b128 v[220:223], v129 offset:6144
	ds_read_b128 v[224:227], v130 offset:38912
	s_waitcnt lgkmcnt(0)
	s_barrier
	v_mfma_f32_16x16x32_f16 v[132:135], v[194:197], v[190:193], v[132:135]
	global_load_dwordx4 v[32:35], v[104:105], off offset:1152
	v_mfma_f32_16x16x32_f16 v[92:95], v[194:197], v[198:201], v[92:95]
	global_load_dwordx4 v[36:39], v[106:107], off offset:1152
	v_mfma_f32_16x16x32_f16 v[136:139], v[202:205], v[190:193], v[136:139]
	global_load_dwordx4 v[40:43], v[108:109], off offset:1152
	v_mfma_f32_16x16x32_f16 v[144:147], v[202:205], v[198:201], v[144:147]
	global_load_dwordx4 v[44:47], v[110:111], off offset:1152
	v_mfma_f32_16x16x32_f16 v[158:161], v[194:197], v[206:209], v[158:161]
	global_load_dwordx4 v[48:51], v[112:113], off offset:1152
	v_mfma_f32_16x16x32_f16 v[68:71], v[194:197], v[220:223], v[68:71]
	ds_read_b128 v[194:197], v131 offset:49152
	v_mfma_f32_16x16x32_f16 v[162:165], v[202:205], v[206:209], v[162:165]
	global_load_dwordx4 v[52:55], v[114:115], off offset:1152
	v_mfma_f32_16x16x32_f16 v[76:79], v[202:205], v[220:223], v[76:79]
	ds_read_b128 v[202:205], v131 offset:51200
	v_mfma_f32_16x16x32_f16 v[140:143], v[210:213], v[190:193], v[140:143]
	global_load_dwordx4 v[56:59], v[116:117], off offset:1152
	v_mfma_f32_16x16x32_f16 v[154:157], v[210:213], v[198:201], v[154:157]
	global_load_dwordx4 v[60:63], v[118:119], off offset:1152
	v_mfma_f32_16x16x32_f16 v[64:67], v[224:227], v[190:193], v[64:67]
	ds_read_b128 v[190:193], v128 offset:16384
	v_mfma_f32_16x16x32_f16 v[72:75], v[224:227], v[198:201], v[72:75]
	ds_read_b128 v[198:201], v128 offset:18432
	v_mfma_f32_16x16x32_f16 v[166:169], v[210:213], v[206:209], v[166:169]
	s_waitcnt vmcnt(15)
	ds_write_b128 v126, v[0:3]
	v_mfma_f32_16x16x32_f16 v[84:87], v[210:213], v[220:223], v[84:87]
	ds_read_b128 v[210:213], v131 offset:53248
	v_mfma_f32_16x16x32_f16 v[80:83], v[224:227], v[206:209], v[80:83]
	ds_read_b128 v[206:209], v128 offset:20480
	v_mfma_f32_16x16x32_f16 v[88:91], v[224:227], v[220:223], v[88:91]
	ds_read_b128 v[220:223], v128 offset:22528
	s_waitcnt lgkmcnt(5)
	v_mfma_f32_16x16x32_f16 v[132:135], v[194:197], v[190:193], v[132:135]
	ds_read_b128 v[224:227], v131 offset:55296
	s_waitcnt lgkmcnt(5)
	v_mfma_f32_16x16x32_f16 v[92:95], v[194:197], v[198:201], v[92:95]
	s_waitcnt vmcnt(14)
	ds_write_b128 v124, v[4:7]
	v_mfma_f32_16x16x32_f16 v[136:139], v[202:205], v[190:193], v[136:139]
	s_waitcnt vmcnt(13)
	ds_write_b128 v125, v[8:11]
	v_mfma_f32_16x16x32_f16 v[144:147], v[202:205], v[198:201], v[144:147]
	s_waitcnt vmcnt(12)
	ds_write_b128 v127, v[12:15]
	s_waitcnt lgkmcnt(5)
	v_mfma_f32_16x16x32_f16 v[158:161], v[194:197], v[206:209], v[158:161]
	s_waitcnt vmcnt(11)
	ds_write_b128 v126, v[16:19] offset:32768
	s_waitcnt lgkmcnt(5)
	v_mfma_f32_16x16x32_f16 v[68:71], v[194:197], v[220:223], v[68:71]
	ds_read_b128 v[194:197], v130 offset:49152
	v_mfma_f32_16x16x32_f16 v[162:165], v[202:205], v[206:209], v[162:165]
	s_waitcnt vmcnt(10)
	ds_write_b128 v124, v[20:23] offset:32768
	v_mfma_f32_16x16x32_f16 v[76:79], v[202:205], v[220:223], v[76:79]
	ds_read_b128 v[202:205], v130 offset:51200
	v_mfma_f32_16x16x32_f16 v[140:143], v[210:213], v[190:193], v[140:143]
	s_waitcnt vmcnt(9)
	ds_write_b128 v125, v[24:27] offset:32768
	v_mfma_f32_16x16x32_f16 v[154:157], v[210:213], v[198:201], v[154:157]
	s_waitcnt vmcnt(8)
	ds_write_b128 v127, v[28:31] offset:32768
	s_waitcnt lgkmcnt(9)
	v_mfma_f32_16x16x32_f16 v[64:67], v[224:227], v[190:193], v[64:67]
	ds_read_b128 v[190:193], v129 offset:16384
	v_mfma_f32_16x16x32_f16 v[72:75], v[224:227], v[198:201], v[72:75]
	ds_read_b128 v[198:201], v129 offset:18432
	v_mfma_f32_16x16x32_f16 v[166:169], v[210:213], v[206:209], v[166:169]
	v_mfma_f32_16x16x32_f16 v[84:87], v[210:213], v[220:223], v[84:87]
	ds_read_b128 v[210:213], v130 offset:53248
	v_mfma_f32_16x16x32_f16 v[80:83], v[224:227], v[206:209], v[80:83]
	ds_read_b128 v[206:209], v129 offset:20480
	v_mfma_f32_16x16x32_f16 v[88:91], v[224:227], v[220:223], v[88:91]
	ds_read_b128 v[220:223], v129 offset:22528
	ds_read_b128 v[224:227], v130 offset:55296
	s_waitcnt lgkmcnt(0)
	s_barrier
; #define GL_LOAD(s_, kt_) if (VAR != 1) { a##s_##0 = GL_A(0, kt_); a##s_##1 = GL_A(1, kt_); a##s_##2 = GL_A(2, kt_); a##s_##3 = GL_A(3, kt_); b##s_##0 = GL_B(0, kt_); b##s_##1 = GL_B(1, kt_); b##s_##2 = GL_B(2, kt_); b##s_##3 = GL_B(3, kt_); }
; #define LDS_STORE(s_, buf_) if (VAR != 2) { LDS_ST1(sA, 0, buf_, a##s_##0) LDS_ST1(sA, 1, buf_, a##s_##1) LDS_ST1(sA, 2, buf_, a##s_##2) LDS_ST1(sA, 3, buf_, a##s_##3) LDS_ST1(sB, 0, buf_, b##s_##0) LDS_ST1(sB, 1, buf_, b##s_##1) LDS_ST1(sB, 2, buf_, b##s_##2) LDS_ST1(sB, 3, buf_, b##s_##3) }
;     ...
;   GL_LOAD(0, 0)
;   GL_LOAD(1, 1)
;   LDS_STORE(0, 0)
;   if (VAR != 4) __syncthreads();
; #pragma unroll
;   for (int kt = 0; kt < nk; kt += 2) {
;     if (kt + 2 < nk) { GL_LOAD(0, kt + 2) }
;     MMA_TILE(0)
;     LDS_STORE(1, 1)
;     if (VAR != 4) __syncthreads();
;     if (kt + 3 < nk) { GL_LOAD(1, kt + 3) }
;     MMA_TILE(1)
;     if (kt + 2 < nk) { LDS_STORE(0, 0) }
;     if (VAR != 4) __syncthreads();
	v_mfma_f32_16x16x32_f16 v[132:135], v[194:197], v[190:193], v[132:135]
	global_load_dwordx4 v[0:3], v[104:105], off offset:1280
	v_mfma_f32_16x16x32_f16 v[92:95], v[194:197], v[198:201], v[92:95]
	global_load_dwordx4 v[4:7], v[106:107], off offset:1280
	v_mfma_f32_16x16x32_f16 v[136:139], v[202:205], v[190:193], v[136:139]
	global_load_dwordx4 v[8:11], v[108:109], off offset:1280
	v_mfma_f32_16x16x32_f16 v[144:147], v[202:205], v[198:201], v[144:147]
	global_load_dwordx4 v[12:15], v[110:111], off offset:1280
	v_mfma_f32_16x16x32_f16 v[158:161], v[194:197], v[206:209], v[158:161]
	global_load_dwordx4 v[16:19], v[112:113], off offset:1280
	v_mfma_f32_16x16x32_f16 v[68:71], v[194:197], v[220:223], v[68:71]
	ds_read_b128 v[194:197], v131 offset:32768
	v_mfma_f32_16x16x32_f16 v[162:165], v[202:205], v[206:209], v[162:165]
	global_load_dwordx4 v[20:23], v[114:115], off offset:1280
	v_mfma_f32_16x16x32_f16 v[76:79], v[202:205], v[220:223], v[76:79]
	ds_read_b128 v[202:205], v131 offset:34816
	v_mfma_f32_16x16x32_f16 v[140:143], v[210:213], v[190:193], v[140:143]
	global_load_dwordx4 v[24:27], v[116:117], off offset:1280
	v_mfma_f32_16x16x32_f16 v[154:157], v[210:213], v[198:201], v[154:157]
	global_load_dwordx4 v[28:31], v[118:119], off offset:1280
	v_mfma_f32_16x16x32_f16 v[64:67], v[224:227], v[190:193], v[64:67]
	ds_read_b128 v[190:193], v128
	v_mfma_f32_16x16x32_f16 v[72:75], v[224:227], v[198:201], v[72:75]
	ds_read_b128 v[198:201], v128 offset:2048
	v_mfma_f32_16x16x32_f16 v[166:169], v[210:213], v[206:209], v[166:169]
	s_waitcnt vmcnt(15)
	ds_write_b128 v126, v[32:35] offset:16384
	v_mfma_f32_16x16x32_f16 v[84:87], v[210:213], v[220:223], v[84:87]
	ds_read_b128 v[210:213], v131 offset:36864
	v_mfma_f32_16x16x32_f16 v[80:83], v[224:227], v[206:209], v[80:83]
	ds_read_b128 v[206:209], v128 offset:4096
	v_mfma_f32_16x16x32_f16 v[88:91], v[224:227], v[220:223], v[88:91]
	ds_read_b128 v[220:223], v128 offset:6144
	s_waitcnt lgkmcnt(5)
	v_mfma_f32_16x16x32_f16 v[132:135], v[194:197], v[190:193], v[132:135]
	ds_read_b128 v[224:227], v131 offset:38912
	s_waitcnt lgkmcnt(5)
	v_mfma_f32_16x16x32_f16 v[92:95], v[194:197], v[198:201], v[92:95]
	s_waitcnt vmcnt(14)
	ds_write_b128 v124, v[36:39] offset:16384
	v_mfma_f32_16x16x32_f16 v[136:139], v[202:205], v[190:193], v[136:139]
	s_waitcnt vmcnt(13)
	ds_write_b128 v125, v[40:43] offset:16384
	v_mfma_f32_16x16x32_f16 v[144:147], v[202:205], v[198:201], v[144:147]
	s_waitcnt vmcnt(12)
	ds_write_b128 v127, v[44:47] offset:16384
	s_waitcnt lgkmcnt(5)
	v_mfma_f32_16x16x32_f16 v[158:161], v[194:197], v[206:209], v[158:161]
	s_waitcnt vmcnt(11)
	ds_write_b128 v126, v[48:51] offset:49152
	s_waitcnt lgkmcnt(5)
	v_mfma_f32_16x16x32_f16 v[68:71], v[194:197], v[220:223], v[68:71]
	ds_read_b128 v[194:197], v130 offset:32768
	v_mfma_f32_16x16x32_f16 v[162:165], v[202:205], v[206:209], v[162:165]
	s_waitcnt vmcnt(10)
	ds_write_b128 v124, v[52:55] offset:49152
	v_mfma_f32_16x16x32_f16 v[76:79], v[202:205], v[220:223], v[76:79]
	ds_read_b128 v[202:205], v130 offset:34816
	v_mfma_f32_16x16x32_f16 v[140:143], v[210:213], v[190:193], v[140:143]
	s_waitcnt vmcnt(9)
	ds_write_b128 v125, v[56:59] offset:49152
	v_mfma_f32_16x16x32_f16 v[154:157], v[210:213], v[198:201], v[154:157]
	s_waitcnt vmcnt(8)
	ds_write_b128 v127, v[60:63] offset:49152
	s_waitcnt lgkmcnt(9)
	v_mfma_f32_16x16x32_f16 v[64:67], v[224:227], v[190:193], v[64:67]
	ds_read_b128 v[190:193], v129
	v_mfma_f32_16x16x32_f16 v[72:75], v[224:227], v[198:201], v[72:75]
	ds_read_b128 v[198:201], v129 offset:2048
	v_mfma_f32_16x16x32_f16 v[166:169], v[210:213], v[206:209], v[166:169]
	v_mfma_f32_16x16x32_f16 v[84:87], v[210:213], v[220:223], v[84:87]
	ds_read_b128 v[210:213], v130 offset:36864
	v_mfma_f32_16x16x32_f16 v[80:83], v[224:227], v[206:209], v[80:83]
	ds_read_b128 v[206:209], v129 offset:4096
	v_mfma_f32_16x16x32_f16 v[88:91], v[224:227], v[220:223], v[88:91]
	ds_read_b128 v[220:223], v129 offset:6144
	ds_read_b128 v[224:227], v130 offset:38912
	s_waitcnt lgkmcnt(0)
	s_barrier
	v_mfma_f32_16x16x32_f16 v[132:135], v[194:197], v[190:193], v[132:135]
	global_load_dwordx4 v[32:35], v[104:105], off offset:1408
	v_mfma_f32_16x16x32_f16 v[92:95], v[194:197], v[198:201], v[92:95]
	global_load_dwordx4 v[36:39], v[106:107], off offset:1408
	v_mfma_f32_16x16x32_f16 v[136:139], v[202:205], v[190:193], v[136:139]
	global_load_dwordx4 v[40:43], v[108:109], off offset:1408
	v_mfma_f32_16x16x32_f16 v[144:147], v[202:205], v[198:201], v[144:147]
	global_load_dwordx4 v[44:47], v[110:111], off offset:1408
	v_mfma_f32_16x16x32_f16 v[158:161], v[194:197], v[206:209], v[158:161]
	global_load_dwordx4 v[48:51], v[112:113], off offset:1408
	v_mfma_f32_16x16x32_f16 v[68:71], v[194:197], v[220:223], v[68:71]
	ds_read_b128 v[194:197], v131 offset:49152
	v_mfma_f32_16x16x32_f16 v[162:165], v[202:205], v[206:209], v[162:165]
	global_load_dwordx4 v[52:55], v[114:115], off offset:1408
	v_mfma_f32_16x16x32_f16 v[76:79], v[202:205], v[220:223], v[76:79]
	ds_read_b128 v[202:205], v131 offset:51200
	v_mfma_f32_16x16x32_f16 v[140:143], v[210:213], v[190:193], v[140:143]
	global_load_dwordx4 v[56:59], v[116:117], off offset:1408
	v_mfma_f32_16x16x32_f16 v[154:157], v[210:213], v[198:201], v[154:157]
	global_load_dwordx4 v[60:63], v[118:119], off offset:1408
	v_mfma_f32_16x16x32_f16 v[64:67], v[224:227], v[190:193], v[64:67]
	ds_read_b128 v[190:193], v128 offset:16384
	v_mfma_f32_16x16x32_f16 v[72:75], v[224:227], v[198:201], v[72:75]
	ds_read_b128 v[198:201], v128 offset:18432
	v_mfma_f32_16x16x32_f16 v[166:169], v[210:213], v[206:209], v[166:169]
	s_waitcnt vmcnt(15)
; #define GL_LOAD(s_, kt_) if (VAR != 1) { a##s_##0 = GL_A(0, kt_); a##s_##1 = GL_A(1, kt_); a##s_##2 = GL_A(2, kt_); a##s_##3 = GL_A(3, kt_); b##s_##0 = GL_B(0, kt_); b##s_##1 = GL_B(1, kt_); b##s_##2 = GL_B(2, kt_); b##s_##3 = GL_B(3, kt_); }
; #define LDS_STORE(s_, buf_) if (VAR != 2) { LDS_ST1(sA, 0, buf_, a##s_##0) LDS_ST1(sA, 1, buf_, a##s_##1) LDS_ST1(sA, 2, buf_, a##s_##2) LDS_ST1(sA, 3, buf_, a##s_##3) LDS_ST1(sB, 0, buf_, b##s_##0) LDS_ST1(sB, 1, buf_, b##s_##1) LDS_ST1(sB, 2, buf_, b##s_##2) LDS_ST1(sB, 3, buf_, b##s_##3) }
;     ...
;   GL_LOAD(0, 0)
;   GL_LOAD(1, 1)
;   LDS_STORE(0, 0)
;   if (VAR != 4) __syncthreads();
; #pragma unroll
;   for (int kt = 0; kt < nk; kt += 2) {
;     if (kt + 2 < nk) { GL_LOAD(0, kt + 2) }
;     MMA_TILE(0)
;     LDS_STORE(1, 1)
;     if (VAR != 4) __syncthreads();
;     if (kt + 3 < nk) { GL_LOAD(1, kt + 3) }
;     MMA_TILE(1)
;     if (kt + 2 < nk) { LDS_STORE(0, 0) }
;     if (VAR != 4) __syncthreads();
	ds_write_b128 v126, v[0:3]
	v_mfma_f32_16x16x32_f16 v[84:87], v[210:213], v[220:223], v[84:87]
	ds_read_b128 v[210:213], v131 offset:53248
	v_mfma_f32_16x16x32_f16 v[80:83], v[224:227], v[206:209], v[80:83]
	ds_read_b128 v[206:209], v128 offset:20480
	v_mfma_f32_16x16x32_f16 v[88:91], v[224:227], v[220:223], v[88:91]
	ds_read_b128 v[220:223], v128 offset:22528
	s_waitcnt lgkmcnt(5)
	v_mfma_f32_16x16x32_f16 v[132:135], v[194:197], v[190:193], v[132:135]
	ds_read_b128 v[224:227], v131 offset:55296
	s_waitcnt lgkmcnt(5)
	v_mfma_f32_16x16x32_f16 v[92:95], v[194:197], v[198:201], v[92:95]
	s_waitcnt vmcnt(14)
	ds_write_b128 v124, v[4:7]
	v_mfma_f32_16x16x32_f16 v[136:139], v[202:205], v[190:193], v[136:139]
	s_waitcnt vmcnt(13)
	ds_write_b128 v125, v[8:11]
	v_mfma_f32_16x16x32_f16 v[144:147], v[202:205], v[198:201], v[144:147]
	s_waitcnt vmcnt(12)
	ds_write_b128 v127, v[12:15]
	s_waitcnt lgkmcnt(5)
	v_mfma_f32_16x16x32_f16 v[158:161], v[194:197], v[206:209], v[158:161]
	s_waitcnt vmcnt(11)
	ds_write_b128 v126, v[16:19] offset:32768
	s_waitcnt lgkmcnt(5)
	v_mfma_f32_16x16x32_f16 v[68:71], v[194:197], v[220:223], v[68:71]
	ds_read_b128 v[194:197], v130 offset:49152
	v_mfma_f32_16x16x32_f16 v[162:165], v[202:205], v[206:209], v[162:165]
	s_waitcnt vmcnt(10)
	ds_write_b128 v124, v[20:23] offset:32768
	v_mfma_f32_16x16x32_f16 v[76:79], v[202:205], v[220:223], v[76:79]
	ds_read_b128 v[202:205], v130 offset:51200
	v_mfma_f32_16x16x32_f16 v[140:143], v[210:213], v[190:193], v[140:143]
	s_waitcnt vmcnt(9)
	ds_write_b128 v125, v[24:27] offset:32768
	v_mfma_f32_16x16x32_f16 v[154:157], v[210:213], v[198:201], v[154:157]
	s_waitcnt vmcnt(8)
	ds_write_b128 v127, v[28:31] offset:32768
	s_waitcnt lgkmcnt(9)
	v_mfma_f32_16x16x32_f16 v[64:67], v[224:227], v[190:193], v[64:67]
	ds_read_b128 v[190:193], v129 offset:16384
	v_mfma_f32_16x16x32_f16 v[72:75], v[224:227], v[198:201], v[72:75]
	ds_read_b128 v[198:201], v129 offset:18432
	v_mfma_f32_16x16x32_f16 v[166:169], v[210:213], v[206:209], v[166:169]
	v_mfma_f32_16x16x32_f16 v[84:87], v[210:213], v[220:223], v[84:87]
	ds_read_b128 v[210:213], v130 offset:53248
	v_mfma_f32_16x16x32_f16 v[80:83], v[224:227], v[206:209], v[80:83]
	ds_read_b128 v[206:209], v129 offset:20480
	v_mfma_f32_16x16x32_f16 v[88:91], v[224:227], v[220:223], v[88:91]
	ds_read_b128 v[220:223], v129 offset:22528
	s_waitcnt lgkmcnt(4)
	v_mfma_f32_16x16x32_f16 v[132:135], v[194:197], v[190:193], v[132:135]
	ds_read_b128 v[224:227], v130 offset:55296
	s_waitcnt lgkmcnt(0)
	s_barrier
	v_mfma_f32_16x16x32_f16 v[136:139], v[202:205], v[190:193], v[136:139]
	ds_read_b128 v[0:3], v128
	v_mfma_f32_16x16x32_f16 v[144:147], v[202:205], v[198:201], v[144:147]
	ds_read_b128 v[4:7], v131 offset:32768
	v_mfma_f32_16x16x32_f16 v[140:143], v[210:213], v[190:193], v[140:143]
	ds_read_b128 v[8:11], v128 offset:2048
	v_mfma_f32_16x16x32_f16 v[154:157], v[210:213], v[198:201], v[154:157]
	ds_read_b128 v[12:15], v131 offset:34816
	v_mfma_f32_16x16x32_f16 v[162:165], v[202:205], v[206:209], v[162:165]
	ds_read_b128 v[16:19], v128 offset:4096
	v_mfma_f32_16x16x32_f16 v[202:205], v[202:205], v[220:223], v[76:79]
	ds_read_b128 v[20:23], v131 offset:36864
	v_mfma_f32_16x16x32_f16 v[166:169], v[210:213], v[206:209], v[166:169]
	ds_read_b128 v[24:27], v128 offset:6144
	v_mfma_f32_16x16x32_f16 v[210:213], v[210:213], v[220:223], v[84:87]
	ds_read_b128 v[28:31], v131 offset:38912
	v_mfma_f32_16x16x32_f16 v[190:193], v[224:227], v[190:193], v[64:67]
	s_nop 2
	global_load_dwordx4 v[64:67], v[104:105], off offset:1536
	v_mfma_f32_16x16x32_f16 v[228:231], v[194:197], v[198:201], v[92:95]
	v_mfma_f32_16x16x32_f16 v[198:201], v[224:227], v[198:201], v[72:75]
	s_waitcnt vmcnt(8)
	ds_write_b128 v126, v[32:35] offset:16384
	s_waitcnt vmcnt(7)
	ds_write_b128 v124, v[36:39] offset:16384
	v_mfma_f32_16x16x32_f16 v[158:161], v[194:197], v[206:209], v[158:161]
	v_mfma_f32_16x16x32_f16 v[206:209], v[224:227], v[206:209], v[80:83]
	s_waitcnt vmcnt(6)
	ds_write_b128 v125, v[40:43] offset:16384
	v_mfma_f32_16x16x32_f16 v[194:197], v[194:197], v[220:223], v[68:71]
	v_mfma_f32_16x16x32_f16 v[220:223], v[224:227], v[220:223], v[88:91]
	ds_read_b128 v[224:227], v130 offset:38912
	s_nop 0
	global_load_dwordx4 v[68:71], v[106:107], off offset:1536
	global_load_dwordx4 v[72:75], v[108:109], off offset:1536
	global_load_dwordx4 v[76:79], v[110:111], off offset:1536
	s_waitcnt lgkmcnt(10)
	v_mfma_f32_16x16x32_f16 v[132:135], v[4:7], v[0:3], v[132:135]
	global_load_dwordx4 v[80:83], v[112:113], off offset:1536
	s_waitcnt lgkmcnt(8)
	v_mfma_f32_16x16x32_f16 v[136:139], v[12:15], v[0:3], v[136:139]
	s_waitcnt lgkmcnt(6)
	v_mfma_f32_16x16x32_f16 v[140:143], v[20:23], v[0:3], v[140:143]
	s_waitcnt lgkmcnt(4)
	v_mfma_f32_16x16x32_f16 v[0:3], v[28:31], v[0:3], v[190:193]
	v_mfma_f32_16x16x32_f16 v[190:193], v[4:7], v[8:11], v[228:231]
	global_load_dwordx4 v[84:87], v[114:115], off offset:1536
	global_load_dwordx4 v[88:91], v[116:117], off offset:1536
	global_load_dwordx4 v[92:95], v[118:119], off offset:1536
	v_mfma_f32_16x16x32_f16 v[144:147], v[12:15], v[8:11], v[144:147]
	s_waitcnt vmcnt(12)
	ds_write_b128 v127, v[44:47] offset:16384
	v_mfma_f32_16x16x32_f16 v[158:161], v[4:7], v[16:19], v[158:161]
	s_waitcnt vmcnt(11)
	ds_write_b128 v126, v[48:51] offset:49152
	v_mfma_f32_16x16x32_f16 v[4:7], v[4:7], v[24:27], v[194:197]
	s_nop 2
	ds_read_b128 v[194:197], v130 offset:32768
	v_mfma_f32_16x16x32_f16 v[162:165], v[12:15], v[16:19], v[162:165]
	s_waitcnt vmcnt(10)
	ds_write_b128 v124, v[52:55] offset:49152
	v_mfma_f32_16x16x32_f16 v[12:15], v[12:15], v[24:27], v[202:205]
	s_nop 2
	ds_read_b128 v[202:205], v130 offset:34816
	s_waitcnt vmcnt(9)
	ds_write_b128 v125, v[56:59] offset:49152
	v_mfma_f32_16x16x32_f16 v[154:157], v[20:23], v[8:11], v[154:157]
	s_waitcnt vmcnt(8)
	ds_write_b128 v127, v[60:63] offset:49152
	v_mfma_f32_16x16x32_f16 v[8:11], v[28:31], v[8:11], v[198:201]
	s_nop 2
	ds_read_b128 v[198:201], v129 offset:2048
	v_mfma_f32_16x16x32_f16 v[166:169], v[20:23], v[16:19], v[166:169]
	v_mfma_f32_16x16x32_f16 v[20:23], v[20:23], v[24:27], v[210:213]
	s_nop 2
	ds_read_b128 v[210:213], v130 offset:36864
	v_mfma_f32_16x16x32_f16 v[16:19], v[28:31], v[16:19], v[206:209]
	s_nop 2
	ds_read_b128 v[206:209], v129 offset:4096
	v_mfma_f32_16x16x32_f16 v[24:27], v[28:31], v[24:27], v[220:223]
	ds_read_b128 v[28:31], v129
	s_waitcnt lgkmcnt(0)
	v_mfma_f32_16x16x32_f16 v[132:135], v[194:197], v[28:31], v[132:135]
	ds_read_b128 v[220:223], v129 offset:6144
	s_waitcnt lgkmcnt(0)
	s_barrier
; #define GL_LOAD(s_, kt_) if (VAR != 1) { a##s_##0 = GL_A(0, kt_); a##s_##1 = GL_A(1, kt_); a##s_##2 = GL_A(2, kt_); a##s_##3 = GL_A(3, kt_); b##s_##0 = GL_B(0, kt_); b##s_##1 = GL_B(1, kt_); b##s_##2 = GL_B(2, kt_); b##s_##3 = GL_B(3, kt_); }
; #define LDS_STORE(s_, buf_) if (VAR != 2) { LDS_ST1(sA, 0, buf_, a##s_##0) LDS_ST1(sA, 1, buf_, a##s_##1) LDS_ST1(sA, 2, buf_, a##s_##2) LDS_ST1(sA, 3, buf_, a##s_##3) LDS_ST1(sB, 0, buf_, b##s_##0) LDS_ST1(sB, 1, buf_, b##s_##1) LDS_ST1(sB, 2, buf_, b##s_##2) LDS_ST1(sB, 3, buf_, b##s_##3) }
;     ...
;   GL_LOAD(0, 0)
;   GL_LOAD(1, 1)
;   LDS_STORE(0, 0)
;   if (VAR != 4) __syncthreads();
; #pragma unroll
;   for (int kt = 0; kt < nk; kt += 2) {
;     if (kt + 2 < nk) { GL_LOAD(0, kt + 2) }
;     MMA_TILE(0)
;     LDS_STORE(1, 1)
;     if (VAR != 4) __syncthreads();
;     if (kt + 3 < nk) { GL_LOAD(1, kt + 3) }
;     MMA_TILE(1)
;     if (kt + 2 < nk) { LDS_STORE(0, 0) }
;     if (VAR != 4) __syncthreads();
	v_mfma_f32_16x16x32_f16 v[136:139], v[202:205], v[28:31], v[136:139]
	ds_read_b128 v[32:35], v128 offset:16384
	v_mfma_f32_16x16x32_f16 v[144:147], v[202:205], v[198:201], v[144:147]
	ds_read_b128 v[36:39], v131 offset:49152
	v_mfma_f32_16x16x32_f16 v[140:143], v[210:213], v[28:31], v[140:143]
	ds_read_b128 v[40:43], v128 offset:18432
	v_mfma_f32_16x16x32_f16 v[154:157], v[210:213], v[198:201], v[154:157]
	ds_read_b128 v[44:47], v131 offset:51200
	v_mfma_f32_16x16x32_f16 v[162:165], v[202:205], v[206:209], v[162:165]
	ds_read_b128 v[48:51], v128 offset:20480
	v_mfma_f32_16x16x32_f16 v[202:205], v[202:205], v[220:223], v[12:15]
	ds_read_b128 v[52:55], v131 offset:53248
	v_mfma_f32_16x16x32_f16 v[166:169], v[210:213], v[206:209], v[166:169]
	ds_read_b128 v[56:59], v128 offset:22528
	v_mfma_f32_16x16x32_f16 v[210:213], v[210:213], v[220:223], v[20:23]
	ds_read_b128 v[60:63], v131 offset:55296
	v_mfma_f32_16x16x32_f16 v[228:231], v[224:227], v[28:31], v[0:3]
	global_load_dwordx4 v[28:31], v[104:105], off offset:1664
	v_mfma_f32_16x16x32_f16 v[190:193], v[194:197], v[198:201], v[190:193]
	v_mfma_f32_16x16x32_f16 v[198:201], v[224:227], v[198:201], v[8:11]
	s_waitcnt vmcnt(8)
	ds_write_b128 v126, v[64:67]
	s_waitcnt vmcnt(7)
	ds_write_b128 v124, v[68:71]
	v_mfma_f32_16x16x32_f16 v[158:161], v[194:197], v[206:209], v[158:161]
	v_mfma_f32_16x16x32_f16 v[206:209], v[224:227], v[206:209], v[16:19]
	s_waitcnt vmcnt(6)
	ds_write_b128 v125, v[72:75]
	v_mfma_f32_16x16x32_f16 v[194:197], v[194:197], v[220:223], v[4:7]
	v_mfma_f32_16x16x32_f16 v[220:223], v[224:227], v[220:223], v[24:27]
	ds_read_b128 v[224:227], v130 offset:55296
	s_nop 1
	global_load_dwordx4 v[24:27], v[106:107], off offset:1664
	global_load_dwordx4 v[12:15], v[108:109], off offset:1664
	global_load_dwordx4 v[16:19], v[110:111], off offset:1664
	s_waitcnt lgkmcnt(10)
	v_mfma_f32_16x16x32_f16 v[132:135], v[36:39], v[32:35], v[132:135]
	global_load_dwordx4 v[20:23], v[112:113], off offset:1664
	s_waitcnt lgkmcnt(9)
	v_mfma_f32_16x16x32_f16 v[190:193], v[36:39], v[40:43], v[190:193]
	global_load_dwordx4 v[0:3], v[114:115], off offset:1664
	s_waitcnt lgkmcnt(8)
	v_mfma_f32_16x16x32_f16 v[136:139], v[44:47], v[32:35], v[136:139]
	global_load_dwordx4 v[4:7], v[116:117], off offset:1664
	v_mfma_f32_16x16x32_f16 v[144:147], v[44:47], v[40:43], v[144:147]
	global_load_dwordx4 v[8:11], v[118:119], off offset:1664
	s_waitcnt lgkmcnt(7)
	v_mfma_f32_16x16x32_f16 v[158:161], v[36:39], v[48:51], v[158:161]
	s_waitcnt vmcnt(12)
	ds_write_b128 v127, v[76:79]
	s_waitcnt lgkmcnt(6)
	v_mfma_f32_16x16x32_f16 v[36:39], v[36:39], v[56:59], v[194:197]
	s_nop 2
	ds_read_b128 v[194:197], v130 offset:49152
	v_mfma_f32_16x16x32_f16 v[162:165], v[44:47], v[48:51], v[162:165]
	s_waitcnt vmcnt(11)
	ds_write_b128 v126, v[80:83] offset:32768
	v_mfma_f32_16x16x32_f16 v[44:47], v[44:47], v[56:59], v[202:205]
	s_nop 2
	ds_read_b128 v[202:205], v130 offset:51200
	v_mfma_f32_16x16x32_f16 v[140:143], v[52:55], v[32:35], v[140:143]
	s_waitcnt vmcnt(10)
	ds_write_b128 v124, v[84:87] offset:32768
	v_mfma_f32_16x16x32_f16 v[154:157], v[52:55], v[40:43], v[154:157]
	s_waitcnt vmcnt(9)
	ds_write_b128 v125, v[88:91] offset:32768
	s_waitcnt lgkmcnt(10)
	v_mfma_f32_16x16x32_f16 v[32:35], v[60:63], v[32:35], v[228:231]
	s_waitcnt vmcnt(8)
	ds_write_b128 v127, v[92:95] offset:32768
	v_mfma_f32_16x16x32_f16 v[40:43], v[60:63], v[40:43], v[198:201]
	s_nop 2
	ds_read_b128 v[198:201], v129 offset:18432
	v_mfma_f32_16x16x32_f16 v[166:169], v[52:55], v[48:51], v[166:169]
	v_mfma_f32_16x16x32_f16 v[52:55], v[52:55], v[56:59], v[210:213]
	s_nop 2
	ds_read_b128 v[210:213], v130 offset:53248
	v_mfma_f32_16x16x32_f16 v[48:51], v[60:63], v[48:51], v[206:209]
	s_nop 2
	ds_read_b128 v[206:209], v129 offset:20480
	v_mfma_f32_16x16x32_f16 v[56:59], v[60:63], v[56:59], v[220:223]
	ds_read_b128 v[60:63], v129 offset:16384
	s_waitcnt lgkmcnt(0)
	v_mfma_f32_16x16x32_f16 v[132:135], v[194:197], v[60:63], v[132:135]
	ds_read_b128 v[220:223], v129 offset:22528
	s_waitcnt lgkmcnt(0)
	s_barrier
	v_mfma_f32_16x16x32_f16 v[136:139], v[202:205], v[60:63], v[136:139]
	ds_read_b128 v[64:67], v128
	v_mfma_f32_16x16x32_f16 v[144:147], v[202:205], v[198:201], v[144:147]
	ds_read_b128 v[68:71], v131 offset:32768
	v_mfma_f32_16x16x32_f16 v[140:143], v[210:213], v[60:63], v[140:143]
	ds_read_b128 v[72:75], v128 offset:2048
	v_mfma_f32_16x16x32_f16 v[154:157], v[210:213], v[198:201], v[154:157]
	ds_read_b128 v[76:79], v131 offset:34816
	v_mfma_f32_16x16x32_f16 v[162:165], v[202:205], v[206:209], v[162:165]
	ds_read_b128 v[80:83], v128 offset:4096
	v_mfma_f32_16x16x32_f16 v[202:205], v[202:205], v[220:223], v[44:47]
	ds_read_b128 v[84:87], v131 offset:36864
	v_mfma_f32_16x16x32_f16 v[166:169], v[210:213], v[206:209], v[166:169]
	ds_read_b128 v[88:91], v128 offset:6144
	v_mfma_f32_16x16x32_f16 v[210:213], v[210:213], v[220:223], v[52:55]
	ds_read_b128 v[92:95], v131 offset:38912
	v_mfma_f32_16x16x32_f16 v[228:231], v[224:227], v[60:63], v[32:35]
	s_nop 0
	global_load_dwordx4 v[52:55], v[104:105], off offset:1792
	v_mfma_f32_16x16x32_f16 v[190:193], v[194:197], v[198:201], v[190:193]
	v_mfma_f32_16x16x32_f16 v[198:201], v[224:227], v[198:201], v[40:43]
	s_waitcnt vmcnt(8)
	ds_write_b128 v126, v[28:31] offset:16384
	s_waitcnt vmcnt(7)
	ds_write_b128 v124, v[24:27] offset:16384
	s_waitcnt vmcnt(6)
	ds_write_b128 v125, v[12:15] offset:16384
	v_mfma_f32_16x16x32_f16 v[158:161], v[194:197], v[206:209], v[158:161]
	v_mfma_f32_16x16x32_f16 v[206:209], v[224:227], v[206:209], v[48:51]
	s_waitcnt vmcnt(5)
; #define GL_LOAD(s_, kt_) if (VAR != 1) { a##s_##0 = GL_A(0, kt_); a##s_##1 = GL_A(1, kt_); a##s_##2 = GL_A(2, kt_); a##s_##3 = GL_A(3, kt_); b##s_##0 = GL_B(0, kt_); b##s_##1 = GL_B(1, kt_); b##s_##2 = GL_B(2, kt_); b##s_##3 = GL_B(3, kt_); }
; #define LDS_STORE(s_, buf_) if (VAR != 2) { LDS_ST1(sA, 0, buf_, a##s_##0) LDS_ST1(sA, 1, buf_, a##s_##1) LDS_ST1(sA, 2, buf_, a##s_##2) LDS_ST1(sA, 3, buf_, a##s_##3) LDS_ST1(sB, 0, buf_, b##s_##0) LDS_ST1(sB, 1, buf_, b##s_##1) LDS_ST1(sB, 2, buf_, b##s_##2) LDS_ST1(sB, 3, buf_, b##s_##3) }
;     ...
;   GL_LOAD(0, 0)
;   GL_LOAD(1, 1)
;   LDS_STORE(0, 0)
;   if (VAR != 4) __syncthreads();
; #pragma unroll
;   for (int kt = 0; kt < nk; kt += 2) {
;     if (kt + 2 < nk) { GL_LOAD(0, kt + 2) }
;     MMA_TILE(0)
;     LDS_STORE(1, 1)
;     if (VAR != 4) __syncthreads();
;     if (kt + 3 < nk) { GL_LOAD(1, kt + 3) }
;     MMA_TILE(1)
;     if (kt + 2 < nk) { LDS_STORE(0, 0) }
;     if (VAR != 4) __syncthreads();
	ds_write_b128 v127, v[16:19] offset:16384
	v_mfma_f32_16x16x32_f16 v[194:197], v[194:197], v[220:223], v[36:39]
	v_mfma_f32_16x16x32_f16 v[220:223], v[224:227], v[220:223], v[56:59]
	ds_read_b128 v[224:227], v130 offset:38912
	s_nop 1
	global_load_dwordx4 v[56:59], v[106:107], off offset:1792
	global_load_dwordx4 v[60:63], v[108:109], off offset:1792
	global_load_dwordx4 v[40:43], v[110:111], off offset:1792
	s_waitcnt lgkmcnt(11)
	v_mfma_f32_16x16x32_f16 v[132:135], v[68:71], v[64:67], v[132:135]
	global_load_dwordx4 v[44:47], v[112:113], off offset:1792
	s_waitcnt lgkmcnt(10)
	v_mfma_f32_16x16x32_f16 v[190:193], v[68:71], v[72:75], v[190:193]
	global_load_dwordx4 v[48:51], v[114:115], off offset:1792
	s_waitcnt lgkmcnt(9)
	v_mfma_f32_16x16x32_f16 v[136:139], v[76:79], v[64:67], v[136:139]
	global_load_dwordx4 v[32:35], v[116:117], off offset:1792
	v_mfma_f32_16x16x32_f16 v[144:147], v[76:79], v[72:75], v[144:147]
	global_load_dwordx4 v[36:39], v[118:119], off offset:1792
	s_waitcnt lgkmcnt(8)
	v_mfma_f32_16x16x32_f16 v[158:161], v[68:71], v[80:83], v[158:161]
	s_waitcnt vmcnt(11)
	ds_write_b128 v126, v[20:23] offset:49152
	s_waitcnt lgkmcnt(7)
	v_mfma_f32_16x16x32_f16 v[68:71], v[68:71], v[88:91], v[194:197]
	s_nop 2
	ds_read_b128 v[194:197], v130 offset:32768
	v_mfma_f32_16x16x32_f16 v[162:165], v[76:79], v[80:83], v[162:165]
	s_waitcnt vmcnt(10)
	ds_write_b128 v124, v[0:3] offset:49152
	v_mfma_f32_16x16x32_f16 v[76:79], v[76:79], v[88:91], v[202:205]
	s_nop 2
	ds_read_b128 v[202:205], v130 offset:34816
	v_mfma_f32_16x16x32_f16 v[140:143], v[84:87], v[64:67], v[140:143]
	s_waitcnt vmcnt(9)
	ds_write_b128 v125, v[4:7] offset:49152
	v_mfma_f32_16x16x32_f16 v[154:157], v[84:87], v[72:75], v[154:157]
	s_waitcnt vmcnt(8)
	ds_write_b128 v127, v[8:11] offset:49152
	s_waitcnt lgkmcnt(11)
	v_mfma_f32_16x16x32_f16 v[64:67], v[92:95], v[64:67], v[228:231]
	v_mfma_f32_16x16x32_f16 v[72:75], v[92:95], v[72:75], v[198:201]
	s_nop 2
	ds_read_b128 v[198:201], v129 offset:2048
	v_mfma_f32_16x16x32_f16 v[166:169], v[84:87], v[80:83], v[166:169]
	v_mfma_f32_16x16x32_f16 v[84:87], v[84:87], v[88:91], v[210:213]
	s_nop 2
	ds_read_b128 v[210:213], v130 offset:36864
	v_mfma_f32_16x16x32_f16 v[80:83], v[92:95], v[80:83], v[206:209]
	s_nop 2
	ds_read_b128 v[206:209], v129 offset:4096
	v_mfma_f32_16x16x32_f16 v[88:91], v[92:95], v[88:91], v[220:223]
	ds_read_b128 v[92:95], v129
	s_nop 1
	ds_read_b128 v[220:223], v129 offset:6144
	s_waitcnt lgkmcnt(0)
	s_barrier
	v_mfma_f32_16x16x32_f16 v[132:135], v[194:197], v[92:95], v[132:135]
	global_load_dwordx4 v[24:27], v[104:105], off offset:1920
	v_mfma_f32_16x16x32_f16 v[136:139], v[202:205], v[92:95], v[136:139]
	v_mfma_f32_16x16x32_f16 v[140:143], v[210:213], v[92:95], v[140:143]
	v_mfma_f32_16x16x32_f16 v[64:67], v[224:227], v[92:95], v[64:67]
	v_mfma_f32_16x16x32_f16 v[92:95], v[194:197], v[198:201], v[190:193]
	s_nop 2
	ds_read_b128 v[190:193], v128 offset:20480
	global_load_dwordx4 v[28:31], v[106:107], off offset:1920
	ds_read_b128 v[104:107], v128 offset:16384
	v_mfma_f32_16x16x32_f16 v[144:147], v[202:205], v[198:201], v[144:147]
	global_load_dwordx4 v[12:15], v[108:109], off offset:1920
	v_mfma_f32_16x16x32_f16 v[158:161], v[194:197], v[206:209], v[158:161]
	global_load_dwordx4 v[16:19], v[110:111], off offset:1920
	v_mfma_f32_16x16x32_f16 v[68:71], v[194:197], v[220:223], v[68:71]
	ds_read_b128 v[108:111], v131 offset:49152
	v_mfma_f32_16x16x32_f16 v[162:165], v[202:205], v[206:209], v[162:165]
	ds_read_b128 v[194:197], v131 offset:53248
	v_mfma_f32_16x16x32_f16 v[76:79], v[202:205], v[220:223], v[76:79]
	ds_read_b128 v[202:205], v131 offset:55296
	global_load_dwordx4 v[20:23], v[112:113], off offset:1920
	v_mfma_f32_16x16x32_f16 v[154:157], v[210:213], v[198:201], v[154:157]
	global_load_dwordx4 v[0:3], v[114:115], off offset:1920
	ds_read_b128 v[112:115], v128 offset:18432
	v_mfma_f32_16x16x32_f16 v[72:75], v[224:227], v[198:201], v[72:75]
	ds_read_b128 v[198:201], v128 offset:22528
	v_mfma_f32_16x16x32_f16 v[166:169], v[210:213], v[206:209], v[166:169]
	global_load_dwordx4 v[4:7], v[116:117], off offset:1920
	v_mfma_f32_16x16x32_f16 v[84:87], v[210:213], v[220:223], v[84:87]
	global_load_dwordx4 v[8:11], v[118:119], off offset:1920
	v_mfma_f32_16x16x32_f16 v[80:83], v[224:227], v[206:209], v[80:83]
	ds_read_b128 v[116:119], v131 offset:51200
	v_mfma_f32_16x16x32_f16 v[88:91], v[224:227], v[220:223], v[88:91]
	s_waitcnt vmcnt(15)
	ds_write_b128 v126, v[52:55]
	s_waitcnt lgkmcnt(6)
	v_mfma_f32_16x16x32_f16 v[132:135], v[108:111], v[104:107], v[132:135]
	s_waitcnt vmcnt(14)
	ds_write_b128 v124, v[56:59]
	s_waitcnt lgkmcnt(4)
	v_mfma_f32_16x16x32_f16 v[92:95], v[108:111], v[112:115], v[92:95]
	s_waitcnt vmcnt(13)
	ds_write_b128 v125, v[60:63]
	s_waitcnt lgkmcnt(3)
	v_mfma_f32_16x16x32_f16 v[136:139], v[116:119], v[104:107], v[136:139]
	s_waitcnt vmcnt(12)
	ds_write_b128 v127, v[40:43]
	v_mfma_f32_16x16x32_f16 v[140:143], v[194:197], v[104:107], v[140:143]
	v_mfma_f32_16x16x32_f16 v[64:67], v[202:205], v[104:107], v[64:67]
	v_mfma_f32_16x16x32_f16 v[104:107], v[116:119], v[112:115], v[144:147]
	s_waitcnt vmcnt(11)
	ds_write_b128 v126, v[44:47] offset:32768
	v_mfma_f32_16x16x32_f16 v[144:147], v[194:197], v[112:115], v[154:157]
	v_mfma_f32_16x16x32_f16 v[72:75], v[202:205], v[112:115], v[72:75]
	v_mfma_f32_16x16x32_f16 v[112:115], v[108:111], v[190:193], v[158:161]
	s_waitcnt vmcnt(10)
	ds_write_b128 v124, v[48:51] offset:32768
	s_waitcnt vmcnt(9)
	ds_write_b128 v125, v[32:35] offset:32768
	v_mfma_f32_16x16x32_f16 v[68:71], v[108:111], v[198:201], v[68:71]
	ds_read_b128 v[108:111], v129 offset:16384
	v_mfma_f32_16x16x32_f16 v[154:157], v[116:119], v[190:193], v[162:165]
	s_nop 2
	ds_read_b128 v[162:165], v129 offset:18432
	v_mfma_f32_16x16x32_f16 v[76:79], v[116:119], v[198:201], v[76:79]
	ds_read_b128 v[116:119], v130 offset:49152
	s_waitcnt vmcnt(8)
	ds_write_b128 v127, v[36:39] offset:32768
	v_mfma_f32_16x16x32_f16 v[158:161], v[194:197], v[190:193], v[166:169]
	s_nop 2
	ds_read_b128 v[166:169], v130 offset:51200
	v_mfma_f32_16x16x32_f16 v[84:87], v[194:197], v[198:201], v[84:87]
	ds_read_b128 v[194:197], v130 offset:53248
	v_mfma_f32_16x16x32_f16 v[80:83], v[202:205], v[190:193], v[80:83]
	ds_read_b128 v[190:193], v129 offset:20480
	v_mfma_f32_16x16x32_f16 v[88:91], v[202:205], v[198:201], v[88:91]
	ds_read_b128 v[198:201], v129 offset:22528
	s_waitcnt lgkmcnt(5)
	v_mfma_f32_16x16x32_f16 v[132:135], v[116:119], v[108:111], v[132:135]
	ds_read_b128 v[202:205], v130 offset:55296
	s_waitcnt lgkmcnt(0)
	s_barrier
; #define GL_LOAD(s_, kt_) if (VAR != 1) { a##s_##0 = GL_A(0, kt_); a##s_##1 = GL_A(1, kt_); a##s_##2 = GL_A(2, kt_); a##s_##3 = GL_A(3, kt_); b##s_##0 = GL_B(0, kt_); b##s_##1 = GL_B(1, kt_); b##s_##2 = GL_B(2, kt_); b##s_##3 = GL_B(3, kt_); }
; #define LDS_STORE(s_, buf_) if (VAR != 2) { LDS_ST1(sA, 0, buf_, a##s_##0) LDS_ST1(sA, 1, buf_, a##s_##1) LDS_ST1(sA, 2, buf_, a##s_##2) LDS_ST1(sA, 3, buf_, a##s_##3) LDS_ST1(sB, 0, buf_, b##s_##0) LDS_ST1(sB, 1, buf_, b##s_##1) LDS_ST1(sB, 2, buf_, b##s_##2) LDS_ST1(sB, 3, buf_, b##s_##3) }
;     ...
;   for (int kt = 0; kt < nk; kt += 2) {
;     if (kt + 2 < nk) { GL_LOAD(0, kt + 2) }
;     MMA_TILE(0)
;     LDS_STORE(1, 1)
;     if (VAR != 4) __syncthreads();
;     if (kt + 3 < nk) { GL_LOAD(1, kt + 3) }
;     MMA_TILE(1)
;     if (kt + 2 < nk) { LDS_STORE(0, 0) }
;     if (VAR != 4) __syncthreads();
;   }
	ds_read_b128 v[32:35], v128
	ds_read_b128 v[36:39], v131 offset:32768
	ds_read_b128 v[40:43], v128 offset:2048
	ds_read_b128 v[44:47], v131 offset:34816
	ds_read_b128 v[48:51], v128 offset:4096
	ds_read_b128 v[52:55], v131 offset:36864
	ds_read_b128 v[56:59], v128 offset:6144
	ds_read_b128 v[60:63], v131 offset:38912
	v_mfma_f32_16x16x32_f16 v[136:139], v[166:169], v[108:111], v[136:139]
	v_mfma_f32_16x16x32_f16 v[140:143], v[194:197], v[108:111], v[140:143]
	v_mfma_f32_16x16x32_f16 v[64:67], v[202:205], v[108:111], v[64:67]
	v_mfma_f32_16x16x32_f16 v[92:95], v[116:119], v[162:165], v[92:95]
	v_mfma_f32_16x16x32_f16 v[104:107], v[166:169], v[162:165], v[104:107]
	v_mfma_f32_16x16x32_f16 v[108:111], v[194:197], v[162:165], v[144:147]
	v_mfma_f32_16x16x32_f16 v[72:75], v[202:205], v[162:165], v[72:75]
	v_mfma_f32_16x16x32_f16 v[112:115], v[116:119], v[190:193], v[112:115]
	v_mfma_f32_16x16x32_f16 v[144:147], v[166:169], v[190:193], v[154:157]
	v_mfma_f32_16x16x32_f16 v[154:157], v[194:197], v[190:193], v[158:161]
	v_mfma_f32_16x16x32_f16 v[80:83], v[202:205], v[190:193], v[80:83]
	v_mfma_f32_16x16x32_f16 v[68:71], v[116:119], v[198:201], v[68:71]
	v_mfma_f32_16x16x32_f16 v[76:79], v[166:169], v[198:201], v[76:79]
	v_mfma_f32_16x16x32_f16 v[84:87], v[194:197], v[198:201], v[84:87]
	v_mfma_f32_16x16x32_f16 v[88:91], v[202:205], v[198:201], v[88:91]
	s_waitcnt lgkmcnt(6)
	v_mfma_f32_16x16x32_f16 v[116:119], v[36:39], v[32:35], v[132:135]
	s_waitcnt lgkmcnt(4)
	v_mfma_f32_16x16x32_f16 v[132:135], v[44:47], v[32:35], v[136:139]
	s_waitcnt lgkmcnt(2)
	v_mfma_f32_16x16x32_f16 v[136:139], v[52:55], v[32:35], v[140:143]
	s_waitcnt lgkmcnt(0)
	v_mfma_f32_16x16x32_f16 v[32:35], v[60:63], v[32:35], v[64:67]
	v_mfma_f32_16x16x32_f16 v[64:67], v[36:39], v[40:43], v[92:95]
	v_mfma_f32_16x16x32_f16 v[92:95], v[44:47], v[40:43], v[104:107]
	v_mfma_f32_16x16x32_f16 v[104:107], v[52:55], v[40:43], v[108:111]
	v_mfma_f32_16x16x32_f16 v[40:43], v[60:63], v[40:43], v[72:75]
	v_mfma_f32_16x16x32_f16 v[72:75], v[36:39], v[48:51], v[112:115]
	v_mfma_f32_16x16x32_f16 v[108:111], v[44:47], v[48:51], v[144:147]
	v_mfma_f32_16x16x32_f16 v[112:115], v[52:55], v[48:51], v[154:157]
	v_mfma_f32_16x16x32_f16 v[48:51], v[60:63], v[48:51], v[80:83]
	v_mfma_f32_16x16x32_f16 v[36:39], v[36:39], v[56:59], v[68:71]
	v_mfma_f32_16x16x32_f16 v[44:47], v[44:47], v[56:59], v[76:79]
	v_mfma_f32_16x16x32_f16 v[52:55], v[52:55], v[56:59], v[84:87]
	v_mfma_f32_16x16x32_f16 v[56:59], v[60:63], v[56:59], v[88:91]
	ds_read_b128 v[60:63], v129
	ds_read_b128 v[68:71], v130 offset:32768
	ds_read_b128 v[76:79], v129 offset:2048
	ds_read_b128 v[80:83], v130 offset:34816
	ds_read_b128 v[84:87], v129 offset:4096
	ds_read_b128 v[88:91], v130 offset:36864
	ds_read_b128 v[140:143], v129 offset:6144
	ds_read_b128 v[144:147], v130 offset:38912
	s_waitcnt vmcnt(7)
	ds_write_b128 v126, v[24:27] offset:16384
	s_waitcnt vmcnt(6)
	ds_write_b128 v124, v[28:31] offset:16384
	s_waitcnt vmcnt(5)
	ds_write_b128 v125, v[12:15] offset:16384
	s_waitcnt vmcnt(4)
	ds_write_b128 v127, v[16:19] offset:16384
	s_waitcnt vmcnt(3)
	ds_write_b128 v126, v[20:23] offset:49152
	s_waitcnt vmcnt(2)
	ds_write_b128 v124, v[0:3] offset:49152
	s_waitcnt vmcnt(1)
	ds_write_b128 v125, v[4:7] offset:49152
	s_waitcnt vmcnt(0)
	ds_write_b128 v127, v[8:11] offset:49152
	s_waitcnt lgkmcnt(0)
	v_mfma_f32_16x16x32_f16 v[116:119], v[68:71], v[60:63], v[116:119]
	s_barrier
	ds_read_b128 v[0:3], v128 offset:16384
	ds_read_b128 v[4:7], v131 offset:49152
	ds_read_b128 v[8:11], v128 offset:18432
	ds_read_b128 v[12:15], v131 offset:51200
	ds_read_b128 v[16:19], v128 offset:20480
	ds_read_b128 v[20:23], v131 offset:53248
	ds_read_b128 v[24:27], v128 offset:22528
	ds_read_b128 v[28:31], v131 offset:55296
	v_mfma_f32_16x16x32_f16 v[132:135], v[80:83], v[60:63], v[132:135]
	v_mfma_f32_16x16x32_f16 v[136:139], v[88:91], v[60:63], v[136:139]
	v_mfma_f32_16x16x32_f16 v[32:35], v[144:147], v[60:63], v[32:35]
	v_mfma_f32_16x16x32_f16 v[60:63], v[68:71], v[76:79], v[64:67]
	v_mfma_f32_16x16x32_f16 v[64:67], v[80:83], v[76:79], v[92:95]
	v_mfma_f32_16x16x32_f16 v[92:95], v[88:91], v[76:79], v[104:107]
	v_mfma_f32_16x16x32_f16 v[40:43], v[144:147], v[76:79], v[40:43]
	v_mfma_f32_16x16x32_f16 v[72:75], v[68:71], v[84:87], v[72:75]
	v_mfma_f32_16x16x32_f16 v[76:79], v[80:83], v[84:87], v[108:111]
	v_mfma_f32_16x16x32_f16 v[104:107], v[88:91], v[84:87], v[112:115]
	v_mfma_f32_16x16x32_f16 v[48:51], v[144:147], v[84:87], v[48:51]
	v_mfma_f32_16x16x32_f16 v[36:39], v[68:71], v[140:143], v[36:39]
	v_mfma_f32_16x16x32_f16 v[44:47], v[80:83], v[140:143], v[44:47]
	v_mfma_f32_16x16x32_f16 v[52:55], v[88:91], v[140:143], v[52:55]
	v_mfma_f32_16x16x32_f16 v[56:59], v[144:147], v[140:143], v[56:59]
	s_waitcnt lgkmcnt(6)
	v_mfma_f32_16x16x32_f16 v[68:71], v[4:7], v[0:3], v[116:119]
	s_waitcnt lgkmcnt(4)
	v_mfma_f32_16x16x32_f16 v[80:83], v[12:15], v[0:3], v[132:135]
	s_waitcnt lgkmcnt(2)
	v_mfma_f32_16x16x32_f16 v[84:87], v[20:23], v[0:3], v[136:139]
	s_waitcnt lgkmcnt(0)
	v_mfma_f32_16x16x32_f16 v[0:3], v[28:31], v[0:3], v[32:35]
	v_mfma_f32_16x16x32_f16 v[32:35], v[4:7], v[8:11], v[60:63]
	v_mfma_f32_16x16x32_f16 v[60:63], v[12:15], v[8:11], v[64:67]
	v_mfma_f32_16x16x32_f16 v[64:67], v[20:23], v[8:11], v[92:95]
	v_mfma_f32_16x16x32_f16 v[8:11], v[28:31], v[8:11], v[40:43]
	v_mfma_f32_16x16x32_f16 v[40:43], v[4:7], v[16:19], v[72:75]
	v_mfma_f32_16x16x32_f16 v[72:75], v[12:15], v[16:19], v[76:79]
	v_mfma_f32_16x16x32_f16 v[92:95], v[20:23], v[16:19], v[104:107]
	v_mfma_f32_16x16x32_f16 v[16:19], v[28:31], v[16:19], v[48:51]
	v_mfma_f32_16x16x32_f16 v[4:7], v[4:7], v[24:27], v[36:39]
	v_mfma_f32_16x16x32_f16 v[12:15], v[12:15], v[24:27], v[44:47]
	v_mfma_f32_16x16x32_f16 v[52:55], v[20:23], v[24:27], v[52:55]
	v_mfma_f32_16x16x32_f16 v[28:31], v[28:31], v[24:27], v[56:59]
	ds_read_b128 v[20:23], v129 offset:16384
	ds_read_b128 v[104:107], v130 offset:49152
	ds_read_b128 v[24:27], v129 offset:18432
	ds_read_b128 v[108:111], v130 offset:51200
	ds_read_b128 v[112:115], v129 offset:20480
	ds_read_b128 v[116:119], v130 offset:53248
	ds_read_b128 v[124:127], v129 offset:22528
	ds_read_b128 v[128:131], v130 offset:55296
	s_waitcnt lgkmcnt(0)
	s_barrier
; DI unsigned pack2(float lo, float hi) { f2_t v = {lo, hi}; h2_t b = __builtin_convertvector(v, h2_t); return __builtin_bit_cast(unsigned, b); }
; DI float lo_f(unsigned u) { return (float)(__builtin_bit_cast(h2_t, u)[0]); }
; DI float hi_f(unsigned u) { return (float)(__builtin_bit_cast(h2_t, u)[1]); }
; DI float sigmoidf_(float x) { return 1.0f / (1.0f + __expf(-x)); }
; DI void epi_residual(const f32x4 (&v)[4][4], int row0, int col0, const float* xsrc, float* x, bf16_t* xb, float* ssq_out, bool write_xb, bool write_ssq) {
;     ...
;       const int col = col0 + nt * 16 + 4 * g;
;       float4* px = (float4*)(x + (size_t)row * DM + col);
;       float4 o = *(const float4*)(xsrc + (size_t)row * DM + col);
;       o.x += v[mt][nt][0]; o.y += v[mt][nt][1]; o.z += v[mt][nt][2]; o.w += v[mt][nt][3];
;       *px = o;
;       ss += (o.x * o.x + o.y * o.y) + (o.z * o.z + o.w * o.w);
;       if (write_xb) *(uint2*)(xb + (size_t)row * DM + col) = make_uint2(pack2(o.x, o.y), pack2(o.z, o.w));
; DI void phase_ple(const Params& P, int l, char* smem) {
;     ...
; #pragma unroll
;     for (int mt = 0; mt < 4; ++mt)
; #pragma unroll
;       for (int h = 0; h < 2; ++h) {
;         const uint4 q = park[mt * 2 + h];
;         acc[mt][2 * h][0] = sigmoidf_(acc[mt][2 * h][0] * rs[mt]) * lo_f(q.x);
;         acc[mt][2 * h][1] = sigmoidf_(acc[mt][2 * h][1] * rs[mt]) * hi_f(q.x);
;         acc[mt][2 * h][2] = sigmoidf_(acc[mt][2 * h][2] * rs[mt]) * lo_f(q.y);
;         acc[mt][2 * h][3] = sigmoidf_(acc[mt][2 * h][3] * rs[mt]) * hi_f(q.y);
;         acc[mt][2 * h + 1][0] = sigmoidf_(acc[mt][2 * h + 1][0] * rs[mt]) * lo_f(q.z);
;         acc[mt][2 * h + 1][1] = sigmoidf_(acc[mt][2 * h + 1][1] * rs[mt]) * hi_f(q.z);
;         acc[mt][2 * h + 1][2] = sigmoidf_(acc[mt][2 * h + 1][2] * rs[mt]) * lo_f(q.w);
;         acc[mt][2 * h + 1][3] = sigmoidf_(acc[mt][2 * h + 1][3] * rs[mt]) * hi_f(q.w);
;       }
;     epi_residual(acc, row0, col0, P.out, P.out, xb2, ssq_out, l + 1 < DEPTH, l + 1 < DEPTH);
	s_setprio 0
	v_mfma_f32_16x16x32_f16 v[132:135], v[104:107], v[20:23], v[68:71]
	v_mfma_f32_16x16x32_f16 v[88:91], v[108:111], v[20:23], v[80:83]
	v_mfma_f32_16x16x32_f16 v[84:87], v[116:119], v[20:23], v[84:87]
	v_mfma_f32_16x16x32_f16 v[76:79], v[128:131], v[20:23], v[0:3]
	v_mfma_f32_16x16x32_f16 v[20:23], v[104:107], v[124:127], v[4:7]
	s_nop 3
	v_mul_f32_e32 v4, v101, v132
	v_mul_f32_e32 v4, 0xbfb8aa3b, v4
	v_mfma_f32_16x16x32_f16 v[36:39], v[108:111], v[112:115], v[72:75]
	s_nop 2
	v_exp_f32_e32 v72, v4
	v_mul_f32_e32 v4, v101, v133
	v_mul_f32_e32 v4, 0xbfb8aa3b, v4
	v_exp_f32_e32 v73, v4
	v_mul_f32_e32 v4, v101, v134
	v_mul_f32_e32 v4, 0xbfb8aa3b, v4
	v_mfma_f32_16x16x32_f16 v[60:63], v[108:111], v[24:27], v[60:63]
	v_mov_b32_e32 v74, v148
	v_pk_add_f32 v[72:73], v[72:73], 1.0 op_sel_hi:[1,0]
	v_mfma_f32_16x16x32_f16 v[12:15], v[108:111], v[124:127], v[12:15]
	v_exp_f32_e32 v110, v4
	v_mul_f32_e32 v4, v101, v135
	v_mul_f32_e32 v4, 0xbfb8aa3b, v4
	v_mfma_f32_16x16x32_f16 v[68:71], v[104:107], v[24:27], v[32:35]
	v_exp_f32_e32 v111, v4
	s_nop 0
	v_pk_add_f32 v[110:111], v[110:111], 1.0 op_sel_hi:[1,0]
	v_mfma_f32_16x16x32_f16 v[56:59], v[116:119], v[24:27], v[64:67]
	v_mfma_f32_16x16x32_f16 v[48:51], v[128:131], v[24:27], v[8:11]
	v_mfma_f32_16x16x32_f16 v[44:47], v[104:107], v[112:115], v[40:43]
	v_mfma_f32_16x16x32_f16 v[32:35], v[116:119], v[112:115], v[92:95]
	v_mfma_f32_16x16x32_f16 v[24:27], v[128:131], v[112:115], v[16:19]
	v_or_b32_e32 v114, s2, v120
	v_mfma_f32_16x16x32_f16 v[8:11], v[116:119], v[124:127], v[52:55]
	s_nop 2
	global_load_dwordx4 v[52:55], v[102:103], off offset:48
	global_load_dwordx4 v[64:67], v[102:103], off offset:32
	global_load_dwordx4 v[80:83], v[102:103], off offset:16
	global_load_dwordx4 v[92:95], v[102:103], off
	s_waitcnt vmcnt(0)
	v_cvt_f32_f16_e32 v116, v92
	v_mfma_f32_16x16x32_f16 v[0:3], v[128:131], v[124:127], v[28:31]
	global_load_dwordx4 v[4:7], v[102:103], off offset:112
	global_load_dwordx4 v[16:19], v[102:103], off offset:96
	s_nop 0
	global_load_dwordx4 v[28:31], v[102:103], off offset:80
	global_load_dwordx4 v[40:43], v[102:103], off offset:64
	v_cvt_f32_f16_sdwa v117, v92 dst_sel:DWORD dst_unused:UNUSED_PAD src0_sel:WORD_1
	v_and_or_b32 v104, v74, 15, v123
	v_bfe_u32 v115, v74, 4, 2
	v_ashrrev_i32_e32 v105, 31, v104
	v_lshl_or_b32 v118, v115, 2, v114
	v_lshlrev_b64 v[74:75], 12, v[104:105]
	v_lshlrev_b64 v[102:103], 11, v[104:105]
	v_lshl_add_u64 v[74:75], s[16:17], 0, v[74:75]
	v_lshl_add_u64 v[106:107], s[6:7], 0, v[102:103]
	v_lshlrev_b32_e32 v102, 2, v118
	v_mov_b32_e32 v103, v151
	v_lshl_add_u64 v[108:109], v[74:75], 0, v[102:103]
	v_div_scale_f32 v74, s[6:7], v73, v73, 1.0
	v_rcp_f32_e32 v75, v74
	v_div_scale_f32 v92, s[6:7], v111, v111, 1.0
	v_fma_f32 v103, -v74, v75, 1.0
	v_fmac_f32_e32 v75, v103, v75
	v_div_scale_f32 v103, vcc, 1.0, v73, 1.0
	v_mul_f32_e32 v112, v103, v75
	v_fma_f32 v113, -v74, v112, v103
	v_fmac_f32_e32 v112, v113, v75
	v_fma_f32 v74, -v74, v112, v103
	v_div_fmas_f32 v74, v74, v75, v112
	v_div_fixup_f32 v113, v74, v73, 1.0
	v_div_scale_f32 v73, s[6:7], v72, v72, 1.0
	v_rcp_f32_e32 v74, v73
	s_nop 0
	v_fma_f32 v75, -v73, v74, 1.0
	v_fmac_f32_e32 v74, v75, v74
	v_div_scale_f32 v75, vcc, 1.0, v72, 1.0
	v_mul_f32_e32 v103, v75, v74
	v_fma_f32 v112, -v73, v103, v75
	v_fmac_f32_e32 v103, v112, v74
	v_fma_f32 v73, -v73, v103, v75
	v_div_fmas_f32 v73, v73, v74, v103
	v_div_fixup_f32 v112, v73, v72, 1.0
	global_load_dwordx4 v[72:75], v[108:109], off
	v_rcp_f32_e32 v103, v92
	s_waitcnt vmcnt(0)
	v_pk_fma_f32 v[72:73], v[112:113], v[116:117], v[72:73]
	v_fma_f32 v112, -v92, v103, 1.0
	v_fmac_f32_e32 v103, v112, v103
	v_div_scale_f32 v112, vcc, 1.0, v111, 1.0
	v_mul_f32_e32 v113, v112, v103
	v_fma_f32 v116, -v92, v113, v112
	v_fmac_f32_e32 v113, v116, v103
	v_fma_f32 v92, -v92, v113, v112
	v_div_fmas_f32 v92, v92, v103, v113
	v_div_fixup_f32 v111, v92, v111, 1.0
	v_div_scale_f32 v92, s[6:7], v110, v110, 1.0
	v_rcp_f32_e32 v103, v92
	s_nop 0
	v_fma_f32 v112, -v92, v103, 1.0
	v_fmac_f32_e32 v103, v112, v103
	v_div_scale_f32 v112, vcc, 1.0, v110, 1.0
	v_mul_f32_e32 v113, v112, v103
	v_fma_f32 v116, -v92, v113, v112
	v_fmac_f32_e32 v113, v116, v103
	v_fma_f32 v92, -v92, v113, v112
	v_div_fmas_f32 v92, v92, v103, v113
	v_div_fixup_f32 v110, v92, v110, 1.0
	v_cvt_f32_f16_e32 v92, v93
	v_cvt_f32_f16_sdwa v93, v93 dst_sel:DWORD dst_unused:UNUSED_PAD src0_sel:WORD_1
	s_andn2_b64 vcc, exec, s[4:5]
	v_pk_fma_f32 v[74:75], v[110:111], v[92:93], v[74:75]
	v_cndmask_b32_e64 v92, 0, 1, s[4:5]
	v_cmp_ne_u32_e64 s[42:43], 1, v92
	v_lshlrev_b32_e32 v92, 1, v118
	global_store_dwordx4 v[108:109], v[72:75], off
	s_cbranch_vccnz .LBB0_1438
	v_mov_b32_e32 v93, v151
	v_cvt_pk_f16_f32 v110, v72, v73
	v_cvt_pk_f16_f32 v111, v74, v75
	v_lshl_add_u64 v[112:113], v[106:107], 0, v[92:93]
	global_store_dwordx2 v[112:113], v[110:111], off
